# hyena phases: removed 774 s_nop 0 pads an earlier edit left between plain dependent f32 VALU pairs (no software wait state is needed there; hipcc emits such pairs back to back)
# baseline (speedup 1.0000x reference)
.LBB0_536:
	s_nop 1
	v_lshlrev_b32_e32 v0, 2, v146
	s_add_i32 s47, 16, 0x10000
	v_add_u32_e32 v64, 16, v0
	v_add_u32_e32 v65, s47, v0
	s_waitcnt lgkmcnt(0)
	s_barrier
	ds_read2st64_b32 v[2:3], v64 offset1:8
	ds_read2st64_b32 v[4:5], v65 offset1:8
	ds_read2st64_b32 v[8:9], v64 offset0:16 offset1:24
	ds_read2st64_b32 v[10:11], v65 offset0:16 offset1:24
	ds_read2st64_b32 v[12:13], v64 offset0:32 offset1:40
	ds_read2st64_b32 v[14:15], v65 offset0:32 offset1:40
	s_mov_b32 s49, s40
	s_waitcnt lgkmcnt(5)
	v_mov_b32_e32 v6, v2
	s_waitcnt lgkmcnt(4)
	v_mov_b32_e32 v7, v4
	v_mov_b32_e32 v4, v3
	s_waitcnt lgkmcnt(3)
	v_mov_b32_e32 v2, v8
	s_waitcnt lgkmcnt(2)
	v_mov_b32_e32 v3, v10
	v_mov_b32_e32 v10, v9
	ds_read2st64_b32 v[8:9], v64 offset0:48 offset1:56
	ds_read2st64_b32 v[16:17], v65 offset0:48 offset1:56
	s_waitcnt lgkmcnt(3)
	v_mov_b32_e32 v18, v12
	s_waitcnt lgkmcnt(2)
	v_mov_b32_e32 v19, v14
	v_mov_b32_e32 v14, v13
	s_waitcnt lgkmcnt(1)
	v_mov_b32_e32 v12, v8
	s_waitcnt lgkmcnt(0)
	v_mov_b32_e32 v13, v16
	ds_read2st64_b32 v[20:21], v64 offset0:64 offset1:72
	ds_read2st64_b32 v[22:23], v65 offset0:64 offset1:72
	v_mov_b32_e32 v16, v9
	ds_read2st64_b32 v[8:9], v64 offset0:80 offset1:88
	ds_read2st64_b32 v[24:25], v65 offset0:80 offset1:88
	s_mov_b32 s41, s45
	s_waitcnt lgkmcnt(3)
	v_mov_b32_e32 v26, v20
	s_waitcnt lgkmcnt(2)
	v_mov_b32_e32 v27, v22
	v_mov_b32_e32 v22, v21
	s_waitcnt lgkmcnt(1)
	v_mov_b32_e32 v28, v8
	s_waitcnt lgkmcnt(0)
	v_mov_b32_e32 v29, v24
	ds_read2st64_b32 v[20:21], v64 offset0:96 offset1:104
	ds_read2st64_b32 v[30:31], v65 offset0:96 offset1:104
	v_mov_b32_e32 v24, v9
	ds_read2st64_b32 v[8:9], v64 offset0:112 offset1:120
	ds_read2st64_b32 v[32:33], v65 offset0:112 offset1:120
	v_and_b32_e32 v196, 63, v146
	v_lshlrev_b32_e32 v196, 2, v196
	v_and_b32_e32 v0, 0xffffffc0, v146
	v_lshl_add_u32 v0, v0, 5, v196
	v_add_u32_e32 v0, 0x400, v0
	s_waitcnt lgkmcnt(3)
	v_mov_b32_e32 v34, v20
	s_waitcnt lgkmcnt(2)
	v_mov_b32_e32 v35, v30
	v_mov_b32_e32 v30, v21
	s_waitcnt lgkmcnt(1)
	v_mov_b32_e32 v36, v8
	s_waitcnt lgkmcnt(0)
	v_mov_b32_e32 v37, v32
	ds_read2st64_b32 v[20:21], v64 offset0:128 offset1:136
	ds_read2st64_b32 v[38:39], v65 offset0:128 offset1:136
	v_mov_b32_e32 v32, v9
	ds_read2st64_b32 v[8:9], v64 offset0:144 offset1:152
	ds_read2st64_b32 v[40:41], v65 offset0:144 offset1:152
	v_readlane_b32 s0, v252, 48
	s_waitcnt lgkmcnt(3)
	v_mov_b32_e32 v42, v20
	s_waitcnt lgkmcnt(2)
	v_mov_b32_e32 v43, v38
	v_mov_b32_e32 v38, v21
	s_waitcnt lgkmcnt(1)
	v_mov_b32_e32 v44, v8
	s_waitcnt lgkmcnt(0)
	v_mov_b32_e32 v45, v40
	ds_read2st64_b32 v[20:21], v64 offset0:160 offset1:168
	ds_read2st64_b32 v[46:47], v65 offset0:160 offset1:168
	v_mov_b32_e32 v40, v9
	ds_read2st64_b32 v[8:9], v64 offset0:176 offset1:184
	ds_read2st64_b32 v[48:49], v65 offset0:176 offset1:184
	v_ashrrev_i32_e32 v1, 31, v0
	s_waitcnt lgkmcnt(3)
	v_mov_b32_e32 v50, v20
	s_waitcnt lgkmcnt(2)
	v_mov_b32_e32 v51, v46
	v_mov_b32_e32 v46, v21
	s_waitcnt lgkmcnt(1)
	v_mov_b32_e32 v52, v8
	s_waitcnt lgkmcnt(0)
	v_mov_b32_e32 v53, v48
	ds_read2st64_b32 v[20:21], v64 offset0:192 offset1:200
	ds_read2st64_b32 v[54:55], v65 offset0:192 offset1:200
	v_mov_b32_e32 v48, v9
	ds_read2st64_b32 v[8:9], v64 offset0:208 offset1:216
	ds_read2st64_b32 v[56:57], v65 offset0:208 offset1:216
	v_readlane_b32 s1, v252, 49
	s_waitcnt lgkmcnt(3)
	v_mov_b32_e32 v58, v20
	s_waitcnt lgkmcnt(2)
	v_mov_b32_e32 v59, v54
	v_mov_b32_e32 v54, v21
	s_waitcnt lgkmcnt(1)
	v_mov_b32_e32 v60, v8
	s_waitcnt lgkmcnt(0)
	v_mov_b32_e32 v61, v56
	ds_read2st64_b32 v[20:21], v64 offset0:224 offset1:232
	ds_read2st64_b32 v[62:63], v65 offset0:224 offset1:232
	v_mov_b32_e32 v56, v9
	ds_read2st64_b32 v[8:9], v64 offset0:240 offset1:248
	ds_read2st64_b32 v[64:65], v65 offset0:240 offset1:248
	s_waitcnt lgkmcnt(0)
	v_mov_b32_e32 v66, v20
	v_mov_b32_e32 v67, v62
	v_mov_b32_e32 v72, v8
	v_mov_b32_e32 v73, v64
	v_mov_b32_e32 v64, v9
	v_pk_add_f32 v[8:9], v[6:7], v[42:43]
	v_pk_add_f32 v[6:7], v[6:7], v[42:43] neg_lo:[0,1] neg_hi:[0,1]
	v_pk_add_f32 v[42:43], v[4:5], v[38:39]
	v_pk_add_f32 v[4:5], v[4:5], v[38:39] neg_lo:[0,1] neg_hi:[0,1]
	v_mov_b32_e32 v62, v21
	v_pk_mul_f32 v[38:39], v[4:5], s[58:59] op_sel:[1,0] op_sel_hi:[0,0] neg_hi:[1,0]
	v_mov_b32_e32 v21, v146
	v_pk_fma_f32 v[4:5], v[4:5], s[46:47], v[38:39] op_sel_hi:[1,0,1]
	v_pk_add_f32 v[38:39], v[2:3], v[44:45]
	v_pk_add_f32 v[2:3], v[2:3], v[44:45] neg_lo:[0,1] neg_hi:[0,1]
	s_barrier
	s_nop 0
	s_nop 0
	v_pk_mul_f32 v[44:45], v[2:3], s[62:63] op_sel:[1,0] op_sel_hi:[0,0] neg_hi:[1,0]
	s_nop 0
	v_pk_fma_f32 v[2:3], v[2:3], s[60:61], v[44:45] op_sel_hi:[1,0,1]
	v_pk_add_f32 v[44:45], v[10:11], v[40:41]
	v_pk_add_f32 v[10:11], v[10:11], v[40:41] neg_lo:[0,1] neg_hi:[0,1]
	s_lshl_b64 s[10:11], s[68:69], 2
	s_nop 0
	s_nop 0
	v_pk_mul_f32 v[40:41], v[10:11], s[66:67] op_sel:[1,0] op_sel_hi:[0,0] neg_hi:[1,0]
	s_add_u32 s90, s54, s10
	v_pk_fma_f32 v[10:11], v[10:11], s[64:65], v[40:41] op_sel_hi:[1,0,1]
	v_pk_add_f32 v[40:41], v[18:19], v[50:51]
	v_pk_add_f32 v[18:19], v[18:19], v[50:51] neg_lo:[0,1] neg_hi:[0,1]
	s_addc_u32 s91, s55, s11
	s_nop 0
	s_nop 0
	v_pk_mul_f32 v[50:51], v[18:19], s[70:71] op_sel:[1,0] op_sel_hi:[0,0] neg_hi:[1,0]
	v_add_u32_e32 v70, 0x200, v146
	v_pk_fma_f32 v[18:19], v[18:19], s[70:71], v[50:51] op_sel_hi:[1,0,1]
	v_pk_add_f32 v[50:51], v[14:15], v[46:47]
	v_pk_add_f32 v[14:15], v[14:15], v[46:47] neg_lo:[0,1] neg_hi:[0,1]
	v_ashrrev_i32_e32 v147, 31, v146
	s_nop 0
	s_nop 0
	v_pk_mul_f32 v[46:47], v[14:15], s[64:65] op_sel:[1,0] op_sel_hi:[0,0] neg_hi:[1,0]
	v_add_u32_e32 v69, 0x400, v146
	v_pk_fma_f32 v[14:15], v[14:15], s[66:67], v[46:47] op_sel_hi:[1,0,1]
	v_pk_add_f32 v[46:47], v[12:13], v[52:53]
	v_pk_add_f32 v[12:13], v[12:13], v[52:53] neg_lo:[0,1] neg_hi:[0,1]
	v_add_u32_e32 v68, 0x600, v146
	v_pk_mul_f32 v[52:53], v[12:13], s[60:61] op_sel:[1,0] op_sel_hi:[0,0] neg_hi:[1,0]
	s_mov_b32 s16, 0
	v_pk_fma_f32 v[12:13], v[12:13], s[62:63], v[52:53] op_sel_hi:[1,0,1]
	v_pk_add_f32 v[52:53], v[16:17], v[48:49]
	v_pk_add_f32 v[16:17], v[16:17], v[48:49] neg_lo:[0,1] neg_hi:[0,1]
	v_pk_mul_f32 v[48:49], v[16:17], s[46:47] op_sel:[1,0] op_sel_hi:[0,0] neg_hi:[1,0]
	v_pk_fma_f32 v[16:17], v[16:17], s[58:59], v[48:49] op_sel_hi:[1,0,1]
	v_pk_add_f32 v[48:49], v[26:27], v[58:59]
	v_pk_add_f32 v[26:27], v[26:27], v[58:59] neg_lo:[0,1] neg_hi:[0,1]
	v_xor_b32_e32 v59, 0x80000000, v26
	v_mov_b32_e32 v58, v27
	v_pk_add_f32 v[26:27], v[22:23], v[54:55]
	v_pk_add_f32 v[22:23], v[22:23], v[54:55] neg_lo:[0,1] neg_hi:[0,1]
	v_pk_mul_f32 v[54:55], v[22:23], s[58:59] op_sel_hi:[1,0]
	v_xor_b32_e32 v75, 0x80000000, v22
	v_mov_b32_e32 v74, v23
	v_pk_fma_f32 v[22:23], v[74:75], s[46:47], v[54:55] op_sel_hi:[1,0,1] neg_lo:[0,0,1] neg_hi:[0,0,1]
	v_pk_add_f32 v[54:55], v[28:29], v[60:61]
	v_pk_add_f32 v[28:29], v[28:29], v[60:61] neg_lo:[0,1] neg_hi:[0,1]
	v_pk_mul_f32 v[60:61], v[28:29], s[62:63] op_sel_hi:[1,0]
	v_xor_b32_e32 v75, 0x80000000, v28
	v_mov_b32_e32 v74, v29
	v_pk_fma_f32 v[28:29], v[74:75], s[60:61], v[60:61] op_sel_hi:[1,0,1] neg_lo:[0,0,1] neg_hi:[0,0,1]
	v_pk_add_f32 v[60:61], v[24:25], v[56:57]
	v_pk_add_f32 v[24:25], v[24:25], v[56:57] neg_lo:[0,1] neg_hi:[0,1]
	v_pk_mul_f32 v[56:57], v[24:25], s[66:67] op_sel_hi:[1,0]
	v_xor_b32_e32 v75, 0x80000000, v24
	v_mov_b32_e32 v74, v25
	v_pk_fma_f32 v[24:25], v[74:75], s[64:65], v[56:57] op_sel_hi:[1,0,1] neg_lo:[0,0,1] neg_hi:[0,0,1]
	v_pk_add_f32 v[56:57], v[34:35], v[66:67]
	v_pk_add_f32 v[34:35], v[34:35], v[66:67] neg_lo:[0,1] neg_hi:[0,1]
	v_pk_mul_f32 v[66:67], v[34:35], s[70:71] op_sel_hi:[1,0]
	v_xor_b32_e32 v75, 0x80000000, v34
	v_mov_b32_e32 v74, v35
	v_pk_fma_f32 v[34:35], v[74:75], s[70:71], v[66:67] op_sel_hi:[1,0,1] neg_lo:[0,0,1] neg_hi:[0,0,1]
	v_pk_add_f32 v[66:67], v[30:31], v[62:63]
	v_pk_add_f32 v[30:31], v[30:31], v[62:63] neg_lo:[0,1] neg_hi:[0,1]
	v_pk_mul_f32 v[62:63], v[30:31], s[64:65] op_sel_hi:[1,0]
	v_xor_b32_e32 v75, 0x80000000, v30
	v_mov_b32_e32 v74, v31
	v_pk_fma_f32 v[30:31], v[74:75], s[66:67], v[62:63] op_sel_hi:[1,0,1] neg_lo:[0,0,1] neg_hi:[0,0,1]
	v_pk_add_f32 v[62:63], v[36:37], v[72:73]
	v_pk_add_f32 v[36:37], v[36:37], v[72:73] neg_lo:[0,1] neg_hi:[0,1]
	v_pk_mul_f32 v[72:73], v[36:37], s[60:61] op_sel_hi:[1,0]
	v_xor_b32_e32 v75, 0x80000000, v36
	v_mov_b32_e32 v74, v37
	v_pk_fma_f32 v[36:37], v[74:75], s[62:63], v[72:73] op_sel_hi:[1,0,1] neg_lo:[0,0,1] neg_hi:[0,0,1]
	v_pk_add_f32 v[72:73], v[32:33], v[64:65]
	v_pk_add_f32 v[32:33], v[32:33], v[64:65] neg_lo:[0,1] neg_hi:[0,1]
	v_pk_mul_f32 v[64:65], v[32:33], s[46:47] op_sel_hi:[1,0]
	v_xor_b32_e32 v75, 0x80000000, v32
	v_mov_b32_e32 v74, v33
	v_pk_fma_f32 v[32:33], v[74:75], s[58:59], v[64:65] op_sel_hi:[1,0,1] neg_lo:[0,0,1] neg_hi:[0,0,1]
	v_pk_add_f32 v[64:65], v[8:9], v[48:49]
	v_pk_add_f32 v[8:9], v[8:9], v[48:49] neg_lo:[0,1] neg_hi:[0,1]
	v_pk_add_f32 v[48:49], v[42:43], v[26:27]
	v_pk_add_f32 v[26:27], v[42:43], v[26:27] neg_lo:[0,1] neg_hi:[0,1]
	v_pk_mul_f32 v[42:43], v[26:27], s[62:63] op_sel:[1,0] op_sel_hi:[0,0] neg_hi:[1,0]
	v_pk_fma_f32 v[26:27], v[26:27], s[60:61], v[42:43] op_sel_hi:[1,0,1]
	v_pk_add_f32 v[42:43], v[38:39], v[54:55]
	v_pk_add_f32 v[38:39], v[38:39], v[54:55] neg_lo:[0,1] neg_hi:[0,1]
	v_pk_mul_f32 v[54:55], v[38:39], s[70:71] op_sel:[1,0] op_sel_hi:[0,0] neg_hi:[1,0]
	v_pk_fma_f32 v[38:39], v[38:39], s[70:71], v[54:55] op_sel_hi:[1,0,1]
	v_pk_add_f32 v[54:55], v[44:45], v[60:61]
	v_pk_add_f32 v[44:45], v[44:45], v[60:61] neg_lo:[0,1] neg_hi:[0,1]
	v_pk_mul_f32 v[60:61], v[44:45], s[60:61] op_sel:[1,0] op_sel_hi:[0,0] neg_hi:[1,0]
	v_pk_fma_f32 v[44:45], v[44:45], s[62:63], v[60:61] op_sel_hi:[1,0,1]
	v_pk_add_f32 v[60:61], v[40:41], v[56:57]
	v_pk_add_f32 v[40:41], v[40:41], v[56:57] neg_lo:[0,1] neg_hi:[0,1]
	v_xor_b32_e32 v57, 0x80000000, v40
	v_mov_b32_e32 v56, v41
	v_pk_add_f32 v[40:41], v[50:51], v[66:67]
	v_pk_add_f32 v[50:51], v[50:51], v[66:67] neg_lo:[0,1] neg_hi:[0,1]
	v_pk_mul_f32 v[66:67], v[50:51], s[62:63] op_sel_hi:[1,0]
	v_xor_b32_e32 v75, 0x80000000, v50
	v_mov_b32_e32 v74, v51
	v_pk_fma_f32 v[50:51], v[74:75], s[60:61], v[66:67] op_sel_hi:[1,0,1] neg_lo:[0,0,1] neg_hi:[0,0,1]
	v_pk_add_f32 v[66:67], v[46:47], v[62:63]
	v_pk_add_f32 v[46:47], v[46:47], v[62:63] neg_lo:[0,1] neg_hi:[0,1]
	v_pk_mul_f32 v[62:63], v[46:47], s[70:71] op_sel_hi:[1,0]
	v_xor_b32_e32 v75, 0x80000000, v46
	v_mov_b32_e32 v74, v47
	v_pk_fma_f32 v[46:47], v[74:75], s[70:71], v[62:63] op_sel_hi:[1,0,1] neg_lo:[0,0,1] neg_hi:[0,0,1]
	v_pk_add_f32 v[62:63], v[52:53], v[72:73]
	v_pk_add_f32 v[52:53], v[52:53], v[72:73] neg_lo:[0,1] neg_hi:[0,1]
	v_pk_mul_f32 v[72:73], v[52:53], s[60:61] op_sel_hi:[1,0]
	v_xor_b32_e32 v75, 0x80000000, v52
	v_mov_b32_e32 v74, v53
	v_pk_fma_f32 v[52:53], v[74:75], s[62:63], v[72:73] op_sel_hi:[1,0,1] neg_lo:[0,0,1] neg_hi:[0,0,1]
	v_pk_add_f32 v[72:73], v[6:7], v[58:59]
	v_pk_add_f32 v[6:7], v[6:7], v[58:59] neg_lo:[0,1] neg_hi:[0,1]
	v_pk_add_f32 v[58:59], v[4:5], v[22:23]
	v_pk_add_f32 v[4:5], v[4:5], v[22:23] neg_lo:[0,1] neg_hi:[0,1]
	v_pk_mul_f32 v[22:23], v[4:5], s[62:63] op_sel:[1,0] op_sel_hi:[0,0] neg_hi:[1,0]
	v_pk_fma_f32 v[4:5], v[4:5], s[60:61], v[22:23] op_sel_hi:[1,0,1]
	v_pk_add_f32 v[22:23], v[2:3], v[28:29]
	v_pk_add_f32 v[2:3], v[2:3], v[28:29] neg_lo:[0,1] neg_hi:[0,1]
	v_pk_mul_f32 v[28:29], v[2:3], s[70:71] op_sel:[1,0] op_sel_hi:[0,0] neg_hi:[1,0]
	v_pk_fma_f32 v[2:3], v[2:3], s[70:71], v[28:29] op_sel_hi:[1,0,1]
	v_pk_add_f32 v[28:29], v[10:11], v[24:25]
	v_pk_add_f32 v[10:11], v[10:11], v[24:25] neg_lo:[0,1] neg_hi:[0,1]
	v_pk_mul_f32 v[24:25], v[10:11], s[60:61] op_sel:[1,0] op_sel_hi:[0,0] neg_hi:[1,0]
	v_pk_fma_f32 v[10:11], v[10:11], s[62:63], v[24:25] op_sel_hi:[1,0,1]
	v_pk_add_f32 v[24:25], v[18:19], v[34:35]
	v_pk_add_f32 v[18:19], v[18:19], v[34:35] neg_lo:[0,1] neg_hi:[0,1]
	v_xor_b32_e32 v35, 0x80000000, v18
	v_mov_b32_e32 v34, v19
	v_pk_add_f32 v[18:19], v[14:15], v[30:31]
	v_pk_add_f32 v[14:15], v[14:15], v[30:31] neg_lo:[0,1] neg_hi:[0,1]
	v_pk_mul_f32 v[30:31], v[14:15], s[62:63] op_sel_hi:[1,0]
	v_xor_b32_e32 v75, 0x80000000, v14
	v_mov_b32_e32 v74, v15
	v_pk_fma_f32 v[14:15], v[74:75], s[60:61], v[30:31] op_sel_hi:[1,0,1] neg_lo:[0,0,1] neg_hi:[0,0,1]
	v_pk_add_f32 v[30:31], v[12:13], v[36:37]
	v_pk_add_f32 v[12:13], v[12:13], v[36:37] neg_lo:[0,1] neg_hi:[0,1]
	v_pk_mul_f32 v[36:37], v[12:13], s[70:71] op_sel_hi:[1,0]
	v_xor_b32_e32 v75, 0x80000000, v12
	v_mov_b32_e32 v74, v13
	v_pk_fma_f32 v[12:13], v[74:75], s[70:71], v[36:37] op_sel_hi:[1,0,1] neg_lo:[0,0,1] neg_hi:[0,0,1]
	v_pk_add_f32 v[36:37], v[16:17], v[32:33]
	v_pk_add_f32 v[16:17], v[16:17], v[32:33] neg_lo:[0,1] neg_hi:[0,1]
	v_pk_mul_f32 v[32:33], v[16:17], s[60:61] op_sel_hi:[1,0]
	v_xor_b32_e32 v75, 0x80000000, v16
	v_mov_b32_e32 v74, v17
	v_pk_fma_f32 v[16:17], v[74:75], s[62:63], v[32:33] op_sel_hi:[1,0,1] neg_lo:[0,0,1] neg_hi:[0,0,1]
	v_pk_add_f32 v[32:33], v[64:65], v[60:61]
	v_pk_add_f32 v[60:61], v[64:65], v[60:61] neg_lo:[0,1] neg_hi:[0,1]
	v_pk_add_f32 v[64:65], v[48:49], v[40:41]
	v_pk_add_f32 v[40:41], v[48:49], v[40:41] neg_lo:[0,1] neg_hi:[0,1]
	v_pk_mul_f32 v[48:49], v[40:41], s[70:71] op_sel:[1,0] op_sel_hi:[0,0] neg_hi:[1,0]
	v_pk_fma_f32 v[40:41], v[40:41], s[70:71], v[48:49] op_sel_hi:[1,0,1]
	v_pk_add_f32 v[48:49], v[42:43], v[66:67]
	v_pk_add_f32 v[42:43], v[42:43], v[66:67] neg_lo:[0,1] neg_hi:[0,1]
	v_xor_b32_e32 v67, 0x80000000, v42
	v_mov_b32_e32 v66, v43
	v_pk_add_f32 v[42:43], v[54:55], v[62:63]
	v_pk_add_f32 v[54:55], v[54:55], v[62:63] neg_lo:[0,1] neg_hi:[0,1]
	v_pk_mul_f32 v[62:63], v[54:55], s[70:71] op_sel_hi:[1,0]
	v_xor_b32_e32 v75, 0x80000000, v54
	v_mov_b32_e32 v74, v55
	v_pk_fma_f32 v[54:55], v[74:75], s[70:71], v[62:63] op_sel_hi:[1,0,1] neg_lo:[0,0,1] neg_hi:[0,0,1]
	v_pk_add_f32 v[62:63], v[8:9], v[56:57]
	v_pk_add_f32 v[8:9], v[8:9], v[56:57] neg_lo:[0,1] neg_hi:[0,1]
	v_pk_add_f32 v[56:57], v[26:27], v[50:51]
	v_pk_add_f32 v[26:27], v[26:27], v[50:51] neg_lo:[0,1] neg_hi:[0,1]
	v_pk_mul_f32 v[50:51], v[26:27], s[70:71] op_sel:[1,0] op_sel_hi:[0,0] neg_hi:[1,0]
	v_pk_fma_f32 v[26:27], v[26:27], s[70:71], v[50:51] op_sel_hi:[1,0,1]
	v_pk_add_f32 v[50:51], v[38:39], v[46:47]
	v_pk_add_f32 v[38:39], v[38:39], v[46:47] neg_lo:[0,1] neg_hi:[0,1]
	v_xor_b32_e32 v47, 0x80000000, v38
	v_mov_b32_e32 v46, v39
	v_pk_add_f32 v[38:39], v[44:45], v[52:53]
	v_pk_add_f32 v[44:45], v[44:45], v[52:53] neg_lo:[0,1] neg_hi:[0,1]
	v_pk_mul_f32 v[52:53], v[44:45], s[70:71] op_sel_hi:[1,0]
	v_xor_b32_e32 v75, 0x80000000, v44
	v_mov_b32_e32 v74, v45
	v_pk_fma_f32 v[44:45], v[74:75], s[70:71], v[52:53] op_sel_hi:[1,0,1] neg_lo:[0,0,1] neg_hi:[0,0,1]
	v_pk_add_f32 v[52:53], v[72:73], v[24:25]
	v_pk_add_f32 v[24:25], v[72:73], v[24:25] neg_lo:[0,1] neg_hi:[0,1]
	v_pk_add_f32 v[72:73], v[58:59], v[18:19]
	v_pk_add_f32 v[18:19], v[58:59], v[18:19] neg_lo:[0,1] neg_hi:[0,1]
	v_pk_mul_f32 v[58:59], v[18:19], s[70:71] op_sel:[1,0] op_sel_hi:[0,0] neg_hi:[1,0]
	v_pk_fma_f32 v[18:19], v[18:19], s[70:71], v[58:59] op_sel_hi:[1,0,1]
	v_pk_add_f32 v[58:59], v[22:23], v[30:31]
	v_pk_add_f32 v[22:23], v[22:23], v[30:31] neg_lo:[0,1] neg_hi:[0,1]
	v_xor_b32_e32 v31, 0x80000000, v22
	v_mov_b32_e32 v30, v23
	v_pk_add_f32 v[22:23], v[28:29], v[36:37]
	v_pk_add_f32 v[28:29], v[28:29], v[36:37] neg_lo:[0,1] neg_hi:[0,1]
	v_pk_add_f32 v[76:77], v[24:25], v[30:31]
	v_pk_mul_f32 v[36:37], v[28:29], s[70:71] op_sel_hi:[1,0]
	v_xor_b32_e32 v75, 0x80000000, v28
	v_mov_b32_e32 v74, v29
	v_pk_fma_f32 v[28:29], v[74:75], s[70:71], v[36:37] op_sel_hi:[1,0,1] neg_lo:[0,0,1] neg_hi:[0,0,1]
	v_pk_add_f32 v[36:37], v[6:7], v[34:35]
	v_pk_add_f32 v[6:7], v[6:7], v[34:35] neg_lo:[0,1] neg_hi:[0,1]
	v_pk_add_f32 v[34:35], v[4:5], v[14:15]
	v_pk_add_f32 v[4:5], v[4:5], v[14:15] neg_lo:[0,1] neg_hi:[0,1]
	v_pk_add_f32 v[78:79], v[18:19], v[28:29]
	v_pk_mul_f32 v[14:15], v[4:5], s[70:71] op_sel:[1,0] op_sel_hi:[0,0] neg_hi:[1,0]
	v_pk_add_f32 v[18:19], v[18:19], v[28:29] neg_lo:[0,1] neg_hi:[0,1]
	v_pk_fma_f32 v[4:5], v[4:5], s[70:71], v[14:15] op_sel_hi:[1,0,1]
	v_pk_add_f32 v[14:15], v[2:3], v[12:13]
	v_pk_add_f32 v[2:3], v[2:3], v[12:13] neg_lo:[0,1] neg_hi:[0,1]
	v_xor_b32_e32 v81, 0x80000000, v18
	v_xor_b32_e32 v13, 0x80000000, v2
	v_mov_b32_e32 v12, v3
	v_pk_add_f32 v[2:3], v[10:11], v[16:17]
	v_pk_add_f32 v[10:11], v[10:11], v[16:17] neg_lo:[0,1] neg_hi:[0,1]
	v_mov_b32_e32 v80, v19
	v_pk_mul_f32 v[16:17], v[10:11], s[70:71] op_sel_hi:[1,0]
	v_pk_fma_f32 v[10:11], v[10:11], s[70:71], v[16:17] op_sel:[1,0,0] op_sel_hi:[0,0,1] neg_lo:[0,0,1] neg_hi:[1,0,1]
	v_pk_add_f32 v[74:75], v[62:63], v[50:51]
	v_pk_add_f32 v[50:51], v[62:63], v[50:51] neg_lo:[0,1] neg_hi:[0,1]
	v_pk_add_f32 v[62:63], v[56:57], v[38:39]
	v_pk_add_f32 v[38:39], v[56:57], v[38:39] neg_lo:[0,1] neg_hi:[0,1]
	v_pk_add_f32 v[16:17], v[32:33], v[48:49]
	v_pk_add_f32 v[32:33], v[32:33], v[48:49] neg_lo:[0,1] neg_hi:[0,1]
	v_pk_add_f32 v[48:49], v[64:65], v[42:43]
	v_pk_add_f32 v[42:43], v[64:65], v[42:43] neg_lo:[0,1] neg_hi:[0,1]
	v_xor_b32_e32 v57, 0x80000000, v38
	v_mov_b32_e32 v56, v39
	v_pk_add_f32 v[38:39], v[8:9], v[46:47]
	v_pk_add_f32 v[8:9], v[8:9], v[46:47] neg_lo:[0,1] neg_hi:[0,1]
	v_pk_add_f32 v[46:47], v[26:27], v[44:45]
	v_pk_add_f32 v[26:27], v[26:27], v[44:45] neg_lo:[0,1] neg_hi:[0,1]
	v_xor_b32_e32 v65, 0x80000000, v42
	v_mov_b32_e32 v64, v43
	v_pk_add_f32 v[42:43], v[60:61], v[66:67]
	v_pk_add_f32 v[60:61], v[60:61], v[66:67] neg_lo:[0,1] neg_hi:[0,1]
	v_pk_add_f32 v[66:67], v[40:41], v[54:55]
	v_pk_add_f32 v[40:41], v[40:41], v[54:55] neg_lo:[0,1] neg_hi:[0,1]
	v_xor_b32_e32 v45, 0x80000000, v26
	v_mov_b32_e32 v44, v27
	v_pk_add_f32 v[26:27], v[52:53], v[58:59]
	v_pk_add_f32 v[52:53], v[52:53], v[58:59] neg_lo:[0,1] neg_hi:[0,1]
	v_pk_add_f32 v[58:59], v[72:73], v[22:23]
	v_pk_add_f32 v[22:23], v[72:73], v[22:23] neg_lo:[0,1] neg_hi:[0,1]
	v_pk_add_f32 v[18:19], v[36:37], v[14:15]
	v_pk_add_f32 v[14:15], v[36:37], v[14:15] neg_lo:[0,1] neg_hi:[0,1]
	v_pk_add_f32 v[36:37], v[34:35], v[2:3]
	v_pk_add_f32 v[2:3], v[34:35], v[2:3] neg_lo:[0,1] neg_hi:[0,1]
	v_xor_b32_e32 v73, 0x80000000, v22
	v_mov_b32_e32 v72, v23
	v_xor_b32_e32 v35, 0x80000000, v2
	v_mov_b32_e32 v34, v3
	v_pk_add_f32 v[2:3], v[4:5], v[10:11] neg_lo:[0,1] neg_hi:[0,1]
	v_pk_add_f32 v[24:25], v[24:25], v[30:31] neg_lo:[0,1] neg_hi:[0,1]
	v_pk_add_f32 v[82:83], v[6:7], v[12:13]
	v_pk_add_f32 v[12:13], v[6:7], v[12:13] neg_lo:[0,1] neg_hi:[0,1]
	v_xor_b32_e32 v87, 0x80000000, v2
	v_mov_b32_e32 v86, v3
	v_pk_add_f32 v[2:3], v[16:17], v[48:49]
	v_pk_add_f32 v[88:89], v[16:17], v[48:49] neg_lo:[0,1] neg_hi:[0,1]
	v_pk_add_f32 v[48:49], v[32:33], v[64:65]
	v_pk_add_f32 v[28:29], v[32:33], v[64:65] neg_lo:[0,1] neg_hi:[0,1]
	v_pk_add_f32 v[64:65], v[60:61], v[40:41] op_sel:[0,1] op_sel_hi:[1,0] neg_hi:[0,1]
	v_pk_add_f32 v[6:7], v[60:61], v[40:41] op_sel:[0,1] op_sel_hi:[1,0] neg_lo:[0,1]
	v_pk_add_f32 v[60:61], v[50:51], v[56:57]
	v_pk_add_f32 v[22:23], v[50:51], v[56:57] neg_lo:[0,1] neg_hi:[0,1]
	v_pk_add_f32 v[50:51], v[52:53], v[72:73]
	v_pk_add_f32 v[30:31], v[52:53], v[72:73] neg_lo:[0,1] neg_hi:[0,1]
	v_pk_add_f32 v[52:53], v[18:19], v[36:37]
	v_pk_add_f32 v[56:57], v[18:19], v[36:37] neg_lo:[0,1] neg_hi:[0,1]
	v_mov_b32_e32 v18, v21
	v_pk_add_f32 v[84:85], v[4:5], v[10:11]
	v_cvt_f32_i32_e32 v18, v18
	v_pk_add_f32 v[32:33], v[42:43], v[66:67]
	v_pk_add_f32 v[40:41], v[42:43], v[66:67] neg_lo:[0,1] neg_hi:[0,1]
	v_pk_add_f32 v[66:67], v[24:25], v[80:81]
	v_pk_add_f32 v[10:11], v[24:25], v[80:81] neg_lo:[0,1] neg_hi:[0,1]
	v_pk_add_f32 v[72:73], v[14:15], v[34:35]
	v_pk_add_f32 v[24:25], v[14:15], v[34:35] neg_lo:[0,1] neg_hi:[0,1]
	v_mul_f32_e32 v15, 0x38800000, v18
	v_cos_f32_e32 v14, v15
	v_sin_f32_e32 v15, v15
	v_pk_add_f32 v[16:17], v[74:75], v[62:63]
	v_pk_add_f32 v[54:55], v[74:75], v[62:63] neg_lo:[0,1] neg_hi:[0,1]
	v_pk_add_f32 v[62:63], v[8:9], v[44:45]
	v_pk_add_f32 v[4:5], v[8:9], v[44:45] neg_lo:[0,1] neg_hi:[0,1]
	v_pk_add_f32 v[8:9], v[26:27], v[58:59]
	v_add_f32_e32 v20, v14, v14
	v_pk_add_f32 v[42:43], v[38:39], v[46:47]
	v_pk_add_f32 v[38:39], v[38:39], v[46:47] neg_lo:[0,1] neg_hi:[0,1]
	v_pk_add_f32 v[58:59], v[26:27], v[58:59] neg_lo:[0,1] neg_hi:[0,1]
	v_pk_add_f32 v[26:27], v[76:77], v[78:79]
	v_pk_add_f32 v[46:47], v[76:77], v[78:79] neg_lo:[0,1] neg_hi:[0,1]
	v_pk_mul_f32 v[18:19], v[14:15], v[14:15]
	v_mul_f32_e32 v20, v15, v20
	v_mov_b32_e32 v78, v15
	v_pk_add_f32 v[18:19], v[18:19], v[18:19] op_sel:[0,1] op_sel_hi:[0,1] neg_lo:[0,1] neg_hi:[0,1]
	v_pk_mul_f32 v[34:35], v[14:15], v[20:21] op_sel:[1,0] op_sel_hi:[0,0] neg_lo:[1,0]
	v_pk_mul_f32 v[36:37], v[78:79], v[8:9] op_sel:[0,1] op_sel_hi:[0,0] neg_hi:[0,1]
	v_pk_fma_f32 v[34:35], v[14:15], v[18:19], v[34:35]
	v_pk_fma_f32 v[8:9], v[14:15], v[8:9], v[36:37] op_sel_hi:[0,1,1]
	v_pk_mul_f32 v[14:15], v[20:21], s[48:49] op_sel_hi:[0,1]
	v_pk_fma_f32 v[36:37], v[18:19], s[40:41], v[14:15]
	v_pk_mul_f32 v[14:15], v[16:17], v[36:37] op_sel:[1,1] op_sel_hi:[0,1] neg_hi:[1,0]
	v_pk_add_f32 v[74:75], v[82:83], v[84:85]
	v_pk_fma_f32 v[16:17], v[16:17], v[36:37], v[14:15] op_sel_hi:[1,0,1]
	v_pk_mul_f32 v[14:15], v[20:21], v[34:35] op_sel:[0,1] op_sel_hi:[0,0] neg_lo:[0,1]
	v_pk_fma_f32 v[78:79], v[18:19], v[34:35], v[14:15]
	v_pk_mul_f32 v[14:15], v[34:35], v[52:53] op_sel:[1,1] op_sel_hi:[1,0] neg_hi:[0,1]
	v_pk_add_f32 v[76:77], v[12:13], v[86:87]
	v_pk_fma_f32 v[14:15], v[34:35], v[52:53], v[14:15] op_sel_hi:[0,1,1]
	v_pk_mul_f32 v[34:35], v[20:21], v[36:37] op_sel:[0,1] op_sel_hi:[0,0] neg_lo:[0,1]
	v_pk_fma_f32 v[36:37], v[18:19], v[36:37], v[34:35]
	v_pk_mul_f32 v[52:53], v[26:27], v[78:79] op_sel:[1,1] op_sel_hi:[0,1] neg_hi:[1,0]
	v_pk_mul_f32 v[34:35], v[32:33], v[36:37] op_sel:[1,1] op_sel_hi:[0,1] neg_hi:[1,0]
	v_pk_fma_f32 v[26:27], v[26:27], v[78:79], v[52:53] op_sel_hi:[1,0,1]
	v_pk_fma_f32 v[34:35], v[32:33], v[36:37], v[34:35] op_sel_hi:[1,0,1]
	v_pk_mul_f32 v[52:53], v[20:21], v[36:37] op_sel:[0,1] op_sel_hi:[0,0] neg_lo:[0,1]
	v_pk_mul_f32 v[32:33], v[20:21], v[78:79] op_sel:[0,1] op_sel_hi:[0,0] neg_lo:[0,1]
	v_pk_fma_f32 v[52:53], v[18:19], v[36:37], v[52:53]
	v_pk_fma_f32 v[32:33], v[18:19], v[78:79], v[32:33]
	v_pk_mul_f32 v[36:37], v[42:43], v[52:53] op_sel:[1,1] op_sel_hi:[0,1] neg_hi:[1,0]
	v_pk_fma_f32 v[36:37], v[42:43], v[52:53], v[36:37] op_sel_hi:[1,0,1]
	v_pk_mul_f32 v[42:43], v[20:21], v[32:33] op_sel:[0,1] op_sel_hi:[0,0] neg_lo:[0,1]
	v_pk_mul_f32 v[78:79], v[74:75], v[32:33] op_sel:[1,1] op_sel_hi:[0,1] neg_hi:[1,0]
	v_pk_fma_f32 v[42:43], v[18:19], v[32:33], v[42:43]
	v_pk_fma_f32 v[32:33], v[74:75], v[32:33], v[78:79] op_sel_hi:[1,0,1]
	v_pk_mul_f32 v[74:75], v[20:21], v[52:53] op_sel:[0,1] op_sel_hi:[0,0] neg_lo:[0,1]
	v_pk_fma_f32 v[52:53], v[18:19], v[52:53], v[74:75]
	v_pk_mul_f32 v[74:75], v[48:49], v[52:53] op_sel:[1,1] op_sel_hi:[0,1] neg_hi:[1,0]
	v_pk_fma_f32 v[48:49], v[48:49], v[52:53], v[74:75] op_sel_hi:[1,0,1]
	v_pk_mul_f32 v[74:75], v[20:21], v[42:43] op_sel:[0,1] op_sel_hi:[0,0] neg_lo:[0,1]
	v_pk_mul_f32 v[78:79], v[50:51], v[42:43] op_sel:[1,1] op_sel_hi:[0,1] neg_hi:[1,0]
	v_pk_fma_f32 v[74:75], v[18:19], v[42:43], v[74:75]
	v_pk_fma_f32 v[42:43], v[50:51], v[42:43], v[78:79] op_sel_hi:[1,0,1]
	v_pk_mul_f32 v[50:51], v[20:21], v[52:53] op_sel:[0,1] op_sel_hi:[0,0] neg_lo:[0,1]
	v_pk_fma_f32 v[78:79], v[18:19], v[52:53], v[50:51]
	v_pk_mul_f32 v[50:51], v[60:61], v[78:79] op_sel:[1,1] op_sel_hi:[0,1] neg_hi:[1,0]
	v_xor_b32_e32 v81, 0x80000000, v58
	v_pk_fma_f32 v[52:53], v[60:61], v[78:79], v[50:51] op_sel_hi:[1,0,1]
	v_pk_mul_f32 v[50:51], v[20:21], v[74:75] op_sel:[0,1] op_sel_hi:[0,0] neg_lo:[0,1]
	v_pk_fma_f32 v[60:61], v[18:19], v[74:75], v[50:51]
	v_pk_mul_f32 v[50:51], v[72:73], v[74:75] op_sel:[1,1] op_sel_hi:[0,1] neg_hi:[1,0]
	v_mov_b32_e32 v80, v59
	v_pk_fma_f32 v[50:51], v[72:73], v[74:75], v[50:51] op_sel_hi:[1,0,1]
	v_pk_mul_f32 v[72:73], v[20:21], v[78:79] op_sel:[0,1] op_sel_hi:[0,0] neg_lo:[0,1]
	v_pk_fma_f32 v[72:73], v[18:19], v[78:79], v[72:73]
	v_pk_mul_f32 v[74:75], v[64:65], v[72:73] op_sel:[1,1] op_sel_hi:[0,1] neg_hi:[1,0]
	v_pk_fma_f32 v[64:65], v[64:65], v[72:73], v[74:75] op_sel_hi:[1,0,1]
	v_pk_mul_f32 v[74:75], v[20:21], v[60:61] op_sel:[0,1] op_sel_hi:[0,0] neg_lo:[0,1]
	v_pk_mul_f32 v[78:79], v[66:67], v[60:61] op_sel:[1,1] op_sel_hi:[0,1] neg_hi:[1,0]
	v_pk_fma_f32 v[74:75], v[18:19], v[60:61], v[74:75]
	v_pk_fma_f32 v[60:61], v[66:67], v[60:61], v[78:79] op_sel_hi:[1,0,1]
	v_pk_mul_f32 v[66:67], v[20:21], v[72:73] op_sel:[0,1] op_sel_hi:[0,0] neg_lo:[0,1]
	v_pk_fma_f32 v[66:67], v[18:19], v[72:73], v[66:67]
	v_pk_mul_f32 v[72:73], v[62:63], v[66:67] op_sel:[1,1] op_sel_hi:[0,1] neg_hi:[1,0]
	v_pk_fma_f32 v[62:63], v[62:63], v[66:67], v[72:73] op_sel_hi:[1,0,1]
	v_pk_mul_f32 v[72:73], v[20:21], v[74:75] op_sel:[0,1] op_sel_hi:[0,0] neg_lo:[0,1]
	v_pk_mul_f32 v[78:79], v[76:77], v[74:75] op_sel:[1,1] op_sel_hi:[0,1] neg_hi:[1,0]
	v_pk_fma_f32 v[72:73], v[18:19], v[74:75], v[72:73]
	v_pk_fma_f32 v[74:75], v[76:77], v[74:75], v[78:79] op_sel_hi:[1,0,1]
	v_pk_mul_f32 v[76:77], v[20:21], v[66:67] op_sel:[0,1] op_sel_hi:[0,0] neg_lo:[0,1]
	v_pk_fma_f32 v[66:67], v[18:19], v[66:67], v[76:77]
	v_pk_mul_f32 v[78:79], v[20:21], v[72:73] op_sel:[0,1] op_sel_hi:[0,0] neg_lo:[0,1]
	v_pk_mul_f32 v[80:81], v[80:81], v[72:73] op_sel:[0,1]
	v_pk_fma_f32 v[78:79], v[18:19], v[72:73], v[78:79]
	v_pk_fma_f32 v[58:59], v[58:59], v[72:73], v[80:81] op_sel_hi:[1,0,1]
	v_pk_mul_f32 v[76:77], v[88:89], v[66:67] op_sel:[1,1] op_sel_hi:[0,1] neg_hi:[1,0]
	v_pk_mul_f32 v[72:73], v[20:21], v[66:67] op_sel:[0,1] op_sel_hi:[0,0] neg_lo:[0,1]
	v_pk_fma_f32 v[76:77], v[88:89], v[66:67], v[76:77] op_sel_hi:[1,0,1]
	v_pk_fma_f32 v[66:67], v[18:19], v[66:67], v[72:73]
	v_pk_mul_f32 v[72:73], v[54:55], v[66:67] op_sel:[1,1] op_sel_hi:[0,1] neg_hi:[1,0]
	v_pk_fma_f32 v[54:55], v[54:55], v[66:67], v[72:73] op_sel_hi:[1,0,1]
	v_pk_mul_f32 v[72:73], v[20:21], v[78:79] op_sel:[0,1] op_sel_hi:[0,0] neg_lo:[0,1]
	v_pk_mul_f32 v[80:81], v[56:57], v[78:79] op_sel:[1,1] op_sel_hi:[0,1] neg_hi:[1,0]
	v_pk_fma_f32 v[72:73], v[18:19], v[78:79], v[72:73]
	v_pk_fma_f32 v[56:57], v[56:57], v[78:79], v[80:81] op_sel_hi:[1,0,1]
	v_pk_mul_f32 v[78:79], v[20:21], v[66:67] op_sel:[0,1] op_sel_hi:[0,0] neg_lo:[0,1]
	v_pk_fma_f32 v[66:67], v[18:19], v[66:67], v[78:79]
	v_pk_mul_f32 v[78:79], v[40:41], v[66:67] op_sel:[1,1] op_sel_hi:[0,1] neg_hi:[1,0]
	v_pk_fma_f32 v[40:41], v[40:41], v[66:67], v[78:79] op_sel_hi:[1,0,1]
	v_pk_mul_f32 v[78:79], v[20:21], v[72:73] op_sel:[0,1] op_sel_hi:[0,0] neg_lo:[0,1]
	v_pk_mul_f32 v[80:81], v[46:47], v[72:73] op_sel:[1,1] op_sel_hi:[0,1] neg_hi:[1,0]
	v_pk_fma_f32 v[78:79], v[18:19], v[72:73], v[78:79]
	v_pk_fma_f32 v[46:47], v[46:47], v[72:73], v[80:81] op_sel_hi:[1,0,1]
	v_pk_mul_f32 v[72:73], v[20:21], v[66:67] op_sel:[0,1] op_sel_hi:[0,0] neg_lo:[0,1]
	v_pk_fma_f32 v[66:67], v[18:19], v[66:67], v[72:73]
	v_pk_add_f32 v[44:45], v[82:83], v[84:85] neg_lo:[0,1] neg_hi:[0,1]
	v_pk_mul_f32 v[72:73], v[38:39], v[66:67] op_sel:[1,1] op_sel_hi:[0,1] neg_hi:[1,0]
	v_pk_fma_f32 v[38:39], v[38:39], v[66:67], v[72:73] op_sel_hi:[1,0,1]
	v_pk_mul_f32 v[72:73], v[20:21], v[78:79] op_sel:[0,1] op_sel_hi:[0,0] neg_lo:[0,1]
	v_pk_mul_f32 v[80:81], v[44:45], v[78:79] op_sel:[1,1] op_sel_hi:[0,1] neg_hi:[1,0]
	v_pk_fma_f32 v[72:73], v[18:19], v[78:79], v[72:73]
	v_pk_fma_f32 v[44:45], v[44:45], v[78:79], v[80:81] op_sel_hi:[1,0,1]
	v_pk_mul_f32 v[78:79], v[20:21], v[66:67] op_sel:[0,1] op_sel_hi:[0,0] neg_lo:[0,1]
	v_pk_fma_f32 v[66:67], v[18:19], v[66:67], v[78:79]
	v_pk_mul_f32 v[78:79], v[28:29], v[66:67] op_sel:[1,1] op_sel_hi:[0,1] neg_hi:[1,0]
	v_pk_fma_f32 v[28:29], v[28:29], v[66:67], v[78:79] op_sel_hi:[1,0,1]
	v_pk_mul_f32 v[78:79], v[20:21], v[72:73] op_sel:[0,1] op_sel_hi:[0,0] neg_lo:[0,1]
	v_pk_mul_f32 v[80:81], v[30:31], v[72:73] op_sel:[1,1] op_sel_hi:[0,1] neg_hi:[1,0]
	v_pk_fma_f32 v[78:79], v[18:19], v[72:73], v[78:79]
	v_pk_fma_f32 v[30:31], v[30:31], v[72:73], v[80:81] op_sel_hi:[1,0,1]
	v_pk_mul_f32 v[72:73], v[20:21], v[66:67] op_sel:[0,1] op_sel_hi:[0,0] neg_lo:[0,1]
	v_pk_fma_f32 v[66:67], v[18:19], v[66:67], v[72:73]
	v_pk_mul_f32 v[72:73], v[22:23], v[66:67] op_sel:[1,1] op_sel_hi:[0,1] neg_hi:[1,0]
	v_pk_fma_f32 v[22:23], v[22:23], v[66:67], v[72:73] op_sel_hi:[1,0,1]
	v_pk_mul_f32 v[72:73], v[20:21], v[78:79] op_sel:[0,1] op_sel_hi:[0,0] neg_lo:[0,1]
	v_pk_mul_f32 v[80:81], v[24:25], v[78:79] op_sel:[1,1] op_sel_hi:[0,1] neg_hi:[1,0]
	v_pk_fma_f32 v[72:73], v[18:19], v[78:79], v[72:73]
	v_pk_fma_f32 v[24:25], v[24:25], v[78:79], v[80:81] op_sel_hi:[1,0,1]
	v_pk_mul_f32 v[78:79], v[20:21], v[66:67] op_sel:[0,1] op_sel_hi:[0,0] neg_lo:[0,1]
	v_pk_fma_f32 v[66:67], v[18:19], v[66:67], v[78:79]
	v_pk_mul_f32 v[78:79], v[6:7], v[66:67] op_sel:[1,1] op_sel_hi:[0,1] neg_hi:[1,0]
	v_pk_fma_f32 v[6:7], v[6:7], v[66:67], v[78:79] op_sel_hi:[1,0,1]
	v_pk_mul_f32 v[78:79], v[20:21], v[72:73] op_sel:[0,1] op_sel_hi:[0,0] neg_lo:[0,1]
	v_pk_mul_f32 v[80:81], v[10:11], v[72:73] op_sel:[1,1] op_sel_hi:[0,1] neg_hi:[1,0]
	v_pk_fma_f32 v[78:79], v[18:19], v[72:73], v[78:79]
	v_pk_fma_f32 v[10:11], v[10:11], v[72:73], v[80:81] op_sel_hi:[1,0,1]
	v_pk_mul_f32 v[72:73], v[20:21], v[66:67] op_sel:[0,1] op_sel_hi:[0,0] neg_lo:[0,1]
	v_pk_fma_f32 v[18:19], v[18:19], v[66:67], v[72:73]
	v_pk_add_f32 v[12:13], v[12:13], v[86:87] neg_lo:[0,1] neg_hi:[0,1]
	v_pk_mul_f32 v[66:67], v[4:5], v[18:19] op_sel:[1,1] op_sel_hi:[0,1] neg_hi:[1,0]
	v_pk_fma_f32 v[4:5], v[4:5], v[18:19], v[66:67] op_sel_hi:[1,0,1]
	v_pk_mul_f32 v[18:19], v[12:13], v[78:79] op_sel:[1,1] op_sel_hi:[0,1] neg_hi:[1,0]
	s_nop 0
	v_pk_fma_f32 v[12:13], v[12:13], v[78:79], v[18:19] op_sel_hi:[1,0,1]
	v_lshrrev_b32_e32 v18, 5, v21
	v_bitop3_b32 v18, v18, v21, 15 bitop3:0x6c
	v_lshlrev_b32_e32 v18, 3, v18
	v_bfe_u32 v19, v21, 5, 4
	v_add_u32_e32 v20, 16, v18
	ds_write_b64 v20, v[2:3]
	v_bitop3_b32 v2, v19, v21, 16 bitop3:0x36
	v_lshl_add_u32 v2, v2, 3, 16
	v_add_u32_e32 v3, s47, v18
	ds_write_b64 v2, v[76:77] offset:4096
	ds_write_b64 v20, v[48:49] offset:8192
	ds_write_b64 v2, v[28:29] offset:12288
	ds_write_b64 v20, v[34:35] offset:16384
	ds_write_b64 v2, v[40:41] offset:20480
	ds_write_b64 v20, v[64:65] offset:24576
	ds_write_b64 v2, v[6:7] offset:28672
	ds_write_b64 v20, v[16:17] offset:32768
	ds_write_b64 v2, v[54:55] offset:36864
	ds_write_b64 v20, v[52:53] offset:40960
	ds_write_b64 v2, v[22:23] offset:45056
	ds_write_b64 v20, v[36:37] offset:49152
	ds_write_b64 v2, v[38:39] offset:53248
	ds_write_b64 v20, v[62:63] offset:57344
	ds_write_b64 v2, v[4:5] offset:61440
	ds_write_b64 v3, v[8:9]
	v_add_u32_e32 v3, 0x11000, v2
	ds_write_b64 v3, v[58:59]
	v_add_u32_e32 v3, 0x12000, v20
	ds_write_b64 v3, v[42:43]
	v_add_u32_e32 v3, 0x13000, v2
	ds_write_b64 v3, v[30:31]
	v_add_u32_e32 v3, 0x14000, v20
	ds_write_b64 v3, v[26:27]
	v_add_u32_e32 v3, 0x15000, v2
	ds_write_b64 v3, v[46:47]
	v_add_u32_e32 v3, 0x16000, v20
	ds_write_b64 v3, v[60:61]
	v_add_u32_e32 v3, 0x17000, v2
	ds_write_b64 v3, v[10:11]
	v_add_u32_e32 v3, 0x18000, v20
	ds_write_b64 v3, v[14:15]
	v_add_u32_e32 v3, 0x19000, v2
	ds_write_b64 v3, v[56:57]
	v_add_u32_e32 v3, 0x1a000, v20
	ds_write_b64 v3, v[50:51]
	v_add_u32_e32 v3, 0x1b000, v2
	ds_write_b64 v3, v[24:25]
	v_add_u32_e32 v3, 0x1c000, v20
	ds_write_b64 v3, v[32:33]
	v_add_u32_e32 v3, 0x1d000, v2
	ds_write_b64 v3, v[44:45]
	v_add_u32_e32 v3, 0x1e000, v20
	v_add_u32_e32 v2, 0x1f000, v2
	v_mov_b32_e32 v11, v146
	ds_write_b64 v3, v[74:75]
	ds_write_b64 v2, v[12:13]
	s_waitcnt lgkmcnt(0)
	s_barrier
	s_nop 0
	v_lshlrev_b32_e32 v2, 5, v11
	v_and_b32_e32 v2, 0xfffffe00, v2
	v_and_or_b32 v3, v11, 16, v2
	v_bitop3_b32 v2, v2, 16, v11 bitop3:0x34
	v_bitop3_b32 v12, v11, 2, 15 bitop3:0x6c
	v_bitop3_b32 v22, v11, 4, 15 bitop3:0x6c
	v_bitop3_b32 v30, v11, 6, 15 bitop3:0x6c
	v_bitop3_b32 v38, v11, 8, 15 bitop3:0x6c
	v_and_b32_e32 v10, 15, v11
	v_lshl_add_u32 v18, v3, 3, 16
	v_lshl_add_u32 v87, v2, 3, 16
	v_lshlrev_b32_e32 v12, 3, v12
	v_lshlrev_b32_e32 v22, 3, v22
	v_lshlrev_b32_e32 v30, 3, v30
	v_lshlrev_b32_e32 v38, 3, v38
	v_lshlrev_b32_e32 v3, 3, v10
	v_bitop3_b32 v2, v11, 1, 15 bitop3:0x6c
	v_add_u32_e32 v57, v18, v12
	v_add_u32_e32 v58, v87, v12
	v_bitop3_b32 v12, v11, 3, 15 bitop3:0x6c
	v_add_u32_e32 v61, v18, v22
	v_add_u32_e32 v62, v87, v22
	v_bitop3_b32 v22, v11, 5, 15 bitop3:0x6c
	v_add_u32_e32 v65, v18, v30
	v_add_u32_e32 v66, v87, v30
	v_bitop3_b32 v30, v11, 7, 15 bitop3:0x6c
	v_add_u32_e32 v72, v18, v38
	v_add_u32_e32 v73, v87, v38
	v_bitop3_b32 v38, v11, 9, 15 bitop3:0x6c
	v_add_u32_e32 v19, v18, v3
	v_lshlrev_b32_e32 v2, 3, v2
	v_lshlrev_b32_e32 v12, 3, v12
	v_lshlrev_b32_e32 v22, 3, v22
	v_lshlrev_b32_e32 v30, 3, v30
	v_lshlrev_b32_e32 v38, 3, v38
	v_add_u32_e32 v54, v87, v3
	v_add_u32_e32 v55, v18, v2
	v_add_u32_e32 v56, v87, v2
	ds_read_b64 v[2:3], v19
	ds_read_b64 v[4:5], v54
	ds_read_b64 v[6:7], v55 offset:256
	ds_read_b64 v[8:9], v56 offset:256
	v_add_u32_e32 v59, v18, v12
	v_add_u32_e32 v60, v87, v12
	ds_read_b64 v[12:13], v57 offset:512
	ds_read_b64 v[14:15], v58 offset:512
	ds_read_b64 v[16:17], v59 offset:768
	ds_read_b64 v[20:21], v60 offset:768
	v_add_u32_e32 v63, v18, v22
	v_add_u32_e32 v64, v87, v22
	ds_read_b64 v[22:23], v61 offset:1024
	ds_read_b64 v[24:25], v62 offset:1024
	ds_read_b64 v[26:27], v63 offset:1280
	ds_read_b64 v[28:29], v64 offset:1280
	v_add_u32_e32 v67, v18, v30
	v_add_u32_e32 v71, v87, v30
	ds_read_b64 v[30:31], v65 offset:1536
	ds_read_b64 v[32:33], v66 offset:1536
	ds_read_b64 v[34:35], v67 offset:1792
	ds_read_b64 v[36:37], v71 offset:1792
	v_add_u32_e32 v74, v18, v38
	v_add_u32_e32 v75, v87, v38
	ds_read_b64 v[38:39], v72 offset:2048
	ds_read_b64 v[40:41], v73 offset:2048
	ds_read_b64 v[42:43], v74 offset:2304
	ds_read_b64 v[44:45], v75 offset:2304
	v_bitop3_b32 v46, v11, 10, 15 bitop3:0x6c
	s_waitcnt lgkmcnt(3)
	v_pk_add_f32 v[104:105], v[2:3], v[38:39]
	v_pk_add_f32 v[2:3], v[2:3], v[38:39] neg_lo:[0,1] neg_hi:[0,1]
	s_waitcnt lgkmcnt(2)
	v_pk_add_f32 v[38:39], v[4:5], v[40:41]
	v_pk_add_f32 v[4:5], v[4:5], v[40:41] neg_lo:[0,1] neg_hi:[0,1]
	v_lshlrev_b32_e32 v46, 3, v46
	v_pk_mul_f32 v[40:41], v[4:5], s[58:59] op_sel:[1,0] op_sel_hi:[0,0] neg_hi:[1,0]
	v_add_u32_e32 v76, v18, v46
	v_pk_fma_f32 v[4:5], v[4:5], s[46:47], v[40:41] op_sel_hi:[1,0,1]
	s_waitcnt lgkmcnt(1)
	v_pk_add_f32 v[40:41], v[6:7], v[42:43]
	v_pk_add_f32 v[6:7], v[6:7], v[42:43] neg_lo:[0,1] neg_hi:[0,1]
	v_add_u32_e32 v77, v87, v46
	v_bitop3_b32 v46, v11, 11, 15 bitop3:0x6c
	v_pk_mul_f32 v[42:43], v[6:7], s[62:63] op_sel:[1,0] op_sel_hi:[0,0] neg_hi:[1,0]
	v_lshlrev_b32_e32 v46, 3, v46
	v_pk_fma_f32 v[6:7], v[6:7], s[60:61], v[42:43] op_sel_hi:[1,0,1]
	s_waitcnt lgkmcnt(0)
	v_pk_add_f32 v[42:43], v[8:9], v[44:45]
	v_pk_add_f32 v[8:9], v[8:9], v[44:45] neg_lo:[0,1] neg_hi:[0,1]
	v_add_u32_e32 v78, v18, v46
	v_add_u32_e32 v79, v87, v46
	ds_read_b64 v[46:47], v76 offset:2560
	ds_read_b64 v[48:49], v77 offset:2560
	ds_read_b64 v[50:51], v78 offset:2816
	ds_read_b64 v[52:53], v79 offset:2816
	v_pk_mul_f32 v[44:45], v[8:9], s[66:67] op_sel:[1,0] op_sel_hi:[0,0] neg_hi:[1,0]
	v_bitop3_b32 v80, v11, 12, 15 bitop3:0x6c
	v_pk_fma_f32 v[8:9], v[8:9], s[64:65], v[44:45] op_sel_hi:[1,0,1]
	s_waitcnt lgkmcnt(3)
	v_pk_add_f32 v[44:45], v[12:13], v[46:47]
	v_pk_add_f32 v[12:13], v[12:13], v[46:47] neg_lo:[0,1] neg_hi:[0,1]
	v_lshlrev_b32_e32 v81, 3, v80
	v_pk_mul_f32 v[46:47], v[12:13], s[70:71] op_sel:[1,0] op_sel_hi:[0,0] neg_hi:[1,0]
	v_bitop3_b32 v82, v11, 13, 15 bitop3:0x6c
	v_pk_fma_f32 v[12:13], v[12:13], s[70:71], v[46:47] op_sel_hi:[1,0,1]
	s_waitcnt lgkmcnt(2)
	v_pk_add_f32 v[46:47], v[14:15], v[48:49]
	v_pk_add_f32 v[14:15], v[14:15], v[48:49] neg_lo:[0,1] neg_hi:[0,1]
	v_add_u32_e32 v80, v18, v81
	v_pk_mul_f32 v[48:49], v[14:15], s[64:65] op_sel:[1,0] op_sel_hi:[0,0] neg_hi:[1,0]
	v_lshlrev_b32_e32 v83, 3, v82
	v_pk_fma_f32 v[14:15], v[14:15], s[66:67], v[48:49] op_sel_hi:[1,0,1]
	s_waitcnt lgkmcnt(1)
	v_pk_add_f32 v[48:49], v[16:17], v[50:51]
	v_pk_add_f32 v[16:17], v[16:17], v[50:51] neg_lo:[0,1] neg_hi:[0,1]
	v_add_u32_e32 v81, v87, v81
	v_pk_mul_f32 v[50:51], v[16:17], s[60:61] op_sel:[1,0] op_sel_hi:[0,0] neg_hi:[1,0]
	v_add_u32_e32 v82, v18, v83
	v_pk_fma_f32 v[16:17], v[16:17], s[62:63], v[50:51] op_sel_hi:[1,0,1]
	s_waitcnt lgkmcnt(0)
	v_pk_add_f32 v[50:51], v[20:21], v[52:53]
	v_pk_add_f32 v[20:21], v[20:21], v[52:53] neg_lo:[0,1] neg_hi:[0,1]
	v_add_u32_e32 v83, v87, v83
	ds_read_b64 v[88:89], v80 offset:3072
	ds_read_b64 v[90:91], v81 offset:3072
	ds_read_b64 v[92:93], v82 offset:3328
	ds_read_b64 v[94:95], v83 offset:3328
	v_pk_mul_f32 v[52:53], v[20:21], s[46:47] op_sel:[1,0] op_sel_hi:[0,0] neg_hi:[1,0]
	v_bitop3_b32 v84, v11, 14, 15 bitop3:0x6c
	v_pk_fma_f32 v[20:21], v[20:21], s[58:59], v[52:53] op_sel_hi:[1,0,1]
	s_waitcnt lgkmcnt(3)
	v_pk_add_f32 v[52:53], v[22:23], v[88:89]
	v_pk_add_f32 v[22:23], v[22:23], v[88:89] neg_lo:[0,1] neg_hi:[0,1]
	v_lshlrev_b32_e32 v85, 3, v84
	v_xor_b32_e32 v89, 0x80000000, v22
	v_mov_b32_e32 v88, v23
	s_waitcnt lgkmcnt(2)
	v_pk_add_f32 v[22:23], v[24:25], v[90:91]
	v_pk_add_f32 v[24:25], v[24:25], v[90:91] neg_lo:[0,1] neg_hi:[0,1]
	v_bitop3_b32 v11, v11, 15, v11 bitop3:0xc
	v_pk_mul_f32 v[90:91], v[24:25], s[58:59] op_sel_hi:[1,0]
	v_xor_b32_e32 v107, 0x80000000, v24
	v_mov_b32_e32 v106, v25
	v_pk_fma_f32 v[24:25], v[106:107], s[46:47], v[90:91] op_sel_hi:[1,0,1] neg_lo:[0,0,1] neg_hi:[0,0,1]
	s_waitcnt lgkmcnt(1)
	v_pk_add_f32 v[90:91], v[26:27], v[92:93]
	v_pk_add_f32 v[26:27], v[26:27], v[92:93] neg_lo:[0,1] neg_hi:[0,1]
	v_add_u32_e32 v84, v18, v85
	v_lshlrev_b32_e32 v11, 3, v11
	v_pk_mul_f32 v[92:93], v[26:27], s[62:63] op_sel_hi:[1,0]
	v_xor_b32_e32 v107, 0x80000000, v26
	v_mov_b32_e32 v106, v27
	v_add_u32_e32 v85, v87, v85
	v_add_u32_e32 v86, v18, v11
	v_add_u32_e32 v87, v87, v11
	ds_read_b64 v[96:97], v84 offset:3584
	ds_read_b64 v[98:99], v85 offset:3584
	ds_read_b64 v[100:101], v86 offset:3840
	ds_read_b64 v[102:103], v87 offset:3840
	v_pk_fma_f32 v[26:27], v[106:107], s[60:61], v[92:93] op_sel_hi:[1,0,1] neg_lo:[0,0,1] neg_hi:[0,0,1]
	s_waitcnt lgkmcnt(4)
	v_pk_add_f32 v[92:93], v[28:29], v[94:95]
	v_pk_add_f32 v[28:29], v[28:29], v[94:95] neg_lo:[0,1] neg_hi:[0,1]
	s_nop 0
	v_pk_mul_f32 v[94:95], v[28:29], s[66:67] op_sel_hi:[1,0]
	v_xor_b32_e32 v107, 0x80000000, v28
	v_mov_b32_e32 v106, v29
	v_pk_fma_f32 v[28:29], v[106:107], s[64:65], v[94:95] op_sel_hi:[1,0,1] neg_lo:[0,0,1] neg_hi:[0,0,1]
	s_waitcnt lgkmcnt(3)
	v_pk_add_f32 v[94:95], v[30:31], v[96:97]
	v_pk_add_f32 v[30:31], v[30:31], v[96:97] neg_lo:[0,1] neg_hi:[0,1]
	v_cvt_f32_i32_e32 v10, v10
	v_pk_mul_f32 v[96:97], v[30:31], s[70:71] op_sel_hi:[1,0]
	v_xor_b32_e32 v107, 0x80000000, v30
	v_mov_b32_e32 v106, v31
	v_pk_fma_f32 v[30:31], v[106:107], s[70:71], v[96:97] op_sel_hi:[1,0,1] neg_lo:[0,0,1] neg_hi:[0,0,1]
	s_waitcnt lgkmcnt(2)
	v_pk_add_f32 v[96:97], v[32:33], v[98:99]
	v_pk_add_f32 v[32:33], v[32:33], v[98:99] neg_lo:[0,1] neg_hi:[0,1]
	v_mul_f32_e32 v10, 0x3b000000, v10
	v_pk_mul_f32 v[98:99], v[32:33], s[64:65] op_sel_hi:[1,0]
	v_xor_b32_e32 v107, 0x80000000, v32
	v_mov_b32_e32 v106, v33
	v_pk_fma_f32 v[32:33], v[106:107], s[66:67], v[98:99] op_sel_hi:[1,0,1] neg_lo:[0,0,1] neg_hi:[0,0,1]
	s_waitcnt lgkmcnt(1)
	v_pk_add_f32 v[98:99], v[34:35], v[100:101]
	v_pk_add_f32 v[34:35], v[34:35], v[100:101] neg_lo:[0,1] neg_hi:[0,1]
	s_nop 0
	v_pk_mul_f32 v[100:101], v[34:35], s[60:61] op_sel_hi:[1,0]
	v_xor_b32_e32 v107, 0x80000000, v34
	v_mov_b32_e32 v106, v35
	v_pk_fma_f32 v[34:35], v[106:107], s[62:63], v[100:101] op_sel_hi:[1,0,1] neg_lo:[0,0,1] neg_hi:[0,0,1]
	s_waitcnt lgkmcnt(0)
	v_pk_add_f32 v[100:101], v[36:37], v[102:103]
	v_pk_add_f32 v[36:37], v[36:37], v[102:103] neg_lo:[0,1] neg_hi:[0,1]
	s_nop 0
	v_pk_mul_f32 v[102:103], v[36:37], s[46:47] op_sel_hi:[1,0]
	v_xor_b32_e32 v107, 0x80000000, v36
	v_mov_b32_e32 v106, v37
	v_pk_fma_f32 v[36:37], v[106:107], s[58:59], v[102:103] op_sel_hi:[1,0,1] neg_lo:[0,0,1] neg_hi:[0,0,1]
	v_pk_add_f32 v[102:103], v[104:105], v[52:53]
	v_pk_add_f32 v[52:53], v[104:105], v[52:53] neg_lo:[0,1] neg_hi:[0,1]
	v_pk_add_f32 v[104:105], v[38:39], v[22:23]
	v_pk_add_f32 v[22:23], v[38:39], v[22:23] neg_lo:[0,1] neg_hi:[0,1]
	v_pk_mul_f32 v[38:39], v[22:23], s[62:63] op_sel:[1,0] op_sel_hi:[0,0] neg_hi:[1,0]
	v_pk_fma_f32 v[22:23], v[22:23], s[60:61], v[38:39] op_sel_hi:[1,0,1]
	v_pk_add_f32 v[38:39], v[40:41], v[90:91]
	v_pk_add_f32 v[40:41], v[40:41], v[90:91] neg_lo:[0,1] neg_hi:[0,1]
	v_pk_mul_f32 v[90:91], v[40:41], s[70:71] op_sel:[1,0] op_sel_hi:[0,0] neg_hi:[1,0]
	v_pk_fma_f32 v[40:41], v[40:41], s[70:71], v[90:91] op_sel_hi:[1,0,1]
	v_pk_add_f32 v[90:91], v[42:43], v[92:93]
	v_pk_add_f32 v[42:43], v[42:43], v[92:93] neg_lo:[0,1] neg_hi:[0,1]
	v_pk_mul_f32 v[92:93], v[42:43], s[60:61] op_sel:[1,0] op_sel_hi:[0,0] neg_hi:[1,0]
	v_pk_fma_f32 v[42:43], v[42:43], s[62:63], v[92:93] op_sel_hi:[1,0,1]
	v_pk_add_f32 v[92:93], v[44:45], v[94:95]
	v_pk_add_f32 v[44:45], v[44:45], v[94:95] neg_lo:[0,1] neg_hi:[0,1]
	v_xor_b32_e32 v95, 0x80000000, v44
	v_mov_b32_e32 v94, v45
	v_pk_add_f32 v[44:45], v[46:47], v[96:97]
	v_pk_add_f32 v[46:47], v[46:47], v[96:97] neg_lo:[0,1] neg_hi:[0,1]
	v_pk_mul_f32 v[96:97], v[46:47], s[62:63] op_sel_hi:[1,0]
	v_xor_b32_e32 v107, 0x80000000, v46
	v_mov_b32_e32 v106, v47
	v_pk_fma_f32 v[46:47], v[106:107], s[60:61], v[96:97] op_sel_hi:[1,0,1] neg_lo:[0,0,1] neg_hi:[0,0,1]
	v_pk_add_f32 v[96:97], v[48:49], v[98:99]
	v_pk_add_f32 v[48:49], v[48:49], v[98:99] neg_lo:[0,1] neg_hi:[0,1]
	v_pk_mul_f32 v[98:99], v[48:49], s[70:71] op_sel_hi:[1,0]
	v_xor_b32_e32 v107, 0x80000000, v48
	v_mov_b32_e32 v106, v49
	v_pk_fma_f32 v[48:49], v[106:107], s[70:71], v[98:99] op_sel_hi:[1,0,1] neg_lo:[0,0,1] neg_hi:[0,0,1]
	v_pk_add_f32 v[98:99], v[50:51], v[100:101]
	v_pk_add_f32 v[50:51], v[50:51], v[100:101] neg_lo:[0,1] neg_hi:[0,1]
	v_pk_mul_f32 v[100:101], v[50:51], s[60:61] op_sel_hi:[1,0]
	v_xor_b32_e32 v107, 0x80000000, v50
	v_mov_b32_e32 v106, v51
	v_pk_fma_f32 v[50:51], v[106:107], s[62:63], v[100:101] op_sel_hi:[1,0,1] neg_lo:[0,0,1] neg_hi:[0,0,1]
	v_pk_add_f32 v[100:101], v[2:3], v[88:89]
	v_pk_add_f32 v[2:3], v[2:3], v[88:89] neg_lo:[0,1] neg_hi:[0,1]
	v_pk_add_f32 v[88:89], v[4:5], v[24:25]
	v_pk_add_f32 v[4:5], v[4:5], v[24:25] neg_lo:[0,1] neg_hi:[0,1]
	v_pk_mul_f32 v[24:25], v[4:5], s[62:63] op_sel:[1,0] op_sel_hi:[0,0] neg_hi:[1,0]
	v_pk_fma_f32 v[4:5], v[4:5], s[60:61], v[24:25] op_sel_hi:[1,0,1]
	v_pk_add_f32 v[24:25], v[6:7], v[26:27]
	v_pk_add_f32 v[6:7], v[6:7], v[26:27] neg_lo:[0,1] neg_hi:[0,1]
	v_pk_mul_f32 v[26:27], v[6:7], s[70:71] op_sel:[1,0] op_sel_hi:[0,0] neg_hi:[1,0]
	v_pk_fma_f32 v[6:7], v[6:7], s[70:71], v[26:27] op_sel_hi:[1,0,1]
	v_pk_add_f32 v[26:27], v[8:9], v[28:29]
	v_pk_add_f32 v[8:9], v[8:9], v[28:29] neg_lo:[0,1] neg_hi:[0,1]
	v_pk_mul_f32 v[28:29], v[8:9], s[60:61] op_sel:[1,0] op_sel_hi:[0,0] neg_hi:[1,0]
	v_pk_fma_f32 v[8:9], v[8:9], s[62:63], v[28:29] op_sel_hi:[1,0,1]
	v_pk_add_f32 v[28:29], v[12:13], v[30:31]
	v_pk_add_f32 v[12:13], v[12:13], v[30:31] neg_lo:[0,1] neg_hi:[0,1]
	v_xor_b32_e32 v31, 0x80000000, v12
	v_mov_b32_e32 v30, v13
	v_pk_add_f32 v[12:13], v[14:15], v[32:33]
	v_pk_add_f32 v[14:15], v[14:15], v[32:33] neg_lo:[0,1] neg_hi:[0,1]
	v_pk_mul_f32 v[32:33], v[14:15], s[62:63] op_sel_hi:[1,0]
	v_xor_b32_e32 v107, 0x80000000, v14
	v_mov_b32_e32 v106, v15
	v_pk_fma_f32 v[14:15], v[106:107], s[60:61], v[32:33] op_sel_hi:[1,0,1] neg_lo:[0,0,1] neg_hi:[0,0,1]
	v_pk_add_f32 v[32:33], v[16:17], v[34:35]
	v_pk_add_f32 v[16:17], v[16:17], v[34:35] neg_lo:[0,1] neg_hi:[0,1]
	v_pk_mul_f32 v[34:35], v[16:17], s[70:71] op_sel_hi:[1,0]
	v_xor_b32_e32 v107, 0x80000000, v16
	v_mov_b32_e32 v106, v17
	v_pk_fma_f32 v[16:17], v[106:107], s[70:71], v[34:35] op_sel_hi:[1,0,1] neg_lo:[0,0,1] neg_hi:[0,0,1]
	v_pk_add_f32 v[34:35], v[20:21], v[36:37]
	v_pk_add_f32 v[20:21], v[20:21], v[36:37] neg_lo:[0,1] neg_hi:[0,1]
	v_pk_mul_f32 v[36:37], v[20:21], s[60:61] op_sel_hi:[1,0]
	v_xor_b32_e32 v107, 0x80000000, v20
	v_mov_b32_e32 v106, v21
	v_pk_fma_f32 v[20:21], v[106:107], s[62:63], v[36:37] op_sel_hi:[1,0,1] neg_lo:[0,0,1] neg_hi:[0,0,1]
	v_pk_add_f32 v[36:37], v[102:103], v[92:93]
	v_pk_add_f32 v[92:93], v[102:103], v[92:93] neg_lo:[0,1] neg_hi:[0,1]
	v_pk_add_f32 v[102:103], v[104:105], v[44:45]
	v_pk_add_f32 v[44:45], v[104:105], v[44:45] neg_lo:[0,1] neg_hi:[0,1]
	v_pk_mul_f32 v[104:105], v[44:45], s[70:71] op_sel:[1,0] op_sel_hi:[0,0] neg_hi:[1,0]
	v_pk_fma_f32 v[44:45], v[44:45], s[70:71], v[104:105] op_sel_hi:[1,0,1]
	v_pk_add_f32 v[104:105], v[38:39], v[96:97]
	v_pk_add_f32 v[38:39], v[38:39], v[96:97] neg_lo:[0,1] neg_hi:[0,1]
	v_xor_b32_e32 v97, 0x80000000, v38
	v_mov_b32_e32 v96, v39
	v_pk_add_f32 v[38:39], v[90:91], v[98:99]
	v_pk_add_f32 v[90:91], v[90:91], v[98:99] neg_lo:[0,1] neg_hi:[0,1]
	v_pk_mul_f32 v[98:99], v[90:91], s[70:71] op_sel_hi:[1,0]
	v_xor_b32_e32 v107, 0x80000000, v90
	v_mov_b32_e32 v106, v91
	v_pk_fma_f32 v[90:91], v[106:107], s[70:71], v[98:99] op_sel_hi:[1,0,1] neg_lo:[0,0,1] neg_hi:[0,0,1]
	v_pk_add_f32 v[98:99], v[52:53], v[94:95]
	v_pk_add_f32 v[52:53], v[52:53], v[94:95] neg_lo:[0,1] neg_hi:[0,1]
	v_pk_add_f32 v[94:95], v[22:23], v[46:47]
	v_pk_add_f32 v[22:23], v[22:23], v[46:47] neg_lo:[0,1] neg_hi:[0,1]
	v_pk_mul_f32 v[46:47], v[22:23], s[70:71] op_sel:[1,0] op_sel_hi:[0,0] neg_hi:[1,0]
	v_pk_fma_f32 v[22:23], v[22:23], s[70:71], v[46:47] op_sel_hi:[1,0,1]
	v_pk_add_f32 v[46:47], v[40:41], v[48:49]
	v_pk_add_f32 v[40:41], v[40:41], v[48:49] neg_lo:[0,1] neg_hi:[0,1]
	v_xor_b32_e32 v49, 0x80000000, v40
	v_mov_b32_e32 v48, v41
	v_pk_add_f32 v[40:41], v[42:43], v[50:51]
	v_pk_add_f32 v[42:43], v[42:43], v[50:51] neg_lo:[0,1] neg_hi:[0,1]
	v_pk_mul_f32 v[50:51], v[42:43], s[70:71] op_sel_hi:[1,0]
	v_xor_b32_e32 v107, 0x80000000, v42
	v_mov_b32_e32 v106, v43
	v_pk_fma_f32 v[42:43], v[106:107], s[70:71], v[50:51] op_sel_hi:[1,0,1] neg_lo:[0,0,1] neg_hi:[0,0,1]
	v_pk_add_f32 v[50:51], v[100:101], v[28:29]
	v_pk_add_f32 v[28:29], v[100:101], v[28:29] neg_lo:[0,1] neg_hi:[0,1]
	v_pk_add_f32 v[100:101], v[88:89], v[12:13]
	v_pk_add_f32 v[12:13], v[88:89], v[12:13] neg_lo:[0,1] neg_hi:[0,1]
	v_pk_mul_f32 v[88:89], v[12:13], s[70:71] op_sel:[1,0] op_sel_hi:[0,0] neg_hi:[1,0]
	v_pk_fma_f32 v[12:13], v[12:13], s[70:71], v[88:89] op_sel_hi:[1,0,1]
	v_pk_add_f32 v[88:89], v[24:25], v[32:33]
	v_pk_add_f32 v[24:25], v[24:25], v[32:33] neg_lo:[0,1] neg_hi:[0,1]
	v_pk_add_f32 v[108:109], v[50:51], v[88:89]
	v_xor_b32_e32 v33, 0x80000000, v24
	v_mov_b32_e32 v32, v25
	v_pk_add_f32 v[24:25], v[26:27], v[34:35]
	v_pk_add_f32 v[26:27], v[26:27], v[34:35] neg_lo:[0,1] neg_hi:[0,1]
	v_pk_add_f32 v[50:51], v[50:51], v[88:89] neg_lo:[0,1] neg_hi:[0,1]
	v_pk_mul_f32 v[34:35], v[26:27], s[70:71] op_sel_hi:[1,0]
	v_xor_b32_e32 v107, 0x80000000, v26
	v_mov_b32_e32 v106, v27
	v_pk_fma_f32 v[26:27], v[106:107], s[70:71], v[34:35] op_sel_hi:[1,0,1] neg_lo:[0,0,1] neg_hi:[0,0,1]
	v_pk_add_f32 v[34:35], v[2:3], v[30:31]
	v_pk_add_f32 v[2:3], v[2:3], v[30:31] neg_lo:[0,1] neg_hi:[0,1]
	v_pk_add_f32 v[30:31], v[4:5], v[14:15]
	v_pk_add_f32 v[4:5], v[4:5], v[14:15] neg_lo:[0,1] neg_hi:[0,1]
	v_pk_add_f32 v[110:111], v[12:13], v[26:27]
	v_pk_mul_f32 v[14:15], v[4:5], s[70:71] op_sel:[1,0] op_sel_hi:[0,0] neg_hi:[1,0]
	v_pk_add_f32 v[12:13], v[12:13], v[26:27] neg_lo:[0,1] neg_hi:[0,1]
	v_pk_fma_f32 v[4:5], v[4:5], s[70:71], v[14:15] op_sel_hi:[1,0,1]
	v_pk_add_f32 v[14:15], v[6:7], v[16:17]
	v_pk_add_f32 v[6:7], v[6:7], v[16:17] neg_lo:[0,1] neg_hi:[0,1]
	v_pk_add_f32 v[88:89], v[100:101], v[24:25]
	v_xor_b32_e32 v17, 0x80000000, v6
	v_mov_b32_e32 v16, v7
	v_pk_add_f32 v[6:7], v[8:9], v[20:21]
	v_pk_add_f32 v[8:9], v[8:9], v[20:21] neg_lo:[0,1] neg_hi:[0,1]
	v_xor_b32_e32 v113, 0x80000000, v12
	v_pk_mul_f32 v[20:21], v[8:9], s[70:71] op_sel_hi:[1,0]
	v_pk_fma_f32 v[8:9], v[8:9], s[70:71], v[20:21] op_sel:[1,0,0] op_sel_hi:[0,0,1] neg_lo:[0,0,1] neg_hi:[1,0,1]
	v_pk_add_f32 v[20:21], v[36:37], v[104:105]
	v_pk_add_f32 v[36:37], v[36:37], v[104:105] neg_lo:[0,1] neg_hi:[0,1]
	v_pk_add_f32 v[104:105], v[102:103], v[38:39]
	v_pk_add_f32 v[38:39], v[102:103], v[38:39] neg_lo:[0,1] neg_hi:[0,1]
	v_pk_add_f32 v[106:107], v[52:53], v[48:49]
	v_xor_b32_e32 v103, 0x80000000, v38
	v_mov_b32_e32 v102, v39
	v_pk_add_f32 v[38:39], v[92:93], v[96:97]
	v_pk_add_f32 v[92:93], v[92:93], v[96:97] neg_lo:[0,1] neg_hi:[0,1]
	v_pk_add_f32 v[96:97], v[44:45], v[90:91]
	v_pk_add_f32 v[44:45], v[44:45], v[90:91] neg_lo:[0,1] neg_hi:[0,1]
	v_pk_add_f32 v[48:49], v[52:53], v[48:49] neg_lo:[0,1] neg_hi:[0,1]
	v_pk_add_f32 v[52:53], v[22:23], v[42:43]
	v_pk_add_f32 v[22:23], v[22:23], v[42:43] neg_lo:[0,1] neg_hi:[0,1]
	v_xor_b32_e32 v91, 0x80000000, v44
	v_mov_b32_e32 v90, v45
	v_pk_add_f32 v[44:45], v[98:99], v[46:47]
	v_pk_add_f32 v[46:47], v[98:99], v[46:47] neg_lo:[0,1] neg_hi:[0,1]
	v_pk_add_f32 v[98:99], v[94:95], v[40:41]
	v_pk_add_f32 v[40:41], v[94:95], v[40:41] neg_lo:[0,1] neg_hi:[0,1]
	v_xor_b32_e32 v43, 0x80000000, v22
	v_mov_b32_e32 v42, v23
	v_pk_add_f32 v[22:23], v[100:101], v[24:25] neg_lo:[0,1] neg_hi:[0,1]
	v_xor_b32_e32 v95, 0x80000000, v40
	v_mov_b32_e32 v94, v41
	v_xor_b32_e32 v25, 0x80000000, v22
	v_mov_b32_e32 v24, v23
	v_pk_add_f32 v[100:101], v[28:29], v[32:33]
	v_pk_add_f32 v[32:33], v[28:29], v[32:33] neg_lo:[0,1] neg_hi:[0,1]
	v_mov_b32_e32 v112, v13
	v_pk_add_f32 v[12:13], v[34:35], v[14:15]
	v_pk_add_f32 v[14:15], v[34:35], v[14:15] neg_lo:[0,1] neg_hi:[0,1]
	v_pk_add_f32 v[34:35], v[30:31], v[6:7]
	v_pk_add_f32 v[6:7], v[30:31], v[6:7] neg_lo:[0,1] neg_hi:[0,1]
	v_pk_add_f32 v[114:115], v[2:3], v[16:17]
	v_pk_add_f32 v[16:17], v[2:3], v[16:17] neg_lo:[0,1] neg_hi:[0,1]
	v_pk_add_f32 v[2:3], v[4:5], v[8:9] neg_lo:[0,1] neg_hi:[0,1]
	v_xor_b32_e32 v31, 0x80000000, v6
	v_mov_b32_e32 v30, v7
	v_pk_add_f32 v[116:117], v[4:5], v[8:9]
	v_xor_b32_e32 v119, 0x80000000, v2
	v_mov_b32_e32 v118, v3
	v_pk_add_f32 v[2:3], v[20:21], v[104:105]
	v_pk_add_f32 v[104:105], v[20:21], v[104:105] neg_lo:[0,1] neg_hi:[0,1]
	v_pk_add_f32 v[120:121], v[36:37], v[102:103]
	v_pk_add_f32 v[26:27], v[36:37], v[102:103] neg_lo:[0,1] neg_hi:[0,1]
	v_pk_add_f32 v[36:37], v[38:39], v[96:97]
	v_pk_add_f32 v[40:41], v[38:39], v[96:97] neg_lo:[0,1] neg_hi:[0,1]
	v_pk_add_f32 v[96:97], v[92:93], v[90:91]
	v_pk_add_f32 v[6:7], v[92:93], v[90:91] neg_lo:[0,1] neg_hi:[0,1]
	v_pk_add_f32 v[20:21], v[44:45], v[98:99]
	v_pk_add_f32 v[90:91], v[44:45], v[98:99] neg_lo:[0,1] neg_hi:[0,1]
	v_pk_add_f32 v[92:93], v[46:47], v[94:95]
	v_pk_add_f32 v[22:23], v[46:47], v[94:95] neg_lo:[0,1] neg_hi:[0,1]
	v_pk_add_f32 v[46:47], v[106:107], v[52:53]
	v_pk_add_f32 v[38:39], v[106:107], v[52:53] neg_lo:[0,1] neg_hi:[0,1]
	v_pk_add_f32 v[52:53], v[50:51], v[24:25]
	v_pk_add_f32 v[28:29], v[50:51], v[24:25] neg_lo:[0,1] neg_hi:[0,1]
	v_pk_add_f32 v[50:51], v[100:101], v[110:111]
	v_pk_add_f32 v[44:45], v[100:101], v[110:111] neg_lo:[0,1] neg_hi:[0,1]
	v_pk_add_f32 v[98:99], v[32:33], v[112:113]
	v_pk_add_f32 v[8:9], v[32:33], v[112:113] neg_lo:[0,1] neg_hi:[0,1]
	v_pk_add_f32 v[32:33], v[12:13], v[34:35]
	v_pk_add_f32 v[100:101], v[12:13], v[34:35] neg_lo:[0,1] neg_hi:[0,1]
	v_cos_f32_e32 v12, v10
	v_sin_f32_e32 v13, v10
	v_pk_add_f32 v[94:95], v[48:49], v[42:43]
	v_pk_add_f32 v[4:5], v[48:49], v[42:43] neg_lo:[0,1] neg_hi:[0,1]
	v_pk_add_f32 v[48:49], v[108:109], v[88:89]
	v_pk_add_f32 v[102:103], v[14:15], v[30:31]
	v_pk_add_f32 v[24:25], v[14:15], v[30:31] neg_lo:[0,1] neg_hi:[0,1]
	v_pk_add_f32 v[106:107], v[16:17], v[118:119]
	v_pk_add_f32 v[10:11], v[16:17], v[118:119] neg_lo:[0,1] neg_hi:[0,1]
	v_pk_mul_f32 v[14:15], v[12:13], v[12:13]
	v_add_f32_e32 v16, v12, v12
	v_pk_add_f32 v[88:89], v[108:109], v[88:89] neg_lo:[0,1] neg_hi:[0,1]
	v_mul_f32_e32 v18, v13, v16
	v_pk_add_f32 v[16:17], v[14:15], v[14:15] op_sel:[0,1] op_sel_hi:[0,1] neg_lo:[0,1] neg_hi:[0,1]
	v_mov_b32_e32 v108, v13
	v_pk_mul_f32 v[14:15], v[12:13], v[18:19] op_sel:[1,0] op_sel_hi:[0,0] neg_lo:[1,0]
	v_pk_mul_f32 v[30:31], v[108:109], v[48:49] op_sel:[0,1] op_sel_hi:[0,0] neg_hi:[0,1]
	v_pk_fma_f32 v[14:15], v[12:13], v[16:17], v[14:15]
	v_pk_fma_f32 v[12:13], v[12:13], v[48:49], v[30:31] op_sel_hi:[0,1,1]
	v_pk_mul_f32 v[30:31], v[18:19], s[48:49] op_sel_hi:[0,1]
	v_pk_fma_f32 v[30:31], v[16:17], s[40:41], v[30:31]
	v_pk_mul_f32 v[48:49], v[30:31], v[20:21] op_sel:[1,1] op_sel_hi:[1,0] neg_hi:[0,1]
	v_pk_fma_f32 v[20:21], v[20:21], v[30:31], v[48:49] op_sel_hi:[1,0,1]
	v_pk_mul_f32 v[48:49], v[18:19], v[14:15] op_sel:[0,1] op_sel_hi:[0,0] neg_lo:[0,1]
	v_pk_mul_f32 v[108:109], v[14:15], v[32:33] op_sel:[1,1] op_sel_hi:[1,0] neg_hi:[0,1]
	v_pk_fma_f32 v[48:49], v[16:17], v[14:15], v[48:49]
	v_pk_fma_f32 v[14:15], v[14:15], v[32:33], v[108:109] op_sel_hi:[0,1,1]
	v_pk_mul_f32 v[32:33], v[18:19], v[30:31] op_sel:[0,1] op_sel_hi:[0,0] neg_lo:[0,1]
	v_pk_fma_f32 v[108:109], v[16:17], v[30:31], v[32:33]
	v_pk_mul_f32 v[30:31], v[36:37], v[108:109] op_sel:[1,1] op_sel_hi:[0,1] neg_hi:[1,0]
	v_pk_add_f32 v[34:35], v[114:115], v[116:117]
	v_pk_fma_f32 v[32:33], v[36:37], v[108:109], v[30:31] op_sel_hi:[1,0,1]
	v_pk_mul_f32 v[30:31], v[18:19], v[48:49] op_sel:[0,1] op_sel_hi:[0,0] neg_lo:[0,1]
	v_pk_fma_f32 v[110:111], v[16:17], v[48:49], v[30:31]
	v_pk_mul_f32 v[30:31], v[48:49], v[50:51] op_sel:[1,1] op_sel_hi:[1,0] neg_hi:[0,1]
	v_pk_mul_f32 v[36:37], v[18:19], v[108:109] op_sel:[0,1] op_sel_hi:[0,0] neg_lo:[0,1]
	v_pk_fma_f32 v[30:31], v[50:51], v[48:49], v[30:31] op_sel_hi:[1,0,1]
	v_pk_fma_f32 v[48:49], v[16:17], v[108:109], v[36:37]
	v_pk_mul_f32 v[36:37], v[46:47], v[48:49] op_sel:[1,1] op_sel_hi:[0,1] neg_hi:[1,0]
	v_pk_fma_f32 v[36:37], v[46:47], v[48:49], v[36:37] op_sel_hi:[1,0,1]
	v_pk_mul_f32 v[46:47], v[18:19], v[110:111] op_sel:[0,1] op_sel_hi:[0,0] neg_lo:[0,1]
	v_pk_mul_f32 v[50:51], v[110:111], v[34:35] op_sel:[1,1] op_sel_hi:[1,0] neg_hi:[0,1]
	v_pk_fma_f32 v[46:47], v[16:17], v[110:111], v[46:47]
	v_pk_fma_f32 v[34:35], v[34:35], v[110:111], v[50:51] op_sel_hi:[1,0,1]
	v_pk_mul_f32 v[50:51], v[18:19], v[48:49] op_sel:[0,1] op_sel_hi:[0,0] neg_lo:[0,1]
	v_pk_fma_f32 v[50:51], v[16:17], v[48:49], v[50:51]
	v_pk_mul_f32 v[108:109], v[18:19], v[46:47] op_sel:[0,1] op_sel_hi:[0,0] neg_lo:[0,1]
	v_pk_mul_f32 v[110:111], v[52:53], v[46:47] op_sel:[1,1] op_sel_hi:[0,1] neg_hi:[1,0]
	v_pk_fma_f32 v[108:109], v[16:17], v[46:47], v[108:109]
	v_pk_fma_f32 v[46:47], v[52:53], v[46:47], v[110:111] op_sel_hi:[1,0,1]
	v_pk_mul_f32 v[48:49], v[120:121], v[50:51] op_sel:[1,1] op_sel_hi:[0,1] neg_hi:[1,0]
	v_pk_mul_f32 v[52:53], v[18:19], v[50:51] op_sel:[0,1] op_sel_hi:[0,0] neg_lo:[0,1]
	v_pk_fma_f32 v[48:49], v[120:121], v[50:51], v[48:49] op_sel_hi:[1,0,1]
	v_pk_fma_f32 v[110:111], v[16:17], v[50:51], v[52:53]
	v_pk_mul_f32 v[50:51], v[92:93], v[110:111] op_sel:[1,1] op_sel_hi:[0,1] neg_hi:[1,0]
	v_pk_add_f32 v[42:43], v[114:115], v[116:117] neg_lo:[0,1] neg_hi:[0,1]
	v_pk_fma_f32 v[52:53], v[92:93], v[110:111], v[50:51] op_sel_hi:[1,0,1]
	v_pk_mul_f32 v[50:51], v[18:19], v[108:109] op_sel:[0,1] op_sel_hi:[0,0] neg_lo:[0,1]
	v_pk_fma_f32 v[92:93], v[16:17], v[108:109], v[50:51]
	v_pk_mul_f32 v[50:51], v[102:103], v[108:109] op_sel:[1,1] op_sel_hi:[0,1] neg_hi:[1,0]
	v_pk_fma_f32 v[50:51], v[102:103], v[108:109], v[50:51] op_sel_hi:[1,0,1]
	v_pk_mul_f32 v[102:103], v[18:19], v[110:111] op_sel:[0,1] op_sel_hi:[0,0] neg_lo:[0,1]
	v_pk_fma_f32 v[102:103], v[16:17], v[110:111], v[102:103]
	v_pk_mul_f32 v[108:109], v[96:97], v[102:103] op_sel:[1,1] op_sel_hi:[0,1] neg_hi:[1,0]
	v_pk_fma_f32 v[96:97], v[96:97], v[102:103], v[108:109] op_sel_hi:[1,0,1]
	v_pk_mul_f32 v[108:109], v[18:19], v[92:93] op_sel:[0,1] op_sel_hi:[0,0] neg_lo:[0,1]
	v_pk_mul_f32 v[110:111], v[98:99], v[92:93] op_sel:[1,1] op_sel_hi:[0,1] neg_hi:[1,0]
	v_pk_fma_f32 v[108:109], v[16:17], v[92:93], v[108:109]
	v_pk_fma_f32 v[92:93], v[98:99], v[92:93], v[110:111] op_sel_hi:[1,0,1]
	v_pk_mul_f32 v[98:99], v[18:19], v[102:103] op_sel:[0,1] op_sel_hi:[0,0] neg_lo:[0,1]
	v_pk_fma_f32 v[98:99], v[16:17], v[102:103], v[98:99]
	v_pk_mul_f32 v[102:103], v[94:95], v[98:99] op_sel:[1,1] op_sel_hi:[0,1] neg_hi:[1,0]
	v_pk_fma_f32 v[94:95], v[94:95], v[98:99], v[102:103] op_sel_hi:[1,0,1]
	v_pk_mul_f32 v[102:103], v[18:19], v[108:109] op_sel:[0,1] op_sel_hi:[0,0] neg_lo:[0,1]
	v_pk_mul_f32 v[110:111], v[106:107], v[108:109] op_sel:[1,1] op_sel_hi:[0,1] neg_hi:[1,0]
	v_pk_fma_f32 v[102:103], v[16:17], v[108:109], v[102:103]
	v_pk_fma_f32 v[106:107], v[106:107], v[108:109], v[110:111] op_sel_hi:[1,0,1]
	v_pk_mul_f32 v[108:109], v[18:19], v[98:99] op_sel:[0,1] op_sel_hi:[0,0] neg_lo:[0,1]
	v_pk_fma_f32 v[98:99], v[16:17], v[98:99], v[108:109]
	v_pk_mul_f32 v[108:109], v[104:105], v[98:99] op_sel:[1,1] op_sel_hi:[0,1] neg_hi:[1,0]
	v_pk_fma_f32 v[104:105], v[104:105], v[98:99], v[108:109] op_sel_hi:[1,0,1]
	v_pk_mul_f32 v[108:109], v[18:19], v[102:103] op_sel:[0,1] op_sel_hi:[0,0] neg_lo:[0,1]
	v_pk_mul_f32 v[110:111], v[88:89], v[102:103] op_sel:[1,1] op_sel_hi:[0,1] neg_hi:[1,0]
	v_pk_fma_f32 v[108:109], v[16:17], v[102:103], v[108:109]
	v_pk_fma_f32 v[88:89], v[88:89], v[102:103], v[110:111] op_sel_hi:[1,0,1]
	v_pk_mul_f32 v[102:103], v[18:19], v[98:99] op_sel:[0,1] op_sel_hi:[0,0] neg_lo:[0,1]
	v_pk_fma_f32 v[98:99], v[16:17], v[98:99], v[102:103]
	v_pk_mul_f32 v[102:103], v[90:91], v[98:99] op_sel:[1,1] op_sel_hi:[0,1] neg_hi:[1,0]
	v_pk_fma_f32 v[90:91], v[90:91], v[98:99], v[102:103] op_sel_hi:[1,0,1]
	v_pk_mul_f32 v[102:103], v[18:19], v[108:109] op_sel:[0,1] op_sel_hi:[0,0] neg_lo:[0,1]
	v_pk_mul_f32 v[110:111], v[100:101], v[108:109] op_sel:[1,1] op_sel_hi:[0,1] neg_hi:[1,0]
	v_pk_fma_f32 v[102:103], v[16:17], v[108:109], v[102:103]
	v_pk_fma_f32 v[100:101], v[100:101], v[108:109], v[110:111] op_sel_hi:[1,0,1]
	v_pk_mul_f32 v[108:109], v[18:19], v[98:99] op_sel:[0,1] op_sel_hi:[0,0] neg_lo:[0,1]
	v_pk_fma_f32 v[98:99], v[16:17], v[98:99], v[108:109]
	v_pk_mul_f32 v[108:109], v[40:41], v[98:99] op_sel:[1,1] op_sel_hi:[0,1] neg_hi:[1,0]
	v_pk_fma_f32 v[40:41], v[40:41], v[98:99], v[108:109] op_sel_hi:[1,0,1]
	v_pk_mul_f32 v[108:109], v[18:19], v[102:103] op_sel:[0,1] op_sel_hi:[0,0] neg_lo:[0,1]
	v_pk_mul_f32 v[110:111], v[44:45], v[102:103] op_sel:[1,1] op_sel_hi:[0,1] neg_hi:[1,0]
	v_pk_fma_f32 v[108:109], v[16:17], v[102:103], v[108:109]
	v_pk_fma_f32 v[44:45], v[44:45], v[102:103], v[110:111] op_sel_hi:[1,0,1]
	v_pk_mul_f32 v[102:103], v[18:19], v[98:99] op_sel:[0,1] op_sel_hi:[0,0] neg_lo:[0,1]
	v_pk_fma_f32 v[98:99], v[16:17], v[98:99], v[102:103]
	v_pk_mul_f32 v[102:103], v[38:39], v[98:99] op_sel:[1,1] op_sel_hi:[0,1] neg_hi:[1,0]
	v_pk_fma_f32 v[38:39], v[38:39], v[98:99], v[102:103] op_sel_hi:[1,0,1]
	v_pk_mul_f32 v[102:103], v[18:19], v[108:109] op_sel:[0,1] op_sel_hi:[0,0] neg_lo:[0,1]
	v_pk_mul_f32 v[110:111], v[42:43], v[108:109] op_sel:[1,1] op_sel_hi:[0,1] neg_hi:[1,0]
	v_pk_fma_f32 v[102:103], v[16:17], v[108:109], v[102:103]
	v_pk_fma_f32 v[42:43], v[42:43], v[108:109], v[110:111] op_sel_hi:[1,0,1]
	v_pk_mul_f32 v[108:109], v[18:19], v[98:99] op_sel:[0,1] op_sel_hi:[0,0] neg_lo:[0,1]
	v_pk_fma_f32 v[98:99], v[16:17], v[98:99], v[108:109]
	v_pk_mul_f32 v[108:109], v[26:27], v[98:99] op_sel:[1,1] op_sel_hi:[0,1] neg_hi:[1,0]
	v_pk_fma_f32 v[26:27], v[26:27], v[98:99], v[108:109] op_sel_hi:[1,0,1]
	v_pk_mul_f32 v[108:109], v[18:19], v[102:103] op_sel:[0,1] op_sel_hi:[0,0] neg_lo:[0,1]
	v_pk_mul_f32 v[110:111], v[28:29], v[102:103] op_sel:[1,1] op_sel_hi:[0,1] neg_hi:[1,0]
	v_pk_fma_f32 v[108:109], v[16:17], v[102:103], v[108:109]
	v_pk_fma_f32 v[28:29], v[28:29], v[102:103], v[110:111] op_sel_hi:[1,0,1]
	v_pk_mul_f32 v[102:103], v[18:19], v[98:99] op_sel:[0,1] op_sel_hi:[0,0] neg_lo:[0,1]
	v_pk_fma_f32 v[98:99], v[16:17], v[98:99], v[102:103]
	v_pk_mul_f32 v[102:103], v[22:23], v[98:99] op_sel:[1,1] op_sel_hi:[0,1] neg_hi:[1,0]
	v_pk_fma_f32 v[22:23], v[22:23], v[98:99], v[102:103] op_sel_hi:[1,0,1]
	v_pk_mul_f32 v[102:103], v[18:19], v[108:109] op_sel:[0,1] op_sel_hi:[0,0] neg_lo:[0,1]
	v_pk_mul_f32 v[110:111], v[24:25], v[108:109] op_sel:[1,1] op_sel_hi:[0,1] neg_hi:[1,0]
	v_pk_fma_f32 v[102:103], v[16:17], v[108:109], v[102:103]
	v_pk_fma_f32 v[24:25], v[24:25], v[108:109], v[110:111] op_sel_hi:[1,0,1]
	v_pk_mul_f32 v[108:109], v[18:19], v[98:99] op_sel:[0,1] op_sel_hi:[0,0] neg_lo:[0,1]
	v_pk_fma_f32 v[98:99], v[16:17], v[98:99], v[108:109]
	v_pk_mul_f32 v[108:109], v[6:7], v[98:99] op_sel:[1,1] op_sel_hi:[0,1] neg_hi:[1,0]
	v_pk_fma_f32 v[6:7], v[6:7], v[98:99], v[108:109] op_sel_hi:[1,0,1]
	v_pk_mul_f32 v[108:109], v[18:19], v[102:103] op_sel:[0,1] op_sel_hi:[0,0] neg_lo:[0,1]
	v_pk_mul_f32 v[110:111], v[8:9], v[102:103] op_sel:[1,1] op_sel_hi:[0,1] neg_hi:[1,0]
	v_pk_fma_f32 v[108:109], v[16:17], v[102:103], v[108:109]
	v_pk_fma_f32 v[8:9], v[8:9], v[102:103], v[110:111] op_sel_hi:[1,0,1]
	v_pk_mul_f32 v[102:103], v[18:19], v[98:99] op_sel:[0,1] op_sel_hi:[0,0] neg_lo:[0,1]
	v_pk_fma_f32 v[16:17], v[16:17], v[98:99], v[102:103]
	v_pk_mul_f32 v[98:99], v[4:5], v[16:17] op_sel:[1,1] op_sel_hi:[0,1] neg_hi:[1,0]
	v_pk_fma_f32 v[4:5], v[4:5], v[16:17], v[98:99] op_sel_hi:[1,0,1]
	v_pk_mul_f32 v[16:17], v[10:11], v[108:109] op_sel:[1,1] op_sel_hi:[0,1] neg_hi:[1,0]
	s_nop 0
	v_pk_fma_f32 v[10:11], v[10:11], v[108:109], v[16:17] op_sel_hi:[1,0,1]
	ds_write_b64 v19, v[2:3]
	ds_write_b64 v54, v[104:105]
	ds_write_b64 v55, v[48:49] offset:256
	ds_write_b64 v56, v[26:27] offset:256
	ds_write_b64 v57, v[32:33] offset:512
	ds_write_b64 v58, v[40:41] offset:512
	ds_write_b64 v59, v[96:97] offset:768
	ds_write_b64 v60, v[6:7] offset:768
	ds_write_b64 v61, v[20:21] offset:1024
	ds_write_b64 v62, v[90:91] offset:1024
	ds_write_b64 v63, v[52:53] offset:1280
	ds_write_b64 v64, v[22:23] offset:1280
	ds_write_b64 v65, v[36:37] offset:1536
	ds_write_b64 v66, v[38:39] offset:1536
	ds_write_b64 v67, v[94:95] offset:1792
	ds_write_b64 v71, v[4:5] offset:1792
	ds_write_b64 v72, v[12:13] offset:2048
	ds_write_b64 v73, v[88:89] offset:2048
	ds_write_b64 v74, v[46:47] offset:2304
	ds_write_b64 v75, v[28:29] offset:2304
	ds_write_b64 v76, v[30:31] offset:2560
	ds_write_b64 v77, v[44:45] offset:2560
	ds_write_b64 v78, v[92:93] offset:2816
	ds_write_b64 v79, v[8:9] offset:2816
	ds_write_b64 v80, v[14:15] offset:3072
	ds_write_b64 v81, v[100:101] offset:3072
	ds_write_b64 v82, v[50:51] offset:3328
	ds_write_b64 v83, v[24:25] offset:3328
	ds_write_b64 v84, v[34:35] offset:3584
	ds_write_b64 v85, v[42:43] offset:3584
	ds_write_b64 v86, v[106:107] offset:3840
	ds_write_b64 v87, v[10:11] offset:3840
	v_mov_b32_e32 v2, v146
	s_waitcnt lgkmcnt(0)
	s_barrier
	s_nop 0
	v_lshlrev_b32_e32 v34, 4, v2
	v_lshrrev_b32_e32 v35, 1, v2
	v_bitop3_b32 v3, v35, v34, 16 bitop3:0x6c
	v_lshl_add_u32 v26, v3, 3, 16
	v_bitop3_b32 v3, v35, 1, 15 bitop3:0x6c
	v_bitop3_b32 v11, v35, 5, 15 bitop3:0x6c
	v_bitop3_b32 v19, v35, 9, 15 bitop3:0x6c
	v_lshlrev_b32_e32 v37, 3, v3
	v_bitop3_b32 v3, v35, 2, 15 bitop3:0x6c
	v_lshlrev_b32_e32 v45, 3, v11
	v_bitop3_b32 v11, v35, 6, 15 bitop3:0x6c
	v_lshlrev_b32_e32 v49, 3, v19
	v_bitop3_b32 v19, v35, 10, 15 bitop3:0x6c
	v_bitop3_b32 v29, v35, 14, 15 bitop3:0x6c
	v_add_u32_e32 v34, 0x2000, v34
	v_bfe_u32 v2, v2, 1, 4
	v_lshlrev_b32_e32 v38, 3, v3
	v_bitop3_b32 v3, v35, 3, 15 bitop3:0x6c
	v_bitop3_b32 v10, v35, 4, 15 bitop3:0x6c
	v_lshlrev_b32_e32 v46, 3, v11
	v_bitop3_b32 v11, v35, 7, 15 bitop3:0x6c
	v_bitop3_b32 v18, v35, 8, 15 bitop3:0x6c
	v_lshlrev_b32_e32 v50, 3, v19
	v_bitop3_b32 v19, v35, 11, 15 bitop3:0x6c
	v_bitop3_b32 v27, v35, 12, 15 bitop3:0x6c
	v_bitop3_b32 v28, v35, 13, 15 bitop3:0x6c
	v_lshlrev_b32_e32 v54, 3, v29
	v_bitop3_b32 v29, v35, 15, v35 bitop3:0xc
	v_bitop3_b32 v34, v34, v35, 16 bitop3:0x78
	v_lshlrev_b32_e32 v36, 3, v2
	v_lshlrev_b32_e32 v39, 3, v3
	v_lshlrev_b32_e32 v44, 3, v10
	v_lshlrev_b32_e32 v47, 3, v11
	v_lshlrev_b32_e32 v48, 3, v18
	v_lshlrev_b32_e32 v51, 3, v19
	v_lshlrev_b32_e32 v52, 3, v27
	v_lshlrev_b32_e32 v53, 3, v28
	v_lshlrev_b32_e32 v55, 3, v29
	v_lshl_add_u32 v34, v34, 3, 16
	v_add_u32_e32 v2, v26, v36
	v_add_u32_e32 v4, v26, v37
	v_add_u32_e32 v6, v26, v38
	v_add_u32_e32 v8, v26, v39
	v_add_u32_e32 v10, v26, v44
	v_add_u32_e32 v12, v26, v45
	v_add_u32_e32 v14, v26, v46
	v_add_u32_e32 v16, v26, v47
	v_add_u32_e32 v18, v26, v48
	v_add_u32_e32 v20, v26, v49
	v_add_u32_e32 v22, v26, v50
	v_add_u32_e32 v24, v26, v51
	v_add_u32_e32 v27, v26, v52
	v_add_u32_e32 v28, v26, v53
	v_add_u32_e32 v30, v26, v54
	v_add_u32_e32 v32, v26, v55
	v_add_u32_e32 v35, v34, v36
	v_add_u32_e32 v40, v34, v37
	v_add_u32_e32 v41, v34, v38
	v_add_u32_e32 v42, v34, v39
	ds_read_b64 v[2:3], v2
	ds_read_b64 v[4:5], v4
	ds_read_b64 v[6:7], v6
	ds_read_b64 v[8:9], v8
	ds_read_b64 v[10:11], v10
	ds_read_b64 v[12:13], v12
	ds_read_b64 v[14:15], v14
	ds_read_b64 v[16:17], v16
	ds_read_b64 v[18:19], v18
	ds_read_b64 v[20:21], v20
	ds_read_b64 v[22:23], v22
	ds_read_b64 v[24:25], v24
	ds_read_b64 v[26:27], v27
	ds_read_b64 v[28:29], v28
	ds_read_b64 v[30:31], v30
	ds_read_b64 v[32:33], v32
	ds_read_b64 v[36:37], v35
	ds_read_b64 v[38:39], v40
	ds_read_b64 v[40:41], v41
	ds_read_b64 v[42:43], v42
	v_add_u32_e32 v35, v34, v44
	v_add_u32_e32 v44, v34, v45
	v_add_u32_e32 v45, v34, v46
	v_add_u32_e32 v46, v34, v47
	ds_read_b64 v[72:73], v35
	ds_read_b64 v[74:75], v44
	ds_read_b64 v[76:77], v45
	ds_read_b64 v[78:79], v46
	v_add_u32_e32 v35, v34, v48
	v_add_u32_e32 v44, v34, v49
	v_add_u32_e32 v45, v34, v50
	v_add_u32_e32 v46, v34, v51
	ds_read_b64 v[80:81], v35
	ds_read_b64 v[82:83], v44
	ds_read_b64 v[84:85], v45
	ds_read_b64 v[86:87], v46
	v_add_u32_e32 v35, v34, v52
	v_add_u32_e32 v44, v34, v53
	v_add_u32_e32 v45, v34, v54
	v_add_u32_e32 v34, v34, v55
	ds_read_b64 v[88:89], v35
	ds_read_b64 v[90:91], v44
	ds_read_b64 v[92:93], v45
	ds_read_b64 v[94:95], v34
	s_waitcnt lgkmcnt(14)
	v_pk_add_f32 v[34:35], v[2:3], v[18:19]
	v_pk_add_f32 v[2:3], v[2:3], v[18:19] neg_lo:[0,1] neg_hi:[0,1]
	v_pk_add_f32 v[18:19], v[4:5], v[20:21]
	v_pk_add_f32 v[4:5], v[4:5], v[20:21] neg_lo:[0,1] neg_hi:[0,1]
	v_pk_mul_f32 v[20:21], v[4:5], s[62:63] op_sel:[1,0] op_sel_hi:[0,0] neg_hi:[1,0]
	v_pk_fma_f32 v[4:5], v[4:5], s[60:61], v[20:21] op_sel_hi:[1,0,1]
	v_pk_add_f32 v[20:21], v[6:7], v[22:23]
	v_pk_add_f32 v[6:7], v[6:7], v[22:23] neg_lo:[0,1] neg_hi:[0,1]
	v_pk_mul_f32 v[22:23], v[6:7], s[70:71] op_sel:[1,0] op_sel_hi:[0,0] neg_hi:[1,0]
	v_pk_fma_f32 v[6:7], v[6:7], s[70:71], v[22:23] op_sel_hi:[1,0,1]
	v_pk_add_f32 v[22:23], v[8:9], v[24:25]
	v_pk_add_f32 v[8:9], v[8:9], v[24:25] neg_lo:[0,1] neg_hi:[0,1]
	v_pk_mul_f32 v[24:25], v[8:9], s[60:61] op_sel:[1,0] op_sel_hi:[0,0] neg_hi:[1,0]
	v_pk_fma_f32 v[8:9], v[8:9], s[62:63], v[24:25] op_sel_hi:[1,0,1]
	v_pk_add_f32 v[24:25], v[10:11], v[26:27]
	v_pk_add_f32 v[10:11], v[10:11], v[26:27] neg_lo:[0,1] neg_hi:[0,1]
	v_xor_b32_e32 v27, 0x80000000, v10
	v_mov_b32_e32 v26, v11
	v_pk_add_f32 v[10:11], v[12:13], v[28:29]
	v_pk_add_f32 v[12:13], v[12:13], v[28:29] neg_lo:[0,1] neg_hi:[0,1]
	v_pk_mul_f32 v[28:29], v[12:13], s[62:63] op_sel_hi:[1,0]
	v_xor_b32_e32 v45, 0x80000000, v12
	v_mov_b32_e32 v44, v13
	v_pk_fma_f32 v[12:13], v[44:45], s[60:61], v[28:29] op_sel_hi:[1,0,1] neg_lo:[0,0,1] neg_hi:[0,0,1]
	v_pk_add_f32 v[28:29], v[14:15], v[30:31]
	v_pk_add_f32 v[14:15], v[14:15], v[30:31] neg_lo:[0,1] neg_hi:[0,1]
	v_pk_mul_f32 v[30:31], v[14:15], s[70:71] op_sel_hi:[1,0]
	v_xor_b32_e32 v45, 0x80000000, v14
	v_mov_b32_e32 v44, v15
	v_pk_fma_f32 v[14:15], v[44:45], s[70:71], v[30:31] op_sel_hi:[1,0,1] neg_lo:[0,0,1] neg_hi:[0,0,1]
	v_pk_add_f32 v[30:31], v[16:17], v[32:33]
	v_pk_add_f32 v[16:17], v[16:17], v[32:33] neg_lo:[0,1] neg_hi:[0,1]
	v_pk_mul_f32 v[32:33], v[16:17], s[60:61] op_sel_hi:[1,0]
	v_xor_b32_e32 v45, 0x80000000, v16
	v_mov_b32_e32 v44, v17
	v_pk_fma_f32 v[16:17], v[44:45], s[62:63], v[32:33] op_sel_hi:[1,0,1] neg_lo:[0,0,1] neg_hi:[0,0,1]
	v_pk_add_f32 v[32:33], v[34:35], v[24:25]
	v_pk_add_f32 v[24:25], v[34:35], v[24:25] neg_lo:[0,1] neg_hi:[0,1]
	v_pk_add_f32 v[34:35], v[18:19], v[10:11]
	v_pk_add_f32 v[10:11], v[18:19], v[10:11] neg_lo:[0,1] neg_hi:[0,1]
	v_pk_mul_f32 v[18:19], v[10:11], s[70:71] op_sel:[1,0] op_sel_hi:[0,0] neg_hi:[1,0]
	v_pk_fma_f32 v[10:11], v[10:11], s[70:71], v[18:19] op_sel_hi:[1,0,1]
	v_pk_add_f32 v[18:19], v[20:21], v[28:29]
	v_pk_add_f32 v[20:21], v[20:21], v[28:29] neg_lo:[0,1] neg_hi:[0,1]
	v_xor_b32_e32 v29, 0x80000000, v20
	v_mov_b32_e32 v28, v21
	v_pk_add_f32 v[20:21], v[22:23], v[30:31]
	v_pk_add_f32 v[22:23], v[22:23], v[30:31] neg_lo:[0,1] neg_hi:[0,1]
	v_pk_mul_f32 v[30:31], v[22:23], s[70:71] op_sel_hi:[1,0]
	v_xor_b32_e32 v45, 0x80000000, v22
	v_mov_b32_e32 v44, v23
	v_pk_fma_f32 v[22:23], v[44:45], s[70:71], v[30:31] op_sel_hi:[1,0,1] neg_lo:[0,0,1] neg_hi:[0,0,1]
	v_pk_add_f32 v[30:31], v[2:3], v[26:27]
	v_pk_add_f32 v[2:3], v[2:3], v[26:27] neg_lo:[0,1] neg_hi:[0,1]
	v_pk_add_f32 v[26:27], v[4:5], v[12:13]
	v_pk_add_f32 v[4:5], v[4:5], v[12:13] neg_lo:[0,1] neg_hi:[0,1]
	v_pk_mul_f32 v[12:13], v[4:5], s[70:71] op_sel:[1,0] op_sel_hi:[0,0] neg_hi:[1,0]
	v_pk_fma_f32 v[4:5], v[4:5], s[70:71], v[12:13] op_sel_hi:[1,0,1]
	v_pk_add_f32 v[12:13], v[6:7], v[14:15]
	v_pk_add_f32 v[6:7], v[6:7], v[14:15] neg_lo:[0,1] neg_hi:[0,1]
	v_xor_b32_e32 v15, 0x80000000, v6
	v_mov_b32_e32 v14, v7
	v_pk_add_f32 v[6:7], v[8:9], v[16:17]
	v_pk_add_f32 v[8:9], v[8:9], v[16:17] neg_lo:[0,1] neg_hi:[0,1]
	v_pk_mul_f32 v[16:17], v[8:9], s[70:71] op_sel_hi:[1,0]
	v_pk_fma_f32 v[8:9], v[8:9], s[70:71], v[16:17] op_sel:[1,0,0] op_sel_hi:[0,0,1] neg_lo:[0,0,1] neg_hi:[1,0,1]
	v_pk_add_f32 v[16:17], v[32:33], v[18:19]
	v_pk_add_f32 v[18:19], v[32:33], v[18:19] neg_lo:[0,1] neg_hi:[0,1]
	v_pk_add_f32 v[32:33], v[34:35], v[20:21]
	v_pk_add_f32 v[20:21], v[34:35], v[20:21] neg_lo:[0,1] neg_hi:[0,1]
	v_pk_add_f32 v[66:67], v[16:17], v[32:33]
	v_xor_b32_e32 v35, 0x80000000, v20
	v_mov_b32_e32 v34, v21
	v_pk_add_f32 v[20:21], v[24:25], v[28:29]
	v_pk_add_f32 v[24:25], v[24:25], v[28:29] neg_lo:[0,1] neg_hi:[0,1]
	v_pk_add_f32 v[28:29], v[10:11], v[22:23]
	v_pk_add_f32 v[10:11], v[10:11], v[22:23] neg_lo:[0,1] neg_hi:[0,1]
	v_pk_add_f32 v[58:59], v[20:21], v[28:29]
	v_xor_b32_e32 v23, 0x80000000, v10
	v_mov_b32_e32 v22, v11
	v_pk_add_f32 v[10:11], v[30:31], v[12:13]
	v_pk_add_f32 v[12:13], v[30:31], v[12:13] neg_lo:[0,1] neg_hi:[0,1]
	v_pk_add_f32 v[30:31], v[26:27], v[6:7]
	v_pk_add_f32 v[6:7], v[26:27], v[6:7] neg_lo:[0,1] neg_hi:[0,1]
	v_pk_add_f32 v[54:55], v[24:25], v[22:23]
	v_xor_b32_e32 v27, 0x80000000, v6
	v_mov_b32_e32 v26, v7
	v_pk_add_f32 v[6:7], v[2:3], v[14:15]
	v_pk_add_f32 v[2:3], v[2:3], v[14:15] neg_lo:[0,1] neg_hi:[0,1]
	v_pk_add_f32 v[14:15], v[4:5], v[8:9]
	v_pk_add_f32 v[4:5], v[4:5], v[8:9] neg_lo:[0,1] neg_hi:[0,1]
	v_pk_add_f32 v[52:53], v[24:25], v[22:23] neg_lo:[0,1] neg_hi:[0,1]
	v_pk_add_f32 v[50:51], v[10:11], v[30:31]
	v_pk_add_f32 v[48:49], v[10:11], v[30:31] neg_lo:[0,1] neg_hi:[0,1]
	v_pk_add_f32 v[46:47], v[12:13], v[26:27]
	v_pk_add_f32 v[44:45], v[12:13], v[26:27] neg_lo:[0,1] neg_hi:[0,1]
	v_pk_add_f32 v[30:31], v[2:3], v[4:5] op_sel:[0,1] op_sel_hi:[1,0] neg_hi:[0,1]
	v_pk_add_f32 v[26:27], v[2:3], v[4:5] op_sel:[0,1] op_sel_hi:[1,0] neg_lo:[0,1]
	s_waitcnt lgkmcnt(6)
	v_pk_add_f32 v[8:9], v[38:39], v[82:83] neg_lo:[0,1] neg_hi:[0,1]
	s_waitcnt lgkmcnt(2)
	v_pk_add_f32 v[24:25], v[74:75], v[90:91] neg_lo:[0,1] neg_hi:[0,1]
	v_pk_add_f32 v[56:57], v[20:21], v[28:29] neg_lo:[0,1] neg_hi:[0,1]
	v_pk_add_f32 v[2:3], v[36:37], v[80:81]
	v_pk_add_f32 v[4:5], v[36:37], v[80:81] neg_lo:[0,1] neg_hi:[0,1]
	v_pk_mul_f32 v[28:29], v[24:25], s[62:63] op_sel_hi:[1,0]
	v_pk_add_f32 v[64:65], v[16:17], v[32:33] neg_lo:[0,1] neg_hi:[0,1]
	v_pk_mul_f32 v[10:11], v[8:9], s[62:63] op_sel:[1,0] op_sel_hi:[0,0] neg_hi:[1,0]
	v_pk_add_f32 v[12:13], v[40:41], v[84:85] neg_lo:[0,1] neg_hi:[0,1]
	v_pk_add_f32 v[16:17], v[42:43], v[86:87] neg_lo:[0,1] neg_hi:[0,1]
	v_pk_fma_f32 v[24:25], v[24:25], s[60:61], v[28:29] op_sel:[1,0,0] op_sel_hi:[0,0,1] neg_lo:[0,0,1] neg_hi:[1,0,1]
	s_waitcnt lgkmcnt(1)
	v_pk_add_f32 v[36:37], v[76:77], v[92:93] neg_lo:[0,1] neg_hi:[0,1]
	v_pk_add_f32 v[62:63], v[18:19], v[34:35]
	v_pk_add_f32 v[60:61], v[18:19], v[34:35] neg_lo:[0,1] neg_hi:[0,1]
	v_pk_add_f32 v[34:35], v[6:7], v[14:15]
	v_pk_add_f32 v[32:33], v[6:7], v[14:15] neg_lo:[0,1] neg_hi:[0,1]
	v_pk_add_f32 v[6:7], v[38:39], v[82:83]
	v_pk_fma_f32 v[8:9], v[8:9], s[60:61], v[10:11] op_sel_hi:[1,0,1]
	v_pk_add_f32 v[10:11], v[40:41], v[84:85]
	v_pk_mul_f32 v[38:39], v[36:37], s[70:71] op_sel_hi:[1,0]
	v_pk_mul_f32 v[14:15], v[12:13], s[70:71] op_sel:[1,0] op_sel_hi:[0,0] neg_hi:[1,0]
	v_pk_mul_f32 v[18:19], v[16:17], s[60:61] op_sel:[1,0] op_sel_hi:[0,0] neg_hi:[1,0]
	v_pk_add_f32 v[20:21], v[72:73], v[88:89] neg_lo:[0,1] neg_hi:[0,1]
	v_pk_fma_f32 v[36:37], v[36:37], s[70:71], v[38:39] op_sel:[1,0,0] op_sel_hi:[0,0,1] neg_lo:[0,0,1] neg_hi:[1,0,1]
	s_waitcnt lgkmcnt(0)
	v_pk_add_f32 v[40:41], v[78:79], v[94:95] neg_lo:[0,1] neg_hi:[0,1]
	v_pk_fma_f32 v[12:13], v[12:13], s[70:71], v[14:15] op_sel_hi:[1,0,1]
	v_pk_add_f32 v[14:15], v[42:43], v[86:87]
	v_pk_fma_f32 v[16:17], v[16:17], s[62:63], v[18:19] op_sel_hi:[1,0,1]
	v_pk_add_f32 v[18:19], v[72:73], v[88:89]
	v_xor_b32_e32 v23, 0x80000000, v20
	v_mov_b32_e32 v22, v21
	v_pk_add_f32 v[20:21], v[74:75], v[90:91]
	v_pk_mul_f32 v[42:43], v[40:41], s[60:61] op_sel_hi:[1,0]
	v_xor_b32_e32 v73, 0x80000000, v40
	v_mov_b32_e32 v72, v41
	v_pk_fma_f32 v[40:41], v[72:73], s[62:63], v[42:43] op_sel_hi:[1,0,1] neg_lo:[0,0,1] neg_hi:[0,0,1]
	v_pk_add_f32 v[42:43], v[2:3], v[18:19]
	v_pk_add_f32 v[2:3], v[2:3], v[18:19] neg_lo:[0,1] neg_hi:[0,1]
	v_pk_add_f32 v[18:19], v[6:7], v[20:21]
	v_pk_add_f32 v[6:7], v[6:7], v[20:21] neg_lo:[0,1] neg_hi:[0,1]
	v_pk_add_f32 v[28:29], v[76:77], v[92:93]
	v_pk_mul_f32 v[20:21], v[6:7], s[70:71] op_sel:[1,0] op_sel_hi:[0,0] neg_hi:[1,0]
	v_pk_add_f32 v[38:39], v[78:79], v[94:95]
	v_pk_fma_f32 v[6:7], v[6:7], s[70:71], v[20:21] op_sel_hi:[1,0,1]
	v_pk_add_f32 v[20:21], v[10:11], v[28:29]
	v_pk_add_f32 v[10:11], v[10:11], v[28:29] neg_lo:[0,1] neg_hi:[0,1]
	v_xor_b32_e32 v29, 0x80000000, v10
	v_mov_b32_e32 v28, v11
	v_pk_add_f32 v[10:11], v[14:15], v[38:39]
	v_pk_add_f32 v[14:15], v[14:15], v[38:39] neg_lo:[0,1] neg_hi:[0,1]
	v_pk_mul_f32 v[38:39], v[14:15], s[70:71] op_sel_hi:[1,0]
	v_xor_b32_e32 v73, 0x80000000, v14
	v_mov_b32_e32 v72, v15
	v_pk_fma_f32 v[14:15], v[72:73], s[70:71], v[38:39] op_sel_hi:[1,0,1] neg_lo:[0,0,1] neg_hi:[0,0,1]
	v_pk_add_f32 v[38:39], v[4:5], v[22:23]
	v_pk_add_f32 v[4:5], v[4:5], v[22:23] neg_lo:[0,1] neg_hi:[0,1]
	v_pk_add_f32 v[22:23], v[8:9], v[24:25]
	v_pk_add_f32 v[8:9], v[8:9], v[24:25] neg_lo:[0,1] neg_hi:[0,1]
	v_pk_mul_f32 v[24:25], v[8:9], s[70:71] op_sel:[1,0] op_sel_hi:[0,0] neg_hi:[1,0]
	v_pk_fma_f32 v[8:9], v[8:9], s[70:71], v[24:25] op_sel_hi:[1,0,1]
	v_pk_add_f32 v[24:25], v[12:13], v[36:37]
	v_pk_add_f32 v[12:13], v[12:13], v[36:37] neg_lo:[0,1] neg_hi:[0,1]
	v_pk_add_f32 v[74:75], v[38:39], v[24:25] neg_lo:[0,1] neg_hi:[0,1]
	v_xor_b32_e32 v37, 0x80000000, v12
	v_mov_b32_e32 v36, v13
	v_pk_add_f32 v[12:13], v[16:17], v[40:41]
	v_pk_add_f32 v[16:17], v[16:17], v[40:41] neg_lo:[0,1] neg_hi:[0,1]
	v_pk_add_f32 v[76:77], v[22:23], v[12:13]
	v_pk_mul_f32 v[40:41], v[16:17], s[70:71] op_sel_hi:[1,0]
	v_pk_fma_f32 v[16:17], v[16:17], s[70:71], v[40:41] op_sel:[1,0,0] op_sel_hi:[0,0,1] neg_lo:[0,0,1] neg_hi:[1,0,1]
	v_pk_add_f32 v[72:73], v[18:19], v[10:11]
	v_pk_add_f32 v[10:11], v[18:19], v[10:11] neg_lo:[0,1] neg_hi:[0,1]
	v_pk_add_f32 v[12:13], v[22:23], v[12:13] neg_lo:[0,1] neg_hi:[0,1]
	v_xor_b32_e32 v19, 0x80000000, v10
	v_mov_b32_e32 v18, v11
	v_pk_add_f32 v[10:11], v[2:3], v[28:29]
	v_pk_add_f32 v[2:3], v[2:3], v[28:29] neg_lo:[0,1] neg_hi:[0,1]
	v_pk_add_f32 v[28:29], v[6:7], v[14:15]
	v_pk_add_f32 v[6:7], v[6:7], v[14:15] neg_lo:[0,1] neg_hi:[0,1]
	v_pk_add_f32 v[22:23], v[10:11], v[28:29] neg_lo:[0,1] neg_hi:[0,1]
	v_xor_b32_e32 v15, 0x80000000, v6
	v_mov_b32_e32 v14, v7
	v_pk_add_f32 v[6:7], v[38:39], v[24:25]
	v_pk_add_f32 v[24:25], v[10:11], v[28:29]
	v_mov_b32_e32 v28, v146
	v_pk_add_f32 v[40:41], v[42:43], v[20:21]
	v_pk_add_f32 v[20:21], v[42:43], v[20:21] neg_lo:[0,1] neg_hi:[0,1]
	v_lshlrev_b32_e32 v71, 4, v28
	v_lshrrev_b32_e32 v29, 1, v28
	v_pk_add_f32 v[42:43], v[40:41], v[72:73]
	v_pk_add_f32 v[40:41], v[40:41], v[72:73] neg_lo:[0,1] neg_hi:[0,1]
	v_bfe_u32 v28, v28, 1, 4
	v_bitop3_b32 v72, v29, v71, 16 bitop3:0x6c
	v_lshl_add_u32 v72, v72, 3, 16
	v_lshlrev_b32_e32 v28, 3, v28
	v_add_u32_e32 v73, v72, v28
	ds_write_b64 v73, v[66:67]
	v_bitop3_b32 v73, v29, 1, 15 bitop3:0x6c
	v_xor_b32_e32 v79, 0x80000000, v12
	v_mov_b32_e32 v78, v13
	v_lshlrev_b32_e32 v73, 3, v73
	v_pk_add_f32 v[12:13], v[74:75], v[78:79]
	v_pk_add_f32 v[10:11], v[74:75], v[78:79] neg_lo:[0,1] neg_hi:[0,1]
	v_add_u32_e32 v74, v72, v73
	ds_write_b64 v74, v[64:65]
	v_bitop3_b32 v74, v29, 2, 15 bitop3:0x6c
	v_lshlrev_b32_e32 v74, 3, v74
	v_add_u32_e32 v75, v72, v74
	ds_write_b64 v75, v[62:63]
	v_bitop3_b32 v75, v29, 3, 15 bitop3:0x6c
	v_lshlrev_b32_e32 v75, 3, v75
	v_pk_add_f32 v[80:81], v[4:5], v[36:37]
	v_pk_add_f32 v[82:83], v[4:5], v[36:37] neg_lo:[0,1] neg_hi:[0,1]
	v_pk_add_f32 v[4:5], v[8:9], v[16:17]
	v_pk_add_f32 v[8:9], v[8:9], v[16:17] neg_lo:[0,1] neg_hi:[0,1]
	v_pk_add_f32 v[38:39], v[20:21], v[18:19]
	v_pk_add_f32 v[36:37], v[20:21], v[18:19] neg_lo:[0,1] neg_hi:[0,1]
	v_pk_add_f32 v[20:21], v[2:3], v[14:15]
	v_pk_add_f32 v[18:19], v[2:3], v[14:15] neg_lo:[0,1] neg_hi:[0,1]
	v_pk_add_f32 v[16:17], v[6:7], v[76:77]
	v_pk_add_f32 v[14:15], v[6:7], v[76:77] neg_lo:[0,1] neg_hi:[0,1]
	v_add_u32_e32 v76, v72, v75
	ds_write_b64 v76, v[60:61]
	v_bitop3_b32 v76, v29, 4, 15 bitop3:0x6c
	v_lshlrev_b32_e32 v76, 3, v76
	v_add_u32_e32 v77, v72, v76
	ds_write_b64 v77, v[58:59]
	v_bitop3_b32 v77, v29, 5, 15 bitop3:0x6c
	v_lshlrev_b32_e32 v77, 3, v77
	v_add_u32_e32 v78, v72, v77
	ds_write_b64 v78, v[56:57]
	v_bitop3_b32 v78, v29, 6, 15 bitop3:0x6c
	v_lshlrev_b32_e32 v78, 3, v78
	v_add_u32_e32 v79, v72, v78
	ds_write_b64 v79, v[54:55]
	v_bitop3_b32 v79, v29, 7, 15 bitop3:0x6c
	v_lshlrev_b32_e32 v79, 3, v79
	v_xor_b32_e32 v85, 0x80000000, v8
	v_mov_b32_e32 v84, v9
	v_pk_add_f32 v[8:9], v[80:81], v[4:5]
	v_pk_add_f32 v[6:7], v[80:81], v[4:5] neg_lo:[0,1] neg_hi:[0,1]
	v_add_u32_e32 v80, v72, v79
	ds_write_b64 v80, v[52:53]
	v_bitop3_b32 v80, v29, 8, 15 bitop3:0x6c
	v_lshlrev_b32_e32 v80, 3, v80
	v_add_u32_e32 v81, v72, v80
	ds_write_b64 v81, v[50:51]
	v_bitop3_b32 v81, v29, 9, 15 bitop3:0x6c
	v_lshlrev_b32_e32 v81, 3, v81
	v_pk_add_f32 v[4:5], v[82:83], v[84:85]
	v_pk_add_f32 v[2:3], v[82:83], v[84:85] neg_lo:[0,1] neg_hi:[0,1]
	v_add_u32_e32 v82, v72, v81
	ds_write_b64 v82, v[48:49]
	v_bitop3_b32 v82, v29, 10, 15 bitop3:0x6c
	v_lshlrev_b32_e32 v82, 3, v82
	v_add_u32_e32 v83, v72, v82
	ds_write_b64 v83, v[46:47]
	v_bitop3_b32 v83, v29, 11, 15 bitop3:0x6c
	v_lshlrev_b32_e32 v83, 3, v83
	v_add_u32_e32 v84, v72, v83
	ds_write_b64 v84, v[44:45]
	v_bitop3_b32 v84, v29, 12, 15 bitop3:0x6c
	v_lshlrev_b32_e32 v84, 3, v84
	v_add_u32_e32 v85, v72, v84
	ds_write_b64 v85, v[34:35]
	v_bitop3_b32 v85, v29, 13, 15 bitop3:0x6c
	v_lshlrev_b32_e32 v85, 3, v85
	v_add_u32_e32 v86, v72, v85
	ds_write_b64 v86, v[32:33]
	v_bitop3_b32 v86, v29, 14, 15 bitop3:0x6c
	v_lshlrev_b32_e32 v86, 3, v86
	v_add_u32_e32 v87, v72, v86
	v_add_u32_e32 v88, 0x2000, v71
	ds_write_b64 v87, v[30:31]
	v_bitop3_b32 v87, v29, 15, v29 bitop3:0xc
	v_bitop3_b32 v29, v88, v29, 16 bitop3:0x78
	v_lshlrev_b32_e32 v87, 3, v87
	v_lshl_add_u32 v29, v29, 3, 16
	v_add_u32_e32 v72, v72, v87
	v_add_u32_e32 v28, v29, v28
	ds_write_b64 v72, v[26:27]
	ds_write_b64 v28, v[42:43]
	v_add_u32_e32 v28, v29, v73
	ds_write_b64 v28, v[40:41]
	v_add_u32_e32 v28, v29, v74
	ds_write_b64 v28, v[38:39]
	v_add_u32_e32 v28, v29, v75
	ds_write_b64 v28, v[36:37]
	v_add_u32_e32 v28, v29, v76
	ds_write_b64 v28, v[24:25]
	v_add_u32_e32 v28, v29, v77
	ds_write_b64 v28, v[22:23]
	v_add_u32_e32 v28, v29, v78
	ds_write_b64 v28, v[20:21]
	v_add_u32_e32 v28, v29, v79
	ds_write_b64 v28, v[18:19]
	v_add_u32_e32 v28, v29, v80
	ds_write_b64 v28, v[16:17]
	v_add_u32_e32 v28, v29, v81
	ds_write_b64 v28, v[14:15]
	v_add_u32_e32 v28, v29, v82
	v_or_b32_e32 v72, 1, v71
	ds_write_b64 v28, v[12:13]
	v_add_u32_e32 v28, v29, v83
	v_bfrev_b32_e32 v72, v72
	ds_write_b64 v28, v[10:11]
	v_add_u32_e32 v28, v29, v84
	v_lshrrev_b32_e32 v72, 18, v72
	ds_write_b64 v28, v[8:9]
	v_add_u32_e32 v28, v29, v85
	v_sub_u32_e32 v72, 0, v72
	ds_write_b64 v28, v[6:7]
	v_add_u32_e32 v28, v29, v86
	v_and_b32_e32 v72, 0x3fff, v72
	ds_write_b64 v28, v[4:5]
	v_add_u32_e32 v28, v29, v87
	v_bfrev_b32_e32 v72, v72
	ds_write_b64 v28, v[2:3]
	v_lshl_add_u64 v[28:29], v[0:1], 2, s[0:1]
	v_bfrev_b32_e32 v0, v71
	v_lshrrev_b32_e32 v73, 18, v72
	v_lshrrev_b32_e32 v72, 23, v72
	v_lshrrev_b32_e32 v0, 18, v0
	v_bitop3_b32 v72, v72, v73, 31 bitop3:0x6c
	v_or_b32_e32 v73, 2, v71
	v_sub_u32_e32 v0, 0, v0
	v_bfrev_b32_e32 v73, v73
	v_and_b32_e32 v0, 0x3fff, v0
	v_lshrrev_b32_e32 v73, 18, v73
	v_bfrev_b32_e32 v0, v0
	v_sub_u32_e32 v73, 0, v73
	v_lshrrev_b32_e32 v1, 18, v0
	v_lshrrev_b32_e32 v0, 23, v0
	v_and_b32_e32 v74, 0x3fff, v73
	v_bitop3_b32 v0, v0, v1, 31 bitop3:0x6c
	v_bfrev_b32_e32 v74, v74
	v_and_b32_e32 v73, 0x1fff, v73
	v_lshl_add_u32 v0, v0, 3, 16
	v_lshrrev_b32_e32 v75, 18, v74
	v_lshrrev_b32_e32 v74, 23, v74
	v_bfrev_b32_e32 v73, v73
	s_waitcnt lgkmcnt(0)
	s_barrier
	ds_read_b64 v[0:1], v0
	v_bitop3_b32 v74, v74, v75, 31 bitop3:0x6c
	v_lshrrev_b32_e32 v75, 18, v73
	v_lshrrev_b32_e32 v73, 23, v73
	v_bitop3_b32 v73, v73, v75, 31 bitop3:0x6c
	v_lshl_add_u32 v72, v72, 3, 16
	v_lshl_add_u32 v74, v74, 3, 16
	v_lshl_add_u32 v76, v73, 3, 16
	ds_read_b64 v[72:73], v72
	ds_read_b64 v[74:75], v74
	ds_read_b64 v[76:77], v76
	s_waitcnt lgkmcnt(3)
	v_pk_add_f32 v[78:79], v[66:67], v[0:1]
	v_sub_f32_e32 v1, v67, v1
	v_sub_f32_e32 v0, v0, v66
	v_mul_f32_e32 v67, 0.5, v1
	v_mul_f32_e32 v66, 0.5, v0
	s_waitcnt lgkmcnt(2)
	v_pk_add_f32 v[0:1], v[64:65], v[72:73]
	v_mul_f32_e32 v78, 0.5, v78
	v_mul_f32_e32 v80, 0.5, v0
	v_sub_f32_e32 v0, v65, v73
	v_mul_f32_e32 v65, 0.5, v0
	v_sub_f32_e32 v0, v72, v64
	v_mul_f32_e32 v73, 0.5, v1
	v_mul_f32_e32 v64, 0.5, v0
	s_waitcnt lgkmcnt(1)
	v_pk_add_f32 v[0:1], v[62:63], v[74:75]
	s_mov_b32 s0, 0x10000
	v_mul_f32_e32 v72, 0.5, v0
	v_sub_f32_e32 v0, v63, v75
	v_mul_f32_e32 v75, 0.5, v0
	v_sub_f32_e32 v0, v74, v62
	v_mul_f32_e32 v81, 0.5, v1
	v_mul_f32_e32 v74, 0.5, v0
	s_waitcnt lgkmcnt(0)
	v_pk_add_f32 v[0:1], v[60:61], v[76:77]
	v_sub_f32_e32 v61, v61, v77
	v_mul_f32_e32 v0, 0.5, v0
	v_mul_f32_e32 v61, 0.5, v61
	v_sub_f32_e32 v60, v76, v60
	v_mul_f32_e32 v79, 0.5, v79
	v_mul_f32_e32 v1, 0.5, v1
	v_mul_f32_e32 v76, 0.5, v60
	v_cvt_pk_f16_f32 v63, v0, v61
	v_cvt_pk_f16_f32 v62, v72, v75
	v_cvt_pk_f16_f32 v61, v80, v65
	v_cvt_pk_f16_f32 v60, v78, v67
	v_add_co_u32_e32 v0, vcc, s0, v28
	global_store_dwordx4 v[28:29], v[60:63], off offset:-4096
	s_lshl_b64 s[0:1], s[68:69], 13
	s_add_u32 s92, s0, 0xc00000
	v_cvt_pk_f16_f32 v63, v1, v76
	v_cvt_pk_f16_f32 v62, v81, v74
	v_cvt_pk_f16_f32 v61, v73, v64
	v_cvt_pk_f16_f32 v60, v79, v66
	v_addc_co_u32_e32 v1, vcc, 0, v29, vcc
	global_store_dwordx4 v[0:1], v[60:63], off offset:-4096
	s_addc_u32 s93, s1, 0
	s_add_u32 s94, s56, s10
	v_or_b32_e32 v60, 4, v71
	v_bfrev_b32_e32 v60, v60
	v_lshrrev_b32_e32 v60, 18, v60
	v_sub_u32_e32 v62, 0, v60
	v_and_b32_e32 v63, 0x1fff, v62
	v_bfrev_b32_e32 v63, v63
	v_lshrrev_b32_e32 v64, 18, v63
	v_lshrrev_b32_e32 v63, 23, v63
	v_bitop3_b32 v63, v63, v64, 31 bitop3:0x6c
	v_or_b32_e32 v64, 6, v71
	v_bfrev_b32_e32 v64, v64
	v_and_b32_e32 v60, 0x3fff, v62
	v_lshrrev_b32_e32 v64, 18, v64
	v_bfrev_b32_e32 v60, v60
	v_sub_u32_e32 v64, 0, v64
	v_lshrrev_b32_e32 v61, 18, v60
	v_lshrrev_b32_e32 v60, 23, v60
	v_and_b32_e32 v64, 0x2fff, v64
	v_bitop3_b32 v60, v60, v61, 31 bitop3:0x6c
	v_bfrev_b32_e32 v64, v64
	v_and_b32_e32 v62, 0xfff, v62
	v_lshl_add_u32 v60, v60, 3, 16
	v_lshrrev_b32_e32 v65, 18, v64
	v_lshrrev_b32_e32 v64, 23, v64
	v_bfrev_b32_e32 v62, v62
	ds_read_b64 v[60:61], v60
	v_bitop3_b32 v64, v64, v65, 31 bitop3:0x6c
	v_lshrrev_b32_e32 v65, 18, v62
	v_lshrrev_b32_e32 v62, 23, v62
	v_bitop3_b32 v62, v62, v65, 31 bitop3:0x6c
	v_lshl_add_u32 v63, v63, 3, 16
	v_lshl_add_u32 v64, v64, 3, 16
	v_lshl_add_u32 v66, v62, 3, 16
	ds_read_b64 v[62:63], v63
	ds_read_b64 v[64:65], v64
	ds_read_b64 v[66:67], v66
	s_waitcnt lgkmcnt(3)
	v_pk_add_f32 v[72:73], v[58:59], v[60:61]
	v_sub_f32_e32 v59, v59, v61
	v_sub_f32_e32 v58, v60, v58
	v_mul_f32_e32 v61, 0.5, v59
	v_mul_f32_e32 v60, 0.5, v58
	s_waitcnt lgkmcnt(2)
	v_pk_add_f32 v[58:59], v[56:57], v[62:63]
	v_sub_f32_e32 v57, v57, v63
	v_sub_f32_e32 v56, v62, v56
	v_mul_f32_e32 v63, 0.5, v57
	v_mul_f32_e32 v62, 0.5, v56
	s_waitcnt lgkmcnt(1)
	v_pk_add_f32 v[56:57], v[54:55], v[64:65]
	v_sub_f32_e32 v55, v55, v65
	v_sub_f32_e32 v54, v64, v54
	v_mul_f32_e32 v65, 0.5, v55
	v_mul_f32_e32 v64, 0.5, v54
	s_waitcnt lgkmcnt(0)
	v_pk_add_f32 v[54:55], v[52:53], v[66:67]
	v_sub_f32_e32 v53, v53, v67
	v_mul_f32_e32 v72, 0.5, v72
	v_mul_f32_e32 v58, 0.5, v58
	v_mul_f32_e32 v56, 0.5, v56
	v_mul_f32_e32 v54, 0.5, v54
	v_mul_f32_e32 v53, 0.5, v53
	v_sub_f32_e32 v52, v66, v52
	v_mul_f32_e32 v73, 0.5, v73
	v_mul_f32_e32 v59, 0.5, v59
	v_mul_f32_e32 v57, 0.5, v57
	v_mul_f32_e32 v67, 0.5, v55
	v_mul_f32_e32 v66, 0.5, v52
	v_cvt_pk_f16_f32 v55, v54, v53
	v_cvt_pk_f16_f32 v54, v56, v65
	v_cvt_pk_f16_f32 v53, v58, v63
	v_cvt_pk_f16_f32 v52, v72, v61
	global_store_dwordx4 v[28:29], v[52:55], off offset:-3072
	s_addc_u32 s95, s57, s11
	s_lshl_b64 s[0:1], s[68:69], 14
	v_cvt_pk_f16_f32 v55, v67, v66
	v_cvt_pk_f16_f32 v54, v57, v64
	v_cvt_pk_f16_f32 v53, v59, v62
	v_cvt_pk_f16_f32 v52, v73, v60
	global_store_dwordx4 v[0:1], v[52:55], off offset:-3072
	s_add_u32 s12, s26, s0
	s_addc_u32 s13, s27, s1
	v_or_b32_e32 v52, 8, v71
	v_bfrev_b32_e32 v52, v52
	v_lshrrev_b32_e32 v52, 18, v52
	v_sub_u32_e32 v62, 0, v52
	v_and_b32_e32 v54, 0x1fff, v62
	v_bfrev_b32_e32 v54, v54
	v_lshrrev_b32_e32 v55, 18, v54
	v_lshrrev_b32_e32 v54, 23, v54
	v_bitop3_b32 v54, v54, v55, 31 bitop3:0x6c
	v_or_b32_e32 v55, 10, v71
	v_bfrev_b32_e32 v55, v55
	v_lshrrev_b32_e32 v55, 18, v55
	v_sub_u32_e32 v55, 0, v55
	v_and_b32_e32 v55, 0x2fff, v55
	v_and_b32_e32 v52, 0x3fff, v62
	v_bfrev_b32_e32 v55, v55
	v_bfrev_b32_e32 v52, v52
	v_lshrrev_b32_e32 v56, 18, v55
	v_lshrrev_b32_e32 v55, 23, v55
	v_lshrrev_b32_e32 v53, 18, v52
	v_lshrrev_b32_e32 v52, 23, v52
	v_bitop3_b32 v55, v55, v56, 31 bitop3:0x6c
	v_bitop3_b32 v52, v52, v53, 31 bitop3:0x6c
	v_lshl_add_u32 v56, v55, 3, 16
	v_and_b32_e32 v55, 0xfff, v62
	v_lshl_add_u32 v52, v52, 3, 16
	v_bfrev_b32_e32 v55, v55
	ds_read_b64 v[52:53], v52
	v_lshrrev_b32_e32 v57, 18, v55
	v_lshrrev_b32_e32 v55, 23, v55
	v_bitop3_b32 v55, v55, v57, 31 bitop3:0x6c
	v_lshl_add_u32 v54, v54, 3, 16
	v_lshl_add_u32 v58, v55, 3, 16
	ds_read_b64 v[54:55], v54
	ds_read_b64 v[56:57], v56
	ds_read_b64 v[58:59], v58
	s_waitcnt lgkmcnt(3)
	v_pk_add_f32 v[60:61], v[50:51], v[52:53]
	v_sub_f32_e32 v51, v51, v53
	v_sub_f32_e32 v50, v52, v50
	v_mul_f32_e32 v53, 0.5, v51
	v_mul_f32_e32 v52, 0.5, v50
	s_waitcnt lgkmcnt(2)
	v_pk_add_f32 v[50:51], v[48:49], v[54:55]
	v_sub_f32_e32 v49, v49, v55
	v_sub_f32_e32 v48, v54, v48
	v_mul_f32_e32 v55, 0.5, v49
	v_mul_f32_e32 v54, 0.5, v48
	s_waitcnt lgkmcnt(1)
	v_pk_add_f32 v[48:49], v[46:47], v[56:57]
	v_sub_f32_e32 v47, v47, v57
	v_sub_f32_e32 v46, v56, v46
	v_mul_f32_e32 v57, 0.5, v47
	v_mul_f32_e32 v56, 0.5, v46
	s_waitcnt lgkmcnt(0)
	v_pk_add_f32 v[46:47], v[44:45], v[58:59]
	v_sub_f32_e32 v45, v45, v59
	v_mul_f32_e32 v60, 0.5, v60
	v_mul_f32_e32 v50, 0.5, v50
	v_mul_f32_e32 v48, 0.5, v48
	v_mul_f32_e32 v46, 0.5, v46
	v_mul_f32_e32 v45, 0.5, v45
	v_sub_f32_e32 v44, v58, v44
	v_mul_f32_e32 v61, 0.5, v61
	v_mul_f32_e32 v51, 0.5, v51
	v_mul_f32_e32 v49, 0.5, v49
	v_mul_f32_e32 v59, 0.5, v47
	v_mul_f32_e32 v58, 0.5, v44
	v_cvt_pk_f16_f32 v47, v46, v45
	v_cvt_pk_f16_f32 v46, v48, v57
	v_cvt_pk_f16_f32 v45, v50, v55
	v_cvt_pk_f16_f32 v44, v60, v53
	global_store_dwordx4 v[28:29], v[44:47], off offset:-2048
	s_add_u32 s14, s30, s0
	s_addc_u32 s15, s31, s1
	v_cvt_pk_f16_f32 v47, v59, v58
	v_cvt_pk_f16_f32 v46, v49, v56
	v_cvt_pk_f16_f32 v45, v51, v54
	v_cvt_pk_f16_f32 v44, v61, v52
	global_store_dwordx4 v[0:1], v[44:47], off offset:-2048
	v_cmp_lt_i32_e32 vcc, s25, v146
	v_add_u32_e32 v55, 0xe00, v146
	v_or_b32_e32 v44, 12, v71
	v_bfrev_b32_e32 v44, v44
	v_lshrrev_b32_e32 v44, 18, v44
	v_sub_u32_e32 v46, 0, v44
	v_and_b32_e32 v44, 0x37ff, v46
	v_and_b32_e32 v46, 0x17ff, v46
	v_bfrev_b32_e32 v46, v46
	v_lshrrev_b32_e32 v47, 18, v46
	v_lshrrev_b32_e32 v46, 23, v46
	v_bitop3_b32 v46, v46, v47, 31 bitop3:0x6c
	v_or_b32_e32 v47, 14, v71
	v_bfrev_b32_e32 v47, v47
	v_lshrrev_b32_e32 v47, 18, v47
	v_sub_u32_e32 v47, 0, v47
	v_and_b32_e32 v47, 0x27ff, v47
	v_bfrev_b32_e32 v47, v47
	v_bfrev_b32_e32 v44, v44
	v_lshrrev_b32_e32 v48, 18, v47
	v_lshrrev_b32_e32 v47, 23, v47
	v_lshrrev_b32_e32 v45, 18, v44
	v_lshrrev_b32_e32 v44, 23, v44
	v_bitop3_b32 v47, v47, v48, 31 bitop3:0x6c
	v_bitop3_b32 v44, v44, v45, 31 bitop3:0x6c
	v_lshl_add_u32 v48, v47, 3, 16
	v_and_b32_e32 v47, 0x7ff, v62
	v_lshl_add_u32 v44, v44, 3, 16
	v_bfrev_b32_e32 v47, v47
	ds_read_b64 v[44:45], v44
	v_lshrrev_b32_e32 v49, 18, v47
	v_lshrrev_b32_e32 v47, 23, v47
	v_bitop3_b32 v47, v47, v49, 31 bitop3:0x6c
	v_lshl_add_u32 v46, v46, 3, 16
	v_lshl_add_u32 v50, v47, 3, 16
	ds_read_b64 v[46:47], v46
	ds_read_b64 v[48:49], v48
	ds_read_b64 v[50:51], v50
	s_waitcnt lgkmcnt(3)
	v_pk_add_f32 v[52:53], v[34:35], v[44:45]
	v_sub_f32_e32 v35, v35, v45
	v_sub_f32_e32 v34, v44, v34
	v_mul_f32_e32 v45, 0.5, v35
	v_mul_f32_e32 v44, 0.5, v34
	s_waitcnt lgkmcnt(2)
	v_pk_add_f32 v[34:35], v[32:33], v[46:47]
	v_sub_f32_e32 v33, v33, v47
	v_sub_f32_e32 v32, v46, v32
	v_mul_f32_e32 v47, 0.5, v33
	v_mul_f32_e32 v46, 0.5, v32
	s_waitcnt lgkmcnt(1)
	v_pk_add_f32 v[32:33], v[30:31], v[48:49]
	v_sub_f32_e32 v31, v31, v49
	v_sub_f32_e32 v30, v48, v30
	v_mul_f32_e32 v49, 0.5, v31
	v_mul_f32_e32 v48, 0.5, v30
	s_waitcnt lgkmcnt(0)
	v_pk_add_f32 v[30:31], v[26:27], v[50:51]
	v_sub_f32_e32 v27, v27, v51
	v_mul_f32_e32 v52, 0.5, v52
	v_mul_f32_e32 v34, 0.5, v34
	v_mul_f32_e32 v32, 0.5, v32
	v_mul_f32_e32 v30, 0.5, v30
	v_mul_f32_e32 v27, 0.5, v27
	v_sub_f32_e32 v26, v50, v26
	v_mul_f32_e32 v53, 0.5, v53
	v_mul_f32_e32 v35, 0.5, v35
	v_mul_f32_e32 v54, 0.5, v33
	v_mul_f32_e32 v51, 0.5, v31
	v_mul_f32_e32 v26, 0.5, v26
	v_cvt_pk_f16_f32 v33, v30, v27
	v_cvt_pk_f16_f32 v32, v32, v49
	v_cvt_pk_f16_f32 v31, v34, v47
	v_cvt_pk_f16_f32 v30, v52, v45
	global_store_dwordx4 v[28:29], v[30:33], off offset:-1024
	v_add_u32_e32 v52, 0x800, v146
	s_nop 0
	v_cvt_pk_f16_f32 v33, v51, v26
	v_cvt_pk_f16_f32 v32, v54, v48
	v_cvt_pk_f16_f32 v31, v35, v46
	v_cvt_pk_f16_f32 v30, v53, v44
	global_store_dwordx4 v[0:1], v[30:33], off offset:-1024
	v_bfrev_b32_e32 v26, v88
	v_lshrrev_b32_e32 v26, 18, v26
	v_add_u32_e32 v30, 0x2001, v71
	v_bfrev_b32_e32 v30, v30
	v_lshrrev_b32_e32 v30, 18, v30
	v_sub_u32_e32 v30, 0, v30
	v_and_b32_e32 v30, 0x3fff, v30
	v_bfrev_b32_e32 v30, v30
	v_lshrrev_b32_e32 v31, 18, v30
	v_lshrrev_b32_e32 v30, 23, v30
	v_bitop3_b32 v30, v30, v31, 31 bitop3:0x6c
	v_add_u32_e32 v31, 0x2002, v71
	v_bfrev_b32_e32 v31, v31
	v_lshrrev_b32_e32 v31, 18, v31
	v_sub_u32_e32 v31, 0, v31
	v_and_b32_e32 v31, 0x3fff, v31
	v_bfrev_b32_e32 v31, v31
	v_lshrrev_b32_e32 v32, 18, v31
	v_lshrrev_b32_e32 v31, 23, v31
	v_bitop3_b32 v31, v31, v32, 31 bitop3:0x6c
	v_sub_u32_e32 v26, 0, v26
	v_lshl_add_u32 v32, v31, 3, 16
	v_add_u32_e32 v31, 0x2003, v71
	v_and_b32_e32 v26, 0x3fff, v26
	v_bfrev_b32_e32 v31, v31
	v_bfrev_b32_e32 v26, v26
	v_lshrrev_b32_e32 v31, 18, v31
	v_lshrrev_b32_e32 v27, 18, v26
	v_lshrrev_b32_e32 v26, 23, v26
	v_sub_u32_e32 v31, 0, v31
	v_bitop3_b32 v26, v26, v27, 31 bitop3:0x6c
	v_and_b32_e32 v31, 0x1fff, v31
	v_lshl_add_u32 v26, v26, 3, 16
	v_bfrev_b32_e32 v31, v31
	ds_read_b64 v[26:27], v26
	v_lshrrev_b32_e32 v33, 18, v31
	v_lshrrev_b32_e32 v31, 23, v31
	v_bitop3_b32 v31, v31, v33, 31 bitop3:0x6c
	v_lshl_add_u32 v30, v30, 3, 16
	v_lshl_add_u32 v34, v31, 3, 16
	ds_read_b64 v[30:31], v30
	ds_read_b64 v[32:33], v32
	ds_read_b64 v[34:35], v34
	s_waitcnt lgkmcnt(3)
	v_pk_add_f32 v[44:45], v[42:43], v[26:27]
	v_sub_f32_e32 v27, v43, v27
	v_sub_f32_e32 v26, v26, v42
	v_mul_f32_e32 v43, 0.5, v27
	v_mul_f32_e32 v42, 0.5, v26
	s_waitcnt lgkmcnt(2)
	v_pk_add_f32 v[26:27], v[40:41], v[30:31]
	v_mul_f32_e32 v44, 0.5, v44
	v_mul_f32_e32 v46, 0.5, v26
	v_sub_f32_e32 v26, v41, v31
	v_mul_f32_e32 v31, 0.5, v26
	v_sub_f32_e32 v26, v30, v40
	v_mul_f32_e32 v41, 0.5, v27
	v_mul_f32_e32 v40, 0.5, v26
	s_waitcnt lgkmcnt(1)
	v_pk_add_f32 v[26:27], v[38:39], v[32:33]
	v_mul_f32_e32 v45, 0.5, v45
	v_mul_f32_e32 v30, 0.5, v26
	v_sub_f32_e32 v26, v39, v33
	v_mul_f32_e32 v39, 0.5, v26
	v_sub_f32_e32 v26, v32, v38
	v_mul_f32_e32 v47, 0.5, v27
	v_mul_f32_e32 v38, 0.5, v26
	s_waitcnt lgkmcnt(0)
	v_pk_add_f32 v[26:27], v[36:37], v[34:35]
	v_sub_f32_e32 v32, v37, v35
	v_mul_f32_e32 v26, 0.5, v26
	v_mul_f32_e32 v32, 0.5, v32
	v_sub_f32_e32 v33, v34, v36
	v_mul_f32_e32 v27, 0.5, v27
	v_mul_f32_e32 v34, 0.5, v33
	v_cvt_pk_f16_f32 v33, v26, v32
	v_cvt_pk_f16_f32 v32, v30, v39
	v_cvt_pk_f16_f32 v31, v46, v31
	v_cvt_pk_f16_f32 v30, v44, v43
	global_store_dwordx4 v[28:29], v[30:33], off
	v_add_u32_e32 v26, 0x2004, v71
	v_bfrev_b32_e32 v26, v26
	v_cvt_pk_f16_f32 v33, v27, v34
	v_cvt_pk_f16_f32 v32, v47, v38
	v_cvt_pk_f16_f32 v31, v41, v40
	v_cvt_pk_f16_f32 v30, v45, v42
	global_store_dwordx4 v[0:1], v[30:33], off
	v_lshrrev_b32_e32 v26, 18, v26
	v_sub_u32_e32 v26, 0, v26
	v_add_u32_e32 v30, 0x2005, v71
	v_bfrev_b32_e32 v30, v30
	v_lshrrev_b32_e32 v30, 18, v30
	v_sub_u32_e32 v30, 0, v30
	v_and_b32_e32 v30, 0x1fff, v30
	v_bfrev_b32_e32 v30, v30
	v_lshrrev_b32_e32 v31, 18, v30
	v_lshrrev_b32_e32 v30, 23, v30
	v_bitop3_b32 v30, v30, v31, 31 bitop3:0x6c
	v_add_u32_e32 v31, 0x2006, v71
	v_bfrev_b32_e32 v31, v31
	v_lshrrev_b32_e32 v31, 18, v31
	v_sub_u32_e32 v31, 0, v31
	v_and_b32_e32 v31, 0x2fff, v31
	v_bfrev_b32_e32 v31, v31
	v_lshrrev_b32_e32 v32, 18, v31
	v_lshrrev_b32_e32 v31, 23, v31
	v_bitop3_b32 v31, v31, v32, 31 bitop3:0x6c
	v_lshl_add_u32 v32, v31, 3, 16
	v_add_u32_e32 v31, 0x2007, v71
	v_and_b32_e32 v26, 0x3fff, v26
	v_bfrev_b32_e32 v31, v31
	v_bfrev_b32_e32 v26, v26
	v_lshrrev_b32_e32 v31, 18, v31
	v_lshrrev_b32_e32 v27, 18, v26
	v_lshrrev_b32_e32 v26, 23, v26
	v_sub_u32_e32 v31, 0, v31
	v_bitop3_b32 v26, v26, v27, 31 bitop3:0x6c
	v_and_b32_e32 v31, 0xfff, v31
	v_lshl_add_u32 v26, v26, 3, 16
	v_bfrev_b32_e32 v31, v31
	ds_read_b64 v[26:27], v26
	v_lshrrev_b32_e32 v33, 18, v31
	v_lshrrev_b32_e32 v31, 23, v31
	v_bitop3_b32 v31, v31, v33, 31 bitop3:0x6c
	v_lshl_add_u32 v30, v30, 3, 16
	v_lshl_add_u32 v34, v31, 3, 16
	ds_read_b64 v[30:31], v30
	ds_read_b64 v[32:33], v32
	ds_read_b64 v[34:35], v34
	s_waitcnt lgkmcnt(3)
	v_pk_add_f32 v[36:37], v[24:25], v[26:27]
	v_sub_f32_e32 v25, v25, v27
	v_sub_f32_e32 v24, v26, v24
	v_mul_f32_e32 v27, 0.5, v25
	v_mul_f32_e32 v26, 0.5, v24
	s_waitcnt lgkmcnt(2)
	v_pk_add_f32 v[24:25], v[22:23], v[30:31]
	v_sub_f32_e32 v23, v23, v31
	v_sub_f32_e32 v22, v30, v22
	v_mul_f32_e32 v31, 0.5, v23
	v_mul_f32_e32 v30, 0.5, v22
	s_waitcnt lgkmcnt(1)
	v_pk_add_f32 v[22:23], v[20:21], v[32:33]
	v_sub_f32_e32 v21, v21, v33
	v_sub_f32_e32 v20, v32, v20
	v_mul_f32_e32 v33, 0.5, v21
	v_mul_f32_e32 v32, 0.5, v20
	s_waitcnt lgkmcnt(0)
	v_pk_add_f32 v[20:21], v[18:19], v[34:35]
	v_sub_f32_e32 v19, v19, v35
	v_mul_f32_e32 v36, 0.5, v36
	v_mul_f32_e32 v24, 0.5, v24
	v_mul_f32_e32 v22, 0.5, v22
	v_mul_f32_e32 v20, 0.5, v20
	v_mul_f32_e32 v19, 0.5, v19
	v_sub_f32_e32 v18, v34, v18
	v_mul_f32_e32 v37, 0.5, v37
	v_mul_f32_e32 v25, 0.5, v25
	v_mul_f32_e32 v23, 0.5, v23
	v_mul_f32_e32 v35, 0.5, v21
	v_mul_f32_e32 v34, 0.5, v18
	v_cvt_pk_f16_f32 v21, v20, v19
	v_cvt_pk_f16_f32 v20, v22, v33
	v_cvt_pk_f16_f32 v19, v24, v31
	v_cvt_pk_f16_f32 v18, v36, v27
	global_store_dwordx4 v[28:29], v[18:21], off offset:1024
	v_add_u32_e32 v53, 0xa00, v146
	v_add_u32_e32 v54, 0xc00, v146
	v_cvt_pk_f16_f32 v21, v35, v34
	v_cvt_pk_f16_f32 v20, v23, v32
	v_cvt_pk_f16_f32 v19, v25, v30
	v_cvt_pk_f16_f32 v18, v37, v26
	global_store_dwordx4 v[0:1], v[18:21], off offset:1024
	v_add_u32_e32 v47, 0x1000, v146
	v_add_u32_e32 v46, 0x1200, v146
	v_add_u32_e32 v20, 0x2009, v71
	v_bfrev_b32_e32 v20, v20
	v_lshrrev_b32_e32 v20, 18, v20
	v_sub_u32_e32 v20, 0, v20
	v_and_b32_e32 v20, 0x1fff, v20
	v_bfrev_b32_e32 v20, v20
	v_lshrrev_b32_e32 v21, 18, v20
	v_lshrrev_b32_e32 v20, 23, v20
	v_bitop3_b32 v20, v20, v21, 31 bitop3:0x6c
	v_add_u32_e32 v21, 0x200a, v71
	v_bfrev_b32_e32 v21, v21
	v_lshrrev_b32_e32 v21, 18, v21
	v_sub_u32_e32 v21, 0, v21
	v_and_b32_e32 v21, 0x2fff, v21
	v_add_u32_e32 v18, 0x2008, v71
	v_bfrev_b32_e32 v21, v21
	v_bfrev_b32_e32 v18, v18
	v_lshrrev_b32_e32 v22, 18, v21
	v_lshrrev_b32_e32 v21, 23, v21
	v_lshrrev_b32_e32 v18, 18, v18
	v_bitop3_b32 v21, v21, v22, 31 bitop3:0x6c
	v_sub_u32_e32 v18, 0, v18
	v_lshl_add_u32 v22, v21, 3, 16
	v_add_u32_e32 v21, 0x200b, v71
	v_and_b32_e32 v18, 0x3fff, v18
	v_bfrev_b32_e32 v21, v21
	v_bfrev_b32_e32 v18, v18
	v_lshrrev_b32_e32 v21, 18, v21
	v_lshrrev_b32_e32 v19, 18, v18
	v_lshrrev_b32_e32 v18, 23, v18
	v_sub_u32_e32 v21, 0, v21
	v_bitop3_b32 v18, v18, v19, 31 bitop3:0x6c
	v_and_b32_e32 v21, 0xfff, v21
	v_lshl_add_u32 v18, v18, 3, 16
	v_bfrev_b32_e32 v21, v21
	ds_read_b64 v[18:19], v18
	v_lshrrev_b32_e32 v23, 18, v21
	v_lshrrev_b32_e32 v21, 23, v21
	v_bitop3_b32 v21, v21, v23, 31 bitop3:0x6c
	v_lshl_add_u32 v20, v20, 3, 16
	v_lshl_add_u32 v24, v21, 3, 16
	ds_read_b64 v[20:21], v20
	ds_read_b64 v[22:23], v22
	ds_read_b64 v[24:25], v24
	s_waitcnt lgkmcnt(3)
	v_pk_add_f32 v[26:27], v[16:17], v[18:19]
	v_sub_f32_e32 v17, v17, v19
	v_sub_f32_e32 v16, v18, v16
	v_mul_f32_e32 v19, 0.5, v17
	v_mul_f32_e32 v18, 0.5, v16
	s_waitcnt lgkmcnt(2)
	v_pk_add_f32 v[16:17], v[14:15], v[20:21]
	v_sub_f32_e32 v15, v15, v21
	v_sub_f32_e32 v14, v20, v14
	v_mul_f32_e32 v21, 0.5, v15
	v_mul_f32_e32 v20, 0.5, v14
	s_waitcnt lgkmcnt(1)
	v_pk_add_f32 v[14:15], v[12:13], v[22:23]
	v_sub_f32_e32 v13, v13, v23
	v_sub_f32_e32 v12, v22, v12
	v_mul_f32_e32 v23, 0.5, v13
	v_mul_f32_e32 v22, 0.5, v12
	s_waitcnt lgkmcnt(0)
	v_pk_add_f32 v[12:13], v[10:11], v[24:25]
	v_sub_f32_e32 v11, v11, v25
	v_mul_f32_e32 v26, 0.5, v26
	v_mul_f32_e32 v16, 0.5, v16
	v_mul_f32_e32 v14, 0.5, v14
	v_mul_f32_e32 v12, 0.5, v12
	v_mul_f32_e32 v11, 0.5, v11
	v_sub_f32_e32 v10, v24, v10
	v_mul_f32_e32 v27, 0.5, v27
	v_mul_f32_e32 v17, 0.5, v17
	v_mul_f32_e32 v15, 0.5, v15
	v_mul_f32_e32 v25, 0.5, v13
	v_mul_f32_e32 v24, 0.5, v10
	v_cvt_pk_f16_f32 v13, v12, v11
	v_cvt_pk_f16_f32 v12, v14, v23
	v_cvt_pk_f16_f32 v11, v16, v21
	v_cvt_pk_f16_f32 v10, v26, v19
	global_store_dwordx4 v[28:29], v[10:13], off offset:2048
	v_add_u32_e32 v26, 0x1600, v146
	s_nop 0
	v_cvt_pk_f16_f32 v13, v25, v24
	v_cvt_pk_f16_f32 v12, v15, v22
	v_cvt_pk_f16_f32 v11, v17, v20
	v_cvt_pk_f16_f32 v10, v27, v18
	global_store_dwordx4 v[0:1], v[10:13], off offset:2048
	v_add_u32_e32 v27, 0x1400, v146
	s_nop 0
	v_add_u32_e32 v12, 0x200d, v71
	v_bfrev_b32_e32 v12, v12
	v_lshrrev_b32_e32 v12, 18, v12
	v_sub_u32_e32 v12, 0, v12
	v_and_b32_e32 v12, 0x17ff, v12
	v_bfrev_b32_e32 v12, v12
	v_lshrrev_b32_e32 v13, 18, v12
	v_lshrrev_b32_e32 v12, 23, v12
	v_bitop3_b32 v12, v12, v13, 31 bitop3:0x6c
	v_add_u32_e32 v13, 0x200e, v71
	v_bfrev_b32_e32 v13, v13
	v_lshrrev_b32_e32 v13, 18, v13
	v_sub_u32_e32 v13, 0, v13
	v_and_b32_e32 v13, 0x27ff, v13
	v_add_u32_e32 v10, 0x200c, v71
	v_bfrev_b32_e32 v13, v13
	v_bfrev_b32_e32 v10, v10
	v_lshrrev_b32_e32 v14, 18, v13
	v_lshrrev_b32_e32 v13, 23, v13
	v_lshrrev_b32_e32 v10, 18, v10
	v_bitop3_b32 v13, v13, v14, 31 bitop3:0x6c
	v_sub_u32_e32 v10, 0, v10
	v_lshl_add_u32 v14, v13, 3, 16
	v_add_u32_e32 v13, 0x200f, v71
	v_and_b32_e32 v10, 0x37ff, v10
	v_bfrev_b32_e32 v13, v13
	v_bfrev_b32_e32 v10, v10
	v_lshrrev_b32_e32 v13, 18, v13
	v_lshrrev_b32_e32 v11, 18, v10
	v_lshrrev_b32_e32 v10, 23, v10
	v_sub_u32_e32 v13, 0, v13
	v_bitop3_b32 v10, v10, v11, 31 bitop3:0x6c
	v_and_b32_e32 v13, 0x7ff, v13
	v_lshl_add_u32 v10, v10, 3, 16
	v_bfrev_b32_e32 v13, v13
	ds_read_b64 v[10:11], v10
	v_lshrrev_b32_e32 v15, 18, v13
	v_lshrrev_b32_e32 v13, 23, v13
	v_bitop3_b32 v13, v13, v15, 31 bitop3:0x6c
	v_lshl_add_u32 v12, v12, 3, 16
	v_lshl_add_u32 v16, v13, 3, 16
	ds_read_b64 v[12:13], v12
	ds_read_b64 v[14:15], v14
	ds_read_b64 v[16:17], v16
	s_waitcnt lgkmcnt(3)
	v_pk_add_f32 v[18:19], v[8:9], v[10:11]
	v_sub_f32_e32 v9, v9, v11
	v_sub_f32_e32 v8, v10, v8
	v_mul_f32_e32 v11, 0.5, v9
	v_mul_f32_e32 v10, 0.5, v8
	s_waitcnt lgkmcnt(2)
	v_pk_add_f32 v[8:9], v[6:7], v[12:13]
	v_sub_f32_e32 v7, v7, v13
	v_sub_f32_e32 v6, v12, v6
	v_mul_f32_e32 v13, 0.5, v7
	v_mul_f32_e32 v12, 0.5, v6
	s_waitcnt lgkmcnt(1)
	v_pk_add_f32 v[6:7], v[4:5], v[14:15]
	v_sub_f32_e32 v5, v5, v15
	v_sub_f32_e32 v4, v14, v4
	v_mul_f32_e32 v15, 0.5, v5
	v_mul_f32_e32 v14, 0.5, v4
	s_waitcnt lgkmcnt(0)
	v_pk_add_f32 v[4:5], v[2:3], v[16:17]
	v_sub_f32_e32 v3, v3, v17
	v_mul_f32_e32 v18, 0.5, v18
	v_mul_f32_e32 v8, 0.5, v8
	v_mul_f32_e32 v6, 0.5, v6
	v_mul_f32_e32 v4, 0.5, v4
	v_mul_f32_e32 v3, 0.5, v3
	v_sub_f32_e32 v2, v16, v2
	v_mul_f32_e32 v19, 0.5, v19
	v_mul_f32_e32 v9, 0.5, v9
	v_mul_f32_e32 v7, 0.5, v7
	v_mul_f32_e32 v17, 0.5, v5
	v_mul_f32_e32 v16, 0.5, v2
	v_cvt_pk_f16_f32 v5, v4, v3
	v_cvt_pk_f16_f32 v4, v6, v15
	v_cvt_pk_f16_f32 v3, v8, v13
	v_cvt_pk_f16_f32 v2, v18, v11
	global_store_dwordx4 v[28:29], v[2:5], off offset:3072
	s_nop 1
	v_cvt_pk_f16_f32 v5, v17, v16
	v_cvt_pk_f16_f32 v4, v7, v14
	v_cvt_pk_f16_f32 v3, v9, v12
	v_cvt_pk_f16_f32 v2, v19, v10
	global_store_dwordx4 v[0:1], v[2:5], off offset:3072
	global_load_dword v2, v153, s[90:91] offset:2048
	global_load_dword v0, v154, s[90:91]
	global_load_dword v6, v145, s[90:91]
	global_load_dword v4, v145, s[94:95]
	v_lshlrev_b32_e32 v8, 1, v146
	v_max_i32_e32 v12, 1, v146
	v_add_u32_e32 v13, 0x1e00, v146
	v_cmp_lt_i32_e32 vcc, 0, v146
	v_add_u32_e32 v9, 0x1000, v8
	v_add_u32_e32 v10, 0x2000, v8
	v_add_u32_e32 v11, 0x3000, v8
	v_lshlrev_b32_e32 v12, 1, v12
	v_cndmask_b32_e64 v14, 0, 1.0, vcc
	v_cmp_gt_i32_e32 vcc, 0x1fff, v13
	v_min_i32_e32 v13, 0x1ffe, v13
	v_lshlrev_b32_e32 v13, 1, v13
	s_nop 0
	v_cndmask_b32_e64 v15, 0, 1.0, vcc
	global_load_ushort v163, v12, s[12:13] offset:-2
	global_load_ushort v164, v8, s[12:13]
	global_load_ushort v165, v8, s[12:13] offset:2
	global_load_ushort v166, v12, s[14:15] offset:-2
	global_load_ushort v167, v8, s[14:15]
	global_load_ushort v168, v8, s[14:15] offset:2
	global_load_ushort v169, v8, s[12:13] offset:1022
	global_load_ushort v170, v8, s[12:13] offset:1024
	global_load_ushort v171, v8, s[12:13] offset:1026
	global_load_ushort v172, v8, s[14:15] offset:1022
	global_load_ushort v173, v8, s[14:15] offset:1024
	global_load_ushort v174, v8, s[14:15] offset:1026
	global_load_ushort v175, v8, s[12:13] offset:2046
	global_load_ushort v176, v8, s[12:13] offset:2048
	global_load_ushort v177, v8, s[12:13] offset:2050
	global_load_ushort v178, v8, s[14:15] offset:2046
	global_load_ushort v179, v8, s[14:15] offset:2048
	global_load_ushort v180, v8, s[14:15] offset:2050
	global_load_ushort v181, v8, s[12:13] offset:3070
	global_load_ushort v182, v8, s[12:13] offset:3072
	global_load_ushort v183, v8, s[12:13] offset:3074
	global_load_ushort v184, v8, s[14:15] offset:3070
	global_load_ushort v185, v8, s[14:15] offset:3072
	global_load_ushort v186, v8, s[14:15] offset:3074
	global_load_ushort v187, v9, s[12:13] offset:-2
	global_load_ushort v188, v9, s[12:13]
	global_load_ushort v189, v9, s[12:13] offset:2
	global_load_ushort v190, v9, s[14:15] offset:-2
	global_load_ushort v191, v9, s[14:15]
	global_load_ushort v192, v9, s[14:15] offset:2
	global_load_ushort v193, v9, s[12:13] offset:1022
	global_load_ushort v194, v9, s[12:13] offset:1024
	global_load_ushort v195, v9, s[12:13] offset:1026
	global_load_ushort v196, v9, s[14:15] offset:1022
	global_load_ushort v197, v9, s[14:15] offset:1024
	global_load_ushort v62, v9, s[14:15] offset:1026
	global_load_ushort v63, v9, s[12:13] offset:2046
	global_load_ushort v64, v9, s[12:13] offset:2048
	global_load_ushort v65, v9, s[12:13] offset:2050
	global_load_ushort v66, v9, s[14:15] offset:2046
	global_load_ushort v67, v9, s[14:15] offset:2048
	global_load_ushort v68, v9, s[14:15] offset:2050
	global_load_ushort v69, v9, s[12:13] offset:3070
	global_load_ushort v70, v9, s[12:13] offset:3072
	global_load_ushort v71, v9, s[12:13] offset:3074
	global_load_ushort v72, v9, s[14:15] offset:3070
	global_load_ushort v73, v9, s[14:15] offset:3072
	global_load_ushort v74, v9, s[14:15] offset:3074
	global_load_ushort v75, v10, s[12:13] offset:-2
	global_load_ushort v76, v10, s[12:13]
	global_load_ushort v77, v10, s[12:13] offset:2
	global_load_ushort v221, v10, s[14:15] offset:-2
	global_load_ushort v222, v10, s[14:15]
	global_load_ushort v223, v10, s[14:15] offset:2
	global_load_ushort v224, v10, s[12:13] offset:1022
	global_load_ushort v225, v10, s[12:13] offset:1024
	global_load_ushort v226, v10, s[12:13] offset:1026
	global_load_ushort v227, v10, s[14:15] offset:1022
	global_load_ushort v228, v10, s[14:15] offset:1024
	global_load_ushort v229, v10, s[14:15] offset:1026
	global_load_ushort v230, v10, s[12:13] offset:2046
	global_load_ushort v231, v10, s[12:13] offset:2048
	global_load_ushort v232, v10, s[12:13] offset:2050
	global_load_ushort v233, v10, s[14:15] offset:2046
	global_load_ushort v234, v10, s[14:15] offset:2048
	global_load_ushort v235, v10, s[14:15] offset:2050
	global_load_ushort v236, v10, s[12:13] offset:3070
	global_load_ushort v237, v10, s[12:13] offset:3072
	global_load_ushort v238, v10, s[12:13] offset:3074
	global_load_ushort v239, v10, s[14:15] offset:3070
	global_load_ushort v240, v10, s[14:15] offset:3072
	global_load_ushort v241, v10, s[14:15] offset:3074
	global_load_ushort v242, v11, s[12:13] offset:-2
	global_load_ushort v243, v11, s[12:13]
	global_load_ushort v244, v11, s[12:13] offset:2
	global_load_ushort v245, v11, s[14:15] offset:-2
	global_load_ushort v246, v11, s[14:15]
	global_load_ushort v247, v11, s[14:15] offset:2
	global_load_ushort v248, v11, s[12:13] offset:1022
	global_load_ushort v249, v11, s[12:13] offset:1024
	global_load_ushort v250, v11, s[12:13] offset:1026
	global_load_ushort v251, v11, s[14:15] offset:1022
	global_load_ushort v253, v11, s[14:15] offset:1024
	global_load_ushort v254, v11, s[14:15] offset:1026
	global_load_ushort v255, v11, s[12:13] offset:2046
	global_load_ushort v1, v11, s[12:13] offset:2048
	global_load_ushort v3, v11, s[12:13] offset:2050
	global_load_ushort v5, v11, s[14:15] offset:2046
	global_load_ushort v7, v11, s[14:15] offset:2048
	global_load_ushort v16, v11, s[14:15] offset:2050
	global_load_ushort v17, v11, s[12:13] offset:3070
	global_load_ushort v18, v11, s[12:13] offset:3072
	global_load_ushort v19, v13, s[12:13] offset:2
	global_load_ushort v20, v11, s[14:15] offset:3070
	global_load_ushort v21, v11, s[14:15] offset:3072
	global_load_ushort v22, v13, s[14:15] offset:2
	s_waitcnt vmcnt(48)
	v_lshlrev_b32_e32 v163, 16, v163
	v_lshlrev_b32_e32 v164, 16, v164
	v_lshlrev_b32_e32 v165, 16, v165
	v_mul_f32_e32 v163, v14, v163
	v_mul_f32_e32 v163, v6, v163
	v_fmac_f32_e32 v163, v2, v164
	v_fmac_f32_e32 v163, v0, v165
	v_add_f32_e32 v32, v4, v163
	v_lshlrev_b32_e32 v166, 16, v166
	v_lshlrev_b32_e32 v167, 16, v167
	v_lshlrev_b32_e32 v168, 16, v168
	v_mul_f32_e32 v166, v14, v166
	v_mul_f32_e32 v166, v6, v166
	v_fmac_f32_e32 v166, v2, v167
	v_fmac_f32_e32 v166, v0, v168
	v_add_f32_e32 v34, v4, v166
	v_lshlrev_b32_e32 v169, 16, v169
	v_lshlrev_b32_e32 v170, 16, v170
	v_lshlrev_b32_e32 v171, 16, v171
	v_mul_f32_e32 v169, v6, v169
	v_fmac_f32_e32 v169, v2, v170
	v_fmac_f32_e32 v169, v0, v171
	v_add_f32_e32 v33, v4, v169
	v_lshlrev_b32_e32 v172, 16, v172
	v_lshlrev_b32_e32 v173, 16, v173
	v_lshlrev_b32_e32 v174, 16, v174
	v_mul_f32_e32 v172, v6, v172
	v_fmac_f32_e32 v172, v2, v173
	v_fmac_f32_e32 v172, v0, v174
	v_add_f32_e32 v35, v4, v172
	v_lshlrev_b32_e32 v175, 16, v175
	v_lshlrev_b32_e32 v176, 16, v176
	v_lshlrev_b32_e32 v177, 16, v177
	v_mul_f32_e32 v175, v6, v175
	v_fmac_f32_e32 v175, v2, v176
	v_fmac_f32_e32 v175, v0, v177
	v_add_f32_e32 v37, v4, v175
	v_lshlrev_b32_e32 v178, 16, v178
	v_lshlrev_b32_e32 v179, 16, v179
	v_lshlrev_b32_e32 v180, 16, v180
	v_mul_f32_e32 v178, v6, v178
	v_fmac_f32_e32 v178, v2, v179
	v_fmac_f32_e32 v178, v0, v180
	v_add_f32_e32 v31, v4, v178
	v_lshlrev_b32_e32 v181, 16, v181
	v_lshlrev_b32_e32 v182, 16, v182
	v_lshlrev_b32_e32 v183, 16, v183
	v_mul_f32_e32 v181, v6, v181
	v_fmac_f32_e32 v181, v2, v182
	v_fmac_f32_e32 v181, v0, v183
	v_add_f32_e32 v36, v4, v181
	v_lshlrev_b32_e32 v184, 16, v184
	v_lshlrev_b32_e32 v185, 16, v185
	v_lshlrev_b32_e32 v186, 16, v186
	v_mul_f32_e32 v184, v6, v184
	v_fmac_f32_e32 v184, v2, v185
	v_fmac_f32_e32 v184, v0, v186
	v_add_f32_e32 v30, v4, v184
	v_lshlrev_b32_e32 v187, 16, v187
	v_lshlrev_b32_e32 v188, 16, v188
	v_lshlrev_b32_e32 v189, 16, v189
	v_mul_f32_e32 v187, v6, v187
	v_fmac_f32_e32 v187, v2, v188
	v_fmac_f32_e32 v187, v0, v189
	v_add_f32_e32 v39, v4, v187
	v_lshlrev_b32_e32 v190, 16, v190
	v_lshlrev_b32_e32 v191, 16, v191
	v_lshlrev_b32_e32 v192, 16, v192
	v_mul_f32_e32 v190, v6, v190
	v_fmac_f32_e32 v190, v2, v191
	v_fmac_f32_e32 v190, v0, v192
	v_add_f32_e32 v41, v4, v190
	v_lshlrev_b32_e32 v193, 16, v193
	v_lshlrev_b32_e32 v194, 16, v194
	v_lshlrev_b32_e32 v195, 16, v195
	v_mul_f32_e32 v193, v6, v193
	v_fmac_f32_e32 v193, v2, v194
	v_fmac_f32_e32 v193, v0, v195
	v_add_f32_e32 v38, v4, v193
	v_lshlrev_b32_e32 v196, 16, v196
	v_lshlrev_b32_e32 v197, 16, v197
	v_lshlrev_b32_e32 v62, 16, v62
	v_mul_f32_e32 v196, v6, v196
	v_fmac_f32_e32 v196, v2, v197
	v_fmac_f32_e32 v196, v0, v62
	v_add_f32_e32 v40, v4, v196
	v_lshlrev_b32_e32 v63, 16, v63
	v_lshlrev_b32_e32 v64, 16, v64
	v_lshlrev_b32_e32 v65, 16, v65
	v_mul_f32_e32 v63, v6, v63
	v_fmac_f32_e32 v63, v2, v64
	v_fmac_f32_e32 v63, v0, v65
	v_add_f32_e32 v43, v4, v63
	v_lshlrev_b32_e32 v66, 16, v66
	v_lshlrev_b32_e32 v67, 16, v67
	v_lshlrev_b32_e32 v68, 16, v68
	v_mul_f32_e32 v66, v6, v66
	v_fmac_f32_e32 v66, v2, v67
	v_fmac_f32_e32 v66, v0, v68
	v_add_f32_e32 v45, v4, v66
	v_lshlrev_b32_e32 v69, 16, v69
	v_lshlrev_b32_e32 v70, 16, v70
	v_lshlrev_b32_e32 v71, 16, v71
	v_mul_f32_e32 v69, v6, v69
	v_fmac_f32_e32 v69, v2, v70
	v_fmac_f32_e32 v69, v0, v71
	v_add_f32_e32 v42, v4, v69
	v_lshlrev_b32_e32 v72, 16, v72
	v_lshlrev_b32_e32 v73, 16, v73
	v_lshlrev_b32_e32 v74, 16, v74
	v_mul_f32_e32 v72, v6, v72
	v_fmac_f32_e32 v72, v2, v73
	v_fmac_f32_e32 v72, v0, v74
	v_add_f32_e32 v44, v4, v72
	s_waitcnt vmcnt(0)
	v_lshlrev_b32_e32 v75, 16, v75
	v_lshlrev_b32_e32 v76, 16, v76
	v_lshlrev_b32_e32 v77, 16, v77
	v_mul_f32_e32 v75, v6, v75
	v_fmac_f32_e32 v75, v2, v76
	v_fmac_f32_e32 v75, v0, v77
	v_add_f32_e32 v47, v4, v75
	v_lshlrev_b32_e32 v221, 16, v221
	v_lshlrev_b32_e32 v222, 16, v222
	v_lshlrev_b32_e32 v223, 16, v223
	v_mul_f32_e32 v221, v6, v221
	v_fmac_f32_e32 v221, v2, v222
	v_fmac_f32_e32 v221, v0, v223
	v_add_f32_e32 v49, v4, v221
	v_lshlrev_b32_e32 v224, 16, v224
	v_lshlrev_b32_e32 v225, 16, v225
	v_lshlrev_b32_e32 v226, 16, v226
	v_mul_f32_e32 v224, v6, v224
	v_fmac_f32_e32 v224, v2, v225
	v_fmac_f32_e32 v224, v0, v226
	v_add_f32_e32 v46, v4, v224
	v_lshlrev_b32_e32 v227, 16, v227
	v_lshlrev_b32_e32 v228, 16, v228
	v_lshlrev_b32_e32 v229, 16, v229
	v_mul_f32_e32 v227, v6, v227
	v_fmac_f32_e32 v227, v2, v228
	v_fmac_f32_e32 v227, v0, v229
	v_add_f32_e32 v48, v4, v227
	v_lshlrev_b32_e32 v230, 16, v230
	v_lshlrev_b32_e32 v231, 16, v231
	v_lshlrev_b32_e32 v232, 16, v232
	v_mul_f32_e32 v230, v6, v230
	v_fmac_f32_e32 v230, v2, v231
	v_fmac_f32_e32 v230, v0, v232
	v_add_f32_e32 v51, v4, v230
	v_lshlrev_b32_e32 v233, 16, v233
	v_lshlrev_b32_e32 v234, 16, v234
	v_lshlrev_b32_e32 v235, 16, v235
	v_mul_f32_e32 v233, v6, v233
	v_fmac_f32_e32 v233, v2, v234
	v_fmac_f32_e32 v233, v0, v235
	v_add_f32_e32 v53, v4, v233
	v_lshlrev_b32_e32 v236, 16, v236
	v_lshlrev_b32_e32 v237, 16, v237
	v_lshlrev_b32_e32 v238, 16, v238
	v_mul_f32_e32 v236, v6, v236
	v_fmac_f32_e32 v236, v2, v237
	v_fmac_f32_e32 v236, v0, v238
	v_add_f32_e32 v50, v4, v236
	v_lshlrev_b32_e32 v239, 16, v239
	v_lshlrev_b32_e32 v240, 16, v240
	v_lshlrev_b32_e32 v241, 16, v241
	v_mul_f32_e32 v239, v6, v239
	v_fmac_f32_e32 v239, v2, v240
	v_fmac_f32_e32 v239, v0, v241
	v_add_f32_e32 v52, v4, v239
	v_lshlrev_b32_e32 v242, 16, v242
	v_lshlrev_b32_e32 v243, 16, v243
	v_lshlrev_b32_e32 v244, 16, v244
	v_mul_f32_e32 v242, v6, v242
	v_fmac_f32_e32 v242, v2, v243
	v_fmac_f32_e32 v242, v0, v244
	v_add_f32_e32 v55, v4, v242
	v_lshlrev_b32_e32 v245, 16, v245
	v_lshlrev_b32_e32 v246, 16, v246
	v_lshlrev_b32_e32 v247, 16, v247
	v_mul_f32_e32 v245, v6, v245
	v_fmac_f32_e32 v245, v2, v246
	v_fmac_f32_e32 v245, v0, v247
	v_add_f32_e32 v57, v4, v245
	v_lshlrev_b32_e32 v248, 16, v248
	v_lshlrev_b32_e32 v249, 16, v249
	v_lshlrev_b32_e32 v250, 16, v250
	v_mul_f32_e32 v248, v6, v248
	v_fmac_f32_e32 v248, v2, v249
	v_fmac_f32_e32 v248, v0, v250
	v_add_f32_e32 v54, v4, v248
	v_lshlrev_b32_e32 v251, 16, v251
	v_lshlrev_b32_e32 v253, 16, v253
	v_lshlrev_b32_e32 v254, 16, v254
	v_mul_f32_e32 v251, v6, v251
	v_fmac_f32_e32 v251, v2, v253
	v_fmac_f32_e32 v251, v0, v254
	v_add_f32_e32 v56, v4, v251
	v_lshlrev_b32_e32 v255, 16, v255
	v_lshlrev_b32_e32 v1, 16, v1
	v_lshlrev_b32_e32 v3, 16, v3
	v_mul_f32_e32 v255, v6, v255
	v_fmac_f32_e32 v255, v2, v1
	v_fmac_f32_e32 v255, v0, v3
	v_add_f32_e32 v59, v4, v255
	v_lshlrev_b32_e32 v5, 16, v5
	v_lshlrev_b32_e32 v7, 16, v7
	v_lshlrev_b32_e32 v16, 16, v16
	v_mul_f32_e32 v5, v6, v5
	v_fmac_f32_e32 v5, v2, v7
	v_fmac_f32_e32 v5, v0, v16
	v_add_f32_e32 v61, v4, v5
	v_lshlrev_b32_e32 v17, 16, v17
	v_lshlrev_b32_e32 v18, 16, v18
	v_lshlrev_b32_e32 v19, 16, v19
	v_mul_f32_e32 v19, v15, v19
	v_mul_f32_e32 v17, v6, v17
	v_fmac_f32_e32 v17, v2, v18
	v_fmac_f32_e32 v17, v0, v19
	v_add_f32_e32 v58, v4, v17
	v_lshlrev_b32_e32 v20, 16, v20
	v_lshlrev_b32_e32 v21, 16, v21
	v_lshlrev_b32_e32 v22, 16, v22
	v_mul_f32_e32 v22, v15, v22
	v_mul_f32_e32 v20, v6, v20
	v_fmac_f32_e32 v20, v2, v21
	v_fmac_f32_e32 v20, v0, v22
	v_add_f32_e32 v60, v4, v20
	v_readlane_b32 s72, v252, 22
	v_readlane_b32 s78, v252, 28
	v_readlane_b32 s79, v252, 29
	s_add_u32 s24, s78, s10
	s_addc_u32 s59, s79, s11
	s_lshl_b64 s[0:1], s[68:69], 1
	v_readlane_b32 s4, v252, 50
	v_readlane_b32 s73, v252, 23
	v_readlane_b32 s74, v252, 24
	v_readlane_b32 s75, v252, 25
	v_readlane_b32 s76, v252, 26
	v_readlane_b32 s77, v252, 27
	v_readlane_b32 s80, v252, 30
	v_readlane_b32 s81, v252, 31
	v_readlane_b32 s82, v252, 32
	v_readlane_b32 s83, v252, 33
	s_add_u32 s96, s4, s0
	v_readlane_b32 s0, v252, 51
	s_movk_i32 s83, 0xea00
	s_movk_i32 s82, 0xdff
	s_movk_i32 s81, 0xee00
	s_movk_i32 s80, 0x13ff
	s_movk_i32 s77, 0xf200
	s_movk_i32 s76, 0x7ff
	s_movk_i32 s73, 0xf000
	s_movk_i32 s72, 0x1ff
	s_movk_i32 s75, 0xfff
	s_movk_i32 s74, 0x1fff
	s_movk_i32 s78, 0xf400
	s_movk_i32 s79, 0x11ff
	s_movk_i32 s69, 0xec00
	s_addc_u32 s97, s0, s1
	s_mov_b64 s[14:15], -1
	v_readlane_b32 s84, v252, 34
	v_readlane_b32 s85, v252, 35
	v_readlane_b32 s86, v252, 36
	v_readlane_b32 s87, v252, 37
	s_branch .LBB0_538

.LBB0_538:
	s_lshl_b32 s0, s16, 11
	s_add_u32 s0, s24, s0
	s_addc_u32 s1, s59, 0
	global_load_dword v221, v145, s[0:1]
	s_lshl_b32 s4, s16, 9
	s_add_i32 s4, s4, 0x200
	s_add_i32 s0, s4, s68
	s_ashr_i32 s1, s0, 31
	s_lshl_b32 s6, s4, 2
	s_add_u32 s4, s90, s6
	s_addc_u32 s5, s91, 0
	s_lshl_b64 s[0:1], s[0:1], 14
	v_mov_b32_e32 v163, s6
	s_add_u32 s8, s26, s0
	s_addc_u32 s9, s27, s1
	s_add_u32 s10, s30, s0
	s_addc_u32 s11, s31, s1
	v_lshlrev_b32_e32 v232, 1, v146
	v_min_i32_e32 v233, 0x1ffe, v146
	v_max_i32_e32 v234, 1, v146
	global_load_dword v222, v163, s[90:91]
	global_load_dword v223, v153, s[4:5] offset:2048
	global_load_dword v224, v154, s[4:5]
	global_load_dword v225, v163, s[94:95]
	v_lshlrev_b32_e32 v233, 1, v233
	v_lshlrev_b32_e32 v234, 1, v234
	global_load_ushort v226, v232, s[8:9]
	global_load_ushort v227, v233, s[8:9] offset:2
	global_load_ushort v228, v234, s[8:9] offset:-2
	global_load_ushort v229, v232, s[10:11]
	global_load_ushort v230, v233, s[10:11] offset:2
	global_load_ushort v231, v234, s[10:11] offset:-2
	s_lshl_b32 s98, s16, 16
	s_mov_b32 s99, 0
	v_lshl_add_u64 v[196:197], s[98:99], 0, v[28:29]
	global_load_dwordx4 v[164:167], v[196:197], off offset:-4096
	global_load_dwordx4 v[168:171], v[196:197], off offset:-3072
	global_load_dwordx4 v[172:175], v[196:197], off offset:-2048
	global_load_dwordx4 v[176:179], v[196:197], off offset:-1024
	global_load_dwordx4 v[180:183], v[196:197], off
	global_load_dwordx4 v[184:187], v[196:197], off offset:1024
	global_load_dwordx4 v[188:191], v[196:197], off offset:2048
	global_load_dwordx4 v[192:195], v[196:197], off offset:3072
	v_mov_b32_e32 v20, v46
	v_mov_b32_e32 v21, v48
	v_mov_b32_e32 v22, v51
	v_mov_b32_e32 v23, v53
	v_pk_add_f32 v[88:89], v[20:21], 0 op_sel_hi:[1,0]
	v_pk_mul_f32 v[20:21], v[20:21], s[58:59] op_sel_hi:[1,0]
	v_xor_b32_e32 v91, 0x80000000, v46
	v_mov_b32_e32 v90, v48
	v_pk_add_f32 v[92:93], v[50:51], 0 neg_lo:[1,1] neg_hi:[1,1]
	v_mov_b32_e32 v24, v50
	v_mov_b32_e32 v25, v52
	v_pk_fma_f32 v[20:21], v[90:91], s[46:47], v[20:21] op_sel_hi:[1,0,1] neg_lo:[0,0,1] neg_hi:[0,0,1]
	v_pk_add_f32 v[90:91], v[22:23], 0 op_sel_hi:[1,0]
	v_pk_mul_f32 v[22:23], v[22:23], s[62:63] op_sel_hi:[1,0]
	v_mov_b32_e32 v92, v53
	v_mov_b32_e32 v26, v55
	v_mov_b32_e32 v27, v57
	v_pk_fma_f32 v[22:23], v[92:93], s[60:61], v[22:23] op_sel_hi:[1,0,1] neg_lo:[0,0,1] neg_hi:[0,0,1]
	v_pk_add_f32 v[92:93], v[24:25], 0 op_sel_hi:[1,0]
	v_pk_mul_f32 v[24:25], v[24:25], s[66:67] op_sel_hi:[1,0]
	v_xor_b32_e32 v95, 0x80000000, v50
	v_mov_b32_e32 v94, v52
	v_pk_add_f32 v[96:97], v[54:55], 0 neg_lo:[1,1] neg_hi:[1,1]
	v_mov_b32_e32 v64, v54
	v_mov_b32_e32 v65, v56
	v_pk_fma_f32 v[24:25], v[94:95], s[64:65], v[24:25] op_sel_hi:[1,0,1] neg_lo:[0,0,1] neg_hi:[0,0,1]
	v_pk_add_f32 v[94:95], v[26:27], 0 op_sel_hi:[1,0]
	v_pk_mul_f32 v[26:27], v[26:27], s[70:71] op_sel_hi:[1,0]
	v_mov_b32_e32 v96, v57
	v_mov_b32_e32 v66, v59
	v_mov_b32_e32 v67, v61
	v_pk_fma_f32 v[26:27], v[96:97], s[70:71], v[26:27] op_sel_hi:[1,0,1] neg_lo:[0,0,1] neg_hi:[0,0,1]
	v_pk_add_f32 v[96:97], v[64:65], 0 op_sel_hi:[1,0]
	v_pk_mul_f32 v[64:65], v[64:65], s[64:65] op_sel_hi:[1,0]
	v_xor_b32_e32 v99, 0x80000000, v54
	v_mov_b32_e32 v98, v56
	v_pk_add_f32 v[100:101], v[58:59], 0 neg_lo:[1,1] neg_hi:[1,1]
	v_mov_b32_e32 v2, v32
	v_mov_b32_e32 v3, v34
	v_mov_b32_e32 v4, v33
	v_mov_b32_e32 v5, v35
	v_mov_b32_e32 v18, v47
	v_mov_b32_e32 v19, v49
	v_mov_b32_e32 v68, v58
	v_mov_b32_e32 v69, v60
	v_pk_fma_f32 v[64:65], v[98:99], s[66:67], v[64:65] op_sel_hi:[1,0,1] neg_lo:[0,0,1] neg_hi:[0,0,1]
	v_pk_add_f32 v[98:99], v[66:67], 0 op_sel_hi:[1,0]
	v_pk_mul_f32 v[66:67], v[66:67], s[60:61] op_sel_hi:[1,0]
	v_mov_b32_e32 v100, v61
	v_pk_add_f32 v[70:71], v[2:3], 0 op_sel_hi:[1,0]
	v_pk_add_f32 v[72:73], v[4:5], 0 op_sel_hi:[1,0]
	v_pk_add_f32 v[74:75], v[32:33], 0 neg_lo:[1,1] neg_hi:[1,1]
	v_pk_add_f32 v[18:19], v[18:19], 0 op_sel_hi:[1,0]
	v_pk_fma_f32 v[66:67], v[100:101], s[62:63], v[66:67] op_sel_hi:[1,0,1] neg_lo:[0,0,1] neg_hi:[0,0,1]
	v_pk_add_f32 v[100:101], v[68:69], 0 op_sel_hi:[1,0]
	v_pk_mul_f32 v[68:69], v[68:69], s[46:47] op_sel_hi:[1,0]
	v_xor_b32_e32 v103, 0x80000000, v58
	v_mov_b32_e32 v102, v60
	v_mov_b32_e32 v74, v35
	v_pk_fma_f32 v[68:69], v[102:103], s[58:59], v[68:69] op_sel_hi:[1,0,1] neg_lo:[0,0,1] neg_hi:[0,0,1]
	v_pk_add_f32 v[102:103], v[18:19], v[70:71]
	v_pk_add_f32 v[18:19], v[70:71], v[18:19] neg_lo:[0,1] neg_hi:[0,1]
	v_pk_add_f32 v[70:71], v[88:89], v[72:73]
	v_pk_add_f32 v[72:73], v[72:73], v[88:89] neg_lo:[0,1] neg_hi:[0,1]
	v_mov_b32_e32 v6, v37
	v_mov_b32_e32 v7, v31
	v_pk_mul_f32 v[74:75], v[74:75], s[58:59] op_sel_hi:[1,0]
	v_pk_fma_f32 v[4:5], v[4:5], s[46:47], v[74:75] op_sel_hi:[1,0,1]
	v_pk_add_f32 v[74:75], v[6:7], 0 op_sel_hi:[1,0]
	v_pk_add_f32 v[76:77], v[36:37], 0 neg_lo:[1,1] neg_hi:[1,1]
	v_pk_mul_f32 v[88:89], v[72:73], s[62:63] op_sel:[1,0] op_sel_hi:[0,0] neg_hi:[1,0]
	v_mov_b32_e32 v76, v31
	v_pk_fma_f32 v[72:73], v[72:73], s[60:61], v[88:89] op_sel_hi:[1,0,1]
	v_pk_add_f32 v[88:89], v[90:91], v[74:75]
	v_pk_add_f32 v[74:75], v[74:75], v[90:91] neg_lo:[0,1] neg_hi:[0,1]
	v_mov_b32_e32 v8, v36
	v_mov_b32_e32 v9, v30
	v_pk_mul_f32 v[76:77], v[76:77], s[62:63] op_sel_hi:[1,0]
	v_pk_fma_f32 v[6:7], v[6:7], s[60:61], v[76:77] op_sel_hi:[1,0,1]
	v_pk_add_f32 v[76:77], v[8:9], 0 op_sel_hi:[1,0]
	v_pk_mul_f32 v[90:91], v[74:75], s[70:71] op_sel:[1,0] op_sel_hi:[0,0] neg_hi:[1,0]
	v_xor_b32_e32 v79, 0x80000000, v36
	v_mov_b32_e32 v78, v30
	v_pk_add_f32 v[80:81], v[38:39], 0 neg_lo:[1,1] neg_hi:[1,1]
	v_pk_fma_f32 v[74:75], v[74:75], s[70:71], v[90:91] op_sel_hi:[1,0,1]
	v_pk_add_f32 v[90:91], v[92:93], v[76:77]
	v_pk_add_f32 v[76:77], v[76:77], v[92:93] neg_lo:[0,1] neg_hi:[0,1]
	v_mov_b32_e32 v10, v39
	v_mov_b32_e32 v11, v41
	v_pk_mul_f32 v[78:79], v[78:79], s[66:67] op_sel_hi:[1,0]
	v_mov_b32_e32 v80, v41
	v_mov_b32_e32 v12, v38
	v_mov_b32_e32 v13, v40
	v_pk_fma_f32 v[8:9], v[8:9], s[64:65], v[78:79] op_sel_hi:[1,0,1]
	v_pk_add_f32 v[78:79], v[10:11], 0 op_sel_hi:[1,0]
	v_pk_mul_f32 v[80:81], v[80:81], s[70:71] op_sel_hi:[1,0]
	v_pk_mul_f32 v[92:93], v[76:77], s[60:61] op_sel:[1,0] op_sel_hi:[0,0] neg_hi:[1,0]
	v_pk_fma_f32 v[10:11], v[10:11], s[70:71], v[80:81] op_sel_hi:[1,0,1]
	v_pk_add_f32 v[80:81], v[12:13], 0 op_sel_hi:[1,0]
	v_xor_b32_e32 v83, 0x80000000, v38
	v_mov_b32_e32 v82, v40
	v_pk_fma_f32 v[76:77], v[76:77], s[62:63], v[92:93] op_sel_hi:[1,0,1]
	v_pk_add_f32 v[92:93], v[94:95], v[78:79]
	v_pk_add_f32 v[78:79], v[78:79], v[94:95] neg_lo:[0,1] neg_hi:[0,1]
	v_mov_b32_e32 v14, v43
	v_mov_b32_e32 v15, v45
	v_pk_mul_f32 v[82:83], v[82:83], s[64:65] op_sel_hi:[1,0]
	v_pk_add_f32 v[84:85], v[42:43], 0 neg_lo:[1,1] neg_hi:[1,1]
	v_xor_b32_e32 v95, 0x80000000, v78
	v_mov_b32_e32 v94, v79
	v_pk_add_f32 v[78:79], v[96:97], v[80:81]
	v_pk_add_f32 v[80:81], v[80:81], v[96:97] neg_lo:[0,1] neg_hi:[0,1]
	v_pk_fma_f32 v[12:13], v[12:13], s[66:67], v[82:83] op_sel_hi:[1,0,1]
	v_pk_add_f32 v[82:83], v[14:15], 0 op_sel_hi:[1,0]
	v_mov_b32_e32 v84, v45
	v_pk_mul_f32 v[96:97], v[80:81], s[62:63] op_sel_hi:[1,0]
	v_xor_b32_e32 v105, 0x80000000, v80
	v_mov_b32_e32 v104, v81
	v_mov_b32_e32 v16, v42
	v_mov_b32_e32 v17, v44
	v_pk_mul_f32 v[84:85], v[84:85], s[60:61] op_sel_hi:[1,0]
	v_xor_b32_e32 v87, 0x80000000, v42
	v_mov_b32_e32 v86, v44
	v_pk_fma_f32 v[80:81], v[104:105], s[60:61], v[96:97] op_sel_hi:[1,0,1] neg_lo:[0,0,1] neg_hi:[0,0,1]
	v_pk_add_f32 v[96:97], v[98:99], v[82:83]
	v_pk_add_f32 v[82:83], v[82:83], v[98:99] neg_lo:[0,1] neg_hi:[0,1]
	v_pk_fma_f32 v[14:15], v[14:15], s[62:63], v[84:85] op_sel_hi:[1,0,1]
	v_pk_add_f32 v[84:85], v[16:17], 0 op_sel_hi:[1,0]
	v_pk_mul_f32 v[86:87], v[86:87], s[46:47] op_sel_hi:[1,0]
	v_pk_mul_f32 v[98:99], v[82:83], s[70:71] op_sel_hi:[1,0]
	v_xor_b32_e32 v105, 0x80000000, v82
	v_mov_b32_e32 v104, v83
	v_pk_fma_f32 v[16:17], v[16:17], s[58:59], v[86:87] op_sel_hi:[1,0,1]
	v_pk_add_f32 v[86:87], v[46:47], 0 neg_lo:[1,1] neg_hi:[1,1]
	v_pk_fma_f32 v[82:83], v[104:105], s[70:71], v[98:99] op_sel_hi:[1,0,1] neg_lo:[0,0,1] neg_hi:[0,0,1]
	v_pk_add_f32 v[98:99], v[100:101], v[84:85]
	v_pk_add_f32 v[84:85], v[84:85], v[100:101] neg_lo:[0,1] neg_hi:[0,1]
	v_mov_b32_e32 v86, v49
	v_pk_mul_f32 v[100:101], v[84:85], s[60:61] op_sel_hi:[1,0]
	v_xor_b32_e32 v105, 0x80000000, v84
	v_mov_b32_e32 v104, v85
	v_pk_fma_f32 v[84:85], v[104:105], s[62:63], v[100:101] op_sel_hi:[1,0,1] neg_lo:[0,0,1] neg_hi:[0,0,1]
	v_pk_add_f32 v[100:101], v[86:87], v[2:3]
	v_pk_add_f32 v[2:3], v[2:3], v[86:87] neg_lo:[0,1] neg_hi:[0,1]
	v_pk_add_f32 v[86:87], v[20:21], v[4:5]
	v_pk_add_f32 v[4:5], v[4:5], v[20:21] neg_lo:[0,1] neg_hi:[0,1]
	v_mov_b32_e32 v63, v146
	v_pk_mul_f32 v[20:21], v[4:5], s[62:63] op_sel:[1,0] op_sel_hi:[0,0] neg_hi:[1,0]
	v_pk_fma_f32 v[4:5], v[4:5], s[60:61], v[20:21] op_sel_hi:[1,0,1]
	v_pk_add_f32 v[20:21], v[22:23], v[6:7]
	v_pk_add_f32 v[6:7], v[6:7], v[22:23] neg_lo:[0,1] neg_hi:[0,1]
	s_barrier
	v_pk_mul_f32 v[22:23], v[6:7], s[70:71] op_sel:[1,0] op_sel_hi:[0,0] neg_hi:[1,0]
	s_nop 0
	v_pk_fma_f32 v[6:7], v[6:7], s[70:71], v[22:23] op_sel_hi:[1,0,1]
	v_pk_add_f32 v[22:23], v[24:25], v[8:9]
	v_pk_add_f32 v[8:9], v[8:9], v[24:25] neg_lo:[0,1] neg_hi:[0,1]
	s_add_i32 s19, 16, 0x11000
	v_pk_mul_f32 v[24:25], v[8:9], s[60:61] op_sel:[1,0] op_sel_hi:[0,0] neg_hi:[1,0]
	s_add_i32 s18, 16, 0x12000
	v_pk_fma_f32 v[8:9], v[8:9], s[62:63], v[24:25] op_sel_hi:[1,0,1]
	v_pk_add_f32 v[24:25], v[26:27], v[10:11]
	v_pk_add_f32 v[10:11], v[10:11], v[26:27] neg_lo:[0,1] neg_hi:[0,1]
	s_add_i32 s17, 16, 0x13000
	v_xor_b32_e32 v27, 0x80000000, v10
	v_mov_b32_e32 v26, v11
	v_pk_add_f32 v[10:11], v[64:65], v[12:13]
	v_pk_add_f32 v[12:13], v[12:13], v[64:65] neg_lo:[0,1] neg_hi:[0,1]
	s_add_i32 s13, 16, 0x14000
	v_pk_mul_f32 v[64:65], v[12:13], s[62:63] op_sel_hi:[1,0]
	v_xor_b32_e32 v105, 0x80000000, v12
	v_mov_b32_e32 v104, v13
	v_pk_fma_f32 v[12:13], v[104:105], s[60:61], v[64:65] op_sel_hi:[1,0,1] neg_lo:[0,0,1] neg_hi:[0,0,1]
	v_pk_add_f32 v[64:65], v[66:67], v[14:15]
	v_pk_add_f32 v[14:15], v[14:15], v[66:67] neg_lo:[0,1] neg_hi:[0,1]
	s_add_i32 s12, 16, 0x15000
	v_pk_mul_f32 v[66:67], v[14:15], s[70:71] op_sel_hi:[1,0]
	v_xor_b32_e32 v105, 0x80000000, v14
	v_mov_b32_e32 v104, v15
	v_pk_fma_f32 v[14:15], v[104:105], s[70:71], v[66:67] op_sel_hi:[1,0,1] neg_lo:[0,0,1] neg_hi:[0,0,1]
	v_pk_add_f32 v[66:67], v[68:69], v[16:17]
	v_pk_add_f32 v[16:17], v[16:17], v[68:69] neg_lo:[0,1] neg_hi:[0,1]
	s_add_i32 s11, 16, 0x16000
	v_pk_mul_f32 v[68:69], v[16:17], s[60:61] op_sel_hi:[1,0]
	v_xor_b32_e32 v105, 0x80000000, v16
	v_mov_b32_e32 v104, v17
	v_pk_fma_f32 v[16:17], v[104:105], s[62:63], v[68:69] op_sel_hi:[1,0,1] neg_lo:[0,0,1] neg_hi:[0,0,1]
	v_pk_add_f32 v[68:69], v[92:93], v[102:103]
	v_pk_add_f32 v[92:93], v[102:103], v[92:93] neg_lo:[0,1] neg_hi:[0,1]
	v_pk_add_f32 v[102:103], v[78:79], v[70:71]
	v_pk_add_f32 v[70:71], v[70:71], v[78:79] neg_lo:[0,1] neg_hi:[0,1]
	s_add_i32 s10, 16, 0x17000
	v_pk_mul_f32 v[78:79], v[70:71], s[70:71] op_sel:[1,0] op_sel_hi:[0,0] neg_hi:[1,0]
	s_add_i32 s9, 16, 0x18000
	v_pk_fma_f32 v[70:71], v[70:71], s[70:71], v[78:79] op_sel_hi:[1,0,1]
	v_pk_add_f32 v[78:79], v[96:97], v[88:89]
	v_pk_add_f32 v[88:89], v[88:89], v[96:97] neg_lo:[0,1] neg_hi:[0,1]
	s_add_i32 s8, 16, 0x19000
	v_xor_b32_e32 v97, 0x80000000, v88
	v_mov_b32_e32 v96, v89
	v_pk_add_f32 v[88:89], v[98:99], v[90:91]
	v_pk_add_f32 v[90:91], v[90:91], v[98:99] neg_lo:[0,1] neg_hi:[0,1]
	s_add_i32 s7, 16, 0x1a000
	v_pk_mul_f32 v[98:99], v[90:91], s[70:71] op_sel_hi:[1,0]
	v_xor_b32_e32 v105, 0x80000000, v90
	v_mov_b32_e32 v104, v91
	v_pk_fma_f32 v[90:91], v[104:105], s[70:71], v[98:99] op_sel_hi:[1,0,1] neg_lo:[0,0,1] neg_hi:[0,0,1]
	v_pk_add_f32 v[98:99], v[94:95], v[18:19]
	v_pk_add_f32 v[18:19], v[18:19], v[94:95] neg_lo:[0,1] neg_hi:[0,1]
	v_pk_add_f32 v[94:95], v[80:81], v[72:73]
	v_pk_add_f32 v[72:73], v[72:73], v[80:81] neg_lo:[0,1] neg_hi:[0,1]
	s_add_i32 s6, 16, 0x1b000
	v_pk_mul_f32 v[80:81], v[72:73], s[70:71] op_sel:[1,0] op_sel_hi:[0,0] neg_hi:[1,0]
	s_add_i32 s5, 16, 0x1c000
	v_pk_fma_f32 v[72:73], v[72:73], s[70:71], v[80:81] op_sel_hi:[1,0,1]
	v_pk_add_f32 v[80:81], v[82:83], v[74:75]
	v_pk_add_f32 v[74:75], v[74:75], v[82:83] neg_lo:[0,1] neg_hi:[0,1]
	s_add_i32 s4, 16, 0x1d000
	v_xor_b32_e32 v83, 0x80000000, v74
	v_mov_b32_e32 v82, v75
	v_pk_add_f32 v[74:75], v[84:85], v[76:77]
	v_pk_add_f32 v[76:77], v[76:77], v[84:85] neg_lo:[0,1] neg_hi:[0,1]
	v_pk_add_f32 v[106:107], v[18:19], v[82:83]
	v_pk_mul_f32 v[84:85], v[76:77], s[70:71] op_sel_hi:[1,0]
	v_xor_b32_e32 v105, 0x80000000, v76
	v_mov_b32_e32 v104, v77
	v_pk_fma_f32 v[76:77], v[104:105], s[70:71], v[84:85] op_sel_hi:[1,0,1] neg_lo:[0,0,1] neg_hi:[0,0,1]
	v_pk_add_f32 v[84:85], v[24:25], v[100:101]
	v_pk_add_f32 v[24:25], v[100:101], v[24:25] neg_lo:[0,1] neg_hi:[0,1]
	v_pk_add_f32 v[100:101], v[10:11], v[86:87]
	v_pk_add_f32 v[10:11], v[86:87], v[10:11] neg_lo:[0,1] neg_hi:[0,1]
	v_pk_add_f32 v[18:19], v[18:19], v[82:83] neg_lo:[0,1] neg_hi:[0,1]
	v_pk_mul_f32 v[86:87], v[10:11], s[70:71] op_sel:[1,0] op_sel_hi:[0,0] neg_hi:[1,0]
	v_pk_add_f32 v[82:83], v[76:77], v[72:73]
	v_pk_fma_f32 v[10:11], v[10:11], s[70:71], v[86:87] op_sel_hi:[1,0,1]
	v_pk_add_f32 v[86:87], v[64:65], v[20:21]
	v_pk_add_f32 v[20:21], v[20:21], v[64:65] neg_lo:[0,1] neg_hi:[0,1]
	v_pk_add_f32 v[72:73], v[72:73], v[76:77] neg_lo:[0,1] neg_hi:[0,1]
	v_xor_b32_e32 v65, 0x80000000, v20
	v_mov_b32_e32 v64, v21
	v_pk_add_f32 v[20:21], v[66:67], v[22:23]
	v_pk_add_f32 v[22:23], v[22:23], v[66:67] neg_lo:[0,1] neg_hi:[0,1]
	v_xor_b32_e32 v77, 0x80000000, v72
	v_pk_mul_f32 v[66:67], v[22:23], s[70:71] op_sel_hi:[1,0]
	v_xor_b32_e32 v105, 0x80000000, v22
	v_mov_b32_e32 v104, v23
	v_pk_fma_f32 v[22:23], v[104:105], s[70:71], v[66:67] op_sel_hi:[1,0,1] neg_lo:[0,0,1] neg_hi:[0,0,1]
	v_pk_add_f32 v[66:67], v[2:3], v[26:27]
	v_pk_add_f32 v[2:3], v[2:3], v[26:27] neg_lo:[0,1] neg_hi:[0,1]
	v_pk_add_f32 v[26:27], v[12:13], v[4:5]
	v_pk_add_f32 v[4:5], v[4:5], v[12:13] neg_lo:[0,1] neg_hi:[0,1]
	v_mov_b32_e32 v76, v73
	v_pk_mul_f32 v[12:13], v[4:5], s[70:71] op_sel:[1,0] op_sel_hi:[0,0] neg_hi:[1,0]
	v_pk_add_f32 v[72:73], v[84:85], v[86:87]
	v_pk_fma_f32 v[4:5], v[4:5], s[70:71], v[12:13] op_sel_hi:[1,0,1]
	v_pk_add_f32 v[12:13], v[14:15], v[6:7]
	v_pk_add_f32 v[6:7], v[6:7], v[14:15] neg_lo:[0,1] neg_hi:[0,1]
	v_pk_add_f32 v[84:85], v[84:85], v[86:87] neg_lo:[0,1] neg_hi:[0,1]
	v_xor_b32_e32 v15, 0x80000000, v6
	v_mov_b32_e32 v14, v7
	v_pk_add_f32 v[6:7], v[16:17], v[8:9]
	v_pk_add_f32 v[8:9], v[8:9], v[16:17] neg_lo:[0,1] neg_hi:[0,1]
	v_pk_add_f32 v[86:87], v[20:21], v[100:101]
	v_pk_mul_f32 v[16:17], v[8:9], s[70:71] op_sel_hi:[1,0]
	v_pk_fma_f32 v[8:9], v[8:9], s[70:71], v[16:17] op_sel:[1,0,0] op_sel_hi:[0,0,1] neg_lo:[0,0,1] neg_hi:[1,0,1]
	v_pk_add_f32 v[104:105], v[92:93], v[96:97]
	v_pk_add_f32 v[92:93], v[92:93], v[96:97] neg_lo:[0,1] neg_hi:[0,1]
	v_pk_add_f32 v[96:97], v[90:91], v[70:71]
	v_pk_add_f32 v[70:71], v[70:71], v[90:91] neg_lo:[0,1] neg_hi:[0,1]
	v_pk_add_f32 v[16:17], v[78:79], v[68:69]
	v_pk_add_f32 v[68:69], v[68:69], v[78:79] neg_lo:[0,1] neg_hi:[0,1]
	v_pk_add_f32 v[78:79], v[88:89], v[102:103]
	v_pk_add_f32 v[88:89], v[102:103], v[88:89] neg_lo:[0,1] neg_hi:[0,1]
	v_xor_b32_e32 v91, 0x80000000, v70
	v_mov_b32_e32 v90, v71
	v_pk_add_f32 v[70:71], v[98:99], v[80:81]
	v_pk_add_f32 v[98:99], v[98:99], v[80:81] neg_lo:[0,1] neg_hi:[0,1]
	v_pk_add_f32 v[80:81], v[74:75], v[94:95]
	v_pk_add_f32 v[74:75], v[94:95], v[74:75] neg_lo:[0,1] neg_hi:[0,1]
	v_pk_add_f32 v[20:21], v[100:101], v[20:21] neg_lo:[0,1] neg_hi:[0,1]
	v_pk_add_f32 v[108:109], v[24:25], v[64:65]
	v_pk_add_f32 v[24:25], v[24:25], v[64:65] neg_lo:[0,1] neg_hi:[0,1]
	v_pk_add_f32 v[64:65], v[22:23], v[10:11]
	v_pk_add_f32 v[10:11], v[10:11], v[22:23] neg_lo:[0,1] neg_hi:[0,1]
	v_pk_add_f32 v[114:115], v[6:7], v[26:27]
	v_pk_add_f32 v[6:7], v[26:27], v[6:7] neg_lo:[0,1] neg_hi:[0,1]
	v_xor_b32_e32 v103, 0x80000000, v88
	v_mov_b32_e32 v102, v89
	v_xor_b32_e32 v95, 0x80000000, v74
	v_mov_b32_e32 v94, v75
	v_xor_b32_e32 v101, 0x80000000, v20
	v_mov_b32_e32 v100, v21
	v_xor_b32_e32 v27, 0x80000000, v6
	v_mov_b32_e32 v26, v7
	v_pk_add_f32 v[6:7], v[2:3], v[14:15]
	v_pk_add_f32 v[116:117], v[2:3], v[14:15] neg_lo:[0,1] neg_hi:[0,1]
	v_pk_add_f32 v[2:3], v[4:5], v[8:9] neg_lo:[0,1] neg_hi:[0,1]
	v_pk_add_f32 v[112:113], v[66:67], v[12:13]
	v_pk_add_f32 v[66:67], v[66:67], v[12:13] neg_lo:[0,1] neg_hi:[0,1]
	v_pk_add_f32 v[118:119], v[8:9], v[4:5]
	v_xor_b32_e32 v121, 0x80000000, v2
	v_mov_b32_e32 v120, v3
	v_pk_add_f32 v[2:3], v[78:79], v[16:17]
	v_pk_add_f32 v[88:89], v[16:17], v[78:79] neg_lo:[0,1] neg_hi:[0,1]
	v_pk_add_f32 v[122:123], v[68:69], v[102:103]
	v_pk_add_f32 v[20:21], v[68:69], v[102:103] neg_lo:[0,1] neg_hi:[0,1]
	v_pk_add_f32 v[78:79], v[104:105], v[96:97]
	v_pk_add_f32 v[74:75], v[104:105], v[96:97] neg_lo:[0,1] neg_hi:[0,1]
	v_pk_add_f32 v[96:97], v[92:93], v[90:91]
	v_pk_add_f32 v[8:9], v[92:93], v[90:91] neg_lo:[0,1] neg_hi:[0,1]
	v_pk_add_f32 v[102:103], v[98:99], v[94:95]
	v_pk_add_f32 v[12:13], v[98:99], v[94:95] neg_lo:[0,1] neg_hi:[0,1]
	v_pk_add_f32 v[98:99], v[18:19], v[76:77]
	v_pk_add_f32 v[4:5], v[18:19], v[76:77] neg_lo:[0,1] neg_hi:[0,1]
	v_pk_add_f32 v[18:19], v[72:73], v[86:87]
	v_pk_add_f32 v[92:93], v[72:73], v[86:87] neg_lo:[0,1] neg_hi:[0,1]
	v_pk_add_f32 v[86:87], v[84:85], v[100:101]
	v_pk_add_f32 v[22:23], v[84:85], v[100:101] neg_lo:[0,1] neg_hi:[0,1]
	v_pk_add_f32 v[100:101], v[24:25], v[10:11] op_sel:[0,1] op_sel_hi:[1,0] neg_hi:[0,1]
	v_pk_add_f32 v[10:11], v[24:25], v[10:11] op_sel:[0,1] op_sel_hi:[1,0] neg_lo:[0,1]
	v_mov_b32_e32 v24, v63
	v_pk_add_f32 v[84:85], v[108:109], v[64:65]
	v_cvt_f32_i32_e32 v24, v24
	v_pk_add_f32 v[76:77], v[108:109], v[64:65] neg_lo:[0,1] neg_hi:[0,1]
	v_pk_add_f32 v[104:105], v[66:67], v[26:27]
	v_pk_add_f32 v[14:15], v[66:67], v[26:27] neg_lo:[0,1] neg_hi:[0,1]
	v_mul_f32_e32 v25, 0x38800000, v24
	v_cos_f32_e32 v24, v25
	v_sin_f32_e32 v25, v25
	s_nop 0
	s_nop 0
	v_add_f32_e32 v62, v24, v24
	v_pk_mul_f32 v[26:27], v[24:25], v[24:25]
	v_mul_f32_e32 v62, v25, v62
	v_mov_b32_e32 v108, v25
	v_pk_add_f32 v[26:27], v[26:27], v[26:27] op_sel:[0,1] op_sel_hi:[0,1] neg_lo:[0,1] neg_hi:[0,1]
	v_pk_mul_f32 v[72:73], v[24:25], v[62:63] op_sel:[1,0] op_sel_hi:[0,0] neg_lo:[1,0]
	v_pk_mul_f32 v[94:95], v[18:19], v[108:109] op_sel:[1,0] op_sel_hi:[0,0] neg_hi:[1,0]
	v_pk_add_f32 v[16:17], v[70:71], v[80:81]
	v_pk_fma_f32 v[72:73], v[24:25], v[26:27], v[72:73]
	v_pk_fma_f32 v[18:19], v[18:19], v[24:25], v[94:95] op_sel_hi:[1,0,1]
	v_pk_mul_f32 v[24:25], v[62:63], s[48:49] op_sel_hi:[0,1]
	v_pk_fma_f32 v[94:95], v[26:27], s[40:41], v[24:25]
	v_pk_mul_f32 v[24:25], v[16:17], v[94:95] op_sel:[1,1] op_sel_hi:[0,1] neg_hi:[1,0]
	v_pk_add_f32 v[64:65], v[112:113], v[114:115]
	v_pk_fma_f32 v[24:25], v[16:17], v[94:95], v[24:25] op_sel_hi:[1,0,1]
	v_pk_mul_f32 v[16:17], v[62:63], v[72:73] op_sel:[0,1] op_sel_hi:[0,0] neg_lo:[0,1]
	v_pk_fma_f32 v[108:109], v[26:27], v[72:73], v[16:17]
	v_pk_mul_f32 v[16:17], v[64:65], v[72:73] op_sel:[1,1] op_sel_hi:[0,1] neg_hi:[1,0]
	v_pk_add_f32 v[90:91], v[106:107], v[82:83]
	v_pk_fma_f32 v[16:17], v[64:65], v[72:73], v[16:17] op_sel_hi:[1,0,1]
	v_pk_mul_f32 v[64:65], v[62:63], v[94:95] op_sel:[0,1] op_sel_hi:[0,0] neg_lo:[0,1]
	v_pk_fma_f32 v[94:95], v[26:27], v[94:95], v[64:65]
	v_pk_mul_f32 v[64:65], v[78:79], v[94:95] op_sel:[1,1] op_sel_hi:[0,1] neg_hi:[1,0]
	v_pk_add_f32 v[66:67], v[6:7], v[118:119]
	v_pk_fma_f32 v[72:73], v[78:79], v[94:95], v[64:65] op_sel_hi:[1,0,1]
	v_pk_mul_f32 v[64:65], v[62:63], v[108:109] op_sel:[0,1] op_sel_hi:[0,0] neg_lo:[0,1]
	v_pk_fma_f32 v[110:111], v[26:27], v[108:109], v[64:65]
	v_pk_mul_f32 v[64:65], v[84:85], v[108:109] op_sel:[1,1] op_sel_hi:[0,1] neg_hi:[1,0]
	v_pk_mul_f32 v[78:79], v[62:63], v[94:95] op_sel:[0,1] op_sel_hi:[0,0] neg_lo:[0,1]
	v_pk_fma_f32 v[64:65], v[84:85], v[108:109], v[64:65] op_sel_hi:[1,0,1]
	v_pk_fma_f32 v[84:85], v[26:27], v[94:95], v[78:79]
	v_pk_mul_f32 v[78:79], v[90:91], v[84:85] op_sel:[1,1] op_sel_hi:[0,1] neg_hi:[1,0]
	v_pk_add_f32 v[68:69], v[106:107], v[82:83] neg_lo:[0,1] neg_hi:[0,1]
	v_pk_fma_f32 v[78:79], v[90:91], v[84:85], v[78:79] op_sel_hi:[1,0,1]
	v_pk_mul_f32 v[90:91], v[62:63], v[110:111] op_sel:[0,1] op_sel_hi:[0,0] neg_lo:[0,1]
	v_pk_fma_f32 v[94:95], v[26:27], v[110:111], v[90:91]
	v_pk_mul_f32 v[90:91], v[66:67], v[110:111] op_sel:[1,1] op_sel_hi:[0,1] neg_hi:[1,0]
	v_pk_add_f32 v[106:107], v[116:117], v[120:121]
	v_pk_fma_f32 v[66:67], v[66:67], v[110:111], v[90:91] op_sel_hi:[1,0,1]
	v_pk_mul_f32 v[90:91], v[62:63], v[84:85] op_sel:[0,1] op_sel_hi:[0,0] neg_lo:[0,1]
	v_pk_fma_f32 v[108:109], v[26:27], v[84:85], v[90:91]
	v_pk_mul_f32 v[84:85], v[122:123], v[108:109] op_sel:[1,1] op_sel_hi:[0,1] neg_hi:[1,0]
	v_pk_add_f32 v[80:81], v[70:71], v[80:81] neg_lo:[0,1] neg_hi:[0,1]
	v_pk_fma_f32 v[90:91], v[122:123], v[108:109], v[84:85] op_sel_hi:[1,0,1]
	v_pk_mul_f32 v[84:85], v[62:63], v[94:95] op_sel:[0,1] op_sel_hi:[0,0] neg_lo:[0,1]
	v_pk_fma_f32 v[110:111], v[26:27], v[94:95], v[84:85]
	v_pk_mul_f32 v[84:85], v[86:87], v[94:95] op_sel:[1,1] op_sel_hi:[0,1] neg_hi:[1,0]
	v_pk_add_f32 v[82:83], v[112:113], v[114:115] neg_lo:[0,1] neg_hi:[0,1]
	v_pk_fma_f32 v[84:85], v[86:87], v[94:95], v[84:85] op_sel_hi:[1,0,1]
	v_pk_mul_f32 v[86:87], v[62:63], v[108:109] op_sel:[0,1] op_sel_hi:[0,0] neg_lo:[0,1]
	v_pk_fma_f32 v[108:109], v[26:27], v[108:109], v[86:87]
	v_pk_mul_f32 v[86:87], v[102:103], v[108:109] op_sel:[1,1] op_sel_hi:[0,1] neg_hi:[1,0]
	v_pk_add_f32 v[70:71], v[6:7], v[118:119] neg_lo:[0,1] neg_hi:[0,1]
	v_pk_fma_f32 v[94:95], v[102:103], v[108:109], v[86:87] op_sel_hi:[1,0,1]
	v_pk_mul_f32 v[86:87], v[62:63], v[110:111] op_sel:[0,1] op_sel_hi:[0,0] neg_lo:[0,1]
	v_pk_fma_f32 v[102:103], v[26:27], v[110:111], v[86:87]
	v_pk_mul_f32 v[86:87], v[104:105], v[110:111] op_sel:[1,1] op_sel_hi:[0,1] neg_hi:[1,0]
	v_pk_add_f32 v[6:7], v[116:117], v[120:121] neg_lo:[0,1] neg_hi:[0,1]
	v_pk_fma_f32 v[86:87], v[104:105], v[110:111], v[86:87] op_sel_hi:[1,0,1]
	v_pk_mul_f32 v[104:105], v[62:63], v[108:109] op_sel:[0,1] op_sel_hi:[0,0] neg_lo:[0,1]
	v_pk_fma_f32 v[104:105], v[26:27], v[108:109], v[104:105]
	v_pk_mul_f32 v[108:109], v[96:97], v[104:105] op_sel:[1,1] op_sel_hi:[0,1] neg_hi:[1,0]
	v_pk_fma_f32 v[96:97], v[96:97], v[104:105], v[108:109] op_sel_hi:[1,0,1]
	v_pk_mul_f32 v[108:109], v[62:63], v[102:103] op_sel:[0,1] op_sel_hi:[0,0] neg_lo:[0,1]
	v_pk_mul_f32 v[110:111], v[100:101], v[102:103] op_sel:[1,1] op_sel_hi:[0,1] neg_hi:[1,0]
	v_pk_fma_f32 v[108:109], v[26:27], v[102:103], v[108:109]
	v_pk_fma_f32 v[100:101], v[100:101], v[102:103], v[110:111] op_sel_hi:[1,0,1]
	v_pk_mul_f32 v[102:103], v[62:63], v[104:105] op_sel:[0,1] op_sel_hi:[0,0] neg_lo:[0,1]
	v_pk_fma_f32 v[102:103], v[26:27], v[104:105], v[102:103]
	v_pk_mul_f32 v[104:105], v[98:99], v[102:103] op_sel:[1,1] op_sel_hi:[0,1] neg_hi:[1,0]
	v_pk_fma_f32 v[98:99], v[98:99], v[102:103], v[104:105] op_sel_hi:[1,0,1]
	v_pk_mul_f32 v[104:105], v[62:63], v[108:109] op_sel:[0,1] op_sel_hi:[0,0] neg_lo:[0,1]
	v_pk_mul_f32 v[110:111], v[106:107], v[108:109] op_sel:[1,1] op_sel_hi:[0,1] neg_hi:[1,0]
	v_pk_fma_f32 v[104:105], v[26:27], v[108:109], v[104:105]
	v_pk_fma_f32 v[106:107], v[106:107], v[108:109], v[110:111] op_sel_hi:[1,0,1]
	v_pk_mul_f32 v[108:109], v[62:63], v[102:103] op_sel:[0,1] op_sel_hi:[0,0] neg_lo:[0,1]
	v_pk_fma_f32 v[102:103], v[26:27], v[102:103], v[108:109]
	v_pk_mul_f32 v[108:109], v[88:89], v[102:103] op_sel:[1,1] op_sel_hi:[0,1] neg_hi:[1,0]
	v_pk_fma_f32 v[88:89], v[88:89], v[102:103], v[108:109] op_sel_hi:[1,0,1]
	v_pk_mul_f32 v[108:109], v[62:63], v[104:105] op_sel:[0,1] op_sel_hi:[0,0] neg_lo:[0,1]
	v_pk_mul_f32 v[110:111], v[92:93], v[104:105] op_sel:[1,1] op_sel_hi:[0,1] neg_hi:[1,0]
	v_pk_fma_f32 v[108:109], v[26:27], v[104:105], v[108:109]
	v_pk_fma_f32 v[92:93], v[92:93], v[104:105], v[110:111] op_sel_hi:[1,0,1]
	v_pk_mul_f32 v[104:105], v[62:63], v[102:103] op_sel:[0,1] op_sel_hi:[0,0] neg_lo:[0,1]
	v_pk_fma_f32 v[102:103], v[26:27], v[102:103], v[104:105]
	v_pk_mul_f32 v[104:105], v[80:81], v[102:103] op_sel:[1,1] op_sel_hi:[0,1] neg_hi:[1,0]
	v_pk_fma_f32 v[80:81], v[80:81], v[102:103], v[104:105] op_sel_hi:[1,0,1]
	v_pk_mul_f32 v[104:105], v[62:63], v[108:109] op_sel:[0,1] op_sel_hi:[0,0] neg_lo:[0,1]
	v_pk_mul_f32 v[110:111], v[82:83], v[108:109] op_sel:[1,1] op_sel_hi:[0,1] neg_hi:[1,0]
	v_pk_fma_f32 v[104:105], v[26:27], v[108:109], v[104:105]
	v_pk_fma_f32 v[82:83], v[82:83], v[108:109], v[110:111] op_sel_hi:[1,0,1]
	v_pk_mul_f32 v[108:109], v[62:63], v[102:103] op_sel:[0,1] op_sel_hi:[0,0] neg_lo:[0,1]
	v_pk_fma_f32 v[102:103], v[26:27], v[102:103], v[108:109]
	v_pk_mul_f32 v[108:109], v[74:75], v[102:103] op_sel:[1,1] op_sel_hi:[0,1] neg_hi:[1,0]
	v_pk_fma_f32 v[74:75], v[74:75], v[102:103], v[108:109] op_sel_hi:[1,0,1]
	v_pk_mul_f32 v[108:109], v[62:63], v[104:105] op_sel:[0,1] op_sel_hi:[0,0] neg_lo:[0,1]
	v_pk_mul_f32 v[110:111], v[76:77], v[104:105] op_sel:[1,1] op_sel_hi:[0,1] neg_hi:[1,0]
	v_pk_fma_f32 v[108:109], v[26:27], v[104:105], v[108:109]
	v_pk_fma_f32 v[76:77], v[76:77], v[104:105], v[110:111] op_sel_hi:[1,0,1]
	v_pk_mul_f32 v[104:105], v[62:63], v[102:103] op_sel:[0,1] op_sel_hi:[0,0] neg_lo:[0,1]
	v_pk_fma_f32 v[102:103], v[26:27], v[102:103], v[104:105]
	v_pk_mul_f32 v[104:105], v[68:69], v[102:103] op_sel:[1,1] op_sel_hi:[0,1] neg_hi:[1,0]
	v_pk_fma_f32 v[68:69], v[68:69], v[102:103], v[104:105] op_sel_hi:[1,0,1]
	v_pk_mul_f32 v[104:105], v[62:63], v[108:109] op_sel:[0,1] op_sel_hi:[0,0] neg_lo:[0,1]
	v_pk_mul_f32 v[110:111], v[70:71], v[108:109] op_sel:[1,1] op_sel_hi:[0,1] neg_hi:[1,0]
	v_pk_fma_f32 v[104:105], v[26:27], v[108:109], v[104:105]
	v_pk_fma_f32 v[70:71], v[70:71], v[108:109], v[110:111] op_sel_hi:[1,0,1]
	v_pk_mul_f32 v[108:109], v[62:63], v[102:103] op_sel:[0,1] op_sel_hi:[0,0] neg_lo:[0,1]
	v_pk_fma_f32 v[102:103], v[26:27], v[102:103], v[108:109]
	v_pk_mul_f32 v[108:109], v[20:21], v[102:103] op_sel:[1,1] op_sel_hi:[0,1] neg_hi:[1,0]
	v_pk_fma_f32 v[20:21], v[20:21], v[102:103], v[108:109] op_sel_hi:[1,0,1]
	v_pk_mul_f32 v[108:109], v[62:63], v[104:105] op_sel:[0,1] op_sel_hi:[0,0] neg_lo:[0,1]
	v_pk_mul_f32 v[110:111], v[22:23], v[104:105] op_sel:[1,1] op_sel_hi:[0,1] neg_hi:[1,0]
	v_pk_fma_f32 v[108:109], v[26:27], v[104:105], v[108:109]
	v_pk_fma_f32 v[22:23], v[22:23], v[104:105], v[110:111] op_sel_hi:[1,0,1]
	v_pk_mul_f32 v[104:105], v[62:63], v[102:103] op_sel:[0,1] op_sel_hi:[0,0] neg_lo:[0,1]
	v_pk_fma_f32 v[102:103], v[26:27], v[102:103], v[104:105]
	v_pk_mul_f32 v[104:105], v[12:13], v[102:103] op_sel:[1,1] op_sel_hi:[0,1] neg_hi:[1,0]
	v_pk_fma_f32 v[12:13], v[12:13], v[102:103], v[104:105] op_sel_hi:[1,0,1]
	v_pk_mul_f32 v[104:105], v[62:63], v[108:109] op_sel:[0,1] op_sel_hi:[0,0] neg_lo:[0,1]
	v_pk_mul_f32 v[110:111], v[14:15], v[108:109] op_sel:[1,1] op_sel_hi:[0,1] neg_hi:[1,0]
	v_pk_fma_f32 v[104:105], v[26:27], v[108:109], v[104:105]
	v_pk_fma_f32 v[14:15], v[14:15], v[108:109], v[110:111] op_sel_hi:[1,0,1]
	v_pk_mul_f32 v[108:109], v[62:63], v[102:103] op_sel:[0,1] op_sel_hi:[0,0] neg_lo:[0,1]
	v_pk_fma_f32 v[102:103], v[26:27], v[102:103], v[108:109]
	v_pk_mul_f32 v[108:109], v[8:9], v[102:103] op_sel:[1,1] op_sel_hi:[0,1] neg_hi:[1,0]
	v_pk_fma_f32 v[8:9], v[8:9], v[102:103], v[108:109] op_sel_hi:[1,0,1]
	v_pk_mul_f32 v[108:109], v[62:63], v[104:105] op_sel:[0,1] op_sel_hi:[0,0] neg_lo:[0,1]
	v_pk_mul_f32 v[110:111], v[10:11], v[104:105] op_sel:[1,1] op_sel_hi:[0,1] neg_hi:[1,0]
	v_pk_fma_f32 v[108:109], v[26:27], v[104:105], v[108:109]
	v_pk_fma_f32 v[10:11], v[10:11], v[104:105], v[110:111] op_sel_hi:[1,0,1]
	v_pk_mul_f32 v[104:105], v[62:63], v[102:103] op_sel:[0,1] op_sel_hi:[0,0] neg_lo:[0,1]
	v_pk_fma_f32 v[26:27], v[26:27], v[102:103], v[104:105]
	s_nop 0
	v_pk_mul_f32 v[102:103], v[4:5], v[26:27] op_sel:[1,1] op_sel_hi:[0,1] neg_hi:[1,0]
	s_add_i32 s1, 16, 0x1e000
	v_pk_fma_f32 v[4:5], v[4:5], v[26:27], v[102:103] op_sel_hi:[1,0,1]
	s_nop 0
	s_nop 0
	v_pk_mul_f32 v[26:27], v[6:7], v[108:109] op_sel:[1,1] op_sel_hi:[0,1] neg_hi:[1,0]
	s_add_i32 s0, 16, 0x1f000
	v_pk_fma_f32 v[6:7], v[6:7], v[108:109], v[26:27] op_sel_hi:[1,0,1]
	v_lshrrev_b32_e32 v26, 5, v63
	v_bitop3_b32 v26, v26, v63, 15 bitop3:0x6c
	v_lshlrev_b32_e32 v26, 3, v26
	v_bfe_u32 v27, v63, 5, 4
	v_add_u32_e32 v62, 16, v26
	ds_write_b64 v62, v[2:3]
	v_bitop3_b32 v2, v27, v63, 16 bitop3:0x36
	v_lshlrev_b32_e32 v2, 3, v2
	v_add_u32_e32 v3, 16, v2
	ds_write_b64 v3, v[88:89] offset:4096
	ds_write_b64 v62, v[90:91] offset:8192
	ds_write_b64 v3, v[20:21] offset:12288
	ds_write_b64 v62, v[72:73] offset:16384
	ds_write_b64 v3, v[74:75] offset:20480
	ds_write_b64 v62, v[96:97] offset:24576
	ds_write_b64 v3, v[8:9] offset:28672
	ds_write_b64 v62, v[24:25] offset:32768
	ds_write_b64 v3, v[80:81] offset:36864
	ds_write_b64 v62, v[94:95] offset:40960
	ds_write_b64 v3, v[12:13] offset:45056
	ds_write_b64 v62, v[78:79] offset:49152
	ds_write_b64 v3, v[68:69] offset:53248
	ds_write_b64 v62, v[98:99] offset:57344
	ds_write_b64 v3, v[4:5] offset:61440
	v_add_u32_e32 v3, s47, v26
	ds_write_b64 v3, v[18:19]
	v_add_u32_e32 v3, s19, v2
	ds_write_b64 v3, v[92:93]
	v_add_u32_e32 v3, s18, v26
	ds_write_b64 v3, v[84:85]
	v_add_u32_e32 v3, s17, v2
	ds_write_b64 v3, v[22:23]
	v_add_u32_e32 v3, s13, v26
	ds_write_b64 v3, v[64:65]
	v_add_u32_e32 v3, s12, v2
	ds_write_b64 v3, v[76:77]
	v_add_u32_e32 v3, s11, v26
	ds_write_b64 v3, v[100:101]
	v_add_u32_e32 v3, s10, v2
	ds_write_b64 v3, v[10:11]
	v_add_u32_e32 v3, s9, v26
	ds_write_b64 v3, v[16:17]
	v_add_u32_e32 v3, s8, v2
	ds_write_b64 v3, v[82:83]
	v_add_u32_e32 v3, s7, v26
	ds_write_b64 v3, v[86:87]
	v_add_u32_e32 v3, s6, v2
	ds_write_b64 v3, v[14:15]
	v_add_u32_e32 v3, s5, v26
	ds_write_b64 v3, v[66:67]
	v_add_u32_e32 v3, s4, v2
	ds_write_b64 v3, v[70:71]
	v_add_u32_e32 v3, s1, v26
	v_add_u32_e32 v2, s0, v2
	v_mov_b32_e32 v21, v146
	ds_write_b64 v3, v[106:107]
	ds_write_b64 v2, v[6:7]
	s_waitcnt lgkmcnt(0)
	s_barrier
	s_lshl_b32 s44, s16, 14
	v_lshlrev_b32_e32 v2, 5, v21
	v_and_b32_e32 v4, 0xfffffe00, v2
	v_and_b32_e32 v20, 15, v21
	v_and_or_b32 v2, v21, 16, v4
	v_bitop3_b32 v4, v4, 16, v21 bitop3:0x34
	v_bitop3_b32 v72, v21, 8, 15 bitop3:0x6c
	v_lshl_add_u32 v26, v2, 3, 16
	v_lshlrev_b32_e32 v5, 3, v20
	v_lshl_add_u32 v126, v4, 3, 16
	v_lshlrev_b32_e32 v74, 3, v72
	v_add_u32_e32 v27, v26, v5
	v_add_u32_e32 v96, v126, v5
	v_add_u32_e32 v111, v26, v74
	v_add_u32_e32 v112, v126, v74
	ds_read_b64 v[2:3], v27
	ds_read_b64 v[4:5], v96
	v_bitop3_b32 v6, v21, 1, 15 bitop3:0x6c
	ds_read_b64 v[72:73], v111 offset:2048
	ds_read_b64 v[74:75], v112 offset:2048
	v_bitop3_b32 v76, v21, 9, 15 bitop3:0x6c
	v_lshlrev_b32_e32 v8, 3, v6
	v_lshlrev_b32_e32 v78, 3, v76
	v_add_u32_e32 v97, v26, v8
	v_add_u32_e32 v113, v26, v78
	ds_read_b64 v[6:7], v97 offset:256
	ds_read_b64 v[76:77], v113 offset:2304
	v_add_u32_e32 v98, v126, v8
	v_add_u32_e32 v114, v126, v78
	ds_read_b64 v[8:9], v98 offset:256
	ds_read_b64 v[78:79], v114 offset:2304
	s_waitcnt lgkmcnt(5)
	v_pk_add_f32 v[136:137], v[2:3], v[72:73]
	v_pk_add_f32 v[2:3], v[2:3], v[72:73] neg_lo:[0,1] neg_hi:[0,1]
	s_waitcnt lgkmcnt(4)
	v_pk_add_f32 v[72:73], v[4:5], v[74:75]
	v_pk_add_f32 v[4:5], v[4:5], v[74:75] neg_lo:[0,1] neg_hi:[0,1]
	v_bitop3_b32 v10, v21, 2, 15 bitop3:0x6c
	v_bitop3_b32 v80, v21, 10, 15 bitop3:0x6c
	v_lshlrev_b32_e32 v12, 3, v10
	v_lshlrev_b32_e32 v82, 3, v80
	v_pk_mul_f32 v[74:75], v[4:5], s[58:59] op_sel:[1,0] op_sel_hi:[0,0] neg_hi:[1,0]
	v_add_u32_e32 v99, v26, v12
	v_add_u32_e32 v115, v26, v82
	v_pk_fma_f32 v[4:5], v[4:5], s[46:47], v[74:75] op_sel_hi:[1,0,1]
	s_waitcnt lgkmcnt(2)
	v_pk_add_f32 v[74:75], v[6:7], v[76:77]
	v_pk_add_f32 v[6:7], v[6:7], v[76:77] neg_lo:[0,1] neg_hi:[0,1]
	ds_read_b64 v[10:11], v99 offset:512
	ds_read_b64 v[80:81], v115 offset:2560
	v_pk_mul_f32 v[76:77], v[6:7], s[62:63] op_sel:[1,0] op_sel_hi:[0,0] neg_hi:[1,0]
	v_add_u32_e32 v100, v126, v12
	v_bitop3_b32 v14, v21, 3, 15 bitop3:0x6c
	v_add_u32_e32 v116, v126, v82
	v_bitop3_b32 v84, v21, 11, 15 bitop3:0x6c
	v_pk_fma_f32 v[6:7], v[6:7], s[60:61], v[76:77] op_sel_hi:[1,0,1]
	s_waitcnt lgkmcnt(2)
	v_pk_add_f32 v[76:77], v[8:9], v[78:79]
	v_pk_add_f32 v[8:9], v[8:9], v[78:79] neg_lo:[0,1] neg_hi:[0,1]
	ds_read_b64 v[12:13], v100 offset:512
	v_lshlrev_b32_e32 v16, 3, v14
	ds_read_b64 v[82:83], v116 offset:2560
	v_lshlrev_b32_e32 v86, 3, v84
	v_add_u32_e32 v101, v26, v16
	v_add_u32_e32 v102, v126, v16
	v_add_u32_e32 v117, v26, v86
	v_add_u32_e32 v118, v126, v86
	v_pk_mul_f32 v[78:79], v[8:9], s[66:67] op_sel:[1,0] op_sel_hi:[0,0] neg_hi:[1,0]
	ds_read_b64 v[14:15], v101 offset:768
	ds_read_b64 v[16:17], v102 offset:768
	ds_read_b64 v[84:85], v117 offset:2816
	ds_read_b64 v[86:87], v118 offset:2816
	v_pk_fma_f32 v[8:9], v[8:9], s[64:65], v[78:79] op_sel_hi:[1,0,1]
	s_waitcnt lgkmcnt(6)
	v_pk_add_f32 v[78:79], v[10:11], v[80:81]
	v_pk_add_f32 v[10:11], v[10:11], v[80:81] neg_lo:[0,1] neg_hi:[0,1]
	v_bitop3_b32 v18, v21, 4, 15 bitop3:0x6c
	v_pk_mul_f32 v[80:81], v[10:11], s[70:71] op_sel:[1,0] op_sel_hi:[0,0] neg_hi:[1,0]
	v_bitop3_b32 v88, v21, 12, 15 bitop3:0x6c
	v_pk_fma_f32 v[10:11], v[10:11], s[70:71], v[80:81] op_sel_hi:[1,0,1]
	s_waitcnt lgkmcnt(4)
	v_pk_add_f32 v[80:81], v[12:13], v[82:83]
	v_pk_add_f32 v[12:13], v[12:13], v[82:83] neg_lo:[0,1] neg_hi:[0,1]
	v_lshlrev_b32_e32 v22, 3, v18
	v_lshlrev_b32_e32 v90, 3, v88
	v_pk_mul_f32 v[82:83], v[12:13], s[64:65] op_sel:[1,0] op_sel_hi:[0,0] neg_hi:[1,0]
	v_add_u32_e32 v103, v26, v22
	v_add_u32_e32 v119, v26, v90
	v_pk_fma_f32 v[12:13], v[12:13], s[66:67], v[82:83] op_sel_hi:[1,0,1]
	s_waitcnt lgkmcnt(1)
	v_pk_add_f32 v[82:83], v[14:15], v[84:85]
	v_pk_add_f32 v[14:15], v[14:15], v[84:85] neg_lo:[0,1] neg_hi:[0,1]
	ds_read_b64 v[18:19], v103 offset:1024
	v_add_u32_e32 v104, v126, v22
	v_bitop3_b32 v24, v21, 5, 15 bitop3:0x6c
	ds_read_b64 v[88:89], v119 offset:3072
	v_add_u32_e32 v120, v126, v90
	v_bitop3_b32 v92, v21, 13, 15 bitop3:0x6c
	ds_read_b64 v[22:23], v104 offset:1024
	v_lshlrev_b32_e32 v62, 3, v24
	ds_read_b64 v[90:91], v120 offset:3072
	v_lshlrev_b32_e32 v94, 3, v92
	v_pk_mul_f32 v[84:85], v[14:15], s[60:61] op_sel:[1,0] op_sel_hi:[0,0] neg_hi:[1,0]
	v_add_u32_e32 v105, v26, v62
	v_add_u32_e32 v121, v26, v94
	v_pk_fma_f32 v[14:15], v[14:15], s[62:63], v[84:85] op_sel_hi:[1,0,1]
	s_waitcnt lgkmcnt(4)
	v_pk_add_f32 v[84:85], v[16:17], v[86:87]
	v_pk_add_f32 v[16:17], v[16:17], v[86:87] neg_lo:[0,1] neg_hi:[0,1]
	ds_read_b64 v[24:25], v105 offset:1280
	ds_read_b64 v[92:93], v121 offset:3328
	v_add_u32_e32 v106, v126, v62
	v_bitop3_b32 v64, v21, 6, 15 bitop3:0x6c
	v_add_u32_e32 v122, v126, v94
	v_bitop3_b32 v123, v21, 14, 15 bitop3:0x6c
	v_pk_mul_f32 v[86:87], v[16:17], s[46:47] op_sel:[1,0] op_sel_hi:[0,0] neg_hi:[1,0]
	ds_read_b64 v[62:63], v106 offset:1280
	v_lshlrev_b32_e32 v66, 3, v64
	ds_read_b64 v[94:95], v122 offset:3328
	v_lshlrev_b32_e32 v124, 3, v123
	v_pk_fma_f32 v[16:17], v[16:17], s[58:59], v[86:87] op_sel_hi:[1,0,1]
	s_waitcnt lgkmcnt(6)
	v_pk_add_f32 v[86:87], v[18:19], v[88:89]
	v_pk_add_f32 v[18:19], v[18:19], v[88:89] neg_lo:[0,1] neg_hi:[0,1]
	v_add_u32_e32 v107, v26, v66
	v_add_u32_e32 v123, v26, v124
	v_xor_b32_e32 v89, 0x80000000, v18
	v_mov_b32_e32 v88, v19
	s_waitcnt lgkmcnt(4)
	v_pk_add_f32 v[18:19], v[22:23], v[90:91]
	v_pk_add_f32 v[22:23], v[22:23], v[90:91] neg_lo:[0,1] neg_hi:[0,1]
	ds_read_b64 v[64:65], v107 offset:1536
	ds_read_b64 v[128:129], v123 offset:3584
	v_pk_mul_f32 v[90:91], v[22:23], s[58:59] op_sel_hi:[1,0]
	v_xor_b32_e32 v139, 0x80000000, v22
	v_mov_b32_e32 v138, v23
	v_add_u32_e32 v108, v126, v66
	v_bitop3_b32 v68, v21, 7, 15 bitop3:0x6c
	v_add_u32_e32 v124, v126, v124
	v_bitop3_b32 v21, v21, 15, v21 bitop3:0xc
	v_pk_fma_f32 v[22:23], v[138:139], s[46:47], v[90:91] op_sel_hi:[1,0,1] neg_lo:[0,0,1] neg_hi:[0,0,1]
	s_waitcnt lgkmcnt(4)
	v_pk_add_f32 v[90:91], v[24:25], v[92:93]
	v_pk_add_f32 v[24:25], v[24:25], v[92:93] neg_lo:[0,1] neg_hi:[0,1]
	ds_read_b64 v[66:67], v108 offset:1536
	v_lshlrev_b32_e32 v70, 3, v68
	ds_read_b64 v[130:131], v124 offset:3584
	v_lshlrev_b32_e32 v21, 3, v21
	v_pk_mul_f32 v[92:93], v[24:25], s[62:63] op_sel_hi:[1,0]
	v_xor_b32_e32 v139, 0x80000000, v24
	v_mov_b32_e32 v138, v25
	v_add_u32_e32 v109, v26, v70
	v_add_u32_e32 v125, v26, v21
	v_pk_fma_f32 v[24:25], v[138:139], s[60:61], v[92:93] op_sel_hi:[1,0,1] neg_lo:[0,0,1] neg_hi:[0,0,1]
	s_waitcnt lgkmcnt(4)
	v_pk_add_f32 v[92:93], v[62:63], v[94:95]
	v_pk_add_f32 v[62:63], v[62:63], v[94:95] neg_lo:[0,1] neg_hi:[0,1]
	ds_read_b64 v[68:69], v109 offset:1792
	v_add_u32_e32 v110, v126, v70
	ds_read_b64 v[132:133], v125 offset:3840
	v_add_u32_e32 v126, v126, v21
	v_pk_mul_f32 v[94:95], v[62:63], s[66:67] op_sel_hi:[1,0]
	v_xor_b32_e32 v139, 0x80000000, v62
	v_mov_b32_e32 v138, v63
	ds_read_b64 v[70:71], v110 offset:1792
	ds_read_b64 v[134:135], v126 offset:3840
	v_pk_fma_f32 v[62:63], v[138:139], s[64:65], v[94:95] op_sel_hi:[1,0,1] neg_lo:[0,0,1] neg_hi:[0,0,1]
	s_waitcnt lgkmcnt(6)
	v_pk_add_f32 v[94:95], v[64:65], v[128:129]
	v_pk_add_f32 v[64:65], v[64:65], v[128:129] neg_lo:[0,1] neg_hi:[0,1]
	v_lshl_add_u64 v[0:1], s[44:45], 2, v[28:29]
	v_pk_mul_f32 v[128:129], v[64:65], s[70:71] op_sel_hi:[1,0]
	v_xor_b32_e32 v139, 0x80000000, v64
	v_mov_b32_e32 v138, v65
	v_pk_fma_f32 v[64:65], v[138:139], s[70:71], v[128:129] op_sel_hi:[1,0,1] neg_lo:[0,0,1] neg_hi:[0,0,1]
	s_waitcnt lgkmcnt(4)
	v_pk_add_f32 v[128:129], v[66:67], v[130:131]
	v_pk_add_f32 v[66:67], v[66:67], v[130:131] neg_lo:[0,1] neg_hi:[0,1]
	v_cvt_f32_i32_e32 v20, v20
	v_pk_mul_f32 v[130:131], v[66:67], s[64:65] op_sel_hi:[1,0]
	v_xor_b32_e32 v139, 0x80000000, v66
	v_mov_b32_e32 v138, v67
	v_pk_fma_f32 v[66:67], v[138:139], s[66:67], v[130:131] op_sel_hi:[1,0,1] neg_lo:[0,0,1] neg_hi:[0,0,1]
	s_waitcnt lgkmcnt(2)
	v_pk_add_f32 v[130:131], v[68:69], v[132:133]
	v_pk_add_f32 v[68:69], v[68:69], v[132:133] neg_lo:[0,1] neg_hi:[0,1]
	v_mul_f32_e32 v21, 0x3b000000, v20
	v_pk_mul_f32 v[132:133], v[68:69], s[60:61] op_sel_hi:[1,0]
	v_xor_b32_e32 v139, 0x80000000, v68
	v_mov_b32_e32 v138, v69
	v_pk_fma_f32 v[68:69], v[138:139], s[62:63], v[132:133] op_sel_hi:[1,0,1] neg_lo:[0,0,1] neg_hi:[0,0,1]
	s_waitcnt lgkmcnt(0)
	v_pk_add_f32 v[132:133], v[70:71], v[134:135]
	v_pk_add_f32 v[70:71], v[70:71], v[134:135] neg_lo:[0,1] neg_hi:[0,1]
	v_cos_f32_e32 v20, v21
	v_pk_mul_f32 v[134:135], v[70:71], s[46:47] op_sel_hi:[1,0]
	v_xor_b32_e32 v139, 0x80000000, v70
	v_mov_b32_e32 v138, v71
	v_pk_fma_f32 v[70:71], v[138:139], s[58:59], v[134:135] op_sel_hi:[1,0,1] neg_lo:[0,0,1] neg_hi:[0,0,1]
	v_pk_add_f32 v[134:135], v[136:137], v[86:87]
	v_pk_add_f32 v[86:87], v[136:137], v[86:87] neg_lo:[0,1] neg_hi:[0,1]
	v_pk_add_f32 v[136:137], v[72:73], v[18:19]
	v_pk_add_f32 v[18:19], v[72:73], v[18:19] neg_lo:[0,1] neg_hi:[0,1]
	v_sin_f32_e32 v21, v21
	s_nop 0
	s_nop 0
	v_pk_mul_f32 v[72:73], v[18:19], s[62:63] op_sel:[1,0] op_sel_hi:[0,0] neg_hi:[1,0]
	v_add_f32_e32 v26, v20, v20
	v_pk_fma_f32 v[18:19], v[18:19], s[60:61], v[72:73] op_sel_hi:[1,0,1]
	v_pk_add_f32 v[72:73], v[74:75], v[90:91]
	v_pk_add_f32 v[74:75], v[74:75], v[90:91] neg_lo:[0,1] neg_hi:[0,1]
	v_mul_f32_e32 v26, v21, v26
	s_nop 0
	s_nop 0
	v_pk_mul_f32 v[90:91], v[74:75], s[70:71] op_sel:[1,0] op_sel_hi:[0,0] neg_hi:[1,0]
	s_lshl_b32 s44, s16, 9
	v_pk_fma_f32 v[74:75], v[74:75], s[70:71], v[90:91] op_sel_hi:[1,0,1]
	v_pk_add_f32 v[90:91], v[76:77], v[92:93]
	v_pk_add_f32 v[76:77], v[76:77], v[92:93] neg_lo:[0,1] neg_hi:[0,1]
	s_mov_b64 s[28:29], -1
	s_nop 0
	s_nop 0
	v_pk_mul_f32 v[92:93], v[76:77], s[60:61] op_sel:[1,0] op_sel_hi:[0,0] neg_hi:[1,0]
	s_nop 0
	v_pk_fma_f32 v[76:77], v[76:77], s[62:63], v[92:93] op_sel_hi:[1,0,1]
	v_pk_add_f32 v[92:93], v[78:79], v[94:95]
	v_pk_add_f32 v[78:79], v[78:79], v[94:95] neg_lo:[0,1] neg_hi:[0,1]
	v_xor_b32_e32 v95, 0x80000000, v78
	v_mov_b32_e32 v94, v79
	v_pk_add_f32 v[78:79], v[80:81], v[128:129]
	v_pk_add_f32 v[80:81], v[80:81], v[128:129] neg_lo:[0,1] neg_hi:[0,1]
	v_pk_mul_f32 v[128:129], v[80:81], s[62:63] op_sel_hi:[1,0]
	v_xor_b32_e32 v139, 0x80000000, v80
	v_mov_b32_e32 v138, v81
	v_pk_fma_f32 v[80:81], v[138:139], s[60:61], v[128:129] op_sel_hi:[1,0,1] neg_lo:[0,0,1] neg_hi:[0,0,1]
	v_pk_add_f32 v[128:129], v[82:83], v[130:131]
	v_pk_add_f32 v[82:83], v[82:83], v[130:131] neg_lo:[0,1] neg_hi:[0,1]
	v_pk_mul_f32 v[130:131], v[82:83], s[70:71] op_sel_hi:[1,0]
	v_xor_b32_e32 v139, 0x80000000, v82
	v_mov_b32_e32 v138, v83
	v_pk_fma_f32 v[82:83], v[138:139], s[70:71], v[130:131] op_sel_hi:[1,0,1] neg_lo:[0,0,1] neg_hi:[0,0,1]
	v_pk_add_f32 v[130:131], v[84:85], v[132:133]
	v_pk_add_f32 v[84:85], v[84:85], v[132:133] neg_lo:[0,1] neg_hi:[0,1]
	v_pk_mul_f32 v[132:133], v[84:85], s[60:61] op_sel_hi:[1,0]
	v_xor_b32_e32 v139, 0x80000000, v84
	v_mov_b32_e32 v138, v85
	v_pk_fma_f32 v[84:85], v[138:139], s[62:63], v[132:133] op_sel_hi:[1,0,1] neg_lo:[0,0,1] neg_hi:[0,0,1]
	v_pk_add_f32 v[132:133], v[2:3], v[88:89]
	v_pk_add_f32 v[2:3], v[2:3], v[88:89] neg_lo:[0,1] neg_hi:[0,1]
	v_pk_add_f32 v[88:89], v[4:5], v[22:23]
	v_pk_add_f32 v[4:5], v[4:5], v[22:23] neg_lo:[0,1] neg_hi:[0,1]
	v_pk_mul_f32 v[22:23], v[4:5], s[62:63] op_sel:[1,0] op_sel_hi:[0,0] neg_hi:[1,0]
	v_pk_fma_f32 v[4:5], v[4:5], s[60:61], v[22:23] op_sel_hi:[1,0,1]
	v_pk_add_f32 v[22:23], v[6:7], v[24:25]
	v_pk_add_f32 v[6:7], v[6:7], v[24:25] neg_lo:[0,1] neg_hi:[0,1]
	v_pk_mul_f32 v[24:25], v[6:7], s[70:71] op_sel:[1,0] op_sel_hi:[0,0] neg_hi:[1,0]
	v_pk_fma_f32 v[6:7], v[6:7], s[70:71], v[24:25] op_sel_hi:[1,0,1]
	v_pk_add_f32 v[24:25], v[8:9], v[62:63]
	v_pk_add_f32 v[8:9], v[8:9], v[62:63] neg_lo:[0,1] neg_hi:[0,1]
	v_pk_mul_f32 v[62:63], v[8:9], s[60:61] op_sel:[1,0] op_sel_hi:[0,0] neg_hi:[1,0]
	v_pk_fma_f32 v[8:9], v[8:9], s[62:63], v[62:63] op_sel_hi:[1,0,1]
	v_pk_add_f32 v[62:63], v[10:11], v[64:65]
	v_pk_add_f32 v[10:11], v[10:11], v[64:65] neg_lo:[0,1] neg_hi:[0,1]
	v_xor_b32_e32 v65, 0x80000000, v10
	v_mov_b32_e32 v64, v11
	v_pk_add_f32 v[10:11], v[12:13], v[66:67]
	v_pk_add_f32 v[12:13], v[12:13], v[66:67] neg_lo:[0,1] neg_hi:[0,1]
	v_pk_mul_f32 v[66:67], v[12:13], s[62:63] op_sel_hi:[1,0]
	v_xor_b32_e32 v139, 0x80000000, v12
	v_mov_b32_e32 v138, v13
	v_pk_fma_f32 v[12:13], v[138:139], s[60:61], v[66:67] op_sel_hi:[1,0,1] neg_lo:[0,0,1] neg_hi:[0,0,1]
	v_pk_add_f32 v[66:67], v[14:15], v[68:69]
	v_pk_add_f32 v[14:15], v[14:15], v[68:69] neg_lo:[0,1] neg_hi:[0,1]
	v_pk_mul_f32 v[68:69], v[14:15], s[70:71] op_sel_hi:[1,0]
	v_xor_b32_e32 v139, 0x80000000, v14
	v_mov_b32_e32 v138, v15
	v_pk_fma_f32 v[14:15], v[138:139], s[70:71], v[68:69] op_sel_hi:[1,0,1] neg_lo:[0,0,1] neg_hi:[0,0,1]
	v_pk_add_f32 v[68:69], v[16:17], v[70:71]
	v_pk_add_f32 v[16:17], v[16:17], v[70:71] neg_lo:[0,1] neg_hi:[0,1]
	v_pk_mul_f32 v[70:71], v[16:17], s[60:61] op_sel_hi:[1,0]
	v_xor_b32_e32 v139, 0x80000000, v16
	v_mov_b32_e32 v138, v17
	v_pk_fma_f32 v[16:17], v[138:139], s[62:63], v[70:71] op_sel_hi:[1,0,1] neg_lo:[0,0,1] neg_hi:[0,0,1]
	v_pk_add_f32 v[70:71], v[134:135], v[92:93]
	v_pk_add_f32 v[92:93], v[134:135], v[92:93] neg_lo:[0,1] neg_hi:[0,1]
	v_pk_add_f32 v[134:135], v[136:137], v[78:79]
	v_pk_add_f32 v[78:79], v[136:137], v[78:79] neg_lo:[0,1] neg_hi:[0,1]
	v_pk_mul_f32 v[136:137], v[78:79], s[70:71] op_sel:[1,0] op_sel_hi:[0,0] neg_hi:[1,0]
	v_pk_fma_f32 v[78:79], v[78:79], s[70:71], v[136:137] op_sel_hi:[1,0,1]
	v_pk_add_f32 v[136:137], v[72:73], v[128:129]
	v_pk_add_f32 v[72:73], v[72:73], v[128:129] neg_lo:[0,1] neg_hi:[0,1]
	v_xor_b32_e32 v129, 0x80000000, v72
	v_mov_b32_e32 v128, v73
	v_pk_add_f32 v[72:73], v[90:91], v[130:131]
	v_pk_add_f32 v[90:91], v[90:91], v[130:131] neg_lo:[0,1] neg_hi:[0,1]
	v_pk_mul_f32 v[130:131], v[90:91], s[70:71] op_sel_hi:[1,0]
	v_xor_b32_e32 v139, 0x80000000, v90
	v_mov_b32_e32 v138, v91
	v_pk_fma_f32 v[90:91], v[138:139], s[70:71], v[130:131] op_sel_hi:[1,0,1] neg_lo:[0,0,1] neg_hi:[0,0,1]
	v_pk_add_f32 v[130:131], v[86:87], v[94:95]
	v_pk_add_f32 v[86:87], v[86:87], v[94:95] neg_lo:[0,1] neg_hi:[0,1]
	v_pk_add_f32 v[94:95], v[18:19], v[80:81]
	v_pk_add_f32 v[18:19], v[18:19], v[80:81] neg_lo:[0,1] neg_hi:[0,1]
	v_pk_mul_f32 v[80:81], v[18:19], s[70:71] op_sel:[1,0] op_sel_hi:[0,0] neg_hi:[1,0]
	v_pk_fma_f32 v[18:19], v[18:19], s[70:71], v[80:81] op_sel_hi:[1,0,1]
	v_pk_add_f32 v[80:81], v[74:75], v[82:83]
	v_pk_add_f32 v[74:75], v[74:75], v[82:83] neg_lo:[0,1] neg_hi:[0,1]
	v_xor_b32_e32 v83, 0x80000000, v74
	v_mov_b32_e32 v82, v75
	v_pk_add_f32 v[74:75], v[76:77], v[84:85]
	v_pk_add_f32 v[76:77], v[76:77], v[84:85] neg_lo:[0,1] neg_hi:[0,1]
	v_pk_mul_f32 v[84:85], v[76:77], s[70:71] op_sel_hi:[1,0]
	v_xor_b32_e32 v139, 0x80000000, v76
	v_mov_b32_e32 v138, v77
	v_pk_fma_f32 v[76:77], v[138:139], s[70:71], v[84:85] op_sel_hi:[1,0,1] neg_lo:[0,0,1] neg_hi:[0,0,1]
	v_pk_add_f32 v[84:85], v[132:133], v[62:63]
	v_pk_add_f32 v[62:63], v[132:133], v[62:63] neg_lo:[0,1] neg_hi:[0,1]
	v_pk_add_f32 v[132:133], v[88:89], v[10:11]
	v_pk_add_f32 v[10:11], v[88:89], v[10:11] neg_lo:[0,1] neg_hi:[0,1]
	v_pk_mul_f32 v[88:89], v[10:11], s[70:71] op_sel:[1,0] op_sel_hi:[0,0] neg_hi:[1,0]
	v_pk_fma_f32 v[10:11], v[10:11], s[70:71], v[88:89] op_sel_hi:[1,0,1]
	v_pk_add_f32 v[88:89], v[22:23], v[66:67]
	v_pk_add_f32 v[22:23], v[22:23], v[66:67] neg_lo:[0,1] neg_hi:[0,1]
	v_xor_b32_e32 v67, 0x80000000, v22
	v_mov_b32_e32 v66, v23
	v_pk_add_f32 v[22:23], v[24:25], v[68:69]
	v_pk_add_f32 v[24:25], v[24:25], v[68:69] neg_lo:[0,1] neg_hi:[0,1]
	v_pk_mul_f32 v[68:69], v[24:25], s[70:71] op_sel_hi:[1,0]
	v_xor_b32_e32 v139, 0x80000000, v24
	v_mov_b32_e32 v138, v25
	v_pk_fma_f32 v[24:25], v[138:139], s[70:71], v[68:69] op_sel_hi:[1,0,1] neg_lo:[0,0,1] neg_hi:[0,0,1]
	v_pk_add_f32 v[68:69], v[2:3], v[64:65]
	v_pk_add_f32 v[2:3], v[2:3], v[64:65] neg_lo:[0,1] neg_hi:[0,1]
	v_pk_add_f32 v[64:65], v[4:5], v[12:13]
	v_pk_add_f32 v[4:5], v[4:5], v[12:13] neg_lo:[0,1] neg_hi:[0,1]
	v_pk_mul_f32 v[12:13], v[4:5], s[70:71] op_sel:[1,0] op_sel_hi:[0,0] neg_hi:[1,0]
	v_pk_fma_f32 v[4:5], v[4:5], s[70:71], v[12:13] op_sel_hi:[1,0,1]
	v_pk_add_f32 v[12:13], v[6:7], v[14:15]
	v_pk_add_f32 v[6:7], v[6:7], v[14:15] neg_lo:[0,1] neg_hi:[0,1]
	v_pk_add_f32 v[140:141], v[68:69], v[12:13]
	v_xor_b32_e32 v15, 0x80000000, v6
	v_mov_b32_e32 v14, v7
	v_pk_add_f32 v[6:7], v[8:9], v[16:17]
	v_pk_add_f32 v[8:9], v[8:9], v[16:17] neg_lo:[0,1] neg_hi:[0,1]
	v_pk_add_f32 v[142:143], v[64:65], v[6:7]
	v_pk_mul_f32 v[16:17], v[8:9], s[70:71] op_sel_hi:[1,0]
	v_pk_fma_f32 v[8:9], v[8:9], s[70:71], v[16:17] op_sel:[1,0,0] op_sel_hi:[0,0,1] neg_lo:[0,0,1] neg_hi:[1,0,1]
	v_pk_add_f32 v[16:17], v[70:71], v[136:137]
	v_pk_add_f32 v[70:71], v[70:71], v[136:137] neg_lo:[0,1] neg_hi:[0,1]
	v_pk_add_f32 v[136:137], v[134:135], v[72:73]
	v_pk_add_f32 v[72:73], v[134:135], v[72:73] neg_lo:[0,1] neg_hi:[0,1]
	v_pk_add_f32 v[138:139], v[84:85], v[88:89] neg_lo:[0,1] neg_hi:[0,1]
	v_xor_b32_e32 v135, 0x80000000, v72
	v_mov_b32_e32 v134, v73
	v_pk_add_f32 v[72:73], v[92:93], v[128:129]
	v_pk_add_f32 v[92:93], v[92:93], v[128:129] neg_lo:[0,1] neg_hi:[0,1]
	v_pk_add_f32 v[128:129], v[78:79], v[90:91]
	v_pk_add_f32 v[78:79], v[78:79], v[90:91] neg_lo:[0,1] neg_hi:[0,1]
	v_pk_add_f32 v[6:7], v[64:65], v[6:7] neg_lo:[0,1] neg_hi:[0,1]
	v_xor_b32_e32 v91, 0x80000000, v78
	v_mov_b32_e32 v90, v79
	v_pk_add_f32 v[78:79], v[130:131], v[80:81]
	v_pk_add_f32 v[130:131], v[130:131], v[80:81] neg_lo:[0,1] neg_hi:[0,1]
	v_pk_add_f32 v[80:81], v[94:95], v[74:75]
	v_pk_add_f32 v[74:75], v[94:95], v[74:75] neg_lo:[0,1] neg_hi:[0,1]
	v_xor_b32_e32 v149, 0x80000000, v6
	v_xor_b32_e32 v95, 0x80000000, v74
	v_mov_b32_e32 v94, v75
	v_pk_add_f32 v[74:75], v[86:87], v[82:83]
	v_pk_add_f32 v[82:83], v[86:87], v[82:83] neg_lo:[0,1] neg_hi:[0,1]
	v_pk_add_f32 v[86:87], v[18:19], v[76:77]
	v_pk_add_f32 v[18:19], v[18:19], v[76:77] neg_lo:[0,1] neg_hi:[0,1]
	v_mov_b32_e32 v148, v7
	v_xor_b32_e32 v77, 0x80000000, v18
	v_mov_b32_e32 v76, v19
	v_pk_add_f32 v[18:19], v[84:85], v[88:89]
	v_pk_add_f32 v[88:89], v[132:133], v[22:23]
	v_pk_add_f32 v[22:23], v[132:133], v[22:23] neg_lo:[0,1] neg_hi:[0,1]
	v_pk_add_f32 v[6:7], v[2:3], v[14:15]
	v_xor_b32_e32 v133, 0x80000000, v22
	v_mov_b32_e32 v132, v23
	v_pk_add_f32 v[22:23], v[62:63], v[66:67]
	v_pk_add_f32 v[62:63], v[62:63], v[66:67] neg_lo:[0,1] neg_hi:[0,1]
	v_pk_add_f32 v[66:67], v[10:11], v[24:25]
	v_pk_add_f32 v[10:11], v[10:11], v[24:25] neg_lo:[0,1] neg_hi:[0,1]
	v_pk_add_f32 v[150:151], v[2:3], v[14:15] neg_lo:[0,1] neg_hi:[0,1]
	v_pk_add_f32 v[2:3], v[4:5], v[8:9] neg_lo:[0,1] neg_hi:[0,1]
	v_pk_add_f32 v[68:69], v[68:69], v[12:13] neg_lo:[0,1] neg_hi:[0,1]
	v_pk_add_f32 v[156:157], v[4:5], v[8:9]
	v_xor_b32_e32 v159, 0x80000000, v2
	v_mov_b32_e32 v158, v3
	v_pk_add_f32 v[2:3], v[16:17], v[136:137]
	v_pk_add_f32 v[84:85], v[16:17], v[136:137] neg_lo:[0,1] neg_hi:[0,1]
	v_pk_add_f32 v[136:137], v[70:71], v[134:135]
	v_pk_add_f32 v[16:17], v[70:71], v[134:135] neg_lo:[0,1] neg_hi:[0,1]
	v_pk_add_f32 v[134:135], v[72:73], v[128:129]
	v_pk_add_f32 v[70:71], v[72:73], v[128:129] neg_lo:[0,1] neg_hi:[0,1]
	v_pk_add_f32 v[128:129], v[92:93], v[90:91]
	v_pk_add_f32 v[8:9], v[92:93], v[90:91] neg_lo:[0,1] neg_hi:[0,1]
	v_pk_add_f32 v[72:73], v[78:79], v[80:81]
	v_pk_add_f32 v[80:81], v[78:79], v[80:81] neg_lo:[0,1] neg_hi:[0,1]
	v_pk_add_f32 v[92:93], v[130:131], v[94:95]
	v_pk_add_f32 v[12:13], v[130:131], v[94:95] neg_lo:[0,1] neg_hi:[0,1]
	v_pk_add_f32 v[78:79], v[74:75], v[86:87]
	v_pk_add_f32 v[64:65], v[74:75], v[86:87] neg_lo:[0,1] neg_hi:[0,1]
	v_pk_add_f32 v[130:131], v[82:83], v[76:77]
	v_pk_add_f32 v[4:5], v[82:83], v[76:77] neg_lo:[0,1] neg_hi:[0,1]
	v_pk_add_f32 v[76:77], v[18:19], v[88:89]
	v_pk_add_f32 v[88:89], v[18:19], v[88:89] neg_lo:[0,1] neg_hi:[0,1]
	v_pk_add_f32 v[86:87], v[138:139], v[132:133]
	v_pk_add_f32 v[18:19], v[138:139], v[132:133] neg_lo:[0,1] neg_hi:[0,1]
	v_pk_add_f32 v[132:133], v[62:63], v[10:11] op_sel:[0,1] op_sel_hi:[1,0] neg_hi:[0,1]
	v_pk_add_f32 v[10:11], v[62:63], v[10:11] op_sel:[0,1] op_sel_hi:[1,0] neg_lo:[0,1]
	v_pk_mul_f32 v[24:25], v[20:21], v[20:21]
	v_pk_add_f32 v[24:25], v[24:25], v[24:25] op_sel:[0,1] op_sel_hi:[0,1] neg_lo:[0,1] neg_hi:[0,1]
	v_pk_mul_f32 v[62:63], v[20:21], v[26:27] op_sel:[1,0] op_sel_hi:[0,0] neg_lo:[1,0]
	v_pk_add_f32 v[90:91], v[22:23], v[66:67]
	v_pk_add_f32 v[74:75], v[22:23], v[66:67] neg_lo:[0,1] neg_hi:[0,1]
	v_pk_add_f32 v[22:23], v[140:141], v[142:143]
	v_pk_add_f32 v[82:83], v[140:141], v[142:143] neg_lo:[0,1] neg_hi:[0,1]
	v_pk_add_f32 v[138:139], v[68:69], v[148:149]
	v_pk_add_f32 v[14:15], v[68:69], v[148:149] neg_lo:[0,1] neg_hi:[0,1]
	v_pk_fma_f32 v[68:69], v[20:21], v[24:25], v[62:63]
	v_mov_b32_e32 v142, v21
	v_pk_mul_f32 v[62:63], v[142:143], v[76:77] op_sel:[0,1] op_sel_hi:[0,0] neg_hi:[0,1]
	v_pk_fma_f32 v[20:21], v[20:21], v[76:77], v[62:63] op_sel_hi:[0,1,1]
	v_pk_mul_f32 v[62:63], v[26:27], s[48:49] op_sel_hi:[0,1]
	v_pk_fma_f32 v[76:77], v[24:25], s[40:41], v[62:63]
	v_pk_mul_f32 v[62:63], v[76:77], v[72:73] op_sel:[1,1] op_sel_hi:[1,0] neg_hi:[0,1]
	v_pk_add_f32 v[94:95], v[6:7], v[156:157]
	v_pk_fma_f32 v[62:63], v[72:73], v[76:77], v[62:63] op_sel_hi:[1,0,1]
	v_pk_mul_f32 v[72:73], v[26:27], v[68:69] op_sel:[0,1] op_sel_hi:[0,0] neg_lo:[0,1]
	v_pk_fma_f32 v[142:143], v[24:25], v[68:69], v[72:73]
	v_pk_mul_f32 v[72:73], v[68:69], v[22:23] op_sel:[1,1] op_sel_hi:[1,0] neg_hi:[0,1]
	v_pk_add_f32 v[140:141], v[150:151], v[158:159]
	v_pk_fma_f32 v[22:23], v[68:69], v[22:23], v[72:73] op_sel_hi:[0,1,1]
	v_pk_mul_f32 v[68:69], v[26:27], v[76:77] op_sel:[0,1] op_sel_hi:[0,0] neg_lo:[0,1]
	v_pk_fma_f32 v[76:77], v[24:25], v[76:77], v[68:69]
	v_pk_mul_f32 v[68:69], v[134:135], v[76:77] op_sel:[1,1] op_sel_hi:[0,1] neg_hi:[1,0]
	v_pk_add_f32 v[66:67], v[6:7], v[156:157] neg_lo:[0,1] neg_hi:[0,1]
	v_pk_fma_f32 v[72:73], v[134:135], v[76:77], v[68:69] op_sel_hi:[1,0,1]
	v_pk_mul_f32 v[68:69], v[26:27], v[142:143] op_sel:[0,1] op_sel_hi:[0,0] neg_lo:[0,1]
	v_pk_fma_f32 v[134:135], v[24:25], v[142:143], v[68:69]
	v_pk_mul_f32 v[68:69], v[142:143], v[90:91] op_sel:[1,1] op_sel_hi:[1,0] neg_hi:[0,1]
	v_pk_add_f32 v[6:7], v[150:151], v[158:159] neg_lo:[0,1] neg_hi:[0,1]
	v_pk_fma_f32 v[68:69], v[90:91], v[142:143], v[68:69] op_sel_hi:[1,0,1]
	v_pk_mul_f32 v[90:91], v[26:27], v[76:77] op_sel:[0,1] op_sel_hi:[0,0] neg_lo:[0,1]
	v_pk_fma_f32 v[90:91], v[24:25], v[76:77], v[90:91]
	v_pk_mul_f32 v[76:77], v[78:79], v[90:91] op_sel:[1,1] op_sel_hi:[0,1] neg_hi:[1,0]
	v_pk_fma_f32 v[78:79], v[78:79], v[90:91], v[76:77] op_sel_hi:[1,0,1]
	v_pk_mul_f32 v[76:77], v[26:27], v[134:135] op_sel:[0,1] op_sel_hi:[0,0] neg_lo:[0,1]
	v_pk_fma_f32 v[142:143], v[24:25], v[134:135], v[76:77]
	v_pk_mul_f32 v[76:77], v[134:135], v[94:95] op_sel:[1,1] op_sel_hi:[1,0] neg_hi:[0,1]
	v_pk_fma_f32 v[76:77], v[94:95], v[134:135], v[76:77] op_sel_hi:[1,0,1]
	v_pk_mul_f32 v[94:95], v[26:27], v[90:91] op_sel:[0,1] op_sel_hi:[0,0] neg_lo:[0,1]
	v_pk_fma_f32 v[94:95], v[24:25], v[90:91], v[94:95]
	v_pk_mul_f32 v[90:91], v[136:137], v[94:95] op_sel:[1,1] op_sel_hi:[0,1] neg_hi:[1,0]
	v_xor_b32_e32 v134, 0x80000000, v143
	v_pk_fma_f32 v[90:91], v[136:137], v[94:95], v[90:91] op_sel_hi:[1,0,1]
	v_pk_mul_f32 v[136:137], v[86:87], v[142:143] op_sel:[1,1] op_sel_hi:[0,1] neg_hi:[1,0]
	v_mov_b32_e32 v135, v142
	v_pk_fma_f32 v[86:87], v[86:87], v[142:143], v[136:137] op_sel_hi:[1,0,1]
	v_pk_mul_f32 v[136:137], v[26:27], v[94:95] op_sel:[0,1] op_sel_hi:[0,0] neg_lo:[0,1]
	v_pk_mul_f32 v[134:135], v[26:27], v[134:135] op_sel_hi:[0,1]
	v_pk_fma_f32 v[136:137], v[24:25], v[94:95], v[136:137]
	v_pk_fma_f32 v[134:135], v[24:25], v[142:143], v[134:135]
	v_pk_mul_f32 v[94:95], v[92:93], v[136:137] op_sel:[1,1] op_sel_hi:[0,1] neg_hi:[1,0]
	v_pk_fma_f32 v[94:95], v[92:93], v[136:137], v[94:95] op_sel_hi:[1,0,1]
	v_pk_mul_f32 v[92:93], v[26:27], v[134:135] op_sel:[0,1] op_sel_hi:[0,0] neg_lo:[0,1]
	v_pk_fma_f32 v[142:143], v[24:25], v[134:135], v[92:93]
	v_pk_mul_f32 v[92:93], v[138:139], v[134:135] op_sel:[1,1] op_sel_hi:[0,1] neg_hi:[1,0]
	v_pk_fma_f32 v[92:93], v[138:139], v[134:135], v[92:93] op_sel_hi:[1,0,1]
	v_pk_mul_f32 v[134:135], v[26:27], v[136:137] op_sel:[0,1] op_sel_hi:[0,0] neg_lo:[0,1]
	v_pk_fma_f32 v[134:135], v[24:25], v[136:137], v[134:135]
	v_pk_mul_f32 v[138:139], v[132:133], v[142:143] op_sel:[1,1] op_sel_hi:[0,1] neg_hi:[1,0]
	v_pk_mul_f32 v[136:137], v[128:129], v[134:135] op_sel:[1,1] op_sel_hi:[0,1] neg_hi:[1,0]
	v_pk_fma_f32 v[132:133], v[132:133], v[142:143], v[138:139] op_sel_hi:[1,0,1]
	v_pk_fma_f32 v[128:129], v[128:129], v[134:135], v[136:137] op_sel_hi:[1,0,1]
	v_pk_mul_f32 v[138:139], v[26:27], v[134:135] op_sel:[0,1] op_sel_hi:[0,0] neg_lo:[0,1]
	v_pk_mul_f32 v[136:137], v[26:27], v[142:143] op_sel:[0,1] op_sel_hi:[0,0] neg_lo:[0,1]
	v_pk_fma_f32 v[134:135], v[24:25], v[134:135], v[138:139]
	v_pk_fma_f32 v[136:137], v[24:25], v[142:143], v[136:137]
	v_pk_mul_f32 v[138:139], v[130:131], v[134:135] op_sel:[1,1] op_sel_hi:[0,1] neg_hi:[1,0]
	v_pk_fma_f32 v[130:131], v[130:131], v[134:135], v[138:139] op_sel_hi:[1,0,1]
	v_pk_mul_f32 v[138:139], v[26:27], v[136:137] op_sel:[0,1] op_sel_hi:[0,0] neg_lo:[0,1]
	v_pk_mul_f32 v[142:143], v[140:141], v[136:137] op_sel:[1,1] op_sel_hi:[0,1] neg_hi:[1,0]
	v_pk_fma_f32 v[138:139], v[24:25], v[136:137], v[138:139]
	v_pk_fma_f32 v[136:137], v[140:141], v[136:137], v[142:143] op_sel_hi:[1,0,1]
	v_pk_mul_f32 v[140:141], v[26:27], v[134:135] op_sel:[0,1] op_sel_hi:[0,0] neg_lo:[0,1]
	v_pk_fma_f32 v[134:135], v[24:25], v[134:135], v[140:141]
	v_pk_mul_f32 v[140:141], v[84:85], v[134:135] op_sel:[1,1] op_sel_hi:[0,1] neg_hi:[1,0]
	v_pk_fma_f32 v[84:85], v[84:85], v[134:135], v[140:141] op_sel_hi:[1,0,1]
	v_pk_mul_f32 v[140:141], v[26:27], v[138:139] op_sel:[0,1] op_sel_hi:[0,0] neg_lo:[0,1]
	v_pk_mul_f32 v[142:143], v[88:89], v[138:139] op_sel:[1,1] op_sel_hi:[0,1] neg_hi:[1,0]
	v_pk_fma_f32 v[140:141], v[24:25], v[138:139], v[140:141]
	v_pk_fma_f32 v[88:89], v[88:89], v[138:139], v[142:143] op_sel_hi:[1,0,1]
	v_pk_mul_f32 v[138:139], v[26:27], v[134:135] op_sel:[0,1] op_sel_hi:[0,0] neg_lo:[0,1]
	v_pk_fma_f32 v[134:135], v[24:25], v[134:135], v[138:139]
	v_pk_mul_f32 v[138:139], v[80:81], v[134:135] op_sel:[1,1] op_sel_hi:[0,1] neg_hi:[1,0]
	v_pk_fma_f32 v[80:81], v[80:81], v[134:135], v[138:139] op_sel_hi:[1,0,1]
	v_pk_mul_f32 v[138:139], v[26:27], v[140:141] op_sel:[0,1] op_sel_hi:[0,0] neg_lo:[0,1]
	v_pk_mul_f32 v[142:143], v[82:83], v[140:141] op_sel:[1,1] op_sel_hi:[0,1] neg_hi:[1,0]
	v_pk_fma_f32 v[138:139], v[24:25], v[140:141], v[138:139]
	v_pk_fma_f32 v[82:83], v[82:83], v[140:141], v[142:143] op_sel_hi:[1,0,1]
	v_pk_mul_f32 v[140:141], v[26:27], v[134:135] op_sel:[0,1] op_sel_hi:[0,0] neg_lo:[0,1]
	v_pk_fma_f32 v[134:135], v[24:25], v[134:135], v[140:141]
	v_pk_mul_f32 v[140:141], v[70:71], v[134:135] op_sel:[1,1] op_sel_hi:[0,1] neg_hi:[1,0]
	v_pk_fma_f32 v[70:71], v[70:71], v[134:135], v[140:141] op_sel_hi:[1,0,1]
	v_pk_mul_f32 v[140:141], v[26:27], v[138:139] op_sel:[0,1] op_sel_hi:[0,0] neg_lo:[0,1]
	v_pk_mul_f32 v[142:143], v[74:75], v[138:139] op_sel:[1,1] op_sel_hi:[0,1] neg_hi:[1,0]
	v_pk_fma_f32 v[140:141], v[24:25], v[138:139], v[140:141]
	v_pk_fma_f32 v[74:75], v[74:75], v[138:139], v[142:143] op_sel_hi:[1,0,1]
	v_pk_mul_f32 v[138:139], v[26:27], v[134:135] op_sel:[0,1] op_sel_hi:[0,0] neg_lo:[0,1]
	v_pk_fma_f32 v[134:135], v[24:25], v[134:135], v[138:139]
	v_pk_mul_f32 v[138:139], v[64:65], v[134:135] op_sel:[1,1] op_sel_hi:[0,1] neg_hi:[1,0]
	v_pk_fma_f32 v[64:65], v[64:65], v[134:135], v[138:139] op_sel_hi:[1,0,1]
	v_pk_mul_f32 v[138:139], v[26:27], v[140:141] op_sel:[0,1] op_sel_hi:[0,0] neg_lo:[0,1]
	v_pk_mul_f32 v[142:143], v[66:67], v[140:141] op_sel:[1,1] op_sel_hi:[0,1] neg_hi:[1,0]
	v_pk_fma_f32 v[138:139], v[24:25], v[140:141], v[138:139]
	v_pk_fma_f32 v[66:67], v[66:67], v[140:141], v[142:143] op_sel_hi:[1,0,1]
	v_pk_mul_f32 v[140:141], v[26:27], v[134:135] op_sel:[0,1] op_sel_hi:[0,0] neg_lo:[0,1]
	v_pk_fma_f32 v[134:135], v[24:25], v[134:135], v[140:141]
	v_pk_mul_f32 v[140:141], v[16:17], v[134:135] op_sel:[1,1] op_sel_hi:[0,1] neg_hi:[1,0]
	v_pk_fma_f32 v[16:17], v[16:17], v[134:135], v[140:141] op_sel_hi:[1,0,1]
	v_pk_mul_f32 v[140:141], v[26:27], v[138:139] op_sel:[0,1] op_sel_hi:[0,0] neg_lo:[0,1]
	v_pk_mul_f32 v[142:143], v[18:19], v[138:139] op_sel:[1,1] op_sel_hi:[0,1] neg_hi:[1,0]
	v_pk_fma_f32 v[140:141], v[24:25], v[138:139], v[140:141]
	v_pk_fma_f32 v[18:19], v[18:19], v[138:139], v[142:143] op_sel_hi:[1,0,1]
	v_pk_mul_f32 v[138:139], v[26:27], v[134:135] op_sel:[0,1] op_sel_hi:[0,0] neg_lo:[0,1]
	v_pk_fma_f32 v[134:135], v[24:25], v[134:135], v[138:139]
	v_pk_mul_f32 v[138:139], v[12:13], v[134:135] op_sel:[1,1] op_sel_hi:[0,1] neg_hi:[1,0]
	v_pk_fma_f32 v[12:13], v[12:13], v[134:135], v[138:139] op_sel_hi:[1,0,1]
	v_pk_mul_f32 v[138:139], v[26:27], v[140:141] op_sel:[0,1] op_sel_hi:[0,0] neg_lo:[0,1]
	v_pk_mul_f32 v[142:143], v[14:15], v[140:141] op_sel:[1,1] op_sel_hi:[0,1] neg_hi:[1,0]
	v_pk_fma_f32 v[138:139], v[24:25], v[140:141], v[138:139]
	v_pk_fma_f32 v[14:15], v[14:15], v[140:141], v[142:143] op_sel_hi:[1,0,1]
	v_pk_mul_f32 v[140:141], v[26:27], v[134:135] op_sel:[0,1] op_sel_hi:[0,0] neg_lo:[0,1]
	v_pk_fma_f32 v[134:135], v[24:25], v[134:135], v[140:141]
	v_pk_mul_f32 v[140:141], v[8:9], v[134:135] op_sel:[1,1] op_sel_hi:[0,1] neg_hi:[1,0]
	v_pk_fma_f32 v[8:9], v[8:9], v[134:135], v[140:141] op_sel_hi:[1,0,1]
	v_pk_mul_f32 v[140:141], v[26:27], v[138:139] op_sel:[0,1] op_sel_hi:[0,0] neg_lo:[0,1]
	v_pk_mul_f32 v[142:143], v[10:11], v[138:139] op_sel:[1,1] op_sel_hi:[0,1] neg_hi:[1,0]
	v_pk_fma_f32 v[140:141], v[24:25], v[138:139], v[140:141]
	v_pk_fma_f32 v[10:11], v[10:11], v[138:139], v[142:143] op_sel_hi:[1,0,1]
	v_pk_mul_f32 v[138:139], v[26:27], v[134:135] op_sel:[0,1] op_sel_hi:[0,0] neg_lo:[0,1]
	v_pk_fma_f32 v[24:25], v[24:25], v[134:135], v[138:139]
	v_pk_mul_f32 v[134:135], v[4:5], v[24:25] op_sel:[1,1] op_sel_hi:[0,1] neg_hi:[1,0]
	v_pk_fma_f32 v[4:5], v[4:5], v[24:25], v[134:135] op_sel_hi:[1,0,1]
	v_pk_mul_f32 v[24:25], v[6:7], v[140:141] op_sel:[1,1] op_sel_hi:[0,1] neg_hi:[1,0]
	s_nop 0
	v_pk_fma_f32 v[6:7], v[6:7], v[140:141], v[24:25] op_sel_hi:[1,0,1]
	ds_write_b64 v27, v[2:3]
	ds_write_b64 v96, v[84:85]
	ds_write_b64 v97, v[90:91] offset:256
	ds_write_b64 v98, v[16:17] offset:256
	ds_write_b64 v99, v[72:73] offset:512
	ds_write_b64 v100, v[70:71] offset:512
	ds_write_b64 v101, v[128:129] offset:768
	ds_write_b64 v102, v[8:9] offset:768
	ds_write_b64 v103, v[62:63] offset:1024
	ds_write_b64 v104, v[80:81] offset:1024
	ds_write_b64 v105, v[94:95] offset:1280
	ds_write_b64 v106, v[12:13] offset:1280
	ds_write_b64 v107, v[78:79] offset:1536
	ds_write_b64 v108, v[64:65] offset:1536
	ds_write_b64 v109, v[130:131] offset:1792
	ds_write_b64 v110, v[4:5] offset:1792
	ds_write_b64 v111, v[20:21] offset:2048
	ds_write_b64 v112, v[88:89] offset:2048
	ds_write_b64 v113, v[86:87] offset:2304
	ds_write_b64 v114, v[18:19] offset:2304
	ds_write_b64 v115, v[68:69] offset:2560
	ds_write_b64 v116, v[74:75] offset:2560
	ds_write_b64 v117, v[132:133] offset:2816
	ds_write_b64 v118, v[10:11] offset:2816
	ds_write_b64 v119, v[22:23] offset:3072
	ds_write_b64 v120, v[82:83] offset:3072
	ds_write_b64 v121, v[92:93] offset:3328
	ds_write_b64 v122, v[14:15] offset:3328
	ds_write_b64 v123, v[76:77] offset:3584
	ds_write_b64 v124, v[66:67] offset:3584
	ds_write_b64 v125, v[136:137] offset:3840
	ds_write_b64 v126, v[6:7] offset:3840
	v_mov_b32_e32 v2, v146
	s_waitcnt lgkmcnt(0)
	s_barrier
	s_nop 0
	v_lshlrev_b32_e32 v3, 4, v2
	v_lshrrev_b32_e32 v4, 1, v2
	v_bfe_u32 v2, v2, 1, 4
	v_bitop3_b32 v5, v4, v3, 16 bitop3:0x6c
	v_lshl_add_u32 v5, v5, 3, 16
	v_lshlrev_b32_e32 v2, 3, v2
	v_add_u32_e32 v6, v5, v2
	ds_read_b64 v[12:13], v6
	v_bitop3_b32 v6, v4, 1, 15 bitop3:0x6c
	v_lshlrev_b32_e32 v8, 3, v6
	v_add_u32_e32 v6, v5, v8
	ds_read_b64 v[14:15], v6
	v_bitop3_b32 v6, v4, 2, 15 bitop3:0x6c
	v_lshlrev_b32_e32 v9, 3, v6
	v_add_u32_e32 v6, v5, v9
	ds_read_b64 v[16:17], v6
	v_bitop3_b32 v6, v4, 3, 15 bitop3:0x6c
	v_lshlrev_b32_e32 v10, 3, v6
	v_add_u32_e32 v6, v5, v10
	ds_read_b64 v[18:19], v6
	v_bitop3_b32 v6, v4, 4, 15 bitop3:0x6c
	v_lshlrev_b32_e32 v11, 3, v6
	v_add_u32_e32 v6, v5, v11
	ds_read_b64 v[20:21], v6
	v_bitop3_b32 v6, v4, 5, 15 bitop3:0x6c
	v_lshlrev_b32_e32 v82, 3, v6
	v_add_u32_e32 v6, v5, v82
	ds_read_b64 v[22:23], v6
	v_bitop3_b32 v6, v4, 6, 15 bitop3:0x6c
	v_lshlrev_b32_e32 v83, 3, v6
	v_add_u32_e32 v6, v5, v83
	ds_read_b64 v[24:25], v6
	v_bitop3_b32 v6, v4, 7, 15 bitop3:0x6c
	v_lshlrev_b32_e32 v84, 3, v6
	v_add_u32_e32 v6, v5, v84
	ds_read_b64 v[26:27], v6
	v_bitop3_b32 v6, v4, 8, 15 bitop3:0x6c
	v_lshlrev_b32_e32 v85, 3, v6
	v_add_u32_e32 v6, v5, v85
	ds_read_b64 v[62:63], v6
	v_bitop3_b32 v6, v4, 9, 15 bitop3:0x6c
	v_lshlrev_b32_e32 v86, 3, v6
	v_add_u32_e32 v6, v5, v86
	ds_read_b64 v[64:65], v6
	v_bitop3_b32 v6, v4, 10, 15 bitop3:0x6c
	v_lshlrev_b32_e32 v87, 3, v6
	v_add_u32_e32 v6, v5, v87
	ds_read_b64 v[66:67], v6
	v_bitop3_b32 v6, v4, 11, 15 bitop3:0x6c
	v_lshlrev_b32_e32 v88, 3, v6
	v_add_u32_e32 v6, v5, v88
	ds_read_b64 v[68:69], v6
	v_bitop3_b32 v6, v4, 12, 15 bitop3:0x6c
	v_lshlrev_b32_e32 v89, 3, v6
	v_add_u32_e32 v6, v5, v89
	ds_read_b64 v[70:71], v6
	v_bitop3_b32 v6, v4, 13, 15 bitop3:0x6c
	v_lshlrev_b32_e32 v90, 3, v6
	v_add_u32_e32 v6, v5, v90
	ds_read_b64 v[72:73], v6
	v_bitop3_b32 v6, v4, 14, 15 bitop3:0x6c
	v_lshlrev_b32_e32 v91, 3, v6
	v_add_u32_e32 v6, v5, v91
	v_add_u32_e32 v3, 0x2000, v3
	ds_read_b64 v[74:75], v6
	v_bitop3_b32 v6, v4, 15, v4 bitop3:0xc
	v_bitop3_b32 v3, v3, v4, 16 bitop3:0x78
	v_lshlrev_b32_e32 v106, 3, v6
	v_lshl_add_u32 v107, v3, 3, 16
	v_add_u32_e32 v5, v5, v106
	v_add_u32_e32 v2, v107, v2
	ds_read_b64 v[76:77], v5
	ds_read_b64 v[6:7], v2
	v_add_u32_e32 v2, v107, v8
	ds_read_b64 v[78:79], v2
	v_add_u32_e32 v2, v107, v9
	ds_read_b64 v[8:9], v2
	v_add_u32_e32 v2, v107, v10
	ds_read_b64 v[80:81], v2
	v_add_u32_e32 v2, v107, v11
	ds_read_b64 v[10:11], v2
	v_add_u32_e32 v2, v107, v82
	v_add_u32_e32 v82, v107, v84
	v_add_u32_e32 v84, v107, v85
	ds_read_b64 v[4:5], v2
	ds_read_b64 v[92:93], v84
	v_add_u32_e32 v2, v107, v83
	v_add_u32_e32 v84, v107, v86
	ds_read_b64 v[2:3], v2
	ds_read_b64 v[82:83], v82
	ds_read_b64 v[94:95], v84
	v_add_u32_e32 v84, v107, v87
	ds_read_b64 v[96:97], v84
	v_add_u32_e32 v84, v107, v88
	ds_read_b64 v[98:99], v84
	v_add_u32_e32 v84, v107, v89
	ds_read_b64 v[100:101], v84
	v_add_u32_e32 v84, v107, v90
	ds_read_b64 v[102:103], v84
	v_add_u32_e32 v84, v107, v91
	ds_read_b64 v[104:105], v84
	v_add_u32_e32 v84, v107, v106
	ds_read_b64 v[106:107], v84
	s_waitcnt lgkmcnt(14)
	v_pk_add_f32 v[84:85], v[12:13], v[62:63]
	v_pk_add_f32 v[12:13], v[12:13], v[62:63] neg_lo:[0,1] neg_hi:[0,1]
	v_pk_add_f32 v[62:63], v[14:15], v[64:65]
	v_pk_add_f32 v[14:15], v[14:15], v[64:65] neg_lo:[0,1] neg_hi:[0,1]
	v_pk_mul_f32 v[64:65], v[14:15], s[62:63] op_sel:[1,0] op_sel_hi:[0,0] neg_hi:[1,0]
	v_pk_fma_f32 v[14:15], v[14:15], s[60:61], v[64:65] op_sel_hi:[1,0,1]
	v_pk_add_f32 v[64:65], v[16:17], v[66:67]
	v_pk_add_f32 v[16:17], v[16:17], v[66:67] neg_lo:[0,1] neg_hi:[0,1]
	v_pk_mul_f32 v[66:67], v[16:17], s[70:71] op_sel:[1,0] op_sel_hi:[0,0] neg_hi:[1,0]
	v_pk_fma_f32 v[16:17], v[16:17], s[70:71], v[66:67] op_sel_hi:[1,0,1]
	v_pk_add_f32 v[66:67], v[18:19], v[68:69]
	v_pk_add_f32 v[18:19], v[18:19], v[68:69] neg_lo:[0,1] neg_hi:[0,1]
	v_pk_mul_f32 v[68:69], v[18:19], s[60:61] op_sel:[1,0] op_sel_hi:[0,0] neg_hi:[1,0]
	v_pk_fma_f32 v[18:19], v[18:19], s[62:63], v[68:69] op_sel_hi:[1,0,1]
	v_pk_add_f32 v[68:69], v[20:21], v[70:71]
	v_pk_add_f32 v[20:21], v[20:21], v[70:71] neg_lo:[0,1] neg_hi:[0,1]
	v_xor_b32_e32 v71, 0x80000000, v20
	v_mov_b32_e32 v70, v21
	v_pk_add_f32 v[20:21], v[22:23], v[72:73]
	v_pk_add_f32 v[22:23], v[22:23], v[72:73] neg_lo:[0,1] neg_hi:[0,1]
	v_pk_mul_f32 v[72:73], v[22:23], s[62:63] op_sel_hi:[1,0]
	v_xor_b32_e32 v87, 0x80000000, v22
	v_mov_b32_e32 v86, v23
	v_pk_fma_f32 v[22:23], v[86:87], s[60:61], v[72:73] op_sel_hi:[1,0,1] neg_lo:[0,0,1] neg_hi:[0,0,1]
	v_pk_add_f32 v[72:73], v[24:25], v[74:75]
	v_pk_add_f32 v[24:25], v[24:25], v[74:75] neg_lo:[0,1] neg_hi:[0,1]
	v_pk_mul_f32 v[74:75], v[24:25], s[70:71] op_sel_hi:[1,0]
	v_xor_b32_e32 v87, 0x80000000, v24
	v_mov_b32_e32 v86, v25
	v_pk_fma_f32 v[24:25], v[86:87], s[70:71], v[74:75] op_sel_hi:[1,0,1] neg_lo:[0,0,1] neg_hi:[0,0,1]
	v_pk_add_f32 v[74:75], v[26:27], v[76:77]
	v_pk_add_f32 v[26:27], v[26:27], v[76:77] neg_lo:[0,1] neg_hi:[0,1]
	v_pk_mul_f32 v[76:77], v[26:27], s[60:61] op_sel_hi:[1,0]
	v_xor_b32_e32 v87, 0x80000000, v26
	v_mov_b32_e32 v86, v27
	v_pk_fma_f32 v[26:27], v[86:87], s[62:63], v[76:77] op_sel_hi:[1,0,1] neg_lo:[0,0,1] neg_hi:[0,0,1]
	v_pk_add_f32 v[76:77], v[84:85], v[68:69]
	v_pk_add_f32 v[68:69], v[84:85], v[68:69] neg_lo:[0,1] neg_hi:[0,1]
	v_pk_add_f32 v[84:85], v[62:63], v[20:21]
	v_pk_add_f32 v[20:21], v[62:63], v[20:21] neg_lo:[0,1] neg_hi:[0,1]
	v_pk_mul_f32 v[62:63], v[20:21], s[70:71] op_sel:[1,0] op_sel_hi:[0,0] neg_hi:[1,0]
	v_pk_fma_f32 v[20:21], v[20:21], s[70:71], v[62:63] op_sel_hi:[1,0,1]
	v_pk_add_f32 v[62:63], v[64:65], v[72:73]
	v_pk_add_f32 v[64:65], v[64:65], v[72:73] neg_lo:[0,1] neg_hi:[0,1]
	v_xor_b32_e32 v73, 0x80000000, v64
	v_mov_b32_e32 v72, v65
	v_pk_add_f32 v[64:65], v[66:67], v[74:75]
	v_pk_add_f32 v[66:67], v[66:67], v[74:75] neg_lo:[0,1] neg_hi:[0,1]
	v_pk_mul_f32 v[74:75], v[66:67], s[70:71] op_sel_hi:[1,0]
	v_xor_b32_e32 v87, 0x80000000, v66
	v_mov_b32_e32 v86, v67
	v_pk_fma_f32 v[66:67], v[86:87], s[70:71], v[74:75] op_sel_hi:[1,0,1] neg_lo:[0,0,1] neg_hi:[0,0,1]
	v_pk_add_f32 v[74:75], v[12:13], v[70:71]
	v_pk_add_f32 v[12:13], v[12:13], v[70:71] neg_lo:[0,1] neg_hi:[0,1]
	v_pk_add_f32 v[70:71], v[14:15], v[22:23]
	v_pk_add_f32 v[14:15], v[14:15], v[22:23] neg_lo:[0,1] neg_hi:[0,1]
	v_pk_mul_f32 v[22:23], v[14:15], s[70:71] op_sel:[1,0] op_sel_hi:[0,0] neg_hi:[1,0]
	v_pk_fma_f32 v[14:15], v[14:15], s[70:71], v[22:23] op_sel_hi:[1,0,1]
	v_pk_add_f32 v[22:23], v[16:17], v[24:25]
	v_pk_add_f32 v[16:17], v[16:17], v[24:25] neg_lo:[0,1] neg_hi:[0,1]
	v_xor_b32_e32 v25, 0x80000000, v16
	v_mov_b32_e32 v24, v17
	v_pk_add_f32 v[16:17], v[18:19], v[26:27]
	v_pk_add_f32 v[18:19], v[18:19], v[26:27] neg_lo:[0,1] neg_hi:[0,1]
	v_pk_add_f32 v[108:109], v[12:13], v[24:25]
	v_pk_mul_f32 v[26:27], v[18:19], s[70:71] op_sel_hi:[1,0]
	v_pk_fma_f32 v[18:19], v[18:19], s[70:71], v[26:27] op_sel:[1,0,0] op_sel_hi:[0,0,1] neg_lo:[0,0,1] neg_hi:[1,0,1]
	v_pk_add_f32 v[26:27], v[76:77], v[62:63]
	v_pk_add_f32 v[62:63], v[76:77], v[62:63] neg_lo:[0,1] neg_hi:[0,1]
	v_pk_add_f32 v[76:77], v[84:85], v[64:65]
	v_pk_add_f32 v[64:65], v[84:85], v[64:65] neg_lo:[0,1] neg_hi:[0,1]
	v_pk_add_f32 v[110:111], v[12:13], v[24:25] neg_lo:[0,1] neg_hi:[0,1]
	v_xor_b32_e32 v85, 0x80000000, v64
	v_mov_b32_e32 v84, v65
	v_pk_add_f32 v[64:65], v[68:69], v[72:73]
	v_pk_add_f32 v[68:69], v[68:69], v[72:73] neg_lo:[0,1] neg_hi:[0,1]
	v_pk_add_f32 v[72:73], v[20:21], v[66:67]
	v_pk_add_f32 v[20:21], v[20:21], v[66:67] neg_lo:[0,1] neg_hi:[0,1]
	v_pk_add_f32 v[12:13], v[14:15], v[18:19] neg_lo:[0,1] neg_hi:[0,1]
	v_pk_add_f32 v[112:113], v[14:15], v[18:19]
	v_xor_b32_e32 v115, 0x80000000, v12
	v_mov_b32_e32 v114, v13
	v_pk_add_f32 v[12:13], v[26:27], v[76:77]
	v_pk_add_f32 v[14:15], v[26:27], v[76:77] neg_lo:[0,1] neg_hi:[0,1]
	v_pk_add_f32 v[24:25], v[68:69], v[20:21] op_sel:[0,1] op_sel_hi:[1,0] neg_hi:[0,1]
	v_pk_add_f32 v[26:27], v[68:69], v[20:21] op_sel:[0,1] op_sel_hi:[1,0] neg_lo:[0,1]
	s_waitcnt lgkmcnt(6)
	v_pk_add_f32 v[66:67], v[78:79], v[94:95] neg_lo:[0,1] neg_hi:[0,1]
	v_pk_add_f32 v[86:87], v[74:75], v[22:23]
	v_pk_mul_f32 v[76:77], v[66:67], s[62:63] op_sel:[1,0] op_sel_hi:[0,0] neg_hi:[1,0]
	v_pk_add_f32 v[74:75], v[74:75], v[22:23] neg_lo:[0,1] neg_hi:[0,1]
	v_pk_fma_f32 v[66:67], v[66:67], s[60:61], v[76:77] op_sel_hi:[1,0,1]
	s_waitcnt lgkmcnt(5)
	v_pk_add_f32 v[76:77], v[8:9], v[96:97]
	v_pk_add_f32 v[8:9], v[8:9], v[96:97] neg_lo:[0,1] neg_hi:[0,1]
	v_pk_add_f32 v[20:21], v[64:65], v[72:73]
	v_pk_add_f32 v[22:23], v[64:65], v[72:73] neg_lo:[0,1] neg_hi:[0,1]
	v_pk_add_f32 v[64:65], v[78:79], v[94:95]
	v_pk_mul_f32 v[78:79], v[8:9], s[70:71] op_sel:[1,0] op_sel_hi:[0,0] neg_hi:[1,0]
	v_pk_add_f32 v[88:89], v[70:71], v[16:17]
	v_pk_add_f32 v[16:17], v[70:71], v[16:17] neg_lo:[0,1] neg_hi:[0,1]
	v_pk_fma_f32 v[8:9], v[8:9], s[70:71], v[78:79] op_sel_hi:[1,0,1]
	s_waitcnt lgkmcnt(4)
	v_pk_add_f32 v[78:79], v[80:81], v[98:99]
	v_pk_add_f32 v[80:81], v[80:81], v[98:99] neg_lo:[0,1] neg_hi:[0,1]
	v_xor_b32_e32 v91, 0x80000000, v16
	v_mov_b32_e32 v90, v17
	v_pk_add_f32 v[16:17], v[62:63], v[84:85]
	v_pk_add_f32 v[18:19], v[62:63], v[84:85] neg_lo:[0,1] neg_hi:[0,1]
	v_pk_add_f32 v[62:63], v[6:7], v[92:93]
	v_pk_add_f32 v[6:7], v[6:7], v[92:93] neg_lo:[0,1] neg_hi:[0,1]
	v_pk_mul_f32 v[92:93], v[80:81], s[60:61] op_sel:[1,0] op_sel_hi:[0,0] neg_hi:[1,0]
	v_pk_add_f32 v[68:69], v[86:87], v[88:89]
	v_pk_fma_f32 v[80:81], v[80:81], s[62:63], v[92:93] op_sel_hi:[1,0,1]
	s_waitcnt lgkmcnt(3)
	v_pk_add_f32 v[92:93], v[10:11], v[100:101]
	v_pk_add_f32 v[10:11], v[10:11], v[100:101] neg_lo:[0,1] neg_hi:[0,1]
	v_pk_add_f32 v[70:71], v[86:87], v[88:89] neg_lo:[0,1] neg_hi:[0,1]
	v_xor_b32_e32 v95, 0x80000000, v10
	v_mov_b32_e32 v94, v11
	s_waitcnt lgkmcnt(2)
	v_pk_add_f32 v[10:11], v[4:5], v[102:103]
	v_pk_add_f32 v[4:5], v[4:5], v[102:103] neg_lo:[0,1] neg_hi:[0,1]
	v_pk_add_f32 v[84:85], v[108:109], v[112:113]
	v_pk_mul_f32 v[96:97], v[4:5], s[62:63] op_sel_hi:[1,0]
	s_nop 0
	v_pk_fma_f32 v[4:5], v[4:5], s[60:61], v[96:97] op_sel:[1,0,0] op_sel_hi:[0,0,1] neg_lo:[0,0,1] neg_hi:[1,0,1]
	s_waitcnt lgkmcnt(1)
	v_pk_add_f32 v[96:97], v[2:3], v[104:105]
	v_pk_add_f32 v[2:3], v[2:3], v[104:105] neg_lo:[0,1] neg_hi:[0,1]
	v_pk_add_f32 v[86:87], v[108:109], v[112:113] neg_lo:[0,1] neg_hi:[0,1]
	v_pk_mul_f32 v[98:99], v[2:3], s[70:71] op_sel_hi:[1,0]
	s_nop 0
	v_pk_fma_f32 v[2:3], v[2:3], s[70:71], v[98:99] op_sel:[1,0,0] op_sel_hi:[0,0,1] neg_lo:[0,0,1] neg_hi:[1,0,1]
	s_waitcnt lgkmcnt(0)
	v_pk_add_f32 v[98:99], v[82:83], v[106:107]
	v_pk_add_f32 v[82:83], v[82:83], v[106:107] neg_lo:[0,1] neg_hi:[0,1]
	v_pk_add_f32 v[72:73], v[74:75], v[90:91]
	v_pk_mul_f32 v[100:101], v[82:83], s[60:61] op_sel_hi:[1,0]
	v_xor_b32_e32 v103, 0x80000000, v82
	v_mov_b32_e32 v102, v83
	v_pk_fma_f32 v[82:83], v[102:103], s[62:63], v[100:101] op_sel_hi:[1,0,1] neg_lo:[0,0,1] neg_hi:[0,0,1]
	v_pk_add_f32 v[100:101], v[62:63], v[92:93]
	v_pk_add_f32 v[62:63], v[62:63], v[92:93] neg_lo:[0,1] neg_hi:[0,1]
	v_pk_add_f32 v[92:93], v[64:65], v[10:11]
	v_pk_add_f32 v[10:11], v[64:65], v[10:11] neg_lo:[0,1] neg_hi:[0,1]
	v_pk_add_f32 v[74:75], v[74:75], v[90:91] neg_lo:[0,1] neg_hi:[0,1]
	v_pk_mul_f32 v[64:65], v[10:11], s[70:71] op_sel:[1,0] op_sel_hi:[0,0] neg_hi:[1,0]
	v_pk_add_f32 v[88:89], v[110:111], v[114:115]
	v_pk_fma_f32 v[10:11], v[10:11], s[70:71], v[64:65] op_sel_hi:[1,0,1]
	v_pk_add_f32 v[64:65], v[76:77], v[96:97]
	v_pk_add_f32 v[76:77], v[76:77], v[96:97] neg_lo:[0,1] neg_hi:[0,1]
	v_pk_add_f32 v[90:91], v[110:111], v[114:115] neg_lo:[0,1] neg_hi:[0,1]
	v_xor_b32_e32 v97, 0x80000000, v76
	v_mov_b32_e32 v96, v77
	v_pk_add_f32 v[76:77], v[78:79], v[98:99]
	v_pk_add_f32 v[78:79], v[78:79], v[98:99] neg_lo:[0,1] neg_hi:[0,1]
	v_pk_mul_f32 v[98:99], v[78:79], s[70:71] op_sel_hi:[1,0]
	v_xor_b32_e32 v103, 0x80000000, v78
	v_mov_b32_e32 v102, v79
	v_pk_fma_f32 v[78:79], v[102:103], s[70:71], v[98:99] op_sel_hi:[1,0,1] neg_lo:[0,0,1] neg_hi:[0,0,1]
	v_pk_add_f32 v[98:99], v[6:7], v[94:95]
	v_pk_add_f32 v[6:7], v[6:7], v[94:95] neg_lo:[0,1] neg_hi:[0,1]
	v_pk_add_f32 v[94:95], v[66:67], v[4:5]
	v_pk_add_f32 v[4:5], v[66:67], v[4:5] neg_lo:[0,1] neg_hi:[0,1]
	v_pk_mul_f32 v[66:67], v[4:5], s[70:71] op_sel:[1,0] op_sel_hi:[0,0] neg_hi:[1,0]
	v_pk_fma_f32 v[4:5], v[4:5], s[70:71], v[66:67] op_sel_hi:[1,0,1]
	v_pk_add_f32 v[66:67], v[8:9], v[2:3]
	v_pk_add_f32 v[2:3], v[8:9], v[2:3] neg_lo:[0,1] neg_hi:[0,1]
	v_pk_add_f32 v[106:107], v[98:99], v[66:67] neg_lo:[0,1] neg_hi:[0,1]
	v_xor_b32_e32 v9, 0x80000000, v2
	v_mov_b32_e32 v8, v3
	v_pk_add_f32 v[2:3], v[80:81], v[82:83]
	v_pk_add_f32 v[80:81], v[80:81], v[82:83] neg_lo:[0,1] neg_hi:[0,1]
	v_pk_add_f32 v[108:109], v[94:95], v[2:3]
	v_pk_mul_f32 v[82:83], v[80:81], s[70:71] op_sel_hi:[1,0]
	v_pk_fma_f32 v[80:81], v[80:81], s[70:71], v[82:83] op_sel:[1,0,0] op_sel_hi:[0,0,1] neg_lo:[0,0,1] neg_hi:[1,0,1]
	v_pk_add_f32 v[82:83], v[100:101], v[64:65]
	v_pk_add_f32 v[64:65], v[100:101], v[64:65] neg_lo:[0,1] neg_hi:[0,1]
	v_pk_add_f32 v[100:101], v[92:93], v[76:77]
	v_pk_add_f32 v[76:77], v[92:93], v[76:77] neg_lo:[0,1] neg_hi:[0,1]
	v_pk_add_f32 v[102:103], v[10:11], v[78:79]
	v_xor_b32_e32 v93, 0x80000000, v76
	v_mov_b32_e32 v92, v77
	v_pk_add_f32 v[76:77], v[62:63], v[96:97]
	v_pk_add_f32 v[10:11], v[10:11], v[78:79] neg_lo:[0,1] neg_hi:[0,1]
	v_pk_add_f32 v[2:3], v[94:95], v[2:3] neg_lo:[0,1] neg_hi:[0,1]
	v_pk_add_f32 v[62:63], v[62:63], v[96:97] neg_lo:[0,1] neg_hi:[0,1]
	v_xor_b32_e32 v105, 0x80000000, v10
	v_mov_b32_e32 v104, v11
	v_pk_add_f32 v[10:11], v[98:99], v[66:67]
	v_xor_b32_e32 v111, 0x80000000, v2
	v_mov_b32_e32 v110, v3
	v_pk_add_f32 v[112:113], v[6:7], v[8:9]
	v_pk_add_f32 v[114:115], v[6:7], v[8:9] neg_lo:[0,1] neg_hi:[0,1]
	v_pk_add_f32 v[6:7], v[4:5], v[80:81]
	v_pk_add_f32 v[2:3], v[4:5], v[80:81] neg_lo:[0,1] neg_hi:[0,1]
	v_pk_add_f32 v[98:99], v[82:83], v[100:101]
	v_pk_add_f32 v[96:97], v[82:83], v[100:101] neg_lo:[0,1] neg_hi:[0,1]
	v_pk_add_f32 v[82:83], v[76:77], v[102:103]
	v_pk_add_f32 v[80:81], v[76:77], v[102:103] neg_lo:[0,1] neg_hi:[0,1]
	s_waitcnt vmcnt(7)
	v_mov_b64 v[100:101], v[164:165]
	v_mov_b64 v[102:103], v[166:167]
	v_pk_add_f32 v[78:79], v[62:63], v[104:105]
	v_pk_add_f32 v[76:77], v[62:63], v[104:105] neg_lo:[0,1] neg_hi:[0,1]
	v_xor_b32_e32 v5, 0x80000000, v2
	v_mov_b32_e32 v4, v3
	v_pk_add_f32 v[62:63], v[106:107], v[110:111]
	v_pk_add_f32 v[2:3], v[106:107], v[110:111] neg_lo:[0,1] neg_hi:[0,1]
	v_pk_add_f32 v[94:95], v[64:65], v[92:93]
	v_pk_add_f32 v[92:93], v[64:65], v[92:93] neg_lo:[0,1] neg_hi:[0,1]
	v_pk_add_f32 v[66:67], v[10:11], v[108:109]
	v_pk_add_f32 v[64:65], v[10:11], v[108:109] neg_lo:[0,1] neg_hi:[0,1]
	v_pk_add_f32 v[10:11], v[112:113], v[6:7]
	v_pk_add_f32 v[8:9], v[112:113], v[6:7] neg_lo:[0,1] neg_hi:[0,1]
	v_pk_add_f32 v[6:7], v[114:115], v[4:5]
	v_pk_add_f32 v[4:5], v[114:115], v[4:5] neg_lo:[0,1] neg_hi:[0,1]
	v_cvt_f32_f16_e32 v104, v100
	v_cvt_f32_f16_sdwa v100, v100 dst_sel:DWORD dst_unused:UNUSED_PAD src0_sel:WORD_1
	v_mul_f32_e32 v104, 0x38800000, v104
	v_mul_f32_e32 v100, 0x38800000, v100
	s_nop 0
	v_pk_mul_f32 v[106:107], v[12:13], v[100:101] op_sel:[1,0] op_sel_hi:[0,0] neg_lo:[1,0]
	v_cvt_f32_f16_e32 v100, v101
	v_cvt_f32_f16_sdwa v101, v101 dst_sel:DWORD dst_unused:UNUSED_PAD src0_sel:WORD_1
	v_pk_fma_f32 v[12:13], v[12:13], v[104:105], v[106:107] op_sel_hi:[1,0,1]
	v_xor_b32_e32 v106, 0x80000000, v15
	v_mov_b32_e32 v107, v14
	v_mul_f32_e32 v104, 0x38800000, v101
	v_mul_f32_e32 v100, 0x38800000, v100
	v_pk_mul_f32 v[104:105], v[106:107], v[104:105] op_sel_hi:[1,0]
	v_xor_b32_e32 v106, 0x80000000, v21
	v_pk_fma_f32 v[14:15], v[14:15], v[100:101], v[104:105] op_sel_hi:[1,0,1]
	v_cvt_f32_f16_sdwa v101, v102 dst_sel:DWORD dst_unused:UNUSED_PAD src0_sel:WORD_1
	v_cvt_f32_f16_e32 v100, v102
	s_nop 0
	s_nop 0
	v_mul_f32_e32 v102, 0x38800000, v101
	v_mul_f32_e32 v100, 0x38800000, v100
	v_pk_mul_f32 v[104:105], v[16:17], v[102:103] op_sel:[1,0] op_sel_hi:[0,0] neg_lo:[1,0]
	v_mov_b32_e32 v107, v20
	v_pk_fma_f32 v[16:17], v[16:17], v[100:101], v[104:105] op_sel_hi:[1,0,1]
	v_cvt_f32_f16_sdwa v101, v103 dst_sel:DWORD dst_unused:UNUSED_PAD src0_sel:WORD_1
	v_cvt_f32_f16_e32 v100, v103
	v_xor_b32_e32 v104, 0x80000000, v19
	v_mov_b32_e32 v105, v18
	v_mul_f32_e32 v102, 0x38800000, v101
	v_mul_f32_e32 v100, 0x38800000, v100
	v_pk_mul_f32 v[102:103], v[104:105], v[102:103] op_sel_hi:[1,0]
	s_nop 0
	v_pk_fma_f32 v[18:19], v[18:19], v[100:101], v[102:103] op_sel_hi:[1,0,1]
	s_waitcnt vmcnt(6)
	v_mov_b64 v[100:101], v[168:169]
	v_mov_b64 v[102:103], v[170:171]
	v_cvt_f32_f16_e32 v104, v100
	v_cvt_f32_f16_sdwa v100, v100 dst_sel:DWORD dst_unused:UNUSED_PAD src0_sel:WORD_1
	v_mul_f32_e32 v104, 0x38800000, v104
	v_mul_f32_e32 v100, 0x38800000, v100
	v_pk_mul_f32 v[106:107], v[106:107], v[100:101] op_sel_hi:[1,0]
	v_cvt_f32_f16_e32 v100, v101
	v_cvt_f32_f16_sdwa v101, v101 dst_sel:DWORD dst_unused:UNUSED_PAD src0_sel:WORD_1
	v_pk_fma_f32 v[20:21], v[20:21], v[104:105], v[106:107] op_sel_hi:[1,0,1]
	v_xor_b32_e32 v106, 0x80000000, v23
	v_mov_b32_e32 v107, v22
	v_mul_f32_e32 v104, 0x38800000, v101
	v_mul_f32_e32 v100, 0x38800000, v100
	v_pk_mul_f32 v[104:105], v[106:107], v[104:105] op_sel_hi:[1,0]
	v_xor_b32_e32 v106, 0x80000000, v69
	v_pk_fma_f32 v[22:23], v[22:23], v[100:101], v[104:105] op_sel_hi:[1,0,1]
	v_cvt_f32_f16_sdwa v101, v102 dst_sel:DWORD dst_unused:UNUSED_PAD src0_sel:WORD_1
	v_cvt_f32_f16_e32 v100, v102
	s_nop 0
	s_nop 0
	v_mul_f32_e32 v102, 0x38800000, v101
	v_mul_f32_e32 v100, 0x38800000, v100
	v_pk_mul_f32 v[104:105], v[24:25], v[102:103] op_sel:[1,0] op_sel_hi:[0,0] neg_lo:[1,0]
	v_mov_b32_e32 v107, v68
	v_pk_fma_f32 v[24:25], v[24:25], v[100:101], v[104:105] op_sel_hi:[1,0,1]
	v_cvt_f32_f16_sdwa v101, v103 dst_sel:DWORD dst_unused:UNUSED_PAD src0_sel:WORD_1
	v_cvt_f32_f16_e32 v100, v103
	v_xor_b32_e32 v104, 0x80000000, v27
	v_mov_b32_e32 v105, v26
	v_mul_f32_e32 v102, 0x38800000, v101
	v_mul_f32_e32 v100, 0x38800000, v100
	v_pk_mul_f32 v[102:103], v[104:105], v[102:103] op_sel_hi:[1,0]
	s_nop 0
	v_pk_fma_f32 v[26:27], v[26:27], v[100:101], v[102:103] op_sel_hi:[1,0,1]
	s_waitcnt vmcnt(5)
	v_mov_b64 v[100:101], v[172:173]
	v_mov_b64 v[102:103], v[174:175]
	v_cvt_f32_f16_e32 v104, v100
	v_cvt_f32_f16_sdwa v100, v100 dst_sel:DWORD dst_unused:UNUSED_PAD src0_sel:WORD_1
	v_mul_f32_e32 v104, 0x38800000, v104
	v_mul_f32_e32 v100, 0x38800000, v100
	v_pk_mul_f32 v[106:107], v[106:107], v[100:101] op_sel_hi:[1,0]
	v_cvt_f32_f16_e32 v100, v101
	v_cvt_f32_f16_sdwa v101, v101 dst_sel:DWORD dst_unused:UNUSED_PAD src0_sel:WORD_1
	v_pk_fma_f32 v[68:69], v[68:69], v[104:105], v[106:107] op_sel_hi:[1,0,1]
	v_xor_b32_e32 v106, 0x80000000, v71
	v_mov_b32_e32 v107, v70
	v_mul_f32_e32 v104, 0x38800000, v101
	v_mul_f32_e32 v100, 0x38800000, v100
	v_pk_mul_f32 v[104:105], v[106:107], v[104:105] op_sel_hi:[1,0]
	v_xor_b32_e32 v106, 0x80000000, v85
	v_pk_fma_f32 v[70:71], v[70:71], v[100:101], v[104:105] op_sel_hi:[1,0,1]
	v_cvt_f32_f16_sdwa v101, v102 dst_sel:DWORD dst_unused:UNUSED_PAD src0_sel:WORD_1
	v_cvt_f32_f16_e32 v100, v102
	s_nop 0
	s_nop 0
	v_mul_f32_e32 v102, 0x38800000, v101
	v_mul_f32_e32 v100, 0x38800000, v100
	v_pk_mul_f32 v[104:105], v[72:73], v[102:103] op_sel:[1,0] op_sel_hi:[0,0] neg_lo:[1,0]
	v_mov_b32_e32 v107, v84
	v_pk_fma_f32 v[72:73], v[72:73], v[100:101], v[104:105] op_sel_hi:[1,0,1]
	v_cvt_f32_f16_sdwa v101, v103 dst_sel:DWORD dst_unused:UNUSED_PAD src0_sel:WORD_1
	v_cvt_f32_f16_e32 v100, v103
	v_xor_b32_e32 v104, 0x80000000, v75
	v_mov_b32_e32 v105, v74
	v_mul_f32_e32 v102, 0x38800000, v101
	v_mul_f32_e32 v100, 0x38800000, v100
	v_pk_mul_f32 v[102:103], v[104:105], v[102:103] op_sel_hi:[1,0]
	s_nop 0
	v_pk_fma_f32 v[74:75], v[74:75], v[100:101], v[102:103] op_sel_hi:[1,0,1]
	s_waitcnt vmcnt(4)
	v_mov_b64 v[100:101], v[176:177]
	v_mov_b64 v[102:103], v[178:179]
	v_cvt_f32_f16_e32 v104, v100
	v_cvt_f32_f16_sdwa v100, v100 dst_sel:DWORD dst_unused:UNUSED_PAD src0_sel:WORD_1
	v_mul_f32_e32 v104, 0x38800000, v104
	v_mul_f32_e32 v100, 0x38800000, v100
	v_pk_mul_f32 v[106:107], v[106:107], v[100:101] op_sel_hi:[1,0]
	v_cvt_f32_f16_e32 v100, v101
	v_cvt_f32_f16_sdwa v101, v101 dst_sel:DWORD dst_unused:UNUSED_PAD src0_sel:WORD_1
	v_pk_fma_f32 v[84:85], v[84:85], v[104:105], v[106:107] op_sel_hi:[1,0,1]
	v_xor_b32_e32 v106, 0x80000000, v87
	v_mov_b32_e32 v107, v86
	v_mul_f32_e32 v104, 0x38800000, v101
	v_mul_f32_e32 v100, 0x38800000, v100
	v_pk_mul_f32 v[104:105], v[106:107], v[104:105] op_sel_hi:[1,0]
	v_xor_b32_e32 v106, 0x80000000, v99
	v_pk_fma_f32 v[86:87], v[86:87], v[100:101], v[104:105] op_sel_hi:[1,0,1]
	v_cvt_f32_f16_sdwa v101, v102 dst_sel:DWORD dst_unused:UNUSED_PAD src0_sel:WORD_1
	v_cvt_f32_f16_e32 v100, v102
	s_nop 0
	s_nop 0
	v_mul_f32_e32 v102, 0x38800000, v101
	v_mul_f32_e32 v100, 0x38800000, v100
	v_pk_mul_f32 v[104:105], v[88:89], v[102:103] op_sel:[1,0] op_sel_hi:[0,0] neg_lo:[1,0]
	v_mov_b32_e32 v107, v98
	v_pk_fma_f32 v[88:89], v[88:89], v[100:101], v[104:105] op_sel_hi:[1,0,1]
	v_cvt_f32_f16_sdwa v101, v103 dst_sel:DWORD dst_unused:UNUSED_PAD src0_sel:WORD_1
	v_cvt_f32_f16_e32 v100, v103
	v_xor_b32_e32 v104, 0x80000000, v91
	v_mov_b32_e32 v105, v90
	v_mul_f32_e32 v102, 0x38800000, v101
	v_mul_f32_e32 v100, 0x38800000, v100
	v_pk_mul_f32 v[102:103], v[104:105], v[102:103] op_sel_hi:[1,0]
	s_nop 0
	v_pk_fma_f32 v[90:91], v[90:91], v[100:101], v[102:103] op_sel_hi:[1,0,1]
	s_waitcnt vmcnt(3)
	v_mov_b64 v[100:101], v[180:181]
	v_mov_b64 v[102:103], v[182:183]
	v_cvt_f32_f16_e32 v104, v100
	v_cvt_f32_f16_sdwa v100, v100 dst_sel:DWORD dst_unused:UNUSED_PAD src0_sel:WORD_1
	v_mul_f32_e32 v104, 0x38800000, v104
	v_mul_f32_e32 v100, 0x38800000, v100
	v_pk_mul_f32 v[106:107], v[106:107], v[100:101] op_sel_hi:[1,0]
	v_cvt_f32_f16_e32 v100, v101
	v_cvt_f32_f16_sdwa v101, v101 dst_sel:DWORD dst_unused:UNUSED_PAD src0_sel:WORD_1
	v_pk_fma_f32 v[98:99], v[98:99], v[104:105], v[106:107] op_sel_hi:[1,0,1]
	v_xor_b32_e32 v106, 0x80000000, v97
	v_mov_b32_e32 v107, v96
	v_mul_f32_e32 v104, 0x38800000, v101
	v_mul_f32_e32 v100, 0x38800000, v100
	v_pk_mul_f32 v[104:105], v[106:107], v[104:105] op_sel_hi:[1,0]
	v_xor_b32_e32 v106, 0x80000000, v83
	v_pk_fma_f32 v[96:97], v[96:97], v[100:101], v[104:105] op_sel_hi:[1,0,1]
	v_cvt_f32_f16_sdwa v101, v102 dst_sel:DWORD dst_unused:UNUSED_PAD src0_sel:WORD_1
	v_cvt_f32_f16_e32 v100, v102
	s_nop 0
	s_nop 0
	v_mul_f32_e32 v102, 0x38800000, v101
	v_mul_f32_e32 v100, 0x38800000, v100
	v_pk_mul_f32 v[104:105], v[94:95], v[102:103] op_sel:[1,0] op_sel_hi:[0,0] neg_lo:[1,0]
	v_mov_b32_e32 v107, v82
	v_pk_fma_f32 v[94:95], v[94:95], v[100:101], v[104:105] op_sel_hi:[1,0,1]
	v_cvt_f32_f16_sdwa v101, v103 dst_sel:DWORD dst_unused:UNUSED_PAD src0_sel:WORD_1
	v_cvt_f32_f16_e32 v100, v103
	v_xor_b32_e32 v104, 0x80000000, v93
	v_mov_b32_e32 v105, v92
	v_mul_f32_e32 v102, 0x38800000, v101
	v_mul_f32_e32 v100, 0x38800000, v100
	v_pk_mul_f32 v[102:103], v[104:105], v[102:103] op_sel_hi:[1,0]
	s_nop 0
	v_pk_fma_f32 v[92:93], v[92:93], v[100:101], v[102:103] op_sel_hi:[1,0,1]
	s_waitcnt vmcnt(2)
	v_mov_b64 v[100:101], v[184:185]
	v_mov_b64 v[102:103], v[186:187]
	v_cvt_f32_f16_e32 v104, v100
	v_cvt_f32_f16_sdwa v100, v100 dst_sel:DWORD dst_unused:UNUSED_PAD src0_sel:WORD_1
	v_mul_f32_e32 v104, 0x38800000, v104
	v_mul_f32_e32 v100, 0x38800000, v100
	v_pk_mul_f32 v[106:107], v[106:107], v[100:101] op_sel_hi:[1,0]
	v_cvt_f32_f16_e32 v100, v101
	v_cvt_f32_f16_sdwa v101, v101 dst_sel:DWORD dst_unused:UNUSED_PAD src0_sel:WORD_1
	v_pk_fma_f32 v[82:83], v[82:83], v[104:105], v[106:107] op_sel_hi:[1,0,1]
	v_xor_b32_e32 v106, 0x80000000, v81
	v_mov_b32_e32 v107, v80
	v_mul_f32_e32 v104, 0x38800000, v101
	v_mul_f32_e32 v100, 0x38800000, v100
	v_pk_mul_f32 v[104:105], v[106:107], v[104:105] op_sel_hi:[1,0]
	v_xor_b32_e32 v106, 0x80000000, v67
	v_pk_fma_f32 v[80:81], v[80:81], v[100:101], v[104:105] op_sel_hi:[1,0,1]
	v_cvt_f32_f16_sdwa v101, v102 dst_sel:DWORD dst_unused:UNUSED_PAD src0_sel:WORD_1
	v_cvt_f32_f16_e32 v100, v102
	s_nop 0
	s_nop 0
	v_mul_f32_e32 v102, 0x38800000, v101
	v_mul_f32_e32 v100, 0x38800000, v100
	v_pk_mul_f32 v[104:105], v[78:79], v[102:103] op_sel:[1,0] op_sel_hi:[0,0] neg_lo:[1,0]
	v_mov_b32_e32 v107, v66
	v_pk_fma_f32 v[78:79], v[78:79], v[100:101], v[104:105] op_sel_hi:[1,0,1]
	v_cvt_f32_f16_sdwa v101, v103 dst_sel:DWORD dst_unused:UNUSED_PAD src0_sel:WORD_1
	v_cvt_f32_f16_e32 v100, v103
	v_xor_b32_e32 v104, 0x80000000, v77
	v_mov_b32_e32 v105, v76
	v_mul_f32_e32 v102, 0x38800000, v101
	v_mul_f32_e32 v100, 0x38800000, v100
	v_pk_mul_f32 v[102:103], v[104:105], v[102:103] op_sel_hi:[1,0]
	s_nop 0
	v_pk_fma_f32 v[76:77], v[76:77], v[100:101], v[102:103] op_sel_hi:[1,0,1]
	s_waitcnt vmcnt(1)
	v_mov_b64 v[100:101], v[188:189]
	v_mov_b64 v[102:103], v[190:191]
	v_cvt_f32_f16_e32 v104, v100
	v_cvt_f32_f16_sdwa v100, v100 dst_sel:DWORD dst_unused:UNUSED_PAD src0_sel:WORD_1
	v_mul_f32_e32 v104, 0x38800000, v104
	v_mul_f32_e32 v100, 0x38800000, v100
	v_pk_mul_f32 v[106:107], v[106:107], v[100:101] op_sel_hi:[1,0]
	v_cvt_f32_f16_e32 v100, v101
	v_cvt_f32_f16_sdwa v101, v101 dst_sel:DWORD dst_unused:UNUSED_PAD src0_sel:WORD_1
	v_pk_fma_f32 v[66:67], v[66:67], v[104:105], v[106:107] op_sel_hi:[1,0,1]
	v_xor_b32_e32 v106, 0x80000000, v65
	v_mov_b32_e32 v107, v64
	v_mul_f32_e32 v104, 0x38800000, v101
	v_mul_f32_e32 v100, 0x38800000, v100
	v_pk_mul_f32 v[104:105], v[106:107], v[104:105] op_sel_hi:[1,0]
	s_nop 0
	v_pk_fma_f32 v[64:65], v[64:65], v[100:101], v[104:105] op_sel_hi:[1,0,1]
	v_cvt_f32_f16_sdwa v101, v102 dst_sel:DWORD dst_unused:UNUSED_PAD src0_sel:WORD_1
	v_cvt_f32_f16_e32 v100, v102
	s_nop 0
	s_nop 0
	v_mul_f32_e32 v102, 0x38800000, v101
	v_mul_f32_e32 v100, 0x38800000, v100
	v_pk_mul_f32 v[104:105], v[62:63], v[102:103] op_sel:[1,0] op_sel_hi:[0,0] neg_lo:[1,0]
	s_nop 0
	v_pk_fma_f32 v[62:63], v[62:63], v[100:101], v[104:105] op_sel_hi:[1,0,1]
	v_cvt_f32_f16_sdwa v101, v103 dst_sel:DWORD dst_unused:UNUSED_PAD src0_sel:WORD_1
	v_cvt_f32_f16_e32 v100, v103
	v_xor_b32_e32 v104, 0x80000000, v3
	v_mov_b32_e32 v105, v2
	v_mul_f32_e32 v102, 0x38800000, v101
	v_mul_f32_e32 v100, 0x38800000, v100
	v_pk_mul_f32 v[102:103], v[104:105], v[102:103] op_sel_hi:[1,0]
	v_xor_b32_e32 v104, 0x80000000, v11
	v_pk_fma_f32 v[100:101], v[2:3], v[100:101], v[102:103] op_sel_hi:[1,0,1]
	s_waitcnt vmcnt(0)
	v_mov_b64 v[0:1], v[192:193]
	v_mov_b64 v[2:3], v[194:195]
	v_mov_b32_e32 v105, v10
	v_cvt_f32_f16_e32 v102, v0
	v_cvt_f32_f16_sdwa v0, v0 dst_sel:DWORD dst_unused:UNUSED_PAD src0_sel:WORD_1
	v_mul_f32_e32 v102, 0x38800000, v102
	v_mul_f32_e32 v0, 0x38800000, v0
	v_pk_mul_f32 v[104:105], v[104:105], v[0:1] op_sel_hi:[1,0]
	v_cvt_f32_f16_e32 v0, v1
	v_cvt_f32_f16_sdwa v1, v1 dst_sel:DWORD dst_unused:UNUSED_PAD src0_sel:WORD_1
	v_pk_fma_f32 v[10:11], v[10:11], v[102:103], v[104:105] op_sel_hi:[1,0,1]
	v_xor_b32_e32 v104, 0x80000000, v9
	v_mov_b32_e32 v105, v8
	v_mul_f32_e32 v102, 0x38800000, v1
	v_mul_f32_e32 v0, 0x38800000, v0
	v_pk_mul_f32 v[102:103], v[104:105], v[102:103] op_sel_hi:[1,0]
	s_nop 0
	v_pk_fma_f32 v[0:1], v[8:9], v[0:1], v[102:103] op_sel_hi:[1,0,1]
	v_cvt_f32_f16_e32 v8, v2
	v_cvt_f32_f16_sdwa v2, v2 dst_sel:DWORD dst_unused:UNUSED_PAD src0_sel:WORD_1
	s_nop 0
	s_nop 0
	v_mul_f32_e32 v8, 0x38800000, v8
	v_mul_f32_e32 v2, 0x38800000, v2
	s_nop 0
	v_pk_mul_f32 v[102:103], v[6:7], v[2:3] op_sel:[1,0] op_sel_hi:[0,0] neg_lo:[1,0]
	v_cvt_f32_f16_e32 v2, v3
	v_cvt_f32_f16_sdwa v3, v3 dst_sel:DWORD dst_unused:UNUSED_PAD src0_sel:WORD_1
	v_pk_fma_f32 v[6:7], v[6:7], v[8:9], v[102:103] op_sel_hi:[1,0,1]
	v_xor_b32_e32 v102, 0x80000000, v5
	v_mov_b32_e32 v103, v4
	v_mul_f32_e32 v8, 0x38800000, v3
	v_mul_f32_e32 v2, 0x38800000, v2
	v_pk_mul_f32 v[8:9], v[102:103], v[8:9] op_sel_hi:[1,0]
	v_mov_b32_e32 v102, v146
	v_pk_fma_f32 v[2:3], v[4:5], v[2:3], v[8:9] op_sel_hi:[1,0,1]
	v_pk_add_f32 v[4:5], v[12:13], v[14:15]
	v_pk_add_f32 v[8:9], v[12:13], v[14:15] neg_lo:[0,1] neg_hi:[0,1]
	v_pk_add_f32 v[12:13], v[16:17], v[18:19]
	v_pk_add_f32 v[14:15], v[16:17], v[18:19] neg_lo:[0,1] neg_hi:[0,1]
	v_pk_add_f32 v[16:17], v[20:21], v[22:23]
	v_pk_add_f32 v[18:19], v[20:21], v[22:23] neg_lo:[0,1] neg_hi:[0,1]
	v_pk_add_f32 v[20:21], v[24:25], v[26:27]
	v_pk_add_f32 v[22:23], v[24:25], v[26:27] neg_lo:[0,1] neg_hi:[0,1]
	v_pk_add_f32 v[24:25], v[68:69], v[70:71]
	v_pk_add_f32 v[26:27], v[68:69], v[70:71] neg_lo:[0,1] neg_hi:[0,1]
	v_pk_add_f32 v[68:69], v[72:73], v[74:75]
	v_pk_add_f32 v[70:71], v[72:73], v[74:75] neg_lo:[0,1] neg_hi:[0,1]
	v_pk_add_f32 v[72:73], v[84:85], v[86:87]
	v_pk_add_f32 v[74:75], v[84:85], v[86:87] neg_lo:[0,1] neg_hi:[0,1]
	v_pk_add_f32 v[84:85], v[88:89], v[90:91]
	v_pk_add_f32 v[86:87], v[88:89], v[90:91] neg_lo:[0,1] neg_hi:[0,1]
	v_pk_add_f32 v[88:89], v[4:5], v[12:13]
	v_pk_add_f32 v[4:5], v[4:5], v[12:13] neg_lo:[0,1] neg_hi:[0,1]
	v_xor_b32_e32 v12, 0x80000000, v15
	v_mov_b32_e32 v13, v14
	v_pk_add_f32 v[14:15], v[8:9], v[12:13]
	v_pk_add_f32 v[8:9], v[8:9], v[12:13] neg_lo:[0,1] neg_hi:[0,1]
	v_pk_add_f32 v[12:13], v[16:17], v[20:21]
	v_pk_add_f32 v[16:17], v[16:17], v[20:21] neg_lo:[0,1] neg_hi:[0,1]
	v_xor_b32_e32 v20, 0x80000000, v23
	v_mov_b32_e32 v21, v22
	v_pk_add_f32 v[22:23], v[18:19], v[20:21]
	v_pk_add_f32 v[18:19], v[18:19], v[20:21] neg_lo:[0,1] neg_hi:[0,1]
	v_pk_add_f32 v[20:21], v[24:25], v[68:69]
	v_pk_add_f32 v[24:25], v[24:25], v[68:69] neg_lo:[0,1] neg_hi:[0,1]
	v_xor_b32_e32 v68, 0x80000000, v71
	v_mov_b32_e32 v69, v70
	v_pk_add_f32 v[70:71], v[26:27], v[68:69]
	v_pk_add_f32 v[26:27], v[26:27], v[68:69] neg_lo:[0,1] neg_hi:[0,1]
	v_pk_add_f32 v[68:69], v[72:73], v[84:85]
	v_pk_add_f32 v[72:73], v[72:73], v[84:85] neg_lo:[0,1] neg_hi:[0,1]
	v_xor_b32_e32 v84, 0x80000000, v87
	v_mov_b32_e32 v85, v86
	v_pk_add_f32 v[86:87], v[74:75], v[84:85]
	v_pk_add_f32 v[74:75], v[74:75], v[84:85] neg_lo:[0,1] neg_hi:[0,1]
	v_pk_add_f32 v[84:85], v[88:89], v[12:13]
	v_pk_add_f32 v[12:13], v[88:89], v[12:13] neg_lo:[0,1] neg_hi:[0,1]
	v_pk_mul_f32 v[88:89], v[22:23], s[70:71] op_sel:[1,0] op_sel_hi:[0,0] neg_lo:[1,0]
	v_xor_b32_e32 v90, 0x80000000, v19
	v_pk_fma_f32 v[22:23], v[22:23], s[70:71], v[88:89] op_sel_hi:[1,0,1]
	v_mov_b32_e32 v91, v18
	v_pk_add_f32 v[88:89], v[14:15], v[22:23]
	v_pk_add_f32 v[14:15], v[14:15], v[22:23] neg_lo:[0,1] neg_hi:[0,1]
	v_xor_b32_e32 v22, 0x80000000, v17
	v_mov_b32_e32 v23, v16
	v_pk_add_f32 v[16:17], v[4:5], v[22:23]
	v_pk_add_f32 v[4:5], v[4:5], v[22:23] neg_lo:[0,1] neg_hi:[0,1]
	v_pk_mul_f32 v[22:23], v[18:19], s[70:71] op_sel_hi:[1,0]
	s_nop 0
	v_pk_fma_f32 v[18:19], v[90:91], s[70:71], v[22:23] op_sel_hi:[1,0,1] neg_lo:[0,0,1] neg_hi:[0,0,1]
	v_xor_b32_e32 v90, 0x80000000, v75
	v_pk_add_f32 v[22:23], v[8:9], v[18:19]
	v_pk_add_f32 v[8:9], v[8:9], v[18:19] neg_lo:[0,1] neg_hi:[0,1]
	v_pk_add_f32 v[18:19], v[20:21], v[68:69]
	v_pk_add_f32 v[20:21], v[20:21], v[68:69] neg_lo:[0,1] neg_hi:[0,1]
	v_pk_mul_f32 v[68:69], v[86:87], s[70:71] op_sel:[1,0] op_sel_hi:[0,0] neg_lo:[1,0]
	v_mov_b32_e32 v91, v74
	v_pk_fma_f32 v[68:69], v[86:87], s[70:71], v[68:69] op_sel_hi:[1,0,1]
	v_pk_add_f32 v[86:87], v[70:71], v[68:69]
	v_pk_add_f32 v[68:69], v[70:71], v[68:69] neg_lo:[0,1] neg_hi:[0,1]
	v_xor_b32_e32 v70, 0x80000000, v73
	v_mov_b32_e32 v71, v72
	v_pk_add_f32 v[72:73], v[24:25], v[70:71]
	v_pk_add_f32 v[24:25], v[24:25], v[70:71] neg_lo:[0,1] neg_hi:[0,1]
	v_pk_mul_f32 v[70:71], v[74:75], s[70:71] op_sel_hi:[1,0]
	v_pk_fma_f32 v[70:71], v[90:91], s[70:71], v[70:71] op_sel_hi:[1,0,1] neg_lo:[0,0,1] neg_hi:[0,0,1]
	v_xor_b32_e32 v90, 0x80000000, v69
	v_pk_add_f32 v[74:75], v[26:27], v[70:71]
	v_pk_add_f32 v[26:27], v[26:27], v[70:71] neg_lo:[0,1] neg_hi:[0,1]
	v_pk_add_f32 v[70:71], v[84:85], v[18:19]
	v_pk_add_f32 v[18:19], v[84:85], v[18:19] neg_lo:[0,1] neg_hi:[0,1]
	v_pk_mul_f32 v[84:85], v[86:87], s[62:63] op_sel:[1,0] op_sel_hi:[0,0] neg_lo:[1,0]
	v_mov_b32_e32 v91, v68
	v_pk_fma_f32 v[84:85], v[86:87], s[60:61], v[84:85] op_sel_hi:[1,0,1]
	v_pk_add_f32 v[86:87], v[88:89], v[84:85]
	v_pk_add_f32 v[84:85], v[88:89], v[84:85] neg_lo:[0,1] neg_hi:[0,1]
	v_pk_mul_f32 v[88:89], v[72:73], s[70:71] op_sel:[1,0] op_sel_hi:[0,0] neg_lo:[1,0]
	v_pk_fma_f32 v[72:73], v[72:73], s[70:71], v[88:89] op_sel_hi:[1,0,1]
	v_pk_add_f32 v[88:89], v[16:17], v[72:73]
	v_pk_add_f32 v[16:17], v[16:17], v[72:73] neg_lo:[0,1] neg_hi:[0,1]
	v_pk_mul_f32 v[72:73], v[74:75], s[60:61] op_sel:[1,0] op_sel_hi:[0,0] neg_lo:[1,0]
	v_pk_fma_f32 v[72:73], v[74:75], s[62:63], v[72:73] op_sel_hi:[1,0,1]
	v_pk_add_f32 v[74:75], v[22:23], v[72:73]
	v_pk_add_f32 v[22:23], v[22:23], v[72:73] neg_lo:[0,1] neg_hi:[0,1]
	v_xor_b32_e32 v72, 0x80000000, v21
	v_mov_b32_e32 v73, v20
	v_pk_add_f32 v[20:21], v[12:13], v[72:73]
	v_pk_add_f32 v[12:13], v[12:13], v[72:73] neg_lo:[0,1] neg_hi:[0,1]
	v_pk_mul_f32 v[72:73], v[68:69], s[62:63] op_sel_hi:[1,0]
	v_pk_fma_f32 v[68:69], v[90:91], s[60:61], v[72:73] op_sel_hi:[1,0,1] neg_lo:[0,0,1] neg_hi:[0,0,1]
	v_xor_b32_e32 v90, 0x80000000, v25
	v_pk_add_f32 v[72:73], v[14:15], v[68:69]
	v_pk_add_f32 v[14:15], v[14:15], v[68:69] neg_lo:[0,1] neg_hi:[0,1]
	v_pk_mul_f32 v[68:69], v[24:25], s[70:71] op_sel_hi:[1,0]
	v_mov_b32_e32 v91, v24
	v_pk_fma_f32 v[24:25], v[90:91], s[70:71], v[68:69] op_sel_hi:[1,0,1] neg_lo:[0,0,1] neg_hi:[0,0,1]
	v_pk_add_f32 v[68:69], v[4:5], v[24:25]
	v_pk_add_f32 v[4:5], v[4:5], v[24:25] neg_lo:[0,1] neg_hi:[0,1]
	v_pk_mul_f32 v[24:25], v[26:27], s[60:61] op_sel_hi:[1,0]
	v_pk_fma_f32 v[24:25], v[26:27], s[62:63], v[24:25] op_sel:[1,0,0] op_sel_hi:[0,0,1] neg_lo:[1,0,1] neg_hi:[0,0,1]
	v_pk_add_f32 v[90:91], v[98:99], v[96:97] neg_lo:[0,1] neg_hi:[0,1]
	v_pk_add_f32 v[26:27], v[8:9], v[24:25]
	v_pk_add_f32 v[8:9], v[8:9], v[24:25] neg_lo:[0,1] neg_hi:[0,1]
	v_pk_add_f32 v[24:25], v[98:99], v[96:97]
	v_pk_add_f32 v[96:97], v[94:95], v[92:93]
	v_pk_add_f32 v[92:93], v[94:95], v[92:93] neg_lo:[0,1] neg_hi:[0,1]
	v_pk_add_f32 v[94:95], v[82:83], v[80:81]
	v_pk_add_f32 v[80:81], v[82:83], v[80:81] neg_lo:[0,1] neg_hi:[0,1]
	v_pk_add_f32 v[82:83], v[78:79], v[76:77]
	v_pk_add_f32 v[76:77], v[78:79], v[76:77] neg_lo:[0,1] neg_hi:[0,1]
	v_pk_add_f32 v[98:99], v[10:11], v[0:1]
	v_pk_add_f32 v[0:1], v[10:11], v[0:1] neg_lo:[0,1] neg_hi:[0,1]
	v_pk_add_f32 v[10:11], v[6:7], v[2:3]
	v_pk_add_f32 v[2:3], v[6:7], v[2:3] neg_lo:[0,1] neg_hi:[0,1]
	v_pk_add_f32 v[6:7], v[24:25], v[96:97]
	v_pk_add_f32 v[24:25], v[24:25], v[96:97] neg_lo:[0,1] neg_hi:[0,1]
	v_xor_b32_e32 v96, 0x80000000, v93
	v_mov_b32_e32 v97, v92
	v_pk_add_f32 v[78:79], v[66:67], v[64:65]
	v_pk_add_f32 v[64:65], v[66:67], v[64:65] neg_lo:[0,1] neg_hi:[0,1]
	v_pk_add_f32 v[66:67], v[62:63], v[100:101]
	v_pk_add_f32 v[62:63], v[62:63], v[100:101] neg_lo:[0,1] neg_hi:[0,1]
	v_pk_add_f32 v[92:93], v[90:91], v[96:97]
	v_pk_add_f32 v[90:91], v[90:91], v[96:97] neg_lo:[0,1] neg_hi:[0,1]
	v_pk_add_f32 v[96:97], v[94:95], v[82:83]
	v_pk_add_f32 v[82:83], v[94:95], v[82:83] neg_lo:[0,1] neg_hi:[0,1]
	v_xor_b32_e32 v94, 0x80000000, v77
	v_mov_b32_e32 v95, v76
	v_pk_add_f32 v[76:77], v[80:81], v[94:95]
	v_pk_add_f32 v[80:81], v[80:81], v[94:95] neg_lo:[0,1] neg_hi:[0,1]
	v_pk_add_f32 v[94:95], v[78:79], v[66:67]
	v_pk_add_f32 v[66:67], v[78:79], v[66:67] neg_lo:[0,1] neg_hi:[0,1]
	v_xor_b32_e32 v78, 0x80000000, v63
	v_mov_b32_e32 v79, v62
	v_pk_add_f32 v[62:63], v[64:65], v[78:79]
	v_pk_add_f32 v[64:65], v[64:65], v[78:79] neg_lo:[0,1] neg_hi:[0,1]
	v_pk_add_f32 v[78:79], v[98:99], v[10:11]
	v_pk_add_f32 v[10:11], v[98:99], v[10:11] neg_lo:[0,1] neg_hi:[0,1]
	v_xor_b32_e32 v98, 0x80000000, v3
	v_mov_b32_e32 v99, v2
	v_pk_add_f32 v[2:3], v[0:1], v[98:99]
	v_pk_add_f32 v[0:1], v[0:1], v[98:99] neg_lo:[0,1] neg_hi:[0,1]
	v_pk_add_f32 v[98:99], v[6:7], v[96:97]
	v_pk_add_f32 v[6:7], v[6:7], v[96:97] neg_lo:[0,1] neg_hi:[0,1]
	v_pk_mul_f32 v[96:97], v[76:77], s[70:71] op_sel:[1,0] op_sel_hi:[0,0] neg_lo:[1,0]
	v_xor_b32_e32 v100, 0x80000000, v81
	v_pk_fma_f32 v[76:77], v[76:77], s[70:71], v[96:97] op_sel_hi:[1,0,1]
	v_mov_b32_e32 v101, v80
	v_pk_add_f32 v[96:97], v[92:93], v[76:77]
	v_pk_add_f32 v[76:77], v[92:93], v[76:77] neg_lo:[0,1] neg_hi:[0,1]
	v_xor_b32_e32 v92, 0x80000000, v83
	v_mov_b32_e32 v93, v82
	v_pk_add_f32 v[82:83], v[24:25], v[92:93]
	v_pk_add_f32 v[24:25], v[24:25], v[92:93] neg_lo:[0,1] neg_hi:[0,1]
	v_pk_mul_f32 v[92:93], v[80:81], s[70:71] op_sel_hi:[1,0]
	v_pk_fma_f32 v[80:81], v[100:101], s[70:71], v[92:93] op_sel_hi:[1,0,1] neg_lo:[0,0,1] neg_hi:[0,0,1]
	v_xor_b32_e32 v100, 0x80000000, v1
	v_pk_add_f32 v[92:93], v[90:91], v[80:81]
	v_pk_add_f32 v[80:81], v[90:91], v[80:81] neg_lo:[0,1] neg_hi:[0,1]
	v_pk_add_f32 v[90:91], v[94:95], v[78:79]
	v_pk_add_f32 v[78:79], v[94:95], v[78:79] neg_lo:[0,1] neg_hi:[0,1]
	v_pk_mul_f32 v[94:95], v[2:3], s[70:71] op_sel:[1,0] op_sel_hi:[0,0] neg_lo:[1,0]
	v_mov_b32_e32 v101, v0
	v_pk_fma_f32 v[2:3], v[2:3], s[70:71], v[94:95] op_sel_hi:[1,0,1]
	v_pk_add_f32 v[94:95], v[62:63], v[2:3]
	v_pk_add_f32 v[2:3], v[62:63], v[2:3] neg_lo:[0,1] neg_hi:[0,1]
	v_xor_b32_e32 v62, 0x80000000, v11
	v_mov_b32_e32 v63, v10
	v_pk_add_f32 v[10:11], v[66:67], v[62:63]
	v_pk_add_f32 v[62:63], v[66:67], v[62:63] neg_lo:[0,1] neg_hi:[0,1]
	v_pk_mul_f32 v[66:67], v[0:1], s[70:71] op_sel_hi:[1,0]
	v_pk_fma_f32 v[0:1], v[100:101], s[70:71], v[66:67] op_sel_hi:[1,0,1] neg_lo:[0,0,1] neg_hi:[0,0,1]
	v_xor_b32_e32 v100, 0x80000000, v3
	v_pk_add_f32 v[66:67], v[64:65], v[0:1]
	v_pk_add_f32 v[0:1], v[64:65], v[0:1] neg_lo:[0,1] neg_hi:[0,1]
	v_pk_add_f32 v[64:65], v[98:99], v[90:91]
	v_pk_add_f32 v[90:91], v[98:99], v[90:91] neg_lo:[0,1] neg_hi:[0,1]
	v_pk_mul_f32 v[98:99], v[94:95], s[62:63] op_sel:[1,0] op_sel_hi:[0,0] neg_lo:[1,0]
	v_mov_b32_e32 v101, v2
	v_pk_fma_f32 v[94:95], v[94:95], s[60:61], v[98:99] op_sel_hi:[1,0,1]
	v_pk_add_f32 v[98:99], v[96:97], v[94:95]
	v_pk_add_f32 v[94:95], v[96:97], v[94:95] neg_lo:[0,1] neg_hi:[0,1]
	v_pk_mul_f32 v[96:97], v[10:11], s[70:71] op_sel:[1,0] op_sel_hi:[0,0] neg_lo:[1,0]
	v_pk_fma_f32 v[10:11], v[10:11], s[70:71], v[96:97] op_sel_hi:[1,0,1]
	v_pk_add_f32 v[96:97], v[82:83], v[10:11]
	v_pk_add_f32 v[10:11], v[82:83], v[10:11] neg_lo:[0,1] neg_hi:[0,1]
	v_pk_mul_f32 v[82:83], v[66:67], s[60:61] op_sel:[1,0] op_sel_hi:[0,0] neg_lo:[1,0]
	v_pk_fma_f32 v[66:67], v[66:67], s[62:63], v[82:83] op_sel_hi:[1,0,1]
	v_pk_add_f32 v[82:83], v[92:93], v[66:67]
	v_pk_add_f32 v[66:67], v[92:93], v[66:67] neg_lo:[0,1] neg_hi:[0,1]
	v_xor_b32_e32 v92, 0x80000000, v79
	v_mov_b32_e32 v93, v78
	v_pk_add_f32 v[78:79], v[6:7], v[92:93]
	v_pk_add_f32 v[6:7], v[6:7], v[92:93] neg_lo:[0,1] neg_hi:[0,1]
	v_pk_mul_f32 v[92:93], v[2:3], s[62:63] op_sel_hi:[1,0]
	v_pk_fma_f32 v[2:3], v[100:101], s[60:61], v[92:93] op_sel_hi:[1,0,1] neg_lo:[0,0,1] neg_hi:[0,0,1]
	v_xor_b32_e32 v100, 0x80000000, v63
	v_pk_add_f32 v[92:93], v[76:77], v[2:3]
	v_pk_add_f32 v[2:3], v[76:77], v[2:3] neg_lo:[0,1] neg_hi:[0,1]
	v_pk_mul_f32 v[76:77], v[62:63], s[70:71] op_sel_hi:[1,0]
	v_mov_b32_e32 v101, v62
	v_pk_fma_f32 v[62:63], v[100:101], s[70:71], v[76:77] op_sel_hi:[1,0,1] neg_lo:[0,0,1] neg_hi:[0,0,1]
	v_xor_b32_e32 v100, 0x80000000, v1
	v_pk_add_f32 v[76:77], v[24:25], v[62:63]
	v_pk_add_f32 v[24:25], v[24:25], v[62:63] neg_lo:[0,1] neg_hi:[0,1]
	v_pk_mul_f32 v[62:63], v[0:1], s[60:61] op_sel_hi:[1,0]
	v_mov_b32_e32 v101, v0
	v_pk_fma_f32 v[0:1], v[100:101], s[62:63], v[62:63] op_sel_hi:[1,0,1] neg_lo:[0,0,1] neg_hi:[0,0,1]
	v_bfe_u32 v100, v102, 1, 4
	v_pk_add_f32 v[62:63], v[80:81], v[0:1]
	v_pk_add_f32 v[0:1], v[80:81], v[0:1] neg_lo:[0,1] neg_hi:[0,1]
	v_lshlrev_b32_e32 v80, 4, v102
	v_lshrrev_b32_e32 v81, 1, v102
	v_bitop3_b32 v101, v81, v80, 16 bitop3:0x6c
	v_lshl_add_u32 v101, v101, 3, 16
	v_lshlrev_b32_e32 v100, 3, v100
	v_add_u32_e32 v102, v101, v100
	ds_write_b64 v102, v[70:71]
	v_bitop3_b32 v70, v81, 1, 15 bitop3:0x6c
	v_lshlrev_b32_e32 v70, 3, v70
	v_add_u32_e32 v71, v101, v70
	ds_write_b64 v71, v[86:87]
	v_bitop3_b32 v71, v81, 2, 15 bitop3:0x6c
	v_lshlrev_b32_e32 v71, 3, v71
	v_add_u32_e32 v86, v101, v71
	ds_write_b64 v86, v[88:89]
	v_bitop3_b32 v86, v81, 3, 15 bitop3:0x6c
	v_lshlrev_b32_e32 v86, 3, v86
	v_add_u32_e32 v87, v101, v86
	ds_write_b64 v87, v[74:75]
	v_bitop3_b32 v74, v81, 4, 15 bitop3:0x6c
	v_lshlrev_b32_e32 v74, 3, v74
	v_add_u32_e32 v75, v101, v74
	ds_write_b64 v75, v[20:21]
	v_bitop3_b32 v20, v81, 5, 15 bitop3:0x6c
	v_lshlrev_b32_e32 v20, 3, v20
	v_add_u32_e32 v21, v101, v20
	ds_write_b64 v21, v[72:73]
	v_bitop3_b32 v21, v81, 6, 15 bitop3:0x6c
	v_lshlrev_b32_e32 v21, 3, v21
	v_add_u32_e32 v72, v101, v21
	ds_write_b64 v72, v[68:69]
	v_bitop3_b32 v68, v81, 7, 15 bitop3:0x6c
	v_lshlrev_b32_e32 v68, 3, v68
	v_add_u32_e32 v69, v101, v68
	ds_write_b64 v69, v[26:27]
	v_bitop3_b32 v26, v81, 8, 15 bitop3:0x6c
	v_lshlrev_b32_e32 v26, 3, v26
	v_add_u32_e32 v27, v101, v26
	ds_write_b64 v27, v[18:19]
	v_bitop3_b32 v18, v81, 9, 15 bitop3:0x6c
	v_lshlrev_b32_e32 v18, 3, v18
	v_add_u32_e32 v19, v101, v18
	ds_write_b64 v19, v[84:85]
	v_bitop3_b32 v19, v81, 10, 15 bitop3:0x6c
	v_lshlrev_b32_e32 v19, 3, v19
	v_add_u32_e32 v27, v101, v19
	ds_write_b64 v27, v[16:17]
	v_bitop3_b32 v16, v81, 11, 15 bitop3:0x6c
	v_lshlrev_b32_e32 v16, 3, v16
	v_add_u32_e32 v17, v101, v16
	ds_write_b64 v17, v[22:23]
	v_bitop3_b32 v17, v81, 12, 15 bitop3:0x6c
	v_lshlrev_b32_e32 v17, 3, v17
	v_add_u32_e32 v22, v101, v17
	ds_write_b64 v22, v[12:13]
	v_bitop3_b32 v12, v81, 13, 15 bitop3:0x6c
	v_lshlrev_b32_e32 v12, 3, v12
	v_add_u32_e32 v13, v101, v12
	ds_write_b64 v13, v[14:15]
	v_bitop3_b32 v13, v81, 14, 15 bitop3:0x6c
	v_lshlrev_b32_e32 v13, 3, v13
	v_add_u32_e32 v14, v101, v13
	ds_write_b64 v14, v[4:5]
	v_bitop3_b32 v4, v81, 15, v81 bitop3:0xc
	v_lshlrev_b32_e32 v4, 3, v4
	v_add_u32_e32 v5, v101, v4
	ds_write_b64 v5, v[8:9]
	v_add_u32_e32 v5, 0x2000, v80
	v_bitop3_b32 v5, v5, v81, 16 bitop3:0x78
	v_lshl_add_u32 v5, v5, 3, 16
	v_add_u32_e32 v8, v5, v100
	ds_write_b64 v8, v[64:65]
	v_add_u32_e32 v8, v5, v70
	ds_write_b64 v8, v[98:99]
	v_add_u32_e32 v8, v5, v71
	ds_write_b64 v8, v[96:97]
	v_add_u32_e32 v8, v5, v86
	ds_write_b64 v8, v[82:83]
	v_add_u32_e32 v8, v5, v74
	ds_write_b64 v8, v[78:79]
	v_add_u32_e32 v8, v5, v20
	ds_write_b64 v8, v[92:93]
	v_add_u32_e32 v8, v5, v21
	ds_write_b64 v8, v[76:77]
	v_add_u32_e32 v8, v5, v68
	ds_write_b64 v8, v[62:63]
	v_add_u32_e32 v8, v5, v26
	ds_write_b64 v8, v[90:91]
	v_add_u32_e32 v8, v5, v18
	ds_write_b64 v8, v[94:95]
	v_add_u32_e32 v8, v5, v19
	ds_write_b64 v8, v[10:11]
	v_add_u32_e32 v8, v5, v16
	ds_write_b64 v8, v[66:67]
	v_add_u32_e32 v8, v5, v17
	ds_write_b64 v8, v[6:7]
	v_add_u32_e32 v6, v5, v12
	ds_write_b64 v6, v[2:3]
	v_add_u32_e32 v2, v5, v13
	ds_write_b64 v2, v[24:25]
	v_add_u32_e32 v2, v5, v4
	v_mov_b32_e32 v22, v146
	ds_write_b64 v2, v[0:1]
	s_waitcnt lgkmcnt(0)
	s_barrier
	s_nop 0
	v_lshlrev_b32_e32 v0, 5, v22
	v_and_b32_e32 v2, 0xfffffe00, v0
	v_and_or_b32 v0, v22, 16, v2
	v_bitop3_b32 v2, v2, 16, v22 bitop3:0x34
	v_bitop3_b32 v6, v22, 4, 15 bitop3:0x6c
	v_bitop3_b32 v14, v22, 8, 15 bitop3:0x6c
	v_lshl_add_u32 v23, v0, 3, 16
	v_lshl_add_u32 v65, v2, 3, 16
	v_lshlrev_b32_e32 v6, 3, v6
	v_lshlrev_b32_e32 v14, 3, v14
	v_bitop3_b32 v2, v22, 1, 15 bitop3:0x6c
	v_add_u32_e32 v105, v23, v6
	v_add_u32_e32 v106, v65, v6
	v_bitop3_b32 v6, v22, 5, 15 bitop3:0x6c
	v_add_u32_e32 v113, v23, v14
	v_add_u32_e32 v114, v65, v14
	v_bitop3_b32 v14, v22, 9, 15 bitop3:0x6c
	v_lshlrev_b32_e32 v2, 3, v2
	v_lshlrev_b32_e32 v6, 3, v6
	v_lshlrev_b32_e32 v14, 3, v14
	v_add_u32_e32 v99, v23, v2
	v_add_u32_e32 v100, v65, v2
	v_bitop3_b32 v2, v22, 2, 15 bitop3:0x6c
	v_add_u32_e32 v107, v23, v6
	v_add_u32_e32 v108, v65, v6
	v_bitop3_b32 v6, v22, 6, 15 bitop3:0x6c
	v_add_u32_e32 v115, v23, v14
	v_add_u32_e32 v116, v65, v14
	v_bitop3_b32 v14, v22, 10, 15 bitop3:0x6c
	v_bitop3_b32 v26, v22, 12, 15 bitop3:0x6c
	v_lshlrev_b32_e32 v2, 3, v2
	v_lshlrev_b32_e32 v6, 3, v6
	v_lshlrev_b32_e32 v14, 3, v14
	v_lshlrev_b32_e32 v26, 3, v26
	v_and_b32_e32 v64, 15, v22
	v_add_u32_e32 v101, v23, v2
	v_add_u32_e32 v102, v65, v2
	v_bitop3_b32 v2, v22, 3, 15 bitop3:0x6c
	v_add_u32_e32 v109, v23, v6
	v_add_u32_e32 v110, v65, v6
	v_bitop3_b32 v6, v22, 7, 15 bitop3:0x6c
	v_add_u32_e32 v117, v23, v14
	v_add_u32_e32 v118, v65, v14
	v_bitop3_b32 v14, v22, 11, 15 bitop3:0x6c
	v_add_u32_e32 v121, v23, v26
	v_add_u32_e32 v122, v65, v26
	v_bitop3_b32 v26, v22, 13, 15 bitop3:0x6c
	v_bitop3_b32 v66, v22, 14, 15 bitop3:0x6c
	v_bitop3_b32 v22, v22, 15, v22 bitop3:0xc
	v_lshlrev_b32_e32 v3, 3, v64
	v_lshlrev_b32_e32 v2, 3, v2
	v_lshlrev_b32_e32 v6, 3, v6
	v_lshlrev_b32_e32 v14, 3, v14
	v_lshlrev_b32_e32 v26, 3, v26
	v_lshlrev_b32_e32 v66, 3, v66
	v_lshlrev_b32_e32 v22, 3, v22
	v_add_u32_e32 v67, v23, v3
	v_add_u32_e32 v98, v65, v3
	v_add_u32_e32 v103, v23, v2
	v_add_u32_e32 v104, v65, v2
	v_add_u32_e32 v111, v23, v6
	v_add_u32_e32 v112, v65, v6
	v_add_u32_e32 v119, v23, v14
	v_add_u32_e32 v120, v65, v14
	v_add_u32_e32 v123, v23, v26
	v_add_u32_e32 v124, v65, v26
	v_add_u32_e32 v125, v23, v66
	v_add_u32_e32 v126, v65, v66
	v_add_u32_e32 v127, v23, v22
	v_add_u32_e32 v128, v65, v22
	ds_read_b64 v[0:1], v67
	ds_read_b64 v[12:13], v98
	ds_read_b64 v[74:75], v99 offset:256
	ds_read_b64 v[4:5], v100 offset:256
	ds_read_b64 v[76:77], v101 offset:512
	ds_read_b64 v[10:11], v102 offset:512
	ds_read_b64 v[70:71], v103 offset:768
	ds_read_b64 v[2:3], v104 offset:768
	ds_read_b64 v[62:63], v105 offset:1024
	ds_read_b64 v[20:21], v106 offset:1024
	ds_read_b64 v[90:91], v107 offset:1280
	ds_read_b64 v[8:9], v108 offset:1280
	ds_read_b64 v[84:85], v109 offset:1536
	ds_read_b64 v[16:17], v110 offset:1536
	ds_read_b64 v[82:83], v111 offset:1792
	ds_read_b64 v[6:7], v112 offset:1792
	ds_read_b64 v[24:25], v113 offset:2048
	ds_read_b64 v[78:79], v114 offset:2048
	ds_read_b64 v[96:97], v115 offset:2304
	ds_read_b64 v[18:19], v116 offset:2304
	ds_read_b64 v[86:87], v117 offset:2560
	ds_read_b64 v[72:73], v118 offset:2560
	ds_read_b64 v[130:131], v119 offset:2816
	ds_read_b64 v[14:15], v120 offset:2816
	ds_read_b64 v[80:81], v121 offset:3072
	ds_read_b64 v[92:93], v122 offset:3072
	ds_read_b64 v[132:133], v123 offset:3328
	ds_read_b64 v[26:27], v124 offset:3328
	ds_read_b64 v[94:95], v125 offset:3584
	ds_read_b64 v[88:89], v126 offset:3584
	ds_read_b64 v[134:135], v127 offset:3840
	ds_read_b64 v[22:23], v128 offset:3840
	s_waitcnt lgkmcnt(14)
	s_nop 0
	v_cvt_f32_i32_e32 v64, v64
	s_nop 0
	v_mul_f32_e32 v64, 0x3b000000, v64
	v_cos_f32_e32 v68, v64
	v_sin_f32_e32 v69, v64
	v_add_f32_e32 v66, v68, v68
	v_pk_mul_f32 v[64:65], v[68:69], v[68:69]
	v_mul_f32_e32 v66, v69, v66
	v_mov_b32_e32 v140, v69
	v_pk_add_f32 v[64:65], v[64:65], v[64:65] op_sel:[0,1] op_sel_hi:[0,1] neg_lo:[0,1] neg_hi:[0,1]
	v_pk_mul_f32 v[136:137], v[68:69], v[66:67] op_sel:[1,0] op_sel_hi:[0,0] neg_lo:[1,0]
	v_pk_mul_f32 v[138:139], v[24:25], v[140:141] op_sel:[1,0] op_sel_hi:[0,0] neg_lo:[1,0]
	v_pk_fma_f32 v[136:137], v[68:69], v[64:65], v[136:137]
	v_pk_fma_f32 v[24:25], v[24:25], v[68:69], v[138:139] op_sel_hi:[1,0,1]
	v_pk_mul_f32 v[68:69], v[66:67], s[48:49] op_sel_hi:[0,1]
	v_pk_fma_f32 v[138:139], v[64:65], s[40:41], v[68:69]
	v_pk_mul_f32 v[68:69], v[62:63], v[138:139] op_sel:[1,1] op_sel_hi:[0,1] neg_lo:[1,0]
	v_pk_fma_f32 v[68:69], v[62:63], v[138:139], v[68:69] op_sel_hi:[1,0,1]
	v_pk_mul_f32 v[62:63], v[66:67], v[136:137] op_sel:[0,1] op_sel_hi:[0,0] neg_lo:[0,1]
	v_pk_fma_f32 v[140:141], v[64:65], v[136:137], v[62:63]
	s_waitcnt lgkmcnt(7)
	v_pk_mul_f32 v[62:63], v[80:81], v[136:137] op_sel:[1,1] op_sel_hi:[0,1] neg_lo:[1,0]
	s_nop 0
	v_pk_fma_f32 v[62:63], v[80:81], v[136:137], v[62:63] op_sel_hi:[1,0,1]
	v_pk_mul_f32 v[80:81], v[66:67], v[138:139] op_sel:[0,1] op_sel_hi:[0,0] neg_lo:[0,1]
	v_pk_fma_f32 v[136:137], v[64:65], v[138:139], v[80:81]
	v_pk_mul_f32 v[80:81], v[76:77], v[136:137] op_sel:[1,1] op_sel_hi:[0,1] neg_lo:[1,0]
	v_pk_fma_f32 v[80:81], v[76:77], v[136:137], v[80:81] op_sel_hi:[1,0,1]
	v_pk_mul_f32 v[76:77], v[66:67], v[140:141] op_sel:[0,1] op_sel_hi:[0,0] neg_lo:[0,1]
	v_pk_fma_f32 v[138:139], v[64:65], v[140:141], v[76:77]
	v_pk_mul_f32 v[76:77], v[86:87], v[140:141] op_sel:[1,1] op_sel_hi:[0,1] neg_lo:[1,0]
	v_pk_fma_f32 v[76:77], v[86:87], v[140:141], v[76:77] op_sel_hi:[1,0,1]
	v_pk_mul_f32 v[86:87], v[66:67], v[136:137] op_sel:[0,1] op_sel_hi:[0,0] neg_lo:[0,1]
	v_pk_fma_f32 v[136:137], v[64:65], v[136:137], v[86:87]
	v_pk_mul_f32 v[86:87], v[84:85], v[136:137] op_sel:[1,1] op_sel_hi:[0,1] neg_lo:[1,0]
	v_pk_fma_f32 v[86:87], v[84:85], v[136:137], v[86:87] op_sel_hi:[1,0,1]
	v_pk_mul_f32 v[84:85], v[66:67], v[138:139] op_sel:[0,1] op_sel_hi:[0,0] neg_lo:[0,1]
	v_pk_fma_f32 v[140:141], v[64:65], v[138:139], v[84:85]
	s_waitcnt lgkmcnt(3)
	v_pk_mul_f32 v[84:85], v[94:95], v[138:139] op_sel:[1,1] op_sel_hi:[0,1] neg_lo:[1,0]
	s_nop 0
	v_pk_fma_f32 v[84:85], v[94:95], v[138:139], v[84:85] op_sel_hi:[1,0,1]
	v_pk_mul_f32 v[94:95], v[66:67], v[136:137] op_sel:[0,1] op_sel_hi:[0,0] neg_lo:[0,1]
	v_pk_fma_f32 v[136:137], v[64:65], v[136:137], v[94:95]
	v_pk_mul_f32 v[94:95], v[74:75], v[136:137] op_sel:[1,1] op_sel_hi:[0,1] neg_lo:[1,0]
	v_pk_fma_f32 v[94:95], v[74:75], v[136:137], v[94:95] op_sel_hi:[1,0,1]
	v_pk_mul_f32 v[74:75], v[66:67], v[140:141] op_sel:[0,1] op_sel_hi:[0,0] neg_lo:[0,1]
	v_pk_fma_f32 v[138:139], v[64:65], v[140:141], v[74:75]
	v_pk_mul_f32 v[74:75], v[96:97], v[140:141] op_sel:[1,1] op_sel_hi:[0,1] neg_lo:[1,0]
	v_pk_fma_f32 v[74:75], v[96:97], v[140:141], v[74:75] op_sel_hi:[1,0,1]
	v_pk_mul_f32 v[96:97], v[66:67], v[136:137] op_sel:[0,1] op_sel_hi:[0,0] neg_lo:[0,1]
	v_pk_fma_f32 v[136:137], v[64:65], v[136:137], v[96:97]
	v_pk_mul_f32 v[96:97], v[90:91], v[136:137] op_sel:[1,1] op_sel_hi:[0,1] neg_lo:[1,0]
	v_pk_fma_f32 v[96:97], v[90:91], v[136:137], v[96:97] op_sel_hi:[1,0,1]
	v_pk_mul_f32 v[90:91], v[66:67], v[138:139] op_sel:[0,1] op_sel_hi:[0,0] neg_lo:[0,1]
	v_pk_fma_f32 v[140:141], v[64:65], v[138:139], v[90:91]
	v_pk_mul_f32 v[90:91], v[132:133], v[138:139] op_sel:[1,1] op_sel_hi:[0,1] neg_lo:[1,0]
	v_pk_fma_f32 v[90:91], v[132:133], v[138:139], v[90:91] op_sel_hi:[1,0,1]
	v_pk_mul_f32 v[132:133], v[66:67], v[136:137] op_sel:[0,1] op_sel_hi:[0,0] neg_lo:[0,1]
	v_pk_fma_f32 v[132:133], v[64:65], v[136:137], v[132:133]
	v_pk_mul_f32 v[138:139], v[130:131], v[140:141] op_sel:[1,1] op_sel_hi:[0,1] neg_lo:[1,0]
	v_pk_mul_f32 v[136:137], v[70:71], v[132:133] op_sel:[1,1] op_sel_hi:[0,1] neg_lo:[1,0]
	v_pk_fma_f32 v[130:131], v[130:131], v[140:141], v[138:139] op_sel_hi:[1,0,1]
	v_pk_fma_f32 v[70:71], v[70:71], v[132:133], v[136:137] op_sel_hi:[1,0,1]
	v_pk_mul_f32 v[138:139], v[66:67], v[132:133] op_sel:[0,1] op_sel_hi:[0,0] neg_lo:[0,1]
	v_pk_mul_f32 v[136:137], v[66:67], v[140:141] op_sel:[0,1] op_sel_hi:[0,0] neg_lo:[0,1]
	v_pk_fma_f32 v[132:133], v[64:65], v[132:133], v[138:139]
	v_pk_fma_f32 v[136:137], v[64:65], v[140:141], v[136:137]
	v_pk_mul_f32 v[138:139], v[82:83], v[132:133] op_sel:[1,1] op_sel_hi:[0,1] neg_lo:[1,0]
	s_waitcnt lgkmcnt(1)
	v_pk_fma_f32 v[82:83], v[82:83], v[132:133], v[138:139] op_sel_hi:[1,0,1]
	v_pk_mul_f32 v[138:139], v[66:67], v[136:137] op_sel:[0,1] op_sel_hi:[0,0] neg_lo:[0,1]
	v_pk_mul_f32 v[140:141], v[134:135], v[136:137] op_sel:[1,1] op_sel_hi:[0,1] neg_lo:[1,0]
	v_pk_fma_f32 v[138:139], v[64:65], v[136:137], v[138:139]
	v_pk_fma_f32 v[134:135], v[134:135], v[136:137], v[140:141] op_sel_hi:[1,0,1]
	v_pk_mul_f32 v[136:137], v[66:67], v[132:133] op_sel:[0,1] op_sel_hi:[0,0] neg_lo:[0,1]
	v_pk_fma_f32 v[132:133], v[64:65], v[132:133], v[136:137]
	v_pk_mul_f32 v[136:137], v[12:13], v[132:133] op_sel:[1,1] op_sel_hi:[0,1] neg_lo:[1,0]
	v_pk_fma_f32 v[12:13], v[12:13], v[132:133], v[136:137] op_sel_hi:[1,0,1]
	v_pk_mul_f32 v[136:137], v[66:67], v[138:139] op_sel:[0,1] op_sel_hi:[0,0] neg_lo:[0,1]
	v_pk_mul_f32 v[140:141], v[78:79], v[138:139] op_sel:[1,1] op_sel_hi:[0,1] neg_lo:[1,0]
	v_pk_fma_f32 v[136:137], v[64:65], v[138:139], v[136:137]
	v_pk_fma_f32 v[78:79], v[78:79], v[138:139], v[140:141] op_sel_hi:[1,0,1]
	v_pk_mul_f32 v[138:139], v[66:67], v[132:133] op_sel:[0,1] op_sel_hi:[0,0] neg_lo:[0,1]
	v_pk_fma_f32 v[132:133], v[64:65], v[132:133], v[138:139]
	v_pk_mul_f32 v[138:139], v[20:21], v[132:133] op_sel:[1,1] op_sel_hi:[0,1] neg_lo:[1,0]
	v_pk_fma_f32 v[20:21], v[20:21], v[132:133], v[138:139] op_sel_hi:[1,0,1]
	v_pk_mul_f32 v[138:139], v[66:67], v[136:137] op_sel:[0,1] op_sel_hi:[0,0] neg_lo:[0,1]
	v_pk_mul_f32 v[140:141], v[92:93], v[136:137] op_sel:[1,1] op_sel_hi:[0,1] neg_lo:[1,0]
	v_pk_fma_f32 v[138:139], v[64:65], v[136:137], v[138:139]
	v_pk_fma_f32 v[92:93], v[92:93], v[136:137], v[140:141] op_sel_hi:[1,0,1]
	v_pk_mul_f32 v[136:137], v[66:67], v[132:133] op_sel:[0,1] op_sel_hi:[0,0] neg_lo:[0,1]
	v_pk_fma_f32 v[132:133], v[64:65], v[132:133], v[136:137]
	v_pk_mul_f32 v[136:137], v[10:11], v[132:133] op_sel:[1,1] op_sel_hi:[0,1] neg_lo:[1,0]
	v_pk_fma_f32 v[10:11], v[10:11], v[132:133], v[136:137] op_sel_hi:[1,0,1]
	v_pk_mul_f32 v[136:137], v[66:67], v[138:139] op_sel:[0,1] op_sel_hi:[0,0] neg_lo:[0,1]
	v_pk_mul_f32 v[140:141], v[72:73], v[138:139] op_sel:[1,1] op_sel_hi:[0,1] neg_lo:[1,0]
	v_pk_fma_f32 v[136:137], v[64:65], v[138:139], v[136:137]
	v_pk_fma_f32 v[72:73], v[72:73], v[138:139], v[140:141] op_sel_hi:[1,0,1]
	v_pk_mul_f32 v[138:139], v[66:67], v[132:133] op_sel:[0,1] op_sel_hi:[0,0] neg_lo:[0,1]
	v_pk_fma_f32 v[132:133], v[64:65], v[132:133], v[138:139]
	v_pk_mul_f32 v[138:139], v[16:17], v[132:133] op_sel:[1,1] op_sel_hi:[0,1] neg_lo:[1,0]
	v_pk_fma_f32 v[16:17], v[16:17], v[132:133], v[138:139] op_sel_hi:[1,0,1]
	v_pk_mul_f32 v[138:139], v[66:67], v[136:137] op_sel:[0,1] op_sel_hi:[0,0] neg_lo:[0,1]
	v_pk_mul_f32 v[140:141], v[88:89], v[136:137] op_sel:[1,1] op_sel_hi:[0,1] neg_lo:[1,0]
	v_pk_fma_f32 v[138:139], v[64:65], v[136:137], v[138:139]
	v_pk_fma_f32 v[88:89], v[88:89], v[136:137], v[140:141] op_sel_hi:[1,0,1]
	v_pk_mul_f32 v[136:137], v[66:67], v[132:133] op_sel:[0,1] op_sel_hi:[0,0] neg_lo:[0,1]
	v_pk_fma_f32 v[132:133], v[64:65], v[132:133], v[136:137]
	v_pk_mul_f32 v[136:137], v[4:5], v[132:133] op_sel:[1,1] op_sel_hi:[0,1] neg_lo:[1,0]
	v_pk_fma_f32 v[4:5], v[4:5], v[132:133], v[136:137] op_sel_hi:[1,0,1]
	v_pk_mul_f32 v[136:137], v[66:67], v[138:139] op_sel:[0,1] op_sel_hi:[0,0] neg_lo:[0,1]
	v_pk_mul_f32 v[140:141], v[18:19], v[138:139] op_sel:[1,1] op_sel_hi:[0,1] neg_lo:[1,0]
	v_pk_fma_f32 v[136:137], v[64:65], v[138:139], v[136:137]
	v_pk_fma_f32 v[18:19], v[18:19], v[138:139], v[140:141] op_sel_hi:[1,0,1]
	v_pk_mul_f32 v[138:139], v[66:67], v[132:133] op_sel:[0,1] op_sel_hi:[0,0] neg_lo:[0,1]
	v_pk_fma_f32 v[132:133], v[64:65], v[132:133], v[138:139]
	v_pk_mul_f32 v[138:139], v[8:9], v[132:133] op_sel:[1,1] op_sel_hi:[0,1] neg_lo:[1,0]
	v_pk_fma_f32 v[8:9], v[8:9], v[132:133], v[138:139] op_sel_hi:[1,0,1]
	v_pk_mul_f32 v[138:139], v[66:67], v[136:137] op_sel:[0,1] op_sel_hi:[0,0] neg_lo:[0,1]
	v_pk_mul_f32 v[140:141], v[26:27], v[136:137] op_sel:[1,1] op_sel_hi:[0,1] neg_lo:[1,0]
	v_pk_fma_f32 v[138:139], v[64:65], v[136:137], v[138:139]
	v_pk_fma_f32 v[26:27], v[26:27], v[136:137], v[140:141] op_sel_hi:[1,0,1]
	v_pk_mul_f32 v[136:137], v[66:67], v[132:133] op_sel:[0,1] op_sel_hi:[0,0] neg_lo:[0,1]
	v_pk_fma_f32 v[132:133], v[64:65], v[132:133], v[136:137]
	v_pk_mul_f32 v[136:137], v[2:3], v[132:133] op_sel:[1,1] op_sel_hi:[0,1] neg_lo:[1,0]
	v_pk_fma_f32 v[2:3], v[2:3], v[132:133], v[136:137] op_sel_hi:[1,0,1]
	v_pk_mul_f32 v[136:137], v[66:67], v[138:139] op_sel:[0,1] op_sel_hi:[0,0] neg_lo:[0,1]
	v_pk_mul_f32 v[140:141], v[14:15], v[138:139] op_sel:[1,1] op_sel_hi:[0,1] neg_lo:[1,0]
	v_pk_fma_f32 v[136:137], v[64:65], v[138:139], v[136:137]
	v_pk_fma_f32 v[14:15], v[14:15], v[138:139], v[140:141] op_sel_hi:[1,0,1]
	v_pk_mul_f32 v[138:139], v[66:67], v[132:133] op_sel:[0,1] op_sel_hi:[0,0] neg_lo:[0,1]
	v_pk_fma_f32 v[64:65], v[64:65], v[132:133], v[138:139]
	s_nop 0
	v_pk_mul_f32 v[132:133], v[6:7], v[64:65] op_sel:[1,1] op_sel_hi:[0,1] neg_lo:[1,0]
	s_nop 0
	v_pk_fma_f32 v[6:7], v[6:7], v[64:65], v[132:133] op_sel_hi:[1,0,1]
	s_waitcnt lgkmcnt(0)
	v_pk_mul_f32 v[64:65], v[22:23], v[136:137] op_sel:[1,1] op_sel_hi:[0,1] neg_lo:[1,0]
	s_nop 0
	v_pk_fma_f32 v[22:23], v[22:23], v[136:137], v[64:65] op_sel_hi:[1,0,1]
	v_pk_add_f32 v[64:65], v[0:1], v[12:13]
	v_pk_add_f32 v[0:1], v[0:1], v[12:13] neg_lo:[0,1] neg_hi:[0,1]
	v_pk_add_f32 v[12:13], v[94:95], v[4:5]
	v_pk_add_f32 v[4:5], v[94:95], v[4:5] neg_lo:[0,1] neg_hi:[0,1]
	v_pk_add_f32 v[94:95], v[80:81], v[10:11]
	v_pk_add_f32 v[10:11], v[80:81], v[10:11] neg_lo:[0,1] neg_hi:[0,1]
	v_pk_add_f32 v[80:81], v[70:71], v[2:3]
	v_pk_add_f32 v[2:3], v[70:71], v[2:3] neg_lo:[0,1] neg_hi:[0,1]
	v_pk_add_f32 v[132:133], v[64:65], v[12:13]
	v_pk_add_f32 v[12:13], v[64:65], v[12:13] neg_lo:[0,1] neg_hi:[0,1]
	v_xor_b32_e32 v64, 0x80000000, v5
	v_mov_b32_e32 v65, v4
	v_pk_add_f32 v[70:71], v[68:69], v[20:21]
	v_pk_add_f32 v[20:21], v[68:69], v[20:21] neg_lo:[0,1] neg_hi:[0,1]
	v_pk_add_f32 v[68:69], v[96:97], v[8:9]
	v_pk_add_f32 v[8:9], v[96:97], v[8:9] neg_lo:[0,1] neg_hi:[0,1]
	v_pk_add_f32 v[4:5], v[0:1], v[64:65]
	v_pk_add_f32 v[0:1], v[0:1], v[64:65] neg_lo:[0,1] neg_hi:[0,1]
	v_pk_add_f32 v[64:65], v[94:95], v[80:81]
	v_pk_add_f32 v[80:81], v[94:95], v[80:81] neg_lo:[0,1] neg_hi:[0,1]
	v_xor_b32_e32 v94, 0x80000000, v3
	v_mov_b32_e32 v95, v2
	v_pk_add_f32 v[96:97], v[86:87], v[16:17]
	v_pk_add_f32 v[16:17], v[86:87], v[16:17] neg_lo:[0,1] neg_hi:[0,1]
	v_pk_add_f32 v[86:87], v[82:83], v[6:7]
	v_pk_add_f32 v[6:7], v[82:83], v[6:7] neg_lo:[0,1] neg_hi:[0,1]
	v_pk_add_f32 v[2:3], v[10:11], v[94:95]
	v_pk_add_f32 v[10:11], v[10:11], v[94:95] neg_lo:[0,1] neg_hi:[0,1]
	v_pk_add_f32 v[94:95], v[70:71], v[68:69]
	v_pk_add_f32 v[68:69], v[70:71], v[68:69] neg_lo:[0,1] neg_hi:[0,1]
	v_xor_b32_e32 v70, 0x80000000, v9
	v_mov_b32_e32 v71, v8
	v_pk_add_f32 v[82:83], v[24:25], v[78:79]
	v_pk_add_f32 v[24:25], v[24:25], v[78:79] neg_lo:[0,1] neg_hi:[0,1]
	v_pk_add_f32 v[78:79], v[74:75], v[18:19]
	v_pk_add_f32 v[18:19], v[74:75], v[18:19] neg_lo:[0,1] neg_hi:[0,1]
	v_pk_add_f32 v[8:9], v[20:21], v[70:71]
	v_pk_add_f32 v[20:21], v[20:21], v[70:71] neg_lo:[0,1] neg_hi:[0,1]
	v_pk_add_f32 v[70:71], v[96:97], v[86:87]
	v_pk_add_f32 v[86:87], v[96:97], v[86:87] neg_lo:[0,1] neg_hi:[0,1]
	v_xor_b32_e32 v96, 0x80000000, v7
	v_mov_b32_e32 v97, v6
	v_pk_add_f32 v[74:75], v[76:77], v[72:73]
	v_pk_add_f32 v[72:73], v[76:77], v[72:73] neg_lo:[0,1] neg_hi:[0,1]
	v_pk_add_f32 v[76:77], v[130:131], v[14:15]
	v_pk_add_f32 v[14:15], v[130:131], v[14:15] neg_lo:[0,1] neg_hi:[0,1]
	v_pk_add_f32 v[6:7], v[16:17], v[96:97]
	v_pk_add_f32 v[16:17], v[16:17], v[96:97] neg_lo:[0,1] neg_hi:[0,1]
	v_pk_add_f32 v[96:97], v[82:83], v[78:79]
	v_pk_add_f32 v[78:79], v[82:83], v[78:79] neg_lo:[0,1] neg_hi:[0,1]
	v_xor_b32_e32 v82, 0x80000000, v19
	v_mov_b32_e32 v83, v18
	v_pk_add_f32 v[130:131], v[62:63], v[92:93]
	v_pk_add_f32 v[62:63], v[62:63], v[92:93] neg_lo:[0,1] neg_hi:[0,1]
	v_pk_add_f32 v[92:93], v[90:91], v[26:27]
	v_pk_add_f32 v[26:27], v[90:91], v[26:27] neg_lo:[0,1] neg_hi:[0,1]
	v_pk_add_f32 v[18:19], v[24:25], v[82:83]
	v_pk_add_f32 v[24:25], v[24:25], v[82:83] neg_lo:[0,1] neg_hi:[0,1]
	v_pk_add_f32 v[82:83], v[74:75], v[76:77]
	v_pk_add_f32 v[74:75], v[74:75], v[76:77] neg_lo:[0,1] neg_hi:[0,1]
	v_xor_b32_e32 v76, 0x80000000, v15
	v_mov_b32_e32 v77, v14
	v_pk_add_f32 v[90:91], v[84:85], v[88:89]
	v_pk_add_f32 v[84:85], v[84:85], v[88:89] neg_lo:[0,1] neg_hi:[0,1]
	v_pk_add_f32 v[88:89], v[134:135], v[22:23]
	v_pk_add_f32 v[22:23], v[134:135], v[22:23] neg_lo:[0,1] neg_hi:[0,1]
	v_pk_add_f32 v[14:15], v[72:73], v[76:77]
	v_pk_add_f32 v[72:73], v[72:73], v[76:77] neg_lo:[0,1] neg_hi:[0,1]
	v_pk_add_f32 v[76:77], v[130:131], v[92:93]
	v_pk_add_f32 v[92:93], v[130:131], v[92:93] neg_lo:[0,1] neg_hi:[0,1]
	v_xor_b32_e32 v130, 0x80000000, v27
	v_mov_b32_e32 v131, v26
	v_pk_add_f32 v[26:27], v[62:63], v[130:131]
	v_pk_add_f32 v[62:63], v[62:63], v[130:131] neg_lo:[0,1] neg_hi:[0,1]
	v_pk_add_f32 v[130:131], v[90:91], v[88:89]
	v_pk_add_f32 v[88:89], v[90:91], v[88:89] neg_lo:[0,1] neg_hi:[0,1]
	v_xor_b32_e32 v90, 0x80000000, v23
	v_mov_b32_e32 v91, v22
	v_pk_add_f32 v[22:23], v[84:85], v[90:91]
	v_pk_add_f32 v[84:85], v[84:85], v[90:91] neg_lo:[0,1] neg_hi:[0,1]
	v_pk_add_f32 v[90:91], v[132:133], v[64:65]
	v_pk_add_f32 v[64:65], v[132:133], v[64:65] neg_lo:[0,1] neg_hi:[0,1]
	v_pk_mul_f32 v[132:133], v[2:3], s[70:71] op_sel:[1,0] op_sel_hi:[0,0] neg_lo:[1,0]
	v_xor_b32_e32 v134, 0x80000000, v11
	v_pk_fma_f32 v[2:3], v[2:3], s[70:71], v[132:133] op_sel_hi:[1,0,1]
	v_mov_b32_e32 v135, v10
	v_pk_add_f32 v[132:133], v[4:5], v[2:3]
	v_pk_add_f32 v[2:3], v[4:5], v[2:3] neg_lo:[0,1] neg_hi:[0,1]
	v_xor_b32_e32 v4, 0x80000000, v81
	v_mov_b32_e32 v5, v80
	v_pk_add_f32 v[80:81], v[12:13], v[4:5]
	v_pk_add_f32 v[4:5], v[12:13], v[4:5] neg_lo:[0,1] neg_hi:[0,1]
	v_pk_mul_f32 v[12:13], v[10:11], s[70:71] op_sel_hi:[1,0]
	v_pk_fma_f32 v[10:11], v[134:135], s[70:71], v[12:13] op_sel_hi:[1,0,1] neg_lo:[0,0,1] neg_hi:[0,0,1]
	v_xor_b32_e32 v134, 0x80000000, v17
	v_pk_add_f32 v[12:13], v[0:1], v[10:11]
	v_pk_add_f32 v[0:1], v[0:1], v[10:11] neg_lo:[0,1] neg_hi:[0,1]
	v_pk_add_f32 v[10:11], v[94:95], v[70:71]
	v_pk_add_f32 v[70:71], v[94:95], v[70:71] neg_lo:[0,1] neg_hi:[0,1]
	v_pk_mul_f32 v[94:95], v[6:7], s[70:71] op_sel:[1,0] op_sel_hi:[0,0] neg_lo:[1,0]
	v_mov_b32_e32 v135, v16
	v_pk_fma_f32 v[6:7], v[6:7], s[70:71], v[94:95] op_sel_hi:[1,0,1]
	v_pk_add_f32 v[94:95], v[8:9], v[6:7]
	v_pk_add_f32 v[6:7], v[8:9], v[6:7] neg_lo:[0,1] neg_hi:[0,1]
	v_xor_b32_e32 v8, 0x80000000, v87
	v_mov_b32_e32 v9, v86
	v_pk_add_f32 v[86:87], v[68:69], v[8:9]
	v_pk_add_f32 v[8:9], v[68:69], v[8:9] neg_lo:[0,1] neg_hi:[0,1]
	v_pk_mul_f32 v[68:69], v[16:17], s[70:71] op_sel_hi:[1,0]
	v_pk_fma_f32 v[16:17], v[134:135], s[70:71], v[68:69] op_sel_hi:[1,0,1] neg_lo:[0,0,1] neg_hi:[0,0,1]
	v_xor_b32_e32 v134, 0x80000000, v73
	v_pk_add_f32 v[68:69], v[20:21], v[16:17]
	v_pk_add_f32 v[16:17], v[20:21], v[16:17] neg_lo:[0,1] neg_hi:[0,1]
	v_pk_add_f32 v[20:21], v[96:97], v[82:83]
	v_pk_add_f32 v[82:83], v[96:97], v[82:83] neg_lo:[0,1] neg_hi:[0,1]
	v_pk_mul_f32 v[96:97], v[14:15], s[70:71] op_sel:[1,0] op_sel_hi:[0,0] neg_lo:[1,0]
	v_mov_b32_e32 v135, v72
	v_pk_fma_f32 v[14:15], v[14:15], s[70:71], v[96:97] op_sel_hi:[1,0,1]
	v_pk_add_f32 v[96:97], v[18:19], v[14:15]
	v_pk_add_f32 v[14:15], v[18:19], v[14:15] neg_lo:[0,1] neg_hi:[0,1]
	v_xor_b32_e32 v18, 0x80000000, v75
	v_mov_b32_e32 v19, v74
	v_pk_add_f32 v[74:75], v[78:79], v[18:19]
	v_pk_add_f32 v[18:19], v[78:79], v[18:19] neg_lo:[0,1] neg_hi:[0,1]
	v_pk_mul_f32 v[78:79], v[72:73], s[70:71] op_sel_hi:[1,0]
	v_pk_fma_f32 v[72:73], v[134:135], s[70:71], v[78:79] op_sel_hi:[1,0,1] neg_lo:[0,0,1] neg_hi:[0,0,1]
	v_xor_b32_e32 v134, 0x80000000, v85
	v_pk_add_f32 v[78:79], v[24:25], v[72:73]
	v_pk_add_f32 v[24:25], v[24:25], v[72:73] neg_lo:[0,1] neg_hi:[0,1]
	v_pk_add_f32 v[72:73], v[76:77], v[130:131]
	v_pk_add_f32 v[76:77], v[76:77], v[130:131] neg_lo:[0,1] neg_hi:[0,1]
	v_pk_mul_f32 v[130:131], v[22:23], s[70:71] op_sel:[1,0] op_sel_hi:[0,0] neg_lo:[1,0]
	v_mov_b32_e32 v135, v84
	v_pk_fma_f32 v[22:23], v[22:23], s[70:71], v[130:131] op_sel_hi:[1,0,1]
	v_pk_add_f32 v[130:131], v[26:27], v[22:23]
	v_pk_add_f32 v[22:23], v[26:27], v[22:23] neg_lo:[0,1] neg_hi:[0,1]
	v_xor_b32_e32 v26, 0x80000000, v89
	v_mov_b32_e32 v27, v88
	v_pk_add_f32 v[88:89], v[92:93], v[26:27]
	v_pk_add_f32 v[26:27], v[92:93], v[26:27] neg_lo:[0,1] neg_hi:[0,1]
	v_pk_mul_f32 v[92:93], v[84:85], s[70:71] op_sel_hi:[1,0]
	v_pk_fma_f32 v[84:85], v[134:135], s[70:71], v[92:93] op_sel_hi:[1,0,1] neg_lo:[0,0,1] neg_hi:[0,0,1]
	v_xor_b32_e32 v134, 0x80000000, v7
	v_pk_add_f32 v[92:93], v[62:63], v[84:85]
	v_pk_add_f32 v[62:63], v[62:63], v[84:85] neg_lo:[0,1] neg_hi:[0,1]
	v_pk_add_f32 v[84:85], v[90:91], v[10:11]
	v_pk_add_f32 v[10:11], v[90:91], v[10:11] neg_lo:[0,1] neg_hi:[0,1]
	v_pk_mul_f32 v[90:91], v[94:95], s[62:63] op_sel:[1,0] op_sel_hi:[0,0] neg_lo:[1,0]
	v_mov_b32_e32 v135, v6
	v_pk_fma_f32 v[90:91], v[94:95], s[60:61], v[90:91] op_sel_hi:[1,0,1]
	v_pk_add_f32 v[94:95], v[132:133], v[90:91]
	v_pk_add_f32 v[90:91], v[132:133], v[90:91] neg_lo:[0,1] neg_hi:[0,1]
	v_pk_mul_f32 v[132:133], v[86:87], s[70:71] op_sel:[1,0] op_sel_hi:[0,0] neg_lo:[1,0]
	v_pk_fma_f32 v[86:87], v[86:87], s[70:71], v[132:133] op_sel_hi:[1,0,1]
	v_pk_add_f32 v[132:133], v[80:81], v[86:87]
	v_pk_add_f32 v[80:81], v[80:81], v[86:87] neg_lo:[0,1] neg_hi:[0,1]
	v_pk_mul_f32 v[86:87], v[68:69], s[60:61] op_sel:[1,0] op_sel_hi:[0,0] neg_lo:[1,0]
	v_pk_fma_f32 v[68:69], v[68:69], s[62:63], v[86:87] op_sel_hi:[1,0,1]
	v_pk_add_f32 v[86:87], v[12:13], v[68:69]
	v_pk_add_f32 v[12:13], v[12:13], v[68:69] neg_lo:[0,1] neg_hi:[0,1]
	v_xor_b32_e32 v68, 0x80000000, v71
	v_mov_b32_e32 v69, v70
	v_pk_add_f32 v[70:71], v[64:65], v[68:69]
	v_pk_add_f32 v[64:65], v[64:65], v[68:69] neg_lo:[0,1] neg_hi:[0,1]
	v_pk_mul_f32 v[68:69], v[6:7], s[62:63] op_sel_hi:[1,0]
	v_pk_fma_f32 v[6:7], v[134:135], s[60:61], v[68:69] op_sel_hi:[1,0,1] neg_lo:[0,0,1] neg_hi:[0,0,1]
	v_xor_b32_e32 v134, 0x80000000, v9
	v_pk_add_f32 v[68:69], v[2:3], v[6:7]
	v_pk_add_f32 v[2:3], v[2:3], v[6:7] neg_lo:[0,1] neg_hi:[0,1]
	v_pk_mul_f32 v[6:7], v[8:9], s[70:71] op_sel_hi:[1,0]
	v_mov_b32_e32 v135, v8
	v_pk_fma_f32 v[6:7], v[134:135], s[70:71], v[6:7] op_sel_hi:[1,0,1] neg_lo:[0,0,1] neg_hi:[0,0,1]
	v_xor_b32_e32 v134, 0x80000000, v17
	v_pk_add_f32 v[8:9], v[4:5], v[6:7]
	v_pk_add_f32 v[4:5], v[4:5], v[6:7] neg_lo:[0,1] neg_hi:[0,1]
	v_pk_mul_f32 v[6:7], v[16:17], s[60:61] op_sel_hi:[1,0]
	v_mov_b32_e32 v135, v16
	v_pk_fma_f32 v[6:7], v[134:135], s[62:63], v[6:7] op_sel_hi:[1,0,1] neg_lo:[0,0,1] neg_hi:[0,0,1]
	v_xor_b32_e32 v134, 0x80000000, v23
	v_pk_add_f32 v[16:17], v[0:1], v[6:7]
	v_pk_add_f32 v[0:1], v[0:1], v[6:7] neg_lo:[0,1] neg_hi:[0,1]
	v_pk_add_f32 v[6:7], v[20:21], v[72:73]
	v_pk_add_f32 v[20:21], v[20:21], v[72:73] neg_lo:[0,1] neg_hi:[0,1]
	v_pk_mul_f32 v[72:73], v[130:131], s[62:63] op_sel:[1,0] op_sel_hi:[0,0] neg_lo:[1,0]
	v_mov_b32_e32 v135, v22
	v_pk_fma_f32 v[72:73], v[130:131], s[60:61], v[72:73] op_sel_hi:[1,0,1]
	v_pk_add_f32 v[130:131], v[96:97], v[72:73]
	v_pk_add_f32 v[72:73], v[96:97], v[72:73] neg_lo:[0,1] neg_hi:[0,1]
	v_pk_mul_f32 v[96:97], v[88:89], s[70:71] op_sel:[1,0] op_sel_hi:[0,0] neg_lo:[1,0]
	v_pk_fma_f32 v[88:89], v[88:89], s[70:71], v[96:97] op_sel_hi:[1,0,1]
	v_pk_add_f32 v[96:97], v[74:75], v[88:89]
	v_pk_add_f32 v[74:75], v[74:75], v[88:89] neg_lo:[0,1] neg_hi:[0,1]
	v_pk_mul_f32 v[88:89], v[92:93], s[60:61] op_sel:[1,0] op_sel_hi:[0,0] neg_lo:[1,0]
	v_pk_fma_f32 v[88:89], v[92:93], s[62:63], v[88:89] op_sel_hi:[1,0,1]
	v_pk_add_f32 v[92:93], v[78:79], v[88:89]
	v_pk_add_f32 v[78:79], v[78:79], v[88:89] neg_lo:[0,1] neg_hi:[0,1]
	v_xor_b32_e32 v88, 0x80000000, v77
	v_mov_b32_e32 v89, v76
	v_pk_add_f32 v[76:77], v[82:83], v[88:89]
	v_pk_add_f32 v[82:83], v[82:83], v[88:89] neg_lo:[0,1] neg_hi:[0,1]
	v_pk_mul_f32 v[88:89], v[22:23], s[62:63] op_sel_hi:[1,0]
	v_pk_fma_f32 v[22:23], v[134:135], s[60:61], v[88:89] op_sel_hi:[1,0,1] neg_lo:[0,0,1] neg_hi:[0,0,1]
	v_xor_b32_e32 v134, 0x80000000, v27
	v_pk_add_f32 v[88:89], v[14:15], v[22:23]
	v_pk_add_f32 v[14:15], v[14:15], v[22:23] neg_lo:[0,1] neg_hi:[0,1]
	v_pk_mul_f32 v[22:23], v[26:27], s[70:71] op_sel_hi:[1,0]
	v_mov_b32_e32 v135, v26
	v_pk_fma_f32 v[22:23], v[134:135], s[70:71], v[22:23] op_sel_hi:[1,0,1] neg_lo:[0,0,1] neg_hi:[0,0,1]
	v_xor_b32_e32 v134, 0x80000000, v63
	v_pk_add_f32 v[26:27], v[18:19], v[22:23]
	v_pk_add_f32 v[18:19], v[18:19], v[22:23] neg_lo:[0,1] neg_hi:[0,1]
	v_pk_mul_f32 v[22:23], v[62:63], s[60:61] op_sel_hi:[1,0]
	v_mov_b32_e32 v135, v62
	v_pk_fma_f32 v[22:23], v[134:135], s[62:63], v[22:23] op_sel_hi:[1,0,1] neg_lo:[0,0,1] neg_hi:[0,0,1]
	v_xor_b32_e32 v134, 0x80000000, v73
	v_pk_add_f32 v[62:63], v[24:25], v[22:23]
	v_pk_add_f32 v[22:23], v[24:25], v[22:23] neg_lo:[0,1] neg_hi:[0,1]
	v_pk_add_f32 v[24:25], v[84:85], v[6:7]
	v_pk_add_f32 v[6:7], v[84:85], v[6:7] neg_lo:[0,1] neg_hi:[0,1]
	v_pk_mul_f32 v[84:85], v[130:131], s[58:59] op_sel:[1,0] op_sel_hi:[0,0] neg_lo:[1,0]
	v_mov_b32_e32 v135, v72
	v_pk_fma_f32 v[84:85], v[130:131], s[46:47], v[84:85] op_sel_hi:[1,0,1]
	v_pk_add_f32 v[130:131], v[94:95], v[84:85]
	v_pk_add_f32 v[84:85], v[94:95], v[84:85] neg_lo:[0,1] neg_hi:[0,1]
	v_pk_mul_f32 v[94:95], v[96:97], s[62:63] op_sel:[1,0] op_sel_hi:[0,0] neg_lo:[1,0]
	v_pk_fma_f32 v[94:95], v[96:97], s[60:61], v[94:95] op_sel_hi:[1,0,1]
	v_pk_add_f32 v[96:97], v[132:133], v[94:95]
	v_pk_add_f32 v[94:95], v[132:133], v[94:95] neg_lo:[0,1] neg_hi:[0,1]
	v_pk_mul_f32 v[132:133], v[92:93], s[66:67] op_sel:[1,0] op_sel_hi:[0,0] neg_lo:[1,0]
	v_pk_fma_f32 v[92:93], v[92:93], s[64:65], v[132:133] op_sel_hi:[1,0,1]
	v_pk_add_f32 v[132:133], v[86:87], v[92:93]
	v_pk_add_f32 v[86:87], v[86:87], v[92:93] neg_lo:[0,1] neg_hi:[0,1]
	v_pk_mul_f32 v[92:93], v[76:77], s[70:71] op_sel:[1,0] op_sel_hi:[0,0] neg_lo:[1,0]
	v_pk_fma_f32 v[76:77], v[76:77], s[70:71], v[92:93] op_sel_hi:[1,0,1]
	v_pk_add_f32 v[92:93], v[70:71], v[76:77]
	v_pk_add_f32 v[70:71], v[70:71], v[76:77] neg_lo:[0,1] neg_hi:[0,1]
	v_pk_mul_f32 v[76:77], v[88:89], s[64:65] op_sel:[1,0] op_sel_hi:[0,0] neg_lo:[1,0]
	v_pk_fma_f32 v[76:77], v[88:89], s[66:67], v[76:77] op_sel_hi:[1,0,1]
	v_pk_add_f32 v[88:89], v[68:69], v[76:77]
	v_pk_add_f32 v[68:69], v[68:69], v[76:77] neg_lo:[0,1] neg_hi:[0,1]
	v_pk_mul_f32 v[76:77], v[26:27], s[60:61] op_sel:[1,0] op_sel_hi:[0,0] neg_lo:[1,0]
	v_pk_fma_f32 v[26:27], v[26:27], s[62:63], v[76:77] op_sel_hi:[1,0,1]
	v_pk_add_f32 v[76:77], v[8:9], v[26:27]
	v_pk_add_f32 v[8:9], v[8:9], v[26:27] neg_lo:[0,1] neg_hi:[0,1]
	v_pk_mul_f32 v[26:27], v[62:63], s[46:47] op_sel:[1,0] op_sel_hi:[0,0] neg_lo:[1,0]
	v_pk_fma_f32 v[26:27], v[62:63], s[58:59], v[26:27] op_sel_hi:[1,0,1]
	v_pk_add_f32 v[62:63], v[16:17], v[26:27]
	v_pk_add_f32 v[16:17], v[16:17], v[26:27] neg_lo:[0,1] neg_hi:[0,1]
	v_xor_b32_e32 v26, 0x80000000, v21
	v_mov_b32_e32 v27, v20
	v_pk_add_f32 v[20:21], v[10:11], v[26:27]
	v_pk_add_f32 v[10:11], v[10:11], v[26:27] neg_lo:[0,1] neg_hi:[0,1]
	v_pk_mul_f32 v[26:27], v[72:73], s[58:59] op_sel_hi:[1,0]
	v_pk_fma_f32 v[26:27], v[134:135], s[46:47], v[26:27] op_sel_hi:[1,0,1] neg_lo:[0,0,1] neg_hi:[0,0,1]
	v_xor_b32_e32 v134, 0x80000000, v75
	v_pk_add_f32 v[72:73], v[90:91], v[26:27]
	v_pk_add_f32 v[26:27], v[90:91], v[26:27] neg_lo:[0,1] neg_hi:[0,1]
	v_pk_mul_f32 v[90:91], v[74:75], s[62:63] op_sel_hi:[1,0]
	v_mov_b32_e32 v135, v74
	v_pk_fma_f32 v[74:75], v[134:135], s[60:61], v[90:91] op_sel_hi:[1,0,1] neg_lo:[0,0,1] neg_hi:[0,0,1]
	v_xor_b32_e32 v134, 0x80000000, v79
	v_pk_add_f32 v[90:91], v[80:81], v[74:75]
	v_pk_add_f32 v[74:75], v[80:81], v[74:75] neg_lo:[0,1] neg_hi:[0,1]
	v_pk_mul_f32 v[80:81], v[78:79], s[66:67] op_sel_hi:[1,0]
	v_mov_b32_e32 v135, v78
	v_pk_fma_f32 v[78:79], v[134:135], s[64:65], v[80:81] op_sel_hi:[1,0,1] neg_lo:[0,0,1] neg_hi:[0,0,1]
	v_xor_b32_e32 v134, 0x80000000, v83
	v_pk_add_f32 v[80:81], v[12:13], v[78:79]
	v_pk_add_f32 v[12:13], v[12:13], v[78:79] neg_lo:[0,1] neg_hi:[0,1]
	v_pk_mul_f32 v[78:79], v[82:83], s[70:71] op_sel_hi:[1,0]
	v_mov_b32_e32 v135, v82
	v_pk_fma_f32 v[78:79], v[134:135], s[70:71], v[78:79] op_sel_hi:[1,0,1] neg_lo:[0,0,1] neg_hi:[0,0,1]
	v_xor_b32_e32 v134, 0x80000000, v15
	v_pk_add_f32 v[82:83], v[64:65], v[78:79]
	v_pk_add_f32 v[64:65], v[64:65], v[78:79] neg_lo:[0,1] neg_hi:[0,1]
	v_pk_mul_f32 v[78:79], v[14:15], s[64:65] op_sel_hi:[1,0]
	v_mov_b32_e32 v135, v14
	v_pk_fma_f32 v[14:15], v[134:135], s[66:67], v[78:79] op_sel_hi:[1,0,1] neg_lo:[0,0,1] neg_hi:[0,0,1]
	v_xor_b32_e32 v134, 0x80000000, v19
	v_pk_add_f32 v[78:79], v[2:3], v[14:15]
	v_pk_add_f32 v[2:3], v[2:3], v[14:15] neg_lo:[0,1] neg_hi:[0,1]
	v_pk_mul_f32 v[14:15], v[18:19], s[60:61] op_sel_hi:[1,0]
	v_mov_b32_e32 v135, v18
	v_pk_fma_f32 v[14:15], v[134:135], s[62:63], v[14:15] op_sel_hi:[1,0,1] neg_lo:[0,0,1] neg_hi:[0,0,1]
	v_xor_b32_e32 v134, 0x80000000, v23
	v_pk_add_f32 v[18:19], v[4:5], v[14:15]
	v_pk_add_f32 v[4:5], v[4:5], v[14:15] neg_lo:[0,1] neg_hi:[0,1]
	v_pk_mul_f32 v[14:15], v[22:23], s[46:47] op_sel_hi:[1,0]
	v_mov_b32_e32 v135, v22
	v_pk_fma_f32 v[14:15], v[134:135], s[58:59], v[14:15] op_sel_hi:[1,0,1] neg_lo:[0,0,1] neg_hi:[0,0,1]
	s_nop 0
	v_pk_add_f32 v[22:23], v[0:1], v[14:15]
	v_pk_add_f32 v[0:1], v[0:1], v[14:15] neg_lo:[0,1] neg_hi:[0,1]
	ds_write_b64 v67, v[24:25]
	ds_write_b64 v98, v[130:131]
	ds_write_b64 v99, v[96:97] offset:256
	ds_write_b64 v100, v[132:133] offset:256
	ds_write_b64 v101, v[92:93] offset:512
	ds_write_b64 v102, v[88:89] offset:512
	ds_write_b64 v103, v[76:77] offset:768
	ds_write_b64 v104, v[62:63] offset:768
	ds_write_b64 v105, v[20:21] offset:1024
	ds_write_b64 v106, v[72:73] offset:1024
	ds_write_b64 v107, v[90:91] offset:1280
	ds_write_b64 v108, v[80:81] offset:1280
	ds_write_b64 v109, v[82:83] offset:1536
	ds_write_b64 v110, v[78:79] offset:1536
	ds_write_b64 v111, v[18:19] offset:1792
	ds_write_b64 v112, v[22:23] offset:1792
	ds_write_b64 v113, v[6:7] offset:2048
	ds_write_b64 v114, v[84:85] offset:2048
	ds_write_b64 v115, v[94:95] offset:2304
	ds_write_b64 v116, v[86:87] offset:2304
	ds_write_b64 v117, v[70:71] offset:2560
	ds_write_b64 v118, v[68:69] offset:2560
	ds_write_b64 v119, v[8:9] offset:2816
	ds_write_b64 v120, v[16:17] offset:2816
	ds_write_b64 v121, v[10:11] offset:3072
	ds_write_b64 v122, v[26:27] offset:3072
	ds_write_b64 v123, v[74:75] offset:3328
	ds_write_b64 v124, v[12:13] offset:3328
	ds_write_b64 v125, v[64:65] offset:3584
	ds_write_b64 v126, v[2:3] offset:3584
	ds_write_b64 v127, v[4:5] offset:3840
	ds_write_b64 v128, v[0:1] offset:3840
	v_mov_b32_e32 v74, v146
	s_waitcnt lgkmcnt(0)
	s_barrier
	s_nop 0
	v_lshrrev_b32_e32 v0, 5, v74
	v_bfe_u32 v4, v74, 5, 4
	v_bitop3_b32 v0, v0, v74, 15 bitop3:0x6c
	v_bitop3_b32 v4, v4, v74, 16 bitop3:0x36
	v_lshlrev_b32_e32 v66, 3, v0
	v_lshlrev_b32_e32 v67, 3, v4
	v_add_u32_e32 v5, 16, v66
	v_add_u32_e32 v4, 16, v67
	v_add_u32_e32 v62, s47, v66
	v_add_u32_e32 v70, s9, v66
	ds_read2st64_b64 v[0:3], v5 offset1:16
	ds_read2st64_b64 v[16:19], v4 offset0:8 offset1:24
	ds_read2st64_b64 v[24:27], v5 offset0:32 offset1:48
	ds_read2st64_b64 v[8:11], v4 offset0:40 offset1:56
	ds_read2st64_b64 v[92:95], v5 offset0:64 offset1:80
	ds_read2st64_b64 v[12:15], v4 offset0:72 offset1:88
	ds_read2st64_b64 v[20:23], v5 offset0:96 offset1:112
	ds_read2st64_b64 v[4:7], v4 offset0:104 offset1:120
	ds_read_b64 v[68:69], v62
	ds_read_b64 v[72:73], v70
	v_add_u32_e32 v62, s19, v67
	v_add_u32_e32 v70, s8, v67
	ds_read_b64 v[84:85], v62
	ds_read_b64 v[90:91], v70
	v_add_u32_e32 v62, s18, v66
	v_add_u32_e32 v70, s7, v66
	ds_read_b64 v[96:97], v62
	ds_read_b64 v[100:101], v70
	v_add_u32_e32 v62, s17, v67
	v_add_u32_e32 v70, s6, v67
	ds_read_b64 v[64:65], v62
	ds_read_b64 v[70:71], v70
	v_add_u32_e32 v62, s13, v66
	v_add_u32_e32 v75, s5, v66
	ds_read_b64 v[86:87], v62
	ds_read_b64 v[102:103], v75
	v_add_u32_e32 v62, s12, v67
	v_add_u32_e32 v75, s4, v67
	ds_read_b64 v[80:81], v62
	ds_read_b64 v[88:89], v75
	v_add_u32_e32 v62, s11, v66
	v_add_u32_e32 v66, s1, v66
	ds_read_b64 v[98:99], v62
	ds_read_b64 v[104:105], v66
	v_add_u32_e32 v62, s10, v67
	v_add_u32_e32 v66, s0, v67
	ds_read_b64 v[62:63], v62
	ds_read_b64 v[66:67], v66
	s_waitcnt lgkmcnt(14)
	s_nop 0
	v_cvt_f32_i32_e32 v74, v74
	s_nop 0
	s_lshl_b64 s[0:1], s[44:45], 2
	s_add_u32 s0, s24, s0
	v_mul_f32_e32 v74, 0x38800000, v74
	v_cos_f32_e32 v78, v74
	v_sin_f32_e32 v79, v74
	s_addc_u32 s1, s59, s1
	s_and_b64 vcc, s[14:15], exec
	v_add_f32_e32 v76, v78, v78
	v_pk_mul_f32 v[74:75], v[78:79], v[78:79]
	v_mul_f32_e32 v76, v79, v76
	v_mov_b32_e32 v108, v79
	v_pk_add_f32 v[74:75], v[74:75], v[74:75] op_sel:[0,1] op_sel_hi:[0,1] neg_lo:[0,1] neg_hi:[0,1]
	v_pk_mul_f32 v[82:83], v[78:79], v[76:77] op_sel:[1,0] op_sel_hi:[0,0] neg_lo:[1,0]
	v_pk_mul_f32 v[106:107], v[68:69], v[108:109] op_sel:[1,0] op_sel_hi:[0,0] neg_lo:[1,0]
	v_pk_fma_f32 v[82:83], v[78:79], v[74:75], v[82:83]
	v_pk_fma_f32 v[68:69], v[68:69], v[78:79], v[106:107] op_sel_hi:[1,0,1]
	v_pk_mul_f32 v[78:79], v[76:77], s[48:49] op_sel_hi:[0,1]
	v_pk_fma_f32 v[106:107], v[74:75], s[40:41], v[78:79]
	v_pk_mul_f32 v[78:79], v[92:93], v[106:107] op_sel:[1,1] op_sel_hi:[0,1] neg_lo:[1,0]
	v_pk_fma_f32 v[78:79], v[92:93], v[106:107], v[78:79] op_sel_hi:[1,0,1]
	v_pk_mul_f32 v[92:93], v[76:77], v[82:83] op_sel:[0,1] op_sel_hi:[0,0] neg_lo:[0,1]
	v_pk_mul_f32 v[108:109], v[72:73], v[82:83] op_sel:[1,1] op_sel_hi:[0,1] neg_lo:[1,0]
	v_pk_fma_f32 v[92:93], v[74:75], v[82:83], v[92:93]
	v_pk_fma_f32 v[72:73], v[72:73], v[82:83], v[108:109] op_sel_hi:[1,0,1]
	v_pk_mul_f32 v[82:83], v[76:77], v[106:107] op_sel:[0,1] op_sel_hi:[0,0] neg_lo:[0,1]
	v_pk_fma_f32 v[106:107], v[74:75], v[106:107], v[82:83]
	v_pk_mul_f32 v[82:83], v[24:25], v[106:107] op_sel:[1,1] op_sel_hi:[0,1] neg_lo:[1,0]
	v_pk_fma_f32 v[82:83], v[24:25], v[106:107], v[82:83] op_sel_hi:[1,0,1]
	v_pk_mul_f32 v[24:25], v[76:77], v[92:93] op_sel:[0,1] op_sel_hi:[0,0] neg_lo:[0,1]
	v_pk_fma_f32 v[108:109], v[74:75], v[92:93], v[24:25]
	s_waitcnt lgkmcnt(7)
	v_pk_mul_f32 v[24:25], v[86:87], v[92:93] op_sel:[1,1] op_sel_hi:[0,1] neg_lo:[1,0]
	s_nop 0
	v_pk_fma_f32 v[24:25], v[86:87], v[92:93], v[24:25] op_sel_hi:[1,0,1]
	v_pk_mul_f32 v[86:87], v[76:77], v[106:107] op_sel:[0,1] op_sel_hi:[0,0] neg_lo:[0,1]
	v_pk_fma_f32 v[92:93], v[74:75], v[106:107], v[86:87]
	v_pk_mul_f32 v[86:87], v[20:21], v[92:93] op_sel:[1,1] op_sel_hi:[0,1] neg_lo:[1,0]
	v_pk_fma_f32 v[86:87], v[20:21], v[92:93], v[86:87] op_sel_hi:[1,0,1]
	v_pk_mul_f32 v[20:21], v[76:77], v[108:109] op_sel:[0,1] op_sel_hi:[0,0] neg_lo:[0,1]
	v_pk_fma_f32 v[106:107], v[74:75], v[108:109], v[20:21]
	s_waitcnt lgkmcnt(6)
	v_pk_mul_f32 v[20:21], v[102:103], v[108:109] op_sel:[1,1] op_sel_hi:[0,1] neg_lo:[1,0]
	s_nop 0
	v_pk_fma_f32 v[20:21], v[102:103], v[108:109], v[20:21] op_sel_hi:[1,0,1]
	v_pk_mul_f32 v[102:103], v[76:77], v[92:93] op_sel:[0,1] op_sel_hi:[0,0] neg_lo:[0,1]
	v_pk_fma_f32 v[102:103], v[74:75], v[92:93], v[102:103]
	v_pk_mul_f32 v[92:93], v[2:3], v[102:103] op_sel:[1,1] op_sel_hi:[0,1] neg_lo:[1,0]
	v_pk_fma_f32 v[92:93], v[2:3], v[102:103], v[92:93] op_sel_hi:[1,0,1]
	v_pk_mul_f32 v[2:3], v[76:77], v[106:107] op_sel:[0,1] op_sel_hi:[0,0] neg_lo:[0,1]
	v_pk_fma_f32 v[108:109], v[74:75], v[106:107], v[2:3]
	v_pk_mul_f32 v[2:3], v[96:97], v[106:107] op_sel:[1,1] op_sel_hi:[0,1] neg_lo:[1,0]
	v_pk_fma_f32 v[2:3], v[96:97], v[106:107], v[2:3] op_sel_hi:[1,0,1]
	v_pk_mul_f32 v[96:97], v[76:77], v[102:103] op_sel:[0,1] op_sel_hi:[0,0] neg_lo:[0,1]
	v_pk_fma_f32 v[102:103], v[74:75], v[102:103], v[96:97]
	v_pk_mul_f32 v[96:97], v[94:95], v[102:103] op_sel:[1,1] op_sel_hi:[0,1] neg_lo:[1,0]
	v_pk_fma_f32 v[96:97], v[94:95], v[102:103], v[96:97] op_sel_hi:[1,0,1]
	v_pk_mul_f32 v[94:95], v[76:77], v[108:109] op_sel:[0,1] op_sel_hi:[0,0] neg_lo:[0,1]
	v_pk_fma_f32 v[106:107], v[74:75], v[108:109], v[94:95]
	v_pk_mul_f32 v[94:95], v[100:101], v[108:109] op_sel:[1,1] op_sel_hi:[0,1] neg_lo:[1,0]
	v_pk_fma_f32 v[94:95], v[100:101], v[108:109], v[94:95] op_sel_hi:[1,0,1]
	v_pk_mul_f32 v[100:101], v[76:77], v[102:103] op_sel:[0,1] op_sel_hi:[0,0] neg_lo:[0,1]
	v_pk_fma_f32 v[100:101], v[74:75], v[102:103], v[100:101]
	s_nop 0
	v_pk_mul_f32 v[102:103], v[26:27], v[100:101] op_sel:[1,1] op_sel_hi:[0,1] neg_lo:[1,0]
	s_waitcnt lgkmcnt(3)
	v_pk_fma_f32 v[26:27], v[26:27], v[100:101], v[102:103] op_sel_hi:[1,0,1]
	v_pk_mul_f32 v[102:103], v[76:77], v[106:107] op_sel:[0,1] op_sel_hi:[0,0] neg_lo:[0,1]
	v_pk_mul_f32 v[108:109], v[98:99], v[106:107] op_sel:[1,1] op_sel_hi:[0,1] neg_lo:[1,0]
	v_pk_fma_f32 v[102:103], v[74:75], v[106:107], v[102:103]
	v_pk_fma_f32 v[98:99], v[98:99], v[106:107], v[108:109] op_sel_hi:[1,0,1]
	v_pk_mul_f32 v[106:107], v[76:77], v[100:101] op_sel:[0,1] op_sel_hi:[0,0] neg_lo:[0,1]
	v_pk_fma_f32 v[100:101], v[74:75], v[100:101], v[106:107]
	s_nop 0
	v_pk_mul_f32 v[106:107], v[22:23], v[100:101] op_sel:[1,1] op_sel_hi:[0,1] neg_lo:[1,0]
	s_waitcnt lgkmcnt(2)
	v_pk_fma_f32 v[22:23], v[22:23], v[100:101], v[106:107] op_sel_hi:[1,0,1]
	v_pk_mul_f32 v[106:107], v[76:77], v[102:103] op_sel:[0,1] op_sel_hi:[0,0] neg_lo:[0,1]
	v_pk_mul_f32 v[108:109], v[104:105], v[102:103] op_sel:[1,1] op_sel_hi:[0,1] neg_lo:[1,0]
	v_pk_fma_f32 v[106:107], v[74:75], v[102:103], v[106:107]
	v_pk_fma_f32 v[102:103], v[104:105], v[102:103], v[108:109] op_sel_hi:[1,0,1]
	v_pk_mul_f32 v[104:105], v[76:77], v[100:101] op_sel:[0,1] op_sel_hi:[0,0] neg_lo:[0,1]
	v_pk_fma_f32 v[100:101], v[74:75], v[100:101], v[104:105]
	v_pk_mul_f32 v[104:105], v[16:17], v[100:101] op_sel:[1,1] op_sel_hi:[0,1] neg_lo:[1,0]
	v_pk_fma_f32 v[16:17], v[16:17], v[100:101], v[104:105] op_sel_hi:[1,0,1]
	v_pk_mul_f32 v[104:105], v[76:77], v[106:107] op_sel:[0,1] op_sel_hi:[0,0] neg_lo:[0,1]
	v_pk_mul_f32 v[108:109], v[84:85], v[106:107] op_sel:[1,1] op_sel_hi:[0,1] neg_lo:[1,0]
	v_pk_fma_f32 v[104:105], v[74:75], v[106:107], v[104:105]
	v_pk_fma_f32 v[84:85], v[84:85], v[106:107], v[108:109] op_sel_hi:[1,0,1]
	v_pk_mul_f32 v[106:107], v[76:77], v[100:101] op_sel:[0,1] op_sel_hi:[0,0] neg_lo:[0,1]
	v_pk_fma_f32 v[100:101], v[74:75], v[100:101], v[106:107]
	v_pk_mul_f32 v[106:107], v[12:13], v[100:101] op_sel:[1,1] op_sel_hi:[0,1] neg_lo:[1,0]
	v_pk_fma_f32 v[12:13], v[12:13], v[100:101], v[106:107] op_sel_hi:[1,0,1]
	v_pk_mul_f32 v[106:107], v[76:77], v[104:105] op_sel:[0,1] op_sel_hi:[0,0] neg_lo:[0,1]
	v_pk_mul_f32 v[108:109], v[90:91], v[104:105] op_sel:[1,1] op_sel_hi:[0,1] neg_lo:[1,0]
	v_pk_fma_f32 v[106:107], v[74:75], v[104:105], v[106:107]
	v_pk_fma_f32 v[90:91], v[90:91], v[104:105], v[108:109] op_sel_hi:[1,0,1]
	v_pk_mul_f32 v[104:105], v[76:77], v[100:101] op_sel:[0,1] op_sel_hi:[0,0] neg_lo:[0,1]
	v_pk_fma_f32 v[100:101], v[74:75], v[100:101], v[104:105]
	v_pk_mul_f32 v[104:105], v[8:9], v[100:101] op_sel:[1,1] op_sel_hi:[0,1] neg_lo:[1,0]
	v_pk_fma_f32 v[8:9], v[8:9], v[100:101], v[104:105] op_sel_hi:[1,0,1]
	v_pk_mul_f32 v[104:105], v[76:77], v[106:107] op_sel:[0,1] op_sel_hi:[0,0] neg_lo:[0,1]
	v_pk_mul_f32 v[108:109], v[80:81], v[106:107] op_sel:[1,1] op_sel_hi:[0,1] neg_lo:[1,0]
	v_pk_fma_f32 v[104:105], v[74:75], v[106:107], v[104:105]
	v_pk_fma_f32 v[80:81], v[80:81], v[106:107], v[108:109] op_sel_hi:[1,0,1]
	v_pk_mul_f32 v[106:107], v[76:77], v[100:101] op_sel:[0,1] op_sel_hi:[0,0] neg_lo:[0,1]
	v_pk_fma_f32 v[100:101], v[74:75], v[100:101], v[106:107]
	v_pk_mul_f32 v[106:107], v[4:5], v[100:101] op_sel:[1,1] op_sel_hi:[0,1] neg_lo:[1,0]
	v_pk_fma_f32 v[4:5], v[4:5], v[100:101], v[106:107] op_sel_hi:[1,0,1]
	v_pk_mul_f32 v[106:107], v[76:77], v[104:105] op_sel:[0,1] op_sel_hi:[0,0] neg_lo:[0,1]
	v_pk_mul_f32 v[108:109], v[88:89], v[104:105] op_sel:[1,1] op_sel_hi:[0,1] neg_lo:[1,0]
	v_pk_fma_f32 v[106:107], v[74:75], v[104:105], v[106:107]
	v_pk_fma_f32 v[88:89], v[88:89], v[104:105], v[108:109] op_sel_hi:[1,0,1]
	v_pk_mul_f32 v[104:105], v[76:77], v[100:101] op_sel:[0,1] op_sel_hi:[0,0] neg_lo:[0,1]
	v_pk_fma_f32 v[100:101], v[74:75], v[100:101], v[104:105]
	v_pk_mul_f32 v[104:105], v[18:19], v[100:101] op_sel:[1,1] op_sel_hi:[0,1] neg_lo:[1,0]
	v_pk_fma_f32 v[18:19], v[18:19], v[100:101], v[104:105] op_sel_hi:[1,0,1]
	v_pk_mul_f32 v[104:105], v[76:77], v[106:107] op_sel:[0,1] op_sel_hi:[0,0] neg_lo:[0,1]
	v_pk_mul_f32 v[108:109], v[64:65], v[106:107] op_sel:[1,1] op_sel_hi:[0,1] neg_lo:[1,0]
	v_pk_fma_f32 v[104:105], v[74:75], v[106:107], v[104:105]
	v_pk_fma_f32 v[64:65], v[64:65], v[106:107], v[108:109] op_sel_hi:[1,0,1]
	v_pk_mul_f32 v[106:107], v[76:77], v[100:101] op_sel:[0,1] op_sel_hi:[0,0] neg_lo:[0,1]
	v_pk_fma_f32 v[100:101], v[74:75], v[100:101], v[106:107]
	v_pk_mul_f32 v[106:107], v[14:15], v[100:101] op_sel:[1,1] op_sel_hi:[0,1] neg_lo:[1,0]
	v_pk_fma_f32 v[14:15], v[14:15], v[100:101], v[106:107] op_sel_hi:[1,0,1]
	v_pk_mul_f32 v[106:107], v[76:77], v[104:105] op_sel:[0,1] op_sel_hi:[0,0] neg_lo:[0,1]
	v_pk_mul_f32 v[108:109], v[70:71], v[104:105] op_sel:[1,1] op_sel_hi:[0,1] neg_lo:[1,0]
	v_pk_fma_f32 v[106:107], v[74:75], v[104:105], v[106:107]
	v_pk_fma_f32 v[70:71], v[70:71], v[104:105], v[108:109] op_sel_hi:[1,0,1]
	v_pk_mul_f32 v[104:105], v[76:77], v[100:101] op_sel:[0,1] op_sel_hi:[0,0] neg_lo:[0,1]
	v_pk_fma_f32 v[100:101], v[74:75], v[100:101], v[104:105]
	s_nop 0
	v_pk_mul_f32 v[104:105], v[10:11], v[100:101] op_sel:[1,1] op_sel_hi:[0,1] neg_lo:[1,0]
	s_waitcnt lgkmcnt(1)
	v_pk_fma_f32 v[10:11], v[10:11], v[100:101], v[104:105] op_sel_hi:[1,0,1]
	v_pk_mul_f32 v[104:105], v[76:77], v[106:107] op_sel:[0,1] op_sel_hi:[0,0] neg_lo:[0,1]
	v_pk_mul_f32 v[108:109], v[62:63], v[106:107] op_sel:[1,1] op_sel_hi:[0,1] neg_lo:[1,0]
	v_pk_fma_f32 v[104:105], v[74:75], v[106:107], v[104:105]
	v_pk_fma_f32 v[62:63], v[62:63], v[106:107], v[108:109] op_sel_hi:[1,0,1]
	v_pk_mul_f32 v[76:77], v[76:77], v[100:101] op_sel:[0,1] op_sel_hi:[0,0] neg_lo:[0,1]
	v_pk_fma_f32 v[74:75], v[74:75], v[100:101], v[76:77]
	s_nop 0
	v_pk_mul_f32 v[76:77], v[6:7], v[74:75] op_sel:[1,1] op_sel_hi:[0,1] neg_lo:[1,0]
	s_nop 0
	v_pk_fma_f32 v[6:7], v[6:7], v[74:75], v[76:77] op_sel_hi:[1,0,1]
	s_waitcnt lgkmcnt(0)
	v_pk_mul_f32 v[74:75], v[66:67], v[104:105] op_sel:[1,1] op_sel_hi:[0,1] neg_lo:[1,0]
	v_pk_add_f32 v[76:77], v[82:83], v[8:9]
	v_pk_fma_f32 v[66:67], v[66:67], v[104:105], v[74:75] op_sel_hi:[1,0,1]
	v_pk_add_f32 v[74:75], v[0:1], v[16:17]
	v_pk_add_f32 v[0:1], v[0:1], v[16:17] neg_lo:[0,1] neg_hi:[0,1]
	v_pk_add_f32 v[16:17], v[92:93], v[18:19]
	v_pk_add_f32 v[18:19], v[92:93], v[18:19] neg_lo:[0,1] neg_hi:[0,1]
	v_pk_add_f32 v[8:9], v[82:83], v[8:9] neg_lo:[0,1] neg_hi:[0,1]
	v_pk_add_f32 v[82:83], v[26:27], v[10:11]
	v_pk_add_f32 v[10:11], v[26:27], v[10:11] neg_lo:[0,1] neg_hi:[0,1]
	v_pk_add_f32 v[92:93], v[86:87], v[4:5]
	v_pk_add_f32 v[4:5], v[86:87], v[4:5] neg_lo:[0,1] neg_hi:[0,1]
	v_pk_add_f32 v[86:87], v[22:23], v[6:7]
	v_pk_add_f32 v[6:7], v[22:23], v[6:7] neg_lo:[0,1] neg_hi:[0,1]
	v_pk_add_f32 v[22:23], v[68:69], v[84:85]
	v_pk_add_f32 v[68:69], v[68:69], v[84:85] neg_lo:[0,1] neg_hi:[0,1]
	v_pk_add_f32 v[84:85], v[2:3], v[64:65]
	v_pk_add_f32 v[2:3], v[2:3], v[64:65] neg_lo:[0,1] neg_hi:[0,1]
	v_pk_add_f32 v[64:65], v[24:25], v[80:81]
	v_pk_add_f32 v[24:25], v[24:25], v[80:81] neg_lo:[0,1] neg_hi:[0,1]
	v_pk_add_f32 v[80:81], v[98:99], v[62:63]
	v_pk_add_f32 v[62:63], v[98:99], v[62:63] neg_lo:[0,1] neg_hi:[0,1]
	v_pk_add_f32 v[98:99], v[74:75], v[16:17]
	v_pk_add_f32 v[16:17], v[74:75], v[16:17] neg_lo:[0,1] neg_hi:[0,1]
	v_xor_b32_e32 v74, 0x80000000, v19
	v_mov_b32_e32 v75, v18
	v_pk_add_f32 v[26:27], v[78:79], v[12:13]
	v_pk_add_f32 v[12:13], v[78:79], v[12:13] neg_lo:[0,1] neg_hi:[0,1]
	v_pk_add_f32 v[78:79], v[96:97], v[14:15]
	v_pk_add_f32 v[14:15], v[96:97], v[14:15] neg_lo:[0,1] neg_hi:[0,1]
	v_pk_add_f32 v[18:19], v[0:1], v[74:75]
	v_pk_add_f32 v[0:1], v[0:1], v[74:75] neg_lo:[0,1] neg_hi:[0,1]
	v_pk_add_f32 v[74:75], v[76:77], v[82:83]
	v_pk_add_f32 v[76:77], v[76:77], v[82:83] neg_lo:[0,1] neg_hi:[0,1]
	v_xor_b32_e32 v82, 0x80000000, v11
	v_mov_b32_e32 v83, v10
	v_pk_add_f32 v[10:11], v[8:9], v[82:83]
	v_pk_add_f32 v[8:9], v[8:9], v[82:83] neg_lo:[0,1] neg_hi:[0,1]
	v_pk_add_f32 v[82:83], v[26:27], v[78:79]
	v_pk_add_f32 v[26:27], v[26:27], v[78:79] neg_lo:[0,1] neg_hi:[0,1]
	v_xor_b32_e32 v78, 0x80000000, v15
	v_mov_b32_e32 v79, v14
	v_pk_add_f32 v[14:15], v[12:13], v[78:79]
	v_pk_add_f32 v[12:13], v[12:13], v[78:79] neg_lo:[0,1] neg_hi:[0,1]
	v_pk_add_f32 v[78:79], v[92:93], v[86:87]
	v_pk_add_f32 v[86:87], v[92:93], v[86:87] neg_lo:[0,1] neg_hi:[0,1]
	v_xor_b32_e32 v92, 0x80000000, v7
	v_mov_b32_e32 v93, v6
	v_pk_add_f32 v[6:7], v[4:5], v[92:93]
	v_pk_add_f32 v[4:5], v[4:5], v[92:93] neg_lo:[0,1] neg_hi:[0,1]
	v_pk_add_f32 v[92:93], v[22:23], v[84:85]
	v_pk_add_f32 v[22:23], v[22:23], v[84:85] neg_lo:[0,1] neg_hi:[0,1]
	v_xor_b32_e32 v84, 0x80000000, v3
	v_mov_b32_e32 v85, v2
	v_pk_add_f32 v[96:97], v[72:73], v[90:91]
	v_pk_add_f32 v[72:73], v[72:73], v[90:91] neg_lo:[0,1] neg_hi:[0,1]
	v_pk_add_f32 v[90:91], v[94:95], v[70:71]
	v_pk_add_f32 v[70:71], v[94:95], v[70:71] neg_lo:[0,1] neg_hi:[0,1]
	v_pk_add_f32 v[2:3], v[68:69], v[84:85]
	v_pk_add_f32 v[68:69], v[68:69], v[84:85] neg_lo:[0,1] neg_hi:[0,1]
	v_pk_add_f32 v[84:85], v[64:65], v[80:81]
	v_pk_add_f32 v[64:65], v[64:65], v[80:81] neg_lo:[0,1] neg_hi:[0,1]
	v_xor_b32_e32 v80, 0x80000000, v63
	v_mov_b32_e32 v81, v62
	v_pk_add_f32 v[94:95], v[20:21], v[88:89]
	v_pk_add_f32 v[20:21], v[20:21], v[88:89] neg_lo:[0,1] neg_hi:[0,1]
	v_pk_add_f32 v[88:89], v[102:103], v[66:67]
	v_pk_add_f32 v[66:67], v[102:103], v[66:67] neg_lo:[0,1] neg_hi:[0,1]
	v_pk_add_f32 v[62:63], v[24:25], v[80:81]
	v_pk_add_f32 v[24:25], v[24:25], v[80:81] neg_lo:[0,1] neg_hi:[0,1]
	v_pk_add_f32 v[80:81], v[96:97], v[90:91]
	v_pk_add_f32 v[90:91], v[96:97], v[90:91] neg_lo:[0,1] neg_hi:[0,1]
	v_xor_b32_e32 v96, 0x80000000, v71
	v_mov_b32_e32 v97, v70
	v_pk_add_f32 v[70:71], v[72:73], v[96:97]
	v_pk_add_f32 v[72:73], v[72:73], v[96:97] neg_lo:[0,1] neg_hi:[0,1]
	v_pk_add_f32 v[96:97], v[94:95], v[88:89]
	v_pk_add_f32 v[88:89], v[94:95], v[88:89] neg_lo:[0,1] neg_hi:[0,1]
	v_xor_b32_e32 v94, 0x80000000, v67
	v_mov_b32_e32 v95, v66
	v_pk_add_f32 v[66:67], v[20:21], v[94:95]
	v_pk_add_f32 v[20:21], v[20:21], v[94:95] neg_lo:[0,1] neg_hi:[0,1]
	v_pk_add_f32 v[94:95], v[98:99], v[74:75]
	v_pk_add_f32 v[74:75], v[98:99], v[74:75] neg_lo:[0,1] neg_hi:[0,1]
	v_pk_mul_f32 v[98:99], v[10:11], s[70:71] op_sel:[1,0] op_sel_hi:[0,0] neg_lo:[1,0]
	v_xor_b32_e32 v100, 0x80000000, v9
	v_pk_fma_f32 v[10:11], v[10:11], s[70:71], v[98:99] op_sel_hi:[1,0,1]
	v_mov_b32_e32 v101, v8
	v_pk_add_f32 v[98:99], v[18:19], v[10:11]
	v_pk_add_f32 v[10:11], v[18:19], v[10:11] neg_lo:[0,1] neg_hi:[0,1]
	v_xor_b32_e32 v18, 0x80000000, v77
	v_mov_b32_e32 v19, v76
	v_pk_add_f32 v[76:77], v[16:17], v[18:19]
	v_pk_add_f32 v[16:17], v[16:17], v[18:19] neg_lo:[0,1] neg_hi:[0,1]
	v_pk_mul_f32 v[18:19], v[8:9], s[70:71] op_sel_hi:[1,0]
	v_pk_fma_f32 v[8:9], v[100:101], s[70:71], v[18:19] op_sel_hi:[1,0,1] neg_lo:[0,0,1] neg_hi:[0,0,1]
	v_xor_b32_e32 v100, 0x80000000, v5
	v_pk_add_f32 v[18:19], v[0:1], v[8:9]
	v_pk_add_f32 v[0:1], v[0:1], v[8:9] neg_lo:[0,1] neg_hi:[0,1]
	v_pk_add_f32 v[8:9], v[82:83], v[78:79]
	v_pk_add_f32 v[78:79], v[82:83], v[78:79] neg_lo:[0,1] neg_hi:[0,1]
	v_pk_mul_f32 v[82:83], v[6:7], s[70:71] op_sel:[1,0] op_sel_hi:[0,0] neg_lo:[1,0]
	v_mov_b32_e32 v101, v4
	v_pk_fma_f32 v[6:7], v[6:7], s[70:71], v[82:83] op_sel_hi:[1,0,1]
	v_pk_add_f32 v[82:83], v[14:15], v[6:7]
	v_pk_add_f32 v[6:7], v[14:15], v[6:7] neg_lo:[0,1] neg_hi:[0,1]
	v_xor_b32_e32 v14, 0x80000000, v87
	v_mov_b32_e32 v15, v86
	v_pk_add_f32 v[86:87], v[26:27], v[14:15]
	v_pk_add_f32 v[14:15], v[26:27], v[14:15] neg_lo:[0,1] neg_hi:[0,1]
	v_pk_mul_f32 v[26:27], v[4:5], s[70:71] op_sel_hi:[1,0]
	v_pk_fma_f32 v[4:5], v[100:101], s[70:71], v[26:27] op_sel_hi:[1,0,1] neg_lo:[0,0,1] neg_hi:[0,0,1]
	v_xor_b32_e32 v100, 0x80000000, v25
	v_pk_add_f32 v[26:27], v[12:13], v[4:5]
	v_pk_add_f32 v[4:5], v[12:13], v[4:5] neg_lo:[0,1] neg_hi:[0,1]
	v_pk_add_f32 v[12:13], v[92:93], v[84:85]
	v_pk_add_f32 v[84:85], v[92:93], v[84:85] neg_lo:[0,1] neg_hi:[0,1]
	v_pk_mul_f32 v[92:93], v[62:63], s[70:71] op_sel:[1,0] op_sel_hi:[0,0] neg_lo:[1,0]
	v_mov_b32_e32 v101, v24
	v_pk_fma_f32 v[62:63], v[62:63], s[70:71], v[92:93] op_sel_hi:[1,0,1]
	v_pk_add_f32 v[92:93], v[2:3], v[62:63]
	v_pk_add_f32 v[2:3], v[2:3], v[62:63] neg_lo:[0,1] neg_hi:[0,1]
	v_xor_b32_e32 v62, 0x80000000, v65
	v_mov_b32_e32 v63, v64
	v_pk_add_f32 v[64:65], v[22:23], v[62:63]
	v_pk_add_f32 v[22:23], v[22:23], v[62:63] neg_lo:[0,1] neg_hi:[0,1]
	v_pk_mul_f32 v[62:63], v[24:25], s[70:71] op_sel_hi:[1,0]
	v_pk_fma_f32 v[24:25], v[100:101], s[70:71], v[62:63] op_sel_hi:[1,0,1] neg_lo:[0,0,1] neg_hi:[0,0,1]
	v_xor_b32_e32 v100, 0x80000000, v21
	v_pk_add_f32 v[62:63], v[68:69], v[24:25]
	v_pk_add_f32 v[24:25], v[68:69], v[24:25] neg_lo:[0,1] neg_hi:[0,1]
	v_pk_add_f32 v[68:69], v[80:81], v[96:97]
	v_pk_add_f32 v[80:81], v[80:81], v[96:97] neg_lo:[0,1] neg_hi:[0,1]
	v_pk_mul_f32 v[96:97], v[66:67], s[70:71] op_sel:[1,0] op_sel_hi:[0,0] neg_lo:[1,0]
	v_mov_b32_e32 v101, v20
	v_pk_fma_f32 v[66:67], v[66:67], s[70:71], v[96:97] op_sel_hi:[1,0,1]
	v_pk_add_f32 v[96:97], v[70:71], v[66:67]
	v_pk_add_f32 v[66:67], v[70:71], v[66:67] neg_lo:[0,1] neg_hi:[0,1]
	v_xor_b32_e32 v70, 0x80000000, v89
	v_mov_b32_e32 v71, v88
	v_pk_add_f32 v[88:89], v[90:91], v[70:71]
	v_pk_add_f32 v[70:71], v[90:91], v[70:71] neg_lo:[0,1] neg_hi:[0,1]
	v_pk_mul_f32 v[90:91], v[20:21], s[70:71] op_sel_hi:[1,0]
	v_pk_fma_f32 v[20:21], v[100:101], s[70:71], v[90:91] op_sel_hi:[1,0,1] neg_lo:[0,0,1] neg_hi:[0,0,1]
	v_pk_add_f32 v[90:91], v[72:73], v[20:21]
	v_pk_add_f32 v[20:21], v[72:73], v[20:21] neg_lo:[0,1] neg_hi:[0,1]
	v_pk_add_f32 v[72:73], v[94:95], v[8:9]
	v_pk_add_f32 v[8:9], v[94:95], v[8:9] neg_lo:[0,1] neg_hi:[0,1]
	v_pk_mul_f32 v[94:95], v[82:83], s[62:63] op_sel:[1,0] op_sel_hi:[0,0] neg_lo:[1,0]
	v_pk_fma_f32 v[82:83], v[82:83], s[60:61], v[94:95] op_sel_hi:[1,0,1]
	v_pk_add_f32 v[94:95], v[98:99], v[82:83]
	v_pk_add_f32 v[82:83], v[98:99], v[82:83] neg_lo:[0,1] neg_hi:[0,1]
	v_pk_mul_f32 v[98:99], v[86:87], s[70:71] op_sel:[1,0] op_sel_hi:[0,0] neg_lo:[1,0]
	v_pk_fma_f32 v[86:87], v[86:87], s[70:71], v[98:99] op_sel_hi:[1,0,1]
	v_pk_add_f32 v[98:99], v[76:77], v[86:87]
	v_pk_add_f32 v[86:87], v[76:77], v[86:87] neg_lo:[0,1] neg_hi:[0,1]
	v_pk_mul_f32 v[76:77], v[26:27], s[60:61] op_sel:[1,0] op_sel_hi:[0,0] neg_lo:[1,0]
	v_pk_fma_f32 v[26:27], v[26:27], s[62:63], v[76:77] op_sel_hi:[1,0,1]
	v_xor_b32_e32 v76, 0x80000000, v67
	v_pk_add_f32 v[100:101], v[18:19], v[26:27]
	v_pk_add_f32 v[26:27], v[18:19], v[26:27] neg_lo:[0,1] neg_hi:[0,1]
	v_pk_add_f32 v[102:103], v[74:75], v[78:79] op_sel:[0,1] op_sel_hi:[1,0] neg_lo:[0,1]
	v_pk_add_f32 v[104:105], v[74:75], v[78:79] op_sel:[0,1] op_sel_hi:[1,0] neg_hi:[0,1]
	v_pk_mul_f32 v[18:19], v[6:7], s[62:63] op_sel_hi:[1,0]
	v_xor_b32_e32 v74, 0x80000000, v7
	v_mov_b32_e32 v75, v6
	v_pk_fma_f32 v[6:7], v[74:75], s[60:61], v[18:19] op_sel_hi:[1,0,1] neg_lo:[0,0,1] neg_hi:[0,0,1]
	v_xor_b32_e32 v74, 0x80000000, v15
	v_pk_add_f32 v[18:19], v[10:11], v[6:7]
	v_pk_add_f32 v[6:7], v[10:11], v[6:7] neg_lo:[0,1] neg_hi:[0,1]
	v_pk_mul_f32 v[10:11], v[14:15], s[70:71] op_sel_hi:[1,0]
	v_mov_b32_e32 v75, v14
	v_pk_fma_f32 v[10:11], v[74:75], s[70:71], v[10:11] op_sel_hi:[1,0,1] neg_lo:[0,0,1] neg_hi:[0,0,1]
	v_xor_b32_e32 v74, 0x80000000, v5
	v_pk_add_f32 v[14:15], v[16:17], v[10:11]
	v_pk_add_f32 v[10:11], v[16:17], v[10:11] neg_lo:[0,1] neg_hi:[0,1]
	v_pk_mul_f32 v[16:17], v[4:5], s[60:61] op_sel_hi:[1,0]
	v_mov_b32_e32 v75, v4
	v_pk_fma_f32 v[4:5], v[74:75], s[62:63], v[16:17] op_sel_hi:[1,0,1] neg_lo:[0,0,1] neg_hi:[0,0,1]
	v_xor_b32_e32 v74, 0x80000000, v89
	v_pk_add_f32 v[16:17], v[0:1], v[4:5]
	v_pk_add_f32 v[106:107], v[0:1], v[4:5] neg_lo:[0,1] neg_hi:[0,1]
	v_pk_add_f32 v[0:1], v[12:13], v[68:69]
	v_pk_add_f32 v[4:5], v[12:13], v[68:69] neg_lo:[0,1] neg_hi:[0,1]
	v_mov_b32_e32 v75, v88
	v_pk_mul_f32 v[12:13], v[96:97], s[62:63] op_sel:[1,0] op_sel_hi:[0,0] neg_lo:[1,0]
	v_pk_mul_f32 v[74:75], v[74:75], s[70:71] op_sel_hi:[1,0]
	v_pk_fma_f32 v[12:13], v[96:97], s[60:61], v[12:13] op_sel_hi:[1,0,1]
	v_pk_fma_f32 v[74:75], v[88:89], s[70:71], v[74:75] op_sel_hi:[1,0,1]
	v_pk_add_f32 v[68:69], v[92:93], v[12:13]
	v_pk_add_f32 v[12:13], v[92:93], v[12:13] neg_lo:[0,1] neg_hi:[0,1]
	v_pk_add_f32 v[88:89], v[64:65], v[74:75]
	v_pk_add_f32 v[92:93], v[64:65], v[74:75] neg_lo:[0,1] neg_hi:[0,1]
	v_pk_mul_f32 v[64:65], v[90:91], s[60:61] op_sel:[1,0] op_sel_hi:[0,0] neg_lo:[1,0]
	v_pk_add_f32 v[78:79], v[72:73], v[0:1]
	v_pk_fma_f32 v[64:65], v[90:91], s[62:63], v[64:65] op_sel_hi:[1,0,1]
	v_pk_add_f32 v[74:75], v[62:63], v[64:65]
	v_pk_add_f32 v[90:91], v[62:63], v[64:65] neg_lo:[0,1] neg_hi:[0,1]
	v_pk_mul_f32 v[0:1], v[68:69], s[58:59] op_sel:[1,0] op_sel_hi:[0,0] neg_lo:[1,0]
	v_pk_add_f32 v[64:65], v[84:85], v[80:81] op_sel:[0,1] op_sel_hi:[1,0] neg_lo:[0,1]
	v_pk_add_f32 v[80:81], v[84:85], v[80:81] op_sel:[0,1] op_sel_hi:[1,0] neg_hi:[0,1]
	v_pk_mul_f32 v[62:63], v[66:67], s[62:63] op_sel_hi:[1,0]
	v_mov_b32_e32 v77, v66
	v_pk_fma_f32 v[0:1], v[68:69], s[46:47], v[0:1] op_sel_hi:[1,0,1]
	v_pk_fma_f32 v[62:63], v[76:77], s[60:61], v[62:63] op_sel_hi:[1,0,1] neg_lo:[0,0,1] neg_hi:[0,0,1]
	v_pk_add_f32 v[76:77], v[94:95], v[0:1]
	v_pk_mul_f32 v[0:1], v[88:89], s[62:63] op_sel:[1,0] op_sel_hi:[0,0] neg_lo:[1,0]
	v_pk_add_f32 v[84:85], v[2:3], v[62:63]
	v_pk_fma_f32 v[0:1], v[88:89], s[60:61], v[0:1] op_sel_hi:[1,0,1]
	v_pk_add_f32 v[2:3], v[2:3], v[62:63] neg_lo:[0,1] neg_hi:[0,1]
	v_pk_add_f32 v[72:73], v[98:99], v[0:1]
	v_pk_mul_f32 v[0:1], v[74:75], s[66:67] op_sel:[1,0] op_sel_hi:[0,0] neg_lo:[1,0]
	v_pk_mul_f32 v[62:63], v[70:71], s[70:71] op_sel_hi:[1,0]
	v_pk_fma_f32 v[0:1], v[74:75], s[64:65], v[0:1] op_sel_hi:[1,0,1]
	v_xor_b32_e32 v66, 0x80000000, v71
	v_pk_add_f32 v[74:75], v[100:101], v[0:1]
	v_pk_mul_f32 v[0:1], v[64:65], s[70:71] op_sel:[1,0] op_sel_hi:[0,0] neg_lo:[1,0]
	v_mov_b32_e32 v67, v70
	v_pk_fma_f32 v[0:1], v[64:65], s[70:71], v[0:1] op_sel_hi:[1,0,1]
	v_pk_fma_f32 v[62:63], v[66:67], s[70:71], v[62:63] op_sel_hi:[1,0,1] neg_lo:[0,0,1] neg_hi:[0,0,1]
	v_pk_add_f32 v[66:67], v[102:103], v[0:1]
	v_pk_mul_f32 v[0:1], v[84:85], s[64:65] op_sel:[1,0] op_sel_hi:[0,0] neg_lo:[1,0]
	v_pk_add_f32 v[70:71], v[22:23], v[62:63]
	v_pk_fma_f32 v[0:1], v[84:85], s[66:67], v[0:1] op_sel_hi:[1,0,1]
	v_pk_add_f32 v[96:97], v[22:23], v[62:63] neg_lo:[0,1] neg_hi:[0,1]
	v_pk_mul_f32 v[22:23], v[20:21], s[60:61] op_sel_hi:[1,0]
	v_pk_add_f32 v[68:69], v[18:19], v[0:1]
	v_pk_fma_f32 v[20:21], v[20:21], s[62:63], v[22:23] op_sel:[1,0,0] op_sel_hi:[0,0,1] neg_lo:[1,0,1] neg_hi:[0,0,1]
	v_pk_mul_f32 v[0:1], v[70:71], s[60:61] op_sel:[1,0] op_sel_hi:[0,0] neg_lo:[1,0]
	v_pk_add_f32 v[22:23], v[24:25], v[20:21]
	v_pk_fma_f32 v[0:1], v[70:71], s[62:63], v[0:1] op_sel_hi:[1,0,1]
	v_pk_add_f32 v[108:109], v[24:25], v[20:21] neg_lo:[0,1] neg_hi:[0,1]
	v_pk_add_f32 v[62:63], v[14:15], v[0:1]
	v_pk_mul_f32 v[0:1], v[22:23], s[46:47] op_sel:[1,0] op_sel_hi:[0,0] neg_lo:[1,0]
	v_pk_fma_f32 v[0:1], v[22:23], s[58:59], v[0:1] op_sel_hi:[1,0,1]
	v_pk_add_f32 v[64:65], v[16:17], v[0:1]
	v_pk_add_f32 v[22:23], v[8:9], v[4:5] op_sel:[0,1] op_sel_hi:[1,0] neg_lo:[0,1]
	v_pk_mul_f32 v[0:1], v[12:13], s[58:59] op_sel_hi:[1,0]
	v_xor_b32_e32 v4, 0x80000000, v13
	v_mov_b32_e32 v5, v12
	v_pk_fma_f32 v[0:1], v[4:5], s[46:47], v[0:1] op_sel_hi:[1,0,1] neg_lo:[0,0,1] neg_hi:[0,0,1]
	v_xor_b32_e32 v4, 0x80000000, v93
	v_pk_add_f32 v[24:25], v[82:83], v[0:1]
	v_pk_mul_f32 v[0:1], v[92:93], s[62:63] op_sel_hi:[1,0]
	v_mov_b32_e32 v5, v92
	v_pk_fma_f32 v[0:1], v[4:5], s[60:61], v[0:1] op_sel_hi:[1,0,1] neg_lo:[0,0,1] neg_hi:[0,0,1]
	v_xor_b32_e32 v4, 0x80000000, v91
	v_pk_add_f32 v[18:19], v[86:87], v[0:1]
	v_pk_mul_f32 v[0:1], v[90:91], s[66:67] op_sel_hi:[1,0]
	v_mov_b32_e32 v5, v90
	v_pk_fma_f32 v[0:1], v[4:5], s[64:65], v[0:1] op_sel_hi:[1,0,1] neg_lo:[0,0,1] neg_hi:[0,0,1]
	v_pk_add_f32 v[20:21], v[26:27], v[0:1]
	v_pk_mul_f32 v[0:1], v[80:81], s[70:71] op_sel_hi:[1,0]
	v_pk_fma_f32 v[0:1], v[80:81], s[70:71], v[0:1] op_sel:[1,0,0] op_sel_hi:[0,0,1] neg_lo:[1,0,1] neg_hi:[0,0,1]
	v_xor_b32_e32 v8, 0x80000000, v3
	v_pk_add_f32 v[4:5], v[104:105], v[0:1]
	v_pk_mul_f32 v[0:1], v[2:3], s[64:65] op_sel_hi:[1,0]
	v_mov_b32_e32 v9, v2
	v_pk_fma_f32 v[0:1], v[8:9], s[66:67], v[0:1] op_sel_hi:[1,0,1] neg_lo:[0,0,1] neg_hi:[0,0,1]
	v_pk_add_f32 v[6:7], v[6:7], v[0:1]
	v_pk_mul_f32 v[0:1], v[96:97], s[60:61] op_sel_hi:[1,0]
	v_pk_fma_f32 v[0:1], v[96:97], s[62:63], v[0:1] op_sel:[1,0,0] op_sel_hi:[0,0,1] neg_lo:[1,0,1] neg_hi:[0,0,1]
	v_pk_mul_f32 v[2:3], v[108:109], s[46:47] op_sel_hi:[1,0]
	v_pk_add_f32 v[0:1], v[10:11], v[0:1]
	v_xor_b32_e32 v8, 0x80000000, v109
	v_mov_b32_e32 v9, v108
	v_mov_b32_e32 v10, v146
	v_pk_fma_f32 v[2:3], v[8:9], s[58:59], v[2:3] op_sel_hi:[1,0,1] neg_lo:[0,0,1] neg_hi:[0,0,1]
	v_mov_b32_e32 v8, v221
	s_movk_i32 s0, 0x200
	s_cselect_b32 s4, s0, 0x400
	s_add_i32 s0, s4, s68
	s_ashr_i32 s1, s0, 31
	s_lshl_b32 s6, s4, 2
	s_add_u32 s4, s90, s6
	s_addc_u32 s5, s91, 0
	s_lshl_b64 s[0:1], s[0:1], 14
	v_min_i32_e32 v70, 0x1ffe, v10
	v_mov_b32_e32 v9, s6
	s_add_u32 s36, s26, s0
	v_ashrrev_i32_e32 v11, 31, v10
	v_ashrrev_i32_e32 v71, 31, v70
	v_mov_b32_e32 v16, v222
	v_mov_b32_e32 v14, v223
	v_mov_b32_e32 v17, v224
	v_mov_b32_e32 v12, v225
	s_addc_u32 s37, s27, s1
	v_max_i32_e32 v9, 1, v10
	v_lshlrev_b64 v[82:83], 1, v[10:11]
	v_lshlrev_b64 v[84:85], 1, v[70:71]
	v_lshl_add_u64 v[26:27], s[36:37], 0, v[82:83]
	v_lshlrev_b32_e32 v9, 1, v9
	v_lshl_add_u64 v[70:71], s[36:37], 0, v[84:85]
	v_mov_b32_e32 v13, v226
	s_add_u32 s88, s30, s0
	v_mov_b32_e32 v70, v227
	s_addc_u32 s89, s31, s1
	v_mov_b32_e32 v15, v228
	v_cmp_lt_i32_e64 s[0:1], 0, v10
	v_cmp_gt_i32_e64 s[4:5], s74, v10
	v_pk_add_f32 v[2:3], v[106:107], v[2:3]
	v_cndmask_b32_e64 v81, 0, 1.0, s[0:1]
	v_cndmask_b32_e64 v86, 0, 1.0, s[4:5]
	v_add_u32_e32 v92, 0x200, v10
	v_cmp_lt_i32_e64 s[20:21], s25, v10
	v_cmp_gt_i32_e64 s[18:19], s42, v10
	v_add_u32_e32 v90, 0x400, v10
	v_cmp_lt_i32_e64 s[16:17], s33, v10
	v_cmp_gt_i32_e64 s[0:1], s51, v10
	v_add_u32_e32 v88, 0x600, v10
	v_cmp_lt_i32_e64 s[12:13], s43, v10
	v_cmp_gt_i32_e64 s[10:11], s50, v10
	v_cmp_lt_i32_e64 s[8:9], s2, v10
	v_cmp_gt_i32_e64 s[6:7], s38, v10
	v_cmp_lt_i32_e64 s[4:5], s65, v10
	v_cmp_gt_i32_e64 s[22:23], s34, v10
	s_waitcnt vmcnt(2)
	v_lshlrev_b32_e32 v13, 16, v13
	s_waitcnt vmcnt(1)
	v_lshlrev_b32_e32 v70, 16, v70
	v_mul_f32_e32 v70, v86, v70
	s_waitcnt vmcnt(0)
	v_lshlrev_b32_e32 v15, 16, v15
	v_mul_f32_e32 v15, v81, v15
	v_mul_f32_e32 v15, v16, v15
	v_fmac_f32_e32 v15, v14, v13
	v_fmac_f32_e32 v15, v17, v70
	v_lshl_add_u64 v[70:71], s[88:89], 0, v[82:83]
	v_lshl_add_u64 v[82:83], s[88:89], 0, v[84:85]
	v_add_f32_e32 v80, v12, v15
	v_mov_b32_e32 v13, v229
	v_mov_b32_e32 v15, v230
	v_add_u32_e32 v84, 0x800, v10
	v_mov_b32_e32 v9, v231
	v_add_u32_e32 v82, 0xa00, v10
	s_waitcnt vmcnt(2)
	v_lshlrev_b32_e32 v13, 16, v13
	s_waitcnt vmcnt(1)
	v_lshlrev_b32_e32 v15, 16, v15
	v_mul_f32_e32 v15, v86, v15
	s_waitcnt vmcnt(0)
	v_lshlrev_b32_e32 v9, 16, v9
	v_mul_f32_e32 v9, v81, v9
	v_mul_f32_e32 v9, v16, v9
	v_fmac_f32_e32 v9, v14, v13
	v_fmac_f32_e32 v9, v17, v15
	v_add_f32_e32 v86, v12, v9
	s_cbranch_vccnz .LBB0_540
	v_readlane_b32 s98, v252, 56
	s_lshl_b64 s[0:1], s[92:93], 1
	s_add_u32 s4, s0, s30
	s_addc_u32 s5, s1, s31
	s_add_u32 s0, s0, s26
	s_addc_u32 s1, s1, s27
	s_add_u32 s18, s96, 0x800000
	s_addc_u32 s19, s97, 0
	s_cmpk_gt_i32 s98, 0xff
	s_cbranch_scc1 .Lhy_ep1_comb_L0
	v_lshlrev_b32_e32 v109, 1, v10
	v_add_u32_e32 v254, 0x1e00, v10
	v_add_u32_e32 v253, 0x1000, v109
	v_cmp_gt_i32_e32 vcc, 0x1fff, v254
	v_add_u32_e32 v251, 0x2000, v109
	v_add_u32_e32 v250, 0x3000, v109
	v_min_i32_e32 v254, 0x1ffe, v254
	v_cndmask_b32_e64 v255, 0, 1.0, vcc
	v_lshlrev_b32_e32 v254, 1, v254
	global_load_ushort v9, v109, s[0:1]
	global_load_ushort v11, v109, s[4:5]
	global_load_ushort v13, v109, s[36:37] offset:1022
	global_load_ushort v15, v109, s[36:37] offset:1024
	global_load_ushort v81, v109, s[36:37] offset:1026
	global_load_ushort v83, v109, s[88:89] offset:1022
	global_load_ushort v85, v109, s[88:89] offset:1024
	global_load_ushort v87, v109, s[88:89] offset:1026
	global_load_ushort v89, v109, s[0:1] offset:1024
	global_load_ushort v91, v109, s[4:5] offset:1024
	global_load_ushort v93, v109, s[36:37] offset:2046
	global_load_ushort v94, v109, s[36:37] offset:2048
	global_load_ushort v95, v109, s[36:37] offset:2050
	global_load_ushort v96, v109, s[88:89] offset:2046
	global_load_ushort v97, v109, s[88:89] offset:2048
	global_load_ushort v98, v109, s[88:89] offset:2050
	global_load_ushort v99, v109, s[0:1] offset:2048
	global_load_ushort v100, v109, s[4:5] offset:2048
	global_load_ushort v101, v109, s[36:37] offset:3070
	global_load_ushort v102, v109, s[36:37] offset:3072
	global_load_ushort v103, v109, s[36:37] offset:3074
	global_load_ushort v104, v109, s[88:89] offset:3070
	global_load_ushort v105, v109, s[88:89] offset:3072
	global_load_ushort v106, v109, s[88:89] offset:3074
	global_load_ushort v107, v109, s[0:1] offset:3072
	global_load_ushort v108, v109, s[4:5] offset:3072
	global_load_ushort v111, v253, s[36:37] offset:-2
	global_load_ushort v112, v253, s[36:37]
	global_load_ushort v113, v253, s[36:37] offset:2
	global_load_ushort v114, v253, s[88:89] offset:-2
	global_load_ushort v115, v253, s[88:89]
	global_load_ushort v116, v253, s[88:89] offset:2
	global_load_ushort v117, v253, s[0:1]
	global_load_ushort v118, v253, s[4:5]
	global_load_ushort v119, v253, s[36:37] offset:1022
	global_load_ushort v120, v253, s[36:37] offset:1024
	global_load_ushort v121, v253, s[36:37] offset:1026
	global_load_ushort v122, v253, s[88:89] offset:1022
	global_load_ushort v123, v253, s[88:89] offset:1024
	global_load_ushort v124, v253, s[88:89] offset:1026
	global_load_ushort v125, v253, s[0:1] offset:1024
	global_load_ushort v126, v253, s[4:5] offset:1024
	global_load_ushort v127, v253, s[36:37] offset:2046
	global_load_ushort v128, v253, s[36:37] offset:2048
	global_load_ushort v129, v253, s[36:37] offset:2050
	global_load_ushort v130, v253, s[88:89] offset:2046
	global_load_ushort v131, v253, s[88:89] offset:2048
	global_load_ushort v132, v253, s[88:89] offset:2050
	global_load_ushort v133, v253, s[0:1] offset:2048
	global_load_ushort v134, v253, s[4:5] offset:2048
	global_load_ushort v135, v253, s[36:37] offset:3070
	global_load_ushort v136, v253, s[36:37] offset:3072
	global_load_ushort v137, v253, s[36:37] offset:3074
	global_load_ushort v138, v253, s[88:89] offset:3070
	global_load_ushort v139, v253, s[88:89] offset:3072
	global_load_ushort v140, v253, s[88:89] offset:3074
	global_load_ushort v141, v253, s[0:1] offset:3072
	global_load_ushort v142, v253, s[4:5] offset:3072
	global_load_ushort v143, v251, s[36:37] offset:-2
	global_load_ushort v163, v251, s[36:37]
	global_load_ushort v164, v251, s[36:37] offset:2
	global_load_ushort v165, v251, s[88:89] offset:-2
	global_load_ushort v166, v251, s[88:89]
	global_load_ushort v167, v251, s[88:89] offset:2
	global_load_ushort v168, v251, s[0:1]
	global_load_ushort v169, v251, s[4:5]
	global_load_ushort v170, v251, s[36:37] offset:1022
	global_load_ushort v171, v251, s[36:37] offset:1024
	global_load_ushort v172, v251, s[36:37] offset:1026
	global_load_ushort v173, v251, s[88:89] offset:1022
	global_load_ushort v174, v251, s[88:89] offset:1024
	global_load_ushort v175, v251, s[88:89] offset:1026
	global_load_ushort v176, v251, s[0:1] offset:1024
	global_load_ushort v177, v251, s[4:5] offset:1024
	global_load_ushort v178, v251, s[36:37] offset:2046
	global_load_ushort v179, v251, s[36:37] offset:2048
	global_load_ushort v180, v251, s[36:37] offset:2050
	global_load_ushort v181, v251, s[88:89] offset:2046
	global_load_ushort v182, v251, s[88:89] offset:2048
	global_load_ushort v183, v251, s[88:89] offset:2050
	global_load_ushort v184, v251, s[0:1] offset:2048
	global_load_ushort v185, v251, s[4:5] offset:2048
	global_load_ushort v186, v251, s[36:37] offset:3070
	global_load_ushort v187, v251, s[36:37] offset:3072
	global_load_ushort v188, v251, s[36:37] offset:3074
	global_load_ushort v189, v251, s[88:89] offset:3070
	global_load_ushort v190, v251, s[88:89] offset:3072
	global_load_ushort v191, v251, s[88:89] offset:3074
	global_load_ushort v192, v251, s[0:1] offset:3072
	global_load_ushort v193, v251, s[4:5] offset:3072
	global_load_ushort v194, v250, s[36:37] offset:-2
	global_load_ushort v195, v250, s[36:37]
	global_load_ushort v196, v250, s[36:37] offset:2
	global_load_ushort v197, v250, s[88:89] offset:-2
	global_load_ushort v221, v250, s[88:89]
	global_load_ushort v222, v250, s[88:89] offset:2
	global_load_ushort v223, v250, s[0:1]
	global_load_ushort v224, v250, s[4:5]
	global_load_ushort v225, v250, s[36:37] offset:1022
	global_load_ushort v226, v250, s[36:37] offset:1024
	global_load_ushort v227, v250, s[36:37] offset:1026
	global_load_ushort v228, v250, s[88:89] offset:1022
	global_load_ushort v229, v250, s[88:89] offset:1024
	global_load_ushort v230, v250, s[88:89] offset:1026
	global_load_ushort v231, v250, s[0:1] offset:1024
	global_load_ushort v232, v250, s[4:5] offset:1024
	global_load_ushort v233, v250, s[36:37] offset:2046
	global_load_ushort v234, v250, s[36:37] offset:2048
	global_load_ushort v235, v250, s[36:37] offset:2050
	global_load_ushort v236, v250, s[88:89] offset:2046
	global_load_ushort v237, v250, s[88:89] offset:2048
	global_load_ushort v238, v250, s[88:89] offset:2050
	global_load_ushort v239, v250, s[0:1] offset:2048
	global_load_ushort v240, v250, s[4:5] offset:2048
	global_load_ushort v241, v250, s[36:37] offset:3070
	global_load_ushort v242, v250, s[36:37] offset:3072
	global_load_ushort v243, v254, s[36:37] offset:2
	global_load_ushort v244, v250, s[88:89] offset:3070
	global_load_ushort v245, v250, s[88:89] offset:3072
	global_load_ushort v246, v254, s[88:89] offset:2
	global_load_ushort v247, v250, s[0:1] offset:3072
	global_load_ushort v248, v250, s[4:5] offset:3072
	s_waitcnt vmcnt(63)
	v_fma_f32 v27, v32, v8, v78
	v_mul_f32_e32 v70, v80, v27
	v_lshlrev_b32_e32 v9, 16, v9
	v_mul_f32_e32 v84, 0xbfb8aa3b, v9
	v_exp_f32_e32 v84, v84
	s_nop 0
	v_add_f32_e32 v84, 1.0, v84
	v_div_scale_f32 v71, s[28:29], v84, v84, v9
	v_rcp_f32_e32 v82, v71
	s_nop 0
	v_fma_f32 v92, -v71, v82, 1.0
	v_fmac_f32_e32 v82, v92, v82
	v_div_scale_f32 v88, vcc, v9, v84, v9
	v_mul_f32_e32 v90, v88, v82
	v_fma_f32 v92, -v71, v90, v88
	v_fmac_f32_e32 v90, v92, v82
	v_fma_f32 v71, -v71, v90, v88
	v_div_fmas_f32 v71, v71, v82, v90
	v_div_fixup_f32 v9, v71, v84, v9
	v_mul_f32_e32 v70, v70, v9
	v_fma_f32 v27, v34, v8, v79
	v_mul_f32_e32 v110, v86, v27
	v_lshlrev_b32_e32 v11, 16, v11
	v_mul_f32_e32 v84, 0xbfb8aa3b, v11
	v_exp_f32_e32 v84, v84
	s_nop 0
	v_add_f32_e32 v84, 1.0, v84
	v_div_scale_f32 v71, s[28:29], v84, v84, v11
	v_rcp_f32_e32 v82, v71
	s_nop 0
	v_fma_f32 v92, -v71, v82, 1.0
	v_fmac_f32_e32 v82, v92, v82
	v_div_scale_f32 v88, vcc, v11, v84, v11
	v_mul_f32_e32 v90, v88, v82
	v_fma_f32 v92, -v71, v90, v88
	v_fmac_f32_e32 v90, v92, v82
	v_fma_f32 v71, -v71, v90, v88
	v_div_fmas_f32 v71, v71, v82, v90
	v_div_fixup_f32 v11, v71, v84, v11
	v_mul_f32_e32 v110, v110, v11
	v_cvt_pk_bf16_f32 v198, v70, v110
	v_lshlrev_b32_e32 v15, 16, v15
	v_lshlrev_b32_e32 v81, 16, v81
	v_lshlrev_b32_e32 v13, 16, v13
	v_mul_f32_e32 v13, v16, v13
	v_fmac_f32_e32 v13, v14, v15
	v_fmac_f32_e32 v13, v17, v81
	v_add_f32_e32 v13, v12, v13
	v_fma_f32 v27, v33, v8, v76
	v_mul_f32_e32 v70, v27, v13
	v_lshlrev_b32_e32 v89, 16, v89
	v_mul_f32_e32 v84, 0xbfb8aa3b, v89
	v_exp_f32_e32 v84, v84
	s_nop 0
	v_add_f32_e32 v84, 1.0, v84
	v_div_scale_f32 v71, s[28:29], v84, v84, v89
	v_rcp_f32_e32 v82, v71
	s_nop 0
	v_fma_f32 v92, -v71, v82, 1.0
	v_fmac_f32_e32 v82, v92, v82
	v_div_scale_f32 v88, vcc, v89, v84, v89
	v_mul_f32_e32 v90, v88, v82
	v_fma_f32 v92, -v71, v90, v88
	v_fmac_f32_e32 v90, v92, v82
	v_fma_f32 v71, -v71, v90, v88
	v_div_fmas_f32 v71, v71, v82, v90
	v_div_fixup_f32 v89, v71, v84, v89
	v_mul_f32_e32 v70, v70, v89
	v_lshlrev_b32_e32 v85, 16, v85
	v_lshlrev_b32_e32 v87, 16, v87
	v_lshlrev_b32_e32 v83, 16, v83
	v_mul_f32_e32 v83, v16, v83
	v_fmac_f32_e32 v83, v14, v85
	v_fmac_f32_e32 v83, v17, v87
	v_add_f32_e32 v83, v12, v83
	v_fma_f32 v27, v35, v8, v77
	v_mul_f32_e32 v110, v27, v83
	v_lshlrev_b32_e32 v91, 16, v91
	v_mul_f32_e32 v84, 0xbfb8aa3b, v91
	v_exp_f32_e32 v84, v84
	s_nop 0
	v_add_f32_e32 v84, 1.0, v84
	v_div_scale_f32 v71, s[28:29], v84, v84, v91
	v_rcp_f32_e32 v82, v71
	s_nop 0
	v_fma_f32 v92, -v71, v82, 1.0
	v_fmac_f32_e32 v82, v92, v82
	v_div_scale_f32 v88, vcc, v91, v84, v91
	v_mul_f32_e32 v90, v88, v82
	v_fma_f32 v92, -v71, v90, v88
	v_fmac_f32_e32 v90, v92, v82
	v_fma_f32 v71, -v71, v90, v88
	v_div_fmas_f32 v71, v71, v82, v90
	v_div_fixup_f32 v91, v71, v84, v91
	v_mul_f32_e32 v110, v110, v91
	v_cvt_pk_bf16_f32 v199, v70, v110
	v_lshlrev_b32_e32 v94, 16, v94
	v_lshlrev_b32_e32 v95, 16, v95
	v_lshlrev_b32_e32 v93, 16, v93
	v_mul_f32_e32 v93, v16, v93
	v_fmac_f32_e32 v93, v14, v94
	v_fmac_f32_e32 v93, v17, v95
	v_add_f32_e32 v93, v12, v93
	v_fma_f32 v27, v37, v8, v72
	v_mul_f32_e32 v70, v27, v93
	v_lshlrev_b32_e32 v99, 16, v99
	v_mul_f32_e32 v84, 0xbfb8aa3b, v99
	v_exp_f32_e32 v84, v84
	s_nop 0
	v_add_f32_e32 v84, 1.0, v84
	v_div_scale_f32 v71, s[28:29], v84, v84, v99
	v_rcp_f32_e32 v82, v71
	s_nop 0
	v_fma_f32 v92, -v71, v82, 1.0
	v_fmac_f32_e32 v82, v92, v82
	v_div_scale_f32 v88, vcc, v99, v84, v99
	v_mul_f32_e32 v90, v88, v82
	v_fma_f32 v92, -v71, v90, v88
	v_fmac_f32_e32 v90, v92, v82
	v_fma_f32 v71, -v71, v90, v88
	v_div_fmas_f32 v71, v71, v82, v90
	v_div_fixup_f32 v99, v71, v84, v99
	v_mul_f32_e32 v70, v70, v99
	v_lshlrev_b32_e32 v97, 16, v97
	v_lshlrev_b32_e32 v98, 16, v98
	v_lshlrev_b32_e32 v96, 16, v96
	v_mul_f32_e32 v96, v16, v96
	v_fmac_f32_e32 v96, v14, v97
	v_fmac_f32_e32 v96, v17, v98
	v_add_f32_e32 v96, v12, v96
	v_fma_f32 v27, v31, v8, v73
	v_mul_f32_e32 v110, v27, v96
	v_lshlrev_b32_e32 v100, 16, v100
	v_mul_f32_e32 v84, 0xbfb8aa3b, v100
	v_exp_f32_e32 v84, v84
	s_nop 0
	v_add_f32_e32 v84, 1.0, v84
	v_div_scale_f32 v71, s[28:29], v84, v84, v100
	v_rcp_f32_e32 v82, v71
	s_nop 0
	v_fma_f32 v92, -v71, v82, 1.0
	v_fmac_f32_e32 v82, v92, v82
	v_div_scale_f32 v88, vcc, v100, v84, v100
	v_mul_f32_e32 v90, v88, v82
	v_fma_f32 v92, -v71, v90, v88
	v_fmac_f32_e32 v90, v92, v82
	v_fma_f32 v71, -v71, v90, v88
	v_div_fmas_f32 v71, v71, v82, v90
	v_div_fixup_f32 v100, v71, v84, v100
	v_mul_f32_e32 v110, v110, v100
	v_cvt_pk_bf16_f32 v200, v70, v110
	v_lshlrev_b32_e32 v102, 16, v102
	v_lshlrev_b32_e32 v103, 16, v103
	v_lshlrev_b32_e32 v101, 16, v101
	v_mul_f32_e32 v101, v16, v101
	v_fmac_f32_e32 v101, v14, v102
	v_fmac_f32_e32 v101, v17, v103
	v_add_f32_e32 v101, v12, v101
	v_fma_f32 v27, v36, v8, v74
	v_mul_f32_e32 v70, v27, v101
	v_lshlrev_b32_e32 v107, 16, v107
	v_mul_f32_e32 v84, 0xbfb8aa3b, v107
	v_exp_f32_e32 v84, v84
	s_nop 0
	v_add_f32_e32 v84, 1.0, v84
	v_div_scale_f32 v71, s[28:29], v84, v84, v107
	v_rcp_f32_e32 v82, v71
	s_nop 0
	v_fma_f32 v92, -v71, v82, 1.0
	v_fmac_f32_e32 v82, v92, v82
	v_div_scale_f32 v88, vcc, v107, v84, v107
	v_mul_f32_e32 v90, v88, v82
	v_fma_f32 v92, -v71, v90, v88
	v_fmac_f32_e32 v90, v92, v82
	v_fma_f32 v71, -v71, v90, v88
	v_div_fmas_f32 v71, v71, v82, v90
	v_div_fixup_f32 v107, v71, v84, v107
	v_mul_f32_e32 v70, v70, v107
	v_lshlrev_b32_e32 v105, 16, v105
	v_lshlrev_b32_e32 v106, 16, v106
	v_lshlrev_b32_e32 v104, 16, v104
	v_mul_f32_e32 v104, v16, v104
	v_fmac_f32_e32 v104, v14, v105
	v_fmac_f32_e32 v104, v17, v106
	v_add_f32_e32 v104, v12, v104
	v_fma_f32 v27, v30, v8, v75
	v_mul_f32_e32 v110, v27, v104
	v_lshlrev_b32_e32 v108, 16, v108
	v_mul_f32_e32 v84, 0xbfb8aa3b, v108
	v_exp_f32_e32 v84, v84
	s_nop 0
	v_add_f32_e32 v84, 1.0, v84
	v_div_scale_f32 v71, s[28:29], v84, v84, v108
	v_rcp_f32_e32 v82, v71
	s_nop 0
	v_fma_f32 v92, -v71, v82, 1.0
	v_fmac_f32_e32 v82, v92, v82
	v_div_scale_f32 v88, vcc, v108, v84, v108
	v_mul_f32_e32 v90, v88, v82
	v_fma_f32 v92, -v71, v90, v88
	v_fmac_f32_e32 v90, v92, v82
	v_fma_f32 v71, -v71, v90, v88
	v_div_fmas_f32 v71, v71, v82, v90
	v_div_fixup_f32 v108, v71, v84, v108
	v_mul_f32_e32 v110, v110, v108
	v_cvt_pk_bf16_f32 v201, v70, v110
	s_waitcnt vmcnt(63)
	v_lshlrev_b32_e32 v112, 16, v112
	v_lshlrev_b32_e32 v113, 16, v113
	v_lshlrev_b32_e32 v111, 16, v111
	v_mul_f32_e32 v111, v16, v111
	v_fmac_f32_e32 v111, v14, v112
	v_fmac_f32_e32 v111, v17, v113
	v_add_f32_e32 v111, v12, v111
	v_fma_f32 v27, v39, v8, v66
	v_mul_f32_e32 v70, v27, v111
	v_lshlrev_b32_e32 v117, 16, v117
	v_mul_f32_e32 v84, 0xbfb8aa3b, v117
	v_exp_f32_e32 v84, v84
	s_nop 0
	v_add_f32_e32 v84, 1.0, v84
	v_div_scale_f32 v71, s[28:29], v84, v84, v117
	v_rcp_f32_e32 v82, v71
	s_nop 0
	v_fma_f32 v92, -v71, v82, 1.0
	v_fmac_f32_e32 v82, v92, v82
	v_div_scale_f32 v88, vcc, v117, v84, v117
	v_mul_f32_e32 v90, v88, v82
	v_fma_f32 v92, -v71, v90, v88
	v_fmac_f32_e32 v90, v92, v82
	v_fma_f32 v71, -v71, v90, v88
	v_div_fmas_f32 v71, v71, v82, v90
	v_div_fixup_f32 v117, v71, v84, v117
	v_mul_f32_e32 v70, v70, v117
	v_lshlrev_b32_e32 v115, 16, v115
	v_lshlrev_b32_e32 v116, 16, v116
	v_lshlrev_b32_e32 v114, 16, v114
	v_mul_f32_e32 v114, v16, v114
	v_fmac_f32_e32 v114, v14, v115
	v_fmac_f32_e32 v114, v17, v116
	v_add_f32_e32 v114, v12, v114
	v_fma_f32 v27, v41, v8, v67
	v_mul_f32_e32 v110, v27, v114
	v_lshlrev_b32_e32 v118, 16, v118
	v_mul_f32_e32 v84, 0xbfb8aa3b, v118
	v_exp_f32_e32 v84, v84
	s_nop 0
	v_add_f32_e32 v84, 1.0, v84
	v_div_scale_f32 v71, s[28:29], v84, v84, v118
	v_rcp_f32_e32 v82, v71
	s_nop 0
	v_fma_f32 v92, -v71, v82, 1.0
	v_fmac_f32_e32 v82, v92, v82
	v_div_scale_f32 v88, vcc, v118, v84, v118
	v_mul_f32_e32 v90, v88, v82
	v_fma_f32 v92, -v71, v90, v88
	v_fmac_f32_e32 v90, v92, v82
	v_fma_f32 v71, -v71, v90, v88
	v_div_fmas_f32 v71, v71, v82, v90
	v_div_fixup_f32 v118, v71, v84, v118
	v_mul_f32_e32 v110, v110, v118
	v_cvt_pk_bf16_f32 v202, v70, v110
	v_lshlrev_b32_e32 v120, 16, v120
	v_lshlrev_b32_e32 v121, 16, v121
	v_lshlrev_b32_e32 v119, 16, v119
	v_mul_f32_e32 v119, v16, v119
	v_fmac_f32_e32 v119, v14, v120
	v_fmac_f32_e32 v119, v17, v121
	v_add_f32_e32 v119, v12, v119
	v_fma_f32 v27, v38, v8, v68
	v_mul_f32_e32 v70, v27, v119
	v_lshlrev_b32_e32 v125, 16, v125
	v_mul_f32_e32 v84, 0xbfb8aa3b, v125
	v_exp_f32_e32 v84, v84
	s_nop 0
	v_add_f32_e32 v84, 1.0, v84
	v_div_scale_f32 v71, s[28:29], v84, v84, v125
	v_rcp_f32_e32 v82, v71
	s_nop 0
	v_fma_f32 v92, -v71, v82, 1.0
	v_fmac_f32_e32 v82, v92, v82
	v_div_scale_f32 v88, vcc, v125, v84, v125
	v_mul_f32_e32 v90, v88, v82
	v_fma_f32 v92, -v71, v90, v88
	v_fmac_f32_e32 v90, v92, v82
	v_fma_f32 v71, -v71, v90, v88
	v_div_fmas_f32 v71, v71, v82, v90
	v_div_fixup_f32 v125, v71, v84, v125
	v_mul_f32_e32 v70, v70, v125
	v_lshlrev_b32_e32 v123, 16, v123
	v_lshlrev_b32_e32 v124, 16, v124
	v_lshlrev_b32_e32 v122, 16, v122
	v_mul_f32_e32 v122, v16, v122
	v_fmac_f32_e32 v122, v14, v123
	v_fmac_f32_e32 v122, v17, v124
	v_add_f32_e32 v122, v12, v122
	v_fma_f32 v27, v40, v8, v69
	v_mul_f32_e32 v110, v27, v122
	v_lshlrev_b32_e32 v126, 16, v126
	v_mul_f32_e32 v84, 0xbfb8aa3b, v126
	v_exp_f32_e32 v84, v84
	s_nop 0
	v_add_f32_e32 v84, 1.0, v84
	v_div_scale_f32 v71, s[28:29], v84, v84, v126
	v_rcp_f32_e32 v82, v71
	s_nop 0
	v_fma_f32 v92, -v71, v82, 1.0
	v_fmac_f32_e32 v82, v92, v82
	v_div_scale_f32 v88, vcc, v126, v84, v126
	v_mul_f32_e32 v90, v88, v82
	v_fma_f32 v92, -v71, v90, v88
	v_fmac_f32_e32 v90, v92, v82
	v_fma_f32 v71, -v71, v90, v88
	v_div_fmas_f32 v71, v71, v82, v90
	v_div_fixup_f32 v126, v71, v84, v126
	v_mul_f32_e32 v110, v110, v126
	v_cvt_pk_bf16_f32 v203, v70, v110
	v_lshlrev_b32_e32 v128, 16, v128
	v_lshlrev_b32_e32 v129, 16, v129
	v_lshlrev_b32_e32 v127, 16, v127
	v_mul_f32_e32 v127, v16, v127
	v_fmac_f32_e32 v127, v14, v128
	v_fmac_f32_e32 v127, v17, v129
	v_add_f32_e32 v127, v12, v127
	v_fma_f32 v27, v43, v8, v62
	v_mul_f32_e32 v70, v27, v127
	v_lshlrev_b32_e32 v133, 16, v133
	v_mul_f32_e32 v84, 0xbfb8aa3b, v133
	v_exp_f32_e32 v84, v84
	s_nop 0
	v_add_f32_e32 v84, 1.0, v84
	v_div_scale_f32 v71, s[28:29], v84, v84, v133
	v_rcp_f32_e32 v82, v71
	s_nop 0
	v_fma_f32 v92, -v71, v82, 1.0
	v_fmac_f32_e32 v82, v92, v82
	v_div_scale_f32 v88, vcc, v133, v84, v133
	v_mul_f32_e32 v90, v88, v82
	v_fma_f32 v92, -v71, v90, v88
	v_fmac_f32_e32 v90, v92, v82
	v_fma_f32 v71, -v71, v90, v88
	v_div_fmas_f32 v71, v71, v82, v90
	v_div_fixup_f32 v133, v71, v84, v133
	v_mul_f32_e32 v70, v70, v133
	v_lshlrev_b32_e32 v131, 16, v131
	v_lshlrev_b32_e32 v132, 16, v132
	v_lshlrev_b32_e32 v130, 16, v130
	v_mul_f32_e32 v130, v16, v130
	v_fmac_f32_e32 v130, v14, v131
	v_fmac_f32_e32 v130, v17, v132
	v_add_f32_e32 v130, v12, v130
	v_fma_f32 v27, v45, v8, v63
	v_mul_f32_e32 v110, v27, v130
	v_lshlrev_b32_e32 v134, 16, v134
	v_mul_f32_e32 v84, 0xbfb8aa3b, v134
	v_exp_f32_e32 v84, v84
	s_nop 0
	v_add_f32_e32 v84, 1.0, v84
	v_div_scale_f32 v71, s[28:29], v84, v84, v134
	v_rcp_f32_e32 v82, v71
	s_nop 0
	v_fma_f32 v92, -v71, v82, 1.0
	v_fmac_f32_e32 v82, v92, v82
	v_div_scale_f32 v88, vcc, v134, v84, v134
	v_mul_f32_e32 v90, v88, v82
	v_fma_f32 v92, -v71, v90, v88
	v_fmac_f32_e32 v90, v92, v82
	v_fma_f32 v71, -v71, v90, v88
	v_div_fmas_f32 v71, v71, v82, v90
	v_div_fixup_f32 v134, v71, v84, v134
	v_mul_f32_e32 v110, v110, v134
	v_cvt_pk_bf16_f32 v204, v70, v110
	v_lshlrev_b32_e32 v136, 16, v136
	v_lshlrev_b32_e32 v137, 16, v137
	v_lshlrev_b32_e32 v135, 16, v135
	v_mul_f32_e32 v135, v16, v135
	v_fmac_f32_e32 v135, v14, v136
	v_fmac_f32_e32 v135, v17, v137
	v_add_f32_e32 v135, v12, v135
	v_fma_f32 v27, v42, v8, v64
	v_mul_f32_e32 v70, v27, v135
	v_lshlrev_b32_e32 v141, 16, v141
	v_mul_f32_e32 v84, 0xbfb8aa3b, v141
	v_exp_f32_e32 v84, v84
	s_nop 0
	v_add_f32_e32 v84, 1.0, v84
	v_div_scale_f32 v71, s[28:29], v84, v84, v141
	v_rcp_f32_e32 v82, v71
	s_nop 0
	v_fma_f32 v92, -v71, v82, 1.0
	v_fmac_f32_e32 v82, v92, v82
	v_div_scale_f32 v88, vcc, v141, v84, v141
	v_mul_f32_e32 v90, v88, v82
	v_fma_f32 v92, -v71, v90, v88
	v_fmac_f32_e32 v90, v92, v82
	v_fma_f32 v71, -v71, v90, v88
	v_div_fmas_f32 v71, v71, v82, v90
	v_div_fixup_f32 v141, v71, v84, v141
	v_mul_f32_e32 v70, v70, v141
	v_lshlrev_b32_e32 v139, 16, v139
	v_lshlrev_b32_e32 v140, 16, v140
	v_lshlrev_b32_e32 v138, 16, v138
	v_mul_f32_e32 v138, v16, v138
	v_fmac_f32_e32 v138, v14, v139
	v_fmac_f32_e32 v138, v17, v140
	v_add_f32_e32 v138, v12, v138
	v_fma_f32 v27, v44, v8, v65
	v_mul_f32_e32 v110, v27, v138
	v_lshlrev_b32_e32 v142, 16, v142
	v_mul_f32_e32 v84, 0xbfb8aa3b, v142
	v_exp_f32_e32 v84, v84
	s_nop 0
	v_add_f32_e32 v84, 1.0, v84
	v_div_scale_f32 v71, s[28:29], v84, v84, v142
	v_rcp_f32_e32 v82, v71
	s_nop 0
	v_fma_f32 v92, -v71, v82, 1.0
	v_fmac_f32_e32 v82, v92, v82
	v_div_scale_f32 v88, vcc, v142, v84, v142
	v_mul_f32_e32 v90, v88, v82
	v_fma_f32 v92, -v71, v90, v88
	v_fmac_f32_e32 v90, v92, v82
	v_fma_f32 v71, -v71, v90, v88
	v_div_fmas_f32 v71, v71, v82, v90
	v_div_fixup_f32 v142, v71, v84, v142
	v_mul_f32_e32 v110, v110, v142
	v_cvt_pk_bf16_f32 v205, v70, v110
	s_waitcnt vmcnt(32)
	v_lshlrev_b32_e32 v163, 16, v163
	v_lshlrev_b32_e32 v164, 16, v164
	v_lshlrev_b32_e32 v143, 16, v143
	v_mul_f32_e32 v143, v16, v143
	v_fmac_f32_e32 v143, v14, v163
	v_fmac_f32_e32 v143, v17, v164
	v_add_f32_e32 v143, v12, v143
	v_fma_f32 v27, v47, v8, v22
	v_mul_f32_e32 v70, v27, v143
	v_lshlrev_b32_e32 v168, 16, v168
	v_mul_f32_e32 v84, 0xbfb8aa3b, v168
	v_exp_f32_e32 v84, v84
	s_nop 0
	v_add_f32_e32 v84, 1.0, v84
	v_div_scale_f32 v71, s[28:29], v84, v84, v168
	v_rcp_f32_e32 v82, v71
	s_nop 0
	v_fma_f32 v92, -v71, v82, 1.0
	v_fmac_f32_e32 v82, v92, v82
	v_div_scale_f32 v88, vcc, v168, v84, v168
	v_mul_f32_e32 v90, v88, v82
	v_fma_f32 v92, -v71, v90, v88
	v_fmac_f32_e32 v90, v92, v82
	v_fma_f32 v71, -v71, v90, v88
	v_div_fmas_f32 v71, v71, v82, v90
	v_div_fixup_f32 v168, v71, v84, v168
	v_mul_f32_e32 v70, v70, v168
	v_lshlrev_b32_e32 v166, 16, v166
	v_lshlrev_b32_e32 v167, 16, v167
	v_lshlrev_b32_e32 v165, 16, v165
	v_mul_f32_e32 v165, v16, v165
	v_fmac_f32_e32 v165, v14, v166
	v_fmac_f32_e32 v165, v17, v167
	v_add_f32_e32 v165, v12, v165
	v_fma_f32 v27, v49, v8, v23
	v_mul_f32_e32 v110, v27, v165
	v_lshlrev_b32_e32 v169, 16, v169
	v_mul_f32_e32 v84, 0xbfb8aa3b, v169
	v_exp_f32_e32 v84, v84
	s_nop 0
	v_add_f32_e32 v84, 1.0, v84
	v_div_scale_f32 v71, s[28:29], v84, v84, v169
	v_rcp_f32_e32 v82, v71
	s_nop 0
	v_fma_f32 v92, -v71, v82, 1.0
	v_fmac_f32_e32 v82, v92, v82
	v_div_scale_f32 v88, vcc, v169, v84, v169
	v_mul_f32_e32 v90, v88, v82
	v_fma_f32 v92, -v71, v90, v88
	v_fmac_f32_e32 v90, v92, v82
	v_fma_f32 v71, -v71, v90, v88
	v_div_fmas_f32 v71, v71, v82, v90
	v_div_fixup_f32 v169, v71, v84, v169
	v_mul_f32_e32 v110, v110, v169
	v_cvt_pk_bf16_f32 v206, v70, v110
	v_lshlrev_b32_e32 v171, 16, v171
	v_lshlrev_b32_e32 v172, 16, v172
	v_lshlrev_b32_e32 v170, 16, v170
	v_mul_f32_e32 v170, v16, v170
	v_fmac_f32_e32 v170, v14, v171
	v_fmac_f32_e32 v170, v17, v172
	v_add_f32_e32 v170, v12, v170
	v_fma_f32 v27, v46, v8, v24
	v_mul_f32_e32 v70, v27, v170
	v_lshlrev_b32_e32 v176, 16, v176
	v_mul_f32_e32 v84, 0xbfb8aa3b, v176
	v_exp_f32_e32 v84, v84
	s_nop 0
	v_add_f32_e32 v84, 1.0, v84
	v_div_scale_f32 v71, s[28:29], v84, v84, v176
	v_rcp_f32_e32 v82, v71
	s_nop 0
	v_fma_f32 v92, -v71, v82, 1.0
	v_fmac_f32_e32 v82, v92, v82
	v_div_scale_f32 v88, vcc, v176, v84, v176
	v_mul_f32_e32 v90, v88, v82
	v_fma_f32 v92, -v71, v90, v88
	v_fmac_f32_e32 v90, v92, v82
	v_fma_f32 v71, -v71, v90, v88
	v_div_fmas_f32 v71, v71, v82, v90
	v_div_fixup_f32 v176, v71, v84, v176
	v_mul_f32_e32 v70, v70, v176
	v_lshlrev_b32_e32 v174, 16, v174
	v_lshlrev_b32_e32 v175, 16, v175
	v_lshlrev_b32_e32 v173, 16, v173
	v_mul_f32_e32 v173, v16, v173
	v_fmac_f32_e32 v173, v14, v174
	v_fmac_f32_e32 v173, v17, v175
	v_add_f32_e32 v173, v12, v173
	v_fma_f32 v27, v48, v8, v25
	v_mul_f32_e32 v110, v27, v173
	v_lshlrev_b32_e32 v177, 16, v177
	v_mul_f32_e32 v84, 0xbfb8aa3b, v177
	v_exp_f32_e32 v84, v84
	s_nop 0
	v_add_f32_e32 v84, 1.0, v84
	v_div_scale_f32 v71, s[28:29], v84, v84, v177
	v_rcp_f32_e32 v82, v71
	s_nop 0
	v_fma_f32 v92, -v71, v82, 1.0
	v_fmac_f32_e32 v82, v92, v82
	v_div_scale_f32 v88, vcc, v177, v84, v177
	v_mul_f32_e32 v90, v88, v82
	v_fma_f32 v92, -v71, v90, v88
	v_fmac_f32_e32 v90, v92, v82
	v_fma_f32 v71, -v71, v90, v88
	v_div_fmas_f32 v71, v71, v82, v90
	v_div_fixup_f32 v177, v71, v84, v177
	v_mul_f32_e32 v110, v110, v177
	v_cvt_pk_bf16_f32 v207, v70, v110
	v_lshlrev_b32_e32 v179, 16, v179
	v_lshlrev_b32_e32 v180, 16, v180
	v_lshlrev_b32_e32 v178, 16, v178
	v_mul_f32_e32 v178, v16, v178
	v_fmac_f32_e32 v178, v14, v179
	v_fmac_f32_e32 v178, v17, v180
	v_add_f32_e32 v178, v12, v178
	v_fma_f32 v27, v51, v8, v18
	v_mul_f32_e32 v70, v27, v178
	v_lshlrev_b32_e32 v184, 16, v184
	v_mul_f32_e32 v84, 0xbfb8aa3b, v184
	v_exp_f32_e32 v84, v84
	s_nop 0
	v_add_f32_e32 v84, 1.0, v84
	v_div_scale_f32 v71, s[28:29], v84, v84, v184
	v_rcp_f32_e32 v82, v71
	s_nop 0
	v_fma_f32 v92, -v71, v82, 1.0
	v_fmac_f32_e32 v82, v92, v82
	v_div_scale_f32 v88, vcc, v184, v84, v184
	v_mul_f32_e32 v90, v88, v82
	v_fma_f32 v92, -v71, v90, v88
	v_fmac_f32_e32 v90, v92, v82
	v_fma_f32 v71, -v71, v90, v88
	v_div_fmas_f32 v71, v71, v82, v90
	v_div_fixup_f32 v184, v71, v84, v184
	v_mul_f32_e32 v70, v70, v184
	v_lshlrev_b32_e32 v182, 16, v182
	v_lshlrev_b32_e32 v183, 16, v183
	v_lshlrev_b32_e32 v181, 16, v181
	v_mul_f32_e32 v181, v16, v181
	v_fmac_f32_e32 v181, v14, v182
	v_fmac_f32_e32 v181, v17, v183
	v_add_f32_e32 v181, v12, v181
	v_fma_f32 v27, v53, v8, v19
	v_mul_f32_e32 v110, v27, v181
	v_lshlrev_b32_e32 v185, 16, v185
	v_mul_f32_e32 v84, 0xbfb8aa3b, v185
	v_exp_f32_e32 v84, v84
	s_nop 0
	v_add_f32_e32 v84, 1.0, v84
	v_div_scale_f32 v71, s[28:29], v84, v84, v185
	v_rcp_f32_e32 v82, v71
	s_nop 0
	v_fma_f32 v92, -v71, v82, 1.0
	v_fmac_f32_e32 v82, v92, v82
	v_div_scale_f32 v88, vcc, v185, v84, v185
	v_mul_f32_e32 v90, v88, v82
	v_fma_f32 v92, -v71, v90, v88
	v_fmac_f32_e32 v90, v92, v82
	v_fma_f32 v71, -v71, v90, v88
	v_div_fmas_f32 v71, v71, v82, v90
	v_div_fixup_f32 v185, v71, v84, v185
	v_mul_f32_e32 v110, v110, v185
	v_cvt_pk_bf16_f32 v208, v70, v110
	v_lshlrev_b32_e32 v187, 16, v187
	v_lshlrev_b32_e32 v188, 16, v188
	v_lshlrev_b32_e32 v186, 16, v186
	v_mul_f32_e32 v186, v16, v186
	v_fmac_f32_e32 v186, v14, v187
	v_fmac_f32_e32 v186, v17, v188
	v_add_f32_e32 v186, v12, v186
	v_fma_f32 v27, v50, v8, v20
	v_mul_f32_e32 v70, v27, v186
	v_lshlrev_b32_e32 v192, 16, v192
	v_mul_f32_e32 v84, 0xbfb8aa3b, v192
	v_exp_f32_e32 v84, v84
	s_nop 0
	v_add_f32_e32 v84, 1.0, v84
	v_div_scale_f32 v71, s[28:29], v84, v84, v192
	v_rcp_f32_e32 v82, v71
	s_nop 0
	v_fma_f32 v92, -v71, v82, 1.0
	v_fmac_f32_e32 v82, v92, v82
	v_div_scale_f32 v88, vcc, v192, v84, v192
	v_mul_f32_e32 v90, v88, v82
	v_fma_f32 v92, -v71, v90, v88
	v_fmac_f32_e32 v90, v92, v82
	v_fma_f32 v71, -v71, v90, v88
	v_div_fmas_f32 v71, v71, v82, v90
	v_div_fixup_f32 v192, v71, v84, v192
	v_mul_f32_e32 v70, v70, v192
	v_lshlrev_b32_e32 v190, 16, v190
	v_lshlrev_b32_e32 v191, 16, v191
	v_lshlrev_b32_e32 v189, 16, v189
	v_mul_f32_e32 v189, v16, v189
	v_fmac_f32_e32 v189, v14, v190
	v_fmac_f32_e32 v189, v17, v191
	v_add_f32_e32 v189, v12, v189
	v_fma_f32 v27, v52, v8, v21
	v_mul_f32_e32 v110, v27, v189
	v_lshlrev_b32_e32 v193, 16, v193
	v_mul_f32_e32 v84, 0xbfb8aa3b, v193
	v_exp_f32_e32 v84, v84
	s_nop 0
	v_add_f32_e32 v84, 1.0, v84
	v_div_scale_f32 v71, s[28:29], v84, v84, v193
	v_rcp_f32_e32 v82, v71
	s_nop 0
	v_fma_f32 v92, -v71, v82, 1.0
	v_fmac_f32_e32 v82, v92, v82
	v_div_scale_f32 v88, vcc, v193, v84, v193
	v_mul_f32_e32 v90, v88, v82
	v_fma_f32 v92, -v71, v90, v88
	v_fmac_f32_e32 v90, v92, v82
	v_fma_f32 v71, -v71, v90, v88
	v_div_fmas_f32 v71, v71, v82, v90
	v_div_fixup_f32 v193, v71, v84, v193
	v_mul_f32_e32 v110, v110, v193
	v_cvt_pk_bf16_f32 v209, v70, v110
	s_waitcnt vmcnt(0)
	v_lshlrev_b32_e32 v195, 16, v195
	v_lshlrev_b32_e32 v196, 16, v196
	v_lshlrev_b32_e32 v194, 16, v194
	v_mul_f32_e32 v194, v16, v194
	v_fmac_f32_e32 v194, v14, v195
	v_fmac_f32_e32 v194, v17, v196
	v_add_f32_e32 v194, v12, v194
	v_fma_f32 v27, v55, v8, v4
	v_mul_f32_e32 v70, v27, v194
	v_lshlrev_b32_e32 v223, 16, v223
	v_mul_f32_e32 v84, 0xbfb8aa3b, v223
	v_exp_f32_e32 v84, v84
	s_nop 0
	v_add_f32_e32 v84, 1.0, v84
	v_div_scale_f32 v71, s[28:29], v84, v84, v223
	v_rcp_f32_e32 v82, v71
	s_nop 0
	v_fma_f32 v92, -v71, v82, 1.0
	v_fmac_f32_e32 v82, v92, v82
	v_div_scale_f32 v88, vcc, v223, v84, v223
	v_mul_f32_e32 v90, v88, v82
	v_fma_f32 v92, -v71, v90, v88
	v_fmac_f32_e32 v90, v92, v82
	v_fma_f32 v71, -v71, v90, v88
	v_div_fmas_f32 v71, v71, v82, v90
	v_div_fixup_f32 v223, v71, v84, v223
	v_mul_f32_e32 v70, v70, v223
	v_lshlrev_b32_e32 v221, 16, v221
	v_lshlrev_b32_e32 v222, 16, v222
	v_lshlrev_b32_e32 v197, 16, v197
	v_mul_f32_e32 v197, v16, v197
	v_fmac_f32_e32 v197, v14, v221
	v_fmac_f32_e32 v197, v17, v222
	v_add_f32_e32 v197, v12, v197
	v_fma_f32 v27, v57, v8, v5
	v_mul_f32_e32 v110, v27, v197
	v_lshlrev_b32_e32 v224, 16, v224
	v_mul_f32_e32 v84, 0xbfb8aa3b, v224
	v_exp_f32_e32 v84, v84
	s_nop 0
	v_add_f32_e32 v84, 1.0, v84
	v_div_scale_f32 v71, s[28:29], v84, v84, v224
	v_rcp_f32_e32 v82, v71
	s_nop 0
	v_fma_f32 v92, -v71, v82, 1.0
	v_fmac_f32_e32 v82, v92, v82
	v_div_scale_f32 v88, vcc, v224, v84, v224
	v_mul_f32_e32 v90, v88, v82
	v_fma_f32 v92, -v71, v90, v88
	v_fmac_f32_e32 v90, v92, v82
	v_fma_f32 v71, -v71, v90, v88
	v_div_fmas_f32 v71, v71, v82, v90
	v_div_fixup_f32 v224, v71, v84, v224
	v_mul_f32_e32 v110, v110, v224
	v_cvt_pk_bf16_f32 v210, v70, v110
	v_lshlrev_b32_e32 v226, 16, v226
	v_lshlrev_b32_e32 v227, 16, v227
	v_lshlrev_b32_e32 v225, 16, v225
	v_mul_f32_e32 v225, v16, v225
	v_fmac_f32_e32 v225, v14, v226
	v_fmac_f32_e32 v225, v17, v227
	v_add_f32_e32 v225, v12, v225
	v_fma_f32 v27, v54, v8, v6
	v_mul_f32_e32 v70, v27, v225
	v_lshlrev_b32_e32 v231, 16, v231
	v_mul_f32_e32 v84, 0xbfb8aa3b, v231
	v_exp_f32_e32 v84, v84
	s_nop 0
	v_add_f32_e32 v84, 1.0, v84
	v_div_scale_f32 v71, s[28:29], v84, v84, v231
	v_rcp_f32_e32 v82, v71
	s_nop 0
	v_fma_f32 v92, -v71, v82, 1.0
	v_fmac_f32_e32 v82, v92, v82
	v_div_scale_f32 v88, vcc, v231, v84, v231
	v_mul_f32_e32 v90, v88, v82
	v_fma_f32 v92, -v71, v90, v88
	v_fmac_f32_e32 v90, v92, v82
	v_fma_f32 v71, -v71, v90, v88
	v_div_fmas_f32 v71, v71, v82, v90
	v_div_fixup_f32 v231, v71, v84, v231
	v_mul_f32_e32 v70, v70, v231
	v_lshlrev_b32_e32 v229, 16, v229
	v_lshlrev_b32_e32 v230, 16, v230
	v_lshlrev_b32_e32 v228, 16, v228
	v_mul_f32_e32 v228, v16, v228
	v_fmac_f32_e32 v228, v14, v229
	v_fmac_f32_e32 v228, v17, v230
	v_add_f32_e32 v228, v12, v228
	v_fma_f32 v27, v56, v8, v7
	v_mul_f32_e32 v110, v27, v228
	v_lshlrev_b32_e32 v232, 16, v232
	v_mul_f32_e32 v84, 0xbfb8aa3b, v232
	v_exp_f32_e32 v84, v84
	s_nop 0
	v_add_f32_e32 v84, 1.0, v84
	v_div_scale_f32 v71, s[28:29], v84, v84, v232
	v_rcp_f32_e32 v82, v71
	s_nop 0
	v_fma_f32 v92, -v71, v82, 1.0
	v_fmac_f32_e32 v82, v92, v82
	v_div_scale_f32 v88, vcc, v232, v84, v232
	v_mul_f32_e32 v90, v88, v82
	v_fma_f32 v92, -v71, v90, v88
	v_fmac_f32_e32 v90, v92, v82
	v_fma_f32 v71, -v71, v90, v88
	v_div_fmas_f32 v71, v71, v82, v90
	v_div_fixup_f32 v232, v71, v84, v232
	v_mul_f32_e32 v110, v110, v232
	v_cvt_pk_bf16_f32 v211, v70, v110
	v_lshlrev_b32_e32 v234, 16, v234
	v_lshlrev_b32_e32 v235, 16, v235
	v_lshlrev_b32_e32 v233, 16, v233
	v_mul_f32_e32 v233, v16, v233
	v_fmac_f32_e32 v233, v14, v234
	v_fmac_f32_e32 v233, v17, v235
	v_add_f32_e32 v233, v12, v233
	v_fma_f32 v27, v59, v8, v0
	v_mul_f32_e32 v70, v27, v233
	v_lshlrev_b32_e32 v239, 16, v239
	v_mul_f32_e32 v84, 0xbfb8aa3b, v239
	v_exp_f32_e32 v84, v84
	s_nop 0
	v_add_f32_e32 v84, 1.0, v84
	v_div_scale_f32 v71, s[28:29], v84, v84, v239
	v_rcp_f32_e32 v82, v71
	s_nop 0
	v_fma_f32 v92, -v71, v82, 1.0
	v_fmac_f32_e32 v82, v92, v82
	v_div_scale_f32 v88, vcc, v239, v84, v239
	v_mul_f32_e32 v90, v88, v82
	v_fma_f32 v92, -v71, v90, v88
	v_fmac_f32_e32 v90, v92, v82
	v_fma_f32 v71, -v71, v90, v88
	v_div_fmas_f32 v71, v71, v82, v90
	v_div_fixup_f32 v239, v71, v84, v239
	v_mul_f32_e32 v70, v70, v239
	v_lshlrev_b32_e32 v237, 16, v237
	v_lshlrev_b32_e32 v238, 16, v238
	v_lshlrev_b32_e32 v236, 16, v236
	v_mul_f32_e32 v236, v16, v236
	v_fmac_f32_e32 v236, v14, v237
	v_fmac_f32_e32 v236, v17, v238
	v_add_f32_e32 v236, v12, v236
	v_fma_f32 v27, v61, v8, v1
	v_mul_f32_e32 v110, v27, v236
	v_lshlrev_b32_e32 v240, 16, v240
	v_mul_f32_e32 v84, 0xbfb8aa3b, v240
	v_exp_f32_e32 v84, v84
	s_nop 0
	v_add_f32_e32 v84, 1.0, v84
	v_div_scale_f32 v71, s[28:29], v84, v84, v240
	v_rcp_f32_e32 v82, v71
	s_nop 0
	v_fma_f32 v92, -v71, v82, 1.0
	v_fmac_f32_e32 v82, v92, v82
	v_div_scale_f32 v88, vcc, v240, v84, v240
	v_mul_f32_e32 v90, v88, v82
	v_fma_f32 v92, -v71, v90, v88
	v_fmac_f32_e32 v90, v92, v82
	v_fma_f32 v71, -v71, v90, v88
	v_div_fmas_f32 v71, v71, v82, v90
	v_div_fixup_f32 v240, v71, v84, v240
	v_mul_f32_e32 v110, v110, v240
	v_cvt_pk_bf16_f32 v212, v70, v110
	v_lshlrev_b32_e32 v242, 16, v242
	v_lshlrev_b32_e32 v243, 16, v243
	v_lshlrev_b32_e32 v241, 16, v241
	v_mul_f32_e32 v241, v16, v241
	v_mul_f32_e32 v243, v255, v243
	v_fmac_f32_e32 v241, v14, v242
	v_fmac_f32_e32 v241, v17, v243
	v_add_f32_e32 v241, v12, v241
	v_fma_f32 v27, v58, v8, v2
	v_mul_f32_e32 v70, v27, v241
	v_lshlrev_b32_e32 v247, 16, v247
	v_mul_f32_e32 v84, 0xbfb8aa3b, v247
	v_exp_f32_e32 v84, v84
	s_nop 0
	v_add_f32_e32 v84, 1.0, v84
	v_div_scale_f32 v71, s[28:29], v84, v84, v247
	v_rcp_f32_e32 v82, v71
	s_nop 0
	v_fma_f32 v92, -v71, v82, 1.0
	v_fmac_f32_e32 v82, v92, v82
	v_div_scale_f32 v88, vcc, v247, v84, v247
	v_mul_f32_e32 v90, v88, v82
	v_fma_f32 v92, -v71, v90, v88
	v_fmac_f32_e32 v90, v92, v82
	v_fma_f32 v71, -v71, v90, v88
	v_div_fmas_f32 v71, v71, v82, v90
	v_div_fixup_f32 v247, v71, v84, v247
	v_mul_f32_e32 v70, v70, v247
	v_lshlrev_b32_e32 v245, 16, v245
	v_lshlrev_b32_e32 v246, 16, v246
	v_lshlrev_b32_e32 v244, 16, v244
	v_mul_f32_e32 v244, v16, v244
	v_mul_f32_e32 v246, v255, v246
	v_fmac_f32_e32 v244, v14, v245
	v_fmac_f32_e32 v244, v17, v246
	v_add_f32_e32 v244, v12, v244
	v_fma_f32 v27, v60, v8, v3
	v_mul_f32_e32 v110, v27, v244
	v_lshlrev_b32_e32 v248, 16, v248
	v_mul_f32_e32 v84, 0xbfb8aa3b, v248
	v_exp_f32_e32 v84, v84
	s_nop 0
	v_add_f32_e32 v84, 1.0, v84
	v_div_scale_f32 v71, s[28:29], v84, v84, v248
	v_rcp_f32_e32 v82, v71
	s_nop 0
	v_fma_f32 v92, -v71, v82, 1.0
	v_fmac_f32_e32 v82, v92, v82
	v_div_scale_f32 v88, vcc, v248, v84, v248
	v_mul_f32_e32 v90, v88, v82
	v_fma_f32 v92, -v71, v90, v88
	v_fmac_f32_e32 v90, v92, v82
	v_fma_f32 v71, -v71, v90, v88
	v_div_fmas_f32 v71, v71, v82, v90
	v_div_fixup_f32 v248, v71, v84, v248
	v_mul_f32_e32 v110, v110, v248
	v_cvt_pk_bf16_f32 v213, v70, v110
	s_branch .Lhy_ep1_done_L0

.LBB0_908:
	s_nop 1
	v_lshlrev_b32_e32 v0, 2, v146
	s_add_i32 s79, 16, 0x10000
	v_add_u32_e32 v64, 16, v0
	v_add_u32_e32 v65, s79, v0
	s_waitcnt lgkmcnt(0)
	s_barrier
	ds_read2st64_b32 v[2:3], v64 offset1:8
	ds_read2st64_b32 v[4:5], v65 offset1:8
	ds_read2st64_b32 v[8:9], v64 offset0:16 offset1:24
	ds_read2st64_b32 v[10:11], v65 offset0:16 offset1:24
	ds_read2st64_b32 v[12:13], v64 offset0:32 offset1:40
	ds_read2st64_b32 v[14:15], v65 offset0:32 offset1:40
	s_mov_b32 s47, s40
	s_waitcnt lgkmcnt(5)
	v_mov_b32_e32 v6, v2
	s_waitcnt lgkmcnt(4)
	v_mov_b32_e32 v7, v4
	v_mov_b32_e32 v4, v3
	s_waitcnt lgkmcnt(3)
	v_mov_b32_e32 v2, v8
	s_waitcnt lgkmcnt(2)
	v_mov_b32_e32 v3, v10
	v_mov_b32_e32 v10, v9
	ds_read2st64_b32 v[8:9], v64 offset0:48 offset1:56
	ds_read2st64_b32 v[16:17], v65 offset0:48 offset1:56
	s_waitcnt lgkmcnt(3)
	v_mov_b32_e32 v18, v12
	s_waitcnt lgkmcnt(2)
	v_mov_b32_e32 v19, v14
	v_mov_b32_e32 v14, v13
	s_waitcnt lgkmcnt(1)
	v_mov_b32_e32 v12, v8
	s_waitcnt lgkmcnt(0)
	v_mov_b32_e32 v13, v16
	ds_read2st64_b32 v[20:21], v64 offset0:64 offset1:72
	ds_read2st64_b32 v[22:23], v65 offset0:64 offset1:72
	v_mov_b32_e32 v16, v9
	ds_read2st64_b32 v[8:9], v64 offset0:80 offset1:88
	ds_read2st64_b32 v[24:25], v65 offset0:80 offset1:88
	s_mov_b32 s41, s43
	s_waitcnt lgkmcnt(3)
	v_mov_b32_e32 v26, v20
	s_waitcnt lgkmcnt(2)
	v_mov_b32_e32 v27, v22
	v_mov_b32_e32 v22, v21
	s_waitcnt lgkmcnt(1)
	v_mov_b32_e32 v28, v8
	s_waitcnt lgkmcnt(0)
	v_mov_b32_e32 v29, v24
	ds_read2st64_b32 v[20:21], v64 offset0:96 offset1:104
	ds_read2st64_b32 v[30:31], v65 offset0:96 offset1:104
	v_mov_b32_e32 v24, v9
	ds_read2st64_b32 v[8:9], v64 offset0:112 offset1:120
	ds_read2st64_b32 v[32:33], v65 offset0:112 offset1:120
	v_and_b32_e32 v196, 63, v146
	v_lshlrev_b32_e32 v196, 2, v196
	v_and_b32_e32 v0, 0xffffffc0, v146
	v_lshl_add_u32 v0, v0, 5, v196
	v_add_u32_e32 v0, 0x400, v0
	s_waitcnt lgkmcnt(3)
	v_mov_b32_e32 v34, v20
	s_waitcnt lgkmcnt(2)
	v_mov_b32_e32 v35, v30
	v_mov_b32_e32 v30, v21
	s_waitcnt lgkmcnt(1)
	v_mov_b32_e32 v36, v8
	s_waitcnt lgkmcnt(0)
	v_mov_b32_e32 v37, v32
	ds_read2st64_b32 v[20:21], v64 offset0:128 offset1:136
	ds_read2st64_b32 v[38:39], v65 offset0:128 offset1:136
	v_mov_b32_e32 v32, v9
	ds_read2st64_b32 v[8:9], v64 offset0:144 offset1:152
	ds_read2st64_b32 v[40:41], v65 offset0:144 offset1:152
	v_readlane_b32 s0, v252, 48
	s_waitcnt lgkmcnt(3)
	v_mov_b32_e32 v42, v20
	s_waitcnt lgkmcnt(2)
	v_mov_b32_e32 v43, v38
	v_mov_b32_e32 v38, v21
	s_waitcnt lgkmcnt(1)
	v_mov_b32_e32 v44, v8
	s_waitcnt lgkmcnt(0)
	v_mov_b32_e32 v45, v40
	ds_read2st64_b32 v[20:21], v64 offset0:160 offset1:168
	ds_read2st64_b32 v[46:47], v65 offset0:160 offset1:168
	v_mov_b32_e32 v40, v9
	ds_read2st64_b32 v[8:9], v64 offset0:176 offset1:184
	ds_read2st64_b32 v[48:49], v65 offset0:176 offset1:184
	v_ashrrev_i32_e32 v1, 31, v0
	s_waitcnt lgkmcnt(3)
	v_mov_b32_e32 v50, v20
	s_waitcnt lgkmcnt(2)
	v_mov_b32_e32 v51, v46
	v_mov_b32_e32 v46, v21
	s_waitcnt lgkmcnt(1)
	v_mov_b32_e32 v52, v8
	s_waitcnt lgkmcnt(0)
	v_mov_b32_e32 v53, v48
	ds_read2st64_b32 v[20:21], v64 offset0:192 offset1:200
	ds_read2st64_b32 v[54:55], v65 offset0:192 offset1:200
	v_mov_b32_e32 v48, v9
	ds_read2st64_b32 v[8:9], v64 offset0:208 offset1:216
	ds_read2st64_b32 v[56:57], v65 offset0:208 offset1:216
	v_readlane_b32 s1, v252, 49
	s_waitcnt lgkmcnt(3)
	v_mov_b32_e32 v58, v20
	s_waitcnt lgkmcnt(2)
	v_mov_b32_e32 v59, v54
	v_mov_b32_e32 v54, v21
	s_waitcnt lgkmcnt(1)
	v_mov_b32_e32 v60, v8
	s_waitcnt lgkmcnt(0)
	v_mov_b32_e32 v61, v56
	ds_read2st64_b32 v[20:21], v64 offset0:224 offset1:232
	ds_read2st64_b32 v[62:63], v65 offset0:224 offset1:232
	v_mov_b32_e32 v56, v9
	ds_read2st64_b32 v[8:9], v64 offset0:240 offset1:248
	ds_read2st64_b32 v[64:65], v65 offset0:240 offset1:248
	s_waitcnt lgkmcnt(0)
	v_mov_b32_e32 v66, v20
	v_mov_b32_e32 v67, v62
	v_mov_b32_e32 v72, v8
	v_mov_b32_e32 v73, v64
	v_mov_b32_e32 v64, v9
	v_pk_add_f32 v[8:9], v[6:7], v[42:43]
	v_pk_add_f32 v[6:7], v[6:7], v[42:43] neg_lo:[0,1] neg_hi:[0,1]
	v_pk_add_f32 v[42:43], v[4:5], v[38:39]
	v_pk_add_f32 v[4:5], v[4:5], v[38:39] neg_lo:[0,1] neg_hi:[0,1]
	v_mov_b32_e32 v62, v21
	v_pk_mul_f32 v[38:39], v[4:5], s[48:49] op_sel:[1,0] op_sel_hi:[0,0] neg_hi:[1,0]
	v_mov_b32_e32 v21, v146
	v_pk_fma_f32 v[4:5], v[4:5], s[44:45], v[38:39] op_sel_hi:[1,0,1]
	v_pk_add_f32 v[38:39], v[2:3], v[44:45]
	v_pk_add_f32 v[2:3], v[2:3], v[44:45] neg_lo:[0,1] neg_hi:[0,1]
	s_barrier
	s_nop 0
	s_nop 0
	v_pk_mul_f32 v[44:45], v[2:3], s[54:55] op_sel:[1,0] op_sel_hi:[0,0] neg_hi:[1,0]
	s_nop 0
	v_pk_fma_f32 v[2:3], v[2:3], s[52:53], v[44:45] op_sel_hi:[1,0,1]
	v_pk_add_f32 v[44:45], v[10:11], v[40:41]
	v_pk_add_f32 v[10:11], v[10:11], v[40:41] neg_lo:[0,1] neg_hi:[0,1]
	s_lshl_b64 s[10:11], s[62:63], 2
	s_nop 0
	s_nop 0
	v_pk_mul_f32 v[40:41], v[10:11], s[58:59] op_sel:[1,0] op_sel_hi:[0,0] neg_hi:[1,0]
	v_add_u32_e32 v70, 0x200, v146
	v_pk_fma_f32 v[10:11], v[10:11], s[56:57], v[40:41] op_sel_hi:[1,0,1]
	v_pk_add_f32 v[40:41], v[18:19], v[50:51]
	v_pk_add_f32 v[18:19], v[18:19], v[50:51] neg_lo:[0,1] neg_hi:[0,1]
	v_ashrrev_i32_e32 v147, 31, v146
	s_nop 0
	s_nop 0
	v_pk_mul_f32 v[50:51], v[18:19], s[60:61] op_sel:[1,0] op_sel_hi:[0,0] neg_hi:[1,0]
	v_add_u32_e32 v69, 0x400, v146
	v_pk_fma_f32 v[18:19], v[18:19], s[60:61], v[50:51] op_sel_hi:[1,0,1]
	v_pk_add_f32 v[50:51], v[14:15], v[46:47]
	v_pk_add_f32 v[14:15], v[14:15], v[46:47] neg_lo:[0,1] neg_hi:[0,1]
	v_add_u32_e32 v68, 0x600, v146
	v_pk_mul_f32 v[46:47], v[14:15], s[56:57] op_sel:[1,0] op_sel_hi:[0,0] neg_hi:[1,0]
	s_mov_b32 s16, 0
	v_pk_fma_f32 v[14:15], v[14:15], s[58:59], v[46:47] op_sel_hi:[1,0,1]
	v_pk_add_f32 v[46:47], v[12:13], v[52:53]
	v_pk_add_f32 v[12:13], v[12:13], v[52:53] neg_lo:[0,1] neg_hi:[0,1]
	v_pk_mul_f32 v[52:53], v[12:13], s[52:53] op_sel:[1,0] op_sel_hi:[0,0] neg_hi:[1,0]
	v_pk_fma_f32 v[12:13], v[12:13], s[54:55], v[52:53] op_sel_hi:[1,0,1]
	v_pk_add_f32 v[52:53], v[16:17], v[48:49]
	v_pk_add_f32 v[16:17], v[16:17], v[48:49] neg_lo:[0,1] neg_hi:[0,1]
	v_pk_mul_f32 v[48:49], v[16:17], s[44:45] op_sel:[1,0] op_sel_hi:[0,0] neg_hi:[1,0]
	v_pk_fma_f32 v[16:17], v[16:17], s[48:49], v[48:49] op_sel_hi:[1,0,1]
	v_pk_add_f32 v[48:49], v[26:27], v[58:59]
	v_pk_add_f32 v[26:27], v[26:27], v[58:59] neg_lo:[0,1] neg_hi:[0,1]
	v_xor_b32_e32 v59, 0x80000000, v26
	v_mov_b32_e32 v58, v27
	v_pk_add_f32 v[26:27], v[22:23], v[54:55]
	v_pk_add_f32 v[22:23], v[22:23], v[54:55] neg_lo:[0,1] neg_hi:[0,1]
	v_pk_mul_f32 v[54:55], v[22:23], s[48:49] op_sel_hi:[1,0]
	v_xor_b32_e32 v75, 0x80000000, v22
	v_mov_b32_e32 v74, v23
	v_pk_fma_f32 v[22:23], v[74:75], s[44:45], v[54:55] op_sel_hi:[1,0,1] neg_lo:[0,0,1] neg_hi:[0,0,1]
	v_pk_add_f32 v[54:55], v[28:29], v[60:61]
	v_pk_add_f32 v[28:29], v[28:29], v[60:61] neg_lo:[0,1] neg_hi:[0,1]
	v_pk_mul_f32 v[60:61], v[28:29], s[54:55] op_sel_hi:[1,0]
	v_xor_b32_e32 v75, 0x80000000, v28
	v_mov_b32_e32 v74, v29
	v_pk_fma_f32 v[28:29], v[74:75], s[52:53], v[60:61] op_sel_hi:[1,0,1] neg_lo:[0,0,1] neg_hi:[0,0,1]
	v_pk_add_f32 v[60:61], v[24:25], v[56:57]
	v_pk_add_f32 v[24:25], v[24:25], v[56:57] neg_lo:[0,1] neg_hi:[0,1]
	v_pk_mul_f32 v[56:57], v[24:25], s[58:59] op_sel_hi:[1,0]
	v_xor_b32_e32 v75, 0x80000000, v24
	v_mov_b32_e32 v74, v25
	v_pk_fma_f32 v[24:25], v[74:75], s[56:57], v[56:57] op_sel_hi:[1,0,1] neg_lo:[0,0,1] neg_hi:[0,0,1]
	v_pk_add_f32 v[56:57], v[34:35], v[66:67]
	v_pk_add_f32 v[34:35], v[34:35], v[66:67] neg_lo:[0,1] neg_hi:[0,1]
	v_pk_mul_f32 v[66:67], v[34:35], s[60:61] op_sel_hi:[1,0]
	v_xor_b32_e32 v75, 0x80000000, v34
	v_mov_b32_e32 v74, v35
	v_pk_fma_f32 v[34:35], v[74:75], s[60:61], v[66:67] op_sel_hi:[1,0,1] neg_lo:[0,0,1] neg_hi:[0,0,1]
	v_pk_add_f32 v[66:67], v[30:31], v[62:63]
	v_pk_add_f32 v[30:31], v[30:31], v[62:63] neg_lo:[0,1] neg_hi:[0,1]
	v_pk_mul_f32 v[62:63], v[30:31], s[56:57] op_sel_hi:[1,0]
	v_xor_b32_e32 v75, 0x80000000, v30
	v_mov_b32_e32 v74, v31
	v_pk_fma_f32 v[30:31], v[74:75], s[58:59], v[62:63] op_sel_hi:[1,0,1] neg_lo:[0,0,1] neg_hi:[0,0,1]
	v_pk_add_f32 v[62:63], v[36:37], v[72:73]
	v_pk_add_f32 v[36:37], v[36:37], v[72:73] neg_lo:[0,1] neg_hi:[0,1]
	v_pk_mul_f32 v[72:73], v[36:37], s[52:53] op_sel_hi:[1,0]
	v_xor_b32_e32 v75, 0x80000000, v36
	v_mov_b32_e32 v74, v37
	v_pk_fma_f32 v[36:37], v[74:75], s[54:55], v[72:73] op_sel_hi:[1,0,1] neg_lo:[0,0,1] neg_hi:[0,0,1]
	v_pk_add_f32 v[72:73], v[32:33], v[64:65]
	v_pk_add_f32 v[32:33], v[32:33], v[64:65] neg_lo:[0,1] neg_hi:[0,1]
	v_pk_mul_f32 v[64:65], v[32:33], s[44:45] op_sel_hi:[1,0]
	v_xor_b32_e32 v75, 0x80000000, v32
	v_mov_b32_e32 v74, v33
	v_pk_fma_f32 v[32:33], v[74:75], s[48:49], v[64:65] op_sel_hi:[1,0,1] neg_lo:[0,0,1] neg_hi:[0,0,1]
	v_pk_add_f32 v[64:65], v[8:9], v[48:49]
	v_pk_add_f32 v[8:9], v[8:9], v[48:49] neg_lo:[0,1] neg_hi:[0,1]
	v_pk_add_f32 v[48:49], v[42:43], v[26:27]
	v_pk_add_f32 v[26:27], v[42:43], v[26:27] neg_lo:[0,1] neg_hi:[0,1]
	v_pk_mul_f32 v[42:43], v[26:27], s[54:55] op_sel:[1,0] op_sel_hi:[0,0] neg_hi:[1,0]
	v_pk_fma_f32 v[26:27], v[26:27], s[52:53], v[42:43] op_sel_hi:[1,0,1]
	v_pk_add_f32 v[42:43], v[38:39], v[54:55]
	v_pk_add_f32 v[38:39], v[38:39], v[54:55] neg_lo:[0,1] neg_hi:[0,1]
	v_pk_mul_f32 v[54:55], v[38:39], s[60:61] op_sel:[1,0] op_sel_hi:[0,0] neg_hi:[1,0]
	v_pk_fma_f32 v[38:39], v[38:39], s[60:61], v[54:55] op_sel_hi:[1,0,1]
	v_pk_add_f32 v[54:55], v[44:45], v[60:61]
	v_pk_add_f32 v[44:45], v[44:45], v[60:61] neg_lo:[0,1] neg_hi:[0,1]
	v_pk_mul_f32 v[60:61], v[44:45], s[52:53] op_sel:[1,0] op_sel_hi:[0,0] neg_hi:[1,0]
	v_pk_fma_f32 v[44:45], v[44:45], s[54:55], v[60:61] op_sel_hi:[1,0,1]
	v_pk_add_f32 v[60:61], v[40:41], v[56:57]
	v_pk_add_f32 v[40:41], v[40:41], v[56:57] neg_lo:[0,1] neg_hi:[0,1]
	v_xor_b32_e32 v57, 0x80000000, v40
	v_mov_b32_e32 v56, v41
	v_pk_add_f32 v[40:41], v[50:51], v[66:67]
	v_pk_add_f32 v[50:51], v[50:51], v[66:67] neg_lo:[0,1] neg_hi:[0,1]
	v_pk_mul_f32 v[66:67], v[50:51], s[54:55] op_sel_hi:[1,0]
	v_xor_b32_e32 v75, 0x80000000, v50
	v_mov_b32_e32 v74, v51
	v_pk_fma_f32 v[50:51], v[74:75], s[52:53], v[66:67] op_sel_hi:[1,0,1] neg_lo:[0,0,1] neg_hi:[0,0,1]
	v_pk_add_f32 v[66:67], v[46:47], v[62:63]
	v_pk_add_f32 v[46:47], v[46:47], v[62:63] neg_lo:[0,1] neg_hi:[0,1]
	v_pk_mul_f32 v[62:63], v[46:47], s[60:61] op_sel_hi:[1,0]
	v_xor_b32_e32 v75, 0x80000000, v46
	v_mov_b32_e32 v74, v47
	v_pk_fma_f32 v[46:47], v[74:75], s[60:61], v[62:63] op_sel_hi:[1,0,1] neg_lo:[0,0,1] neg_hi:[0,0,1]
	v_pk_add_f32 v[62:63], v[52:53], v[72:73]
	v_pk_add_f32 v[52:53], v[52:53], v[72:73] neg_lo:[0,1] neg_hi:[0,1]
	v_pk_mul_f32 v[72:73], v[52:53], s[52:53] op_sel_hi:[1,0]
	v_xor_b32_e32 v75, 0x80000000, v52
	v_mov_b32_e32 v74, v53
	v_pk_fma_f32 v[52:53], v[74:75], s[54:55], v[72:73] op_sel_hi:[1,0,1] neg_lo:[0,0,1] neg_hi:[0,0,1]
	v_pk_add_f32 v[72:73], v[6:7], v[58:59]
	v_pk_add_f32 v[6:7], v[6:7], v[58:59] neg_lo:[0,1] neg_hi:[0,1]
	v_pk_add_f32 v[58:59], v[4:5], v[22:23]
	v_pk_add_f32 v[4:5], v[4:5], v[22:23] neg_lo:[0,1] neg_hi:[0,1]
	v_pk_mul_f32 v[22:23], v[4:5], s[54:55] op_sel:[1,0] op_sel_hi:[0,0] neg_hi:[1,0]
	v_pk_fma_f32 v[4:5], v[4:5], s[52:53], v[22:23] op_sel_hi:[1,0,1]
	v_pk_add_f32 v[22:23], v[2:3], v[28:29]
	v_pk_add_f32 v[2:3], v[2:3], v[28:29] neg_lo:[0,1] neg_hi:[0,1]
	v_pk_mul_f32 v[28:29], v[2:3], s[60:61] op_sel:[1,0] op_sel_hi:[0,0] neg_hi:[1,0]
	v_pk_fma_f32 v[2:3], v[2:3], s[60:61], v[28:29] op_sel_hi:[1,0,1]
	v_pk_add_f32 v[28:29], v[10:11], v[24:25]
	v_pk_add_f32 v[10:11], v[10:11], v[24:25] neg_lo:[0,1] neg_hi:[0,1]
	v_pk_mul_f32 v[24:25], v[10:11], s[52:53] op_sel:[1,0] op_sel_hi:[0,0] neg_hi:[1,0]
	v_pk_fma_f32 v[10:11], v[10:11], s[54:55], v[24:25] op_sel_hi:[1,0,1]
	v_pk_add_f32 v[24:25], v[18:19], v[34:35]
	v_pk_add_f32 v[18:19], v[18:19], v[34:35] neg_lo:[0,1] neg_hi:[0,1]
	v_xor_b32_e32 v35, 0x80000000, v18
	v_mov_b32_e32 v34, v19
	v_pk_add_f32 v[18:19], v[14:15], v[30:31]
	v_pk_add_f32 v[14:15], v[14:15], v[30:31] neg_lo:[0,1] neg_hi:[0,1]
	v_pk_mul_f32 v[30:31], v[14:15], s[54:55] op_sel_hi:[1,0]
	v_xor_b32_e32 v75, 0x80000000, v14
	v_mov_b32_e32 v74, v15
	v_pk_fma_f32 v[14:15], v[74:75], s[52:53], v[30:31] op_sel_hi:[1,0,1] neg_lo:[0,0,1] neg_hi:[0,0,1]
	v_pk_add_f32 v[30:31], v[12:13], v[36:37]
	v_pk_add_f32 v[12:13], v[12:13], v[36:37] neg_lo:[0,1] neg_hi:[0,1]
	v_pk_mul_f32 v[36:37], v[12:13], s[60:61] op_sel_hi:[1,0]
	v_xor_b32_e32 v75, 0x80000000, v12
	v_mov_b32_e32 v74, v13
	v_pk_fma_f32 v[12:13], v[74:75], s[60:61], v[36:37] op_sel_hi:[1,0,1] neg_lo:[0,0,1] neg_hi:[0,0,1]
	v_pk_add_f32 v[36:37], v[16:17], v[32:33]
	v_pk_add_f32 v[16:17], v[16:17], v[32:33] neg_lo:[0,1] neg_hi:[0,1]
	v_pk_mul_f32 v[32:33], v[16:17], s[52:53] op_sel_hi:[1,0]
	v_xor_b32_e32 v75, 0x80000000, v16
	v_mov_b32_e32 v74, v17
	v_pk_fma_f32 v[16:17], v[74:75], s[54:55], v[32:33] op_sel_hi:[1,0,1] neg_lo:[0,0,1] neg_hi:[0,0,1]
	v_pk_add_f32 v[32:33], v[64:65], v[60:61]
	v_pk_add_f32 v[60:61], v[64:65], v[60:61] neg_lo:[0,1] neg_hi:[0,1]
	v_pk_add_f32 v[64:65], v[48:49], v[40:41]
	v_pk_add_f32 v[40:41], v[48:49], v[40:41] neg_lo:[0,1] neg_hi:[0,1]
	v_pk_mul_f32 v[48:49], v[40:41], s[60:61] op_sel:[1,0] op_sel_hi:[0,0] neg_hi:[1,0]
	v_pk_fma_f32 v[40:41], v[40:41], s[60:61], v[48:49] op_sel_hi:[1,0,1]
	v_pk_add_f32 v[48:49], v[42:43], v[66:67]
	v_pk_add_f32 v[42:43], v[42:43], v[66:67] neg_lo:[0,1] neg_hi:[0,1]
	v_xor_b32_e32 v67, 0x80000000, v42
	v_mov_b32_e32 v66, v43
	v_pk_add_f32 v[42:43], v[54:55], v[62:63]
	v_pk_add_f32 v[54:55], v[54:55], v[62:63] neg_lo:[0,1] neg_hi:[0,1]
	v_pk_mul_f32 v[62:63], v[54:55], s[60:61] op_sel_hi:[1,0]
	v_xor_b32_e32 v75, 0x80000000, v54
	v_mov_b32_e32 v74, v55
	v_pk_fma_f32 v[54:55], v[74:75], s[60:61], v[62:63] op_sel_hi:[1,0,1] neg_lo:[0,0,1] neg_hi:[0,0,1]
	v_pk_add_f32 v[62:63], v[8:9], v[56:57]
	v_pk_add_f32 v[8:9], v[8:9], v[56:57] neg_lo:[0,1] neg_hi:[0,1]
	v_pk_add_f32 v[56:57], v[26:27], v[50:51]
	v_pk_add_f32 v[26:27], v[26:27], v[50:51] neg_lo:[0,1] neg_hi:[0,1]
	v_pk_mul_f32 v[50:51], v[26:27], s[60:61] op_sel:[1,0] op_sel_hi:[0,0] neg_hi:[1,0]
	v_pk_fma_f32 v[26:27], v[26:27], s[60:61], v[50:51] op_sel_hi:[1,0,1]
	v_pk_add_f32 v[50:51], v[38:39], v[46:47]
	v_pk_add_f32 v[38:39], v[38:39], v[46:47] neg_lo:[0,1] neg_hi:[0,1]
	v_xor_b32_e32 v47, 0x80000000, v38
	v_mov_b32_e32 v46, v39
	v_pk_add_f32 v[38:39], v[44:45], v[52:53]
	v_pk_add_f32 v[44:45], v[44:45], v[52:53] neg_lo:[0,1] neg_hi:[0,1]
	v_pk_mul_f32 v[52:53], v[44:45], s[60:61] op_sel_hi:[1,0]
	v_xor_b32_e32 v75, 0x80000000, v44
	v_mov_b32_e32 v74, v45
	v_pk_fma_f32 v[44:45], v[74:75], s[60:61], v[52:53] op_sel_hi:[1,0,1] neg_lo:[0,0,1] neg_hi:[0,0,1]
	v_pk_add_f32 v[52:53], v[72:73], v[24:25]
	v_pk_add_f32 v[24:25], v[72:73], v[24:25] neg_lo:[0,1] neg_hi:[0,1]
	v_pk_add_f32 v[72:73], v[58:59], v[18:19]
	v_pk_add_f32 v[18:19], v[58:59], v[18:19] neg_lo:[0,1] neg_hi:[0,1]
	v_pk_mul_f32 v[58:59], v[18:19], s[60:61] op_sel:[1,0] op_sel_hi:[0,0] neg_hi:[1,0]
	v_pk_fma_f32 v[18:19], v[18:19], s[60:61], v[58:59] op_sel_hi:[1,0,1]
	v_pk_add_f32 v[58:59], v[22:23], v[30:31]
	v_pk_add_f32 v[22:23], v[22:23], v[30:31] neg_lo:[0,1] neg_hi:[0,1]
	v_xor_b32_e32 v31, 0x80000000, v22
	v_mov_b32_e32 v30, v23
	v_pk_add_f32 v[22:23], v[28:29], v[36:37]
	v_pk_add_f32 v[28:29], v[28:29], v[36:37] neg_lo:[0,1] neg_hi:[0,1]
	v_pk_add_f32 v[76:77], v[24:25], v[30:31]
	v_pk_mul_f32 v[36:37], v[28:29], s[60:61] op_sel_hi:[1,0]
	v_xor_b32_e32 v75, 0x80000000, v28
	v_mov_b32_e32 v74, v29
	v_pk_fma_f32 v[28:29], v[74:75], s[60:61], v[36:37] op_sel_hi:[1,0,1] neg_lo:[0,0,1] neg_hi:[0,0,1]
	v_pk_add_f32 v[36:37], v[6:7], v[34:35]
	v_pk_add_f32 v[6:7], v[6:7], v[34:35] neg_lo:[0,1] neg_hi:[0,1]
	v_pk_add_f32 v[34:35], v[4:5], v[14:15]
	v_pk_add_f32 v[4:5], v[4:5], v[14:15] neg_lo:[0,1] neg_hi:[0,1]
	v_pk_add_f32 v[78:79], v[18:19], v[28:29]
	v_pk_mul_f32 v[14:15], v[4:5], s[60:61] op_sel:[1,0] op_sel_hi:[0,0] neg_hi:[1,0]
	v_pk_add_f32 v[18:19], v[18:19], v[28:29] neg_lo:[0,1] neg_hi:[0,1]
	v_pk_fma_f32 v[4:5], v[4:5], s[60:61], v[14:15] op_sel_hi:[1,0,1]
	v_pk_add_f32 v[14:15], v[2:3], v[12:13]
	v_pk_add_f32 v[2:3], v[2:3], v[12:13] neg_lo:[0,1] neg_hi:[0,1]
	v_xor_b32_e32 v81, 0x80000000, v18
	v_xor_b32_e32 v13, 0x80000000, v2
	v_mov_b32_e32 v12, v3
	v_pk_add_f32 v[2:3], v[10:11], v[16:17]
	v_pk_add_f32 v[10:11], v[10:11], v[16:17] neg_lo:[0,1] neg_hi:[0,1]
	v_mov_b32_e32 v80, v19
	v_pk_mul_f32 v[16:17], v[10:11], s[60:61] op_sel_hi:[1,0]
	v_pk_fma_f32 v[10:11], v[10:11], s[60:61], v[16:17] op_sel:[1,0,0] op_sel_hi:[0,0,1] neg_lo:[0,0,1] neg_hi:[1,0,1]
	v_pk_add_f32 v[74:75], v[62:63], v[50:51]
	v_pk_add_f32 v[50:51], v[62:63], v[50:51] neg_lo:[0,1] neg_hi:[0,1]
	v_pk_add_f32 v[62:63], v[56:57], v[38:39]
	v_pk_add_f32 v[38:39], v[56:57], v[38:39] neg_lo:[0,1] neg_hi:[0,1]
	v_pk_add_f32 v[16:17], v[32:33], v[48:49]
	v_pk_add_f32 v[32:33], v[32:33], v[48:49] neg_lo:[0,1] neg_hi:[0,1]
	v_pk_add_f32 v[48:49], v[64:65], v[42:43]
	v_pk_add_f32 v[42:43], v[64:65], v[42:43] neg_lo:[0,1] neg_hi:[0,1]
	v_xor_b32_e32 v57, 0x80000000, v38
	v_mov_b32_e32 v56, v39
	v_pk_add_f32 v[38:39], v[8:9], v[46:47]
	v_pk_add_f32 v[8:9], v[8:9], v[46:47] neg_lo:[0,1] neg_hi:[0,1]
	v_pk_add_f32 v[46:47], v[26:27], v[44:45]
	v_pk_add_f32 v[26:27], v[26:27], v[44:45] neg_lo:[0,1] neg_hi:[0,1]
	v_xor_b32_e32 v65, 0x80000000, v42
	v_mov_b32_e32 v64, v43
	v_pk_add_f32 v[42:43], v[60:61], v[66:67]
	v_pk_add_f32 v[60:61], v[60:61], v[66:67] neg_lo:[0,1] neg_hi:[0,1]
	v_pk_add_f32 v[66:67], v[40:41], v[54:55]
	v_pk_add_f32 v[40:41], v[40:41], v[54:55] neg_lo:[0,1] neg_hi:[0,1]
	v_xor_b32_e32 v45, 0x80000000, v26
	v_mov_b32_e32 v44, v27
	v_pk_add_f32 v[26:27], v[52:53], v[58:59]
	v_pk_add_f32 v[52:53], v[52:53], v[58:59] neg_lo:[0,1] neg_hi:[0,1]
	v_pk_add_f32 v[58:59], v[72:73], v[22:23]
	v_pk_add_f32 v[22:23], v[72:73], v[22:23] neg_lo:[0,1] neg_hi:[0,1]
	v_pk_add_f32 v[18:19], v[36:37], v[14:15]
	v_pk_add_f32 v[14:15], v[36:37], v[14:15] neg_lo:[0,1] neg_hi:[0,1]
	v_pk_add_f32 v[36:37], v[34:35], v[2:3]
	v_pk_add_f32 v[2:3], v[34:35], v[2:3] neg_lo:[0,1] neg_hi:[0,1]
	v_xor_b32_e32 v73, 0x80000000, v22
	v_mov_b32_e32 v72, v23
	v_xor_b32_e32 v35, 0x80000000, v2
	v_mov_b32_e32 v34, v3
	v_pk_add_f32 v[2:3], v[4:5], v[10:11] neg_lo:[0,1] neg_hi:[0,1]
	v_pk_add_f32 v[24:25], v[24:25], v[30:31] neg_lo:[0,1] neg_hi:[0,1]
	v_pk_add_f32 v[82:83], v[6:7], v[12:13]
	v_pk_add_f32 v[12:13], v[6:7], v[12:13] neg_lo:[0,1] neg_hi:[0,1]
	v_xor_b32_e32 v87, 0x80000000, v2
	v_mov_b32_e32 v86, v3
	v_pk_add_f32 v[2:3], v[16:17], v[48:49]
	v_pk_add_f32 v[88:89], v[16:17], v[48:49] neg_lo:[0,1] neg_hi:[0,1]
	v_pk_add_f32 v[48:49], v[32:33], v[64:65]
	v_pk_add_f32 v[28:29], v[32:33], v[64:65] neg_lo:[0,1] neg_hi:[0,1]
	v_pk_add_f32 v[64:65], v[60:61], v[40:41] op_sel:[0,1] op_sel_hi:[1,0] neg_hi:[0,1]
	v_pk_add_f32 v[6:7], v[60:61], v[40:41] op_sel:[0,1] op_sel_hi:[1,0] neg_lo:[0,1]
	v_pk_add_f32 v[60:61], v[50:51], v[56:57]
	v_pk_add_f32 v[22:23], v[50:51], v[56:57] neg_lo:[0,1] neg_hi:[0,1]
	v_pk_add_f32 v[50:51], v[52:53], v[72:73]
	v_pk_add_f32 v[30:31], v[52:53], v[72:73] neg_lo:[0,1] neg_hi:[0,1]
	v_pk_add_f32 v[52:53], v[18:19], v[36:37]
	v_pk_add_f32 v[56:57], v[18:19], v[36:37] neg_lo:[0,1] neg_hi:[0,1]
	v_mov_b32_e32 v18, v21
	v_pk_add_f32 v[84:85], v[4:5], v[10:11]
	v_cvt_f32_i32_e32 v18, v18
	v_pk_add_f32 v[32:33], v[42:43], v[66:67]
	v_pk_add_f32 v[40:41], v[42:43], v[66:67] neg_lo:[0,1] neg_hi:[0,1]
	v_pk_add_f32 v[66:67], v[24:25], v[80:81]
	v_pk_add_f32 v[10:11], v[24:25], v[80:81] neg_lo:[0,1] neg_hi:[0,1]
	v_pk_add_f32 v[72:73], v[14:15], v[34:35]
	v_pk_add_f32 v[24:25], v[14:15], v[34:35] neg_lo:[0,1] neg_hi:[0,1]
	v_mul_f32_e32 v15, 0x38800000, v18
	v_cos_f32_e32 v14, v15
	v_sin_f32_e32 v15, v15
	v_pk_add_f32 v[16:17], v[74:75], v[62:63]
	v_pk_add_f32 v[54:55], v[74:75], v[62:63] neg_lo:[0,1] neg_hi:[0,1]
	v_pk_add_f32 v[62:63], v[8:9], v[44:45]
	v_pk_add_f32 v[4:5], v[8:9], v[44:45] neg_lo:[0,1] neg_hi:[0,1]
	v_pk_add_f32 v[8:9], v[26:27], v[58:59]
	v_add_f32_e32 v20, v14, v14
	v_pk_add_f32 v[42:43], v[38:39], v[46:47]
	v_pk_add_f32 v[38:39], v[38:39], v[46:47] neg_lo:[0,1] neg_hi:[0,1]
	v_pk_add_f32 v[58:59], v[26:27], v[58:59] neg_lo:[0,1] neg_hi:[0,1]
	v_pk_add_f32 v[26:27], v[76:77], v[78:79]
	v_pk_add_f32 v[46:47], v[76:77], v[78:79] neg_lo:[0,1] neg_hi:[0,1]
	v_pk_mul_f32 v[18:19], v[14:15], v[14:15]
	v_mul_f32_e32 v20, v15, v20
	v_mov_b32_e32 v78, v15
	v_pk_add_f32 v[18:19], v[18:19], v[18:19] op_sel:[0,1] op_sel_hi:[0,1] neg_lo:[0,1] neg_hi:[0,1]
	v_pk_mul_f32 v[34:35], v[14:15], v[20:21] op_sel:[1,0] op_sel_hi:[0,0] neg_lo:[1,0]
	v_pk_mul_f32 v[36:37], v[78:79], v[8:9] op_sel:[0,1] op_sel_hi:[0,0] neg_hi:[0,1]
	v_pk_fma_f32 v[34:35], v[14:15], v[18:19], v[34:35]
	v_pk_fma_f32 v[8:9], v[14:15], v[8:9], v[36:37] op_sel_hi:[0,1,1]
	v_pk_mul_f32 v[14:15], v[20:21], s[46:47] op_sel_hi:[0,1]
	v_pk_fma_f32 v[36:37], v[18:19], s[40:41], v[14:15]
	v_pk_mul_f32 v[14:15], v[16:17], v[36:37] op_sel:[1,1] op_sel_hi:[0,1] neg_hi:[1,0]
	v_pk_add_f32 v[74:75], v[82:83], v[84:85]
	v_pk_fma_f32 v[16:17], v[16:17], v[36:37], v[14:15] op_sel_hi:[1,0,1]
	v_pk_mul_f32 v[14:15], v[20:21], v[34:35] op_sel:[0,1] op_sel_hi:[0,0] neg_lo:[0,1]
	v_pk_fma_f32 v[78:79], v[18:19], v[34:35], v[14:15]
	v_pk_mul_f32 v[14:15], v[34:35], v[52:53] op_sel:[1,1] op_sel_hi:[1,0] neg_hi:[0,1]
	v_pk_add_f32 v[76:77], v[12:13], v[86:87]
	v_pk_fma_f32 v[14:15], v[34:35], v[52:53], v[14:15] op_sel_hi:[0,1,1]
	v_pk_mul_f32 v[34:35], v[20:21], v[36:37] op_sel:[0,1] op_sel_hi:[0,0] neg_lo:[0,1]
	v_pk_fma_f32 v[36:37], v[18:19], v[36:37], v[34:35]
	v_pk_mul_f32 v[52:53], v[26:27], v[78:79] op_sel:[1,1] op_sel_hi:[0,1] neg_hi:[1,0]
	v_pk_mul_f32 v[34:35], v[32:33], v[36:37] op_sel:[1,1] op_sel_hi:[0,1] neg_hi:[1,0]
	v_pk_fma_f32 v[26:27], v[26:27], v[78:79], v[52:53] op_sel_hi:[1,0,1]
	v_pk_fma_f32 v[34:35], v[32:33], v[36:37], v[34:35] op_sel_hi:[1,0,1]
	v_pk_mul_f32 v[52:53], v[20:21], v[36:37] op_sel:[0,1] op_sel_hi:[0,0] neg_lo:[0,1]
	v_pk_mul_f32 v[32:33], v[20:21], v[78:79] op_sel:[0,1] op_sel_hi:[0,0] neg_lo:[0,1]
	v_pk_fma_f32 v[52:53], v[18:19], v[36:37], v[52:53]
	v_pk_fma_f32 v[32:33], v[18:19], v[78:79], v[32:33]
	v_pk_mul_f32 v[36:37], v[42:43], v[52:53] op_sel:[1,1] op_sel_hi:[0,1] neg_hi:[1,0]
	v_pk_fma_f32 v[36:37], v[42:43], v[52:53], v[36:37] op_sel_hi:[1,0,1]
	v_pk_mul_f32 v[42:43], v[20:21], v[32:33] op_sel:[0,1] op_sel_hi:[0,0] neg_lo:[0,1]
	v_pk_mul_f32 v[78:79], v[74:75], v[32:33] op_sel:[1,1] op_sel_hi:[0,1] neg_hi:[1,0]
	v_pk_fma_f32 v[42:43], v[18:19], v[32:33], v[42:43]
	v_pk_fma_f32 v[32:33], v[74:75], v[32:33], v[78:79] op_sel_hi:[1,0,1]
	v_pk_mul_f32 v[74:75], v[20:21], v[52:53] op_sel:[0,1] op_sel_hi:[0,0] neg_lo:[0,1]
	v_pk_fma_f32 v[52:53], v[18:19], v[52:53], v[74:75]
	v_pk_mul_f32 v[74:75], v[48:49], v[52:53] op_sel:[1,1] op_sel_hi:[0,1] neg_hi:[1,0]
	v_pk_fma_f32 v[48:49], v[48:49], v[52:53], v[74:75] op_sel_hi:[1,0,1]
	v_pk_mul_f32 v[74:75], v[20:21], v[42:43] op_sel:[0,1] op_sel_hi:[0,0] neg_lo:[0,1]
	v_pk_mul_f32 v[78:79], v[50:51], v[42:43] op_sel:[1,1] op_sel_hi:[0,1] neg_hi:[1,0]
	v_pk_fma_f32 v[74:75], v[18:19], v[42:43], v[74:75]
	v_pk_fma_f32 v[42:43], v[50:51], v[42:43], v[78:79] op_sel_hi:[1,0,1]
	v_pk_mul_f32 v[50:51], v[20:21], v[52:53] op_sel:[0,1] op_sel_hi:[0,0] neg_lo:[0,1]
	v_pk_fma_f32 v[78:79], v[18:19], v[52:53], v[50:51]
	v_pk_mul_f32 v[50:51], v[60:61], v[78:79] op_sel:[1,1] op_sel_hi:[0,1] neg_hi:[1,0]
	v_xor_b32_e32 v81, 0x80000000, v58
	v_pk_fma_f32 v[52:53], v[60:61], v[78:79], v[50:51] op_sel_hi:[1,0,1]
	v_pk_mul_f32 v[50:51], v[20:21], v[74:75] op_sel:[0,1] op_sel_hi:[0,0] neg_lo:[0,1]
	v_pk_fma_f32 v[60:61], v[18:19], v[74:75], v[50:51]
	v_pk_mul_f32 v[50:51], v[72:73], v[74:75] op_sel:[1,1] op_sel_hi:[0,1] neg_hi:[1,0]
	v_mov_b32_e32 v80, v59
	v_pk_fma_f32 v[50:51], v[72:73], v[74:75], v[50:51] op_sel_hi:[1,0,1]
	v_pk_mul_f32 v[72:73], v[20:21], v[78:79] op_sel:[0,1] op_sel_hi:[0,0] neg_lo:[0,1]
	v_pk_fma_f32 v[72:73], v[18:19], v[78:79], v[72:73]
	v_pk_mul_f32 v[74:75], v[64:65], v[72:73] op_sel:[1,1] op_sel_hi:[0,1] neg_hi:[1,0]
	v_pk_fma_f32 v[64:65], v[64:65], v[72:73], v[74:75] op_sel_hi:[1,0,1]
	v_pk_mul_f32 v[74:75], v[20:21], v[60:61] op_sel:[0,1] op_sel_hi:[0,0] neg_lo:[0,1]
	v_pk_mul_f32 v[78:79], v[66:67], v[60:61] op_sel:[1,1] op_sel_hi:[0,1] neg_hi:[1,0]
	v_pk_fma_f32 v[74:75], v[18:19], v[60:61], v[74:75]
	v_pk_fma_f32 v[60:61], v[66:67], v[60:61], v[78:79] op_sel_hi:[1,0,1]
	v_pk_mul_f32 v[66:67], v[20:21], v[72:73] op_sel:[0,1] op_sel_hi:[0,0] neg_lo:[0,1]
	v_pk_fma_f32 v[66:67], v[18:19], v[72:73], v[66:67]
	v_pk_mul_f32 v[72:73], v[62:63], v[66:67] op_sel:[1,1] op_sel_hi:[0,1] neg_hi:[1,0]
	v_pk_fma_f32 v[62:63], v[62:63], v[66:67], v[72:73] op_sel_hi:[1,0,1]
	v_pk_mul_f32 v[72:73], v[20:21], v[74:75] op_sel:[0,1] op_sel_hi:[0,0] neg_lo:[0,1]
	v_pk_mul_f32 v[78:79], v[76:77], v[74:75] op_sel:[1,1] op_sel_hi:[0,1] neg_hi:[1,0]
	v_pk_fma_f32 v[72:73], v[18:19], v[74:75], v[72:73]
	v_pk_fma_f32 v[74:75], v[76:77], v[74:75], v[78:79] op_sel_hi:[1,0,1]
	v_pk_mul_f32 v[76:77], v[20:21], v[66:67] op_sel:[0,1] op_sel_hi:[0,0] neg_lo:[0,1]
	v_pk_fma_f32 v[66:67], v[18:19], v[66:67], v[76:77]
	v_pk_mul_f32 v[78:79], v[20:21], v[72:73] op_sel:[0,1] op_sel_hi:[0,0] neg_lo:[0,1]
	v_pk_mul_f32 v[80:81], v[80:81], v[72:73] op_sel:[0,1]
	v_pk_fma_f32 v[78:79], v[18:19], v[72:73], v[78:79]
	v_pk_fma_f32 v[58:59], v[58:59], v[72:73], v[80:81] op_sel_hi:[1,0,1]
	v_pk_mul_f32 v[76:77], v[88:89], v[66:67] op_sel:[1,1] op_sel_hi:[0,1] neg_hi:[1,0]
	v_pk_mul_f32 v[72:73], v[20:21], v[66:67] op_sel:[0,1] op_sel_hi:[0,0] neg_lo:[0,1]
	v_pk_fma_f32 v[76:77], v[88:89], v[66:67], v[76:77] op_sel_hi:[1,0,1]
	v_pk_fma_f32 v[66:67], v[18:19], v[66:67], v[72:73]
	v_pk_mul_f32 v[72:73], v[54:55], v[66:67] op_sel:[1,1] op_sel_hi:[0,1] neg_hi:[1,0]
	v_pk_fma_f32 v[54:55], v[54:55], v[66:67], v[72:73] op_sel_hi:[1,0,1]
	v_pk_mul_f32 v[72:73], v[20:21], v[78:79] op_sel:[0,1] op_sel_hi:[0,0] neg_lo:[0,1]
	v_pk_mul_f32 v[80:81], v[56:57], v[78:79] op_sel:[1,1] op_sel_hi:[0,1] neg_hi:[1,0]
	v_pk_fma_f32 v[72:73], v[18:19], v[78:79], v[72:73]
	v_pk_fma_f32 v[56:57], v[56:57], v[78:79], v[80:81] op_sel_hi:[1,0,1]
	v_pk_mul_f32 v[78:79], v[20:21], v[66:67] op_sel:[0,1] op_sel_hi:[0,0] neg_lo:[0,1]
	v_pk_fma_f32 v[66:67], v[18:19], v[66:67], v[78:79]
	v_pk_mul_f32 v[78:79], v[40:41], v[66:67] op_sel:[1,1] op_sel_hi:[0,1] neg_hi:[1,0]
	v_pk_fma_f32 v[40:41], v[40:41], v[66:67], v[78:79] op_sel_hi:[1,0,1]
	v_pk_mul_f32 v[78:79], v[20:21], v[72:73] op_sel:[0,1] op_sel_hi:[0,0] neg_lo:[0,1]
	v_pk_mul_f32 v[80:81], v[46:47], v[72:73] op_sel:[1,1] op_sel_hi:[0,1] neg_hi:[1,0]
	v_pk_fma_f32 v[78:79], v[18:19], v[72:73], v[78:79]
	v_pk_fma_f32 v[46:47], v[46:47], v[72:73], v[80:81] op_sel_hi:[1,0,1]
	v_pk_mul_f32 v[72:73], v[20:21], v[66:67] op_sel:[0,1] op_sel_hi:[0,0] neg_lo:[0,1]
	v_pk_fma_f32 v[66:67], v[18:19], v[66:67], v[72:73]
	v_pk_add_f32 v[44:45], v[82:83], v[84:85] neg_lo:[0,1] neg_hi:[0,1]
	v_pk_mul_f32 v[72:73], v[38:39], v[66:67] op_sel:[1,1] op_sel_hi:[0,1] neg_hi:[1,0]
	v_pk_fma_f32 v[38:39], v[38:39], v[66:67], v[72:73] op_sel_hi:[1,0,1]
	v_pk_mul_f32 v[72:73], v[20:21], v[78:79] op_sel:[0,1] op_sel_hi:[0,0] neg_lo:[0,1]
	v_pk_mul_f32 v[80:81], v[44:45], v[78:79] op_sel:[1,1] op_sel_hi:[0,1] neg_hi:[1,0]
	v_pk_fma_f32 v[72:73], v[18:19], v[78:79], v[72:73]
	v_pk_fma_f32 v[44:45], v[44:45], v[78:79], v[80:81] op_sel_hi:[1,0,1]
	v_pk_mul_f32 v[78:79], v[20:21], v[66:67] op_sel:[0,1] op_sel_hi:[0,0] neg_lo:[0,1]
	v_pk_fma_f32 v[66:67], v[18:19], v[66:67], v[78:79]
	v_pk_mul_f32 v[78:79], v[28:29], v[66:67] op_sel:[1,1] op_sel_hi:[0,1] neg_hi:[1,0]
	v_pk_fma_f32 v[28:29], v[28:29], v[66:67], v[78:79] op_sel_hi:[1,0,1]
	v_pk_mul_f32 v[78:79], v[20:21], v[72:73] op_sel:[0,1] op_sel_hi:[0,0] neg_lo:[0,1]
	v_pk_mul_f32 v[80:81], v[30:31], v[72:73] op_sel:[1,1] op_sel_hi:[0,1] neg_hi:[1,0]
	v_pk_fma_f32 v[78:79], v[18:19], v[72:73], v[78:79]
	v_pk_fma_f32 v[30:31], v[30:31], v[72:73], v[80:81] op_sel_hi:[1,0,1]
	v_pk_mul_f32 v[72:73], v[20:21], v[66:67] op_sel:[0,1] op_sel_hi:[0,0] neg_lo:[0,1]
	v_pk_fma_f32 v[66:67], v[18:19], v[66:67], v[72:73]
	v_pk_mul_f32 v[72:73], v[22:23], v[66:67] op_sel:[1,1] op_sel_hi:[0,1] neg_hi:[1,0]
	v_pk_fma_f32 v[22:23], v[22:23], v[66:67], v[72:73] op_sel_hi:[1,0,1]
	v_pk_mul_f32 v[72:73], v[20:21], v[78:79] op_sel:[0,1] op_sel_hi:[0,0] neg_lo:[0,1]
	v_pk_mul_f32 v[80:81], v[24:25], v[78:79] op_sel:[1,1] op_sel_hi:[0,1] neg_hi:[1,0]
	v_pk_fma_f32 v[72:73], v[18:19], v[78:79], v[72:73]
	v_pk_fma_f32 v[24:25], v[24:25], v[78:79], v[80:81] op_sel_hi:[1,0,1]
	v_pk_mul_f32 v[78:79], v[20:21], v[66:67] op_sel:[0,1] op_sel_hi:[0,0] neg_lo:[0,1]
	v_pk_fma_f32 v[66:67], v[18:19], v[66:67], v[78:79]
	v_pk_mul_f32 v[78:79], v[6:7], v[66:67] op_sel:[1,1] op_sel_hi:[0,1] neg_hi:[1,0]
	v_pk_fma_f32 v[6:7], v[6:7], v[66:67], v[78:79] op_sel_hi:[1,0,1]
	v_pk_mul_f32 v[78:79], v[20:21], v[72:73] op_sel:[0,1] op_sel_hi:[0,0] neg_lo:[0,1]
	v_pk_mul_f32 v[80:81], v[10:11], v[72:73] op_sel:[1,1] op_sel_hi:[0,1] neg_hi:[1,0]
	v_pk_fma_f32 v[78:79], v[18:19], v[72:73], v[78:79]
	v_pk_fma_f32 v[10:11], v[10:11], v[72:73], v[80:81] op_sel_hi:[1,0,1]
	v_pk_mul_f32 v[72:73], v[20:21], v[66:67] op_sel:[0,1] op_sel_hi:[0,0] neg_lo:[0,1]
	v_pk_fma_f32 v[18:19], v[18:19], v[66:67], v[72:73]
	v_pk_add_f32 v[12:13], v[12:13], v[86:87] neg_lo:[0,1] neg_hi:[0,1]
	v_pk_mul_f32 v[66:67], v[4:5], v[18:19] op_sel:[1,1] op_sel_hi:[0,1] neg_hi:[1,0]
	v_pk_fma_f32 v[4:5], v[4:5], v[18:19], v[66:67] op_sel_hi:[1,0,1]
	v_pk_mul_f32 v[18:19], v[12:13], v[78:79] op_sel:[1,1] op_sel_hi:[0,1] neg_hi:[1,0]
	s_nop 0
	v_pk_fma_f32 v[12:13], v[12:13], v[78:79], v[18:19] op_sel_hi:[1,0,1]
	v_lshrrev_b32_e32 v18, 5, v21
	v_bitop3_b32 v18, v18, v21, 15 bitop3:0x6c
	v_lshlrev_b32_e32 v18, 3, v18
	v_bfe_u32 v19, v21, 5, 4
	v_add_u32_e32 v20, 16, v18
	ds_write_b64 v20, v[2:3]
	v_bitop3_b32 v2, v19, v21, 16 bitop3:0x36
	v_lshl_add_u32 v2, v2, 3, 16
	v_add_u32_e32 v3, s79, v18
	ds_write_b64 v2, v[76:77] offset:4096
	ds_write_b64 v20, v[48:49] offset:8192
	ds_write_b64 v2, v[28:29] offset:12288
	ds_write_b64 v20, v[34:35] offset:16384
	ds_write_b64 v2, v[40:41] offset:20480
	ds_write_b64 v20, v[64:65] offset:24576
	ds_write_b64 v2, v[6:7] offset:28672
	ds_write_b64 v20, v[16:17] offset:32768
	ds_write_b64 v2, v[54:55] offset:36864
	ds_write_b64 v20, v[52:53] offset:40960
	ds_write_b64 v2, v[22:23] offset:45056
	ds_write_b64 v20, v[36:37] offset:49152
	ds_write_b64 v2, v[38:39] offset:53248
	ds_write_b64 v20, v[62:63] offset:57344
	ds_write_b64 v2, v[4:5] offset:61440
	ds_write_b64 v3, v[8:9]
	v_add_u32_e32 v3, 0x11000, v2
	ds_write_b64 v3, v[58:59]
	v_add_u32_e32 v3, 0x12000, v20
	ds_write_b64 v3, v[42:43]
	v_add_u32_e32 v3, 0x13000, v2
	ds_write_b64 v3, v[30:31]
	v_add_u32_e32 v3, 0x14000, v20
	ds_write_b64 v3, v[26:27]
	v_add_u32_e32 v3, 0x15000, v2
	ds_write_b64 v3, v[46:47]
	v_add_u32_e32 v3, 0x16000, v20
	ds_write_b64 v3, v[60:61]
	v_add_u32_e32 v3, 0x17000, v2
	ds_write_b64 v3, v[10:11]
	v_add_u32_e32 v3, 0x18000, v20
	ds_write_b64 v3, v[14:15]
	v_add_u32_e32 v3, 0x19000, v2
	ds_write_b64 v3, v[56:57]
	v_add_u32_e32 v3, 0x1a000, v20
	ds_write_b64 v3, v[50:51]
	v_add_u32_e32 v3, 0x1b000, v2
	ds_write_b64 v3, v[24:25]
	v_add_u32_e32 v3, 0x1c000, v20
	ds_write_b64 v3, v[32:33]
	v_add_u32_e32 v3, 0x1d000, v2
	ds_write_b64 v3, v[44:45]
	v_add_u32_e32 v3, 0x1e000, v20
	v_add_u32_e32 v2, 0x1f000, v2
	v_mov_b32_e32 v11, v146
	ds_write_b64 v3, v[74:75]
	ds_write_b64 v2, v[12:13]
	s_waitcnt lgkmcnt(0)
	s_barrier
	s_nop 0
	v_lshlrev_b32_e32 v2, 5, v11
	v_and_b32_e32 v2, 0xfffffe00, v2
	v_and_or_b32 v3, v11, 16, v2
	v_bitop3_b32 v2, v2, 16, v11 bitop3:0x34
	v_bitop3_b32 v12, v11, 2, 15 bitop3:0x6c
	v_bitop3_b32 v22, v11, 4, 15 bitop3:0x6c
	v_bitop3_b32 v30, v11, 6, 15 bitop3:0x6c
	v_bitop3_b32 v38, v11, 8, 15 bitop3:0x6c
	v_and_b32_e32 v10, 15, v11
	v_lshl_add_u32 v18, v3, 3, 16
	v_lshl_add_u32 v87, v2, 3, 16
	v_lshlrev_b32_e32 v12, 3, v12
	v_lshlrev_b32_e32 v22, 3, v22
	v_lshlrev_b32_e32 v30, 3, v30
	v_lshlrev_b32_e32 v38, 3, v38
	v_lshlrev_b32_e32 v3, 3, v10
	v_bitop3_b32 v2, v11, 1, 15 bitop3:0x6c
	v_add_u32_e32 v57, v18, v12
	v_add_u32_e32 v58, v87, v12
	v_bitop3_b32 v12, v11, 3, 15 bitop3:0x6c
	v_add_u32_e32 v61, v18, v22
	v_add_u32_e32 v62, v87, v22
	v_bitop3_b32 v22, v11, 5, 15 bitop3:0x6c
	v_add_u32_e32 v65, v18, v30
	v_add_u32_e32 v66, v87, v30
	v_bitop3_b32 v30, v11, 7, 15 bitop3:0x6c
	v_add_u32_e32 v72, v18, v38
	v_add_u32_e32 v73, v87, v38
	v_bitop3_b32 v38, v11, 9, 15 bitop3:0x6c
	v_add_u32_e32 v19, v18, v3
	v_lshlrev_b32_e32 v2, 3, v2
	v_lshlrev_b32_e32 v12, 3, v12
	v_lshlrev_b32_e32 v22, 3, v22
	v_lshlrev_b32_e32 v30, 3, v30
	v_lshlrev_b32_e32 v38, 3, v38
	v_add_u32_e32 v54, v87, v3
	v_add_u32_e32 v55, v18, v2
	v_add_u32_e32 v56, v87, v2
	ds_read_b64 v[2:3], v19
	ds_read_b64 v[4:5], v54
	ds_read_b64 v[6:7], v55 offset:256
	ds_read_b64 v[8:9], v56 offset:256
	v_add_u32_e32 v59, v18, v12
	v_add_u32_e32 v60, v87, v12
	ds_read_b64 v[12:13], v57 offset:512
	ds_read_b64 v[14:15], v58 offset:512
	ds_read_b64 v[16:17], v59 offset:768
	ds_read_b64 v[20:21], v60 offset:768
	v_add_u32_e32 v63, v18, v22
	v_add_u32_e32 v64, v87, v22
	ds_read_b64 v[22:23], v61 offset:1024
	ds_read_b64 v[24:25], v62 offset:1024
	ds_read_b64 v[26:27], v63 offset:1280
	ds_read_b64 v[28:29], v64 offset:1280
	v_add_u32_e32 v67, v18, v30
	v_add_u32_e32 v71, v87, v30
	ds_read_b64 v[30:31], v65 offset:1536
	ds_read_b64 v[32:33], v66 offset:1536
	ds_read_b64 v[34:35], v67 offset:1792
	ds_read_b64 v[36:37], v71 offset:1792
	v_add_u32_e32 v74, v18, v38
	v_add_u32_e32 v75, v87, v38
	ds_read_b64 v[38:39], v72 offset:2048
	ds_read_b64 v[40:41], v73 offset:2048
	ds_read_b64 v[42:43], v74 offset:2304
	ds_read_b64 v[44:45], v75 offset:2304
	v_bitop3_b32 v46, v11, 10, 15 bitop3:0x6c
	s_waitcnt lgkmcnt(3)
	v_pk_add_f32 v[104:105], v[2:3], v[38:39]
	v_pk_add_f32 v[2:3], v[2:3], v[38:39] neg_lo:[0,1] neg_hi:[0,1]
	s_waitcnt lgkmcnt(2)
	v_pk_add_f32 v[38:39], v[4:5], v[40:41]
	v_pk_add_f32 v[4:5], v[4:5], v[40:41] neg_lo:[0,1] neg_hi:[0,1]
	v_lshlrev_b32_e32 v46, 3, v46
	v_pk_mul_f32 v[40:41], v[4:5], s[48:49] op_sel:[1,0] op_sel_hi:[0,0] neg_hi:[1,0]
	v_add_u32_e32 v76, v18, v46
	v_pk_fma_f32 v[4:5], v[4:5], s[44:45], v[40:41] op_sel_hi:[1,0,1]
	s_waitcnt lgkmcnt(1)
	v_pk_add_f32 v[40:41], v[6:7], v[42:43]
	v_pk_add_f32 v[6:7], v[6:7], v[42:43] neg_lo:[0,1] neg_hi:[0,1]
	v_add_u32_e32 v77, v87, v46
	v_bitop3_b32 v46, v11, 11, 15 bitop3:0x6c
	v_pk_mul_f32 v[42:43], v[6:7], s[54:55] op_sel:[1,0] op_sel_hi:[0,0] neg_hi:[1,0]
	v_lshlrev_b32_e32 v46, 3, v46
	v_pk_fma_f32 v[6:7], v[6:7], s[52:53], v[42:43] op_sel_hi:[1,0,1]
	s_waitcnt lgkmcnt(0)
	v_pk_add_f32 v[42:43], v[8:9], v[44:45]
	v_pk_add_f32 v[8:9], v[8:9], v[44:45] neg_lo:[0,1] neg_hi:[0,1]
	v_add_u32_e32 v78, v18, v46
	v_add_u32_e32 v79, v87, v46
	ds_read_b64 v[46:47], v76 offset:2560
	ds_read_b64 v[48:49], v77 offset:2560
	ds_read_b64 v[50:51], v78 offset:2816
	ds_read_b64 v[52:53], v79 offset:2816
	v_pk_mul_f32 v[44:45], v[8:9], s[58:59] op_sel:[1,0] op_sel_hi:[0,0] neg_hi:[1,0]
	v_bitop3_b32 v80, v11, 12, 15 bitop3:0x6c
	v_pk_fma_f32 v[8:9], v[8:9], s[56:57], v[44:45] op_sel_hi:[1,0,1]
	s_waitcnt lgkmcnt(3)
	v_pk_add_f32 v[44:45], v[12:13], v[46:47]
	v_pk_add_f32 v[12:13], v[12:13], v[46:47] neg_lo:[0,1] neg_hi:[0,1]
	v_lshlrev_b32_e32 v81, 3, v80
	v_pk_mul_f32 v[46:47], v[12:13], s[60:61] op_sel:[1,0] op_sel_hi:[0,0] neg_hi:[1,0]
	v_bitop3_b32 v82, v11, 13, 15 bitop3:0x6c
	v_pk_fma_f32 v[12:13], v[12:13], s[60:61], v[46:47] op_sel_hi:[1,0,1]
	s_waitcnt lgkmcnt(2)
	v_pk_add_f32 v[46:47], v[14:15], v[48:49]
	v_pk_add_f32 v[14:15], v[14:15], v[48:49] neg_lo:[0,1] neg_hi:[0,1]
	v_add_u32_e32 v80, v18, v81
	v_pk_mul_f32 v[48:49], v[14:15], s[56:57] op_sel:[1,0] op_sel_hi:[0,0] neg_hi:[1,0]
	v_lshlrev_b32_e32 v83, 3, v82
	v_pk_fma_f32 v[14:15], v[14:15], s[58:59], v[48:49] op_sel_hi:[1,0,1]
	s_waitcnt lgkmcnt(1)
	v_pk_add_f32 v[48:49], v[16:17], v[50:51]
	v_pk_add_f32 v[16:17], v[16:17], v[50:51] neg_lo:[0,1] neg_hi:[0,1]
	v_add_u32_e32 v81, v87, v81
	v_pk_mul_f32 v[50:51], v[16:17], s[52:53] op_sel:[1,0] op_sel_hi:[0,0] neg_hi:[1,0]
	v_add_u32_e32 v82, v18, v83
	v_pk_fma_f32 v[16:17], v[16:17], s[54:55], v[50:51] op_sel_hi:[1,0,1]
	s_waitcnt lgkmcnt(0)
	v_pk_add_f32 v[50:51], v[20:21], v[52:53]
	v_pk_add_f32 v[20:21], v[20:21], v[52:53] neg_lo:[0,1] neg_hi:[0,1]
	v_add_u32_e32 v83, v87, v83
	ds_read_b64 v[88:89], v80 offset:3072
	ds_read_b64 v[90:91], v81 offset:3072
	ds_read_b64 v[92:93], v82 offset:3328
	ds_read_b64 v[94:95], v83 offset:3328
	v_pk_mul_f32 v[52:53], v[20:21], s[44:45] op_sel:[1,0] op_sel_hi:[0,0] neg_hi:[1,0]
	v_bitop3_b32 v84, v11, 14, 15 bitop3:0x6c
	v_pk_fma_f32 v[20:21], v[20:21], s[48:49], v[52:53] op_sel_hi:[1,0,1]
	s_waitcnt lgkmcnt(3)
	v_pk_add_f32 v[52:53], v[22:23], v[88:89]
	v_pk_add_f32 v[22:23], v[22:23], v[88:89] neg_lo:[0,1] neg_hi:[0,1]
	v_lshlrev_b32_e32 v85, 3, v84
	v_xor_b32_e32 v89, 0x80000000, v22
	v_mov_b32_e32 v88, v23
	s_waitcnt lgkmcnt(2)
	v_pk_add_f32 v[22:23], v[24:25], v[90:91]
	v_pk_add_f32 v[24:25], v[24:25], v[90:91] neg_lo:[0,1] neg_hi:[0,1]
	v_bitop3_b32 v11, v11, 15, v11 bitop3:0xc
	v_pk_mul_f32 v[90:91], v[24:25], s[48:49] op_sel_hi:[1,0]
	v_xor_b32_e32 v107, 0x80000000, v24
	v_mov_b32_e32 v106, v25
	v_pk_fma_f32 v[24:25], v[106:107], s[44:45], v[90:91] op_sel_hi:[1,0,1] neg_lo:[0,0,1] neg_hi:[0,0,1]
	s_waitcnt lgkmcnt(1)
	v_pk_add_f32 v[90:91], v[26:27], v[92:93]
	v_pk_add_f32 v[26:27], v[26:27], v[92:93] neg_lo:[0,1] neg_hi:[0,1]
	v_add_u32_e32 v84, v18, v85
	v_lshlrev_b32_e32 v11, 3, v11
	v_pk_mul_f32 v[92:93], v[26:27], s[54:55] op_sel_hi:[1,0]
	v_xor_b32_e32 v107, 0x80000000, v26
	v_mov_b32_e32 v106, v27
	v_add_u32_e32 v85, v87, v85
	v_add_u32_e32 v86, v18, v11
	v_add_u32_e32 v87, v87, v11
	ds_read_b64 v[96:97], v84 offset:3584
	ds_read_b64 v[98:99], v85 offset:3584
	ds_read_b64 v[100:101], v86 offset:3840
	ds_read_b64 v[102:103], v87 offset:3840
	v_pk_fma_f32 v[26:27], v[106:107], s[52:53], v[92:93] op_sel_hi:[1,0,1] neg_lo:[0,0,1] neg_hi:[0,0,1]
	s_waitcnt lgkmcnt(4)
	v_pk_add_f32 v[92:93], v[28:29], v[94:95]
	v_pk_add_f32 v[28:29], v[28:29], v[94:95] neg_lo:[0,1] neg_hi:[0,1]
	s_nop 0
	v_pk_mul_f32 v[94:95], v[28:29], s[58:59] op_sel_hi:[1,0]
	v_xor_b32_e32 v107, 0x80000000, v28
	v_mov_b32_e32 v106, v29
	v_pk_fma_f32 v[28:29], v[106:107], s[56:57], v[94:95] op_sel_hi:[1,0,1] neg_lo:[0,0,1] neg_hi:[0,0,1]
	s_waitcnt lgkmcnt(3)
	v_pk_add_f32 v[94:95], v[30:31], v[96:97]
	v_pk_add_f32 v[30:31], v[30:31], v[96:97] neg_lo:[0,1] neg_hi:[0,1]
	v_cvt_f32_i32_e32 v10, v10
	v_pk_mul_f32 v[96:97], v[30:31], s[60:61] op_sel_hi:[1,0]
	v_xor_b32_e32 v107, 0x80000000, v30
	v_mov_b32_e32 v106, v31
	v_pk_fma_f32 v[30:31], v[106:107], s[60:61], v[96:97] op_sel_hi:[1,0,1] neg_lo:[0,0,1] neg_hi:[0,0,1]
	s_waitcnt lgkmcnt(2)
	v_pk_add_f32 v[96:97], v[32:33], v[98:99]
	v_pk_add_f32 v[32:33], v[32:33], v[98:99] neg_lo:[0,1] neg_hi:[0,1]
	v_mul_f32_e32 v10, 0x3b000000, v10
	v_pk_mul_f32 v[98:99], v[32:33], s[56:57] op_sel_hi:[1,0]
	v_xor_b32_e32 v107, 0x80000000, v32
	v_mov_b32_e32 v106, v33
	v_pk_fma_f32 v[32:33], v[106:107], s[58:59], v[98:99] op_sel_hi:[1,0,1] neg_lo:[0,0,1] neg_hi:[0,0,1]
	s_waitcnt lgkmcnt(1)
	v_pk_add_f32 v[98:99], v[34:35], v[100:101]
	v_pk_add_f32 v[34:35], v[34:35], v[100:101] neg_lo:[0,1] neg_hi:[0,1]
	s_nop 0
	v_pk_mul_f32 v[100:101], v[34:35], s[52:53] op_sel_hi:[1,0]
	v_xor_b32_e32 v107, 0x80000000, v34
	v_mov_b32_e32 v106, v35
	v_pk_fma_f32 v[34:35], v[106:107], s[54:55], v[100:101] op_sel_hi:[1,0,1] neg_lo:[0,0,1] neg_hi:[0,0,1]
	s_waitcnt lgkmcnt(0)
	v_pk_add_f32 v[100:101], v[36:37], v[102:103]
	v_pk_add_f32 v[36:37], v[36:37], v[102:103] neg_lo:[0,1] neg_hi:[0,1]
	s_nop 0
	v_pk_mul_f32 v[102:103], v[36:37], s[44:45] op_sel_hi:[1,0]
	v_xor_b32_e32 v107, 0x80000000, v36
	v_mov_b32_e32 v106, v37
	v_pk_fma_f32 v[36:37], v[106:107], s[48:49], v[102:103] op_sel_hi:[1,0,1] neg_lo:[0,0,1] neg_hi:[0,0,1]
	v_pk_add_f32 v[102:103], v[104:105], v[52:53]
	v_pk_add_f32 v[52:53], v[104:105], v[52:53] neg_lo:[0,1] neg_hi:[0,1]
	v_pk_add_f32 v[104:105], v[38:39], v[22:23]
	v_pk_add_f32 v[22:23], v[38:39], v[22:23] neg_lo:[0,1] neg_hi:[0,1]
	v_pk_mul_f32 v[38:39], v[22:23], s[54:55] op_sel:[1,0] op_sel_hi:[0,0] neg_hi:[1,0]
	v_pk_fma_f32 v[22:23], v[22:23], s[52:53], v[38:39] op_sel_hi:[1,0,1]
	v_pk_add_f32 v[38:39], v[40:41], v[90:91]
	v_pk_add_f32 v[40:41], v[40:41], v[90:91] neg_lo:[0,1] neg_hi:[0,1]
	v_pk_mul_f32 v[90:91], v[40:41], s[60:61] op_sel:[1,0] op_sel_hi:[0,0] neg_hi:[1,0]
	v_pk_fma_f32 v[40:41], v[40:41], s[60:61], v[90:91] op_sel_hi:[1,0,1]
	v_pk_add_f32 v[90:91], v[42:43], v[92:93]
	v_pk_add_f32 v[42:43], v[42:43], v[92:93] neg_lo:[0,1] neg_hi:[0,1]
	v_pk_mul_f32 v[92:93], v[42:43], s[52:53] op_sel:[1,0] op_sel_hi:[0,0] neg_hi:[1,0]
	v_pk_fma_f32 v[42:43], v[42:43], s[54:55], v[92:93] op_sel_hi:[1,0,1]
	v_pk_add_f32 v[92:93], v[44:45], v[94:95]
	v_pk_add_f32 v[44:45], v[44:45], v[94:95] neg_lo:[0,1] neg_hi:[0,1]
	v_xor_b32_e32 v95, 0x80000000, v44
	v_mov_b32_e32 v94, v45
	v_pk_add_f32 v[44:45], v[46:47], v[96:97]
	v_pk_add_f32 v[46:47], v[46:47], v[96:97] neg_lo:[0,1] neg_hi:[0,1]
	v_pk_mul_f32 v[96:97], v[46:47], s[54:55] op_sel_hi:[1,0]
	v_xor_b32_e32 v107, 0x80000000, v46
	v_mov_b32_e32 v106, v47
	v_pk_fma_f32 v[46:47], v[106:107], s[52:53], v[96:97] op_sel_hi:[1,0,1] neg_lo:[0,0,1] neg_hi:[0,0,1]
	v_pk_add_f32 v[96:97], v[48:49], v[98:99]
	v_pk_add_f32 v[48:49], v[48:49], v[98:99] neg_lo:[0,1] neg_hi:[0,1]
	v_pk_mul_f32 v[98:99], v[48:49], s[60:61] op_sel_hi:[1,0]
	v_xor_b32_e32 v107, 0x80000000, v48
	v_mov_b32_e32 v106, v49
	v_pk_fma_f32 v[48:49], v[106:107], s[60:61], v[98:99] op_sel_hi:[1,0,1] neg_lo:[0,0,1] neg_hi:[0,0,1]
	v_pk_add_f32 v[98:99], v[50:51], v[100:101]
	v_pk_add_f32 v[50:51], v[50:51], v[100:101] neg_lo:[0,1] neg_hi:[0,1]
	v_pk_mul_f32 v[100:101], v[50:51], s[52:53] op_sel_hi:[1,0]
	v_xor_b32_e32 v107, 0x80000000, v50
	v_mov_b32_e32 v106, v51
	v_pk_fma_f32 v[50:51], v[106:107], s[54:55], v[100:101] op_sel_hi:[1,0,1] neg_lo:[0,0,1] neg_hi:[0,0,1]
	v_pk_add_f32 v[100:101], v[2:3], v[88:89]
	v_pk_add_f32 v[2:3], v[2:3], v[88:89] neg_lo:[0,1] neg_hi:[0,1]
	v_pk_add_f32 v[88:89], v[4:5], v[24:25]
	v_pk_add_f32 v[4:5], v[4:5], v[24:25] neg_lo:[0,1] neg_hi:[0,1]
	v_pk_mul_f32 v[24:25], v[4:5], s[54:55] op_sel:[1,0] op_sel_hi:[0,0] neg_hi:[1,0]
	v_pk_fma_f32 v[4:5], v[4:5], s[52:53], v[24:25] op_sel_hi:[1,0,1]
	v_pk_add_f32 v[24:25], v[6:7], v[26:27]
	v_pk_add_f32 v[6:7], v[6:7], v[26:27] neg_lo:[0,1] neg_hi:[0,1]
	v_pk_mul_f32 v[26:27], v[6:7], s[60:61] op_sel:[1,0] op_sel_hi:[0,0] neg_hi:[1,0]
	v_pk_fma_f32 v[6:7], v[6:7], s[60:61], v[26:27] op_sel_hi:[1,0,1]
	v_pk_add_f32 v[26:27], v[8:9], v[28:29]
	v_pk_add_f32 v[8:9], v[8:9], v[28:29] neg_lo:[0,1] neg_hi:[0,1]
	v_pk_mul_f32 v[28:29], v[8:9], s[52:53] op_sel:[1,0] op_sel_hi:[0,0] neg_hi:[1,0]
	v_pk_fma_f32 v[8:9], v[8:9], s[54:55], v[28:29] op_sel_hi:[1,0,1]
	v_pk_add_f32 v[28:29], v[12:13], v[30:31]
	v_pk_add_f32 v[12:13], v[12:13], v[30:31] neg_lo:[0,1] neg_hi:[0,1]
	v_xor_b32_e32 v31, 0x80000000, v12
	v_mov_b32_e32 v30, v13
	v_pk_add_f32 v[12:13], v[14:15], v[32:33]
	v_pk_add_f32 v[14:15], v[14:15], v[32:33] neg_lo:[0,1] neg_hi:[0,1]
	v_pk_mul_f32 v[32:33], v[14:15], s[54:55] op_sel_hi:[1,0]
	v_xor_b32_e32 v107, 0x80000000, v14
	v_mov_b32_e32 v106, v15
	v_pk_fma_f32 v[14:15], v[106:107], s[52:53], v[32:33] op_sel_hi:[1,0,1] neg_lo:[0,0,1] neg_hi:[0,0,1]
	v_pk_add_f32 v[32:33], v[16:17], v[34:35]
	v_pk_add_f32 v[16:17], v[16:17], v[34:35] neg_lo:[0,1] neg_hi:[0,1]
	v_pk_mul_f32 v[34:35], v[16:17], s[60:61] op_sel_hi:[1,0]
	v_xor_b32_e32 v107, 0x80000000, v16
	v_mov_b32_e32 v106, v17
	v_pk_fma_f32 v[16:17], v[106:107], s[60:61], v[34:35] op_sel_hi:[1,0,1] neg_lo:[0,0,1] neg_hi:[0,0,1]
	v_pk_add_f32 v[34:35], v[20:21], v[36:37]
	v_pk_add_f32 v[20:21], v[20:21], v[36:37] neg_lo:[0,1] neg_hi:[0,1]
	v_pk_mul_f32 v[36:37], v[20:21], s[52:53] op_sel_hi:[1,0]
	v_xor_b32_e32 v107, 0x80000000, v20
	v_mov_b32_e32 v106, v21
	v_pk_fma_f32 v[20:21], v[106:107], s[54:55], v[36:37] op_sel_hi:[1,0,1] neg_lo:[0,0,1] neg_hi:[0,0,1]
	v_pk_add_f32 v[36:37], v[102:103], v[92:93]
	v_pk_add_f32 v[92:93], v[102:103], v[92:93] neg_lo:[0,1] neg_hi:[0,1]
	v_pk_add_f32 v[102:103], v[104:105], v[44:45]
	v_pk_add_f32 v[44:45], v[104:105], v[44:45] neg_lo:[0,1] neg_hi:[0,1]
	v_pk_mul_f32 v[104:105], v[44:45], s[60:61] op_sel:[1,0] op_sel_hi:[0,0] neg_hi:[1,0]
	v_pk_fma_f32 v[44:45], v[44:45], s[60:61], v[104:105] op_sel_hi:[1,0,1]
	v_pk_add_f32 v[104:105], v[38:39], v[96:97]
	v_pk_add_f32 v[38:39], v[38:39], v[96:97] neg_lo:[0,1] neg_hi:[0,1]
	v_xor_b32_e32 v97, 0x80000000, v38
	v_mov_b32_e32 v96, v39
	v_pk_add_f32 v[38:39], v[90:91], v[98:99]
	v_pk_add_f32 v[90:91], v[90:91], v[98:99] neg_lo:[0,1] neg_hi:[0,1]
	v_pk_mul_f32 v[98:99], v[90:91], s[60:61] op_sel_hi:[1,0]
	v_xor_b32_e32 v107, 0x80000000, v90
	v_mov_b32_e32 v106, v91
	v_pk_fma_f32 v[90:91], v[106:107], s[60:61], v[98:99] op_sel_hi:[1,0,1] neg_lo:[0,0,1] neg_hi:[0,0,1]
	v_pk_add_f32 v[98:99], v[52:53], v[94:95]
	v_pk_add_f32 v[52:53], v[52:53], v[94:95] neg_lo:[0,1] neg_hi:[0,1]
	v_pk_add_f32 v[94:95], v[22:23], v[46:47]
	v_pk_add_f32 v[22:23], v[22:23], v[46:47] neg_lo:[0,1] neg_hi:[0,1]
	v_pk_mul_f32 v[46:47], v[22:23], s[60:61] op_sel:[1,0] op_sel_hi:[0,0] neg_hi:[1,0]
	v_pk_fma_f32 v[22:23], v[22:23], s[60:61], v[46:47] op_sel_hi:[1,0,1]
	v_pk_add_f32 v[46:47], v[40:41], v[48:49]
	v_pk_add_f32 v[40:41], v[40:41], v[48:49] neg_lo:[0,1] neg_hi:[0,1]
	v_xor_b32_e32 v49, 0x80000000, v40
	v_mov_b32_e32 v48, v41
	v_pk_add_f32 v[40:41], v[42:43], v[50:51]
	v_pk_add_f32 v[42:43], v[42:43], v[50:51] neg_lo:[0,1] neg_hi:[0,1]
	v_pk_mul_f32 v[50:51], v[42:43], s[60:61] op_sel_hi:[1,0]
	v_xor_b32_e32 v107, 0x80000000, v42
	v_mov_b32_e32 v106, v43
	v_pk_fma_f32 v[42:43], v[106:107], s[60:61], v[50:51] op_sel_hi:[1,0,1] neg_lo:[0,0,1] neg_hi:[0,0,1]
	v_pk_add_f32 v[50:51], v[100:101], v[28:29]
	v_pk_add_f32 v[28:29], v[100:101], v[28:29] neg_lo:[0,1] neg_hi:[0,1]
	v_pk_add_f32 v[100:101], v[88:89], v[12:13]
	v_pk_add_f32 v[12:13], v[88:89], v[12:13] neg_lo:[0,1] neg_hi:[0,1]
	v_pk_mul_f32 v[88:89], v[12:13], s[60:61] op_sel:[1,0] op_sel_hi:[0,0] neg_hi:[1,0]
	v_pk_fma_f32 v[12:13], v[12:13], s[60:61], v[88:89] op_sel_hi:[1,0,1]
	v_pk_add_f32 v[88:89], v[24:25], v[32:33]
	v_pk_add_f32 v[24:25], v[24:25], v[32:33] neg_lo:[0,1] neg_hi:[0,1]
	v_pk_add_f32 v[108:109], v[50:51], v[88:89]
	v_xor_b32_e32 v33, 0x80000000, v24
	v_mov_b32_e32 v32, v25
	v_pk_add_f32 v[24:25], v[26:27], v[34:35]
	v_pk_add_f32 v[26:27], v[26:27], v[34:35] neg_lo:[0,1] neg_hi:[0,1]
	v_pk_add_f32 v[50:51], v[50:51], v[88:89] neg_lo:[0,1] neg_hi:[0,1]
	v_pk_mul_f32 v[34:35], v[26:27], s[60:61] op_sel_hi:[1,0]
	v_xor_b32_e32 v107, 0x80000000, v26
	v_mov_b32_e32 v106, v27
	v_pk_fma_f32 v[26:27], v[106:107], s[60:61], v[34:35] op_sel_hi:[1,0,1] neg_lo:[0,0,1] neg_hi:[0,0,1]
	v_pk_add_f32 v[34:35], v[2:3], v[30:31]
	v_pk_add_f32 v[2:3], v[2:3], v[30:31] neg_lo:[0,1] neg_hi:[0,1]
	v_pk_add_f32 v[30:31], v[4:5], v[14:15]
	v_pk_add_f32 v[4:5], v[4:5], v[14:15] neg_lo:[0,1] neg_hi:[0,1]
	v_pk_add_f32 v[110:111], v[12:13], v[26:27]
	v_pk_mul_f32 v[14:15], v[4:5], s[60:61] op_sel:[1,0] op_sel_hi:[0,0] neg_hi:[1,0]
	v_pk_add_f32 v[12:13], v[12:13], v[26:27] neg_lo:[0,1] neg_hi:[0,1]
	v_pk_fma_f32 v[4:5], v[4:5], s[60:61], v[14:15] op_sel_hi:[1,0,1]
	v_pk_add_f32 v[14:15], v[6:7], v[16:17]
	v_pk_add_f32 v[6:7], v[6:7], v[16:17] neg_lo:[0,1] neg_hi:[0,1]
	v_pk_add_f32 v[88:89], v[100:101], v[24:25]
	v_xor_b32_e32 v17, 0x80000000, v6
	v_mov_b32_e32 v16, v7
	v_pk_add_f32 v[6:7], v[8:9], v[20:21]
	v_pk_add_f32 v[8:9], v[8:9], v[20:21] neg_lo:[0,1] neg_hi:[0,1]
	v_xor_b32_e32 v113, 0x80000000, v12
	v_pk_mul_f32 v[20:21], v[8:9], s[60:61] op_sel_hi:[1,0]
	v_pk_fma_f32 v[8:9], v[8:9], s[60:61], v[20:21] op_sel:[1,0,0] op_sel_hi:[0,0,1] neg_lo:[0,0,1] neg_hi:[1,0,1]
	v_pk_add_f32 v[20:21], v[36:37], v[104:105]
	v_pk_add_f32 v[36:37], v[36:37], v[104:105] neg_lo:[0,1] neg_hi:[0,1]
	v_pk_add_f32 v[104:105], v[102:103], v[38:39]
	v_pk_add_f32 v[38:39], v[102:103], v[38:39] neg_lo:[0,1] neg_hi:[0,1]
	v_pk_add_f32 v[106:107], v[52:53], v[48:49]
	v_xor_b32_e32 v103, 0x80000000, v38
	v_mov_b32_e32 v102, v39
	v_pk_add_f32 v[38:39], v[92:93], v[96:97]
	v_pk_add_f32 v[92:93], v[92:93], v[96:97] neg_lo:[0,1] neg_hi:[0,1]
	v_pk_add_f32 v[96:97], v[44:45], v[90:91]
	v_pk_add_f32 v[44:45], v[44:45], v[90:91] neg_lo:[0,1] neg_hi:[0,1]
	v_pk_add_f32 v[48:49], v[52:53], v[48:49] neg_lo:[0,1] neg_hi:[0,1]
	v_pk_add_f32 v[52:53], v[22:23], v[42:43]
	v_pk_add_f32 v[22:23], v[22:23], v[42:43] neg_lo:[0,1] neg_hi:[0,1]
	v_xor_b32_e32 v91, 0x80000000, v44
	v_mov_b32_e32 v90, v45
	v_pk_add_f32 v[44:45], v[98:99], v[46:47]
	v_pk_add_f32 v[46:47], v[98:99], v[46:47] neg_lo:[0,1] neg_hi:[0,1]
	v_pk_add_f32 v[98:99], v[94:95], v[40:41]
	v_pk_add_f32 v[40:41], v[94:95], v[40:41] neg_lo:[0,1] neg_hi:[0,1]
	v_xor_b32_e32 v43, 0x80000000, v22
	v_mov_b32_e32 v42, v23
	v_pk_add_f32 v[22:23], v[100:101], v[24:25] neg_lo:[0,1] neg_hi:[0,1]
	v_xor_b32_e32 v95, 0x80000000, v40
	v_mov_b32_e32 v94, v41
	v_xor_b32_e32 v25, 0x80000000, v22
	v_mov_b32_e32 v24, v23
	v_pk_add_f32 v[100:101], v[28:29], v[32:33]
	v_pk_add_f32 v[32:33], v[28:29], v[32:33] neg_lo:[0,1] neg_hi:[0,1]
	v_mov_b32_e32 v112, v13
	v_pk_add_f32 v[12:13], v[34:35], v[14:15]
	v_pk_add_f32 v[14:15], v[34:35], v[14:15] neg_lo:[0,1] neg_hi:[0,1]
	v_pk_add_f32 v[34:35], v[30:31], v[6:7]
	v_pk_add_f32 v[6:7], v[30:31], v[6:7] neg_lo:[0,1] neg_hi:[0,1]
	v_pk_add_f32 v[114:115], v[2:3], v[16:17]
	v_pk_add_f32 v[16:17], v[2:3], v[16:17] neg_lo:[0,1] neg_hi:[0,1]
	v_pk_add_f32 v[2:3], v[4:5], v[8:9] neg_lo:[0,1] neg_hi:[0,1]
	v_xor_b32_e32 v31, 0x80000000, v6
	v_mov_b32_e32 v30, v7
	v_pk_add_f32 v[116:117], v[4:5], v[8:9]
	v_xor_b32_e32 v119, 0x80000000, v2
	v_mov_b32_e32 v118, v3
	v_pk_add_f32 v[2:3], v[20:21], v[104:105]
	v_pk_add_f32 v[104:105], v[20:21], v[104:105] neg_lo:[0,1] neg_hi:[0,1]
	v_pk_add_f32 v[120:121], v[36:37], v[102:103]
	v_pk_add_f32 v[26:27], v[36:37], v[102:103] neg_lo:[0,1] neg_hi:[0,1]
	v_pk_add_f32 v[36:37], v[38:39], v[96:97]
	v_pk_add_f32 v[40:41], v[38:39], v[96:97] neg_lo:[0,1] neg_hi:[0,1]
	v_pk_add_f32 v[96:97], v[92:93], v[90:91]
	v_pk_add_f32 v[6:7], v[92:93], v[90:91] neg_lo:[0,1] neg_hi:[0,1]
	v_pk_add_f32 v[20:21], v[44:45], v[98:99]
	v_pk_add_f32 v[90:91], v[44:45], v[98:99] neg_lo:[0,1] neg_hi:[0,1]
	v_pk_add_f32 v[92:93], v[46:47], v[94:95]
	v_pk_add_f32 v[22:23], v[46:47], v[94:95] neg_lo:[0,1] neg_hi:[0,1]
	v_pk_add_f32 v[46:47], v[106:107], v[52:53]
	v_pk_add_f32 v[38:39], v[106:107], v[52:53] neg_lo:[0,1] neg_hi:[0,1]
	v_pk_add_f32 v[52:53], v[50:51], v[24:25]
	v_pk_add_f32 v[28:29], v[50:51], v[24:25] neg_lo:[0,1] neg_hi:[0,1]
	v_pk_add_f32 v[50:51], v[100:101], v[110:111]
	v_pk_add_f32 v[44:45], v[100:101], v[110:111] neg_lo:[0,1] neg_hi:[0,1]
	v_pk_add_f32 v[98:99], v[32:33], v[112:113]
	v_pk_add_f32 v[8:9], v[32:33], v[112:113] neg_lo:[0,1] neg_hi:[0,1]
	v_pk_add_f32 v[32:33], v[12:13], v[34:35]
	v_pk_add_f32 v[100:101], v[12:13], v[34:35] neg_lo:[0,1] neg_hi:[0,1]
	v_cos_f32_e32 v12, v10
	v_sin_f32_e32 v13, v10
	v_pk_add_f32 v[94:95], v[48:49], v[42:43]
	v_pk_add_f32 v[4:5], v[48:49], v[42:43] neg_lo:[0,1] neg_hi:[0,1]
	v_pk_add_f32 v[48:49], v[108:109], v[88:89]
	v_pk_add_f32 v[102:103], v[14:15], v[30:31]
	v_pk_add_f32 v[24:25], v[14:15], v[30:31] neg_lo:[0,1] neg_hi:[0,1]
	v_pk_add_f32 v[106:107], v[16:17], v[118:119]
	v_pk_add_f32 v[10:11], v[16:17], v[118:119] neg_lo:[0,1] neg_hi:[0,1]
	v_pk_mul_f32 v[14:15], v[12:13], v[12:13]
	v_add_f32_e32 v16, v12, v12
	v_pk_add_f32 v[88:89], v[108:109], v[88:89] neg_lo:[0,1] neg_hi:[0,1]
	v_mul_f32_e32 v18, v13, v16
	v_pk_add_f32 v[16:17], v[14:15], v[14:15] op_sel:[0,1] op_sel_hi:[0,1] neg_lo:[0,1] neg_hi:[0,1]
	v_mov_b32_e32 v108, v13
	v_pk_mul_f32 v[14:15], v[12:13], v[18:19] op_sel:[1,0] op_sel_hi:[0,0] neg_lo:[1,0]
	v_pk_mul_f32 v[30:31], v[108:109], v[48:49] op_sel:[0,1] op_sel_hi:[0,0] neg_hi:[0,1]
	v_pk_fma_f32 v[14:15], v[12:13], v[16:17], v[14:15]
	v_pk_fma_f32 v[12:13], v[12:13], v[48:49], v[30:31] op_sel_hi:[0,1,1]
	v_pk_mul_f32 v[30:31], v[18:19], s[46:47] op_sel_hi:[0,1]
	v_pk_fma_f32 v[30:31], v[16:17], s[40:41], v[30:31]
	v_pk_mul_f32 v[48:49], v[30:31], v[20:21] op_sel:[1,1] op_sel_hi:[1,0] neg_hi:[0,1]
	v_pk_fma_f32 v[20:21], v[20:21], v[30:31], v[48:49] op_sel_hi:[1,0,1]
	v_pk_mul_f32 v[48:49], v[18:19], v[14:15] op_sel:[0,1] op_sel_hi:[0,0] neg_lo:[0,1]
	v_pk_mul_f32 v[108:109], v[14:15], v[32:33] op_sel:[1,1] op_sel_hi:[1,0] neg_hi:[0,1]
	v_pk_fma_f32 v[48:49], v[16:17], v[14:15], v[48:49]
	v_pk_fma_f32 v[14:15], v[14:15], v[32:33], v[108:109] op_sel_hi:[0,1,1]
	v_pk_mul_f32 v[32:33], v[18:19], v[30:31] op_sel:[0,1] op_sel_hi:[0,0] neg_lo:[0,1]
	v_pk_fma_f32 v[108:109], v[16:17], v[30:31], v[32:33]
	v_pk_mul_f32 v[30:31], v[36:37], v[108:109] op_sel:[1,1] op_sel_hi:[0,1] neg_hi:[1,0]
	v_pk_add_f32 v[34:35], v[114:115], v[116:117]
	v_pk_fma_f32 v[32:33], v[36:37], v[108:109], v[30:31] op_sel_hi:[1,0,1]
	v_pk_mul_f32 v[30:31], v[18:19], v[48:49] op_sel:[0,1] op_sel_hi:[0,0] neg_lo:[0,1]
	v_pk_fma_f32 v[110:111], v[16:17], v[48:49], v[30:31]
	v_pk_mul_f32 v[30:31], v[48:49], v[50:51] op_sel:[1,1] op_sel_hi:[1,0] neg_hi:[0,1]
	v_pk_mul_f32 v[36:37], v[18:19], v[108:109] op_sel:[0,1] op_sel_hi:[0,0] neg_lo:[0,1]
	v_pk_fma_f32 v[30:31], v[50:51], v[48:49], v[30:31] op_sel_hi:[1,0,1]
	v_pk_fma_f32 v[48:49], v[16:17], v[108:109], v[36:37]
	v_pk_mul_f32 v[36:37], v[46:47], v[48:49] op_sel:[1,1] op_sel_hi:[0,1] neg_hi:[1,0]
	v_pk_fma_f32 v[36:37], v[46:47], v[48:49], v[36:37] op_sel_hi:[1,0,1]
	v_pk_mul_f32 v[46:47], v[18:19], v[110:111] op_sel:[0,1] op_sel_hi:[0,0] neg_lo:[0,1]
	v_pk_mul_f32 v[50:51], v[110:111], v[34:35] op_sel:[1,1] op_sel_hi:[1,0] neg_hi:[0,1]
	v_pk_fma_f32 v[46:47], v[16:17], v[110:111], v[46:47]
	v_pk_fma_f32 v[34:35], v[34:35], v[110:111], v[50:51] op_sel_hi:[1,0,1]
	v_pk_mul_f32 v[50:51], v[18:19], v[48:49] op_sel:[0,1] op_sel_hi:[0,0] neg_lo:[0,1]
	v_pk_fma_f32 v[50:51], v[16:17], v[48:49], v[50:51]
	v_pk_mul_f32 v[108:109], v[18:19], v[46:47] op_sel:[0,1] op_sel_hi:[0,0] neg_lo:[0,1]
	v_pk_mul_f32 v[110:111], v[52:53], v[46:47] op_sel:[1,1] op_sel_hi:[0,1] neg_hi:[1,0]
	v_pk_fma_f32 v[108:109], v[16:17], v[46:47], v[108:109]
	v_pk_fma_f32 v[46:47], v[52:53], v[46:47], v[110:111] op_sel_hi:[1,0,1]
	v_pk_mul_f32 v[48:49], v[120:121], v[50:51] op_sel:[1,1] op_sel_hi:[0,1] neg_hi:[1,0]
	v_pk_mul_f32 v[52:53], v[18:19], v[50:51] op_sel:[0,1] op_sel_hi:[0,0] neg_lo:[0,1]
	v_pk_fma_f32 v[48:49], v[120:121], v[50:51], v[48:49] op_sel_hi:[1,0,1]
	v_pk_fma_f32 v[110:111], v[16:17], v[50:51], v[52:53]
	v_pk_mul_f32 v[50:51], v[92:93], v[110:111] op_sel:[1,1] op_sel_hi:[0,1] neg_hi:[1,0]
	v_pk_add_f32 v[42:43], v[114:115], v[116:117] neg_lo:[0,1] neg_hi:[0,1]
	v_pk_fma_f32 v[52:53], v[92:93], v[110:111], v[50:51] op_sel_hi:[1,0,1]
	v_pk_mul_f32 v[50:51], v[18:19], v[108:109] op_sel:[0,1] op_sel_hi:[0,0] neg_lo:[0,1]
	v_pk_fma_f32 v[92:93], v[16:17], v[108:109], v[50:51]
	v_pk_mul_f32 v[50:51], v[102:103], v[108:109] op_sel:[1,1] op_sel_hi:[0,1] neg_hi:[1,0]
	v_pk_fma_f32 v[50:51], v[102:103], v[108:109], v[50:51] op_sel_hi:[1,0,1]
	v_pk_mul_f32 v[102:103], v[18:19], v[110:111] op_sel:[0,1] op_sel_hi:[0,0] neg_lo:[0,1]
	v_pk_fma_f32 v[102:103], v[16:17], v[110:111], v[102:103]
	v_pk_mul_f32 v[108:109], v[96:97], v[102:103] op_sel:[1,1] op_sel_hi:[0,1] neg_hi:[1,0]
	v_pk_fma_f32 v[96:97], v[96:97], v[102:103], v[108:109] op_sel_hi:[1,0,1]
	v_pk_mul_f32 v[108:109], v[18:19], v[92:93] op_sel:[0,1] op_sel_hi:[0,0] neg_lo:[0,1]
	v_pk_mul_f32 v[110:111], v[98:99], v[92:93] op_sel:[1,1] op_sel_hi:[0,1] neg_hi:[1,0]
	v_pk_fma_f32 v[108:109], v[16:17], v[92:93], v[108:109]
	v_pk_fma_f32 v[92:93], v[98:99], v[92:93], v[110:111] op_sel_hi:[1,0,1]
	v_pk_mul_f32 v[98:99], v[18:19], v[102:103] op_sel:[0,1] op_sel_hi:[0,0] neg_lo:[0,1]
	v_pk_fma_f32 v[98:99], v[16:17], v[102:103], v[98:99]
	v_pk_mul_f32 v[102:103], v[94:95], v[98:99] op_sel:[1,1] op_sel_hi:[0,1] neg_hi:[1,0]
	v_pk_fma_f32 v[94:95], v[94:95], v[98:99], v[102:103] op_sel_hi:[1,0,1]
	v_pk_mul_f32 v[102:103], v[18:19], v[108:109] op_sel:[0,1] op_sel_hi:[0,0] neg_lo:[0,1]
	v_pk_mul_f32 v[110:111], v[106:107], v[108:109] op_sel:[1,1] op_sel_hi:[0,1] neg_hi:[1,0]
	v_pk_fma_f32 v[102:103], v[16:17], v[108:109], v[102:103]
	v_pk_fma_f32 v[106:107], v[106:107], v[108:109], v[110:111] op_sel_hi:[1,0,1]
	v_pk_mul_f32 v[108:109], v[18:19], v[98:99] op_sel:[0,1] op_sel_hi:[0,0] neg_lo:[0,1]
	v_pk_fma_f32 v[98:99], v[16:17], v[98:99], v[108:109]
	v_pk_mul_f32 v[108:109], v[104:105], v[98:99] op_sel:[1,1] op_sel_hi:[0,1] neg_hi:[1,0]
	v_pk_fma_f32 v[104:105], v[104:105], v[98:99], v[108:109] op_sel_hi:[1,0,1]
	v_pk_mul_f32 v[108:109], v[18:19], v[102:103] op_sel:[0,1] op_sel_hi:[0,0] neg_lo:[0,1]
	v_pk_mul_f32 v[110:111], v[88:89], v[102:103] op_sel:[1,1] op_sel_hi:[0,1] neg_hi:[1,0]
	v_pk_fma_f32 v[108:109], v[16:17], v[102:103], v[108:109]
	v_pk_fma_f32 v[88:89], v[88:89], v[102:103], v[110:111] op_sel_hi:[1,0,1]
	v_pk_mul_f32 v[102:103], v[18:19], v[98:99] op_sel:[0,1] op_sel_hi:[0,0] neg_lo:[0,1]
	v_pk_fma_f32 v[98:99], v[16:17], v[98:99], v[102:103]
	v_pk_mul_f32 v[102:103], v[90:91], v[98:99] op_sel:[1,1] op_sel_hi:[0,1] neg_hi:[1,0]
	v_pk_fma_f32 v[90:91], v[90:91], v[98:99], v[102:103] op_sel_hi:[1,0,1]
	v_pk_mul_f32 v[102:103], v[18:19], v[108:109] op_sel:[0,1] op_sel_hi:[0,0] neg_lo:[0,1]
	v_pk_mul_f32 v[110:111], v[100:101], v[108:109] op_sel:[1,1] op_sel_hi:[0,1] neg_hi:[1,0]
	v_pk_fma_f32 v[102:103], v[16:17], v[108:109], v[102:103]
	v_pk_fma_f32 v[100:101], v[100:101], v[108:109], v[110:111] op_sel_hi:[1,0,1]
	v_pk_mul_f32 v[108:109], v[18:19], v[98:99] op_sel:[0,1] op_sel_hi:[0,0] neg_lo:[0,1]
	v_pk_fma_f32 v[98:99], v[16:17], v[98:99], v[108:109]
	v_pk_mul_f32 v[108:109], v[40:41], v[98:99] op_sel:[1,1] op_sel_hi:[0,1] neg_hi:[1,0]
	v_pk_fma_f32 v[40:41], v[40:41], v[98:99], v[108:109] op_sel_hi:[1,0,1]
	v_pk_mul_f32 v[108:109], v[18:19], v[102:103] op_sel:[0,1] op_sel_hi:[0,0] neg_lo:[0,1]
	v_pk_mul_f32 v[110:111], v[44:45], v[102:103] op_sel:[1,1] op_sel_hi:[0,1] neg_hi:[1,0]
	v_pk_fma_f32 v[108:109], v[16:17], v[102:103], v[108:109]
	v_pk_fma_f32 v[44:45], v[44:45], v[102:103], v[110:111] op_sel_hi:[1,0,1]
	v_pk_mul_f32 v[102:103], v[18:19], v[98:99] op_sel:[0,1] op_sel_hi:[0,0] neg_lo:[0,1]
	v_pk_fma_f32 v[98:99], v[16:17], v[98:99], v[102:103]
	v_pk_mul_f32 v[102:103], v[38:39], v[98:99] op_sel:[1,1] op_sel_hi:[0,1] neg_hi:[1,0]
	v_pk_fma_f32 v[38:39], v[38:39], v[98:99], v[102:103] op_sel_hi:[1,0,1]
	v_pk_mul_f32 v[102:103], v[18:19], v[108:109] op_sel:[0,1] op_sel_hi:[0,0] neg_lo:[0,1]
	v_pk_mul_f32 v[110:111], v[42:43], v[108:109] op_sel:[1,1] op_sel_hi:[0,1] neg_hi:[1,0]
	v_pk_fma_f32 v[102:103], v[16:17], v[108:109], v[102:103]
	v_pk_fma_f32 v[42:43], v[42:43], v[108:109], v[110:111] op_sel_hi:[1,0,1]
	v_pk_mul_f32 v[108:109], v[18:19], v[98:99] op_sel:[0,1] op_sel_hi:[0,0] neg_lo:[0,1]
	v_pk_fma_f32 v[98:99], v[16:17], v[98:99], v[108:109]
	v_pk_mul_f32 v[108:109], v[26:27], v[98:99] op_sel:[1,1] op_sel_hi:[0,1] neg_hi:[1,0]
	v_pk_fma_f32 v[26:27], v[26:27], v[98:99], v[108:109] op_sel_hi:[1,0,1]
	v_pk_mul_f32 v[108:109], v[18:19], v[102:103] op_sel:[0,1] op_sel_hi:[0,0] neg_lo:[0,1]
	v_pk_mul_f32 v[110:111], v[28:29], v[102:103] op_sel:[1,1] op_sel_hi:[0,1] neg_hi:[1,0]
	v_pk_fma_f32 v[108:109], v[16:17], v[102:103], v[108:109]
	v_pk_fma_f32 v[28:29], v[28:29], v[102:103], v[110:111] op_sel_hi:[1,0,1]
	v_pk_mul_f32 v[102:103], v[18:19], v[98:99] op_sel:[0,1] op_sel_hi:[0,0] neg_lo:[0,1]
	v_pk_fma_f32 v[98:99], v[16:17], v[98:99], v[102:103]
	v_pk_mul_f32 v[102:103], v[22:23], v[98:99] op_sel:[1,1] op_sel_hi:[0,1] neg_hi:[1,0]
	v_pk_fma_f32 v[22:23], v[22:23], v[98:99], v[102:103] op_sel_hi:[1,0,1]
	v_pk_mul_f32 v[102:103], v[18:19], v[108:109] op_sel:[0,1] op_sel_hi:[0,0] neg_lo:[0,1]
	v_pk_mul_f32 v[110:111], v[24:25], v[108:109] op_sel:[1,1] op_sel_hi:[0,1] neg_hi:[1,0]
	v_pk_fma_f32 v[102:103], v[16:17], v[108:109], v[102:103]
	v_pk_fma_f32 v[24:25], v[24:25], v[108:109], v[110:111] op_sel_hi:[1,0,1]
	v_pk_mul_f32 v[108:109], v[18:19], v[98:99] op_sel:[0,1] op_sel_hi:[0,0] neg_lo:[0,1]
	v_pk_fma_f32 v[98:99], v[16:17], v[98:99], v[108:109]
	v_pk_mul_f32 v[108:109], v[6:7], v[98:99] op_sel:[1,1] op_sel_hi:[0,1] neg_hi:[1,0]
	v_pk_fma_f32 v[6:7], v[6:7], v[98:99], v[108:109] op_sel_hi:[1,0,1]
	v_pk_mul_f32 v[108:109], v[18:19], v[102:103] op_sel:[0,1] op_sel_hi:[0,0] neg_lo:[0,1]
	v_pk_mul_f32 v[110:111], v[8:9], v[102:103] op_sel:[1,1] op_sel_hi:[0,1] neg_hi:[1,0]
	v_pk_fma_f32 v[108:109], v[16:17], v[102:103], v[108:109]
	v_pk_fma_f32 v[8:9], v[8:9], v[102:103], v[110:111] op_sel_hi:[1,0,1]
	v_pk_mul_f32 v[102:103], v[18:19], v[98:99] op_sel:[0,1] op_sel_hi:[0,0] neg_lo:[0,1]
	v_pk_fma_f32 v[16:17], v[16:17], v[98:99], v[102:103]
	v_pk_mul_f32 v[98:99], v[4:5], v[16:17] op_sel:[1,1] op_sel_hi:[0,1] neg_hi:[1,0]
	v_pk_fma_f32 v[4:5], v[4:5], v[16:17], v[98:99] op_sel_hi:[1,0,1]
	v_pk_mul_f32 v[16:17], v[10:11], v[108:109] op_sel:[1,1] op_sel_hi:[0,1] neg_hi:[1,0]
	s_nop 0
	v_pk_fma_f32 v[10:11], v[10:11], v[108:109], v[16:17] op_sel_hi:[1,0,1]
	ds_write_b64 v19, v[2:3]
	ds_write_b64 v54, v[104:105]
	ds_write_b64 v55, v[48:49] offset:256
	ds_write_b64 v56, v[26:27] offset:256
	ds_write_b64 v57, v[32:33] offset:512
	ds_write_b64 v58, v[40:41] offset:512
	ds_write_b64 v59, v[96:97] offset:768
	ds_write_b64 v60, v[6:7] offset:768
	ds_write_b64 v61, v[20:21] offset:1024
	ds_write_b64 v62, v[90:91] offset:1024
	ds_write_b64 v63, v[52:53] offset:1280
	ds_write_b64 v64, v[22:23] offset:1280
	ds_write_b64 v65, v[36:37] offset:1536
	ds_write_b64 v66, v[38:39] offset:1536
	ds_write_b64 v67, v[94:95] offset:1792
	ds_write_b64 v71, v[4:5] offset:1792
	ds_write_b64 v72, v[12:13] offset:2048
	ds_write_b64 v73, v[88:89] offset:2048
	ds_write_b64 v74, v[46:47] offset:2304
	ds_write_b64 v75, v[28:29] offset:2304
	ds_write_b64 v76, v[30:31] offset:2560
	ds_write_b64 v77, v[44:45] offset:2560
	ds_write_b64 v78, v[92:93] offset:2816
	ds_write_b64 v79, v[8:9] offset:2816
	ds_write_b64 v80, v[14:15] offset:3072
	ds_write_b64 v81, v[100:101] offset:3072
	ds_write_b64 v82, v[50:51] offset:3328
	ds_write_b64 v83, v[24:25] offset:3328
	ds_write_b64 v84, v[34:35] offset:3584
	ds_write_b64 v85, v[42:43] offset:3584
	ds_write_b64 v86, v[106:107] offset:3840
	ds_write_b64 v87, v[10:11] offset:3840
	v_mov_b32_e32 v2, v146
	s_waitcnt lgkmcnt(0)
	s_barrier
	s_nop 0
	v_lshlrev_b32_e32 v34, 4, v2
	v_lshrrev_b32_e32 v35, 1, v2
	v_bitop3_b32 v3, v35, v34, 16 bitop3:0x6c
	v_lshl_add_u32 v26, v3, 3, 16
	v_bitop3_b32 v3, v35, 1, 15 bitop3:0x6c
	v_bitop3_b32 v11, v35, 5, 15 bitop3:0x6c
	v_bitop3_b32 v19, v35, 9, 15 bitop3:0x6c
	v_lshlrev_b32_e32 v37, 3, v3
	v_bitop3_b32 v3, v35, 2, 15 bitop3:0x6c
	v_lshlrev_b32_e32 v45, 3, v11
	v_bitop3_b32 v11, v35, 6, 15 bitop3:0x6c
	v_lshlrev_b32_e32 v49, 3, v19
	v_bitop3_b32 v19, v35, 10, 15 bitop3:0x6c
	v_bitop3_b32 v29, v35, 14, 15 bitop3:0x6c
	v_add_u32_e32 v34, 0x2000, v34
	v_bfe_u32 v2, v2, 1, 4
	v_lshlrev_b32_e32 v38, 3, v3
	v_bitop3_b32 v3, v35, 3, 15 bitop3:0x6c
	v_bitop3_b32 v10, v35, 4, 15 bitop3:0x6c
	v_lshlrev_b32_e32 v46, 3, v11
	v_bitop3_b32 v11, v35, 7, 15 bitop3:0x6c
	v_bitop3_b32 v18, v35, 8, 15 bitop3:0x6c
	v_lshlrev_b32_e32 v50, 3, v19
	v_bitop3_b32 v19, v35, 11, 15 bitop3:0x6c
	v_bitop3_b32 v27, v35, 12, 15 bitop3:0x6c
	v_bitop3_b32 v28, v35, 13, 15 bitop3:0x6c
	v_lshlrev_b32_e32 v54, 3, v29
	v_bitop3_b32 v29, v35, 15, v35 bitop3:0xc
	v_bitop3_b32 v34, v34, v35, 16 bitop3:0x78
	v_lshlrev_b32_e32 v36, 3, v2
	v_lshlrev_b32_e32 v39, 3, v3
	v_lshlrev_b32_e32 v44, 3, v10
	v_lshlrev_b32_e32 v47, 3, v11
	v_lshlrev_b32_e32 v48, 3, v18
	v_lshlrev_b32_e32 v51, 3, v19
	v_lshlrev_b32_e32 v52, 3, v27
	v_lshlrev_b32_e32 v53, 3, v28
	v_lshlrev_b32_e32 v55, 3, v29
	v_lshl_add_u32 v34, v34, 3, 16
	v_add_u32_e32 v2, v26, v36
	v_add_u32_e32 v4, v26, v37
	v_add_u32_e32 v6, v26, v38
	v_add_u32_e32 v8, v26, v39
	v_add_u32_e32 v10, v26, v44
	v_add_u32_e32 v12, v26, v45
	v_add_u32_e32 v14, v26, v46
	v_add_u32_e32 v16, v26, v47
	v_add_u32_e32 v18, v26, v48
	v_add_u32_e32 v20, v26, v49
	v_add_u32_e32 v22, v26, v50
	v_add_u32_e32 v24, v26, v51
	v_add_u32_e32 v27, v26, v52
	v_add_u32_e32 v28, v26, v53
	v_add_u32_e32 v30, v26, v54
	v_add_u32_e32 v32, v26, v55
	v_add_u32_e32 v35, v34, v36
	v_add_u32_e32 v40, v34, v37
	v_add_u32_e32 v41, v34, v38
	v_add_u32_e32 v42, v34, v39
	ds_read_b64 v[2:3], v2
	ds_read_b64 v[4:5], v4
	ds_read_b64 v[6:7], v6
	ds_read_b64 v[8:9], v8
	ds_read_b64 v[10:11], v10
	ds_read_b64 v[12:13], v12
	ds_read_b64 v[14:15], v14
	ds_read_b64 v[16:17], v16
	ds_read_b64 v[18:19], v18
	ds_read_b64 v[20:21], v20
	ds_read_b64 v[22:23], v22
	ds_read_b64 v[24:25], v24
	ds_read_b64 v[26:27], v27
	ds_read_b64 v[28:29], v28
	ds_read_b64 v[30:31], v30
	ds_read_b64 v[32:33], v32
	ds_read_b64 v[36:37], v35
	ds_read_b64 v[38:39], v40
	ds_read_b64 v[40:41], v41
	ds_read_b64 v[42:43], v42
	v_add_u32_e32 v35, v34, v44
	v_add_u32_e32 v44, v34, v45
	v_add_u32_e32 v45, v34, v46
	v_add_u32_e32 v46, v34, v47
	ds_read_b64 v[72:73], v35
	ds_read_b64 v[74:75], v44
	ds_read_b64 v[76:77], v45
	ds_read_b64 v[78:79], v46
	v_add_u32_e32 v35, v34, v48
	v_add_u32_e32 v44, v34, v49
	v_add_u32_e32 v45, v34, v50
	v_add_u32_e32 v46, v34, v51
	ds_read_b64 v[80:81], v35
	ds_read_b64 v[82:83], v44
	ds_read_b64 v[84:85], v45
	ds_read_b64 v[86:87], v46
	v_add_u32_e32 v35, v34, v52
	v_add_u32_e32 v44, v34, v53
	v_add_u32_e32 v45, v34, v54
	v_add_u32_e32 v34, v34, v55
	ds_read_b64 v[88:89], v35
	ds_read_b64 v[90:91], v44
	ds_read_b64 v[92:93], v45
	ds_read_b64 v[94:95], v34
	s_waitcnt lgkmcnt(14)
	v_pk_add_f32 v[34:35], v[2:3], v[18:19]
	v_pk_add_f32 v[2:3], v[2:3], v[18:19] neg_lo:[0,1] neg_hi:[0,1]
	v_pk_add_f32 v[18:19], v[4:5], v[20:21]
	v_pk_add_f32 v[4:5], v[4:5], v[20:21] neg_lo:[0,1] neg_hi:[0,1]
	v_pk_mul_f32 v[20:21], v[4:5], s[54:55] op_sel:[1,0] op_sel_hi:[0,0] neg_hi:[1,0]
	v_pk_fma_f32 v[4:5], v[4:5], s[52:53], v[20:21] op_sel_hi:[1,0,1]
	v_pk_add_f32 v[20:21], v[6:7], v[22:23]
	v_pk_add_f32 v[6:7], v[6:7], v[22:23] neg_lo:[0,1] neg_hi:[0,1]
	v_pk_mul_f32 v[22:23], v[6:7], s[60:61] op_sel:[1,0] op_sel_hi:[0,0] neg_hi:[1,0]
	v_pk_fma_f32 v[6:7], v[6:7], s[60:61], v[22:23] op_sel_hi:[1,0,1]
	v_pk_add_f32 v[22:23], v[8:9], v[24:25]
	v_pk_add_f32 v[8:9], v[8:9], v[24:25] neg_lo:[0,1] neg_hi:[0,1]
	v_pk_mul_f32 v[24:25], v[8:9], s[52:53] op_sel:[1,0] op_sel_hi:[0,0] neg_hi:[1,0]
	v_pk_fma_f32 v[8:9], v[8:9], s[54:55], v[24:25] op_sel_hi:[1,0,1]
	v_pk_add_f32 v[24:25], v[10:11], v[26:27]
	v_pk_add_f32 v[10:11], v[10:11], v[26:27] neg_lo:[0,1] neg_hi:[0,1]
	v_xor_b32_e32 v27, 0x80000000, v10
	v_mov_b32_e32 v26, v11
	v_pk_add_f32 v[10:11], v[12:13], v[28:29]
	v_pk_add_f32 v[12:13], v[12:13], v[28:29] neg_lo:[0,1] neg_hi:[0,1]
	v_pk_mul_f32 v[28:29], v[12:13], s[54:55] op_sel_hi:[1,0]
	v_xor_b32_e32 v45, 0x80000000, v12
	v_mov_b32_e32 v44, v13
	v_pk_fma_f32 v[12:13], v[44:45], s[52:53], v[28:29] op_sel_hi:[1,0,1] neg_lo:[0,0,1] neg_hi:[0,0,1]
	v_pk_add_f32 v[28:29], v[14:15], v[30:31]
	v_pk_add_f32 v[14:15], v[14:15], v[30:31] neg_lo:[0,1] neg_hi:[0,1]
	v_pk_mul_f32 v[30:31], v[14:15], s[60:61] op_sel_hi:[1,0]
	v_xor_b32_e32 v45, 0x80000000, v14
	v_mov_b32_e32 v44, v15
	v_pk_fma_f32 v[14:15], v[44:45], s[60:61], v[30:31] op_sel_hi:[1,0,1] neg_lo:[0,0,1] neg_hi:[0,0,1]
	v_pk_add_f32 v[30:31], v[16:17], v[32:33]
	v_pk_add_f32 v[16:17], v[16:17], v[32:33] neg_lo:[0,1] neg_hi:[0,1]
	v_pk_mul_f32 v[32:33], v[16:17], s[52:53] op_sel_hi:[1,0]
	v_xor_b32_e32 v45, 0x80000000, v16
	v_mov_b32_e32 v44, v17
	v_pk_fma_f32 v[16:17], v[44:45], s[54:55], v[32:33] op_sel_hi:[1,0,1] neg_lo:[0,0,1] neg_hi:[0,0,1]
	v_pk_add_f32 v[32:33], v[34:35], v[24:25]
	v_pk_add_f32 v[24:25], v[34:35], v[24:25] neg_lo:[0,1] neg_hi:[0,1]
	v_pk_add_f32 v[34:35], v[18:19], v[10:11]
	v_pk_add_f32 v[10:11], v[18:19], v[10:11] neg_lo:[0,1] neg_hi:[0,1]
	v_pk_mul_f32 v[18:19], v[10:11], s[60:61] op_sel:[1,0] op_sel_hi:[0,0] neg_hi:[1,0]
	v_pk_fma_f32 v[10:11], v[10:11], s[60:61], v[18:19] op_sel_hi:[1,0,1]
	v_pk_add_f32 v[18:19], v[20:21], v[28:29]
	v_pk_add_f32 v[20:21], v[20:21], v[28:29] neg_lo:[0,1] neg_hi:[0,1]
	v_xor_b32_e32 v29, 0x80000000, v20
	v_mov_b32_e32 v28, v21
	v_pk_add_f32 v[20:21], v[22:23], v[30:31]
	v_pk_add_f32 v[22:23], v[22:23], v[30:31] neg_lo:[0,1] neg_hi:[0,1]
	v_pk_mul_f32 v[30:31], v[22:23], s[60:61] op_sel_hi:[1,0]
	v_xor_b32_e32 v45, 0x80000000, v22
	v_mov_b32_e32 v44, v23
	v_pk_fma_f32 v[22:23], v[44:45], s[60:61], v[30:31] op_sel_hi:[1,0,1] neg_lo:[0,0,1] neg_hi:[0,0,1]
	v_pk_add_f32 v[30:31], v[2:3], v[26:27]
	v_pk_add_f32 v[2:3], v[2:3], v[26:27] neg_lo:[0,1] neg_hi:[0,1]
	v_pk_add_f32 v[26:27], v[4:5], v[12:13]
	v_pk_add_f32 v[4:5], v[4:5], v[12:13] neg_lo:[0,1] neg_hi:[0,1]
	v_pk_mul_f32 v[12:13], v[4:5], s[60:61] op_sel:[1,0] op_sel_hi:[0,0] neg_hi:[1,0]
	v_pk_fma_f32 v[4:5], v[4:5], s[60:61], v[12:13] op_sel_hi:[1,0,1]
	v_pk_add_f32 v[12:13], v[6:7], v[14:15]
	v_pk_add_f32 v[6:7], v[6:7], v[14:15] neg_lo:[0,1] neg_hi:[0,1]
	v_xor_b32_e32 v15, 0x80000000, v6
	v_mov_b32_e32 v14, v7
	v_pk_add_f32 v[6:7], v[8:9], v[16:17]
	v_pk_add_f32 v[8:9], v[8:9], v[16:17] neg_lo:[0,1] neg_hi:[0,1]
	v_pk_mul_f32 v[16:17], v[8:9], s[60:61] op_sel_hi:[1,0]
	v_pk_fma_f32 v[8:9], v[8:9], s[60:61], v[16:17] op_sel:[1,0,0] op_sel_hi:[0,0,1] neg_lo:[0,0,1] neg_hi:[1,0,1]
	v_pk_add_f32 v[16:17], v[32:33], v[18:19]
	v_pk_add_f32 v[18:19], v[32:33], v[18:19] neg_lo:[0,1] neg_hi:[0,1]
	v_pk_add_f32 v[32:33], v[34:35], v[20:21]
	v_pk_add_f32 v[20:21], v[34:35], v[20:21] neg_lo:[0,1] neg_hi:[0,1]
	v_pk_add_f32 v[66:67], v[16:17], v[32:33]
	v_xor_b32_e32 v35, 0x80000000, v20
	v_mov_b32_e32 v34, v21
	v_pk_add_f32 v[20:21], v[24:25], v[28:29]
	v_pk_add_f32 v[24:25], v[24:25], v[28:29] neg_lo:[0,1] neg_hi:[0,1]
	v_pk_add_f32 v[28:29], v[10:11], v[22:23]
	v_pk_add_f32 v[10:11], v[10:11], v[22:23] neg_lo:[0,1] neg_hi:[0,1]
	v_pk_add_f32 v[58:59], v[20:21], v[28:29]
	v_xor_b32_e32 v23, 0x80000000, v10
	v_mov_b32_e32 v22, v11
	v_pk_add_f32 v[10:11], v[30:31], v[12:13]
	v_pk_add_f32 v[12:13], v[30:31], v[12:13] neg_lo:[0,1] neg_hi:[0,1]
	v_pk_add_f32 v[30:31], v[26:27], v[6:7]
	v_pk_add_f32 v[6:7], v[26:27], v[6:7] neg_lo:[0,1] neg_hi:[0,1]
	v_pk_add_f32 v[54:55], v[24:25], v[22:23]
	v_xor_b32_e32 v27, 0x80000000, v6
	v_mov_b32_e32 v26, v7
	v_pk_add_f32 v[6:7], v[2:3], v[14:15]
	v_pk_add_f32 v[2:3], v[2:3], v[14:15] neg_lo:[0,1] neg_hi:[0,1]
	v_pk_add_f32 v[14:15], v[4:5], v[8:9]
	v_pk_add_f32 v[4:5], v[4:5], v[8:9] neg_lo:[0,1] neg_hi:[0,1]
	v_pk_add_f32 v[52:53], v[24:25], v[22:23] neg_lo:[0,1] neg_hi:[0,1]
	v_pk_add_f32 v[50:51], v[10:11], v[30:31]
	v_pk_add_f32 v[48:49], v[10:11], v[30:31] neg_lo:[0,1] neg_hi:[0,1]
	v_pk_add_f32 v[46:47], v[12:13], v[26:27]
	v_pk_add_f32 v[44:45], v[12:13], v[26:27] neg_lo:[0,1] neg_hi:[0,1]
	v_pk_add_f32 v[30:31], v[2:3], v[4:5] op_sel:[0,1] op_sel_hi:[1,0] neg_hi:[0,1]
	v_pk_add_f32 v[26:27], v[2:3], v[4:5] op_sel:[0,1] op_sel_hi:[1,0] neg_lo:[0,1]
	s_waitcnt lgkmcnt(6)
	v_pk_add_f32 v[8:9], v[38:39], v[82:83] neg_lo:[0,1] neg_hi:[0,1]
	s_waitcnt lgkmcnt(2)
	v_pk_add_f32 v[24:25], v[74:75], v[90:91] neg_lo:[0,1] neg_hi:[0,1]
	v_pk_add_f32 v[56:57], v[20:21], v[28:29] neg_lo:[0,1] neg_hi:[0,1]
	v_pk_add_f32 v[2:3], v[36:37], v[80:81]
	v_pk_add_f32 v[4:5], v[36:37], v[80:81] neg_lo:[0,1] neg_hi:[0,1]
	v_pk_mul_f32 v[28:29], v[24:25], s[54:55] op_sel_hi:[1,0]
	v_pk_add_f32 v[64:65], v[16:17], v[32:33] neg_lo:[0,1] neg_hi:[0,1]
	v_pk_mul_f32 v[10:11], v[8:9], s[54:55] op_sel:[1,0] op_sel_hi:[0,0] neg_hi:[1,0]
	v_pk_add_f32 v[12:13], v[40:41], v[84:85] neg_lo:[0,1] neg_hi:[0,1]
	v_pk_add_f32 v[16:17], v[42:43], v[86:87] neg_lo:[0,1] neg_hi:[0,1]
	v_pk_fma_f32 v[24:25], v[24:25], s[52:53], v[28:29] op_sel:[1,0,0] op_sel_hi:[0,0,1] neg_lo:[0,0,1] neg_hi:[1,0,1]
	s_waitcnt lgkmcnt(1)
	v_pk_add_f32 v[36:37], v[76:77], v[92:93] neg_lo:[0,1] neg_hi:[0,1]
	v_pk_add_f32 v[62:63], v[18:19], v[34:35]
	v_pk_add_f32 v[60:61], v[18:19], v[34:35] neg_lo:[0,1] neg_hi:[0,1]
	v_pk_add_f32 v[34:35], v[6:7], v[14:15]
	v_pk_add_f32 v[32:33], v[6:7], v[14:15] neg_lo:[0,1] neg_hi:[0,1]
	v_pk_add_f32 v[6:7], v[38:39], v[82:83]
	v_pk_fma_f32 v[8:9], v[8:9], s[52:53], v[10:11] op_sel_hi:[1,0,1]
	v_pk_add_f32 v[10:11], v[40:41], v[84:85]
	v_pk_mul_f32 v[38:39], v[36:37], s[60:61] op_sel_hi:[1,0]
	v_pk_mul_f32 v[14:15], v[12:13], s[60:61] op_sel:[1,0] op_sel_hi:[0,0] neg_hi:[1,0]
	v_pk_mul_f32 v[18:19], v[16:17], s[52:53] op_sel:[1,0] op_sel_hi:[0,0] neg_hi:[1,0]
	v_pk_add_f32 v[20:21], v[72:73], v[88:89] neg_lo:[0,1] neg_hi:[0,1]
	v_pk_fma_f32 v[36:37], v[36:37], s[60:61], v[38:39] op_sel:[1,0,0] op_sel_hi:[0,0,1] neg_lo:[0,0,1] neg_hi:[1,0,1]
	s_waitcnt lgkmcnt(0)
	v_pk_add_f32 v[40:41], v[78:79], v[94:95] neg_lo:[0,1] neg_hi:[0,1]
	v_pk_fma_f32 v[12:13], v[12:13], s[60:61], v[14:15] op_sel_hi:[1,0,1]
	v_pk_add_f32 v[14:15], v[42:43], v[86:87]
	v_pk_fma_f32 v[16:17], v[16:17], s[54:55], v[18:19] op_sel_hi:[1,0,1]
	v_pk_add_f32 v[18:19], v[72:73], v[88:89]
	v_xor_b32_e32 v23, 0x80000000, v20
	v_mov_b32_e32 v22, v21
	v_pk_add_f32 v[20:21], v[74:75], v[90:91]
	v_pk_mul_f32 v[42:43], v[40:41], s[52:53] op_sel_hi:[1,0]
	v_xor_b32_e32 v73, 0x80000000, v40
	v_mov_b32_e32 v72, v41
	v_pk_fma_f32 v[40:41], v[72:73], s[54:55], v[42:43] op_sel_hi:[1,0,1] neg_lo:[0,0,1] neg_hi:[0,0,1]
	v_pk_add_f32 v[42:43], v[2:3], v[18:19]
	v_pk_add_f32 v[2:3], v[2:3], v[18:19] neg_lo:[0,1] neg_hi:[0,1]
	v_pk_add_f32 v[18:19], v[6:7], v[20:21]
	v_pk_add_f32 v[6:7], v[6:7], v[20:21] neg_lo:[0,1] neg_hi:[0,1]
	v_pk_add_f32 v[28:29], v[76:77], v[92:93]
	v_pk_mul_f32 v[20:21], v[6:7], s[60:61] op_sel:[1,0] op_sel_hi:[0,0] neg_hi:[1,0]
	v_pk_add_f32 v[38:39], v[78:79], v[94:95]
	v_pk_fma_f32 v[6:7], v[6:7], s[60:61], v[20:21] op_sel_hi:[1,0,1]
	v_pk_add_f32 v[20:21], v[10:11], v[28:29]
	v_pk_add_f32 v[10:11], v[10:11], v[28:29] neg_lo:[0,1] neg_hi:[0,1]
	v_xor_b32_e32 v29, 0x80000000, v10
	v_mov_b32_e32 v28, v11
	v_pk_add_f32 v[10:11], v[14:15], v[38:39]
	v_pk_add_f32 v[14:15], v[14:15], v[38:39] neg_lo:[0,1] neg_hi:[0,1]
	v_pk_mul_f32 v[38:39], v[14:15], s[60:61] op_sel_hi:[1,0]
	v_xor_b32_e32 v73, 0x80000000, v14
	v_mov_b32_e32 v72, v15
	v_pk_fma_f32 v[14:15], v[72:73], s[60:61], v[38:39] op_sel_hi:[1,0,1] neg_lo:[0,0,1] neg_hi:[0,0,1]
	v_pk_add_f32 v[38:39], v[4:5], v[22:23]
	v_pk_add_f32 v[4:5], v[4:5], v[22:23] neg_lo:[0,1] neg_hi:[0,1]
	v_pk_add_f32 v[22:23], v[8:9], v[24:25]
	v_pk_add_f32 v[8:9], v[8:9], v[24:25] neg_lo:[0,1] neg_hi:[0,1]
	v_pk_mul_f32 v[24:25], v[8:9], s[60:61] op_sel:[1,0] op_sel_hi:[0,0] neg_hi:[1,0]
	v_pk_fma_f32 v[8:9], v[8:9], s[60:61], v[24:25] op_sel_hi:[1,0,1]
	v_pk_add_f32 v[24:25], v[12:13], v[36:37]
	v_pk_add_f32 v[12:13], v[12:13], v[36:37] neg_lo:[0,1] neg_hi:[0,1]
	v_pk_add_f32 v[74:75], v[38:39], v[24:25] neg_lo:[0,1] neg_hi:[0,1]
	v_xor_b32_e32 v37, 0x80000000, v12
	v_mov_b32_e32 v36, v13
	v_pk_add_f32 v[12:13], v[16:17], v[40:41]
	v_pk_add_f32 v[16:17], v[16:17], v[40:41] neg_lo:[0,1] neg_hi:[0,1]
	v_pk_add_f32 v[76:77], v[22:23], v[12:13]
	v_pk_mul_f32 v[40:41], v[16:17], s[60:61] op_sel_hi:[1,0]
	v_pk_fma_f32 v[16:17], v[16:17], s[60:61], v[40:41] op_sel:[1,0,0] op_sel_hi:[0,0,1] neg_lo:[0,0,1] neg_hi:[1,0,1]
	v_pk_add_f32 v[72:73], v[18:19], v[10:11]
	v_pk_add_f32 v[10:11], v[18:19], v[10:11] neg_lo:[0,1] neg_hi:[0,1]
	v_pk_add_f32 v[12:13], v[22:23], v[12:13] neg_lo:[0,1] neg_hi:[0,1]
	v_xor_b32_e32 v19, 0x80000000, v10
	v_mov_b32_e32 v18, v11
	v_pk_add_f32 v[10:11], v[2:3], v[28:29]
	v_pk_add_f32 v[2:3], v[2:3], v[28:29] neg_lo:[0,1] neg_hi:[0,1]
	v_pk_add_f32 v[28:29], v[6:7], v[14:15]
	v_pk_add_f32 v[6:7], v[6:7], v[14:15] neg_lo:[0,1] neg_hi:[0,1]
	v_pk_add_f32 v[22:23], v[10:11], v[28:29] neg_lo:[0,1] neg_hi:[0,1]
	v_xor_b32_e32 v15, 0x80000000, v6
	v_mov_b32_e32 v14, v7
	v_pk_add_f32 v[6:7], v[38:39], v[24:25]
	v_pk_add_f32 v[24:25], v[10:11], v[28:29]
	v_mov_b32_e32 v28, v146
	v_pk_add_f32 v[40:41], v[42:43], v[20:21]
	v_pk_add_f32 v[20:21], v[42:43], v[20:21] neg_lo:[0,1] neg_hi:[0,1]
	v_lshlrev_b32_e32 v71, 4, v28
	v_lshrrev_b32_e32 v29, 1, v28
	v_pk_add_f32 v[42:43], v[40:41], v[72:73]
	v_pk_add_f32 v[40:41], v[40:41], v[72:73] neg_lo:[0,1] neg_hi:[0,1]
	v_bfe_u32 v28, v28, 1, 4
	v_bitop3_b32 v72, v29, v71, 16 bitop3:0x6c
	v_lshl_add_u32 v72, v72, 3, 16
	v_lshlrev_b32_e32 v28, 3, v28
	v_add_u32_e32 v73, v72, v28
	ds_write_b64 v73, v[66:67]
	v_bitop3_b32 v73, v29, 1, 15 bitop3:0x6c
	v_xor_b32_e32 v79, 0x80000000, v12
	v_mov_b32_e32 v78, v13
	v_lshlrev_b32_e32 v73, 3, v73
	v_pk_add_f32 v[12:13], v[74:75], v[78:79]
	v_pk_add_f32 v[10:11], v[74:75], v[78:79] neg_lo:[0,1] neg_hi:[0,1]
	v_add_u32_e32 v74, v72, v73
	ds_write_b64 v74, v[64:65]
	v_bitop3_b32 v74, v29, 2, 15 bitop3:0x6c
	v_lshlrev_b32_e32 v74, 3, v74
	v_add_u32_e32 v75, v72, v74
	ds_write_b64 v75, v[62:63]
	v_bitop3_b32 v75, v29, 3, 15 bitop3:0x6c
	v_lshlrev_b32_e32 v75, 3, v75
	v_pk_add_f32 v[80:81], v[4:5], v[36:37]
	v_pk_add_f32 v[82:83], v[4:5], v[36:37] neg_lo:[0,1] neg_hi:[0,1]
	v_pk_add_f32 v[4:5], v[8:9], v[16:17]
	v_pk_add_f32 v[8:9], v[8:9], v[16:17] neg_lo:[0,1] neg_hi:[0,1]
	v_pk_add_f32 v[38:39], v[20:21], v[18:19]
	v_pk_add_f32 v[36:37], v[20:21], v[18:19] neg_lo:[0,1] neg_hi:[0,1]
	v_pk_add_f32 v[20:21], v[2:3], v[14:15]
	v_pk_add_f32 v[18:19], v[2:3], v[14:15] neg_lo:[0,1] neg_hi:[0,1]
	v_pk_add_f32 v[16:17], v[6:7], v[76:77]
	v_pk_add_f32 v[14:15], v[6:7], v[76:77] neg_lo:[0,1] neg_hi:[0,1]
	v_add_u32_e32 v76, v72, v75
	ds_write_b64 v76, v[60:61]
	v_bitop3_b32 v76, v29, 4, 15 bitop3:0x6c
	v_lshlrev_b32_e32 v76, 3, v76
	v_add_u32_e32 v77, v72, v76
	ds_write_b64 v77, v[58:59]
	v_bitop3_b32 v77, v29, 5, 15 bitop3:0x6c
	v_lshlrev_b32_e32 v77, 3, v77
	v_add_u32_e32 v78, v72, v77
	ds_write_b64 v78, v[56:57]
	v_bitop3_b32 v78, v29, 6, 15 bitop3:0x6c
	v_lshlrev_b32_e32 v78, 3, v78
	v_add_u32_e32 v79, v72, v78
	ds_write_b64 v79, v[54:55]
	v_bitop3_b32 v79, v29, 7, 15 bitop3:0x6c
	v_lshlrev_b32_e32 v79, 3, v79
	v_xor_b32_e32 v85, 0x80000000, v8
	v_mov_b32_e32 v84, v9
	v_pk_add_f32 v[8:9], v[80:81], v[4:5]
	v_pk_add_f32 v[6:7], v[80:81], v[4:5] neg_lo:[0,1] neg_hi:[0,1]
	v_add_u32_e32 v80, v72, v79
	ds_write_b64 v80, v[52:53]
	v_bitop3_b32 v80, v29, 8, 15 bitop3:0x6c
	v_lshlrev_b32_e32 v80, 3, v80
	v_add_u32_e32 v81, v72, v80
	ds_write_b64 v81, v[50:51]
	v_bitop3_b32 v81, v29, 9, 15 bitop3:0x6c
	v_lshlrev_b32_e32 v81, 3, v81
	v_pk_add_f32 v[4:5], v[82:83], v[84:85]
	v_pk_add_f32 v[2:3], v[82:83], v[84:85] neg_lo:[0,1] neg_hi:[0,1]
	v_add_u32_e32 v82, v72, v81
	ds_write_b64 v82, v[48:49]
	v_bitop3_b32 v82, v29, 10, 15 bitop3:0x6c
	v_lshlrev_b32_e32 v82, 3, v82
	v_add_u32_e32 v83, v72, v82
	ds_write_b64 v83, v[46:47]
	v_bitop3_b32 v83, v29, 11, 15 bitop3:0x6c
	v_lshlrev_b32_e32 v83, 3, v83
	v_add_u32_e32 v84, v72, v83
	ds_write_b64 v84, v[44:45]
	v_bitop3_b32 v84, v29, 12, 15 bitop3:0x6c
	v_lshlrev_b32_e32 v84, 3, v84
	v_add_u32_e32 v85, v72, v84
	ds_write_b64 v85, v[34:35]
	v_bitop3_b32 v85, v29, 13, 15 bitop3:0x6c
	v_lshlrev_b32_e32 v85, 3, v85
	v_add_u32_e32 v86, v72, v85
	ds_write_b64 v86, v[32:33]
	v_bitop3_b32 v86, v29, 14, 15 bitop3:0x6c
	v_lshlrev_b32_e32 v86, 3, v86
	v_add_u32_e32 v87, v72, v86
	v_add_u32_e32 v88, 0x2000, v71
	ds_write_b64 v87, v[30:31]
	v_bitop3_b32 v87, v29, 15, v29 bitop3:0xc
	v_bitop3_b32 v29, v88, v29, 16 bitop3:0x78
	v_lshlrev_b32_e32 v87, 3, v87
	v_lshl_add_u32 v29, v29, 3, 16
	v_add_u32_e32 v72, v72, v87
	v_add_u32_e32 v28, v29, v28
	ds_write_b64 v72, v[26:27]
	ds_write_b64 v28, v[42:43]
	v_add_u32_e32 v28, v29, v73
	ds_write_b64 v28, v[40:41]
	v_add_u32_e32 v28, v29, v74
	ds_write_b64 v28, v[38:39]
	v_add_u32_e32 v28, v29, v75
	ds_write_b64 v28, v[36:37]
	v_add_u32_e32 v28, v29, v76
	ds_write_b64 v28, v[24:25]
	v_add_u32_e32 v28, v29, v77
	ds_write_b64 v28, v[22:23]
	v_add_u32_e32 v28, v29, v78
	ds_write_b64 v28, v[20:21]
	v_add_u32_e32 v28, v29, v79
	ds_write_b64 v28, v[18:19]
	v_add_u32_e32 v28, v29, v80
	ds_write_b64 v28, v[16:17]
	v_add_u32_e32 v28, v29, v81
	ds_write_b64 v28, v[14:15]
	v_add_u32_e32 v28, v29, v82
	v_or_b32_e32 v72, 1, v71
	ds_write_b64 v28, v[12:13]
	v_add_u32_e32 v28, v29, v83
	v_bfrev_b32_e32 v72, v72
	ds_write_b64 v28, v[10:11]
	v_add_u32_e32 v28, v29, v84
	v_lshrrev_b32_e32 v72, 18, v72
	ds_write_b64 v28, v[8:9]
	v_add_u32_e32 v28, v29, v85
	v_sub_u32_e32 v72, 0, v72
	ds_write_b64 v28, v[6:7]
	v_add_u32_e32 v28, v29, v86
	v_and_b32_e32 v72, 0x3fff, v72
	ds_write_b64 v28, v[4:5]
	v_add_u32_e32 v28, v29, v87
	v_bfrev_b32_e32 v72, v72
	ds_write_b64 v28, v[2:3]
	v_lshl_add_u64 v[28:29], v[0:1], 2, s[0:1]
	v_bfrev_b32_e32 v0, v71
	v_lshrrev_b32_e32 v73, 18, v72
	v_lshrrev_b32_e32 v72, 23, v72
	v_lshrrev_b32_e32 v0, 18, v0
	v_bitop3_b32 v72, v72, v73, 31 bitop3:0x6c
	v_or_b32_e32 v73, 2, v71
	v_sub_u32_e32 v0, 0, v0
	v_bfrev_b32_e32 v73, v73
	v_and_b32_e32 v0, 0x3fff, v0
	v_lshrrev_b32_e32 v73, 18, v73
	v_bfrev_b32_e32 v0, v0
	v_sub_u32_e32 v73, 0, v73
	v_lshrrev_b32_e32 v1, 18, v0
	v_lshrrev_b32_e32 v0, 23, v0
	v_and_b32_e32 v74, 0x3fff, v73
	v_bitop3_b32 v0, v0, v1, 31 bitop3:0x6c
	v_bfrev_b32_e32 v74, v74
	v_and_b32_e32 v73, 0x1fff, v73
	v_lshl_add_u32 v0, v0, 3, 16
	v_lshrrev_b32_e32 v75, 18, v74
	v_lshrrev_b32_e32 v74, 23, v74
	v_bfrev_b32_e32 v73, v73
	s_waitcnt lgkmcnt(0)
	s_barrier
	ds_read_b64 v[0:1], v0
	v_bitop3_b32 v74, v74, v75, 31 bitop3:0x6c
	v_lshrrev_b32_e32 v75, 18, v73
	v_lshrrev_b32_e32 v73, 23, v73
	v_bitop3_b32 v73, v73, v75, 31 bitop3:0x6c
	v_lshl_add_u32 v72, v72, 3, 16
	v_lshl_add_u32 v74, v74, 3, 16
	v_lshl_add_u32 v76, v73, 3, 16
	ds_read_b64 v[72:73], v72
	ds_read_b64 v[74:75], v74
	ds_read_b64 v[76:77], v76
	s_waitcnt lgkmcnt(3)
	v_pk_add_f32 v[78:79], v[66:67], v[0:1]
	v_sub_f32_e32 v1, v67, v1
	v_sub_f32_e32 v0, v0, v66
	v_mul_f32_e32 v67, 0.5, v1
	v_mul_f32_e32 v66, 0.5, v0
	s_waitcnt lgkmcnt(2)
	v_pk_add_f32 v[0:1], v[64:65], v[72:73]
	v_mul_f32_e32 v78, 0.5, v78
	v_mul_f32_e32 v80, 0.5, v0
	v_sub_f32_e32 v0, v65, v73
	v_mul_f32_e32 v65, 0.5, v0
	v_sub_f32_e32 v0, v72, v64
	v_mul_f32_e32 v73, 0.5, v1
	v_mul_f32_e32 v64, 0.5, v0
	s_waitcnt lgkmcnt(1)
	v_pk_add_f32 v[0:1], v[62:63], v[74:75]
	s_mov_b32 s0, 0x10000
	v_mul_f32_e32 v72, 0.5, v0
	v_sub_f32_e32 v0, v63, v75
	v_mul_f32_e32 v75, 0.5, v0
	v_sub_f32_e32 v0, v74, v62
	v_mul_f32_e32 v81, 0.5, v1
	v_mul_f32_e32 v74, 0.5, v0
	s_waitcnt lgkmcnt(0)
	v_pk_add_f32 v[0:1], v[60:61], v[76:77]
	v_sub_f32_e32 v61, v61, v77
	v_mul_f32_e32 v0, 0.5, v0
	v_mul_f32_e32 v61, 0.5, v61
	v_sub_f32_e32 v60, v76, v60
	v_mul_f32_e32 v79, 0.5, v79
	v_mul_f32_e32 v1, 0.5, v1
	v_mul_f32_e32 v76, 0.5, v60
	v_cvt_pk_f16_f32 v63, v0, v61
	v_cvt_pk_f16_f32 v62, v72, v75
	v_cvt_pk_f16_f32 v61, v80, v65
	v_cvt_pk_f16_f32 v60, v78, v67
	v_add_co_u32_e32 v0, vcc, s0, v28
	global_store_dwordx4 v[28:29], v[60:63], off offset:-4096
	v_readlane_b32 s0, v252, 50
	s_add_u32 s64, s0, s10
	v_cvt_pk_f16_f32 v63, v1, v76
	v_cvt_pk_f16_f32 v62, v81, v74
	v_cvt_pk_f16_f32 v61, v73, v64
	v_cvt_pk_f16_f32 v60, v79, v66
	v_addc_co_u32_e32 v1, vcc, 0, v29, vcc
	global_store_dwordx4 v[0:1], v[60:63], off offset:-4096
	v_readlane_b32 s0, v252, 51
	s_addc_u32 s65, s0, s11
	v_or_b32_e32 v60, 4, v71
	v_bfrev_b32_e32 v60, v60
	v_lshrrev_b32_e32 v60, 18, v60
	v_sub_u32_e32 v62, 0, v60
	v_and_b32_e32 v63, 0x1fff, v62
	v_bfrev_b32_e32 v63, v63
	v_lshrrev_b32_e32 v64, 18, v63
	v_lshrrev_b32_e32 v63, 23, v63
	v_bitop3_b32 v63, v63, v64, 31 bitop3:0x6c
	v_or_b32_e32 v64, 6, v71
	v_bfrev_b32_e32 v64, v64
	v_and_b32_e32 v60, 0x3fff, v62
	v_lshrrev_b32_e32 v64, 18, v64
	v_bfrev_b32_e32 v60, v60
	v_sub_u32_e32 v64, 0, v64
	v_lshrrev_b32_e32 v61, 18, v60
	v_lshrrev_b32_e32 v60, 23, v60
	v_and_b32_e32 v64, 0x2fff, v64
	v_bitop3_b32 v60, v60, v61, 31 bitop3:0x6c
	v_bfrev_b32_e32 v64, v64
	v_and_b32_e32 v62, 0xfff, v62
	v_lshl_add_u32 v60, v60, 3, 16
	v_lshrrev_b32_e32 v65, 18, v64
	v_lshrrev_b32_e32 v64, 23, v64
	v_bfrev_b32_e32 v62, v62
	ds_read_b64 v[60:61], v60
	v_bitop3_b32 v64, v64, v65, 31 bitop3:0x6c
	v_lshrrev_b32_e32 v65, 18, v62
	v_lshrrev_b32_e32 v62, 23, v62
	v_bitop3_b32 v62, v62, v65, 31 bitop3:0x6c
	v_lshl_add_u32 v63, v63, 3, 16
	v_lshl_add_u32 v64, v64, 3, 16
	v_lshl_add_u32 v66, v62, 3, 16
	ds_read_b64 v[62:63], v63
	ds_read_b64 v[64:65], v64
	ds_read_b64 v[66:67], v66
	s_waitcnt lgkmcnt(3)
	v_pk_add_f32 v[72:73], v[58:59], v[60:61]
	v_sub_f32_e32 v59, v59, v61
	v_sub_f32_e32 v58, v60, v58
	v_mul_f32_e32 v61, 0.5, v59
	v_mul_f32_e32 v60, 0.5, v58
	s_waitcnt lgkmcnt(2)
	v_pk_add_f32 v[58:59], v[56:57], v[62:63]
	v_sub_f32_e32 v57, v57, v63
	v_sub_f32_e32 v56, v62, v56
	v_mul_f32_e32 v63, 0.5, v57
	v_mul_f32_e32 v62, 0.5, v56
	s_waitcnt lgkmcnt(1)
	v_pk_add_f32 v[56:57], v[54:55], v[64:65]
	v_sub_f32_e32 v55, v55, v65
	v_sub_f32_e32 v54, v64, v54
	v_mul_f32_e32 v65, 0.5, v55
	v_mul_f32_e32 v64, 0.5, v54
	s_waitcnt lgkmcnt(0)
	v_pk_add_f32 v[54:55], v[52:53], v[66:67]
	v_sub_f32_e32 v53, v53, v67
	v_mul_f32_e32 v72, 0.5, v72
	v_mul_f32_e32 v58, 0.5, v58
	v_mul_f32_e32 v56, 0.5, v56
	v_mul_f32_e32 v54, 0.5, v54
	v_mul_f32_e32 v53, 0.5, v53
	v_sub_f32_e32 v52, v66, v52
	v_mul_f32_e32 v73, 0.5, v73
	v_mul_f32_e32 v59, 0.5, v59
	v_mul_f32_e32 v57, 0.5, v57
	v_mul_f32_e32 v67, 0.5, v55
	v_mul_f32_e32 v66, 0.5, v52
	v_cvt_pk_f16_f32 v55, v54, v53
	v_cvt_pk_f16_f32 v54, v56, v65
	v_cvt_pk_f16_f32 v53, v58, v63
	v_cvt_pk_f16_f32 v52, v72, v61
	global_store_dwordx4 v[28:29], v[52:55], off offset:-3072
	s_lshl_b64 s[0:1], s[62:63], 13
	s_add_u32 s66, s0, 0xc00000
	v_cvt_pk_f16_f32 v55, v67, v66
	v_cvt_pk_f16_f32 v54, v57, v64
	v_cvt_pk_f16_f32 v53, v59, v62
	v_cvt_pk_f16_f32 v52, v73, v60
	global_store_dwordx4 v[0:1], v[52:55], off offset:-3072
	s_addc_u32 s67, s1, 0
	v_readlane_b32 s0, v252, 6
	v_or_b32_e32 v52, 8, v71
	v_bfrev_b32_e32 v52, v52
	v_lshrrev_b32_e32 v52, 18, v52
	v_sub_u32_e32 v62, 0, v52
	v_and_b32_e32 v54, 0x1fff, v62
	v_bfrev_b32_e32 v54, v54
	v_lshrrev_b32_e32 v55, 18, v54
	v_lshrrev_b32_e32 v54, 23, v54
	v_bitop3_b32 v54, v54, v55, 31 bitop3:0x6c
	v_or_b32_e32 v55, 10, v71
	v_bfrev_b32_e32 v55, v55
	v_lshrrev_b32_e32 v55, 18, v55
	v_sub_u32_e32 v55, 0, v55
	v_and_b32_e32 v55, 0x2fff, v55
	v_and_b32_e32 v52, 0x3fff, v62
	v_bfrev_b32_e32 v55, v55
	v_bfrev_b32_e32 v52, v52
	v_lshrrev_b32_e32 v56, 18, v55
	v_lshrrev_b32_e32 v55, 23, v55
	v_lshrrev_b32_e32 v53, 18, v52
	v_lshrrev_b32_e32 v52, 23, v52
	v_bitop3_b32 v55, v55, v56, 31 bitop3:0x6c
	v_bitop3_b32 v52, v52, v53, 31 bitop3:0x6c
	v_lshl_add_u32 v56, v55, 3, 16
	v_and_b32_e32 v55, 0xfff, v62
	v_lshl_add_u32 v52, v52, 3, 16
	v_bfrev_b32_e32 v55, v55
	ds_read_b64 v[52:53], v52
	v_lshrrev_b32_e32 v57, 18, v55
	v_lshrrev_b32_e32 v55, 23, v55
	v_bitop3_b32 v55, v55, v57, 31 bitop3:0x6c
	v_lshl_add_u32 v54, v54, 3, 16
	v_lshl_add_u32 v58, v55, 3, 16
	ds_read_b64 v[54:55], v54
	ds_read_b64 v[56:57], v56
	ds_read_b64 v[58:59], v58
	s_waitcnt lgkmcnt(3)
	v_pk_add_f32 v[60:61], v[50:51], v[52:53]
	v_sub_f32_e32 v51, v51, v53
	v_sub_f32_e32 v50, v52, v50
	v_mul_f32_e32 v53, 0.5, v51
	v_mul_f32_e32 v52, 0.5, v50
	s_waitcnt lgkmcnt(2)
	v_pk_add_f32 v[50:51], v[48:49], v[54:55]
	v_sub_f32_e32 v49, v49, v55
	v_sub_f32_e32 v48, v54, v48
	v_mul_f32_e32 v55, 0.5, v49
	v_mul_f32_e32 v54, 0.5, v48
	s_waitcnt lgkmcnt(1)
	v_pk_add_f32 v[48:49], v[46:47], v[56:57]
	v_sub_f32_e32 v47, v47, v57
	v_sub_f32_e32 v46, v56, v46
	v_mul_f32_e32 v57, 0.5, v47
	v_mul_f32_e32 v56, 0.5, v46
	s_waitcnt lgkmcnt(0)
	v_pk_add_f32 v[46:47], v[44:45], v[58:59]
	v_sub_f32_e32 v45, v45, v59
	v_mul_f32_e32 v60, 0.5, v60
	v_mul_f32_e32 v50, 0.5, v50
	v_mul_f32_e32 v48, 0.5, v48
	v_mul_f32_e32 v46, 0.5, v46
	v_mul_f32_e32 v45, 0.5, v45
	v_sub_f32_e32 v44, v58, v44
	v_mul_f32_e32 v61, 0.5, v61
	v_mul_f32_e32 v51, 0.5, v51
	v_mul_f32_e32 v49, 0.5, v49
	v_mul_f32_e32 v59, 0.5, v47
	v_mul_f32_e32 v58, 0.5, v44
	v_cvt_pk_f16_f32 v47, v46, v45
	v_cvt_pk_f16_f32 v46, v48, v57
	v_cvt_pk_f16_f32 v45, v50, v55
	v_cvt_pk_f16_f32 v44, v60, v53
	global_store_dwordx4 v[28:29], v[44:47], off offset:-2048
	s_add_u32 s68, s0, s10
	v_readlane_b32 s0, v252, 47
	v_cvt_pk_f16_f32 v47, v59, v58
	v_cvt_pk_f16_f32 v46, v49, v56
	v_cvt_pk_f16_f32 v45, v51, v54
	v_cvt_pk_f16_f32 v44, v61, v52
	global_store_dwordx4 v[0:1], v[44:47], off offset:-2048
	s_addc_u32 s69, s0, s11
	s_lshl_b64 s[0:1], s[62:63], 14
	v_or_b32_e32 v44, 12, v71
	v_bfrev_b32_e32 v44, v44
	v_lshrrev_b32_e32 v44, 18, v44
	v_sub_u32_e32 v46, 0, v44
	v_and_b32_e32 v44, 0x37ff, v46
	v_and_b32_e32 v46, 0x17ff, v46
	v_bfrev_b32_e32 v46, v46
	v_lshrrev_b32_e32 v47, 18, v46
	v_lshrrev_b32_e32 v46, 23, v46
	v_bitop3_b32 v46, v46, v47, 31 bitop3:0x6c
	v_or_b32_e32 v47, 14, v71
	v_bfrev_b32_e32 v47, v47
	v_lshrrev_b32_e32 v47, 18, v47
	v_sub_u32_e32 v47, 0, v47
	v_and_b32_e32 v47, 0x27ff, v47
	v_bfrev_b32_e32 v47, v47
	v_bfrev_b32_e32 v44, v44
	v_lshrrev_b32_e32 v48, 18, v47
	v_lshrrev_b32_e32 v47, 23, v47
	v_lshrrev_b32_e32 v45, 18, v44
	v_lshrrev_b32_e32 v44, 23, v44
	v_bitop3_b32 v47, v47, v48, 31 bitop3:0x6c
	v_bitop3_b32 v44, v44, v45, 31 bitop3:0x6c
	v_lshl_add_u32 v48, v47, 3, 16
	v_and_b32_e32 v47, 0x7ff, v62
	v_lshl_add_u32 v44, v44, 3, 16
	v_bfrev_b32_e32 v47, v47
	ds_read_b64 v[44:45], v44
	v_lshrrev_b32_e32 v49, 18, v47
	v_lshrrev_b32_e32 v47, 23, v47
	v_bitop3_b32 v47, v47, v49, 31 bitop3:0x6c
	v_lshl_add_u32 v46, v46, 3, 16
	v_lshl_add_u32 v50, v47, 3, 16
	ds_read_b64 v[46:47], v46
	ds_read_b64 v[48:49], v48
	ds_read_b64 v[50:51], v50
	s_waitcnt lgkmcnt(3)
	v_pk_add_f32 v[52:53], v[34:35], v[44:45]
	v_sub_f32_e32 v35, v35, v45
	v_sub_f32_e32 v34, v44, v34
	v_mul_f32_e32 v45, 0.5, v35
	v_mul_f32_e32 v44, 0.5, v34
	s_waitcnt lgkmcnt(2)
	v_pk_add_f32 v[34:35], v[32:33], v[46:47]
	v_sub_f32_e32 v33, v33, v47
	v_sub_f32_e32 v32, v46, v32
	v_mul_f32_e32 v47, 0.5, v33
	v_mul_f32_e32 v46, 0.5, v32
	s_waitcnt lgkmcnt(1)
	v_pk_add_f32 v[32:33], v[30:31], v[48:49]
	v_sub_f32_e32 v31, v31, v49
	v_sub_f32_e32 v30, v48, v30
	v_mul_f32_e32 v49, 0.5, v31
	v_mul_f32_e32 v48, 0.5, v30
	s_waitcnt lgkmcnt(0)
	v_pk_add_f32 v[30:31], v[26:27], v[50:51]
	v_sub_f32_e32 v27, v27, v51
	v_mul_f32_e32 v52, 0.5, v52
	v_mul_f32_e32 v34, 0.5, v34
	v_mul_f32_e32 v32, 0.5, v32
	v_mul_f32_e32 v30, 0.5, v30
	v_mul_f32_e32 v27, 0.5, v27
	v_sub_f32_e32 v26, v50, v26
	v_mul_f32_e32 v53, 0.5, v53
	v_mul_f32_e32 v35, 0.5, v35
	v_mul_f32_e32 v54, 0.5, v33
	v_mul_f32_e32 v51, 0.5, v31
	v_mul_f32_e32 v26, 0.5, v26
	v_cvt_pk_f16_f32 v33, v30, v27
	v_cvt_pk_f16_f32 v32, v32, v49
	v_cvt_pk_f16_f32 v31, v34, v47
	v_cvt_pk_f16_f32 v30, v52, v45
	global_store_dwordx4 v[28:29], v[30:33], off offset:-1024
	s_add_u32 s12, s26, s0
	s_addc_u32 s13, s27, s1
	v_cvt_pk_f16_f32 v33, v51, v26
	v_cvt_pk_f16_f32 v32, v54, v48
	v_cvt_pk_f16_f32 v31, v35, v46
	v_cvt_pk_f16_f32 v30, v53, v44
	global_store_dwordx4 v[0:1], v[30:33], off offset:-1024
	v_bfrev_b32_e32 v26, v88
	v_lshrrev_b32_e32 v26, 18, v26
	v_add_u32_e32 v30, 0x2001, v71
	v_bfrev_b32_e32 v30, v30
	v_lshrrev_b32_e32 v30, 18, v30
	v_sub_u32_e32 v30, 0, v30
	v_and_b32_e32 v30, 0x3fff, v30
	v_bfrev_b32_e32 v30, v30
	v_lshrrev_b32_e32 v31, 18, v30
	v_lshrrev_b32_e32 v30, 23, v30
	v_bitop3_b32 v30, v30, v31, 31 bitop3:0x6c
	v_add_u32_e32 v31, 0x2002, v71
	v_bfrev_b32_e32 v31, v31
	v_lshrrev_b32_e32 v31, 18, v31
	v_sub_u32_e32 v31, 0, v31
	v_and_b32_e32 v31, 0x3fff, v31
	v_bfrev_b32_e32 v31, v31
	v_lshrrev_b32_e32 v32, 18, v31
	v_lshrrev_b32_e32 v31, 23, v31
	v_bitop3_b32 v31, v31, v32, 31 bitop3:0x6c
	v_sub_u32_e32 v26, 0, v26
	v_lshl_add_u32 v32, v31, 3, 16
	v_add_u32_e32 v31, 0x2003, v71
	v_and_b32_e32 v26, 0x3fff, v26
	v_bfrev_b32_e32 v31, v31
	v_bfrev_b32_e32 v26, v26
	v_lshrrev_b32_e32 v31, 18, v31
	v_lshrrev_b32_e32 v27, 18, v26
	v_lshrrev_b32_e32 v26, 23, v26
	v_sub_u32_e32 v31, 0, v31
	v_bitop3_b32 v26, v26, v27, 31 bitop3:0x6c
	v_and_b32_e32 v31, 0x1fff, v31
	v_lshl_add_u32 v26, v26, 3, 16
	v_bfrev_b32_e32 v31, v31
	ds_read_b64 v[26:27], v26
	v_lshrrev_b32_e32 v33, 18, v31
	v_lshrrev_b32_e32 v31, 23, v31
	v_bitop3_b32 v31, v31, v33, 31 bitop3:0x6c
	v_lshl_add_u32 v30, v30, 3, 16
	v_lshl_add_u32 v34, v31, 3, 16
	ds_read_b64 v[30:31], v30
	ds_read_b64 v[32:33], v32
	ds_read_b64 v[34:35], v34
	s_waitcnt lgkmcnt(3)
	v_pk_add_f32 v[44:45], v[42:43], v[26:27]
	v_sub_f32_e32 v27, v43, v27
	v_sub_f32_e32 v26, v26, v42
	v_mul_f32_e32 v43, 0.5, v27
	v_mul_f32_e32 v42, 0.5, v26
	s_waitcnt lgkmcnt(2)
	v_pk_add_f32 v[26:27], v[40:41], v[30:31]
	v_mul_f32_e32 v44, 0.5, v44
	v_mul_f32_e32 v46, 0.5, v26
	v_sub_f32_e32 v26, v41, v31
	v_mul_f32_e32 v31, 0.5, v26
	v_sub_f32_e32 v26, v30, v40
	v_mul_f32_e32 v41, 0.5, v27
	v_mul_f32_e32 v40, 0.5, v26
	s_waitcnt lgkmcnt(1)
	v_pk_add_f32 v[26:27], v[38:39], v[32:33]
	v_mul_f32_e32 v45, 0.5, v45
	v_mul_f32_e32 v30, 0.5, v26
	v_sub_f32_e32 v26, v39, v33
	v_mul_f32_e32 v39, 0.5, v26
	v_sub_f32_e32 v26, v32, v38
	v_mul_f32_e32 v47, 0.5, v27
	v_mul_f32_e32 v38, 0.5, v26
	s_waitcnt lgkmcnt(0)
	v_pk_add_f32 v[26:27], v[36:37], v[34:35]
	v_sub_f32_e32 v32, v37, v35
	v_mul_f32_e32 v26, 0.5, v26
	v_mul_f32_e32 v32, 0.5, v32
	v_sub_f32_e32 v33, v34, v36
	v_mul_f32_e32 v27, 0.5, v27
	v_mul_f32_e32 v34, 0.5, v33
	v_cvt_pk_f16_f32 v33, v26, v32
	v_cvt_pk_f16_f32 v32, v30, v39
	v_cvt_pk_f16_f32 v31, v46, v31
	v_cvt_pk_f16_f32 v30, v44, v43
	global_store_dwordx4 v[28:29], v[30:33], off
	v_add_u32_e32 v26, 0x2004, v71
	v_bfrev_b32_e32 v26, v26
	v_cvt_pk_f16_f32 v33, v27, v34
	v_cvt_pk_f16_f32 v32, v47, v38
	v_cvt_pk_f16_f32 v31, v41, v40
	v_cvt_pk_f16_f32 v30, v45, v42
	global_store_dwordx4 v[0:1], v[30:33], off
	v_lshrrev_b32_e32 v26, 18, v26
	v_sub_u32_e32 v26, 0, v26
	v_add_u32_e32 v30, 0x2005, v71
	v_bfrev_b32_e32 v30, v30
	v_lshrrev_b32_e32 v30, 18, v30
	v_sub_u32_e32 v30, 0, v30
	v_and_b32_e32 v30, 0x1fff, v30
	v_bfrev_b32_e32 v30, v30
	v_lshrrev_b32_e32 v31, 18, v30
	v_lshrrev_b32_e32 v30, 23, v30
	v_bitop3_b32 v30, v30, v31, 31 bitop3:0x6c
	v_add_u32_e32 v31, 0x2006, v71
	v_bfrev_b32_e32 v31, v31
	v_lshrrev_b32_e32 v31, 18, v31
	v_sub_u32_e32 v31, 0, v31
	v_and_b32_e32 v31, 0x2fff, v31
	v_bfrev_b32_e32 v31, v31
	v_lshrrev_b32_e32 v32, 18, v31
	v_lshrrev_b32_e32 v31, 23, v31
	v_bitop3_b32 v31, v31, v32, 31 bitop3:0x6c
	v_lshl_add_u32 v32, v31, 3, 16
	v_add_u32_e32 v31, 0x2007, v71
	v_and_b32_e32 v26, 0x3fff, v26
	v_bfrev_b32_e32 v31, v31
	v_bfrev_b32_e32 v26, v26
	v_lshrrev_b32_e32 v31, 18, v31
	v_lshrrev_b32_e32 v27, 18, v26
	v_lshrrev_b32_e32 v26, 23, v26
	v_sub_u32_e32 v31, 0, v31
	v_bitop3_b32 v26, v26, v27, 31 bitop3:0x6c
	v_and_b32_e32 v31, 0xfff, v31
	v_lshl_add_u32 v26, v26, 3, 16
	v_bfrev_b32_e32 v31, v31
	ds_read_b64 v[26:27], v26
	v_lshrrev_b32_e32 v33, 18, v31
	v_lshrrev_b32_e32 v31, 23, v31
	v_bitop3_b32 v31, v31, v33, 31 bitop3:0x6c
	v_lshl_add_u32 v30, v30, 3, 16
	v_lshl_add_u32 v34, v31, 3, 16
	ds_read_b64 v[30:31], v30
	ds_read_b64 v[32:33], v32
	ds_read_b64 v[34:35], v34
	s_waitcnt lgkmcnt(3)
	v_pk_add_f32 v[36:37], v[24:25], v[26:27]
	v_sub_f32_e32 v25, v25, v27
	v_sub_f32_e32 v24, v26, v24
	v_mul_f32_e32 v27, 0.5, v25
	v_mul_f32_e32 v26, 0.5, v24
	s_waitcnt lgkmcnt(2)
	v_pk_add_f32 v[24:25], v[22:23], v[30:31]
	v_sub_f32_e32 v23, v23, v31
	v_sub_f32_e32 v22, v30, v22
	v_mul_f32_e32 v31, 0.5, v23
	v_mul_f32_e32 v30, 0.5, v22
	s_waitcnt lgkmcnt(1)
	v_pk_add_f32 v[22:23], v[20:21], v[32:33]
	v_sub_f32_e32 v21, v21, v33
	v_sub_f32_e32 v20, v32, v20
	v_mul_f32_e32 v33, 0.5, v21
	v_mul_f32_e32 v32, 0.5, v20
	s_waitcnt lgkmcnt(0)
	v_pk_add_f32 v[20:21], v[18:19], v[34:35]
	v_sub_f32_e32 v19, v19, v35
	v_mul_f32_e32 v36, 0.5, v36
	v_mul_f32_e32 v24, 0.5, v24
	v_mul_f32_e32 v22, 0.5, v22
	v_mul_f32_e32 v20, 0.5, v20
	v_mul_f32_e32 v19, 0.5, v19
	v_sub_f32_e32 v18, v34, v18
	v_mul_f32_e32 v37, 0.5, v37
	v_mul_f32_e32 v25, 0.5, v25
	v_mul_f32_e32 v23, 0.5, v23
	v_mul_f32_e32 v35, 0.5, v21
	v_mul_f32_e32 v34, 0.5, v18
	v_cvt_pk_f16_f32 v21, v20, v19
	v_cvt_pk_f16_f32 v20, v22, v33
	v_cvt_pk_f16_f32 v19, v24, v31
	v_cvt_pk_f16_f32 v18, v36, v27
	global_store_dwordx4 v[28:29], v[18:21], off offset:1024
	s_add_u32 s14, s30, s0
	s_addc_u32 s15, s31, s1
	v_cvt_pk_f16_f32 v21, v35, v34
	v_cvt_pk_f16_f32 v20, v23, v32
	v_cvt_pk_f16_f32 v19, v25, v30
	v_cvt_pk_f16_f32 v18, v37, v26
	global_store_dwordx4 v[0:1], v[18:21], off offset:1024
	v_cmp_lt_i32_e32 vcc, s33, v146
	v_add_u32_e32 v52, 0x800, v146
	v_add_u32_e32 v20, 0x2009, v71
	v_bfrev_b32_e32 v20, v20
	v_lshrrev_b32_e32 v20, 18, v20
	v_sub_u32_e32 v20, 0, v20
	v_and_b32_e32 v20, 0x1fff, v20
	v_bfrev_b32_e32 v20, v20
	v_lshrrev_b32_e32 v21, 18, v20
	v_lshrrev_b32_e32 v20, 23, v20
	v_bitop3_b32 v20, v20, v21, 31 bitop3:0x6c
	v_add_u32_e32 v21, 0x200a, v71
	v_bfrev_b32_e32 v21, v21
	v_lshrrev_b32_e32 v21, 18, v21
	v_sub_u32_e32 v21, 0, v21
	v_and_b32_e32 v21, 0x2fff, v21
	v_add_u32_e32 v18, 0x2008, v71
	v_bfrev_b32_e32 v21, v21
	v_bfrev_b32_e32 v18, v18
	v_lshrrev_b32_e32 v22, 18, v21
	v_lshrrev_b32_e32 v21, 23, v21
	v_lshrrev_b32_e32 v18, 18, v18
	v_bitop3_b32 v21, v21, v22, 31 bitop3:0x6c
	v_sub_u32_e32 v18, 0, v18
	v_lshl_add_u32 v22, v21, 3, 16
	v_add_u32_e32 v21, 0x200b, v71
	v_and_b32_e32 v18, 0x3fff, v18
	v_bfrev_b32_e32 v21, v21
	v_bfrev_b32_e32 v18, v18
	v_lshrrev_b32_e32 v21, 18, v21
	v_lshrrev_b32_e32 v19, 18, v18
	v_lshrrev_b32_e32 v18, 23, v18
	v_sub_u32_e32 v21, 0, v21
	v_bitop3_b32 v18, v18, v19, 31 bitop3:0x6c
	v_and_b32_e32 v21, 0xfff, v21
	v_lshl_add_u32 v18, v18, 3, 16
	v_bfrev_b32_e32 v21, v21
	ds_read_b64 v[18:19], v18
	v_lshrrev_b32_e32 v23, 18, v21
	v_lshrrev_b32_e32 v21, 23, v21
	v_bitop3_b32 v21, v21, v23, 31 bitop3:0x6c
	v_lshl_add_u32 v20, v20, 3, 16
	v_lshl_add_u32 v24, v21, 3, 16
	ds_read_b64 v[20:21], v20
	ds_read_b64 v[22:23], v22
	ds_read_b64 v[24:25], v24
	s_waitcnt lgkmcnt(3)
	v_pk_add_f32 v[26:27], v[16:17], v[18:19]
	v_sub_f32_e32 v17, v17, v19
	v_sub_f32_e32 v16, v18, v16
	v_mul_f32_e32 v19, 0.5, v17
	v_mul_f32_e32 v18, 0.5, v16
	s_waitcnt lgkmcnt(2)
	v_pk_add_f32 v[16:17], v[14:15], v[20:21]
	v_sub_f32_e32 v15, v15, v21
	v_sub_f32_e32 v14, v20, v14
	v_mul_f32_e32 v21, 0.5, v15
	v_mul_f32_e32 v20, 0.5, v14
	s_waitcnt lgkmcnt(1)
	v_pk_add_f32 v[14:15], v[12:13], v[22:23]
	v_sub_f32_e32 v13, v13, v23
	v_sub_f32_e32 v12, v22, v12
	v_mul_f32_e32 v23, 0.5, v13
	v_mul_f32_e32 v22, 0.5, v12
	s_waitcnt lgkmcnt(0)
	v_pk_add_f32 v[12:13], v[10:11], v[24:25]
	v_sub_f32_e32 v11, v11, v25
	v_mul_f32_e32 v26, 0.5, v26
	v_mul_f32_e32 v16, 0.5, v16
	v_mul_f32_e32 v14, 0.5, v14
	v_mul_f32_e32 v12, 0.5, v12
	v_mul_f32_e32 v11, 0.5, v11
	v_sub_f32_e32 v10, v24, v10
	v_mul_f32_e32 v27, 0.5, v27
	v_mul_f32_e32 v17, 0.5, v17
	v_mul_f32_e32 v15, 0.5, v15
	v_mul_f32_e32 v25, 0.5, v13
	v_mul_f32_e32 v24, 0.5, v10
	v_cvt_pk_f16_f32 v13, v12, v11
	v_cvt_pk_f16_f32 v12, v14, v23
	v_cvt_pk_f16_f32 v11, v16, v21
	v_cvt_pk_f16_f32 v10, v26, v19
	global_store_dwordx4 v[28:29], v[10:13], off offset:2048
	v_add_u32_e32 v53, 0xa00, v146
	v_add_u32_e32 v54, 0xc00, v146
	v_cvt_pk_f16_f32 v13, v25, v24
	v_cvt_pk_f16_f32 v12, v15, v22
	v_cvt_pk_f16_f32 v11, v17, v20
	v_cvt_pk_f16_f32 v10, v27, v18
	global_store_dwordx4 v[0:1], v[10:13], off offset:2048
	v_add_u32_e32 v55, 0xe00, v146
	v_add_u32_e32 v47, 0x1000, v146
	v_add_u32_e32 v12, 0x200d, v71
	v_bfrev_b32_e32 v12, v12
	v_lshrrev_b32_e32 v12, 18, v12
	v_sub_u32_e32 v12, 0, v12
	v_and_b32_e32 v12, 0x17ff, v12
	v_bfrev_b32_e32 v12, v12
	v_lshrrev_b32_e32 v13, 18, v12
	v_lshrrev_b32_e32 v12, 23, v12
	v_bitop3_b32 v12, v12, v13, 31 bitop3:0x6c
	v_add_u32_e32 v13, 0x200e, v71
	v_bfrev_b32_e32 v13, v13
	v_lshrrev_b32_e32 v13, 18, v13
	v_sub_u32_e32 v13, 0, v13
	v_and_b32_e32 v13, 0x27ff, v13
	v_add_u32_e32 v10, 0x200c, v71
	v_bfrev_b32_e32 v13, v13
	v_bfrev_b32_e32 v10, v10
	v_lshrrev_b32_e32 v14, 18, v13
	v_lshrrev_b32_e32 v13, 23, v13
	v_lshrrev_b32_e32 v10, 18, v10
	v_bitop3_b32 v13, v13, v14, 31 bitop3:0x6c
	v_sub_u32_e32 v10, 0, v10
	v_lshl_add_u32 v14, v13, 3, 16
	v_add_u32_e32 v13, 0x200f, v71
	v_and_b32_e32 v10, 0x37ff, v10
	v_bfrev_b32_e32 v13, v13
	v_bfrev_b32_e32 v10, v10
	v_lshrrev_b32_e32 v13, 18, v13
	v_lshrrev_b32_e32 v11, 18, v10
	v_lshrrev_b32_e32 v10, 23, v10
	v_sub_u32_e32 v13, 0, v13
	v_bitop3_b32 v10, v10, v11, 31 bitop3:0x6c
	v_and_b32_e32 v13, 0x7ff, v13
	v_lshl_add_u32 v10, v10, 3, 16
	v_bfrev_b32_e32 v13, v13
	ds_read_b64 v[10:11], v10
	v_lshrrev_b32_e32 v15, 18, v13
	v_lshrrev_b32_e32 v13, 23, v13
	v_bitop3_b32 v13, v13, v15, 31 bitop3:0x6c
	v_lshl_add_u32 v12, v12, 3, 16
	v_lshl_add_u32 v16, v13, 3, 16
	ds_read_b64 v[12:13], v12
	ds_read_b64 v[14:15], v14
	ds_read_b64 v[16:17], v16
	s_waitcnt lgkmcnt(3)
	v_pk_add_f32 v[18:19], v[8:9], v[10:11]
	v_sub_f32_e32 v9, v9, v11
	v_sub_f32_e32 v8, v10, v8
	v_mul_f32_e32 v11, 0.5, v9
	v_mul_f32_e32 v10, 0.5, v8
	s_waitcnt lgkmcnt(2)
	v_pk_add_f32 v[8:9], v[6:7], v[12:13]
	v_sub_f32_e32 v7, v7, v13
	v_sub_f32_e32 v6, v12, v6
	v_mul_f32_e32 v13, 0.5, v7
	v_mul_f32_e32 v12, 0.5, v6
	s_waitcnt lgkmcnt(1)
	v_pk_add_f32 v[6:7], v[4:5], v[14:15]
	v_sub_f32_e32 v5, v5, v15
	v_sub_f32_e32 v4, v14, v4
	v_mul_f32_e32 v15, 0.5, v5
	v_mul_f32_e32 v14, 0.5, v4
	s_waitcnt lgkmcnt(0)
	v_pk_add_f32 v[4:5], v[2:3], v[16:17]
	v_sub_f32_e32 v3, v3, v17
	v_mul_f32_e32 v18, 0.5, v18
	v_mul_f32_e32 v8, 0.5, v8
	v_mul_f32_e32 v6, 0.5, v6
	v_mul_f32_e32 v4, 0.5, v4
	v_mul_f32_e32 v3, 0.5, v3
	v_sub_f32_e32 v2, v16, v2
	v_mul_f32_e32 v19, 0.5, v19
	v_mul_f32_e32 v9, 0.5, v9
	v_mul_f32_e32 v7, 0.5, v7
	v_mul_f32_e32 v17, 0.5, v5
	v_mul_f32_e32 v16, 0.5, v2
	v_cvt_pk_f16_f32 v5, v4, v3
	v_cvt_pk_f16_f32 v4, v6, v15
	v_cvt_pk_f16_f32 v3, v8, v13
	v_cvt_pk_f16_f32 v2, v18, v11
	global_store_dwordx4 v[28:29], v[2:5], off offset:3072
	v_add_u32_e32 v46, 0x1200, v146
	v_add_u32_e32 v27, 0x1400, v146
	v_cvt_pk_f16_f32 v5, v17, v16
	v_cvt_pk_f16_f32 v4, v7, v14
	v_cvt_pk_f16_f32 v3, v9, v12
	v_cvt_pk_f16_f32 v2, v19, v10
	global_store_dwordx4 v[0:1], v[2:5], off offset:3072
	global_load_dword v2, v151, s[64:65] offset:2048
	global_load_dword v0, v152, s[64:65]
	global_load_dword v6, v145, s[64:65]
	global_load_dword v4, v145, s[68:69]
	v_lshlrev_b32_e32 v8, 1, v146
	v_max_i32_e32 v12, 1, v146
	v_add_u32_e32 v13, 0x1e00, v146
	v_cmp_lt_i32_e32 vcc, 0, v146
	v_add_u32_e32 v9, 0x1000, v8
	v_add_u32_e32 v10, 0x2000, v8
	v_add_u32_e32 v11, 0x3000, v8
	v_lshlrev_b32_e32 v12, 1, v12
	v_cndmask_b32_e64 v14, 0, 1.0, vcc
	v_cmp_gt_i32_e32 vcc, 0x1fff, v13
	v_min_i32_e32 v13, 0x1ffe, v13
	v_lshlrev_b32_e32 v13, 1, v13
	s_nop 0
	v_cndmask_b32_e64 v15, 0, 1.0, vcc
	global_load_ushort v163, v12, s[12:13] offset:-2
	global_load_ushort v164, v8, s[12:13]
	global_load_ushort v165, v8, s[12:13] offset:2
	global_load_ushort v166, v12, s[14:15] offset:-2
	global_load_ushort v167, v8, s[14:15]
	global_load_ushort v168, v8, s[14:15] offset:2
	global_load_ushort v169, v8, s[12:13] offset:1022
	global_load_ushort v170, v8, s[12:13] offset:1024
	global_load_ushort v171, v8, s[12:13] offset:1026
	global_load_ushort v172, v8, s[14:15] offset:1022
	global_load_ushort v173, v8, s[14:15] offset:1024
	global_load_ushort v174, v8, s[14:15] offset:1026
	global_load_ushort v175, v8, s[12:13] offset:2046
	global_load_ushort v176, v8, s[12:13] offset:2048
	global_load_ushort v177, v8, s[12:13] offset:2050
	global_load_ushort v178, v8, s[14:15] offset:2046
	global_load_ushort v179, v8, s[14:15] offset:2048
	global_load_ushort v180, v8, s[14:15] offset:2050
	global_load_ushort v181, v8, s[12:13] offset:3070
	global_load_ushort v182, v8, s[12:13] offset:3072
	global_load_ushort v183, v8, s[12:13] offset:3074
	global_load_ushort v184, v8, s[14:15] offset:3070
	global_load_ushort v185, v8, s[14:15] offset:3072
	global_load_ushort v186, v8, s[14:15] offset:3074
	global_load_ushort v187, v9, s[12:13] offset:-2
	global_load_ushort v188, v9, s[12:13]
	global_load_ushort v189, v9, s[12:13] offset:2
	global_load_ushort v190, v9, s[14:15] offset:-2
	global_load_ushort v191, v9, s[14:15]
	global_load_ushort v192, v9, s[14:15] offset:2
	global_load_ushort v193, v9, s[12:13] offset:1022
	global_load_ushort v194, v9, s[12:13] offset:1024
	global_load_ushort v195, v9, s[12:13] offset:1026
	global_load_ushort v196, v9, s[14:15] offset:1022
	global_load_ushort v197, v9, s[14:15] offset:1024
	global_load_ushort v62, v9, s[14:15] offset:1026
	global_load_ushort v63, v9, s[12:13] offset:2046
	global_load_ushort v64, v9, s[12:13] offset:2048
	global_load_ushort v65, v9, s[12:13] offset:2050
	global_load_ushort v66, v9, s[14:15] offset:2046
	global_load_ushort v67, v9, s[14:15] offset:2048
	global_load_ushort v68, v9, s[14:15] offset:2050
	global_load_ushort v69, v9, s[12:13] offset:3070
	global_load_ushort v70, v9, s[12:13] offset:3072
	global_load_ushort v71, v9, s[12:13] offset:3074
	global_load_ushort v72, v9, s[14:15] offset:3070
	global_load_ushort v73, v9, s[14:15] offset:3072
	global_load_ushort v74, v9, s[14:15] offset:3074
	global_load_ushort v75, v10, s[12:13] offset:-2
	global_load_ushort v76, v10, s[12:13]
	global_load_ushort v77, v10, s[12:13] offset:2
	global_load_ushort v221, v10, s[14:15] offset:-2
	global_load_ushort v222, v10, s[14:15]
	global_load_ushort v223, v10, s[14:15] offset:2
	global_load_ushort v224, v10, s[12:13] offset:1022
	global_load_ushort v225, v10, s[12:13] offset:1024
	global_load_ushort v226, v10, s[12:13] offset:1026
	global_load_ushort v227, v10, s[14:15] offset:1022
	global_load_ushort v228, v10, s[14:15] offset:1024
	global_load_ushort v229, v10, s[14:15] offset:1026
	global_load_ushort v230, v10, s[12:13] offset:2046
	global_load_ushort v231, v10, s[12:13] offset:2048
	global_load_ushort v232, v10, s[12:13] offset:2050
	global_load_ushort v233, v10, s[14:15] offset:2046
	global_load_ushort v234, v10, s[14:15] offset:2048
	global_load_ushort v235, v10, s[14:15] offset:2050
	global_load_ushort v236, v10, s[12:13] offset:3070
	global_load_ushort v237, v10, s[12:13] offset:3072
	global_load_ushort v238, v10, s[12:13] offset:3074
	global_load_ushort v239, v10, s[14:15] offset:3070
	global_load_ushort v240, v10, s[14:15] offset:3072
	global_load_ushort v241, v10, s[14:15] offset:3074
	global_load_ushort v242, v11, s[12:13] offset:-2
	global_load_ushort v243, v11, s[12:13]
	global_load_ushort v244, v11, s[12:13] offset:2
	global_load_ushort v245, v11, s[14:15] offset:-2
	global_load_ushort v246, v11, s[14:15]
	global_load_ushort v247, v11, s[14:15] offset:2
	global_load_ushort v248, v11, s[12:13] offset:1022
	global_load_ushort v249, v11, s[12:13] offset:1024
	global_load_ushort v250, v11, s[12:13] offset:1026
	global_load_ushort v251, v11, s[14:15] offset:1022
	global_load_ushort v253, v11, s[14:15] offset:1024
	global_load_ushort v254, v11, s[14:15] offset:1026
	global_load_ushort v255, v11, s[12:13] offset:2046
	global_load_ushort v1, v11, s[12:13] offset:2048
	global_load_ushort v3, v11, s[12:13] offset:2050
	global_load_ushort v5, v11, s[14:15] offset:2046
	global_load_ushort v7, v11, s[14:15] offset:2048
	global_load_ushort v16, v11, s[14:15] offset:2050
	global_load_ushort v17, v11, s[12:13] offset:3070
	global_load_ushort v18, v11, s[12:13] offset:3072
	global_load_ushort v19, v13, s[12:13] offset:2
	global_load_ushort v20, v11, s[14:15] offset:3070
	global_load_ushort v21, v11, s[14:15] offset:3072
	global_load_ushort v22, v13, s[14:15] offset:2
	s_waitcnt vmcnt(48)
	v_lshlrev_b32_e32 v163, 16, v163
	v_lshlrev_b32_e32 v164, 16, v164
	v_lshlrev_b32_e32 v165, 16, v165
	v_mul_f32_e32 v163, v14, v163
	v_mul_f32_e32 v163, v6, v163
	v_fmac_f32_e32 v163, v2, v164
	v_fmac_f32_e32 v163, v0, v165
	v_add_f32_e32 v32, v4, v163
	v_lshlrev_b32_e32 v166, 16, v166
	v_lshlrev_b32_e32 v167, 16, v167
	v_lshlrev_b32_e32 v168, 16, v168
	v_mul_f32_e32 v166, v14, v166
	v_mul_f32_e32 v166, v6, v166
	v_fmac_f32_e32 v166, v2, v167
	v_fmac_f32_e32 v166, v0, v168
	v_add_f32_e32 v34, v4, v166
	v_lshlrev_b32_e32 v169, 16, v169
	v_lshlrev_b32_e32 v170, 16, v170
	v_lshlrev_b32_e32 v171, 16, v171
	v_mul_f32_e32 v169, v6, v169
	v_fmac_f32_e32 v169, v2, v170
	v_fmac_f32_e32 v169, v0, v171
	v_add_f32_e32 v33, v4, v169
	v_lshlrev_b32_e32 v172, 16, v172
	v_lshlrev_b32_e32 v173, 16, v173
	v_lshlrev_b32_e32 v174, 16, v174
	v_mul_f32_e32 v172, v6, v172
	v_fmac_f32_e32 v172, v2, v173
	v_fmac_f32_e32 v172, v0, v174
	v_add_f32_e32 v35, v4, v172
	v_lshlrev_b32_e32 v175, 16, v175
	v_lshlrev_b32_e32 v176, 16, v176
	v_lshlrev_b32_e32 v177, 16, v177
	v_mul_f32_e32 v175, v6, v175
	v_fmac_f32_e32 v175, v2, v176
	v_fmac_f32_e32 v175, v0, v177
	v_add_f32_e32 v37, v4, v175
	v_lshlrev_b32_e32 v178, 16, v178
	v_lshlrev_b32_e32 v179, 16, v179
	v_lshlrev_b32_e32 v180, 16, v180
	v_mul_f32_e32 v178, v6, v178
	v_fmac_f32_e32 v178, v2, v179
	v_fmac_f32_e32 v178, v0, v180
	v_add_f32_e32 v31, v4, v178
	v_lshlrev_b32_e32 v181, 16, v181
	v_lshlrev_b32_e32 v182, 16, v182
	v_lshlrev_b32_e32 v183, 16, v183
	v_mul_f32_e32 v181, v6, v181
	v_fmac_f32_e32 v181, v2, v182
	v_fmac_f32_e32 v181, v0, v183
	v_add_f32_e32 v36, v4, v181
	v_lshlrev_b32_e32 v184, 16, v184
	v_lshlrev_b32_e32 v185, 16, v185
	v_lshlrev_b32_e32 v186, 16, v186
	v_mul_f32_e32 v184, v6, v184
	v_fmac_f32_e32 v184, v2, v185
	v_fmac_f32_e32 v184, v0, v186
	v_add_f32_e32 v30, v4, v184
	v_lshlrev_b32_e32 v187, 16, v187
	v_lshlrev_b32_e32 v188, 16, v188
	v_lshlrev_b32_e32 v189, 16, v189
	v_mul_f32_e32 v187, v6, v187
	v_fmac_f32_e32 v187, v2, v188
	v_fmac_f32_e32 v187, v0, v189
	v_add_f32_e32 v39, v4, v187
	v_lshlrev_b32_e32 v190, 16, v190
	v_lshlrev_b32_e32 v191, 16, v191
	v_lshlrev_b32_e32 v192, 16, v192
	v_mul_f32_e32 v190, v6, v190
	v_fmac_f32_e32 v190, v2, v191
	v_fmac_f32_e32 v190, v0, v192
	v_add_f32_e32 v41, v4, v190
	v_lshlrev_b32_e32 v193, 16, v193
	v_lshlrev_b32_e32 v194, 16, v194
	v_lshlrev_b32_e32 v195, 16, v195
	v_mul_f32_e32 v193, v6, v193
	v_fmac_f32_e32 v193, v2, v194
	v_fmac_f32_e32 v193, v0, v195
	v_add_f32_e32 v38, v4, v193
	v_lshlrev_b32_e32 v196, 16, v196
	v_lshlrev_b32_e32 v197, 16, v197
	v_lshlrev_b32_e32 v62, 16, v62
	v_mul_f32_e32 v196, v6, v196
	v_fmac_f32_e32 v196, v2, v197
	v_fmac_f32_e32 v196, v0, v62
	v_add_f32_e32 v40, v4, v196
	v_lshlrev_b32_e32 v63, 16, v63
	v_lshlrev_b32_e32 v64, 16, v64
	v_lshlrev_b32_e32 v65, 16, v65
	v_mul_f32_e32 v63, v6, v63
	v_fmac_f32_e32 v63, v2, v64
	v_fmac_f32_e32 v63, v0, v65
	v_add_f32_e32 v43, v4, v63
	v_lshlrev_b32_e32 v66, 16, v66
	v_lshlrev_b32_e32 v67, 16, v67
	v_lshlrev_b32_e32 v68, 16, v68
	v_mul_f32_e32 v66, v6, v66
	v_fmac_f32_e32 v66, v2, v67
	v_fmac_f32_e32 v66, v0, v68
	v_add_f32_e32 v45, v4, v66
	v_lshlrev_b32_e32 v69, 16, v69
	v_lshlrev_b32_e32 v70, 16, v70
	v_lshlrev_b32_e32 v71, 16, v71
	v_mul_f32_e32 v69, v6, v69
	v_fmac_f32_e32 v69, v2, v70
	v_fmac_f32_e32 v69, v0, v71
	v_add_f32_e32 v42, v4, v69
	v_lshlrev_b32_e32 v72, 16, v72
	v_lshlrev_b32_e32 v73, 16, v73
	v_lshlrev_b32_e32 v74, 16, v74
	v_mul_f32_e32 v72, v6, v72
	v_fmac_f32_e32 v72, v2, v73
	v_fmac_f32_e32 v72, v0, v74
	v_add_f32_e32 v44, v4, v72
	s_waitcnt vmcnt(0)
	v_lshlrev_b32_e32 v75, 16, v75
	v_lshlrev_b32_e32 v76, 16, v76
	v_lshlrev_b32_e32 v77, 16, v77
	v_mul_f32_e32 v75, v6, v75
	v_fmac_f32_e32 v75, v2, v76
	v_fmac_f32_e32 v75, v0, v77
	v_add_f32_e32 v47, v4, v75
	v_lshlrev_b32_e32 v221, 16, v221
	v_lshlrev_b32_e32 v222, 16, v222
	v_lshlrev_b32_e32 v223, 16, v223
	v_mul_f32_e32 v221, v6, v221
	v_fmac_f32_e32 v221, v2, v222
	v_fmac_f32_e32 v221, v0, v223
	v_add_f32_e32 v49, v4, v221
	v_lshlrev_b32_e32 v224, 16, v224
	v_lshlrev_b32_e32 v225, 16, v225
	v_lshlrev_b32_e32 v226, 16, v226
	v_mul_f32_e32 v224, v6, v224
	v_fmac_f32_e32 v224, v2, v225
	v_fmac_f32_e32 v224, v0, v226
	v_add_f32_e32 v46, v4, v224
	v_lshlrev_b32_e32 v227, 16, v227
	v_lshlrev_b32_e32 v228, 16, v228
	v_lshlrev_b32_e32 v229, 16, v229
	v_mul_f32_e32 v227, v6, v227
	v_fmac_f32_e32 v227, v2, v228
	v_fmac_f32_e32 v227, v0, v229
	v_add_f32_e32 v48, v4, v227
	v_lshlrev_b32_e32 v230, 16, v230
	v_lshlrev_b32_e32 v231, 16, v231
	v_lshlrev_b32_e32 v232, 16, v232
	v_mul_f32_e32 v230, v6, v230
	v_fmac_f32_e32 v230, v2, v231
	v_fmac_f32_e32 v230, v0, v232
	v_add_f32_e32 v51, v4, v230
	v_lshlrev_b32_e32 v233, 16, v233
	v_lshlrev_b32_e32 v234, 16, v234
	v_lshlrev_b32_e32 v235, 16, v235
	v_mul_f32_e32 v233, v6, v233
	v_fmac_f32_e32 v233, v2, v234
	v_fmac_f32_e32 v233, v0, v235
	v_add_f32_e32 v53, v4, v233
	v_lshlrev_b32_e32 v236, 16, v236
	v_lshlrev_b32_e32 v237, 16, v237
	v_lshlrev_b32_e32 v238, 16, v238
	v_mul_f32_e32 v236, v6, v236
	v_fmac_f32_e32 v236, v2, v237
	v_fmac_f32_e32 v236, v0, v238
	v_add_f32_e32 v50, v4, v236
	v_lshlrev_b32_e32 v239, 16, v239
	v_lshlrev_b32_e32 v240, 16, v240
	v_lshlrev_b32_e32 v241, 16, v241
	v_mul_f32_e32 v239, v6, v239
	v_fmac_f32_e32 v239, v2, v240
	v_fmac_f32_e32 v239, v0, v241
	v_add_f32_e32 v52, v4, v239
	v_lshlrev_b32_e32 v242, 16, v242
	v_lshlrev_b32_e32 v243, 16, v243
	v_lshlrev_b32_e32 v244, 16, v244
	v_mul_f32_e32 v242, v6, v242
	v_fmac_f32_e32 v242, v2, v243
	v_fmac_f32_e32 v242, v0, v244
	v_add_f32_e32 v55, v4, v242
	v_lshlrev_b32_e32 v245, 16, v245
	v_lshlrev_b32_e32 v246, 16, v246
	v_lshlrev_b32_e32 v247, 16, v247
	v_mul_f32_e32 v245, v6, v245
	v_fmac_f32_e32 v245, v2, v246
	v_fmac_f32_e32 v245, v0, v247
	v_add_f32_e32 v57, v4, v245
	v_lshlrev_b32_e32 v248, 16, v248
	v_lshlrev_b32_e32 v249, 16, v249
	v_lshlrev_b32_e32 v250, 16, v250
	v_mul_f32_e32 v248, v6, v248
	v_fmac_f32_e32 v248, v2, v249
	v_fmac_f32_e32 v248, v0, v250
	v_add_f32_e32 v54, v4, v248
	v_lshlrev_b32_e32 v251, 16, v251
	v_lshlrev_b32_e32 v253, 16, v253
	v_lshlrev_b32_e32 v254, 16, v254
	v_mul_f32_e32 v251, v6, v251
	v_fmac_f32_e32 v251, v2, v253
	v_fmac_f32_e32 v251, v0, v254
	v_add_f32_e32 v56, v4, v251
	v_lshlrev_b32_e32 v255, 16, v255
	v_lshlrev_b32_e32 v1, 16, v1
	v_lshlrev_b32_e32 v3, 16, v3
	v_mul_f32_e32 v255, v6, v255
	v_fmac_f32_e32 v255, v2, v1
	v_fmac_f32_e32 v255, v0, v3
	v_add_f32_e32 v59, v4, v255
	v_lshlrev_b32_e32 v5, 16, v5
	v_lshlrev_b32_e32 v7, 16, v7
	v_lshlrev_b32_e32 v16, 16, v16
	v_mul_f32_e32 v5, v6, v5
	v_fmac_f32_e32 v5, v2, v7
	v_fmac_f32_e32 v5, v0, v16
	v_add_f32_e32 v61, v4, v5
	v_lshlrev_b32_e32 v17, 16, v17
	v_lshlrev_b32_e32 v18, 16, v18
	v_lshlrev_b32_e32 v19, 16, v19
	v_mul_f32_e32 v19, v15, v19
	v_mul_f32_e32 v17, v6, v17
	v_fmac_f32_e32 v17, v2, v18
	v_fmac_f32_e32 v17, v0, v19
	v_add_f32_e32 v58, v4, v17
	v_lshlrev_b32_e32 v20, 16, v20
	v_lshlrev_b32_e32 v21, 16, v21
	v_lshlrev_b32_e32 v22, 16, v22
	v_mul_f32_e32 v22, v15, v22
	v_mul_f32_e32 v20, v6, v20
	v_fmac_f32_e32 v20, v2, v21
	v_fmac_f32_e32 v20, v0, v22
	v_add_f32_e32 v60, v4, v20
	v_readlane_b32 s0, v252, 43
	s_add_u32 s45, s0, s10
	v_readlane_b32 s0, v252, 42
	s_addc_u32 s24, s0, s11
	s_lshl_b64 s[0:1], s[62:63], 1
	v_readlane_b32 s4, v252, 60
	s_add_u32 s70, s4, s0
	v_readlane_b32 s0, v252, 61
	s_addc_u32 s71, s0, s1
	s_mov_b64 s[14:15], -1
	s_branch .LBB0_910

.LBB0_910:
	s_lshl_b32 s0, s16, 11
	s_add_u32 s0, s45, s0
	s_addc_u32 s1, s24, 0
	global_load_dword v221, v145, s[0:1]
	s_lshl_b32 s4, s16, 9
	s_add_i32 s4, s4, 0x200
	s_add_i32 s0, s4, s62
	s_ashr_i32 s1, s0, 31
	s_lshl_b32 s6, s4, 2
	s_add_u32 s4, s64, s6
	s_addc_u32 s5, s65, 0
	s_lshl_b64 s[0:1], s[0:1], 14
	v_mov_b32_e32 v163, s6
	s_add_u32 s8, s26, s0
	s_addc_u32 s9, s27, s1
	s_add_u32 s10, s30, s0
	s_addc_u32 s11, s31, s1
	v_lshlrev_b32_e32 v232, 1, v146
	v_min_i32_e32 v233, 0x1ffe, v146
	v_max_i32_e32 v234, 1, v146
	global_load_dword v222, v163, s[64:65]
	global_load_dword v223, v151, s[4:5] offset:2048
	global_load_dword v224, v152, s[4:5]
	global_load_dword v225, v163, s[68:69]
	v_lshlrev_b32_e32 v233, 1, v233
	v_lshlrev_b32_e32 v234, 1, v234
	global_load_ushort v226, v232, s[8:9]
	global_load_ushort v227, v233, s[8:9] offset:2
	global_load_ushort v228, v234, s[8:9] offset:-2
	global_load_ushort v229, v232, s[10:11]
	global_load_ushort v230, v233, s[10:11] offset:2
	global_load_ushort v231, v234, s[10:11] offset:-2
	s_lshl_b32 s98, s16, 16
	s_mov_b32 s99, 0
	v_lshl_add_u64 v[196:197], s[98:99], 0, v[28:29]
	global_load_dwordx4 v[164:167], v[196:197], off offset:-4096
	global_load_dwordx4 v[168:171], v[196:197], off offset:-3072
	global_load_dwordx4 v[172:175], v[196:197], off offset:-2048
	global_load_dwordx4 v[176:179], v[196:197], off offset:-1024
	global_load_dwordx4 v[180:183], v[196:197], off
	global_load_dwordx4 v[184:187], v[196:197], off offset:1024
	global_load_dwordx4 v[188:191], v[196:197], off offset:2048
	global_load_dwordx4 v[192:195], v[196:197], off offset:3072
	v_mov_b32_e32 v20, v46
	v_mov_b32_e32 v21, v48
	v_mov_b32_e32 v22, v51
	v_mov_b32_e32 v23, v53
	v_pk_add_f32 v[88:89], v[20:21], 0 op_sel_hi:[1,0]
	v_pk_mul_f32 v[20:21], v[20:21], s[48:49] op_sel_hi:[1,0]
	v_xor_b32_e32 v91, 0x80000000, v46
	v_mov_b32_e32 v90, v48
	v_pk_add_f32 v[92:93], v[50:51], 0 neg_lo:[1,1] neg_hi:[1,1]
	v_mov_b32_e32 v24, v50
	v_mov_b32_e32 v25, v52
	v_pk_fma_f32 v[20:21], v[90:91], s[44:45], v[20:21] op_sel_hi:[1,0,1] neg_lo:[0,0,1] neg_hi:[0,0,1]
	v_pk_add_f32 v[90:91], v[22:23], 0 op_sel_hi:[1,0]
	v_pk_mul_f32 v[22:23], v[22:23], s[54:55] op_sel_hi:[1,0]
	v_mov_b32_e32 v92, v53
	v_mov_b32_e32 v26, v55
	v_mov_b32_e32 v27, v57
	v_pk_fma_f32 v[22:23], v[92:93], s[52:53], v[22:23] op_sel_hi:[1,0,1] neg_lo:[0,0,1] neg_hi:[0,0,1]
	v_pk_add_f32 v[92:93], v[24:25], 0 op_sel_hi:[1,0]
	v_pk_mul_f32 v[24:25], v[24:25], s[58:59] op_sel_hi:[1,0]
	v_xor_b32_e32 v95, 0x80000000, v50
	v_mov_b32_e32 v94, v52
	v_pk_add_f32 v[96:97], v[54:55], 0 neg_lo:[1,1] neg_hi:[1,1]
	v_mov_b32_e32 v64, v54
	v_mov_b32_e32 v65, v56
	v_pk_fma_f32 v[24:25], v[94:95], s[56:57], v[24:25] op_sel_hi:[1,0,1] neg_lo:[0,0,1] neg_hi:[0,0,1]
	v_pk_add_f32 v[94:95], v[26:27], 0 op_sel_hi:[1,0]
	v_pk_mul_f32 v[26:27], v[26:27], s[60:61] op_sel_hi:[1,0]
	v_mov_b32_e32 v96, v57
	v_mov_b32_e32 v66, v59
	v_mov_b32_e32 v67, v61
	v_pk_fma_f32 v[26:27], v[96:97], s[60:61], v[26:27] op_sel_hi:[1,0,1] neg_lo:[0,0,1] neg_hi:[0,0,1]
	v_pk_add_f32 v[96:97], v[64:65], 0 op_sel_hi:[1,0]
	v_pk_mul_f32 v[64:65], v[64:65], s[56:57] op_sel_hi:[1,0]
	v_xor_b32_e32 v99, 0x80000000, v54
	v_mov_b32_e32 v98, v56
	v_pk_add_f32 v[100:101], v[58:59], 0 neg_lo:[1,1] neg_hi:[1,1]
	v_mov_b32_e32 v2, v32
	v_mov_b32_e32 v3, v34
	v_mov_b32_e32 v4, v33
	v_mov_b32_e32 v5, v35
	v_mov_b32_e32 v18, v47
	v_mov_b32_e32 v19, v49
	v_mov_b32_e32 v68, v58
	v_mov_b32_e32 v69, v60
	v_pk_fma_f32 v[64:65], v[98:99], s[58:59], v[64:65] op_sel_hi:[1,0,1] neg_lo:[0,0,1] neg_hi:[0,0,1]
	v_pk_add_f32 v[98:99], v[66:67], 0 op_sel_hi:[1,0]
	v_pk_mul_f32 v[66:67], v[66:67], s[52:53] op_sel_hi:[1,0]
	v_mov_b32_e32 v100, v61
	v_pk_add_f32 v[70:71], v[2:3], 0 op_sel_hi:[1,0]
	v_pk_add_f32 v[72:73], v[4:5], 0 op_sel_hi:[1,0]
	v_pk_add_f32 v[74:75], v[32:33], 0 neg_lo:[1,1] neg_hi:[1,1]
	v_pk_add_f32 v[18:19], v[18:19], 0 op_sel_hi:[1,0]
	v_pk_fma_f32 v[66:67], v[100:101], s[54:55], v[66:67] op_sel_hi:[1,0,1] neg_lo:[0,0,1] neg_hi:[0,0,1]
	v_pk_add_f32 v[100:101], v[68:69], 0 op_sel_hi:[1,0]
	v_pk_mul_f32 v[68:69], v[68:69], s[44:45] op_sel_hi:[1,0]
	v_xor_b32_e32 v103, 0x80000000, v58
	v_mov_b32_e32 v102, v60
	v_mov_b32_e32 v74, v35
	v_pk_fma_f32 v[68:69], v[102:103], s[48:49], v[68:69] op_sel_hi:[1,0,1] neg_lo:[0,0,1] neg_hi:[0,0,1]
	v_pk_add_f32 v[102:103], v[18:19], v[70:71]
	v_pk_add_f32 v[18:19], v[70:71], v[18:19] neg_lo:[0,1] neg_hi:[0,1]
	v_pk_add_f32 v[70:71], v[88:89], v[72:73]
	v_pk_add_f32 v[72:73], v[72:73], v[88:89] neg_lo:[0,1] neg_hi:[0,1]
	v_mov_b32_e32 v6, v37
	v_mov_b32_e32 v7, v31
	v_pk_mul_f32 v[74:75], v[74:75], s[48:49] op_sel_hi:[1,0]
	v_pk_fma_f32 v[4:5], v[4:5], s[44:45], v[74:75] op_sel_hi:[1,0,1]
	v_pk_add_f32 v[74:75], v[6:7], 0 op_sel_hi:[1,0]
	v_pk_add_f32 v[76:77], v[36:37], 0 neg_lo:[1,1] neg_hi:[1,1]
	v_pk_mul_f32 v[88:89], v[72:73], s[54:55] op_sel:[1,0] op_sel_hi:[0,0] neg_hi:[1,0]
	v_mov_b32_e32 v76, v31
	v_pk_fma_f32 v[72:73], v[72:73], s[52:53], v[88:89] op_sel_hi:[1,0,1]
	v_pk_add_f32 v[88:89], v[90:91], v[74:75]
	v_pk_add_f32 v[74:75], v[74:75], v[90:91] neg_lo:[0,1] neg_hi:[0,1]
	v_mov_b32_e32 v8, v36
	v_mov_b32_e32 v9, v30
	v_pk_mul_f32 v[76:77], v[76:77], s[54:55] op_sel_hi:[1,0]
	v_pk_fma_f32 v[6:7], v[6:7], s[52:53], v[76:77] op_sel_hi:[1,0,1]
	v_pk_add_f32 v[76:77], v[8:9], 0 op_sel_hi:[1,0]
	v_pk_mul_f32 v[90:91], v[74:75], s[60:61] op_sel:[1,0] op_sel_hi:[0,0] neg_hi:[1,0]
	v_xor_b32_e32 v79, 0x80000000, v36
	v_mov_b32_e32 v78, v30
	v_pk_add_f32 v[80:81], v[38:39], 0 neg_lo:[1,1] neg_hi:[1,1]
	v_pk_fma_f32 v[74:75], v[74:75], s[60:61], v[90:91] op_sel_hi:[1,0,1]
	v_pk_add_f32 v[90:91], v[92:93], v[76:77]
	v_pk_add_f32 v[76:77], v[76:77], v[92:93] neg_lo:[0,1] neg_hi:[0,1]
	v_mov_b32_e32 v10, v39
	v_mov_b32_e32 v11, v41
	v_pk_mul_f32 v[78:79], v[78:79], s[58:59] op_sel_hi:[1,0]
	v_mov_b32_e32 v80, v41
	v_mov_b32_e32 v12, v38
	v_mov_b32_e32 v13, v40
	v_pk_fma_f32 v[8:9], v[8:9], s[56:57], v[78:79] op_sel_hi:[1,0,1]
	v_pk_add_f32 v[78:79], v[10:11], 0 op_sel_hi:[1,0]
	v_pk_mul_f32 v[80:81], v[80:81], s[60:61] op_sel_hi:[1,0]
	v_pk_mul_f32 v[92:93], v[76:77], s[52:53] op_sel:[1,0] op_sel_hi:[0,0] neg_hi:[1,0]
	v_pk_fma_f32 v[10:11], v[10:11], s[60:61], v[80:81] op_sel_hi:[1,0,1]
	v_pk_add_f32 v[80:81], v[12:13], 0 op_sel_hi:[1,0]
	v_xor_b32_e32 v83, 0x80000000, v38
	v_mov_b32_e32 v82, v40
	v_pk_fma_f32 v[76:77], v[76:77], s[54:55], v[92:93] op_sel_hi:[1,0,1]
	v_pk_add_f32 v[92:93], v[94:95], v[78:79]
	v_pk_add_f32 v[78:79], v[78:79], v[94:95] neg_lo:[0,1] neg_hi:[0,1]
	v_mov_b32_e32 v14, v43
	v_mov_b32_e32 v15, v45
	v_pk_mul_f32 v[82:83], v[82:83], s[56:57] op_sel_hi:[1,0]
	v_pk_add_f32 v[84:85], v[42:43], 0 neg_lo:[1,1] neg_hi:[1,1]
	v_xor_b32_e32 v95, 0x80000000, v78
	v_mov_b32_e32 v94, v79
	v_pk_add_f32 v[78:79], v[96:97], v[80:81]
	v_pk_add_f32 v[80:81], v[80:81], v[96:97] neg_lo:[0,1] neg_hi:[0,1]
	v_pk_fma_f32 v[12:13], v[12:13], s[58:59], v[82:83] op_sel_hi:[1,0,1]
	v_pk_add_f32 v[82:83], v[14:15], 0 op_sel_hi:[1,0]
	v_mov_b32_e32 v84, v45
	v_pk_mul_f32 v[96:97], v[80:81], s[54:55] op_sel_hi:[1,0]
	v_xor_b32_e32 v105, 0x80000000, v80
	v_mov_b32_e32 v104, v81
	v_mov_b32_e32 v16, v42
	v_mov_b32_e32 v17, v44
	v_pk_mul_f32 v[84:85], v[84:85], s[52:53] op_sel_hi:[1,0]
	v_xor_b32_e32 v87, 0x80000000, v42
	v_mov_b32_e32 v86, v44
	v_pk_fma_f32 v[80:81], v[104:105], s[52:53], v[96:97] op_sel_hi:[1,0,1] neg_lo:[0,0,1] neg_hi:[0,0,1]
	v_pk_add_f32 v[96:97], v[98:99], v[82:83]
	v_pk_add_f32 v[82:83], v[82:83], v[98:99] neg_lo:[0,1] neg_hi:[0,1]
	v_pk_fma_f32 v[14:15], v[14:15], s[54:55], v[84:85] op_sel_hi:[1,0,1]
	v_pk_add_f32 v[84:85], v[16:17], 0 op_sel_hi:[1,0]
	v_pk_mul_f32 v[86:87], v[86:87], s[44:45] op_sel_hi:[1,0]
	v_pk_mul_f32 v[98:99], v[82:83], s[60:61] op_sel_hi:[1,0]
	v_xor_b32_e32 v105, 0x80000000, v82
	v_mov_b32_e32 v104, v83
	v_pk_fma_f32 v[16:17], v[16:17], s[48:49], v[86:87] op_sel_hi:[1,0,1]
	v_pk_add_f32 v[86:87], v[46:47], 0 neg_lo:[1,1] neg_hi:[1,1]
	v_pk_fma_f32 v[82:83], v[104:105], s[60:61], v[98:99] op_sel_hi:[1,0,1] neg_lo:[0,0,1] neg_hi:[0,0,1]
	v_pk_add_f32 v[98:99], v[100:101], v[84:85]
	v_pk_add_f32 v[84:85], v[84:85], v[100:101] neg_lo:[0,1] neg_hi:[0,1]
	v_mov_b32_e32 v86, v49
	v_pk_mul_f32 v[100:101], v[84:85], s[52:53] op_sel_hi:[1,0]
	v_xor_b32_e32 v105, 0x80000000, v84
	v_mov_b32_e32 v104, v85
	v_pk_fma_f32 v[84:85], v[104:105], s[54:55], v[100:101] op_sel_hi:[1,0,1] neg_lo:[0,0,1] neg_hi:[0,0,1]
	v_pk_add_f32 v[100:101], v[86:87], v[2:3]
	v_pk_add_f32 v[2:3], v[2:3], v[86:87] neg_lo:[0,1] neg_hi:[0,1]
	v_pk_add_f32 v[86:87], v[20:21], v[4:5]
	v_pk_add_f32 v[4:5], v[4:5], v[20:21] neg_lo:[0,1] neg_hi:[0,1]
	v_mov_b32_e32 v63, v146
	v_pk_mul_f32 v[20:21], v[4:5], s[54:55] op_sel:[1,0] op_sel_hi:[0,0] neg_hi:[1,0]
	v_pk_fma_f32 v[4:5], v[4:5], s[52:53], v[20:21] op_sel_hi:[1,0,1]
	v_pk_add_f32 v[20:21], v[22:23], v[6:7]
	v_pk_add_f32 v[6:7], v[6:7], v[22:23] neg_lo:[0,1] neg_hi:[0,1]
	s_barrier
	v_pk_mul_f32 v[22:23], v[6:7], s[60:61] op_sel:[1,0] op_sel_hi:[0,0] neg_hi:[1,0]
	s_nop 0
	v_pk_fma_f32 v[6:7], v[6:7], s[60:61], v[22:23] op_sel_hi:[1,0,1]
	v_pk_add_f32 v[22:23], v[24:25], v[8:9]
	v_pk_add_f32 v[8:9], v[8:9], v[24:25] neg_lo:[0,1] neg_hi:[0,1]
	s_add_i32 s19, 16, 0x11000
	v_pk_mul_f32 v[24:25], v[8:9], s[52:53] op_sel:[1,0] op_sel_hi:[0,0] neg_hi:[1,0]
	s_add_i32 s18, 16, 0x12000
	v_pk_fma_f32 v[8:9], v[8:9], s[54:55], v[24:25] op_sel_hi:[1,0,1]
	v_pk_add_f32 v[24:25], v[26:27], v[10:11]
	v_pk_add_f32 v[10:11], v[10:11], v[26:27] neg_lo:[0,1] neg_hi:[0,1]
	s_add_i32 s17, 16, 0x13000
	v_xor_b32_e32 v27, 0x80000000, v10
	v_mov_b32_e32 v26, v11
	v_pk_add_f32 v[10:11], v[64:65], v[12:13]
	v_pk_add_f32 v[12:13], v[12:13], v[64:65] neg_lo:[0,1] neg_hi:[0,1]
	s_add_i32 s13, 16, 0x14000
	v_pk_mul_f32 v[64:65], v[12:13], s[54:55] op_sel_hi:[1,0]
	v_xor_b32_e32 v105, 0x80000000, v12
	v_mov_b32_e32 v104, v13
	v_pk_fma_f32 v[12:13], v[104:105], s[52:53], v[64:65] op_sel_hi:[1,0,1] neg_lo:[0,0,1] neg_hi:[0,0,1]
	v_pk_add_f32 v[64:65], v[66:67], v[14:15]
	v_pk_add_f32 v[14:15], v[14:15], v[66:67] neg_lo:[0,1] neg_hi:[0,1]
	s_add_i32 s12, 16, 0x15000
	v_pk_mul_f32 v[66:67], v[14:15], s[60:61] op_sel_hi:[1,0]
	v_xor_b32_e32 v105, 0x80000000, v14
	v_mov_b32_e32 v104, v15
	v_pk_fma_f32 v[14:15], v[104:105], s[60:61], v[66:67] op_sel_hi:[1,0,1] neg_lo:[0,0,1] neg_hi:[0,0,1]
	v_pk_add_f32 v[66:67], v[68:69], v[16:17]
	v_pk_add_f32 v[16:17], v[16:17], v[68:69] neg_lo:[0,1] neg_hi:[0,1]
	s_add_i32 s11, 16, 0x16000
	v_pk_mul_f32 v[68:69], v[16:17], s[52:53] op_sel_hi:[1,0]
	v_xor_b32_e32 v105, 0x80000000, v16
	v_mov_b32_e32 v104, v17
	v_pk_fma_f32 v[16:17], v[104:105], s[54:55], v[68:69] op_sel_hi:[1,0,1] neg_lo:[0,0,1] neg_hi:[0,0,1]
	v_pk_add_f32 v[68:69], v[92:93], v[102:103]
	v_pk_add_f32 v[92:93], v[102:103], v[92:93] neg_lo:[0,1] neg_hi:[0,1]
	v_pk_add_f32 v[102:103], v[78:79], v[70:71]
	v_pk_add_f32 v[70:71], v[70:71], v[78:79] neg_lo:[0,1] neg_hi:[0,1]
	s_add_i32 s10, 16, 0x17000
	v_pk_mul_f32 v[78:79], v[70:71], s[60:61] op_sel:[1,0] op_sel_hi:[0,0] neg_hi:[1,0]
	s_add_i32 s9, 16, 0x18000
	v_pk_fma_f32 v[70:71], v[70:71], s[60:61], v[78:79] op_sel_hi:[1,0,1]
	v_pk_add_f32 v[78:79], v[96:97], v[88:89]
	v_pk_add_f32 v[88:89], v[88:89], v[96:97] neg_lo:[0,1] neg_hi:[0,1]
	s_add_i32 s8, 16, 0x19000
	v_xor_b32_e32 v97, 0x80000000, v88
	v_mov_b32_e32 v96, v89
	v_pk_add_f32 v[88:89], v[98:99], v[90:91]
	v_pk_add_f32 v[90:91], v[90:91], v[98:99] neg_lo:[0,1] neg_hi:[0,1]
	s_add_i32 s7, 16, 0x1a000
	v_pk_mul_f32 v[98:99], v[90:91], s[60:61] op_sel_hi:[1,0]
	v_xor_b32_e32 v105, 0x80000000, v90
	v_mov_b32_e32 v104, v91
	v_pk_fma_f32 v[90:91], v[104:105], s[60:61], v[98:99] op_sel_hi:[1,0,1] neg_lo:[0,0,1] neg_hi:[0,0,1]
	v_pk_add_f32 v[98:99], v[94:95], v[18:19]
	v_pk_add_f32 v[18:19], v[18:19], v[94:95] neg_lo:[0,1] neg_hi:[0,1]
	v_pk_add_f32 v[94:95], v[80:81], v[72:73]
	v_pk_add_f32 v[72:73], v[72:73], v[80:81] neg_lo:[0,1] neg_hi:[0,1]
	s_add_i32 s6, 16, 0x1b000
	v_pk_mul_f32 v[80:81], v[72:73], s[60:61] op_sel:[1,0] op_sel_hi:[0,0] neg_hi:[1,0]
	s_add_i32 s5, 16, 0x1c000
	v_pk_fma_f32 v[72:73], v[72:73], s[60:61], v[80:81] op_sel_hi:[1,0,1]
	v_pk_add_f32 v[80:81], v[82:83], v[74:75]
	v_pk_add_f32 v[74:75], v[74:75], v[82:83] neg_lo:[0,1] neg_hi:[0,1]
	s_add_i32 s4, 16, 0x1d000
	v_xor_b32_e32 v83, 0x80000000, v74
	v_mov_b32_e32 v82, v75
	v_pk_add_f32 v[74:75], v[84:85], v[76:77]
	v_pk_add_f32 v[76:77], v[76:77], v[84:85] neg_lo:[0,1] neg_hi:[0,1]
	v_pk_add_f32 v[106:107], v[18:19], v[82:83]
	v_pk_mul_f32 v[84:85], v[76:77], s[60:61] op_sel_hi:[1,0]
	v_xor_b32_e32 v105, 0x80000000, v76
	v_mov_b32_e32 v104, v77
	v_pk_fma_f32 v[76:77], v[104:105], s[60:61], v[84:85] op_sel_hi:[1,0,1] neg_lo:[0,0,1] neg_hi:[0,0,1]
	v_pk_add_f32 v[84:85], v[24:25], v[100:101]
	v_pk_add_f32 v[24:25], v[100:101], v[24:25] neg_lo:[0,1] neg_hi:[0,1]
	v_pk_add_f32 v[100:101], v[10:11], v[86:87]
	v_pk_add_f32 v[10:11], v[86:87], v[10:11] neg_lo:[0,1] neg_hi:[0,1]
	v_pk_add_f32 v[18:19], v[18:19], v[82:83] neg_lo:[0,1] neg_hi:[0,1]
	v_pk_mul_f32 v[86:87], v[10:11], s[60:61] op_sel:[1,0] op_sel_hi:[0,0] neg_hi:[1,0]
	v_pk_add_f32 v[82:83], v[76:77], v[72:73]
	v_pk_fma_f32 v[10:11], v[10:11], s[60:61], v[86:87] op_sel_hi:[1,0,1]
	v_pk_add_f32 v[86:87], v[64:65], v[20:21]
	v_pk_add_f32 v[20:21], v[20:21], v[64:65] neg_lo:[0,1] neg_hi:[0,1]
	v_pk_add_f32 v[72:73], v[72:73], v[76:77] neg_lo:[0,1] neg_hi:[0,1]
	v_xor_b32_e32 v65, 0x80000000, v20
	v_mov_b32_e32 v64, v21
	v_pk_add_f32 v[20:21], v[66:67], v[22:23]
	v_pk_add_f32 v[22:23], v[22:23], v[66:67] neg_lo:[0,1] neg_hi:[0,1]
	v_xor_b32_e32 v77, 0x80000000, v72
	v_pk_mul_f32 v[66:67], v[22:23], s[60:61] op_sel_hi:[1,0]
	v_xor_b32_e32 v105, 0x80000000, v22
	v_mov_b32_e32 v104, v23
	v_pk_fma_f32 v[22:23], v[104:105], s[60:61], v[66:67] op_sel_hi:[1,0,1] neg_lo:[0,0,1] neg_hi:[0,0,1]
	v_pk_add_f32 v[66:67], v[2:3], v[26:27]
	v_pk_add_f32 v[2:3], v[2:3], v[26:27] neg_lo:[0,1] neg_hi:[0,1]
	v_pk_add_f32 v[26:27], v[12:13], v[4:5]
	v_pk_add_f32 v[4:5], v[4:5], v[12:13] neg_lo:[0,1] neg_hi:[0,1]
	v_mov_b32_e32 v76, v73
	v_pk_mul_f32 v[12:13], v[4:5], s[60:61] op_sel:[1,0] op_sel_hi:[0,0] neg_hi:[1,0]
	v_pk_add_f32 v[72:73], v[84:85], v[86:87]
	v_pk_fma_f32 v[4:5], v[4:5], s[60:61], v[12:13] op_sel_hi:[1,0,1]
	v_pk_add_f32 v[12:13], v[14:15], v[6:7]
	v_pk_add_f32 v[6:7], v[6:7], v[14:15] neg_lo:[0,1] neg_hi:[0,1]
	v_pk_add_f32 v[84:85], v[84:85], v[86:87] neg_lo:[0,1] neg_hi:[0,1]
	v_xor_b32_e32 v15, 0x80000000, v6
	v_mov_b32_e32 v14, v7
	v_pk_add_f32 v[6:7], v[16:17], v[8:9]
	v_pk_add_f32 v[8:9], v[8:9], v[16:17] neg_lo:[0,1] neg_hi:[0,1]
	v_pk_add_f32 v[86:87], v[20:21], v[100:101]
	v_pk_mul_f32 v[16:17], v[8:9], s[60:61] op_sel_hi:[1,0]
	v_pk_fma_f32 v[8:9], v[8:9], s[60:61], v[16:17] op_sel:[1,0,0] op_sel_hi:[0,0,1] neg_lo:[0,0,1] neg_hi:[1,0,1]
	v_pk_add_f32 v[104:105], v[92:93], v[96:97]
	v_pk_add_f32 v[92:93], v[92:93], v[96:97] neg_lo:[0,1] neg_hi:[0,1]
	v_pk_add_f32 v[96:97], v[90:91], v[70:71]
	v_pk_add_f32 v[70:71], v[70:71], v[90:91] neg_lo:[0,1] neg_hi:[0,1]
	v_pk_add_f32 v[16:17], v[78:79], v[68:69]
	v_pk_add_f32 v[68:69], v[68:69], v[78:79] neg_lo:[0,1] neg_hi:[0,1]
	v_pk_add_f32 v[78:79], v[88:89], v[102:103]
	v_pk_add_f32 v[88:89], v[102:103], v[88:89] neg_lo:[0,1] neg_hi:[0,1]
	v_xor_b32_e32 v91, 0x80000000, v70
	v_mov_b32_e32 v90, v71
	v_pk_add_f32 v[70:71], v[98:99], v[80:81]
	v_pk_add_f32 v[98:99], v[98:99], v[80:81] neg_lo:[0,1] neg_hi:[0,1]
	v_pk_add_f32 v[80:81], v[74:75], v[94:95]
	v_pk_add_f32 v[74:75], v[94:95], v[74:75] neg_lo:[0,1] neg_hi:[0,1]
	v_pk_add_f32 v[20:21], v[100:101], v[20:21] neg_lo:[0,1] neg_hi:[0,1]
	v_pk_add_f32 v[108:109], v[24:25], v[64:65]
	v_pk_add_f32 v[24:25], v[24:25], v[64:65] neg_lo:[0,1] neg_hi:[0,1]
	v_pk_add_f32 v[64:65], v[22:23], v[10:11]
	v_pk_add_f32 v[10:11], v[10:11], v[22:23] neg_lo:[0,1] neg_hi:[0,1]
	v_pk_add_f32 v[114:115], v[6:7], v[26:27]
	v_pk_add_f32 v[6:7], v[26:27], v[6:7] neg_lo:[0,1] neg_hi:[0,1]
	v_xor_b32_e32 v103, 0x80000000, v88
	v_mov_b32_e32 v102, v89
	v_xor_b32_e32 v95, 0x80000000, v74
	v_mov_b32_e32 v94, v75
	v_xor_b32_e32 v101, 0x80000000, v20
	v_mov_b32_e32 v100, v21
	v_xor_b32_e32 v27, 0x80000000, v6
	v_mov_b32_e32 v26, v7
	v_pk_add_f32 v[6:7], v[2:3], v[14:15]
	v_pk_add_f32 v[116:117], v[2:3], v[14:15] neg_lo:[0,1] neg_hi:[0,1]
	v_pk_add_f32 v[2:3], v[4:5], v[8:9] neg_lo:[0,1] neg_hi:[0,1]
	v_pk_add_f32 v[112:113], v[66:67], v[12:13]
	v_pk_add_f32 v[66:67], v[66:67], v[12:13] neg_lo:[0,1] neg_hi:[0,1]
	v_pk_add_f32 v[118:119], v[8:9], v[4:5]
	v_xor_b32_e32 v121, 0x80000000, v2
	v_mov_b32_e32 v120, v3
	v_pk_add_f32 v[2:3], v[78:79], v[16:17]
	v_pk_add_f32 v[88:89], v[16:17], v[78:79] neg_lo:[0,1] neg_hi:[0,1]
	v_pk_add_f32 v[122:123], v[68:69], v[102:103]
	v_pk_add_f32 v[20:21], v[68:69], v[102:103] neg_lo:[0,1] neg_hi:[0,1]
	v_pk_add_f32 v[78:79], v[104:105], v[96:97]
	v_pk_add_f32 v[74:75], v[104:105], v[96:97] neg_lo:[0,1] neg_hi:[0,1]
	v_pk_add_f32 v[96:97], v[92:93], v[90:91]
	v_pk_add_f32 v[8:9], v[92:93], v[90:91] neg_lo:[0,1] neg_hi:[0,1]
	v_pk_add_f32 v[102:103], v[98:99], v[94:95]
	v_pk_add_f32 v[12:13], v[98:99], v[94:95] neg_lo:[0,1] neg_hi:[0,1]
	v_pk_add_f32 v[98:99], v[18:19], v[76:77]
	v_pk_add_f32 v[4:5], v[18:19], v[76:77] neg_lo:[0,1] neg_hi:[0,1]
	v_pk_add_f32 v[18:19], v[72:73], v[86:87]
	v_pk_add_f32 v[92:93], v[72:73], v[86:87] neg_lo:[0,1] neg_hi:[0,1]
	v_pk_add_f32 v[86:87], v[84:85], v[100:101]
	v_pk_add_f32 v[22:23], v[84:85], v[100:101] neg_lo:[0,1] neg_hi:[0,1]
	v_pk_add_f32 v[100:101], v[24:25], v[10:11] op_sel:[0,1] op_sel_hi:[1,0] neg_hi:[0,1]
	v_pk_add_f32 v[10:11], v[24:25], v[10:11] op_sel:[0,1] op_sel_hi:[1,0] neg_lo:[0,1]
	v_mov_b32_e32 v24, v63
	v_pk_add_f32 v[84:85], v[108:109], v[64:65]
	v_cvt_f32_i32_e32 v24, v24
	v_pk_add_f32 v[76:77], v[108:109], v[64:65] neg_lo:[0,1] neg_hi:[0,1]
	v_pk_add_f32 v[104:105], v[66:67], v[26:27]
	v_pk_add_f32 v[14:15], v[66:67], v[26:27] neg_lo:[0,1] neg_hi:[0,1]
	v_mul_f32_e32 v25, 0x38800000, v24
	v_cos_f32_e32 v24, v25
	v_sin_f32_e32 v25, v25
	s_nop 0
	s_nop 0
	v_add_f32_e32 v62, v24, v24
	v_pk_mul_f32 v[26:27], v[24:25], v[24:25]
	v_mul_f32_e32 v62, v25, v62
	v_mov_b32_e32 v108, v25
	v_pk_add_f32 v[26:27], v[26:27], v[26:27] op_sel:[0,1] op_sel_hi:[0,1] neg_lo:[0,1] neg_hi:[0,1]
	v_pk_mul_f32 v[72:73], v[24:25], v[62:63] op_sel:[1,0] op_sel_hi:[0,0] neg_lo:[1,0]
	v_pk_mul_f32 v[94:95], v[18:19], v[108:109] op_sel:[1,0] op_sel_hi:[0,0] neg_hi:[1,0]
	v_pk_add_f32 v[16:17], v[70:71], v[80:81]
	v_pk_fma_f32 v[72:73], v[24:25], v[26:27], v[72:73]
	v_pk_fma_f32 v[18:19], v[18:19], v[24:25], v[94:95] op_sel_hi:[1,0,1]
	v_pk_mul_f32 v[24:25], v[62:63], s[46:47] op_sel_hi:[0,1]
	v_pk_fma_f32 v[94:95], v[26:27], s[40:41], v[24:25]
	v_pk_mul_f32 v[24:25], v[16:17], v[94:95] op_sel:[1,1] op_sel_hi:[0,1] neg_hi:[1,0]
	v_pk_add_f32 v[64:65], v[112:113], v[114:115]
	v_pk_fma_f32 v[24:25], v[16:17], v[94:95], v[24:25] op_sel_hi:[1,0,1]
	v_pk_mul_f32 v[16:17], v[62:63], v[72:73] op_sel:[0,1] op_sel_hi:[0,0] neg_lo:[0,1]
	v_pk_fma_f32 v[108:109], v[26:27], v[72:73], v[16:17]
	v_pk_mul_f32 v[16:17], v[64:65], v[72:73] op_sel:[1,1] op_sel_hi:[0,1] neg_hi:[1,0]
	v_pk_add_f32 v[90:91], v[106:107], v[82:83]
	v_pk_fma_f32 v[16:17], v[64:65], v[72:73], v[16:17] op_sel_hi:[1,0,1]
	v_pk_mul_f32 v[64:65], v[62:63], v[94:95] op_sel:[0,1] op_sel_hi:[0,0] neg_lo:[0,1]
	v_pk_fma_f32 v[94:95], v[26:27], v[94:95], v[64:65]
	v_pk_mul_f32 v[64:65], v[78:79], v[94:95] op_sel:[1,1] op_sel_hi:[0,1] neg_hi:[1,0]
	v_pk_add_f32 v[66:67], v[6:7], v[118:119]
	v_pk_fma_f32 v[72:73], v[78:79], v[94:95], v[64:65] op_sel_hi:[1,0,1]
	v_pk_mul_f32 v[64:65], v[62:63], v[108:109] op_sel:[0,1] op_sel_hi:[0,0] neg_lo:[0,1]
	v_pk_fma_f32 v[110:111], v[26:27], v[108:109], v[64:65]
	v_pk_mul_f32 v[64:65], v[84:85], v[108:109] op_sel:[1,1] op_sel_hi:[0,1] neg_hi:[1,0]
	v_pk_mul_f32 v[78:79], v[62:63], v[94:95] op_sel:[0,1] op_sel_hi:[0,0] neg_lo:[0,1]
	v_pk_fma_f32 v[64:65], v[84:85], v[108:109], v[64:65] op_sel_hi:[1,0,1]
	v_pk_fma_f32 v[84:85], v[26:27], v[94:95], v[78:79]
	v_pk_mul_f32 v[78:79], v[90:91], v[84:85] op_sel:[1,1] op_sel_hi:[0,1] neg_hi:[1,0]
	v_pk_add_f32 v[68:69], v[106:107], v[82:83] neg_lo:[0,1] neg_hi:[0,1]
	v_pk_fma_f32 v[78:79], v[90:91], v[84:85], v[78:79] op_sel_hi:[1,0,1]
	v_pk_mul_f32 v[90:91], v[62:63], v[110:111] op_sel:[0,1] op_sel_hi:[0,0] neg_lo:[0,1]
	v_pk_fma_f32 v[94:95], v[26:27], v[110:111], v[90:91]
	v_pk_mul_f32 v[90:91], v[66:67], v[110:111] op_sel:[1,1] op_sel_hi:[0,1] neg_hi:[1,0]
	v_pk_add_f32 v[106:107], v[116:117], v[120:121]
	v_pk_fma_f32 v[66:67], v[66:67], v[110:111], v[90:91] op_sel_hi:[1,0,1]
	v_pk_mul_f32 v[90:91], v[62:63], v[84:85] op_sel:[0,1] op_sel_hi:[0,0] neg_lo:[0,1]
	v_pk_fma_f32 v[108:109], v[26:27], v[84:85], v[90:91]
	v_pk_mul_f32 v[84:85], v[122:123], v[108:109] op_sel:[1,1] op_sel_hi:[0,1] neg_hi:[1,0]
	v_pk_add_f32 v[80:81], v[70:71], v[80:81] neg_lo:[0,1] neg_hi:[0,1]
	v_pk_fma_f32 v[90:91], v[122:123], v[108:109], v[84:85] op_sel_hi:[1,0,1]
	v_pk_mul_f32 v[84:85], v[62:63], v[94:95] op_sel:[0,1] op_sel_hi:[0,0] neg_lo:[0,1]
	v_pk_fma_f32 v[110:111], v[26:27], v[94:95], v[84:85]
	v_pk_mul_f32 v[84:85], v[86:87], v[94:95] op_sel:[1,1] op_sel_hi:[0,1] neg_hi:[1,0]
	v_pk_add_f32 v[82:83], v[112:113], v[114:115] neg_lo:[0,1] neg_hi:[0,1]
	v_pk_fma_f32 v[84:85], v[86:87], v[94:95], v[84:85] op_sel_hi:[1,0,1]
	v_pk_mul_f32 v[86:87], v[62:63], v[108:109] op_sel:[0,1] op_sel_hi:[0,0] neg_lo:[0,1]
	v_pk_fma_f32 v[108:109], v[26:27], v[108:109], v[86:87]
	v_pk_mul_f32 v[86:87], v[102:103], v[108:109] op_sel:[1,1] op_sel_hi:[0,1] neg_hi:[1,0]
	v_pk_add_f32 v[70:71], v[6:7], v[118:119] neg_lo:[0,1] neg_hi:[0,1]
	v_pk_fma_f32 v[94:95], v[102:103], v[108:109], v[86:87] op_sel_hi:[1,0,1]
	v_pk_mul_f32 v[86:87], v[62:63], v[110:111] op_sel:[0,1] op_sel_hi:[0,0] neg_lo:[0,1]
	v_pk_fma_f32 v[102:103], v[26:27], v[110:111], v[86:87]
	v_pk_mul_f32 v[86:87], v[104:105], v[110:111] op_sel:[1,1] op_sel_hi:[0,1] neg_hi:[1,0]
	v_pk_add_f32 v[6:7], v[116:117], v[120:121] neg_lo:[0,1] neg_hi:[0,1]
	v_pk_fma_f32 v[86:87], v[104:105], v[110:111], v[86:87] op_sel_hi:[1,0,1]
	v_pk_mul_f32 v[104:105], v[62:63], v[108:109] op_sel:[0,1] op_sel_hi:[0,0] neg_lo:[0,1]
	v_pk_fma_f32 v[104:105], v[26:27], v[108:109], v[104:105]
	v_pk_mul_f32 v[108:109], v[96:97], v[104:105] op_sel:[1,1] op_sel_hi:[0,1] neg_hi:[1,0]
	v_pk_fma_f32 v[96:97], v[96:97], v[104:105], v[108:109] op_sel_hi:[1,0,1]
	v_pk_mul_f32 v[108:109], v[62:63], v[102:103] op_sel:[0,1] op_sel_hi:[0,0] neg_lo:[0,1]
	v_pk_mul_f32 v[110:111], v[100:101], v[102:103] op_sel:[1,1] op_sel_hi:[0,1] neg_hi:[1,0]
	v_pk_fma_f32 v[108:109], v[26:27], v[102:103], v[108:109]
	v_pk_fma_f32 v[100:101], v[100:101], v[102:103], v[110:111] op_sel_hi:[1,0,1]
	v_pk_mul_f32 v[102:103], v[62:63], v[104:105] op_sel:[0,1] op_sel_hi:[0,0] neg_lo:[0,1]
	v_pk_fma_f32 v[102:103], v[26:27], v[104:105], v[102:103]
	v_pk_mul_f32 v[104:105], v[98:99], v[102:103] op_sel:[1,1] op_sel_hi:[0,1] neg_hi:[1,0]
	v_pk_fma_f32 v[98:99], v[98:99], v[102:103], v[104:105] op_sel_hi:[1,0,1]
	v_pk_mul_f32 v[104:105], v[62:63], v[108:109] op_sel:[0,1] op_sel_hi:[0,0] neg_lo:[0,1]
	v_pk_mul_f32 v[110:111], v[106:107], v[108:109] op_sel:[1,1] op_sel_hi:[0,1] neg_hi:[1,0]
	v_pk_fma_f32 v[104:105], v[26:27], v[108:109], v[104:105]
	v_pk_fma_f32 v[106:107], v[106:107], v[108:109], v[110:111] op_sel_hi:[1,0,1]
	v_pk_mul_f32 v[108:109], v[62:63], v[102:103] op_sel:[0,1] op_sel_hi:[0,0] neg_lo:[0,1]
	v_pk_fma_f32 v[102:103], v[26:27], v[102:103], v[108:109]
	v_pk_mul_f32 v[108:109], v[88:89], v[102:103] op_sel:[1,1] op_sel_hi:[0,1] neg_hi:[1,0]
	v_pk_fma_f32 v[88:89], v[88:89], v[102:103], v[108:109] op_sel_hi:[1,0,1]
	v_pk_mul_f32 v[108:109], v[62:63], v[104:105] op_sel:[0,1] op_sel_hi:[0,0] neg_lo:[0,1]
	v_pk_mul_f32 v[110:111], v[92:93], v[104:105] op_sel:[1,1] op_sel_hi:[0,1] neg_hi:[1,0]
	v_pk_fma_f32 v[108:109], v[26:27], v[104:105], v[108:109]
	v_pk_fma_f32 v[92:93], v[92:93], v[104:105], v[110:111] op_sel_hi:[1,0,1]
	v_pk_mul_f32 v[104:105], v[62:63], v[102:103] op_sel:[0,1] op_sel_hi:[0,0] neg_lo:[0,1]
	v_pk_fma_f32 v[102:103], v[26:27], v[102:103], v[104:105]
	v_pk_mul_f32 v[104:105], v[80:81], v[102:103] op_sel:[1,1] op_sel_hi:[0,1] neg_hi:[1,0]
	v_pk_fma_f32 v[80:81], v[80:81], v[102:103], v[104:105] op_sel_hi:[1,0,1]
	v_pk_mul_f32 v[104:105], v[62:63], v[108:109] op_sel:[0,1] op_sel_hi:[0,0] neg_lo:[0,1]
	v_pk_mul_f32 v[110:111], v[82:83], v[108:109] op_sel:[1,1] op_sel_hi:[0,1] neg_hi:[1,0]
	v_pk_fma_f32 v[104:105], v[26:27], v[108:109], v[104:105]
	v_pk_fma_f32 v[82:83], v[82:83], v[108:109], v[110:111] op_sel_hi:[1,0,1]
	v_pk_mul_f32 v[108:109], v[62:63], v[102:103] op_sel:[0,1] op_sel_hi:[0,0] neg_lo:[0,1]
	v_pk_fma_f32 v[102:103], v[26:27], v[102:103], v[108:109]
	v_pk_mul_f32 v[108:109], v[74:75], v[102:103] op_sel:[1,1] op_sel_hi:[0,1] neg_hi:[1,0]
	v_pk_fma_f32 v[74:75], v[74:75], v[102:103], v[108:109] op_sel_hi:[1,0,1]
	v_pk_mul_f32 v[108:109], v[62:63], v[104:105] op_sel:[0,1] op_sel_hi:[0,0] neg_lo:[0,1]
	v_pk_mul_f32 v[110:111], v[76:77], v[104:105] op_sel:[1,1] op_sel_hi:[0,1] neg_hi:[1,0]
	v_pk_fma_f32 v[108:109], v[26:27], v[104:105], v[108:109]
	v_pk_fma_f32 v[76:77], v[76:77], v[104:105], v[110:111] op_sel_hi:[1,0,1]
	v_pk_mul_f32 v[104:105], v[62:63], v[102:103] op_sel:[0,1] op_sel_hi:[0,0] neg_lo:[0,1]
	v_pk_fma_f32 v[102:103], v[26:27], v[102:103], v[104:105]
	v_pk_mul_f32 v[104:105], v[68:69], v[102:103] op_sel:[1,1] op_sel_hi:[0,1] neg_hi:[1,0]
	v_pk_fma_f32 v[68:69], v[68:69], v[102:103], v[104:105] op_sel_hi:[1,0,1]
	v_pk_mul_f32 v[104:105], v[62:63], v[108:109] op_sel:[0,1] op_sel_hi:[0,0] neg_lo:[0,1]
	v_pk_mul_f32 v[110:111], v[70:71], v[108:109] op_sel:[1,1] op_sel_hi:[0,1] neg_hi:[1,0]
	v_pk_fma_f32 v[104:105], v[26:27], v[108:109], v[104:105]
	v_pk_fma_f32 v[70:71], v[70:71], v[108:109], v[110:111] op_sel_hi:[1,0,1]
	v_pk_mul_f32 v[108:109], v[62:63], v[102:103] op_sel:[0,1] op_sel_hi:[0,0] neg_lo:[0,1]
	v_pk_fma_f32 v[102:103], v[26:27], v[102:103], v[108:109]
	v_pk_mul_f32 v[108:109], v[20:21], v[102:103] op_sel:[1,1] op_sel_hi:[0,1] neg_hi:[1,0]
	v_pk_fma_f32 v[20:21], v[20:21], v[102:103], v[108:109] op_sel_hi:[1,0,1]
	v_pk_mul_f32 v[108:109], v[62:63], v[104:105] op_sel:[0,1] op_sel_hi:[0,0] neg_lo:[0,1]
	v_pk_mul_f32 v[110:111], v[22:23], v[104:105] op_sel:[1,1] op_sel_hi:[0,1] neg_hi:[1,0]
	v_pk_fma_f32 v[108:109], v[26:27], v[104:105], v[108:109]
	v_pk_fma_f32 v[22:23], v[22:23], v[104:105], v[110:111] op_sel_hi:[1,0,1]
	v_pk_mul_f32 v[104:105], v[62:63], v[102:103] op_sel:[0,1] op_sel_hi:[0,0] neg_lo:[0,1]
	v_pk_fma_f32 v[102:103], v[26:27], v[102:103], v[104:105]
	v_pk_mul_f32 v[104:105], v[12:13], v[102:103] op_sel:[1,1] op_sel_hi:[0,1] neg_hi:[1,0]
	v_pk_fma_f32 v[12:13], v[12:13], v[102:103], v[104:105] op_sel_hi:[1,0,1]
	v_pk_mul_f32 v[104:105], v[62:63], v[108:109] op_sel:[0,1] op_sel_hi:[0,0] neg_lo:[0,1]
	v_pk_mul_f32 v[110:111], v[14:15], v[108:109] op_sel:[1,1] op_sel_hi:[0,1] neg_hi:[1,0]
	v_pk_fma_f32 v[104:105], v[26:27], v[108:109], v[104:105]
	v_pk_fma_f32 v[14:15], v[14:15], v[108:109], v[110:111] op_sel_hi:[1,0,1]
	v_pk_mul_f32 v[108:109], v[62:63], v[102:103] op_sel:[0,1] op_sel_hi:[0,0] neg_lo:[0,1]
	v_pk_fma_f32 v[102:103], v[26:27], v[102:103], v[108:109]
	v_pk_mul_f32 v[108:109], v[8:9], v[102:103] op_sel:[1,1] op_sel_hi:[0,1] neg_hi:[1,0]
	v_pk_fma_f32 v[8:9], v[8:9], v[102:103], v[108:109] op_sel_hi:[1,0,1]
	v_pk_mul_f32 v[108:109], v[62:63], v[104:105] op_sel:[0,1] op_sel_hi:[0,0] neg_lo:[0,1]
	v_pk_mul_f32 v[110:111], v[10:11], v[104:105] op_sel:[1,1] op_sel_hi:[0,1] neg_hi:[1,0]
	v_pk_fma_f32 v[108:109], v[26:27], v[104:105], v[108:109]
	v_pk_fma_f32 v[10:11], v[10:11], v[104:105], v[110:111] op_sel_hi:[1,0,1]
	v_pk_mul_f32 v[104:105], v[62:63], v[102:103] op_sel:[0,1] op_sel_hi:[0,0] neg_lo:[0,1]
	v_pk_fma_f32 v[26:27], v[26:27], v[102:103], v[104:105]
	s_nop 0
	v_pk_mul_f32 v[102:103], v[4:5], v[26:27] op_sel:[1,1] op_sel_hi:[0,1] neg_hi:[1,0]
	s_add_i32 s1, 16, 0x1e000
	v_pk_fma_f32 v[4:5], v[4:5], v[26:27], v[102:103] op_sel_hi:[1,0,1]
	s_nop 0
	s_nop 0
	v_pk_mul_f32 v[26:27], v[6:7], v[108:109] op_sel:[1,1] op_sel_hi:[0,1] neg_hi:[1,0]
	s_add_i32 s0, 16, 0x1f000
	v_pk_fma_f32 v[6:7], v[6:7], v[108:109], v[26:27] op_sel_hi:[1,0,1]
	v_lshrrev_b32_e32 v26, 5, v63
	v_bitop3_b32 v26, v26, v63, 15 bitop3:0x6c
	v_lshlrev_b32_e32 v26, 3, v26
	v_bfe_u32 v27, v63, 5, 4
	v_add_u32_e32 v62, 16, v26
	ds_write_b64 v62, v[2:3]
	v_bitop3_b32 v2, v27, v63, 16 bitop3:0x36
	v_lshlrev_b32_e32 v2, 3, v2
	v_add_u32_e32 v3, 16, v2
	ds_write_b64 v3, v[88:89] offset:4096
	ds_write_b64 v62, v[90:91] offset:8192
	ds_write_b64 v3, v[20:21] offset:12288
	ds_write_b64 v62, v[72:73] offset:16384
	ds_write_b64 v3, v[74:75] offset:20480
	ds_write_b64 v62, v[96:97] offset:24576
	ds_write_b64 v3, v[8:9] offset:28672
	ds_write_b64 v62, v[24:25] offset:32768
	ds_write_b64 v3, v[80:81] offset:36864
	ds_write_b64 v62, v[94:95] offset:40960
	ds_write_b64 v3, v[12:13] offset:45056
	ds_write_b64 v62, v[78:79] offset:49152
	ds_write_b64 v3, v[68:69] offset:53248
	ds_write_b64 v62, v[98:99] offset:57344
	ds_write_b64 v3, v[4:5] offset:61440
	v_add_u32_e32 v3, s79, v26
	ds_write_b64 v3, v[18:19]
	v_add_u32_e32 v3, s19, v2
	ds_write_b64 v3, v[92:93]
	v_add_u32_e32 v3, s18, v26
	ds_write_b64 v3, v[84:85]
	v_add_u32_e32 v3, s17, v2
	ds_write_b64 v3, v[22:23]
	v_add_u32_e32 v3, s13, v26
	ds_write_b64 v3, v[64:65]
	v_add_u32_e32 v3, s12, v2
	ds_write_b64 v3, v[76:77]
	v_add_u32_e32 v3, s11, v26
	ds_write_b64 v3, v[100:101]
	v_add_u32_e32 v3, s10, v2
	ds_write_b64 v3, v[10:11]
	v_add_u32_e32 v3, s9, v26
	ds_write_b64 v3, v[16:17]
	v_add_u32_e32 v3, s8, v2
	ds_write_b64 v3, v[82:83]
	v_add_u32_e32 v3, s7, v26
	ds_write_b64 v3, v[86:87]
	v_add_u32_e32 v3, s6, v2
	ds_write_b64 v3, v[14:15]
	v_add_u32_e32 v3, s5, v26
	ds_write_b64 v3, v[66:67]
	v_add_u32_e32 v3, s4, v2
	ds_write_b64 v3, v[70:71]
	v_add_u32_e32 v3, s1, v26
	v_add_u32_e32 v2, s0, v2
	v_mov_b32_e32 v21, v146
	ds_write_b64 v3, v[106:107]
	ds_write_b64 v2, v[6:7]
	s_waitcnt lgkmcnt(0)
	s_barrier
	s_lshl_b32 s42, s16, 14
	v_lshlrev_b32_e32 v2, 5, v21
	v_and_b32_e32 v4, 0xfffffe00, v2
	v_and_b32_e32 v20, 15, v21
	v_and_or_b32 v2, v21, 16, v4
	v_bitop3_b32 v4, v4, 16, v21 bitop3:0x34
	v_bitop3_b32 v72, v21, 8, 15 bitop3:0x6c
	v_lshl_add_u32 v26, v2, 3, 16
	v_lshlrev_b32_e32 v5, 3, v20
	v_lshl_add_u32 v126, v4, 3, 16
	v_lshlrev_b32_e32 v74, 3, v72
	v_add_u32_e32 v27, v26, v5
	v_add_u32_e32 v96, v126, v5
	v_add_u32_e32 v111, v26, v74
	v_add_u32_e32 v112, v126, v74
	ds_read_b64 v[2:3], v27
	ds_read_b64 v[4:5], v96
	v_bitop3_b32 v6, v21, 1, 15 bitop3:0x6c
	ds_read_b64 v[72:73], v111 offset:2048
	ds_read_b64 v[74:75], v112 offset:2048
	v_bitop3_b32 v76, v21, 9, 15 bitop3:0x6c
	v_lshlrev_b32_e32 v8, 3, v6
	v_lshlrev_b32_e32 v78, 3, v76
	v_add_u32_e32 v97, v26, v8
	v_add_u32_e32 v113, v26, v78
	ds_read_b64 v[6:7], v97 offset:256
	ds_read_b64 v[76:77], v113 offset:2304
	v_add_u32_e32 v98, v126, v8
	v_add_u32_e32 v114, v126, v78
	ds_read_b64 v[8:9], v98 offset:256
	ds_read_b64 v[78:79], v114 offset:2304
	s_waitcnt lgkmcnt(5)
	v_pk_add_f32 v[136:137], v[2:3], v[72:73]
	v_pk_add_f32 v[2:3], v[2:3], v[72:73] neg_lo:[0,1] neg_hi:[0,1]
	s_waitcnt lgkmcnt(4)
	v_pk_add_f32 v[72:73], v[4:5], v[74:75]
	v_pk_add_f32 v[4:5], v[4:5], v[74:75] neg_lo:[0,1] neg_hi:[0,1]
	v_bitop3_b32 v10, v21, 2, 15 bitop3:0x6c
	v_bitop3_b32 v80, v21, 10, 15 bitop3:0x6c
	v_lshlrev_b32_e32 v12, 3, v10
	v_lshlrev_b32_e32 v82, 3, v80
	v_pk_mul_f32 v[74:75], v[4:5], s[48:49] op_sel:[1,0] op_sel_hi:[0,0] neg_hi:[1,0]
	v_add_u32_e32 v99, v26, v12
	v_add_u32_e32 v115, v26, v82
	v_pk_fma_f32 v[4:5], v[4:5], s[44:45], v[74:75] op_sel_hi:[1,0,1]
	s_waitcnt lgkmcnt(2)
	v_pk_add_f32 v[74:75], v[6:7], v[76:77]
	v_pk_add_f32 v[6:7], v[6:7], v[76:77] neg_lo:[0,1] neg_hi:[0,1]
	ds_read_b64 v[10:11], v99 offset:512
	ds_read_b64 v[80:81], v115 offset:2560
	v_pk_mul_f32 v[76:77], v[6:7], s[54:55] op_sel:[1,0] op_sel_hi:[0,0] neg_hi:[1,0]
	v_add_u32_e32 v100, v126, v12
	v_bitop3_b32 v14, v21, 3, 15 bitop3:0x6c
	v_add_u32_e32 v116, v126, v82
	v_bitop3_b32 v84, v21, 11, 15 bitop3:0x6c
	v_pk_fma_f32 v[6:7], v[6:7], s[52:53], v[76:77] op_sel_hi:[1,0,1]
	s_waitcnt lgkmcnt(2)
	v_pk_add_f32 v[76:77], v[8:9], v[78:79]
	v_pk_add_f32 v[8:9], v[8:9], v[78:79] neg_lo:[0,1] neg_hi:[0,1]
	ds_read_b64 v[12:13], v100 offset:512
	v_lshlrev_b32_e32 v16, 3, v14
	ds_read_b64 v[82:83], v116 offset:2560
	v_lshlrev_b32_e32 v86, 3, v84
	v_add_u32_e32 v101, v26, v16
	v_add_u32_e32 v102, v126, v16
	v_add_u32_e32 v117, v26, v86
	v_add_u32_e32 v118, v126, v86
	v_pk_mul_f32 v[78:79], v[8:9], s[58:59] op_sel:[1,0] op_sel_hi:[0,0] neg_hi:[1,0]
	ds_read_b64 v[14:15], v101 offset:768
	ds_read_b64 v[16:17], v102 offset:768
	ds_read_b64 v[84:85], v117 offset:2816
	ds_read_b64 v[86:87], v118 offset:2816
	v_pk_fma_f32 v[8:9], v[8:9], s[56:57], v[78:79] op_sel_hi:[1,0,1]
	s_waitcnt lgkmcnt(6)
	v_pk_add_f32 v[78:79], v[10:11], v[80:81]
	v_pk_add_f32 v[10:11], v[10:11], v[80:81] neg_lo:[0,1] neg_hi:[0,1]
	v_bitop3_b32 v18, v21, 4, 15 bitop3:0x6c
	v_pk_mul_f32 v[80:81], v[10:11], s[60:61] op_sel:[1,0] op_sel_hi:[0,0] neg_hi:[1,0]
	v_bitop3_b32 v88, v21, 12, 15 bitop3:0x6c
	v_pk_fma_f32 v[10:11], v[10:11], s[60:61], v[80:81] op_sel_hi:[1,0,1]
	s_waitcnt lgkmcnt(4)
	v_pk_add_f32 v[80:81], v[12:13], v[82:83]
	v_pk_add_f32 v[12:13], v[12:13], v[82:83] neg_lo:[0,1] neg_hi:[0,1]
	v_lshlrev_b32_e32 v22, 3, v18
	v_lshlrev_b32_e32 v90, 3, v88
	v_pk_mul_f32 v[82:83], v[12:13], s[56:57] op_sel:[1,0] op_sel_hi:[0,0] neg_hi:[1,0]
	v_add_u32_e32 v103, v26, v22
	v_add_u32_e32 v119, v26, v90
	v_pk_fma_f32 v[12:13], v[12:13], s[58:59], v[82:83] op_sel_hi:[1,0,1]
	s_waitcnt lgkmcnt(1)
	v_pk_add_f32 v[82:83], v[14:15], v[84:85]
	v_pk_add_f32 v[14:15], v[14:15], v[84:85] neg_lo:[0,1] neg_hi:[0,1]
	ds_read_b64 v[18:19], v103 offset:1024
	v_add_u32_e32 v104, v126, v22
	v_bitop3_b32 v24, v21, 5, 15 bitop3:0x6c
	ds_read_b64 v[88:89], v119 offset:3072
	v_add_u32_e32 v120, v126, v90
	v_bitop3_b32 v92, v21, 13, 15 bitop3:0x6c
	ds_read_b64 v[22:23], v104 offset:1024
	v_lshlrev_b32_e32 v62, 3, v24
	ds_read_b64 v[90:91], v120 offset:3072
	v_lshlrev_b32_e32 v94, 3, v92
	v_pk_mul_f32 v[84:85], v[14:15], s[52:53] op_sel:[1,0] op_sel_hi:[0,0] neg_hi:[1,0]
	v_add_u32_e32 v105, v26, v62
	v_add_u32_e32 v121, v26, v94
	v_pk_fma_f32 v[14:15], v[14:15], s[54:55], v[84:85] op_sel_hi:[1,0,1]
	s_waitcnt lgkmcnt(4)
	v_pk_add_f32 v[84:85], v[16:17], v[86:87]
	v_pk_add_f32 v[16:17], v[16:17], v[86:87] neg_lo:[0,1] neg_hi:[0,1]
	ds_read_b64 v[24:25], v105 offset:1280
	ds_read_b64 v[92:93], v121 offset:3328
	v_add_u32_e32 v106, v126, v62
	v_bitop3_b32 v64, v21, 6, 15 bitop3:0x6c
	v_add_u32_e32 v122, v126, v94
	v_bitop3_b32 v123, v21, 14, 15 bitop3:0x6c
	v_pk_mul_f32 v[86:87], v[16:17], s[44:45] op_sel:[1,0] op_sel_hi:[0,0] neg_hi:[1,0]
	ds_read_b64 v[62:63], v106 offset:1280
	v_lshlrev_b32_e32 v66, 3, v64
	ds_read_b64 v[94:95], v122 offset:3328
	v_lshlrev_b32_e32 v124, 3, v123
	v_pk_fma_f32 v[16:17], v[16:17], s[48:49], v[86:87] op_sel_hi:[1,0,1]
	s_waitcnt lgkmcnt(6)
	v_pk_add_f32 v[86:87], v[18:19], v[88:89]
	v_pk_add_f32 v[18:19], v[18:19], v[88:89] neg_lo:[0,1] neg_hi:[0,1]
	v_add_u32_e32 v107, v26, v66
	v_add_u32_e32 v123, v26, v124
	v_xor_b32_e32 v89, 0x80000000, v18
	v_mov_b32_e32 v88, v19
	s_waitcnt lgkmcnt(4)
	v_pk_add_f32 v[18:19], v[22:23], v[90:91]
	v_pk_add_f32 v[22:23], v[22:23], v[90:91] neg_lo:[0,1] neg_hi:[0,1]
	ds_read_b64 v[64:65], v107 offset:1536
	ds_read_b64 v[128:129], v123 offset:3584
	v_pk_mul_f32 v[90:91], v[22:23], s[48:49] op_sel_hi:[1,0]
	v_xor_b32_e32 v139, 0x80000000, v22
	v_mov_b32_e32 v138, v23
	v_add_u32_e32 v108, v126, v66
	v_bitop3_b32 v68, v21, 7, 15 bitop3:0x6c
	v_add_u32_e32 v124, v126, v124
	v_bitop3_b32 v21, v21, 15, v21 bitop3:0xc
	v_pk_fma_f32 v[22:23], v[138:139], s[44:45], v[90:91] op_sel_hi:[1,0,1] neg_lo:[0,0,1] neg_hi:[0,0,1]
	s_waitcnt lgkmcnt(4)
	v_pk_add_f32 v[90:91], v[24:25], v[92:93]
	v_pk_add_f32 v[24:25], v[24:25], v[92:93] neg_lo:[0,1] neg_hi:[0,1]
	ds_read_b64 v[66:67], v108 offset:1536
	v_lshlrev_b32_e32 v70, 3, v68
	ds_read_b64 v[130:131], v124 offset:3584
	v_lshlrev_b32_e32 v21, 3, v21
	v_pk_mul_f32 v[92:93], v[24:25], s[54:55] op_sel_hi:[1,0]
	v_xor_b32_e32 v139, 0x80000000, v24
	v_mov_b32_e32 v138, v25
	v_add_u32_e32 v109, v26, v70
	v_add_u32_e32 v125, v26, v21
	v_pk_fma_f32 v[24:25], v[138:139], s[52:53], v[92:93] op_sel_hi:[1,0,1] neg_lo:[0,0,1] neg_hi:[0,0,1]
	s_waitcnt lgkmcnt(4)
	v_pk_add_f32 v[92:93], v[62:63], v[94:95]
	v_pk_add_f32 v[62:63], v[62:63], v[94:95] neg_lo:[0,1] neg_hi:[0,1]
	ds_read_b64 v[68:69], v109 offset:1792
	v_add_u32_e32 v110, v126, v70
	ds_read_b64 v[132:133], v125 offset:3840
	v_add_u32_e32 v126, v126, v21
	v_pk_mul_f32 v[94:95], v[62:63], s[58:59] op_sel_hi:[1,0]
	v_xor_b32_e32 v139, 0x80000000, v62
	v_mov_b32_e32 v138, v63
	ds_read_b64 v[70:71], v110 offset:1792
	ds_read_b64 v[134:135], v126 offset:3840
	v_pk_fma_f32 v[62:63], v[138:139], s[56:57], v[94:95] op_sel_hi:[1,0,1] neg_lo:[0,0,1] neg_hi:[0,0,1]
	s_waitcnt lgkmcnt(6)
	v_pk_add_f32 v[94:95], v[64:65], v[128:129]
	v_pk_add_f32 v[64:65], v[64:65], v[128:129] neg_lo:[0,1] neg_hi:[0,1]
	v_lshl_add_u64 v[0:1], s[42:43], 2, v[28:29]
	v_pk_mul_f32 v[128:129], v[64:65], s[60:61] op_sel_hi:[1,0]
	v_xor_b32_e32 v139, 0x80000000, v64
	v_mov_b32_e32 v138, v65
	v_pk_fma_f32 v[64:65], v[138:139], s[60:61], v[128:129] op_sel_hi:[1,0,1] neg_lo:[0,0,1] neg_hi:[0,0,1]
	s_waitcnt lgkmcnt(4)
	v_pk_add_f32 v[128:129], v[66:67], v[130:131]
	v_pk_add_f32 v[66:67], v[66:67], v[130:131] neg_lo:[0,1] neg_hi:[0,1]
	v_cvt_f32_i32_e32 v20, v20
	v_pk_mul_f32 v[130:131], v[66:67], s[56:57] op_sel_hi:[1,0]
	v_xor_b32_e32 v139, 0x80000000, v66
	v_mov_b32_e32 v138, v67
	v_pk_fma_f32 v[66:67], v[138:139], s[58:59], v[130:131] op_sel_hi:[1,0,1] neg_lo:[0,0,1] neg_hi:[0,0,1]
	s_waitcnt lgkmcnt(2)
	v_pk_add_f32 v[130:131], v[68:69], v[132:133]
	v_pk_add_f32 v[68:69], v[68:69], v[132:133] neg_lo:[0,1] neg_hi:[0,1]
	v_mul_f32_e32 v21, 0x3b000000, v20
	v_pk_mul_f32 v[132:133], v[68:69], s[52:53] op_sel_hi:[1,0]
	v_xor_b32_e32 v139, 0x80000000, v68
	v_mov_b32_e32 v138, v69
	v_pk_fma_f32 v[68:69], v[138:139], s[54:55], v[132:133] op_sel_hi:[1,0,1] neg_lo:[0,0,1] neg_hi:[0,0,1]
	s_waitcnt lgkmcnt(0)
	v_pk_add_f32 v[132:133], v[70:71], v[134:135]
	v_pk_add_f32 v[70:71], v[70:71], v[134:135] neg_lo:[0,1] neg_hi:[0,1]
	v_cos_f32_e32 v20, v21
	v_pk_mul_f32 v[134:135], v[70:71], s[44:45] op_sel_hi:[1,0]
	v_xor_b32_e32 v139, 0x80000000, v70
	v_mov_b32_e32 v138, v71
	v_pk_fma_f32 v[70:71], v[138:139], s[48:49], v[134:135] op_sel_hi:[1,0,1] neg_lo:[0,0,1] neg_hi:[0,0,1]
	v_pk_add_f32 v[134:135], v[136:137], v[86:87]
	v_pk_add_f32 v[86:87], v[136:137], v[86:87] neg_lo:[0,1] neg_hi:[0,1]
	v_pk_add_f32 v[136:137], v[72:73], v[18:19]
	v_pk_add_f32 v[18:19], v[72:73], v[18:19] neg_lo:[0,1] neg_hi:[0,1]
	v_sin_f32_e32 v21, v21
	s_nop 0
	s_nop 0
	v_pk_mul_f32 v[72:73], v[18:19], s[54:55] op_sel:[1,0] op_sel_hi:[0,0] neg_hi:[1,0]
	v_add_f32_e32 v26, v20, v20
	v_pk_fma_f32 v[18:19], v[18:19], s[52:53], v[72:73] op_sel_hi:[1,0,1]
	v_pk_add_f32 v[72:73], v[74:75], v[90:91]
	v_pk_add_f32 v[74:75], v[74:75], v[90:91] neg_lo:[0,1] neg_hi:[0,1]
	v_mul_f32_e32 v26, v21, v26
	s_nop 0
	s_nop 0
	v_pk_mul_f32 v[90:91], v[74:75], s[60:61] op_sel:[1,0] op_sel_hi:[0,0] neg_hi:[1,0]
	s_lshl_b32 s42, s16, 9
	v_pk_fma_f32 v[74:75], v[74:75], s[60:61], v[90:91] op_sel_hi:[1,0,1]
	v_pk_add_f32 v[90:91], v[76:77], v[92:93]
	v_pk_add_f32 v[76:77], v[76:77], v[92:93] neg_lo:[0,1] neg_hi:[0,1]
	s_mov_b64 s[74:75], -1
	s_nop 0
	s_nop 0
	v_pk_mul_f32 v[92:93], v[76:77], s[52:53] op_sel:[1,0] op_sel_hi:[0,0] neg_hi:[1,0]
	s_nop 0
	v_pk_fma_f32 v[76:77], v[76:77], s[54:55], v[92:93] op_sel_hi:[1,0,1]
	v_pk_add_f32 v[92:93], v[78:79], v[94:95]
	v_pk_add_f32 v[78:79], v[78:79], v[94:95] neg_lo:[0,1] neg_hi:[0,1]
	v_xor_b32_e32 v95, 0x80000000, v78
	v_mov_b32_e32 v94, v79
	v_pk_add_f32 v[78:79], v[80:81], v[128:129]
	v_pk_add_f32 v[80:81], v[80:81], v[128:129] neg_lo:[0,1] neg_hi:[0,1]
	v_pk_mul_f32 v[128:129], v[80:81], s[54:55] op_sel_hi:[1,0]
	v_xor_b32_e32 v139, 0x80000000, v80
	v_mov_b32_e32 v138, v81
	v_pk_fma_f32 v[80:81], v[138:139], s[52:53], v[128:129] op_sel_hi:[1,0,1] neg_lo:[0,0,1] neg_hi:[0,0,1]
	v_pk_add_f32 v[128:129], v[82:83], v[130:131]
	v_pk_add_f32 v[82:83], v[82:83], v[130:131] neg_lo:[0,1] neg_hi:[0,1]
	v_pk_mul_f32 v[130:131], v[82:83], s[60:61] op_sel_hi:[1,0]
	v_xor_b32_e32 v139, 0x80000000, v82
	v_mov_b32_e32 v138, v83
	v_pk_fma_f32 v[82:83], v[138:139], s[60:61], v[130:131] op_sel_hi:[1,0,1] neg_lo:[0,0,1] neg_hi:[0,0,1]
	v_pk_add_f32 v[130:131], v[84:85], v[132:133]
	v_pk_add_f32 v[84:85], v[84:85], v[132:133] neg_lo:[0,1] neg_hi:[0,1]
	v_pk_mul_f32 v[132:133], v[84:85], s[52:53] op_sel_hi:[1,0]
	v_xor_b32_e32 v139, 0x80000000, v84
	v_mov_b32_e32 v138, v85
	v_pk_fma_f32 v[84:85], v[138:139], s[54:55], v[132:133] op_sel_hi:[1,0,1] neg_lo:[0,0,1] neg_hi:[0,0,1]
	v_pk_add_f32 v[132:133], v[2:3], v[88:89]
	v_pk_add_f32 v[2:3], v[2:3], v[88:89] neg_lo:[0,1] neg_hi:[0,1]
	v_pk_add_f32 v[88:89], v[4:5], v[22:23]
	v_pk_add_f32 v[4:5], v[4:5], v[22:23] neg_lo:[0,1] neg_hi:[0,1]
	v_pk_mul_f32 v[22:23], v[4:5], s[54:55] op_sel:[1,0] op_sel_hi:[0,0] neg_hi:[1,0]
	v_pk_fma_f32 v[4:5], v[4:5], s[52:53], v[22:23] op_sel_hi:[1,0,1]
	v_pk_add_f32 v[22:23], v[6:7], v[24:25]
	v_pk_add_f32 v[6:7], v[6:7], v[24:25] neg_lo:[0,1] neg_hi:[0,1]
	v_pk_mul_f32 v[24:25], v[6:7], s[60:61] op_sel:[1,0] op_sel_hi:[0,0] neg_hi:[1,0]
	v_pk_fma_f32 v[6:7], v[6:7], s[60:61], v[24:25] op_sel_hi:[1,0,1]
	v_pk_add_f32 v[24:25], v[8:9], v[62:63]
	v_pk_add_f32 v[8:9], v[8:9], v[62:63] neg_lo:[0,1] neg_hi:[0,1]
	v_pk_mul_f32 v[62:63], v[8:9], s[52:53] op_sel:[1,0] op_sel_hi:[0,0] neg_hi:[1,0]
	v_pk_fma_f32 v[8:9], v[8:9], s[54:55], v[62:63] op_sel_hi:[1,0,1]
	v_pk_add_f32 v[62:63], v[10:11], v[64:65]
	v_pk_add_f32 v[10:11], v[10:11], v[64:65] neg_lo:[0,1] neg_hi:[0,1]
	v_xor_b32_e32 v65, 0x80000000, v10
	v_mov_b32_e32 v64, v11
	v_pk_add_f32 v[10:11], v[12:13], v[66:67]
	v_pk_add_f32 v[12:13], v[12:13], v[66:67] neg_lo:[0,1] neg_hi:[0,1]
	v_pk_mul_f32 v[66:67], v[12:13], s[54:55] op_sel_hi:[1,0]
	v_xor_b32_e32 v139, 0x80000000, v12
	v_mov_b32_e32 v138, v13
	v_pk_fma_f32 v[12:13], v[138:139], s[52:53], v[66:67] op_sel_hi:[1,0,1] neg_lo:[0,0,1] neg_hi:[0,0,1]
	v_pk_add_f32 v[66:67], v[14:15], v[68:69]
	v_pk_add_f32 v[14:15], v[14:15], v[68:69] neg_lo:[0,1] neg_hi:[0,1]
	v_pk_mul_f32 v[68:69], v[14:15], s[60:61] op_sel_hi:[1,0]
	v_xor_b32_e32 v139, 0x80000000, v14
	v_mov_b32_e32 v138, v15
	v_pk_fma_f32 v[14:15], v[138:139], s[60:61], v[68:69] op_sel_hi:[1,0,1] neg_lo:[0,0,1] neg_hi:[0,0,1]
	v_pk_add_f32 v[68:69], v[16:17], v[70:71]
	v_pk_add_f32 v[16:17], v[16:17], v[70:71] neg_lo:[0,1] neg_hi:[0,1]
	v_pk_mul_f32 v[70:71], v[16:17], s[52:53] op_sel_hi:[1,0]
	v_xor_b32_e32 v139, 0x80000000, v16
	v_mov_b32_e32 v138, v17
	v_pk_fma_f32 v[16:17], v[138:139], s[54:55], v[70:71] op_sel_hi:[1,0,1] neg_lo:[0,0,1] neg_hi:[0,0,1]
	v_pk_add_f32 v[70:71], v[134:135], v[92:93]
	v_pk_add_f32 v[92:93], v[134:135], v[92:93] neg_lo:[0,1] neg_hi:[0,1]
	v_pk_add_f32 v[134:135], v[136:137], v[78:79]
	v_pk_add_f32 v[78:79], v[136:137], v[78:79] neg_lo:[0,1] neg_hi:[0,1]
	v_pk_mul_f32 v[136:137], v[78:79], s[60:61] op_sel:[1,0] op_sel_hi:[0,0] neg_hi:[1,0]
	v_pk_fma_f32 v[78:79], v[78:79], s[60:61], v[136:137] op_sel_hi:[1,0,1]
	v_pk_add_f32 v[136:137], v[72:73], v[128:129]
	v_pk_add_f32 v[72:73], v[72:73], v[128:129] neg_lo:[0,1] neg_hi:[0,1]
	v_xor_b32_e32 v129, 0x80000000, v72
	v_mov_b32_e32 v128, v73
	v_pk_add_f32 v[72:73], v[90:91], v[130:131]
	v_pk_add_f32 v[90:91], v[90:91], v[130:131] neg_lo:[0,1] neg_hi:[0,1]
	v_pk_mul_f32 v[130:131], v[90:91], s[60:61] op_sel_hi:[1,0]
	v_xor_b32_e32 v139, 0x80000000, v90
	v_mov_b32_e32 v138, v91
	v_pk_fma_f32 v[90:91], v[138:139], s[60:61], v[130:131] op_sel_hi:[1,0,1] neg_lo:[0,0,1] neg_hi:[0,0,1]
	v_pk_add_f32 v[130:131], v[86:87], v[94:95]
	v_pk_add_f32 v[86:87], v[86:87], v[94:95] neg_lo:[0,1] neg_hi:[0,1]
	v_pk_add_f32 v[94:95], v[18:19], v[80:81]
	v_pk_add_f32 v[18:19], v[18:19], v[80:81] neg_lo:[0,1] neg_hi:[0,1]
	v_pk_mul_f32 v[80:81], v[18:19], s[60:61] op_sel:[1,0] op_sel_hi:[0,0] neg_hi:[1,0]
	v_pk_fma_f32 v[18:19], v[18:19], s[60:61], v[80:81] op_sel_hi:[1,0,1]
	v_pk_add_f32 v[80:81], v[74:75], v[82:83]
	v_pk_add_f32 v[74:75], v[74:75], v[82:83] neg_lo:[0,1] neg_hi:[0,1]
	v_xor_b32_e32 v83, 0x80000000, v74
	v_mov_b32_e32 v82, v75
	v_pk_add_f32 v[74:75], v[76:77], v[84:85]
	v_pk_add_f32 v[76:77], v[76:77], v[84:85] neg_lo:[0,1] neg_hi:[0,1]
	v_pk_mul_f32 v[84:85], v[76:77], s[60:61] op_sel_hi:[1,0]
	v_xor_b32_e32 v139, 0x80000000, v76
	v_mov_b32_e32 v138, v77
	v_pk_fma_f32 v[76:77], v[138:139], s[60:61], v[84:85] op_sel_hi:[1,0,1] neg_lo:[0,0,1] neg_hi:[0,0,1]
	v_pk_add_f32 v[84:85], v[132:133], v[62:63]
	v_pk_add_f32 v[62:63], v[132:133], v[62:63] neg_lo:[0,1] neg_hi:[0,1]
	v_pk_add_f32 v[132:133], v[88:89], v[10:11]
	v_pk_add_f32 v[10:11], v[88:89], v[10:11] neg_lo:[0,1] neg_hi:[0,1]
	v_pk_mul_f32 v[88:89], v[10:11], s[60:61] op_sel:[1,0] op_sel_hi:[0,0] neg_hi:[1,0]
	v_pk_fma_f32 v[10:11], v[10:11], s[60:61], v[88:89] op_sel_hi:[1,0,1]
	v_pk_add_f32 v[88:89], v[22:23], v[66:67]
	v_pk_add_f32 v[22:23], v[22:23], v[66:67] neg_lo:[0,1] neg_hi:[0,1]
	v_xor_b32_e32 v67, 0x80000000, v22
	v_mov_b32_e32 v66, v23
	v_pk_add_f32 v[22:23], v[24:25], v[68:69]
	v_pk_add_f32 v[24:25], v[24:25], v[68:69] neg_lo:[0,1] neg_hi:[0,1]
	v_pk_mul_f32 v[68:69], v[24:25], s[60:61] op_sel_hi:[1,0]
	v_xor_b32_e32 v139, 0x80000000, v24
	v_mov_b32_e32 v138, v25
	v_pk_fma_f32 v[24:25], v[138:139], s[60:61], v[68:69] op_sel_hi:[1,0,1] neg_lo:[0,0,1] neg_hi:[0,0,1]
	v_pk_add_f32 v[68:69], v[2:3], v[64:65]
	v_pk_add_f32 v[2:3], v[2:3], v[64:65] neg_lo:[0,1] neg_hi:[0,1]
	v_pk_add_f32 v[64:65], v[4:5], v[12:13]
	v_pk_add_f32 v[4:5], v[4:5], v[12:13] neg_lo:[0,1] neg_hi:[0,1]
	v_pk_mul_f32 v[12:13], v[4:5], s[60:61] op_sel:[1,0] op_sel_hi:[0,0] neg_hi:[1,0]
	v_pk_fma_f32 v[4:5], v[4:5], s[60:61], v[12:13] op_sel_hi:[1,0,1]
	v_pk_add_f32 v[12:13], v[6:7], v[14:15]
	v_pk_add_f32 v[6:7], v[6:7], v[14:15] neg_lo:[0,1] neg_hi:[0,1]
	v_pk_add_f32 v[140:141], v[68:69], v[12:13]
	v_xor_b32_e32 v15, 0x80000000, v6
	v_mov_b32_e32 v14, v7
	v_pk_add_f32 v[6:7], v[8:9], v[16:17]
	v_pk_add_f32 v[8:9], v[8:9], v[16:17] neg_lo:[0,1] neg_hi:[0,1]
	v_pk_add_f32 v[142:143], v[64:65], v[6:7]
	v_pk_mul_f32 v[16:17], v[8:9], s[60:61] op_sel_hi:[1,0]
	v_pk_fma_f32 v[8:9], v[8:9], s[60:61], v[16:17] op_sel:[1,0,0] op_sel_hi:[0,0,1] neg_lo:[0,0,1] neg_hi:[1,0,1]
	v_pk_add_f32 v[16:17], v[70:71], v[136:137]
	v_pk_add_f32 v[70:71], v[70:71], v[136:137] neg_lo:[0,1] neg_hi:[0,1]
	v_pk_add_f32 v[136:137], v[134:135], v[72:73]
	v_pk_add_f32 v[72:73], v[134:135], v[72:73] neg_lo:[0,1] neg_hi:[0,1]
	v_pk_add_f32 v[138:139], v[84:85], v[88:89] neg_lo:[0,1] neg_hi:[0,1]
	v_xor_b32_e32 v135, 0x80000000, v72
	v_mov_b32_e32 v134, v73
	v_pk_add_f32 v[72:73], v[92:93], v[128:129]
	v_pk_add_f32 v[92:93], v[92:93], v[128:129] neg_lo:[0,1] neg_hi:[0,1]
	v_pk_add_f32 v[128:129], v[78:79], v[90:91]
	v_pk_add_f32 v[78:79], v[78:79], v[90:91] neg_lo:[0,1] neg_hi:[0,1]
	v_pk_add_f32 v[6:7], v[64:65], v[6:7] neg_lo:[0,1] neg_hi:[0,1]
	v_xor_b32_e32 v91, 0x80000000, v78
	v_mov_b32_e32 v90, v79
	v_pk_add_f32 v[78:79], v[130:131], v[80:81]
	v_pk_add_f32 v[130:131], v[130:131], v[80:81] neg_lo:[0,1] neg_hi:[0,1]
	v_pk_add_f32 v[80:81], v[94:95], v[74:75]
	v_pk_add_f32 v[74:75], v[94:95], v[74:75] neg_lo:[0,1] neg_hi:[0,1]
	v_xor_b32_e32 v149, 0x80000000, v6
	v_xor_b32_e32 v95, 0x80000000, v74
	v_mov_b32_e32 v94, v75
	v_pk_add_f32 v[74:75], v[86:87], v[82:83]
	v_pk_add_f32 v[82:83], v[86:87], v[82:83] neg_lo:[0,1] neg_hi:[0,1]
	v_pk_add_f32 v[86:87], v[18:19], v[76:77]
	v_pk_add_f32 v[18:19], v[18:19], v[76:77] neg_lo:[0,1] neg_hi:[0,1]
	v_mov_b32_e32 v148, v7
	v_xor_b32_e32 v77, 0x80000000, v18
	v_mov_b32_e32 v76, v19
	v_pk_add_f32 v[18:19], v[84:85], v[88:89]
	v_pk_add_f32 v[88:89], v[132:133], v[22:23]
	v_pk_add_f32 v[22:23], v[132:133], v[22:23] neg_lo:[0,1] neg_hi:[0,1]
	v_pk_add_f32 v[6:7], v[2:3], v[14:15]
	v_xor_b32_e32 v133, 0x80000000, v22
	v_mov_b32_e32 v132, v23
	v_pk_add_f32 v[22:23], v[62:63], v[66:67]
	v_pk_add_f32 v[62:63], v[62:63], v[66:67] neg_lo:[0,1] neg_hi:[0,1]
	v_pk_add_f32 v[66:67], v[10:11], v[24:25]
	v_pk_add_f32 v[10:11], v[10:11], v[24:25] neg_lo:[0,1] neg_hi:[0,1]
	v_pk_add_f32 v[154:155], v[2:3], v[14:15] neg_lo:[0,1] neg_hi:[0,1]
	v_pk_add_f32 v[2:3], v[4:5], v[8:9] neg_lo:[0,1] neg_hi:[0,1]
	v_pk_add_f32 v[68:69], v[68:69], v[12:13] neg_lo:[0,1] neg_hi:[0,1]
	v_pk_add_f32 v[156:157], v[4:5], v[8:9]
	v_xor_b32_e32 v159, 0x80000000, v2
	v_mov_b32_e32 v158, v3
	v_pk_add_f32 v[2:3], v[16:17], v[136:137]
	v_pk_add_f32 v[84:85], v[16:17], v[136:137] neg_lo:[0,1] neg_hi:[0,1]
	v_pk_add_f32 v[136:137], v[70:71], v[134:135]
	v_pk_add_f32 v[16:17], v[70:71], v[134:135] neg_lo:[0,1] neg_hi:[0,1]
	v_pk_add_f32 v[134:135], v[72:73], v[128:129]
	v_pk_add_f32 v[70:71], v[72:73], v[128:129] neg_lo:[0,1] neg_hi:[0,1]
	v_pk_add_f32 v[128:129], v[92:93], v[90:91]
	v_pk_add_f32 v[8:9], v[92:93], v[90:91] neg_lo:[0,1] neg_hi:[0,1]
	v_pk_add_f32 v[72:73], v[78:79], v[80:81]
	v_pk_add_f32 v[80:81], v[78:79], v[80:81] neg_lo:[0,1] neg_hi:[0,1]
	v_pk_add_f32 v[92:93], v[130:131], v[94:95]
	v_pk_add_f32 v[12:13], v[130:131], v[94:95] neg_lo:[0,1] neg_hi:[0,1]
	v_pk_add_f32 v[78:79], v[74:75], v[86:87]
	v_pk_add_f32 v[64:65], v[74:75], v[86:87] neg_lo:[0,1] neg_hi:[0,1]
	v_pk_add_f32 v[130:131], v[82:83], v[76:77]
	v_pk_add_f32 v[4:5], v[82:83], v[76:77] neg_lo:[0,1] neg_hi:[0,1]
	v_pk_add_f32 v[76:77], v[18:19], v[88:89]
	v_pk_add_f32 v[88:89], v[18:19], v[88:89] neg_lo:[0,1] neg_hi:[0,1]
	v_pk_add_f32 v[86:87], v[138:139], v[132:133]
	v_pk_add_f32 v[18:19], v[138:139], v[132:133] neg_lo:[0,1] neg_hi:[0,1]
	v_pk_add_f32 v[132:133], v[62:63], v[10:11] op_sel:[0,1] op_sel_hi:[1,0] neg_hi:[0,1]
	v_pk_add_f32 v[10:11], v[62:63], v[10:11] op_sel:[0,1] op_sel_hi:[1,0] neg_lo:[0,1]
	v_pk_mul_f32 v[24:25], v[20:21], v[20:21]
	v_pk_add_f32 v[24:25], v[24:25], v[24:25] op_sel:[0,1] op_sel_hi:[0,1] neg_lo:[0,1] neg_hi:[0,1]
	v_pk_mul_f32 v[62:63], v[20:21], v[26:27] op_sel:[1,0] op_sel_hi:[0,0] neg_lo:[1,0]
	v_pk_add_f32 v[90:91], v[22:23], v[66:67]
	v_pk_add_f32 v[74:75], v[22:23], v[66:67] neg_lo:[0,1] neg_hi:[0,1]
	v_pk_add_f32 v[22:23], v[140:141], v[142:143]
	v_pk_add_f32 v[82:83], v[140:141], v[142:143] neg_lo:[0,1] neg_hi:[0,1]
	v_pk_add_f32 v[138:139], v[68:69], v[148:149]
	v_pk_add_f32 v[14:15], v[68:69], v[148:149] neg_lo:[0,1] neg_hi:[0,1]
	v_pk_fma_f32 v[68:69], v[20:21], v[24:25], v[62:63]
	v_mov_b32_e32 v142, v21
	v_pk_mul_f32 v[62:63], v[142:143], v[76:77] op_sel:[0,1] op_sel_hi:[0,0] neg_hi:[0,1]
	v_pk_fma_f32 v[20:21], v[20:21], v[76:77], v[62:63] op_sel_hi:[0,1,1]
	v_pk_mul_f32 v[62:63], v[26:27], s[46:47] op_sel_hi:[0,1]
	v_pk_fma_f32 v[76:77], v[24:25], s[40:41], v[62:63]
	v_pk_mul_f32 v[62:63], v[76:77], v[72:73] op_sel:[1,1] op_sel_hi:[1,0] neg_hi:[0,1]
	v_pk_add_f32 v[94:95], v[6:7], v[156:157]
	v_pk_fma_f32 v[62:63], v[72:73], v[76:77], v[62:63] op_sel_hi:[1,0,1]
	v_pk_mul_f32 v[72:73], v[26:27], v[68:69] op_sel:[0,1] op_sel_hi:[0,0] neg_lo:[0,1]
	v_pk_fma_f32 v[142:143], v[24:25], v[68:69], v[72:73]
	v_pk_mul_f32 v[72:73], v[68:69], v[22:23] op_sel:[1,1] op_sel_hi:[1,0] neg_hi:[0,1]
	v_pk_add_f32 v[140:141], v[154:155], v[158:159]
	v_pk_fma_f32 v[22:23], v[68:69], v[22:23], v[72:73] op_sel_hi:[0,1,1]
	v_pk_mul_f32 v[68:69], v[26:27], v[76:77] op_sel:[0,1] op_sel_hi:[0,0] neg_lo:[0,1]
	v_pk_fma_f32 v[76:77], v[24:25], v[76:77], v[68:69]
	v_pk_mul_f32 v[68:69], v[134:135], v[76:77] op_sel:[1,1] op_sel_hi:[0,1] neg_hi:[1,0]
	v_pk_add_f32 v[66:67], v[6:7], v[156:157] neg_lo:[0,1] neg_hi:[0,1]
	v_pk_fma_f32 v[72:73], v[134:135], v[76:77], v[68:69] op_sel_hi:[1,0,1]
	v_pk_mul_f32 v[68:69], v[26:27], v[142:143] op_sel:[0,1] op_sel_hi:[0,0] neg_lo:[0,1]
	v_pk_fma_f32 v[134:135], v[24:25], v[142:143], v[68:69]
	v_pk_mul_f32 v[68:69], v[142:143], v[90:91] op_sel:[1,1] op_sel_hi:[1,0] neg_hi:[0,1]
	v_pk_add_f32 v[6:7], v[154:155], v[158:159] neg_lo:[0,1] neg_hi:[0,1]
	v_pk_fma_f32 v[68:69], v[90:91], v[142:143], v[68:69] op_sel_hi:[1,0,1]
	v_pk_mul_f32 v[90:91], v[26:27], v[76:77] op_sel:[0,1] op_sel_hi:[0,0] neg_lo:[0,1]
	v_pk_fma_f32 v[90:91], v[24:25], v[76:77], v[90:91]
	v_pk_mul_f32 v[76:77], v[78:79], v[90:91] op_sel:[1,1] op_sel_hi:[0,1] neg_hi:[1,0]
	v_pk_fma_f32 v[78:79], v[78:79], v[90:91], v[76:77] op_sel_hi:[1,0,1]
	v_pk_mul_f32 v[76:77], v[26:27], v[134:135] op_sel:[0,1] op_sel_hi:[0,0] neg_lo:[0,1]
	v_pk_fma_f32 v[142:143], v[24:25], v[134:135], v[76:77]
	v_pk_mul_f32 v[76:77], v[134:135], v[94:95] op_sel:[1,1] op_sel_hi:[1,0] neg_hi:[0,1]
	v_pk_fma_f32 v[76:77], v[94:95], v[134:135], v[76:77] op_sel_hi:[1,0,1]
	v_pk_mul_f32 v[94:95], v[26:27], v[90:91] op_sel:[0,1] op_sel_hi:[0,0] neg_lo:[0,1]
	v_pk_fma_f32 v[94:95], v[24:25], v[90:91], v[94:95]
	v_pk_mul_f32 v[90:91], v[136:137], v[94:95] op_sel:[1,1] op_sel_hi:[0,1] neg_hi:[1,0]
	v_xor_b32_e32 v134, 0x80000000, v143
	v_pk_fma_f32 v[90:91], v[136:137], v[94:95], v[90:91] op_sel_hi:[1,0,1]
	v_pk_mul_f32 v[136:137], v[86:87], v[142:143] op_sel:[1,1] op_sel_hi:[0,1] neg_hi:[1,0]
	v_mov_b32_e32 v135, v142
	v_pk_fma_f32 v[86:87], v[86:87], v[142:143], v[136:137] op_sel_hi:[1,0,1]
	v_pk_mul_f32 v[136:137], v[26:27], v[94:95] op_sel:[0,1] op_sel_hi:[0,0] neg_lo:[0,1]
	v_pk_mul_f32 v[134:135], v[26:27], v[134:135] op_sel_hi:[0,1]
	v_pk_fma_f32 v[136:137], v[24:25], v[94:95], v[136:137]
	v_pk_fma_f32 v[134:135], v[24:25], v[142:143], v[134:135]
	v_pk_mul_f32 v[94:95], v[92:93], v[136:137] op_sel:[1,1] op_sel_hi:[0,1] neg_hi:[1,0]
	v_pk_fma_f32 v[94:95], v[92:93], v[136:137], v[94:95] op_sel_hi:[1,0,1]
	v_pk_mul_f32 v[92:93], v[26:27], v[134:135] op_sel:[0,1] op_sel_hi:[0,0] neg_lo:[0,1]
	v_pk_fma_f32 v[142:143], v[24:25], v[134:135], v[92:93]
	v_pk_mul_f32 v[92:93], v[138:139], v[134:135] op_sel:[1,1] op_sel_hi:[0,1] neg_hi:[1,0]
	v_pk_fma_f32 v[92:93], v[138:139], v[134:135], v[92:93] op_sel_hi:[1,0,1]
	v_pk_mul_f32 v[134:135], v[26:27], v[136:137] op_sel:[0,1] op_sel_hi:[0,0] neg_lo:[0,1]
	v_pk_fma_f32 v[134:135], v[24:25], v[136:137], v[134:135]
	v_pk_mul_f32 v[138:139], v[132:133], v[142:143] op_sel:[1,1] op_sel_hi:[0,1] neg_hi:[1,0]
	v_pk_mul_f32 v[136:137], v[128:129], v[134:135] op_sel:[1,1] op_sel_hi:[0,1] neg_hi:[1,0]
	v_pk_fma_f32 v[132:133], v[132:133], v[142:143], v[138:139] op_sel_hi:[1,0,1]
	v_pk_fma_f32 v[128:129], v[128:129], v[134:135], v[136:137] op_sel_hi:[1,0,1]
	v_pk_mul_f32 v[138:139], v[26:27], v[134:135] op_sel:[0,1] op_sel_hi:[0,0] neg_lo:[0,1]
	v_pk_mul_f32 v[136:137], v[26:27], v[142:143] op_sel:[0,1] op_sel_hi:[0,0] neg_lo:[0,1]
	v_pk_fma_f32 v[134:135], v[24:25], v[134:135], v[138:139]
	v_pk_fma_f32 v[136:137], v[24:25], v[142:143], v[136:137]
	v_pk_mul_f32 v[138:139], v[130:131], v[134:135] op_sel:[1,1] op_sel_hi:[0,1] neg_hi:[1,0]
	v_pk_fma_f32 v[130:131], v[130:131], v[134:135], v[138:139] op_sel_hi:[1,0,1]
	v_pk_mul_f32 v[138:139], v[26:27], v[136:137] op_sel:[0,1] op_sel_hi:[0,0] neg_lo:[0,1]
	v_pk_mul_f32 v[142:143], v[140:141], v[136:137] op_sel:[1,1] op_sel_hi:[0,1] neg_hi:[1,0]
	v_pk_fma_f32 v[138:139], v[24:25], v[136:137], v[138:139]
	v_pk_fma_f32 v[136:137], v[140:141], v[136:137], v[142:143] op_sel_hi:[1,0,1]
	v_pk_mul_f32 v[140:141], v[26:27], v[134:135] op_sel:[0,1] op_sel_hi:[0,0] neg_lo:[0,1]
	v_pk_fma_f32 v[134:135], v[24:25], v[134:135], v[140:141]
	v_pk_mul_f32 v[140:141], v[84:85], v[134:135] op_sel:[1,1] op_sel_hi:[0,1] neg_hi:[1,0]
	v_pk_fma_f32 v[84:85], v[84:85], v[134:135], v[140:141] op_sel_hi:[1,0,1]
	v_pk_mul_f32 v[140:141], v[26:27], v[138:139] op_sel:[0,1] op_sel_hi:[0,0] neg_lo:[0,1]
	v_pk_mul_f32 v[142:143], v[88:89], v[138:139] op_sel:[1,1] op_sel_hi:[0,1] neg_hi:[1,0]
	v_pk_fma_f32 v[140:141], v[24:25], v[138:139], v[140:141]
	v_pk_fma_f32 v[88:89], v[88:89], v[138:139], v[142:143] op_sel_hi:[1,0,1]
	v_pk_mul_f32 v[138:139], v[26:27], v[134:135] op_sel:[0,1] op_sel_hi:[0,0] neg_lo:[0,1]
	v_pk_fma_f32 v[134:135], v[24:25], v[134:135], v[138:139]
	v_pk_mul_f32 v[138:139], v[80:81], v[134:135] op_sel:[1,1] op_sel_hi:[0,1] neg_hi:[1,0]
	v_pk_fma_f32 v[80:81], v[80:81], v[134:135], v[138:139] op_sel_hi:[1,0,1]
	v_pk_mul_f32 v[138:139], v[26:27], v[140:141] op_sel:[0,1] op_sel_hi:[0,0] neg_lo:[0,1]
	v_pk_mul_f32 v[142:143], v[82:83], v[140:141] op_sel:[1,1] op_sel_hi:[0,1] neg_hi:[1,0]
	v_pk_fma_f32 v[138:139], v[24:25], v[140:141], v[138:139]
	v_pk_fma_f32 v[82:83], v[82:83], v[140:141], v[142:143] op_sel_hi:[1,0,1]
	v_pk_mul_f32 v[140:141], v[26:27], v[134:135] op_sel:[0,1] op_sel_hi:[0,0] neg_lo:[0,1]
	v_pk_fma_f32 v[134:135], v[24:25], v[134:135], v[140:141]
	v_pk_mul_f32 v[140:141], v[70:71], v[134:135] op_sel:[1,1] op_sel_hi:[0,1] neg_hi:[1,0]
	v_pk_fma_f32 v[70:71], v[70:71], v[134:135], v[140:141] op_sel_hi:[1,0,1]
	v_pk_mul_f32 v[140:141], v[26:27], v[138:139] op_sel:[0,1] op_sel_hi:[0,0] neg_lo:[0,1]
	v_pk_mul_f32 v[142:143], v[74:75], v[138:139] op_sel:[1,1] op_sel_hi:[0,1] neg_hi:[1,0]
	v_pk_fma_f32 v[140:141], v[24:25], v[138:139], v[140:141]
	v_pk_fma_f32 v[74:75], v[74:75], v[138:139], v[142:143] op_sel_hi:[1,0,1]
	v_pk_mul_f32 v[138:139], v[26:27], v[134:135] op_sel:[0,1] op_sel_hi:[0,0] neg_lo:[0,1]
	v_pk_fma_f32 v[134:135], v[24:25], v[134:135], v[138:139]
	v_pk_mul_f32 v[138:139], v[64:65], v[134:135] op_sel:[1,1] op_sel_hi:[0,1] neg_hi:[1,0]
	v_pk_fma_f32 v[64:65], v[64:65], v[134:135], v[138:139] op_sel_hi:[1,0,1]
	v_pk_mul_f32 v[138:139], v[26:27], v[140:141] op_sel:[0,1] op_sel_hi:[0,0] neg_lo:[0,1]
	v_pk_mul_f32 v[142:143], v[66:67], v[140:141] op_sel:[1,1] op_sel_hi:[0,1] neg_hi:[1,0]
	v_pk_fma_f32 v[138:139], v[24:25], v[140:141], v[138:139]
	v_pk_fma_f32 v[66:67], v[66:67], v[140:141], v[142:143] op_sel_hi:[1,0,1]
	v_pk_mul_f32 v[140:141], v[26:27], v[134:135] op_sel:[0,1] op_sel_hi:[0,0] neg_lo:[0,1]
	v_pk_fma_f32 v[134:135], v[24:25], v[134:135], v[140:141]
	v_pk_mul_f32 v[140:141], v[16:17], v[134:135] op_sel:[1,1] op_sel_hi:[0,1] neg_hi:[1,0]
	v_pk_fma_f32 v[16:17], v[16:17], v[134:135], v[140:141] op_sel_hi:[1,0,1]
	v_pk_mul_f32 v[140:141], v[26:27], v[138:139] op_sel:[0,1] op_sel_hi:[0,0] neg_lo:[0,1]
	v_pk_mul_f32 v[142:143], v[18:19], v[138:139] op_sel:[1,1] op_sel_hi:[0,1] neg_hi:[1,0]
	v_pk_fma_f32 v[140:141], v[24:25], v[138:139], v[140:141]
	v_pk_fma_f32 v[18:19], v[18:19], v[138:139], v[142:143] op_sel_hi:[1,0,1]
	v_pk_mul_f32 v[138:139], v[26:27], v[134:135] op_sel:[0,1] op_sel_hi:[0,0] neg_lo:[0,1]
	v_pk_fma_f32 v[134:135], v[24:25], v[134:135], v[138:139]
	v_pk_mul_f32 v[138:139], v[12:13], v[134:135] op_sel:[1,1] op_sel_hi:[0,1] neg_hi:[1,0]
	v_pk_fma_f32 v[12:13], v[12:13], v[134:135], v[138:139] op_sel_hi:[1,0,1]
	v_pk_mul_f32 v[138:139], v[26:27], v[140:141] op_sel:[0,1] op_sel_hi:[0,0] neg_lo:[0,1]
	v_pk_mul_f32 v[142:143], v[14:15], v[140:141] op_sel:[1,1] op_sel_hi:[0,1] neg_hi:[1,0]
	v_pk_fma_f32 v[138:139], v[24:25], v[140:141], v[138:139]
	v_pk_fma_f32 v[14:15], v[14:15], v[140:141], v[142:143] op_sel_hi:[1,0,1]
	v_pk_mul_f32 v[140:141], v[26:27], v[134:135] op_sel:[0,1] op_sel_hi:[0,0] neg_lo:[0,1]
	v_pk_fma_f32 v[134:135], v[24:25], v[134:135], v[140:141]
	v_pk_mul_f32 v[140:141], v[8:9], v[134:135] op_sel:[1,1] op_sel_hi:[0,1] neg_hi:[1,0]
	v_pk_fma_f32 v[8:9], v[8:9], v[134:135], v[140:141] op_sel_hi:[1,0,1]
	v_pk_mul_f32 v[140:141], v[26:27], v[138:139] op_sel:[0,1] op_sel_hi:[0,0] neg_lo:[0,1]
	v_pk_mul_f32 v[142:143], v[10:11], v[138:139] op_sel:[1,1] op_sel_hi:[0,1] neg_hi:[1,0]
	v_pk_fma_f32 v[140:141], v[24:25], v[138:139], v[140:141]
	v_pk_fma_f32 v[10:11], v[10:11], v[138:139], v[142:143] op_sel_hi:[1,0,1]
	v_pk_mul_f32 v[138:139], v[26:27], v[134:135] op_sel:[0,1] op_sel_hi:[0,0] neg_lo:[0,1]
	v_pk_fma_f32 v[24:25], v[24:25], v[134:135], v[138:139]
	v_pk_mul_f32 v[134:135], v[4:5], v[24:25] op_sel:[1,1] op_sel_hi:[0,1] neg_hi:[1,0]
	v_pk_fma_f32 v[4:5], v[4:5], v[24:25], v[134:135] op_sel_hi:[1,0,1]
	v_pk_mul_f32 v[24:25], v[6:7], v[140:141] op_sel:[1,1] op_sel_hi:[0,1] neg_hi:[1,0]
	s_nop 0
	v_pk_fma_f32 v[6:7], v[6:7], v[140:141], v[24:25] op_sel_hi:[1,0,1]
	ds_write_b64 v27, v[2:3]
	ds_write_b64 v96, v[84:85]
	ds_write_b64 v97, v[90:91] offset:256
	ds_write_b64 v98, v[16:17] offset:256
	ds_write_b64 v99, v[72:73] offset:512
	ds_write_b64 v100, v[70:71] offset:512
	ds_write_b64 v101, v[128:129] offset:768
	ds_write_b64 v102, v[8:9] offset:768
	ds_write_b64 v103, v[62:63] offset:1024
	ds_write_b64 v104, v[80:81] offset:1024
	ds_write_b64 v105, v[94:95] offset:1280
	ds_write_b64 v106, v[12:13] offset:1280
	ds_write_b64 v107, v[78:79] offset:1536
	ds_write_b64 v108, v[64:65] offset:1536
	ds_write_b64 v109, v[130:131] offset:1792
	ds_write_b64 v110, v[4:5] offset:1792
	ds_write_b64 v111, v[20:21] offset:2048
	ds_write_b64 v112, v[88:89] offset:2048
	ds_write_b64 v113, v[86:87] offset:2304
	ds_write_b64 v114, v[18:19] offset:2304
	ds_write_b64 v115, v[68:69] offset:2560
	ds_write_b64 v116, v[74:75] offset:2560
	ds_write_b64 v117, v[132:133] offset:2816
	ds_write_b64 v118, v[10:11] offset:2816
	ds_write_b64 v119, v[22:23] offset:3072
	ds_write_b64 v120, v[82:83] offset:3072
	ds_write_b64 v121, v[92:93] offset:3328
	ds_write_b64 v122, v[14:15] offset:3328
	ds_write_b64 v123, v[76:77] offset:3584
	ds_write_b64 v124, v[66:67] offset:3584
	ds_write_b64 v125, v[136:137] offset:3840
	ds_write_b64 v126, v[6:7] offset:3840
	v_mov_b32_e32 v2, v146
	s_waitcnt lgkmcnt(0)
	s_barrier
	s_nop 0
	v_lshlrev_b32_e32 v3, 4, v2
	v_lshrrev_b32_e32 v4, 1, v2
	v_bfe_u32 v2, v2, 1, 4
	v_bitop3_b32 v5, v4, v3, 16 bitop3:0x6c
	v_lshl_add_u32 v5, v5, 3, 16
	v_lshlrev_b32_e32 v2, 3, v2
	v_add_u32_e32 v6, v5, v2
	ds_read_b64 v[12:13], v6
	v_bitop3_b32 v6, v4, 1, 15 bitop3:0x6c
	v_lshlrev_b32_e32 v8, 3, v6
	v_add_u32_e32 v6, v5, v8
	ds_read_b64 v[14:15], v6
	v_bitop3_b32 v6, v4, 2, 15 bitop3:0x6c
	v_lshlrev_b32_e32 v9, 3, v6
	v_add_u32_e32 v6, v5, v9
	ds_read_b64 v[16:17], v6
	v_bitop3_b32 v6, v4, 3, 15 bitop3:0x6c
	v_lshlrev_b32_e32 v10, 3, v6
	v_add_u32_e32 v6, v5, v10
	ds_read_b64 v[18:19], v6
	v_bitop3_b32 v6, v4, 4, 15 bitop3:0x6c
	v_lshlrev_b32_e32 v11, 3, v6
	v_add_u32_e32 v6, v5, v11
	ds_read_b64 v[20:21], v6
	v_bitop3_b32 v6, v4, 5, 15 bitop3:0x6c
	v_lshlrev_b32_e32 v82, 3, v6
	v_add_u32_e32 v6, v5, v82
	ds_read_b64 v[22:23], v6
	v_bitop3_b32 v6, v4, 6, 15 bitop3:0x6c
	v_lshlrev_b32_e32 v83, 3, v6
	v_add_u32_e32 v6, v5, v83
	ds_read_b64 v[24:25], v6
	v_bitop3_b32 v6, v4, 7, 15 bitop3:0x6c
	v_lshlrev_b32_e32 v84, 3, v6
	v_add_u32_e32 v6, v5, v84
	ds_read_b64 v[26:27], v6
	v_bitop3_b32 v6, v4, 8, 15 bitop3:0x6c
	v_lshlrev_b32_e32 v85, 3, v6
	v_add_u32_e32 v6, v5, v85
	ds_read_b64 v[62:63], v6
	v_bitop3_b32 v6, v4, 9, 15 bitop3:0x6c
	v_lshlrev_b32_e32 v86, 3, v6
	v_add_u32_e32 v6, v5, v86
	ds_read_b64 v[64:65], v6
	v_bitop3_b32 v6, v4, 10, 15 bitop3:0x6c
	v_lshlrev_b32_e32 v87, 3, v6
	v_add_u32_e32 v6, v5, v87
	ds_read_b64 v[66:67], v6
	v_bitop3_b32 v6, v4, 11, 15 bitop3:0x6c
	v_lshlrev_b32_e32 v88, 3, v6
	v_add_u32_e32 v6, v5, v88
	ds_read_b64 v[68:69], v6
	v_bitop3_b32 v6, v4, 12, 15 bitop3:0x6c
	v_lshlrev_b32_e32 v89, 3, v6
	v_add_u32_e32 v6, v5, v89
	ds_read_b64 v[70:71], v6
	v_bitop3_b32 v6, v4, 13, 15 bitop3:0x6c
	v_lshlrev_b32_e32 v90, 3, v6
	v_add_u32_e32 v6, v5, v90
	ds_read_b64 v[72:73], v6
	v_bitop3_b32 v6, v4, 14, 15 bitop3:0x6c
	v_lshlrev_b32_e32 v91, 3, v6
	v_add_u32_e32 v6, v5, v91
	v_add_u32_e32 v3, 0x2000, v3
	ds_read_b64 v[74:75], v6
	v_bitop3_b32 v6, v4, 15, v4 bitop3:0xc
	v_bitop3_b32 v3, v3, v4, 16 bitop3:0x78
	v_lshlrev_b32_e32 v106, 3, v6
	v_lshl_add_u32 v107, v3, 3, 16
	v_add_u32_e32 v5, v5, v106
	v_add_u32_e32 v2, v107, v2
	ds_read_b64 v[76:77], v5
	ds_read_b64 v[6:7], v2
	v_add_u32_e32 v2, v107, v8
	ds_read_b64 v[78:79], v2
	v_add_u32_e32 v2, v107, v9
	ds_read_b64 v[8:9], v2
	v_add_u32_e32 v2, v107, v10
	ds_read_b64 v[80:81], v2
	v_add_u32_e32 v2, v107, v11
	ds_read_b64 v[10:11], v2
	v_add_u32_e32 v2, v107, v82
	v_add_u32_e32 v82, v107, v84
	v_add_u32_e32 v84, v107, v85
	ds_read_b64 v[4:5], v2
	ds_read_b64 v[92:93], v84
	v_add_u32_e32 v2, v107, v83
	v_add_u32_e32 v84, v107, v86
	ds_read_b64 v[2:3], v2
	ds_read_b64 v[82:83], v82
	ds_read_b64 v[94:95], v84
	v_add_u32_e32 v84, v107, v87
	ds_read_b64 v[96:97], v84
	v_add_u32_e32 v84, v107, v88
	ds_read_b64 v[98:99], v84
	v_add_u32_e32 v84, v107, v89
	ds_read_b64 v[100:101], v84
	v_add_u32_e32 v84, v107, v90
	ds_read_b64 v[102:103], v84
	v_add_u32_e32 v84, v107, v91
	ds_read_b64 v[104:105], v84
	v_add_u32_e32 v84, v107, v106
	ds_read_b64 v[106:107], v84
	s_waitcnt lgkmcnt(14)
	v_pk_add_f32 v[84:85], v[12:13], v[62:63]
	v_pk_add_f32 v[12:13], v[12:13], v[62:63] neg_lo:[0,1] neg_hi:[0,1]
	v_pk_add_f32 v[62:63], v[14:15], v[64:65]
	v_pk_add_f32 v[14:15], v[14:15], v[64:65] neg_lo:[0,1] neg_hi:[0,1]
	v_pk_mul_f32 v[64:65], v[14:15], s[54:55] op_sel:[1,0] op_sel_hi:[0,0] neg_hi:[1,0]
	v_pk_fma_f32 v[14:15], v[14:15], s[52:53], v[64:65] op_sel_hi:[1,0,1]
	v_pk_add_f32 v[64:65], v[16:17], v[66:67]
	v_pk_add_f32 v[16:17], v[16:17], v[66:67] neg_lo:[0,1] neg_hi:[0,1]
	v_pk_mul_f32 v[66:67], v[16:17], s[60:61] op_sel:[1,0] op_sel_hi:[0,0] neg_hi:[1,0]
	v_pk_fma_f32 v[16:17], v[16:17], s[60:61], v[66:67] op_sel_hi:[1,0,1]
	v_pk_add_f32 v[66:67], v[18:19], v[68:69]
	v_pk_add_f32 v[18:19], v[18:19], v[68:69] neg_lo:[0,1] neg_hi:[0,1]
	v_pk_mul_f32 v[68:69], v[18:19], s[52:53] op_sel:[1,0] op_sel_hi:[0,0] neg_hi:[1,0]
	v_pk_fma_f32 v[18:19], v[18:19], s[54:55], v[68:69] op_sel_hi:[1,0,1]
	v_pk_add_f32 v[68:69], v[20:21], v[70:71]
	v_pk_add_f32 v[20:21], v[20:21], v[70:71] neg_lo:[0,1] neg_hi:[0,1]
	v_xor_b32_e32 v71, 0x80000000, v20
	v_mov_b32_e32 v70, v21
	v_pk_add_f32 v[20:21], v[22:23], v[72:73]
	v_pk_add_f32 v[22:23], v[22:23], v[72:73] neg_lo:[0,1] neg_hi:[0,1]
	v_pk_mul_f32 v[72:73], v[22:23], s[54:55] op_sel_hi:[1,0]
	v_xor_b32_e32 v87, 0x80000000, v22
	v_mov_b32_e32 v86, v23
	v_pk_fma_f32 v[22:23], v[86:87], s[52:53], v[72:73] op_sel_hi:[1,0,1] neg_lo:[0,0,1] neg_hi:[0,0,1]
	v_pk_add_f32 v[72:73], v[24:25], v[74:75]
	v_pk_add_f32 v[24:25], v[24:25], v[74:75] neg_lo:[0,1] neg_hi:[0,1]
	v_pk_mul_f32 v[74:75], v[24:25], s[60:61] op_sel_hi:[1,0]
	v_xor_b32_e32 v87, 0x80000000, v24
	v_mov_b32_e32 v86, v25
	v_pk_fma_f32 v[24:25], v[86:87], s[60:61], v[74:75] op_sel_hi:[1,0,1] neg_lo:[0,0,1] neg_hi:[0,0,1]
	v_pk_add_f32 v[74:75], v[26:27], v[76:77]
	v_pk_add_f32 v[26:27], v[26:27], v[76:77] neg_lo:[0,1] neg_hi:[0,1]
	v_pk_mul_f32 v[76:77], v[26:27], s[52:53] op_sel_hi:[1,0]
	v_xor_b32_e32 v87, 0x80000000, v26
	v_mov_b32_e32 v86, v27
	v_pk_fma_f32 v[26:27], v[86:87], s[54:55], v[76:77] op_sel_hi:[1,0,1] neg_lo:[0,0,1] neg_hi:[0,0,1]
	v_pk_add_f32 v[76:77], v[84:85], v[68:69]
	v_pk_add_f32 v[68:69], v[84:85], v[68:69] neg_lo:[0,1] neg_hi:[0,1]
	v_pk_add_f32 v[84:85], v[62:63], v[20:21]
	v_pk_add_f32 v[20:21], v[62:63], v[20:21] neg_lo:[0,1] neg_hi:[0,1]
	v_pk_mul_f32 v[62:63], v[20:21], s[60:61] op_sel:[1,0] op_sel_hi:[0,0] neg_hi:[1,0]
	v_pk_fma_f32 v[20:21], v[20:21], s[60:61], v[62:63] op_sel_hi:[1,0,1]
	v_pk_add_f32 v[62:63], v[64:65], v[72:73]
	v_pk_add_f32 v[64:65], v[64:65], v[72:73] neg_lo:[0,1] neg_hi:[0,1]
	v_xor_b32_e32 v73, 0x80000000, v64
	v_mov_b32_e32 v72, v65
	v_pk_add_f32 v[64:65], v[66:67], v[74:75]
	v_pk_add_f32 v[66:67], v[66:67], v[74:75] neg_lo:[0,1] neg_hi:[0,1]
	v_pk_mul_f32 v[74:75], v[66:67], s[60:61] op_sel_hi:[1,0]
	v_xor_b32_e32 v87, 0x80000000, v66
	v_mov_b32_e32 v86, v67
	v_pk_fma_f32 v[66:67], v[86:87], s[60:61], v[74:75] op_sel_hi:[1,0,1] neg_lo:[0,0,1] neg_hi:[0,0,1]
	v_pk_add_f32 v[74:75], v[12:13], v[70:71]
	v_pk_add_f32 v[12:13], v[12:13], v[70:71] neg_lo:[0,1] neg_hi:[0,1]
	v_pk_add_f32 v[70:71], v[14:15], v[22:23]
	v_pk_add_f32 v[14:15], v[14:15], v[22:23] neg_lo:[0,1] neg_hi:[0,1]
	v_pk_mul_f32 v[22:23], v[14:15], s[60:61] op_sel:[1,0] op_sel_hi:[0,0] neg_hi:[1,0]
	v_pk_fma_f32 v[14:15], v[14:15], s[60:61], v[22:23] op_sel_hi:[1,0,1]
	v_pk_add_f32 v[22:23], v[16:17], v[24:25]
	v_pk_add_f32 v[16:17], v[16:17], v[24:25] neg_lo:[0,1] neg_hi:[0,1]
	v_xor_b32_e32 v25, 0x80000000, v16
	v_mov_b32_e32 v24, v17
	v_pk_add_f32 v[16:17], v[18:19], v[26:27]
	v_pk_add_f32 v[18:19], v[18:19], v[26:27] neg_lo:[0,1] neg_hi:[0,1]
	v_pk_add_f32 v[108:109], v[12:13], v[24:25]
	v_pk_mul_f32 v[26:27], v[18:19], s[60:61] op_sel_hi:[1,0]
	v_pk_fma_f32 v[18:19], v[18:19], s[60:61], v[26:27] op_sel:[1,0,0] op_sel_hi:[0,0,1] neg_lo:[0,0,1] neg_hi:[1,0,1]
	v_pk_add_f32 v[26:27], v[76:77], v[62:63]
	v_pk_add_f32 v[62:63], v[76:77], v[62:63] neg_lo:[0,1] neg_hi:[0,1]
	v_pk_add_f32 v[76:77], v[84:85], v[64:65]
	v_pk_add_f32 v[64:65], v[84:85], v[64:65] neg_lo:[0,1] neg_hi:[0,1]
	v_pk_add_f32 v[110:111], v[12:13], v[24:25] neg_lo:[0,1] neg_hi:[0,1]
	v_xor_b32_e32 v85, 0x80000000, v64
	v_mov_b32_e32 v84, v65
	v_pk_add_f32 v[64:65], v[68:69], v[72:73]
	v_pk_add_f32 v[68:69], v[68:69], v[72:73] neg_lo:[0,1] neg_hi:[0,1]
	v_pk_add_f32 v[72:73], v[20:21], v[66:67]
	v_pk_add_f32 v[20:21], v[20:21], v[66:67] neg_lo:[0,1] neg_hi:[0,1]
	v_pk_add_f32 v[12:13], v[14:15], v[18:19] neg_lo:[0,1] neg_hi:[0,1]
	v_pk_add_f32 v[112:113], v[14:15], v[18:19]
	v_xor_b32_e32 v115, 0x80000000, v12
	v_mov_b32_e32 v114, v13
	v_pk_add_f32 v[12:13], v[26:27], v[76:77]
	v_pk_add_f32 v[14:15], v[26:27], v[76:77] neg_lo:[0,1] neg_hi:[0,1]
	v_pk_add_f32 v[24:25], v[68:69], v[20:21] op_sel:[0,1] op_sel_hi:[1,0] neg_hi:[0,1]
	v_pk_add_f32 v[26:27], v[68:69], v[20:21] op_sel:[0,1] op_sel_hi:[1,0] neg_lo:[0,1]
	s_waitcnt lgkmcnt(6)
	v_pk_add_f32 v[66:67], v[78:79], v[94:95] neg_lo:[0,1] neg_hi:[0,1]
	v_pk_add_f32 v[86:87], v[74:75], v[22:23]
	v_pk_mul_f32 v[76:77], v[66:67], s[54:55] op_sel:[1,0] op_sel_hi:[0,0] neg_hi:[1,0]
	v_pk_add_f32 v[74:75], v[74:75], v[22:23] neg_lo:[0,1] neg_hi:[0,1]
	v_pk_fma_f32 v[66:67], v[66:67], s[52:53], v[76:77] op_sel_hi:[1,0,1]
	s_waitcnt lgkmcnt(5)
	v_pk_add_f32 v[76:77], v[8:9], v[96:97]
	v_pk_add_f32 v[8:9], v[8:9], v[96:97] neg_lo:[0,1] neg_hi:[0,1]
	v_pk_add_f32 v[20:21], v[64:65], v[72:73]
	v_pk_add_f32 v[22:23], v[64:65], v[72:73] neg_lo:[0,1] neg_hi:[0,1]
	v_pk_add_f32 v[64:65], v[78:79], v[94:95]
	v_pk_mul_f32 v[78:79], v[8:9], s[60:61] op_sel:[1,0] op_sel_hi:[0,0] neg_hi:[1,0]
	v_pk_add_f32 v[88:89], v[70:71], v[16:17]
	v_pk_add_f32 v[16:17], v[70:71], v[16:17] neg_lo:[0,1] neg_hi:[0,1]
	v_pk_fma_f32 v[8:9], v[8:9], s[60:61], v[78:79] op_sel_hi:[1,0,1]
	s_waitcnt lgkmcnt(4)
	v_pk_add_f32 v[78:79], v[80:81], v[98:99]
	v_pk_add_f32 v[80:81], v[80:81], v[98:99] neg_lo:[0,1] neg_hi:[0,1]
	v_xor_b32_e32 v91, 0x80000000, v16
	v_mov_b32_e32 v90, v17
	v_pk_add_f32 v[16:17], v[62:63], v[84:85]
	v_pk_add_f32 v[18:19], v[62:63], v[84:85] neg_lo:[0,1] neg_hi:[0,1]
	v_pk_add_f32 v[62:63], v[6:7], v[92:93]
	v_pk_add_f32 v[6:7], v[6:7], v[92:93] neg_lo:[0,1] neg_hi:[0,1]
	v_pk_mul_f32 v[92:93], v[80:81], s[52:53] op_sel:[1,0] op_sel_hi:[0,0] neg_hi:[1,0]
	v_pk_add_f32 v[68:69], v[86:87], v[88:89]
	v_pk_fma_f32 v[80:81], v[80:81], s[54:55], v[92:93] op_sel_hi:[1,0,1]
	s_waitcnt lgkmcnt(3)
	v_pk_add_f32 v[92:93], v[10:11], v[100:101]
	v_pk_add_f32 v[10:11], v[10:11], v[100:101] neg_lo:[0,1] neg_hi:[0,1]
	v_pk_add_f32 v[70:71], v[86:87], v[88:89] neg_lo:[0,1] neg_hi:[0,1]
	v_xor_b32_e32 v95, 0x80000000, v10
	v_mov_b32_e32 v94, v11
	s_waitcnt lgkmcnt(2)
	v_pk_add_f32 v[10:11], v[4:5], v[102:103]
	v_pk_add_f32 v[4:5], v[4:5], v[102:103] neg_lo:[0,1] neg_hi:[0,1]
	v_pk_add_f32 v[84:85], v[108:109], v[112:113]
	v_pk_mul_f32 v[96:97], v[4:5], s[54:55] op_sel_hi:[1,0]
	s_nop 0
	v_pk_fma_f32 v[4:5], v[4:5], s[52:53], v[96:97] op_sel:[1,0,0] op_sel_hi:[0,0,1] neg_lo:[0,0,1] neg_hi:[1,0,1]
	s_waitcnt lgkmcnt(1)
	v_pk_add_f32 v[96:97], v[2:3], v[104:105]
	v_pk_add_f32 v[2:3], v[2:3], v[104:105] neg_lo:[0,1] neg_hi:[0,1]
	v_pk_add_f32 v[86:87], v[108:109], v[112:113] neg_lo:[0,1] neg_hi:[0,1]
	v_pk_mul_f32 v[98:99], v[2:3], s[60:61] op_sel_hi:[1,0]
	s_nop 0
	v_pk_fma_f32 v[2:3], v[2:3], s[60:61], v[98:99] op_sel:[1,0,0] op_sel_hi:[0,0,1] neg_lo:[0,0,1] neg_hi:[1,0,1]
	s_waitcnt lgkmcnt(0)
	v_pk_add_f32 v[98:99], v[82:83], v[106:107]
	v_pk_add_f32 v[82:83], v[82:83], v[106:107] neg_lo:[0,1] neg_hi:[0,1]
	v_pk_add_f32 v[72:73], v[74:75], v[90:91]
	v_pk_mul_f32 v[100:101], v[82:83], s[52:53] op_sel_hi:[1,0]
	v_xor_b32_e32 v103, 0x80000000, v82
	v_mov_b32_e32 v102, v83
	v_pk_fma_f32 v[82:83], v[102:103], s[54:55], v[100:101] op_sel_hi:[1,0,1] neg_lo:[0,0,1] neg_hi:[0,0,1]
	v_pk_add_f32 v[100:101], v[62:63], v[92:93]
	v_pk_add_f32 v[62:63], v[62:63], v[92:93] neg_lo:[0,1] neg_hi:[0,1]
	v_pk_add_f32 v[92:93], v[64:65], v[10:11]
	v_pk_add_f32 v[10:11], v[64:65], v[10:11] neg_lo:[0,1] neg_hi:[0,1]
	v_pk_add_f32 v[74:75], v[74:75], v[90:91] neg_lo:[0,1] neg_hi:[0,1]
	v_pk_mul_f32 v[64:65], v[10:11], s[60:61] op_sel:[1,0] op_sel_hi:[0,0] neg_hi:[1,0]
	v_pk_add_f32 v[88:89], v[110:111], v[114:115]
	v_pk_fma_f32 v[10:11], v[10:11], s[60:61], v[64:65] op_sel_hi:[1,0,1]
	v_pk_add_f32 v[64:65], v[76:77], v[96:97]
	v_pk_add_f32 v[76:77], v[76:77], v[96:97] neg_lo:[0,1] neg_hi:[0,1]
	v_pk_add_f32 v[90:91], v[110:111], v[114:115] neg_lo:[0,1] neg_hi:[0,1]
	v_xor_b32_e32 v97, 0x80000000, v76
	v_mov_b32_e32 v96, v77
	v_pk_add_f32 v[76:77], v[78:79], v[98:99]
	v_pk_add_f32 v[78:79], v[78:79], v[98:99] neg_lo:[0,1] neg_hi:[0,1]
	v_pk_mul_f32 v[98:99], v[78:79], s[60:61] op_sel_hi:[1,0]
	v_xor_b32_e32 v103, 0x80000000, v78
	v_mov_b32_e32 v102, v79
	v_pk_fma_f32 v[78:79], v[102:103], s[60:61], v[98:99] op_sel_hi:[1,0,1] neg_lo:[0,0,1] neg_hi:[0,0,1]
	v_pk_add_f32 v[98:99], v[6:7], v[94:95]
	v_pk_add_f32 v[6:7], v[6:7], v[94:95] neg_lo:[0,1] neg_hi:[0,1]
	v_pk_add_f32 v[94:95], v[66:67], v[4:5]
	v_pk_add_f32 v[4:5], v[66:67], v[4:5] neg_lo:[0,1] neg_hi:[0,1]
	v_pk_mul_f32 v[66:67], v[4:5], s[60:61] op_sel:[1,0] op_sel_hi:[0,0] neg_hi:[1,0]
	v_pk_fma_f32 v[4:5], v[4:5], s[60:61], v[66:67] op_sel_hi:[1,0,1]
	v_pk_add_f32 v[66:67], v[8:9], v[2:3]
	v_pk_add_f32 v[2:3], v[8:9], v[2:3] neg_lo:[0,1] neg_hi:[0,1]
	v_pk_add_f32 v[106:107], v[98:99], v[66:67] neg_lo:[0,1] neg_hi:[0,1]
	v_xor_b32_e32 v9, 0x80000000, v2
	v_mov_b32_e32 v8, v3
	v_pk_add_f32 v[2:3], v[80:81], v[82:83]
	v_pk_add_f32 v[80:81], v[80:81], v[82:83] neg_lo:[0,1] neg_hi:[0,1]
	v_pk_add_f32 v[108:109], v[94:95], v[2:3]
	v_pk_mul_f32 v[82:83], v[80:81], s[60:61] op_sel_hi:[1,0]
	v_pk_fma_f32 v[80:81], v[80:81], s[60:61], v[82:83] op_sel:[1,0,0] op_sel_hi:[0,0,1] neg_lo:[0,0,1] neg_hi:[1,0,1]
	v_pk_add_f32 v[82:83], v[100:101], v[64:65]
	v_pk_add_f32 v[64:65], v[100:101], v[64:65] neg_lo:[0,1] neg_hi:[0,1]
	v_pk_add_f32 v[100:101], v[92:93], v[76:77]
	v_pk_add_f32 v[76:77], v[92:93], v[76:77] neg_lo:[0,1] neg_hi:[0,1]
	v_pk_add_f32 v[102:103], v[10:11], v[78:79]
	v_xor_b32_e32 v93, 0x80000000, v76
	v_mov_b32_e32 v92, v77
	v_pk_add_f32 v[76:77], v[62:63], v[96:97]
	v_pk_add_f32 v[10:11], v[10:11], v[78:79] neg_lo:[0,1] neg_hi:[0,1]
	v_pk_add_f32 v[2:3], v[94:95], v[2:3] neg_lo:[0,1] neg_hi:[0,1]
	v_pk_add_f32 v[62:63], v[62:63], v[96:97] neg_lo:[0,1] neg_hi:[0,1]
	v_xor_b32_e32 v105, 0x80000000, v10
	v_mov_b32_e32 v104, v11
	v_pk_add_f32 v[10:11], v[98:99], v[66:67]
	v_xor_b32_e32 v111, 0x80000000, v2
	v_mov_b32_e32 v110, v3
	v_pk_add_f32 v[112:113], v[6:7], v[8:9]
	v_pk_add_f32 v[114:115], v[6:7], v[8:9] neg_lo:[0,1] neg_hi:[0,1]
	v_pk_add_f32 v[6:7], v[4:5], v[80:81]
	v_pk_add_f32 v[2:3], v[4:5], v[80:81] neg_lo:[0,1] neg_hi:[0,1]
	v_pk_add_f32 v[98:99], v[82:83], v[100:101]
	v_pk_add_f32 v[96:97], v[82:83], v[100:101] neg_lo:[0,1] neg_hi:[0,1]
	v_pk_add_f32 v[82:83], v[76:77], v[102:103]
	v_pk_add_f32 v[80:81], v[76:77], v[102:103] neg_lo:[0,1] neg_hi:[0,1]
	s_waitcnt vmcnt(7)
	v_mov_b64 v[100:101], v[164:165]
	v_mov_b64 v[102:103], v[166:167]
	v_pk_add_f32 v[78:79], v[62:63], v[104:105]
	v_pk_add_f32 v[76:77], v[62:63], v[104:105] neg_lo:[0,1] neg_hi:[0,1]
	v_xor_b32_e32 v5, 0x80000000, v2
	v_mov_b32_e32 v4, v3
	v_pk_add_f32 v[62:63], v[106:107], v[110:111]
	v_pk_add_f32 v[2:3], v[106:107], v[110:111] neg_lo:[0,1] neg_hi:[0,1]
	v_pk_add_f32 v[94:95], v[64:65], v[92:93]
	v_pk_add_f32 v[92:93], v[64:65], v[92:93] neg_lo:[0,1] neg_hi:[0,1]
	v_pk_add_f32 v[66:67], v[10:11], v[108:109]
	v_pk_add_f32 v[64:65], v[10:11], v[108:109] neg_lo:[0,1] neg_hi:[0,1]
	v_pk_add_f32 v[10:11], v[112:113], v[6:7]
	v_pk_add_f32 v[8:9], v[112:113], v[6:7] neg_lo:[0,1] neg_hi:[0,1]
	v_pk_add_f32 v[6:7], v[114:115], v[4:5]
	v_pk_add_f32 v[4:5], v[114:115], v[4:5] neg_lo:[0,1] neg_hi:[0,1]
	v_cvt_f32_f16_e32 v104, v100
	v_cvt_f32_f16_sdwa v100, v100 dst_sel:DWORD dst_unused:UNUSED_PAD src0_sel:WORD_1
	v_mul_f32_e32 v104, 0x38800000, v104
	v_mul_f32_e32 v100, 0x38800000, v100
	s_nop 0
	v_pk_mul_f32 v[106:107], v[12:13], v[100:101] op_sel:[1,0] op_sel_hi:[0,0] neg_lo:[1,0]
	v_cvt_f32_f16_e32 v100, v101
	v_cvt_f32_f16_sdwa v101, v101 dst_sel:DWORD dst_unused:UNUSED_PAD src0_sel:WORD_1
	v_pk_fma_f32 v[12:13], v[12:13], v[104:105], v[106:107] op_sel_hi:[1,0,1]
	v_xor_b32_e32 v106, 0x80000000, v15
	v_mov_b32_e32 v107, v14
	v_mul_f32_e32 v104, 0x38800000, v101
	v_mul_f32_e32 v100, 0x38800000, v100
	v_pk_mul_f32 v[104:105], v[106:107], v[104:105] op_sel_hi:[1,0]
	v_xor_b32_e32 v106, 0x80000000, v21
	v_pk_fma_f32 v[14:15], v[14:15], v[100:101], v[104:105] op_sel_hi:[1,0,1]
	v_cvt_f32_f16_sdwa v101, v102 dst_sel:DWORD dst_unused:UNUSED_PAD src0_sel:WORD_1
	v_cvt_f32_f16_e32 v100, v102
	s_nop 0
	s_nop 0
	v_mul_f32_e32 v102, 0x38800000, v101
	v_mul_f32_e32 v100, 0x38800000, v100
	v_pk_mul_f32 v[104:105], v[16:17], v[102:103] op_sel:[1,0] op_sel_hi:[0,0] neg_lo:[1,0]
	v_mov_b32_e32 v107, v20
	v_pk_fma_f32 v[16:17], v[16:17], v[100:101], v[104:105] op_sel_hi:[1,0,1]
	v_cvt_f32_f16_sdwa v101, v103 dst_sel:DWORD dst_unused:UNUSED_PAD src0_sel:WORD_1
	v_cvt_f32_f16_e32 v100, v103
	v_xor_b32_e32 v104, 0x80000000, v19
	v_mov_b32_e32 v105, v18
	v_mul_f32_e32 v102, 0x38800000, v101
	v_mul_f32_e32 v100, 0x38800000, v100
	v_pk_mul_f32 v[102:103], v[104:105], v[102:103] op_sel_hi:[1,0]
	s_nop 0
	v_pk_fma_f32 v[18:19], v[18:19], v[100:101], v[102:103] op_sel_hi:[1,0,1]
	s_waitcnt vmcnt(6)
	v_mov_b64 v[100:101], v[168:169]
	v_mov_b64 v[102:103], v[170:171]
	v_cvt_f32_f16_e32 v104, v100
	v_cvt_f32_f16_sdwa v100, v100 dst_sel:DWORD dst_unused:UNUSED_PAD src0_sel:WORD_1
	v_mul_f32_e32 v104, 0x38800000, v104
	v_mul_f32_e32 v100, 0x38800000, v100
	v_pk_mul_f32 v[106:107], v[106:107], v[100:101] op_sel_hi:[1,0]
	v_cvt_f32_f16_e32 v100, v101
	v_cvt_f32_f16_sdwa v101, v101 dst_sel:DWORD dst_unused:UNUSED_PAD src0_sel:WORD_1
	v_pk_fma_f32 v[20:21], v[20:21], v[104:105], v[106:107] op_sel_hi:[1,0,1]
	v_xor_b32_e32 v106, 0x80000000, v23
	v_mov_b32_e32 v107, v22
	v_mul_f32_e32 v104, 0x38800000, v101
	v_mul_f32_e32 v100, 0x38800000, v100
	v_pk_mul_f32 v[104:105], v[106:107], v[104:105] op_sel_hi:[1,0]
	v_xor_b32_e32 v106, 0x80000000, v69
	v_pk_fma_f32 v[22:23], v[22:23], v[100:101], v[104:105] op_sel_hi:[1,0,1]
	v_cvt_f32_f16_sdwa v101, v102 dst_sel:DWORD dst_unused:UNUSED_PAD src0_sel:WORD_1
	v_cvt_f32_f16_e32 v100, v102
	s_nop 0
	s_nop 0
	v_mul_f32_e32 v102, 0x38800000, v101
	v_mul_f32_e32 v100, 0x38800000, v100
	v_pk_mul_f32 v[104:105], v[24:25], v[102:103] op_sel:[1,0] op_sel_hi:[0,0] neg_lo:[1,0]
	v_mov_b32_e32 v107, v68
	v_pk_fma_f32 v[24:25], v[24:25], v[100:101], v[104:105] op_sel_hi:[1,0,1]
	v_cvt_f32_f16_sdwa v101, v103 dst_sel:DWORD dst_unused:UNUSED_PAD src0_sel:WORD_1
	v_cvt_f32_f16_e32 v100, v103
	v_xor_b32_e32 v104, 0x80000000, v27
	v_mov_b32_e32 v105, v26
	v_mul_f32_e32 v102, 0x38800000, v101
	v_mul_f32_e32 v100, 0x38800000, v100
	v_pk_mul_f32 v[102:103], v[104:105], v[102:103] op_sel_hi:[1,0]
	s_nop 0
	v_pk_fma_f32 v[26:27], v[26:27], v[100:101], v[102:103] op_sel_hi:[1,0,1]
	s_waitcnt vmcnt(5)
	v_mov_b64 v[100:101], v[172:173]
	v_mov_b64 v[102:103], v[174:175]
	v_cvt_f32_f16_e32 v104, v100
	v_cvt_f32_f16_sdwa v100, v100 dst_sel:DWORD dst_unused:UNUSED_PAD src0_sel:WORD_1
	v_mul_f32_e32 v104, 0x38800000, v104
	v_mul_f32_e32 v100, 0x38800000, v100
	v_pk_mul_f32 v[106:107], v[106:107], v[100:101] op_sel_hi:[1,0]
	v_cvt_f32_f16_e32 v100, v101
	v_cvt_f32_f16_sdwa v101, v101 dst_sel:DWORD dst_unused:UNUSED_PAD src0_sel:WORD_1
	v_pk_fma_f32 v[68:69], v[68:69], v[104:105], v[106:107] op_sel_hi:[1,0,1]
	v_xor_b32_e32 v106, 0x80000000, v71
	v_mov_b32_e32 v107, v70
	v_mul_f32_e32 v104, 0x38800000, v101
	v_mul_f32_e32 v100, 0x38800000, v100
	v_pk_mul_f32 v[104:105], v[106:107], v[104:105] op_sel_hi:[1,0]
	v_xor_b32_e32 v106, 0x80000000, v85
	v_pk_fma_f32 v[70:71], v[70:71], v[100:101], v[104:105] op_sel_hi:[1,0,1]
	v_cvt_f32_f16_sdwa v101, v102 dst_sel:DWORD dst_unused:UNUSED_PAD src0_sel:WORD_1
	v_cvt_f32_f16_e32 v100, v102
	s_nop 0
	s_nop 0
	v_mul_f32_e32 v102, 0x38800000, v101
	v_mul_f32_e32 v100, 0x38800000, v100
	v_pk_mul_f32 v[104:105], v[72:73], v[102:103] op_sel:[1,0] op_sel_hi:[0,0] neg_lo:[1,0]
	v_mov_b32_e32 v107, v84
	v_pk_fma_f32 v[72:73], v[72:73], v[100:101], v[104:105] op_sel_hi:[1,0,1]
	v_cvt_f32_f16_sdwa v101, v103 dst_sel:DWORD dst_unused:UNUSED_PAD src0_sel:WORD_1
	v_cvt_f32_f16_e32 v100, v103
	v_xor_b32_e32 v104, 0x80000000, v75
	v_mov_b32_e32 v105, v74
	v_mul_f32_e32 v102, 0x38800000, v101
	v_mul_f32_e32 v100, 0x38800000, v100
	v_pk_mul_f32 v[102:103], v[104:105], v[102:103] op_sel_hi:[1,0]
	s_nop 0
	v_pk_fma_f32 v[74:75], v[74:75], v[100:101], v[102:103] op_sel_hi:[1,0,1]
	s_waitcnt vmcnt(4)
	v_mov_b64 v[100:101], v[176:177]
	v_mov_b64 v[102:103], v[178:179]
	v_cvt_f32_f16_e32 v104, v100
	v_cvt_f32_f16_sdwa v100, v100 dst_sel:DWORD dst_unused:UNUSED_PAD src0_sel:WORD_1
	v_mul_f32_e32 v104, 0x38800000, v104
	v_mul_f32_e32 v100, 0x38800000, v100
	v_pk_mul_f32 v[106:107], v[106:107], v[100:101] op_sel_hi:[1,0]
	v_cvt_f32_f16_e32 v100, v101
	v_cvt_f32_f16_sdwa v101, v101 dst_sel:DWORD dst_unused:UNUSED_PAD src0_sel:WORD_1
	v_pk_fma_f32 v[84:85], v[84:85], v[104:105], v[106:107] op_sel_hi:[1,0,1]
	v_xor_b32_e32 v106, 0x80000000, v87
	v_mov_b32_e32 v107, v86
	v_mul_f32_e32 v104, 0x38800000, v101
	v_mul_f32_e32 v100, 0x38800000, v100
	v_pk_mul_f32 v[104:105], v[106:107], v[104:105] op_sel_hi:[1,0]
	v_xor_b32_e32 v106, 0x80000000, v99
	v_pk_fma_f32 v[86:87], v[86:87], v[100:101], v[104:105] op_sel_hi:[1,0,1]
	v_cvt_f32_f16_sdwa v101, v102 dst_sel:DWORD dst_unused:UNUSED_PAD src0_sel:WORD_1
	v_cvt_f32_f16_e32 v100, v102
	s_nop 0
	s_nop 0
	v_mul_f32_e32 v102, 0x38800000, v101
	v_mul_f32_e32 v100, 0x38800000, v100
	v_pk_mul_f32 v[104:105], v[88:89], v[102:103] op_sel:[1,0] op_sel_hi:[0,0] neg_lo:[1,0]
	v_mov_b32_e32 v107, v98
	v_pk_fma_f32 v[88:89], v[88:89], v[100:101], v[104:105] op_sel_hi:[1,0,1]
	v_cvt_f32_f16_sdwa v101, v103 dst_sel:DWORD dst_unused:UNUSED_PAD src0_sel:WORD_1
	v_cvt_f32_f16_e32 v100, v103
	v_xor_b32_e32 v104, 0x80000000, v91
	v_mov_b32_e32 v105, v90
	v_mul_f32_e32 v102, 0x38800000, v101
	v_mul_f32_e32 v100, 0x38800000, v100
	v_pk_mul_f32 v[102:103], v[104:105], v[102:103] op_sel_hi:[1,0]
	s_nop 0
	v_pk_fma_f32 v[90:91], v[90:91], v[100:101], v[102:103] op_sel_hi:[1,0,1]
	s_waitcnt vmcnt(3)
	v_mov_b64 v[100:101], v[180:181]
	v_mov_b64 v[102:103], v[182:183]
	v_cvt_f32_f16_e32 v104, v100
	v_cvt_f32_f16_sdwa v100, v100 dst_sel:DWORD dst_unused:UNUSED_PAD src0_sel:WORD_1
	v_mul_f32_e32 v104, 0x38800000, v104
	v_mul_f32_e32 v100, 0x38800000, v100
	v_pk_mul_f32 v[106:107], v[106:107], v[100:101] op_sel_hi:[1,0]
	v_cvt_f32_f16_e32 v100, v101
	v_cvt_f32_f16_sdwa v101, v101 dst_sel:DWORD dst_unused:UNUSED_PAD src0_sel:WORD_1
	v_pk_fma_f32 v[98:99], v[98:99], v[104:105], v[106:107] op_sel_hi:[1,0,1]
	v_xor_b32_e32 v106, 0x80000000, v97
	v_mov_b32_e32 v107, v96
	v_mul_f32_e32 v104, 0x38800000, v101
	v_mul_f32_e32 v100, 0x38800000, v100
	v_pk_mul_f32 v[104:105], v[106:107], v[104:105] op_sel_hi:[1,0]
	v_xor_b32_e32 v106, 0x80000000, v83
	v_pk_fma_f32 v[96:97], v[96:97], v[100:101], v[104:105] op_sel_hi:[1,0,1]
	v_cvt_f32_f16_sdwa v101, v102 dst_sel:DWORD dst_unused:UNUSED_PAD src0_sel:WORD_1
	v_cvt_f32_f16_e32 v100, v102
	s_nop 0
	s_nop 0
	v_mul_f32_e32 v102, 0x38800000, v101
	v_mul_f32_e32 v100, 0x38800000, v100
	v_pk_mul_f32 v[104:105], v[94:95], v[102:103] op_sel:[1,0] op_sel_hi:[0,0] neg_lo:[1,0]
	v_mov_b32_e32 v107, v82
	v_pk_fma_f32 v[94:95], v[94:95], v[100:101], v[104:105] op_sel_hi:[1,0,1]
	v_cvt_f32_f16_sdwa v101, v103 dst_sel:DWORD dst_unused:UNUSED_PAD src0_sel:WORD_1
	v_cvt_f32_f16_e32 v100, v103
	v_xor_b32_e32 v104, 0x80000000, v93
	v_mov_b32_e32 v105, v92
	v_mul_f32_e32 v102, 0x38800000, v101
	v_mul_f32_e32 v100, 0x38800000, v100
	v_pk_mul_f32 v[102:103], v[104:105], v[102:103] op_sel_hi:[1,0]
	s_nop 0
	v_pk_fma_f32 v[92:93], v[92:93], v[100:101], v[102:103] op_sel_hi:[1,0,1]
	s_waitcnt vmcnt(2)
	v_mov_b64 v[100:101], v[184:185]
	v_mov_b64 v[102:103], v[186:187]
	v_cvt_f32_f16_e32 v104, v100
	v_cvt_f32_f16_sdwa v100, v100 dst_sel:DWORD dst_unused:UNUSED_PAD src0_sel:WORD_1
	v_mul_f32_e32 v104, 0x38800000, v104
	v_mul_f32_e32 v100, 0x38800000, v100
	v_pk_mul_f32 v[106:107], v[106:107], v[100:101] op_sel_hi:[1,0]
	v_cvt_f32_f16_e32 v100, v101
	v_cvt_f32_f16_sdwa v101, v101 dst_sel:DWORD dst_unused:UNUSED_PAD src0_sel:WORD_1
	v_pk_fma_f32 v[82:83], v[82:83], v[104:105], v[106:107] op_sel_hi:[1,0,1]
	v_xor_b32_e32 v106, 0x80000000, v81
	v_mov_b32_e32 v107, v80
	v_mul_f32_e32 v104, 0x38800000, v101
	v_mul_f32_e32 v100, 0x38800000, v100
	v_pk_mul_f32 v[104:105], v[106:107], v[104:105] op_sel_hi:[1,0]
	v_xor_b32_e32 v106, 0x80000000, v67
	v_pk_fma_f32 v[80:81], v[80:81], v[100:101], v[104:105] op_sel_hi:[1,0,1]
	v_cvt_f32_f16_sdwa v101, v102 dst_sel:DWORD dst_unused:UNUSED_PAD src0_sel:WORD_1
	v_cvt_f32_f16_e32 v100, v102
	s_nop 0
	s_nop 0
	v_mul_f32_e32 v102, 0x38800000, v101
	v_mul_f32_e32 v100, 0x38800000, v100
	v_pk_mul_f32 v[104:105], v[78:79], v[102:103] op_sel:[1,0] op_sel_hi:[0,0] neg_lo:[1,0]
	v_mov_b32_e32 v107, v66
	v_pk_fma_f32 v[78:79], v[78:79], v[100:101], v[104:105] op_sel_hi:[1,0,1]
	v_cvt_f32_f16_sdwa v101, v103 dst_sel:DWORD dst_unused:UNUSED_PAD src0_sel:WORD_1
	v_cvt_f32_f16_e32 v100, v103
	v_xor_b32_e32 v104, 0x80000000, v77
	v_mov_b32_e32 v105, v76
	v_mul_f32_e32 v102, 0x38800000, v101
	v_mul_f32_e32 v100, 0x38800000, v100
	v_pk_mul_f32 v[102:103], v[104:105], v[102:103] op_sel_hi:[1,0]
	s_nop 0
	v_pk_fma_f32 v[76:77], v[76:77], v[100:101], v[102:103] op_sel_hi:[1,0,1]
	s_waitcnt vmcnt(1)
	v_mov_b64 v[100:101], v[188:189]
	v_mov_b64 v[102:103], v[190:191]
	v_cvt_f32_f16_e32 v104, v100
	v_cvt_f32_f16_sdwa v100, v100 dst_sel:DWORD dst_unused:UNUSED_PAD src0_sel:WORD_1
	v_mul_f32_e32 v104, 0x38800000, v104
	v_mul_f32_e32 v100, 0x38800000, v100
	v_pk_mul_f32 v[106:107], v[106:107], v[100:101] op_sel_hi:[1,0]
	v_cvt_f32_f16_e32 v100, v101
	v_cvt_f32_f16_sdwa v101, v101 dst_sel:DWORD dst_unused:UNUSED_PAD src0_sel:WORD_1
	v_pk_fma_f32 v[66:67], v[66:67], v[104:105], v[106:107] op_sel_hi:[1,0,1]
	v_xor_b32_e32 v106, 0x80000000, v65
	v_mov_b32_e32 v107, v64
	v_mul_f32_e32 v104, 0x38800000, v101
	v_mul_f32_e32 v100, 0x38800000, v100
	v_pk_mul_f32 v[104:105], v[106:107], v[104:105] op_sel_hi:[1,0]
	s_nop 0
	v_pk_fma_f32 v[64:65], v[64:65], v[100:101], v[104:105] op_sel_hi:[1,0,1]
	v_cvt_f32_f16_sdwa v101, v102 dst_sel:DWORD dst_unused:UNUSED_PAD src0_sel:WORD_1
	v_cvt_f32_f16_e32 v100, v102
	s_nop 0
	s_nop 0
	v_mul_f32_e32 v102, 0x38800000, v101
	v_mul_f32_e32 v100, 0x38800000, v100
	v_pk_mul_f32 v[104:105], v[62:63], v[102:103] op_sel:[1,0] op_sel_hi:[0,0] neg_lo:[1,0]
	s_nop 0
	v_pk_fma_f32 v[62:63], v[62:63], v[100:101], v[104:105] op_sel_hi:[1,0,1]
	v_cvt_f32_f16_sdwa v101, v103 dst_sel:DWORD dst_unused:UNUSED_PAD src0_sel:WORD_1
	v_cvt_f32_f16_e32 v100, v103
	v_xor_b32_e32 v104, 0x80000000, v3
	v_mov_b32_e32 v105, v2
	v_mul_f32_e32 v102, 0x38800000, v101
	v_mul_f32_e32 v100, 0x38800000, v100
	v_pk_mul_f32 v[102:103], v[104:105], v[102:103] op_sel_hi:[1,0]
	v_xor_b32_e32 v104, 0x80000000, v11
	v_pk_fma_f32 v[100:101], v[2:3], v[100:101], v[102:103] op_sel_hi:[1,0,1]
	s_waitcnt vmcnt(0)
	v_mov_b64 v[0:1], v[192:193]
	v_mov_b64 v[2:3], v[194:195]
	v_mov_b32_e32 v105, v10
	v_cvt_f32_f16_e32 v102, v0
	v_cvt_f32_f16_sdwa v0, v0 dst_sel:DWORD dst_unused:UNUSED_PAD src0_sel:WORD_1
	v_mul_f32_e32 v102, 0x38800000, v102
	v_mul_f32_e32 v0, 0x38800000, v0
	v_pk_mul_f32 v[104:105], v[104:105], v[0:1] op_sel_hi:[1,0]
	v_cvt_f32_f16_e32 v0, v1
	v_cvt_f32_f16_sdwa v1, v1 dst_sel:DWORD dst_unused:UNUSED_PAD src0_sel:WORD_1
	v_pk_fma_f32 v[10:11], v[10:11], v[102:103], v[104:105] op_sel_hi:[1,0,1]
	v_xor_b32_e32 v104, 0x80000000, v9
	v_mov_b32_e32 v105, v8
	v_mul_f32_e32 v102, 0x38800000, v1
	v_mul_f32_e32 v0, 0x38800000, v0
	v_pk_mul_f32 v[102:103], v[104:105], v[102:103] op_sel_hi:[1,0]
	s_nop 0
	v_pk_fma_f32 v[0:1], v[8:9], v[0:1], v[102:103] op_sel_hi:[1,0,1]
	v_cvt_f32_f16_e32 v8, v2
	v_cvt_f32_f16_sdwa v2, v2 dst_sel:DWORD dst_unused:UNUSED_PAD src0_sel:WORD_1
	s_nop 0
	s_nop 0
	v_mul_f32_e32 v8, 0x38800000, v8
	v_mul_f32_e32 v2, 0x38800000, v2
	s_nop 0
	v_pk_mul_f32 v[102:103], v[6:7], v[2:3] op_sel:[1,0] op_sel_hi:[0,0] neg_lo:[1,0]
	v_cvt_f32_f16_e32 v2, v3
	v_cvt_f32_f16_sdwa v3, v3 dst_sel:DWORD dst_unused:UNUSED_PAD src0_sel:WORD_1
	v_pk_fma_f32 v[6:7], v[6:7], v[8:9], v[102:103] op_sel_hi:[1,0,1]
	v_xor_b32_e32 v102, 0x80000000, v5
	v_mov_b32_e32 v103, v4
	v_mul_f32_e32 v8, 0x38800000, v3
	v_mul_f32_e32 v2, 0x38800000, v2
	v_pk_mul_f32 v[8:9], v[102:103], v[8:9] op_sel_hi:[1,0]
	v_mov_b32_e32 v102, v146
	v_pk_fma_f32 v[2:3], v[4:5], v[2:3], v[8:9] op_sel_hi:[1,0,1]
	v_pk_add_f32 v[4:5], v[12:13], v[14:15]
	v_pk_add_f32 v[8:9], v[12:13], v[14:15] neg_lo:[0,1] neg_hi:[0,1]
	v_pk_add_f32 v[12:13], v[16:17], v[18:19]
	v_pk_add_f32 v[14:15], v[16:17], v[18:19] neg_lo:[0,1] neg_hi:[0,1]
	v_pk_add_f32 v[16:17], v[20:21], v[22:23]
	v_pk_add_f32 v[18:19], v[20:21], v[22:23] neg_lo:[0,1] neg_hi:[0,1]
	v_pk_add_f32 v[20:21], v[24:25], v[26:27]
	v_pk_add_f32 v[22:23], v[24:25], v[26:27] neg_lo:[0,1] neg_hi:[0,1]
	v_pk_add_f32 v[24:25], v[68:69], v[70:71]
	v_pk_add_f32 v[26:27], v[68:69], v[70:71] neg_lo:[0,1] neg_hi:[0,1]
	v_pk_add_f32 v[68:69], v[72:73], v[74:75]
	v_pk_add_f32 v[70:71], v[72:73], v[74:75] neg_lo:[0,1] neg_hi:[0,1]
	v_pk_add_f32 v[72:73], v[84:85], v[86:87]
	v_pk_add_f32 v[74:75], v[84:85], v[86:87] neg_lo:[0,1] neg_hi:[0,1]
	v_pk_add_f32 v[84:85], v[88:89], v[90:91]
	v_pk_add_f32 v[86:87], v[88:89], v[90:91] neg_lo:[0,1] neg_hi:[0,1]
	v_pk_add_f32 v[88:89], v[4:5], v[12:13]
	v_pk_add_f32 v[4:5], v[4:5], v[12:13] neg_lo:[0,1] neg_hi:[0,1]
	v_xor_b32_e32 v12, 0x80000000, v15
	v_mov_b32_e32 v13, v14
	v_pk_add_f32 v[14:15], v[8:9], v[12:13]
	v_pk_add_f32 v[8:9], v[8:9], v[12:13] neg_lo:[0,1] neg_hi:[0,1]
	v_pk_add_f32 v[12:13], v[16:17], v[20:21]
	v_pk_add_f32 v[16:17], v[16:17], v[20:21] neg_lo:[0,1] neg_hi:[0,1]
	v_xor_b32_e32 v20, 0x80000000, v23
	v_mov_b32_e32 v21, v22
	v_pk_add_f32 v[22:23], v[18:19], v[20:21]
	v_pk_add_f32 v[18:19], v[18:19], v[20:21] neg_lo:[0,1] neg_hi:[0,1]
	v_pk_add_f32 v[20:21], v[24:25], v[68:69]
	v_pk_add_f32 v[24:25], v[24:25], v[68:69] neg_lo:[0,1] neg_hi:[0,1]
	v_xor_b32_e32 v68, 0x80000000, v71
	v_mov_b32_e32 v69, v70
	v_pk_add_f32 v[70:71], v[26:27], v[68:69]
	v_pk_add_f32 v[26:27], v[26:27], v[68:69] neg_lo:[0,1] neg_hi:[0,1]
	v_pk_add_f32 v[68:69], v[72:73], v[84:85]
	v_pk_add_f32 v[72:73], v[72:73], v[84:85] neg_lo:[0,1] neg_hi:[0,1]
	v_xor_b32_e32 v84, 0x80000000, v87
	v_mov_b32_e32 v85, v86
	v_pk_add_f32 v[86:87], v[74:75], v[84:85]
	v_pk_add_f32 v[74:75], v[74:75], v[84:85] neg_lo:[0,1] neg_hi:[0,1]
	v_pk_add_f32 v[84:85], v[88:89], v[12:13]
	v_pk_add_f32 v[12:13], v[88:89], v[12:13] neg_lo:[0,1] neg_hi:[0,1]
	v_pk_mul_f32 v[88:89], v[22:23], s[60:61] op_sel:[1,0] op_sel_hi:[0,0] neg_lo:[1,0]
	v_xor_b32_e32 v90, 0x80000000, v19
	v_pk_fma_f32 v[22:23], v[22:23], s[60:61], v[88:89] op_sel_hi:[1,0,1]
	v_mov_b32_e32 v91, v18
	v_pk_add_f32 v[88:89], v[14:15], v[22:23]
	v_pk_add_f32 v[14:15], v[14:15], v[22:23] neg_lo:[0,1] neg_hi:[0,1]
	v_xor_b32_e32 v22, 0x80000000, v17
	v_mov_b32_e32 v23, v16
	v_pk_add_f32 v[16:17], v[4:5], v[22:23]
	v_pk_add_f32 v[4:5], v[4:5], v[22:23] neg_lo:[0,1] neg_hi:[0,1]
	v_pk_mul_f32 v[22:23], v[18:19], s[60:61] op_sel_hi:[1,0]
	s_nop 0
	v_pk_fma_f32 v[18:19], v[90:91], s[60:61], v[22:23] op_sel_hi:[1,0,1] neg_lo:[0,0,1] neg_hi:[0,0,1]
	v_xor_b32_e32 v90, 0x80000000, v75
	v_pk_add_f32 v[22:23], v[8:9], v[18:19]
	v_pk_add_f32 v[8:9], v[8:9], v[18:19] neg_lo:[0,1] neg_hi:[0,1]
	v_pk_add_f32 v[18:19], v[20:21], v[68:69]
	v_pk_add_f32 v[20:21], v[20:21], v[68:69] neg_lo:[0,1] neg_hi:[0,1]
	v_pk_mul_f32 v[68:69], v[86:87], s[60:61] op_sel:[1,0] op_sel_hi:[0,0] neg_lo:[1,0]
	v_mov_b32_e32 v91, v74
	v_pk_fma_f32 v[68:69], v[86:87], s[60:61], v[68:69] op_sel_hi:[1,0,1]
	v_pk_add_f32 v[86:87], v[70:71], v[68:69]
	v_pk_add_f32 v[68:69], v[70:71], v[68:69] neg_lo:[0,1] neg_hi:[0,1]
	v_xor_b32_e32 v70, 0x80000000, v73
	v_mov_b32_e32 v71, v72
	v_pk_add_f32 v[72:73], v[24:25], v[70:71]
	v_pk_add_f32 v[24:25], v[24:25], v[70:71] neg_lo:[0,1] neg_hi:[0,1]
	v_pk_mul_f32 v[70:71], v[74:75], s[60:61] op_sel_hi:[1,0]
	v_pk_fma_f32 v[70:71], v[90:91], s[60:61], v[70:71] op_sel_hi:[1,0,1] neg_lo:[0,0,1] neg_hi:[0,0,1]
	v_xor_b32_e32 v90, 0x80000000, v69
	v_pk_add_f32 v[74:75], v[26:27], v[70:71]
	v_pk_add_f32 v[26:27], v[26:27], v[70:71] neg_lo:[0,1] neg_hi:[0,1]
	v_pk_add_f32 v[70:71], v[84:85], v[18:19]
	v_pk_add_f32 v[18:19], v[84:85], v[18:19] neg_lo:[0,1] neg_hi:[0,1]
	v_pk_mul_f32 v[84:85], v[86:87], s[54:55] op_sel:[1,0] op_sel_hi:[0,0] neg_lo:[1,0]
	v_mov_b32_e32 v91, v68
	v_pk_fma_f32 v[84:85], v[86:87], s[52:53], v[84:85] op_sel_hi:[1,0,1]
	v_pk_add_f32 v[86:87], v[88:89], v[84:85]
	v_pk_add_f32 v[84:85], v[88:89], v[84:85] neg_lo:[0,1] neg_hi:[0,1]
	v_pk_mul_f32 v[88:89], v[72:73], s[60:61] op_sel:[1,0] op_sel_hi:[0,0] neg_lo:[1,0]
	v_pk_fma_f32 v[72:73], v[72:73], s[60:61], v[88:89] op_sel_hi:[1,0,1]
	v_pk_add_f32 v[88:89], v[16:17], v[72:73]
	v_pk_add_f32 v[16:17], v[16:17], v[72:73] neg_lo:[0,1] neg_hi:[0,1]
	v_pk_mul_f32 v[72:73], v[74:75], s[52:53] op_sel:[1,0] op_sel_hi:[0,0] neg_lo:[1,0]
	v_pk_fma_f32 v[72:73], v[74:75], s[54:55], v[72:73] op_sel_hi:[1,0,1]
	v_pk_add_f32 v[74:75], v[22:23], v[72:73]
	v_pk_add_f32 v[22:23], v[22:23], v[72:73] neg_lo:[0,1] neg_hi:[0,1]
	v_xor_b32_e32 v72, 0x80000000, v21
	v_mov_b32_e32 v73, v20
	v_pk_add_f32 v[20:21], v[12:13], v[72:73]
	v_pk_add_f32 v[12:13], v[12:13], v[72:73] neg_lo:[0,1] neg_hi:[0,1]
	v_pk_mul_f32 v[72:73], v[68:69], s[54:55] op_sel_hi:[1,0]
	v_pk_fma_f32 v[68:69], v[90:91], s[52:53], v[72:73] op_sel_hi:[1,0,1] neg_lo:[0,0,1] neg_hi:[0,0,1]
	v_xor_b32_e32 v90, 0x80000000, v25
	v_pk_add_f32 v[72:73], v[14:15], v[68:69]
	v_pk_add_f32 v[14:15], v[14:15], v[68:69] neg_lo:[0,1] neg_hi:[0,1]
	v_pk_mul_f32 v[68:69], v[24:25], s[60:61] op_sel_hi:[1,0]
	v_mov_b32_e32 v91, v24
	v_pk_fma_f32 v[24:25], v[90:91], s[60:61], v[68:69] op_sel_hi:[1,0,1] neg_lo:[0,0,1] neg_hi:[0,0,1]
	v_pk_add_f32 v[68:69], v[4:5], v[24:25]
	v_pk_add_f32 v[4:5], v[4:5], v[24:25] neg_lo:[0,1] neg_hi:[0,1]
	v_pk_mul_f32 v[24:25], v[26:27], s[52:53] op_sel_hi:[1,0]
	v_pk_fma_f32 v[24:25], v[26:27], s[54:55], v[24:25] op_sel:[1,0,0] op_sel_hi:[0,0,1] neg_lo:[1,0,1] neg_hi:[0,0,1]
	v_pk_add_f32 v[90:91], v[98:99], v[96:97] neg_lo:[0,1] neg_hi:[0,1]
	v_pk_add_f32 v[26:27], v[8:9], v[24:25]
	v_pk_add_f32 v[8:9], v[8:9], v[24:25] neg_lo:[0,1] neg_hi:[0,1]
	v_pk_add_f32 v[24:25], v[98:99], v[96:97]
	v_pk_add_f32 v[96:97], v[94:95], v[92:93]
	v_pk_add_f32 v[92:93], v[94:95], v[92:93] neg_lo:[0,1] neg_hi:[0,1]
	v_pk_add_f32 v[94:95], v[82:83], v[80:81]
	v_pk_add_f32 v[80:81], v[82:83], v[80:81] neg_lo:[0,1] neg_hi:[0,1]
	v_pk_add_f32 v[82:83], v[78:79], v[76:77]
	v_pk_add_f32 v[76:77], v[78:79], v[76:77] neg_lo:[0,1] neg_hi:[0,1]
	v_pk_add_f32 v[98:99], v[10:11], v[0:1]
	v_pk_add_f32 v[0:1], v[10:11], v[0:1] neg_lo:[0,1] neg_hi:[0,1]
	v_pk_add_f32 v[10:11], v[6:7], v[2:3]
	v_pk_add_f32 v[2:3], v[6:7], v[2:3] neg_lo:[0,1] neg_hi:[0,1]
	v_pk_add_f32 v[6:7], v[24:25], v[96:97]
	v_pk_add_f32 v[24:25], v[24:25], v[96:97] neg_lo:[0,1] neg_hi:[0,1]
	v_xor_b32_e32 v96, 0x80000000, v93
	v_mov_b32_e32 v97, v92
	v_pk_add_f32 v[78:79], v[66:67], v[64:65]
	v_pk_add_f32 v[64:65], v[66:67], v[64:65] neg_lo:[0,1] neg_hi:[0,1]
	v_pk_add_f32 v[66:67], v[62:63], v[100:101]
	v_pk_add_f32 v[62:63], v[62:63], v[100:101] neg_lo:[0,1] neg_hi:[0,1]
	v_pk_add_f32 v[92:93], v[90:91], v[96:97]
	v_pk_add_f32 v[90:91], v[90:91], v[96:97] neg_lo:[0,1] neg_hi:[0,1]
	v_pk_add_f32 v[96:97], v[94:95], v[82:83]
	v_pk_add_f32 v[82:83], v[94:95], v[82:83] neg_lo:[0,1] neg_hi:[0,1]
	v_xor_b32_e32 v94, 0x80000000, v77
	v_mov_b32_e32 v95, v76
	v_pk_add_f32 v[76:77], v[80:81], v[94:95]
	v_pk_add_f32 v[80:81], v[80:81], v[94:95] neg_lo:[0,1] neg_hi:[0,1]
	v_pk_add_f32 v[94:95], v[78:79], v[66:67]
	v_pk_add_f32 v[66:67], v[78:79], v[66:67] neg_lo:[0,1] neg_hi:[0,1]
	v_xor_b32_e32 v78, 0x80000000, v63
	v_mov_b32_e32 v79, v62
	v_pk_add_f32 v[62:63], v[64:65], v[78:79]
	v_pk_add_f32 v[64:65], v[64:65], v[78:79] neg_lo:[0,1] neg_hi:[0,1]
	v_pk_add_f32 v[78:79], v[98:99], v[10:11]
	v_pk_add_f32 v[10:11], v[98:99], v[10:11] neg_lo:[0,1] neg_hi:[0,1]
	v_xor_b32_e32 v98, 0x80000000, v3
	v_mov_b32_e32 v99, v2
	v_pk_add_f32 v[2:3], v[0:1], v[98:99]
	v_pk_add_f32 v[0:1], v[0:1], v[98:99] neg_lo:[0,1] neg_hi:[0,1]
	v_pk_add_f32 v[98:99], v[6:7], v[96:97]
	v_pk_add_f32 v[6:7], v[6:7], v[96:97] neg_lo:[0,1] neg_hi:[0,1]
	v_pk_mul_f32 v[96:97], v[76:77], s[60:61] op_sel:[1,0] op_sel_hi:[0,0] neg_lo:[1,0]
	v_xor_b32_e32 v100, 0x80000000, v81
	v_pk_fma_f32 v[76:77], v[76:77], s[60:61], v[96:97] op_sel_hi:[1,0,1]
	v_mov_b32_e32 v101, v80
	v_pk_add_f32 v[96:97], v[92:93], v[76:77]
	v_pk_add_f32 v[76:77], v[92:93], v[76:77] neg_lo:[0,1] neg_hi:[0,1]
	v_xor_b32_e32 v92, 0x80000000, v83
	v_mov_b32_e32 v93, v82
	v_pk_add_f32 v[82:83], v[24:25], v[92:93]
	v_pk_add_f32 v[24:25], v[24:25], v[92:93] neg_lo:[0,1] neg_hi:[0,1]
	v_pk_mul_f32 v[92:93], v[80:81], s[60:61] op_sel_hi:[1,0]
	v_pk_fma_f32 v[80:81], v[100:101], s[60:61], v[92:93] op_sel_hi:[1,0,1] neg_lo:[0,0,1] neg_hi:[0,0,1]
	v_xor_b32_e32 v100, 0x80000000, v1
	v_pk_add_f32 v[92:93], v[90:91], v[80:81]
	v_pk_add_f32 v[80:81], v[90:91], v[80:81] neg_lo:[0,1] neg_hi:[0,1]
	v_pk_add_f32 v[90:91], v[94:95], v[78:79]
	v_pk_add_f32 v[78:79], v[94:95], v[78:79] neg_lo:[0,1] neg_hi:[0,1]
	v_pk_mul_f32 v[94:95], v[2:3], s[60:61] op_sel:[1,0] op_sel_hi:[0,0] neg_lo:[1,0]
	v_mov_b32_e32 v101, v0
	v_pk_fma_f32 v[2:3], v[2:3], s[60:61], v[94:95] op_sel_hi:[1,0,1]
	v_pk_add_f32 v[94:95], v[62:63], v[2:3]
	v_pk_add_f32 v[2:3], v[62:63], v[2:3] neg_lo:[0,1] neg_hi:[0,1]
	v_xor_b32_e32 v62, 0x80000000, v11
	v_mov_b32_e32 v63, v10
	v_pk_add_f32 v[10:11], v[66:67], v[62:63]
	v_pk_add_f32 v[62:63], v[66:67], v[62:63] neg_lo:[0,1] neg_hi:[0,1]
	v_pk_mul_f32 v[66:67], v[0:1], s[60:61] op_sel_hi:[1,0]
	v_pk_fma_f32 v[0:1], v[100:101], s[60:61], v[66:67] op_sel_hi:[1,0,1] neg_lo:[0,0,1] neg_hi:[0,0,1]
	v_xor_b32_e32 v100, 0x80000000, v3
	v_pk_add_f32 v[66:67], v[64:65], v[0:1]
	v_pk_add_f32 v[0:1], v[64:65], v[0:1] neg_lo:[0,1] neg_hi:[0,1]
	v_pk_add_f32 v[64:65], v[98:99], v[90:91]
	v_pk_add_f32 v[90:91], v[98:99], v[90:91] neg_lo:[0,1] neg_hi:[0,1]
	v_pk_mul_f32 v[98:99], v[94:95], s[54:55] op_sel:[1,0] op_sel_hi:[0,0] neg_lo:[1,0]
	v_mov_b32_e32 v101, v2
	v_pk_fma_f32 v[94:95], v[94:95], s[52:53], v[98:99] op_sel_hi:[1,0,1]
	v_pk_add_f32 v[98:99], v[96:97], v[94:95]
	v_pk_add_f32 v[94:95], v[96:97], v[94:95] neg_lo:[0,1] neg_hi:[0,1]
	v_pk_mul_f32 v[96:97], v[10:11], s[60:61] op_sel:[1,0] op_sel_hi:[0,0] neg_lo:[1,0]
	v_pk_fma_f32 v[10:11], v[10:11], s[60:61], v[96:97] op_sel_hi:[1,0,1]
	v_pk_add_f32 v[96:97], v[82:83], v[10:11]
	v_pk_add_f32 v[10:11], v[82:83], v[10:11] neg_lo:[0,1] neg_hi:[0,1]
	v_pk_mul_f32 v[82:83], v[66:67], s[52:53] op_sel:[1,0] op_sel_hi:[0,0] neg_lo:[1,0]
	v_pk_fma_f32 v[66:67], v[66:67], s[54:55], v[82:83] op_sel_hi:[1,0,1]
	v_pk_add_f32 v[82:83], v[92:93], v[66:67]
	v_pk_add_f32 v[66:67], v[92:93], v[66:67] neg_lo:[0,1] neg_hi:[0,1]
	v_xor_b32_e32 v92, 0x80000000, v79
	v_mov_b32_e32 v93, v78
	v_pk_add_f32 v[78:79], v[6:7], v[92:93]
	v_pk_add_f32 v[6:7], v[6:7], v[92:93] neg_lo:[0,1] neg_hi:[0,1]
	v_pk_mul_f32 v[92:93], v[2:3], s[54:55] op_sel_hi:[1,0]
	v_pk_fma_f32 v[2:3], v[100:101], s[52:53], v[92:93] op_sel_hi:[1,0,1] neg_lo:[0,0,1] neg_hi:[0,0,1]
	v_xor_b32_e32 v100, 0x80000000, v63
	v_pk_add_f32 v[92:93], v[76:77], v[2:3]
	v_pk_add_f32 v[2:3], v[76:77], v[2:3] neg_lo:[0,1] neg_hi:[0,1]
	v_pk_mul_f32 v[76:77], v[62:63], s[60:61] op_sel_hi:[1,0]
	v_mov_b32_e32 v101, v62
	v_pk_fma_f32 v[62:63], v[100:101], s[60:61], v[76:77] op_sel_hi:[1,0,1] neg_lo:[0,0,1] neg_hi:[0,0,1]
	v_xor_b32_e32 v100, 0x80000000, v1
	v_pk_add_f32 v[76:77], v[24:25], v[62:63]
	v_pk_add_f32 v[24:25], v[24:25], v[62:63] neg_lo:[0,1] neg_hi:[0,1]
	v_pk_mul_f32 v[62:63], v[0:1], s[52:53] op_sel_hi:[1,0]
	v_mov_b32_e32 v101, v0
	v_pk_fma_f32 v[0:1], v[100:101], s[54:55], v[62:63] op_sel_hi:[1,0,1] neg_lo:[0,0,1] neg_hi:[0,0,1]
	v_bfe_u32 v100, v102, 1, 4
	v_pk_add_f32 v[62:63], v[80:81], v[0:1]
	v_pk_add_f32 v[0:1], v[80:81], v[0:1] neg_lo:[0,1] neg_hi:[0,1]
	v_lshlrev_b32_e32 v80, 4, v102
	v_lshrrev_b32_e32 v81, 1, v102
	v_bitop3_b32 v101, v81, v80, 16 bitop3:0x6c
	v_lshl_add_u32 v101, v101, 3, 16
	v_lshlrev_b32_e32 v100, 3, v100
	v_add_u32_e32 v102, v101, v100
	ds_write_b64 v102, v[70:71]
	v_bitop3_b32 v70, v81, 1, 15 bitop3:0x6c
	v_lshlrev_b32_e32 v70, 3, v70
	v_add_u32_e32 v71, v101, v70
	ds_write_b64 v71, v[86:87]
	v_bitop3_b32 v71, v81, 2, 15 bitop3:0x6c
	v_lshlrev_b32_e32 v71, 3, v71
	v_add_u32_e32 v86, v101, v71
	ds_write_b64 v86, v[88:89]
	v_bitop3_b32 v86, v81, 3, 15 bitop3:0x6c
	v_lshlrev_b32_e32 v86, 3, v86
	v_add_u32_e32 v87, v101, v86
	ds_write_b64 v87, v[74:75]
	v_bitop3_b32 v74, v81, 4, 15 bitop3:0x6c
	v_lshlrev_b32_e32 v74, 3, v74
	v_add_u32_e32 v75, v101, v74
	ds_write_b64 v75, v[20:21]
	v_bitop3_b32 v20, v81, 5, 15 bitop3:0x6c
	v_lshlrev_b32_e32 v20, 3, v20
	v_add_u32_e32 v21, v101, v20
	ds_write_b64 v21, v[72:73]
	v_bitop3_b32 v21, v81, 6, 15 bitop3:0x6c
	v_lshlrev_b32_e32 v21, 3, v21
	v_add_u32_e32 v72, v101, v21
	ds_write_b64 v72, v[68:69]
	v_bitop3_b32 v68, v81, 7, 15 bitop3:0x6c
	v_lshlrev_b32_e32 v68, 3, v68
	v_add_u32_e32 v69, v101, v68
	ds_write_b64 v69, v[26:27]
	v_bitop3_b32 v26, v81, 8, 15 bitop3:0x6c
	v_lshlrev_b32_e32 v26, 3, v26
	v_add_u32_e32 v27, v101, v26
	ds_write_b64 v27, v[18:19]
	v_bitop3_b32 v18, v81, 9, 15 bitop3:0x6c
	v_lshlrev_b32_e32 v18, 3, v18
	v_add_u32_e32 v19, v101, v18
	ds_write_b64 v19, v[84:85]
	v_bitop3_b32 v19, v81, 10, 15 bitop3:0x6c
	v_lshlrev_b32_e32 v19, 3, v19
	v_add_u32_e32 v27, v101, v19
	ds_write_b64 v27, v[16:17]
	v_bitop3_b32 v16, v81, 11, 15 bitop3:0x6c
	v_lshlrev_b32_e32 v16, 3, v16
	v_add_u32_e32 v17, v101, v16
	ds_write_b64 v17, v[22:23]
	v_bitop3_b32 v17, v81, 12, 15 bitop3:0x6c
	v_lshlrev_b32_e32 v17, 3, v17
	v_add_u32_e32 v22, v101, v17
	ds_write_b64 v22, v[12:13]
	v_bitop3_b32 v12, v81, 13, 15 bitop3:0x6c
	v_lshlrev_b32_e32 v12, 3, v12
	v_add_u32_e32 v13, v101, v12
	ds_write_b64 v13, v[14:15]
	v_bitop3_b32 v13, v81, 14, 15 bitop3:0x6c
	v_lshlrev_b32_e32 v13, 3, v13
	v_add_u32_e32 v14, v101, v13
	ds_write_b64 v14, v[4:5]
	v_bitop3_b32 v4, v81, 15, v81 bitop3:0xc
	v_lshlrev_b32_e32 v4, 3, v4
	v_add_u32_e32 v5, v101, v4
	ds_write_b64 v5, v[8:9]
	v_add_u32_e32 v5, 0x2000, v80
	v_bitop3_b32 v5, v5, v81, 16 bitop3:0x78
	v_lshl_add_u32 v5, v5, 3, 16
	v_add_u32_e32 v8, v5, v100
	ds_write_b64 v8, v[64:65]
	v_add_u32_e32 v8, v5, v70
	ds_write_b64 v8, v[98:99]
	v_add_u32_e32 v8, v5, v71
	ds_write_b64 v8, v[96:97]
	v_add_u32_e32 v8, v5, v86
	ds_write_b64 v8, v[82:83]
	v_add_u32_e32 v8, v5, v74
	ds_write_b64 v8, v[78:79]
	v_add_u32_e32 v8, v5, v20
	ds_write_b64 v8, v[92:93]
	v_add_u32_e32 v8, v5, v21
	ds_write_b64 v8, v[76:77]
	v_add_u32_e32 v8, v5, v68
	ds_write_b64 v8, v[62:63]
	v_add_u32_e32 v8, v5, v26
	ds_write_b64 v8, v[90:91]
	v_add_u32_e32 v8, v5, v18
	ds_write_b64 v8, v[94:95]
	v_add_u32_e32 v8, v5, v19
	ds_write_b64 v8, v[10:11]
	v_add_u32_e32 v8, v5, v16
	ds_write_b64 v8, v[66:67]
	v_add_u32_e32 v8, v5, v17
	ds_write_b64 v8, v[6:7]
	v_add_u32_e32 v6, v5, v12
	ds_write_b64 v6, v[2:3]
	v_add_u32_e32 v2, v5, v13
	ds_write_b64 v2, v[24:25]
	v_add_u32_e32 v2, v5, v4
	v_mov_b32_e32 v22, v146
	ds_write_b64 v2, v[0:1]
	s_waitcnt lgkmcnt(0)
	s_barrier
	s_nop 0
	v_lshlrev_b32_e32 v0, 5, v22
	v_and_b32_e32 v2, 0xfffffe00, v0
	v_and_or_b32 v0, v22, 16, v2
	v_bitop3_b32 v2, v2, 16, v22 bitop3:0x34
	v_bitop3_b32 v6, v22, 4, 15 bitop3:0x6c
	v_bitop3_b32 v14, v22, 8, 15 bitop3:0x6c
	v_lshl_add_u32 v23, v0, 3, 16
	v_lshl_add_u32 v65, v2, 3, 16
	v_lshlrev_b32_e32 v6, 3, v6
	v_lshlrev_b32_e32 v14, 3, v14
	v_bitop3_b32 v2, v22, 1, 15 bitop3:0x6c
	v_add_u32_e32 v105, v23, v6
	v_add_u32_e32 v106, v65, v6
	v_bitop3_b32 v6, v22, 5, 15 bitop3:0x6c
	v_add_u32_e32 v113, v23, v14
	v_add_u32_e32 v114, v65, v14
	v_bitop3_b32 v14, v22, 9, 15 bitop3:0x6c
	v_lshlrev_b32_e32 v2, 3, v2
	v_lshlrev_b32_e32 v6, 3, v6
	v_lshlrev_b32_e32 v14, 3, v14
	v_add_u32_e32 v99, v23, v2
	v_add_u32_e32 v100, v65, v2
	v_bitop3_b32 v2, v22, 2, 15 bitop3:0x6c
	v_add_u32_e32 v107, v23, v6
	v_add_u32_e32 v108, v65, v6
	v_bitop3_b32 v6, v22, 6, 15 bitop3:0x6c
	v_add_u32_e32 v115, v23, v14
	v_add_u32_e32 v116, v65, v14
	v_bitop3_b32 v14, v22, 10, 15 bitop3:0x6c
	v_bitop3_b32 v26, v22, 12, 15 bitop3:0x6c
	v_lshlrev_b32_e32 v2, 3, v2
	v_lshlrev_b32_e32 v6, 3, v6
	v_lshlrev_b32_e32 v14, 3, v14
	v_lshlrev_b32_e32 v26, 3, v26
	v_and_b32_e32 v64, 15, v22
	v_add_u32_e32 v101, v23, v2
	v_add_u32_e32 v102, v65, v2
	v_bitop3_b32 v2, v22, 3, 15 bitop3:0x6c
	v_add_u32_e32 v109, v23, v6
	v_add_u32_e32 v110, v65, v6
	v_bitop3_b32 v6, v22, 7, 15 bitop3:0x6c
	v_add_u32_e32 v117, v23, v14
	v_add_u32_e32 v118, v65, v14
	v_bitop3_b32 v14, v22, 11, 15 bitop3:0x6c
	v_add_u32_e32 v121, v23, v26
	v_add_u32_e32 v122, v65, v26
	v_bitop3_b32 v26, v22, 13, 15 bitop3:0x6c
	v_bitop3_b32 v66, v22, 14, 15 bitop3:0x6c
	v_bitop3_b32 v22, v22, 15, v22 bitop3:0xc
	v_lshlrev_b32_e32 v3, 3, v64
	v_lshlrev_b32_e32 v2, 3, v2
	v_lshlrev_b32_e32 v6, 3, v6
	v_lshlrev_b32_e32 v14, 3, v14
	v_lshlrev_b32_e32 v26, 3, v26
	v_lshlrev_b32_e32 v66, 3, v66
	v_lshlrev_b32_e32 v22, 3, v22
	v_add_u32_e32 v67, v23, v3
	v_add_u32_e32 v98, v65, v3
	v_add_u32_e32 v103, v23, v2
	v_add_u32_e32 v104, v65, v2
	v_add_u32_e32 v111, v23, v6
	v_add_u32_e32 v112, v65, v6
	v_add_u32_e32 v119, v23, v14
	v_add_u32_e32 v120, v65, v14
	v_add_u32_e32 v123, v23, v26
	v_add_u32_e32 v124, v65, v26
	v_add_u32_e32 v125, v23, v66
	v_add_u32_e32 v126, v65, v66
	v_add_u32_e32 v127, v23, v22
	v_add_u32_e32 v128, v65, v22
	ds_read_b64 v[0:1], v67
	ds_read_b64 v[12:13], v98
	ds_read_b64 v[74:75], v99 offset:256
	ds_read_b64 v[4:5], v100 offset:256
	ds_read_b64 v[76:77], v101 offset:512
	ds_read_b64 v[10:11], v102 offset:512
	ds_read_b64 v[70:71], v103 offset:768
	ds_read_b64 v[2:3], v104 offset:768
	ds_read_b64 v[62:63], v105 offset:1024
	ds_read_b64 v[20:21], v106 offset:1024
	ds_read_b64 v[90:91], v107 offset:1280
	ds_read_b64 v[8:9], v108 offset:1280
	ds_read_b64 v[84:85], v109 offset:1536
	ds_read_b64 v[16:17], v110 offset:1536
	ds_read_b64 v[82:83], v111 offset:1792
	ds_read_b64 v[6:7], v112 offset:1792
	ds_read_b64 v[24:25], v113 offset:2048
	ds_read_b64 v[78:79], v114 offset:2048
	ds_read_b64 v[96:97], v115 offset:2304
	ds_read_b64 v[18:19], v116 offset:2304
	ds_read_b64 v[86:87], v117 offset:2560
	ds_read_b64 v[72:73], v118 offset:2560
	ds_read_b64 v[130:131], v119 offset:2816
	ds_read_b64 v[14:15], v120 offset:2816
	ds_read_b64 v[80:81], v121 offset:3072
	ds_read_b64 v[92:93], v122 offset:3072
	ds_read_b64 v[132:133], v123 offset:3328
	ds_read_b64 v[26:27], v124 offset:3328
	ds_read_b64 v[94:95], v125 offset:3584
	ds_read_b64 v[88:89], v126 offset:3584
	ds_read_b64 v[134:135], v127 offset:3840
	ds_read_b64 v[22:23], v128 offset:3840
	s_waitcnt lgkmcnt(14)
	s_nop 0
	v_cvt_f32_i32_e32 v64, v64
	s_nop 0
	v_mul_f32_e32 v64, 0x3b000000, v64
	v_cos_f32_e32 v68, v64
	v_sin_f32_e32 v69, v64
	v_add_f32_e32 v66, v68, v68
	v_pk_mul_f32 v[64:65], v[68:69], v[68:69]
	v_mul_f32_e32 v66, v69, v66
	v_mov_b32_e32 v140, v69
	v_pk_add_f32 v[64:65], v[64:65], v[64:65] op_sel:[0,1] op_sel_hi:[0,1] neg_lo:[0,1] neg_hi:[0,1]
	v_pk_mul_f32 v[136:137], v[68:69], v[66:67] op_sel:[1,0] op_sel_hi:[0,0] neg_lo:[1,0]
	v_pk_mul_f32 v[138:139], v[24:25], v[140:141] op_sel:[1,0] op_sel_hi:[0,0] neg_lo:[1,0]
	v_pk_fma_f32 v[136:137], v[68:69], v[64:65], v[136:137]
	v_pk_fma_f32 v[24:25], v[24:25], v[68:69], v[138:139] op_sel_hi:[1,0,1]
	v_pk_mul_f32 v[68:69], v[66:67], s[46:47] op_sel_hi:[0,1]
	v_pk_fma_f32 v[138:139], v[64:65], s[40:41], v[68:69]
	v_pk_mul_f32 v[68:69], v[62:63], v[138:139] op_sel:[1,1] op_sel_hi:[0,1] neg_lo:[1,0]
	v_pk_fma_f32 v[68:69], v[62:63], v[138:139], v[68:69] op_sel_hi:[1,0,1]
	v_pk_mul_f32 v[62:63], v[66:67], v[136:137] op_sel:[0,1] op_sel_hi:[0,0] neg_lo:[0,1]
	v_pk_fma_f32 v[140:141], v[64:65], v[136:137], v[62:63]
	s_waitcnt lgkmcnt(7)
	v_pk_mul_f32 v[62:63], v[80:81], v[136:137] op_sel:[1,1] op_sel_hi:[0,1] neg_lo:[1,0]
	s_nop 0
	v_pk_fma_f32 v[62:63], v[80:81], v[136:137], v[62:63] op_sel_hi:[1,0,1]
	v_pk_mul_f32 v[80:81], v[66:67], v[138:139] op_sel:[0,1] op_sel_hi:[0,0] neg_lo:[0,1]
	v_pk_fma_f32 v[136:137], v[64:65], v[138:139], v[80:81]
	v_pk_mul_f32 v[80:81], v[76:77], v[136:137] op_sel:[1,1] op_sel_hi:[0,1] neg_lo:[1,0]
	v_pk_fma_f32 v[80:81], v[76:77], v[136:137], v[80:81] op_sel_hi:[1,0,1]
	v_pk_mul_f32 v[76:77], v[66:67], v[140:141] op_sel:[0,1] op_sel_hi:[0,0] neg_lo:[0,1]
	v_pk_fma_f32 v[138:139], v[64:65], v[140:141], v[76:77]
	v_pk_mul_f32 v[76:77], v[86:87], v[140:141] op_sel:[1,1] op_sel_hi:[0,1] neg_lo:[1,0]
	v_pk_fma_f32 v[76:77], v[86:87], v[140:141], v[76:77] op_sel_hi:[1,0,1]
	v_pk_mul_f32 v[86:87], v[66:67], v[136:137] op_sel:[0,1] op_sel_hi:[0,0] neg_lo:[0,1]
	v_pk_fma_f32 v[136:137], v[64:65], v[136:137], v[86:87]
	v_pk_mul_f32 v[86:87], v[84:85], v[136:137] op_sel:[1,1] op_sel_hi:[0,1] neg_lo:[1,0]
	v_pk_fma_f32 v[86:87], v[84:85], v[136:137], v[86:87] op_sel_hi:[1,0,1]
	v_pk_mul_f32 v[84:85], v[66:67], v[138:139] op_sel:[0,1] op_sel_hi:[0,0] neg_lo:[0,1]
	v_pk_fma_f32 v[140:141], v[64:65], v[138:139], v[84:85]
	s_waitcnt lgkmcnt(3)
	v_pk_mul_f32 v[84:85], v[94:95], v[138:139] op_sel:[1,1] op_sel_hi:[0,1] neg_lo:[1,0]
	s_nop 0
	v_pk_fma_f32 v[84:85], v[94:95], v[138:139], v[84:85] op_sel_hi:[1,0,1]
	v_pk_mul_f32 v[94:95], v[66:67], v[136:137] op_sel:[0,1] op_sel_hi:[0,0] neg_lo:[0,1]
	v_pk_fma_f32 v[136:137], v[64:65], v[136:137], v[94:95]
	v_pk_mul_f32 v[94:95], v[74:75], v[136:137] op_sel:[1,1] op_sel_hi:[0,1] neg_lo:[1,0]
	v_pk_fma_f32 v[94:95], v[74:75], v[136:137], v[94:95] op_sel_hi:[1,0,1]
	v_pk_mul_f32 v[74:75], v[66:67], v[140:141] op_sel:[0,1] op_sel_hi:[0,0] neg_lo:[0,1]
	v_pk_fma_f32 v[138:139], v[64:65], v[140:141], v[74:75]
	v_pk_mul_f32 v[74:75], v[96:97], v[140:141] op_sel:[1,1] op_sel_hi:[0,1] neg_lo:[1,0]
	v_pk_fma_f32 v[74:75], v[96:97], v[140:141], v[74:75] op_sel_hi:[1,0,1]
	v_pk_mul_f32 v[96:97], v[66:67], v[136:137] op_sel:[0,1] op_sel_hi:[0,0] neg_lo:[0,1]
	v_pk_fma_f32 v[136:137], v[64:65], v[136:137], v[96:97]
	v_pk_mul_f32 v[96:97], v[90:91], v[136:137] op_sel:[1,1] op_sel_hi:[0,1] neg_lo:[1,0]
	v_pk_fma_f32 v[96:97], v[90:91], v[136:137], v[96:97] op_sel_hi:[1,0,1]
	v_pk_mul_f32 v[90:91], v[66:67], v[138:139] op_sel:[0,1] op_sel_hi:[0,0] neg_lo:[0,1]
	v_pk_fma_f32 v[140:141], v[64:65], v[138:139], v[90:91]
	v_pk_mul_f32 v[90:91], v[132:133], v[138:139] op_sel:[1,1] op_sel_hi:[0,1] neg_lo:[1,0]
	v_pk_fma_f32 v[90:91], v[132:133], v[138:139], v[90:91] op_sel_hi:[1,0,1]
	v_pk_mul_f32 v[132:133], v[66:67], v[136:137] op_sel:[0,1] op_sel_hi:[0,0] neg_lo:[0,1]
	v_pk_fma_f32 v[132:133], v[64:65], v[136:137], v[132:133]
	v_pk_mul_f32 v[138:139], v[130:131], v[140:141] op_sel:[1,1] op_sel_hi:[0,1] neg_lo:[1,0]
	v_pk_mul_f32 v[136:137], v[70:71], v[132:133] op_sel:[1,1] op_sel_hi:[0,1] neg_lo:[1,0]
	v_pk_fma_f32 v[130:131], v[130:131], v[140:141], v[138:139] op_sel_hi:[1,0,1]
	v_pk_fma_f32 v[70:71], v[70:71], v[132:133], v[136:137] op_sel_hi:[1,0,1]
	v_pk_mul_f32 v[138:139], v[66:67], v[132:133] op_sel:[0,1] op_sel_hi:[0,0] neg_lo:[0,1]
	v_pk_mul_f32 v[136:137], v[66:67], v[140:141] op_sel:[0,1] op_sel_hi:[0,0] neg_lo:[0,1]
	v_pk_fma_f32 v[132:133], v[64:65], v[132:133], v[138:139]
	v_pk_fma_f32 v[136:137], v[64:65], v[140:141], v[136:137]
	v_pk_mul_f32 v[138:139], v[82:83], v[132:133] op_sel:[1,1] op_sel_hi:[0,1] neg_lo:[1,0]
	s_waitcnt lgkmcnt(1)
	v_pk_fma_f32 v[82:83], v[82:83], v[132:133], v[138:139] op_sel_hi:[1,0,1]
	v_pk_mul_f32 v[138:139], v[66:67], v[136:137] op_sel:[0,1] op_sel_hi:[0,0] neg_lo:[0,1]
	v_pk_mul_f32 v[140:141], v[134:135], v[136:137] op_sel:[1,1] op_sel_hi:[0,1] neg_lo:[1,0]
	v_pk_fma_f32 v[138:139], v[64:65], v[136:137], v[138:139]
	v_pk_fma_f32 v[134:135], v[134:135], v[136:137], v[140:141] op_sel_hi:[1,0,1]
	v_pk_mul_f32 v[136:137], v[66:67], v[132:133] op_sel:[0,1] op_sel_hi:[0,0] neg_lo:[0,1]
	v_pk_fma_f32 v[132:133], v[64:65], v[132:133], v[136:137]
	v_pk_mul_f32 v[136:137], v[12:13], v[132:133] op_sel:[1,1] op_sel_hi:[0,1] neg_lo:[1,0]
	v_pk_fma_f32 v[12:13], v[12:13], v[132:133], v[136:137] op_sel_hi:[1,0,1]
	v_pk_mul_f32 v[136:137], v[66:67], v[138:139] op_sel:[0,1] op_sel_hi:[0,0] neg_lo:[0,1]
	v_pk_mul_f32 v[140:141], v[78:79], v[138:139] op_sel:[1,1] op_sel_hi:[0,1] neg_lo:[1,0]
	v_pk_fma_f32 v[136:137], v[64:65], v[138:139], v[136:137]
	v_pk_fma_f32 v[78:79], v[78:79], v[138:139], v[140:141] op_sel_hi:[1,0,1]
	v_pk_mul_f32 v[138:139], v[66:67], v[132:133] op_sel:[0,1] op_sel_hi:[0,0] neg_lo:[0,1]
	v_pk_fma_f32 v[132:133], v[64:65], v[132:133], v[138:139]
	v_pk_mul_f32 v[138:139], v[20:21], v[132:133] op_sel:[1,1] op_sel_hi:[0,1] neg_lo:[1,0]
	v_pk_fma_f32 v[20:21], v[20:21], v[132:133], v[138:139] op_sel_hi:[1,0,1]
	v_pk_mul_f32 v[138:139], v[66:67], v[136:137] op_sel:[0,1] op_sel_hi:[0,0] neg_lo:[0,1]
	v_pk_mul_f32 v[140:141], v[92:93], v[136:137] op_sel:[1,1] op_sel_hi:[0,1] neg_lo:[1,0]
	v_pk_fma_f32 v[138:139], v[64:65], v[136:137], v[138:139]
	v_pk_fma_f32 v[92:93], v[92:93], v[136:137], v[140:141] op_sel_hi:[1,0,1]
	v_pk_mul_f32 v[136:137], v[66:67], v[132:133] op_sel:[0,1] op_sel_hi:[0,0] neg_lo:[0,1]
	v_pk_fma_f32 v[132:133], v[64:65], v[132:133], v[136:137]
	v_pk_mul_f32 v[136:137], v[10:11], v[132:133] op_sel:[1,1] op_sel_hi:[0,1] neg_lo:[1,0]
	v_pk_fma_f32 v[10:11], v[10:11], v[132:133], v[136:137] op_sel_hi:[1,0,1]
	v_pk_mul_f32 v[136:137], v[66:67], v[138:139] op_sel:[0,1] op_sel_hi:[0,0] neg_lo:[0,1]
	v_pk_mul_f32 v[140:141], v[72:73], v[138:139] op_sel:[1,1] op_sel_hi:[0,1] neg_lo:[1,0]
	v_pk_fma_f32 v[136:137], v[64:65], v[138:139], v[136:137]
	v_pk_fma_f32 v[72:73], v[72:73], v[138:139], v[140:141] op_sel_hi:[1,0,1]
	v_pk_mul_f32 v[138:139], v[66:67], v[132:133] op_sel:[0,1] op_sel_hi:[0,0] neg_lo:[0,1]
	v_pk_fma_f32 v[132:133], v[64:65], v[132:133], v[138:139]
	v_pk_mul_f32 v[138:139], v[16:17], v[132:133] op_sel:[1,1] op_sel_hi:[0,1] neg_lo:[1,0]
	v_pk_fma_f32 v[16:17], v[16:17], v[132:133], v[138:139] op_sel_hi:[1,0,1]
	v_pk_mul_f32 v[138:139], v[66:67], v[136:137] op_sel:[0,1] op_sel_hi:[0,0] neg_lo:[0,1]
	v_pk_mul_f32 v[140:141], v[88:89], v[136:137] op_sel:[1,1] op_sel_hi:[0,1] neg_lo:[1,0]
	v_pk_fma_f32 v[138:139], v[64:65], v[136:137], v[138:139]
	v_pk_fma_f32 v[88:89], v[88:89], v[136:137], v[140:141] op_sel_hi:[1,0,1]
	v_pk_mul_f32 v[136:137], v[66:67], v[132:133] op_sel:[0,1] op_sel_hi:[0,0] neg_lo:[0,1]
	v_pk_fma_f32 v[132:133], v[64:65], v[132:133], v[136:137]
	v_pk_mul_f32 v[136:137], v[4:5], v[132:133] op_sel:[1,1] op_sel_hi:[0,1] neg_lo:[1,0]
	v_pk_fma_f32 v[4:5], v[4:5], v[132:133], v[136:137] op_sel_hi:[1,0,1]
	v_pk_mul_f32 v[136:137], v[66:67], v[138:139] op_sel:[0,1] op_sel_hi:[0,0] neg_lo:[0,1]
	v_pk_mul_f32 v[140:141], v[18:19], v[138:139] op_sel:[1,1] op_sel_hi:[0,1] neg_lo:[1,0]
	v_pk_fma_f32 v[136:137], v[64:65], v[138:139], v[136:137]
	v_pk_fma_f32 v[18:19], v[18:19], v[138:139], v[140:141] op_sel_hi:[1,0,1]
	v_pk_mul_f32 v[138:139], v[66:67], v[132:133] op_sel:[0,1] op_sel_hi:[0,0] neg_lo:[0,1]
	v_pk_fma_f32 v[132:133], v[64:65], v[132:133], v[138:139]
	v_pk_mul_f32 v[138:139], v[8:9], v[132:133] op_sel:[1,1] op_sel_hi:[0,1] neg_lo:[1,0]
	v_pk_fma_f32 v[8:9], v[8:9], v[132:133], v[138:139] op_sel_hi:[1,0,1]
	v_pk_mul_f32 v[138:139], v[66:67], v[136:137] op_sel:[0,1] op_sel_hi:[0,0] neg_lo:[0,1]
	v_pk_mul_f32 v[140:141], v[26:27], v[136:137] op_sel:[1,1] op_sel_hi:[0,1] neg_lo:[1,0]
	v_pk_fma_f32 v[138:139], v[64:65], v[136:137], v[138:139]
	v_pk_fma_f32 v[26:27], v[26:27], v[136:137], v[140:141] op_sel_hi:[1,0,1]
	v_pk_mul_f32 v[136:137], v[66:67], v[132:133] op_sel:[0,1] op_sel_hi:[0,0] neg_lo:[0,1]
	v_pk_fma_f32 v[132:133], v[64:65], v[132:133], v[136:137]
	v_pk_mul_f32 v[136:137], v[2:3], v[132:133] op_sel:[1,1] op_sel_hi:[0,1] neg_lo:[1,0]
	v_pk_fma_f32 v[2:3], v[2:3], v[132:133], v[136:137] op_sel_hi:[1,0,1]
	v_pk_mul_f32 v[136:137], v[66:67], v[138:139] op_sel:[0,1] op_sel_hi:[0,0] neg_lo:[0,1]
	v_pk_mul_f32 v[140:141], v[14:15], v[138:139] op_sel:[1,1] op_sel_hi:[0,1] neg_lo:[1,0]
	v_pk_fma_f32 v[136:137], v[64:65], v[138:139], v[136:137]
	v_pk_fma_f32 v[14:15], v[14:15], v[138:139], v[140:141] op_sel_hi:[1,0,1]
	v_pk_mul_f32 v[138:139], v[66:67], v[132:133] op_sel:[0,1] op_sel_hi:[0,0] neg_lo:[0,1]
	v_pk_fma_f32 v[64:65], v[64:65], v[132:133], v[138:139]
	s_nop 0
	v_pk_mul_f32 v[132:133], v[6:7], v[64:65] op_sel:[1,1] op_sel_hi:[0,1] neg_lo:[1,0]
	s_nop 0
	v_pk_fma_f32 v[6:7], v[6:7], v[64:65], v[132:133] op_sel_hi:[1,0,1]
	s_waitcnt lgkmcnt(0)
	v_pk_mul_f32 v[64:65], v[22:23], v[136:137] op_sel:[1,1] op_sel_hi:[0,1] neg_lo:[1,0]
	s_nop 0
	v_pk_fma_f32 v[22:23], v[22:23], v[136:137], v[64:65] op_sel_hi:[1,0,1]
	v_pk_add_f32 v[64:65], v[0:1], v[12:13]
	v_pk_add_f32 v[0:1], v[0:1], v[12:13] neg_lo:[0,1] neg_hi:[0,1]
	v_pk_add_f32 v[12:13], v[94:95], v[4:5]
	v_pk_add_f32 v[4:5], v[94:95], v[4:5] neg_lo:[0,1] neg_hi:[0,1]
	v_pk_add_f32 v[94:95], v[80:81], v[10:11]
	v_pk_add_f32 v[10:11], v[80:81], v[10:11] neg_lo:[0,1] neg_hi:[0,1]
	v_pk_add_f32 v[80:81], v[70:71], v[2:3]
	v_pk_add_f32 v[2:3], v[70:71], v[2:3] neg_lo:[0,1] neg_hi:[0,1]
	v_pk_add_f32 v[132:133], v[64:65], v[12:13]
	v_pk_add_f32 v[12:13], v[64:65], v[12:13] neg_lo:[0,1] neg_hi:[0,1]
	v_xor_b32_e32 v64, 0x80000000, v5
	v_mov_b32_e32 v65, v4
	v_pk_add_f32 v[70:71], v[68:69], v[20:21]
	v_pk_add_f32 v[20:21], v[68:69], v[20:21] neg_lo:[0,1] neg_hi:[0,1]
	v_pk_add_f32 v[68:69], v[96:97], v[8:9]
	v_pk_add_f32 v[8:9], v[96:97], v[8:9] neg_lo:[0,1] neg_hi:[0,1]
	v_pk_add_f32 v[4:5], v[0:1], v[64:65]
	v_pk_add_f32 v[0:1], v[0:1], v[64:65] neg_lo:[0,1] neg_hi:[0,1]
	v_pk_add_f32 v[64:65], v[94:95], v[80:81]
	v_pk_add_f32 v[80:81], v[94:95], v[80:81] neg_lo:[0,1] neg_hi:[0,1]
	v_xor_b32_e32 v94, 0x80000000, v3
	v_mov_b32_e32 v95, v2
	v_pk_add_f32 v[96:97], v[86:87], v[16:17]
	v_pk_add_f32 v[16:17], v[86:87], v[16:17] neg_lo:[0,1] neg_hi:[0,1]
	v_pk_add_f32 v[86:87], v[82:83], v[6:7]
	v_pk_add_f32 v[6:7], v[82:83], v[6:7] neg_lo:[0,1] neg_hi:[0,1]
	v_pk_add_f32 v[2:3], v[10:11], v[94:95]
	v_pk_add_f32 v[10:11], v[10:11], v[94:95] neg_lo:[0,1] neg_hi:[0,1]
	v_pk_add_f32 v[94:95], v[70:71], v[68:69]
	v_pk_add_f32 v[68:69], v[70:71], v[68:69] neg_lo:[0,1] neg_hi:[0,1]
	v_xor_b32_e32 v70, 0x80000000, v9
	v_mov_b32_e32 v71, v8
	v_pk_add_f32 v[82:83], v[24:25], v[78:79]
	v_pk_add_f32 v[24:25], v[24:25], v[78:79] neg_lo:[0,1] neg_hi:[0,1]
	v_pk_add_f32 v[78:79], v[74:75], v[18:19]
	v_pk_add_f32 v[18:19], v[74:75], v[18:19] neg_lo:[0,1] neg_hi:[0,1]
	v_pk_add_f32 v[8:9], v[20:21], v[70:71]
	v_pk_add_f32 v[20:21], v[20:21], v[70:71] neg_lo:[0,1] neg_hi:[0,1]
	v_pk_add_f32 v[70:71], v[96:97], v[86:87]
	v_pk_add_f32 v[86:87], v[96:97], v[86:87] neg_lo:[0,1] neg_hi:[0,1]
	v_xor_b32_e32 v96, 0x80000000, v7
	v_mov_b32_e32 v97, v6
	v_pk_add_f32 v[74:75], v[76:77], v[72:73]
	v_pk_add_f32 v[72:73], v[76:77], v[72:73] neg_lo:[0,1] neg_hi:[0,1]
	v_pk_add_f32 v[76:77], v[130:131], v[14:15]
	v_pk_add_f32 v[14:15], v[130:131], v[14:15] neg_lo:[0,1] neg_hi:[0,1]
	v_pk_add_f32 v[6:7], v[16:17], v[96:97]
	v_pk_add_f32 v[16:17], v[16:17], v[96:97] neg_lo:[0,1] neg_hi:[0,1]
	v_pk_add_f32 v[96:97], v[82:83], v[78:79]
	v_pk_add_f32 v[78:79], v[82:83], v[78:79] neg_lo:[0,1] neg_hi:[0,1]
	v_xor_b32_e32 v82, 0x80000000, v19
	v_mov_b32_e32 v83, v18
	v_pk_add_f32 v[130:131], v[62:63], v[92:93]
	v_pk_add_f32 v[62:63], v[62:63], v[92:93] neg_lo:[0,1] neg_hi:[0,1]
	v_pk_add_f32 v[92:93], v[90:91], v[26:27]
	v_pk_add_f32 v[26:27], v[90:91], v[26:27] neg_lo:[0,1] neg_hi:[0,1]
	v_pk_add_f32 v[18:19], v[24:25], v[82:83]
	v_pk_add_f32 v[24:25], v[24:25], v[82:83] neg_lo:[0,1] neg_hi:[0,1]
	v_pk_add_f32 v[82:83], v[74:75], v[76:77]
	v_pk_add_f32 v[74:75], v[74:75], v[76:77] neg_lo:[0,1] neg_hi:[0,1]
	v_xor_b32_e32 v76, 0x80000000, v15
	v_mov_b32_e32 v77, v14
	v_pk_add_f32 v[90:91], v[84:85], v[88:89]
	v_pk_add_f32 v[84:85], v[84:85], v[88:89] neg_lo:[0,1] neg_hi:[0,1]
	v_pk_add_f32 v[88:89], v[134:135], v[22:23]
	v_pk_add_f32 v[22:23], v[134:135], v[22:23] neg_lo:[0,1] neg_hi:[0,1]
	v_pk_add_f32 v[14:15], v[72:73], v[76:77]
	v_pk_add_f32 v[72:73], v[72:73], v[76:77] neg_lo:[0,1] neg_hi:[0,1]
	v_pk_add_f32 v[76:77], v[130:131], v[92:93]
	v_pk_add_f32 v[92:93], v[130:131], v[92:93] neg_lo:[0,1] neg_hi:[0,1]
	v_xor_b32_e32 v130, 0x80000000, v27
	v_mov_b32_e32 v131, v26
	v_pk_add_f32 v[26:27], v[62:63], v[130:131]
	v_pk_add_f32 v[62:63], v[62:63], v[130:131] neg_lo:[0,1] neg_hi:[0,1]
	v_pk_add_f32 v[130:131], v[90:91], v[88:89]
	v_pk_add_f32 v[88:89], v[90:91], v[88:89] neg_lo:[0,1] neg_hi:[0,1]
	v_xor_b32_e32 v90, 0x80000000, v23
	v_mov_b32_e32 v91, v22
	v_pk_add_f32 v[22:23], v[84:85], v[90:91]
	v_pk_add_f32 v[84:85], v[84:85], v[90:91] neg_lo:[0,1] neg_hi:[0,1]
	v_pk_add_f32 v[90:91], v[132:133], v[64:65]
	v_pk_add_f32 v[64:65], v[132:133], v[64:65] neg_lo:[0,1] neg_hi:[0,1]
	v_pk_mul_f32 v[132:133], v[2:3], s[60:61] op_sel:[1,0] op_sel_hi:[0,0] neg_lo:[1,0]
	v_xor_b32_e32 v134, 0x80000000, v11
	v_pk_fma_f32 v[2:3], v[2:3], s[60:61], v[132:133] op_sel_hi:[1,0,1]
	v_mov_b32_e32 v135, v10
	v_pk_add_f32 v[132:133], v[4:5], v[2:3]
	v_pk_add_f32 v[2:3], v[4:5], v[2:3] neg_lo:[0,1] neg_hi:[0,1]
	v_xor_b32_e32 v4, 0x80000000, v81
	v_mov_b32_e32 v5, v80
	v_pk_add_f32 v[80:81], v[12:13], v[4:5]
	v_pk_add_f32 v[4:5], v[12:13], v[4:5] neg_lo:[0,1] neg_hi:[0,1]
	v_pk_mul_f32 v[12:13], v[10:11], s[60:61] op_sel_hi:[1,0]
	v_pk_fma_f32 v[10:11], v[134:135], s[60:61], v[12:13] op_sel_hi:[1,0,1] neg_lo:[0,0,1] neg_hi:[0,0,1]
	v_xor_b32_e32 v134, 0x80000000, v17
	v_pk_add_f32 v[12:13], v[0:1], v[10:11]
	v_pk_add_f32 v[0:1], v[0:1], v[10:11] neg_lo:[0,1] neg_hi:[0,1]
	v_pk_add_f32 v[10:11], v[94:95], v[70:71]
	v_pk_add_f32 v[70:71], v[94:95], v[70:71] neg_lo:[0,1] neg_hi:[0,1]
	v_pk_mul_f32 v[94:95], v[6:7], s[60:61] op_sel:[1,0] op_sel_hi:[0,0] neg_lo:[1,0]
	v_mov_b32_e32 v135, v16
	v_pk_fma_f32 v[6:7], v[6:7], s[60:61], v[94:95] op_sel_hi:[1,0,1]
	v_pk_add_f32 v[94:95], v[8:9], v[6:7]
	v_pk_add_f32 v[6:7], v[8:9], v[6:7] neg_lo:[0,1] neg_hi:[0,1]
	v_xor_b32_e32 v8, 0x80000000, v87
	v_mov_b32_e32 v9, v86
	v_pk_add_f32 v[86:87], v[68:69], v[8:9]
	v_pk_add_f32 v[8:9], v[68:69], v[8:9] neg_lo:[0,1] neg_hi:[0,1]
	v_pk_mul_f32 v[68:69], v[16:17], s[60:61] op_sel_hi:[1,0]
	v_pk_fma_f32 v[16:17], v[134:135], s[60:61], v[68:69] op_sel_hi:[1,0,1] neg_lo:[0,0,1] neg_hi:[0,0,1]
	v_xor_b32_e32 v134, 0x80000000, v73
	v_pk_add_f32 v[68:69], v[20:21], v[16:17]
	v_pk_add_f32 v[16:17], v[20:21], v[16:17] neg_lo:[0,1] neg_hi:[0,1]
	v_pk_add_f32 v[20:21], v[96:97], v[82:83]
	v_pk_add_f32 v[82:83], v[96:97], v[82:83] neg_lo:[0,1] neg_hi:[0,1]
	v_pk_mul_f32 v[96:97], v[14:15], s[60:61] op_sel:[1,0] op_sel_hi:[0,0] neg_lo:[1,0]
	v_mov_b32_e32 v135, v72
	v_pk_fma_f32 v[14:15], v[14:15], s[60:61], v[96:97] op_sel_hi:[1,0,1]
	v_pk_add_f32 v[96:97], v[18:19], v[14:15]
	v_pk_add_f32 v[14:15], v[18:19], v[14:15] neg_lo:[0,1] neg_hi:[0,1]
	v_xor_b32_e32 v18, 0x80000000, v75
	v_mov_b32_e32 v19, v74
	v_pk_add_f32 v[74:75], v[78:79], v[18:19]
	v_pk_add_f32 v[18:19], v[78:79], v[18:19] neg_lo:[0,1] neg_hi:[0,1]
	v_pk_mul_f32 v[78:79], v[72:73], s[60:61] op_sel_hi:[1,0]
	v_pk_fma_f32 v[72:73], v[134:135], s[60:61], v[78:79] op_sel_hi:[1,0,1] neg_lo:[0,0,1] neg_hi:[0,0,1]
	v_xor_b32_e32 v134, 0x80000000, v85
	v_pk_add_f32 v[78:79], v[24:25], v[72:73]
	v_pk_add_f32 v[24:25], v[24:25], v[72:73] neg_lo:[0,1] neg_hi:[0,1]
	v_pk_add_f32 v[72:73], v[76:77], v[130:131]
	v_pk_add_f32 v[76:77], v[76:77], v[130:131] neg_lo:[0,1] neg_hi:[0,1]
	v_pk_mul_f32 v[130:131], v[22:23], s[60:61] op_sel:[1,0] op_sel_hi:[0,0] neg_lo:[1,0]
	v_mov_b32_e32 v135, v84
	v_pk_fma_f32 v[22:23], v[22:23], s[60:61], v[130:131] op_sel_hi:[1,0,1]
	v_pk_add_f32 v[130:131], v[26:27], v[22:23]
	v_pk_add_f32 v[22:23], v[26:27], v[22:23] neg_lo:[0,1] neg_hi:[0,1]
	v_xor_b32_e32 v26, 0x80000000, v89
	v_mov_b32_e32 v27, v88
	v_pk_add_f32 v[88:89], v[92:93], v[26:27]
	v_pk_add_f32 v[26:27], v[92:93], v[26:27] neg_lo:[0,1] neg_hi:[0,1]
	v_pk_mul_f32 v[92:93], v[84:85], s[60:61] op_sel_hi:[1,0]
	v_pk_fma_f32 v[84:85], v[134:135], s[60:61], v[92:93] op_sel_hi:[1,0,1] neg_lo:[0,0,1] neg_hi:[0,0,1]
	v_xor_b32_e32 v134, 0x80000000, v7
	v_pk_add_f32 v[92:93], v[62:63], v[84:85]
	v_pk_add_f32 v[62:63], v[62:63], v[84:85] neg_lo:[0,1] neg_hi:[0,1]
	v_pk_add_f32 v[84:85], v[90:91], v[10:11]
	v_pk_add_f32 v[10:11], v[90:91], v[10:11] neg_lo:[0,1] neg_hi:[0,1]
	v_pk_mul_f32 v[90:91], v[94:95], s[54:55] op_sel:[1,0] op_sel_hi:[0,0] neg_lo:[1,0]
	v_mov_b32_e32 v135, v6
	v_pk_fma_f32 v[90:91], v[94:95], s[52:53], v[90:91] op_sel_hi:[1,0,1]
	v_pk_add_f32 v[94:95], v[132:133], v[90:91]
	v_pk_add_f32 v[90:91], v[132:133], v[90:91] neg_lo:[0,1] neg_hi:[0,1]
	v_pk_mul_f32 v[132:133], v[86:87], s[60:61] op_sel:[1,0] op_sel_hi:[0,0] neg_lo:[1,0]
	v_pk_fma_f32 v[86:87], v[86:87], s[60:61], v[132:133] op_sel_hi:[1,0,1]
	v_pk_add_f32 v[132:133], v[80:81], v[86:87]
	v_pk_add_f32 v[80:81], v[80:81], v[86:87] neg_lo:[0,1] neg_hi:[0,1]
	v_pk_mul_f32 v[86:87], v[68:69], s[52:53] op_sel:[1,0] op_sel_hi:[0,0] neg_lo:[1,0]
	v_pk_fma_f32 v[68:69], v[68:69], s[54:55], v[86:87] op_sel_hi:[1,0,1]
	v_pk_add_f32 v[86:87], v[12:13], v[68:69]
	v_pk_add_f32 v[12:13], v[12:13], v[68:69] neg_lo:[0,1] neg_hi:[0,1]
	v_xor_b32_e32 v68, 0x80000000, v71
	v_mov_b32_e32 v69, v70
	v_pk_add_f32 v[70:71], v[64:65], v[68:69]
	v_pk_add_f32 v[64:65], v[64:65], v[68:69] neg_lo:[0,1] neg_hi:[0,1]
	v_pk_mul_f32 v[68:69], v[6:7], s[54:55] op_sel_hi:[1,0]
	v_pk_fma_f32 v[6:7], v[134:135], s[52:53], v[68:69] op_sel_hi:[1,0,1] neg_lo:[0,0,1] neg_hi:[0,0,1]
	v_xor_b32_e32 v134, 0x80000000, v9
	v_pk_add_f32 v[68:69], v[2:3], v[6:7]
	v_pk_add_f32 v[2:3], v[2:3], v[6:7] neg_lo:[0,1] neg_hi:[0,1]
	v_pk_mul_f32 v[6:7], v[8:9], s[60:61] op_sel_hi:[1,0]
	v_mov_b32_e32 v135, v8
	v_pk_fma_f32 v[6:7], v[134:135], s[60:61], v[6:7] op_sel_hi:[1,0,1] neg_lo:[0,0,1] neg_hi:[0,0,1]
	v_xor_b32_e32 v134, 0x80000000, v17
	v_pk_add_f32 v[8:9], v[4:5], v[6:7]
	v_pk_add_f32 v[4:5], v[4:5], v[6:7] neg_lo:[0,1] neg_hi:[0,1]
	v_pk_mul_f32 v[6:7], v[16:17], s[52:53] op_sel_hi:[1,0]
	v_mov_b32_e32 v135, v16
	v_pk_fma_f32 v[6:7], v[134:135], s[54:55], v[6:7] op_sel_hi:[1,0,1] neg_lo:[0,0,1] neg_hi:[0,0,1]
	v_xor_b32_e32 v134, 0x80000000, v23
	v_pk_add_f32 v[16:17], v[0:1], v[6:7]
	v_pk_add_f32 v[0:1], v[0:1], v[6:7] neg_lo:[0,1] neg_hi:[0,1]
	v_pk_add_f32 v[6:7], v[20:21], v[72:73]
	v_pk_add_f32 v[20:21], v[20:21], v[72:73] neg_lo:[0,1] neg_hi:[0,1]
	v_pk_mul_f32 v[72:73], v[130:131], s[54:55] op_sel:[1,0] op_sel_hi:[0,0] neg_lo:[1,0]
	v_mov_b32_e32 v135, v22
	v_pk_fma_f32 v[72:73], v[130:131], s[52:53], v[72:73] op_sel_hi:[1,0,1]
	v_pk_add_f32 v[130:131], v[96:97], v[72:73]
	v_pk_add_f32 v[72:73], v[96:97], v[72:73] neg_lo:[0,1] neg_hi:[0,1]
	v_pk_mul_f32 v[96:97], v[88:89], s[60:61] op_sel:[1,0] op_sel_hi:[0,0] neg_lo:[1,0]
	v_pk_fma_f32 v[88:89], v[88:89], s[60:61], v[96:97] op_sel_hi:[1,0,1]
	v_pk_add_f32 v[96:97], v[74:75], v[88:89]
	v_pk_add_f32 v[74:75], v[74:75], v[88:89] neg_lo:[0,1] neg_hi:[0,1]
	v_pk_mul_f32 v[88:89], v[92:93], s[52:53] op_sel:[1,0] op_sel_hi:[0,0] neg_lo:[1,0]
	v_pk_fma_f32 v[88:89], v[92:93], s[54:55], v[88:89] op_sel_hi:[1,0,1]
	v_pk_add_f32 v[92:93], v[78:79], v[88:89]
	v_pk_add_f32 v[78:79], v[78:79], v[88:89] neg_lo:[0,1] neg_hi:[0,1]
	v_xor_b32_e32 v88, 0x80000000, v77
	v_mov_b32_e32 v89, v76
	v_pk_add_f32 v[76:77], v[82:83], v[88:89]
	v_pk_add_f32 v[82:83], v[82:83], v[88:89] neg_lo:[0,1] neg_hi:[0,1]
	v_pk_mul_f32 v[88:89], v[22:23], s[54:55] op_sel_hi:[1,0]
	v_pk_fma_f32 v[22:23], v[134:135], s[52:53], v[88:89] op_sel_hi:[1,0,1] neg_lo:[0,0,1] neg_hi:[0,0,1]
	v_xor_b32_e32 v134, 0x80000000, v27
	v_pk_add_f32 v[88:89], v[14:15], v[22:23]
	v_pk_add_f32 v[14:15], v[14:15], v[22:23] neg_lo:[0,1] neg_hi:[0,1]
	v_pk_mul_f32 v[22:23], v[26:27], s[60:61] op_sel_hi:[1,0]
	v_mov_b32_e32 v135, v26
	v_pk_fma_f32 v[22:23], v[134:135], s[60:61], v[22:23] op_sel_hi:[1,0,1] neg_lo:[0,0,1] neg_hi:[0,0,1]
	v_xor_b32_e32 v134, 0x80000000, v63
	v_pk_add_f32 v[26:27], v[18:19], v[22:23]
	v_pk_add_f32 v[18:19], v[18:19], v[22:23] neg_lo:[0,1] neg_hi:[0,1]
	v_pk_mul_f32 v[22:23], v[62:63], s[52:53] op_sel_hi:[1,0]
	v_mov_b32_e32 v135, v62
	v_pk_fma_f32 v[22:23], v[134:135], s[54:55], v[22:23] op_sel_hi:[1,0,1] neg_lo:[0,0,1] neg_hi:[0,0,1]
	v_xor_b32_e32 v134, 0x80000000, v73
	v_pk_add_f32 v[62:63], v[24:25], v[22:23]
	v_pk_add_f32 v[22:23], v[24:25], v[22:23] neg_lo:[0,1] neg_hi:[0,1]
	v_pk_add_f32 v[24:25], v[84:85], v[6:7]
	v_pk_add_f32 v[6:7], v[84:85], v[6:7] neg_lo:[0,1] neg_hi:[0,1]
	v_pk_mul_f32 v[84:85], v[130:131], s[48:49] op_sel:[1,0] op_sel_hi:[0,0] neg_lo:[1,0]
	v_mov_b32_e32 v135, v72
	v_pk_fma_f32 v[84:85], v[130:131], s[44:45], v[84:85] op_sel_hi:[1,0,1]
	v_pk_add_f32 v[130:131], v[94:95], v[84:85]
	v_pk_add_f32 v[84:85], v[94:95], v[84:85] neg_lo:[0,1] neg_hi:[0,1]
	v_pk_mul_f32 v[94:95], v[96:97], s[54:55] op_sel:[1,0] op_sel_hi:[0,0] neg_lo:[1,0]
	v_pk_fma_f32 v[94:95], v[96:97], s[52:53], v[94:95] op_sel_hi:[1,0,1]
	v_pk_add_f32 v[96:97], v[132:133], v[94:95]
	v_pk_add_f32 v[94:95], v[132:133], v[94:95] neg_lo:[0,1] neg_hi:[0,1]
	v_pk_mul_f32 v[132:133], v[92:93], s[58:59] op_sel:[1,0] op_sel_hi:[0,0] neg_lo:[1,0]
	v_pk_fma_f32 v[92:93], v[92:93], s[56:57], v[132:133] op_sel_hi:[1,0,1]
	v_pk_add_f32 v[132:133], v[86:87], v[92:93]
	v_pk_add_f32 v[86:87], v[86:87], v[92:93] neg_lo:[0,1] neg_hi:[0,1]
	v_pk_mul_f32 v[92:93], v[76:77], s[60:61] op_sel:[1,0] op_sel_hi:[0,0] neg_lo:[1,0]
	v_pk_fma_f32 v[76:77], v[76:77], s[60:61], v[92:93] op_sel_hi:[1,0,1]
	v_pk_add_f32 v[92:93], v[70:71], v[76:77]
	v_pk_add_f32 v[70:71], v[70:71], v[76:77] neg_lo:[0,1] neg_hi:[0,1]
	v_pk_mul_f32 v[76:77], v[88:89], s[56:57] op_sel:[1,0] op_sel_hi:[0,0] neg_lo:[1,0]
	v_pk_fma_f32 v[76:77], v[88:89], s[58:59], v[76:77] op_sel_hi:[1,0,1]
	v_pk_add_f32 v[88:89], v[68:69], v[76:77]
	v_pk_add_f32 v[68:69], v[68:69], v[76:77] neg_lo:[0,1] neg_hi:[0,1]
	v_pk_mul_f32 v[76:77], v[26:27], s[52:53] op_sel:[1,0] op_sel_hi:[0,0] neg_lo:[1,0]
	v_pk_fma_f32 v[26:27], v[26:27], s[54:55], v[76:77] op_sel_hi:[1,0,1]
	v_pk_add_f32 v[76:77], v[8:9], v[26:27]
	v_pk_add_f32 v[8:9], v[8:9], v[26:27] neg_lo:[0,1] neg_hi:[0,1]
	v_pk_mul_f32 v[26:27], v[62:63], s[44:45] op_sel:[1,0] op_sel_hi:[0,0] neg_lo:[1,0]
	v_pk_fma_f32 v[26:27], v[62:63], s[48:49], v[26:27] op_sel_hi:[1,0,1]
	v_pk_add_f32 v[62:63], v[16:17], v[26:27]
	v_pk_add_f32 v[16:17], v[16:17], v[26:27] neg_lo:[0,1] neg_hi:[0,1]
	v_xor_b32_e32 v26, 0x80000000, v21
	v_mov_b32_e32 v27, v20
	v_pk_add_f32 v[20:21], v[10:11], v[26:27]
	v_pk_add_f32 v[10:11], v[10:11], v[26:27] neg_lo:[0,1] neg_hi:[0,1]
	v_pk_mul_f32 v[26:27], v[72:73], s[48:49] op_sel_hi:[1,0]
	v_pk_fma_f32 v[26:27], v[134:135], s[44:45], v[26:27] op_sel_hi:[1,0,1] neg_lo:[0,0,1] neg_hi:[0,0,1]
	v_xor_b32_e32 v134, 0x80000000, v75
	v_pk_add_f32 v[72:73], v[90:91], v[26:27]
	v_pk_add_f32 v[26:27], v[90:91], v[26:27] neg_lo:[0,1] neg_hi:[0,1]
	v_pk_mul_f32 v[90:91], v[74:75], s[54:55] op_sel_hi:[1,0]
	v_mov_b32_e32 v135, v74
	v_pk_fma_f32 v[74:75], v[134:135], s[52:53], v[90:91] op_sel_hi:[1,0,1] neg_lo:[0,0,1] neg_hi:[0,0,1]
	v_xor_b32_e32 v134, 0x80000000, v79
	v_pk_add_f32 v[90:91], v[80:81], v[74:75]
	v_pk_add_f32 v[74:75], v[80:81], v[74:75] neg_lo:[0,1] neg_hi:[0,1]
	v_pk_mul_f32 v[80:81], v[78:79], s[58:59] op_sel_hi:[1,0]
	v_mov_b32_e32 v135, v78
	v_pk_fma_f32 v[78:79], v[134:135], s[56:57], v[80:81] op_sel_hi:[1,0,1] neg_lo:[0,0,1] neg_hi:[0,0,1]
	v_xor_b32_e32 v134, 0x80000000, v83
	v_pk_add_f32 v[80:81], v[12:13], v[78:79]
	v_pk_add_f32 v[12:13], v[12:13], v[78:79] neg_lo:[0,1] neg_hi:[0,1]
	v_pk_mul_f32 v[78:79], v[82:83], s[60:61] op_sel_hi:[1,0]
	v_mov_b32_e32 v135, v82
	v_pk_fma_f32 v[78:79], v[134:135], s[60:61], v[78:79] op_sel_hi:[1,0,1] neg_lo:[0,0,1] neg_hi:[0,0,1]
	v_xor_b32_e32 v134, 0x80000000, v15
	v_pk_add_f32 v[82:83], v[64:65], v[78:79]
	v_pk_add_f32 v[64:65], v[64:65], v[78:79] neg_lo:[0,1] neg_hi:[0,1]
	v_pk_mul_f32 v[78:79], v[14:15], s[56:57] op_sel_hi:[1,0]
	v_mov_b32_e32 v135, v14
	v_pk_fma_f32 v[14:15], v[134:135], s[58:59], v[78:79] op_sel_hi:[1,0,1] neg_lo:[0,0,1] neg_hi:[0,0,1]
	v_xor_b32_e32 v134, 0x80000000, v19
	v_pk_add_f32 v[78:79], v[2:3], v[14:15]
	v_pk_add_f32 v[2:3], v[2:3], v[14:15] neg_lo:[0,1] neg_hi:[0,1]
	v_pk_mul_f32 v[14:15], v[18:19], s[52:53] op_sel_hi:[1,0]
	v_mov_b32_e32 v135, v18
	v_pk_fma_f32 v[14:15], v[134:135], s[54:55], v[14:15] op_sel_hi:[1,0,1] neg_lo:[0,0,1] neg_hi:[0,0,1]
	v_xor_b32_e32 v134, 0x80000000, v23
	v_pk_add_f32 v[18:19], v[4:5], v[14:15]
	v_pk_add_f32 v[4:5], v[4:5], v[14:15] neg_lo:[0,1] neg_hi:[0,1]
	v_pk_mul_f32 v[14:15], v[22:23], s[44:45] op_sel_hi:[1,0]
	v_mov_b32_e32 v135, v22
	v_pk_fma_f32 v[14:15], v[134:135], s[48:49], v[14:15] op_sel_hi:[1,0,1] neg_lo:[0,0,1] neg_hi:[0,0,1]
	s_nop 0
	v_pk_add_f32 v[22:23], v[0:1], v[14:15]
	v_pk_add_f32 v[0:1], v[0:1], v[14:15] neg_lo:[0,1] neg_hi:[0,1]
	ds_write_b64 v67, v[24:25]
	ds_write_b64 v98, v[130:131]
	ds_write_b64 v99, v[96:97] offset:256
	ds_write_b64 v100, v[132:133] offset:256
	ds_write_b64 v101, v[92:93] offset:512
	ds_write_b64 v102, v[88:89] offset:512
	ds_write_b64 v103, v[76:77] offset:768
	ds_write_b64 v104, v[62:63] offset:768
	ds_write_b64 v105, v[20:21] offset:1024
	ds_write_b64 v106, v[72:73] offset:1024
	ds_write_b64 v107, v[90:91] offset:1280
	ds_write_b64 v108, v[80:81] offset:1280
	ds_write_b64 v109, v[82:83] offset:1536
	ds_write_b64 v110, v[78:79] offset:1536
	ds_write_b64 v111, v[18:19] offset:1792
	ds_write_b64 v112, v[22:23] offset:1792
	ds_write_b64 v113, v[6:7] offset:2048
	ds_write_b64 v114, v[84:85] offset:2048
	ds_write_b64 v115, v[94:95] offset:2304
	ds_write_b64 v116, v[86:87] offset:2304
	ds_write_b64 v117, v[70:71] offset:2560
	ds_write_b64 v118, v[68:69] offset:2560
	ds_write_b64 v119, v[8:9] offset:2816
	ds_write_b64 v120, v[16:17] offset:2816
	ds_write_b64 v121, v[10:11] offset:3072
	ds_write_b64 v122, v[26:27] offset:3072
	ds_write_b64 v123, v[74:75] offset:3328
	ds_write_b64 v124, v[12:13] offset:3328
	ds_write_b64 v125, v[64:65] offset:3584
	ds_write_b64 v126, v[2:3] offset:3584
	ds_write_b64 v127, v[4:5] offset:3840
	ds_write_b64 v128, v[0:1] offset:3840
	v_mov_b32_e32 v74, v146
	s_waitcnt lgkmcnt(0)
	s_barrier
	s_nop 0
	v_lshrrev_b32_e32 v0, 5, v74
	v_bfe_u32 v4, v74, 5, 4
	v_bitop3_b32 v0, v0, v74, 15 bitop3:0x6c
	v_bitop3_b32 v4, v4, v74, 16 bitop3:0x36
	v_lshlrev_b32_e32 v66, 3, v0
	v_lshlrev_b32_e32 v67, 3, v4
	v_add_u32_e32 v5, 16, v66
	v_add_u32_e32 v4, 16, v67
	v_add_u32_e32 v62, s79, v66
	v_add_u32_e32 v70, s9, v66
	ds_read2st64_b64 v[0:3], v5 offset1:16
	ds_read2st64_b64 v[16:19], v4 offset0:8 offset1:24
	ds_read2st64_b64 v[24:27], v5 offset0:32 offset1:48
	ds_read2st64_b64 v[8:11], v4 offset0:40 offset1:56
	ds_read2st64_b64 v[92:95], v5 offset0:64 offset1:80
	ds_read2st64_b64 v[12:15], v4 offset0:72 offset1:88
	ds_read2st64_b64 v[20:23], v5 offset0:96 offset1:112
	ds_read2st64_b64 v[4:7], v4 offset0:104 offset1:120
	ds_read_b64 v[68:69], v62
	ds_read_b64 v[72:73], v70
	v_add_u32_e32 v62, s19, v67
	v_add_u32_e32 v70, s8, v67
	ds_read_b64 v[84:85], v62
	ds_read_b64 v[90:91], v70
	v_add_u32_e32 v62, s18, v66
	v_add_u32_e32 v70, s7, v66
	ds_read_b64 v[96:97], v62
	ds_read_b64 v[100:101], v70
	v_add_u32_e32 v62, s17, v67
	v_add_u32_e32 v70, s6, v67
	ds_read_b64 v[64:65], v62
	ds_read_b64 v[70:71], v70
	v_add_u32_e32 v62, s13, v66
	v_add_u32_e32 v75, s5, v66
	ds_read_b64 v[86:87], v62
	ds_read_b64 v[102:103], v75
	v_add_u32_e32 v62, s12, v67
	v_add_u32_e32 v75, s4, v67
	ds_read_b64 v[80:81], v62
	ds_read_b64 v[88:89], v75
	v_add_u32_e32 v62, s11, v66
	v_add_u32_e32 v66, s1, v66
	ds_read_b64 v[98:99], v62
	ds_read_b64 v[104:105], v66
	v_add_u32_e32 v62, s10, v67
	v_add_u32_e32 v66, s0, v67
	ds_read_b64 v[62:63], v62
	ds_read_b64 v[66:67], v66
	s_waitcnt lgkmcnt(14)
	s_nop 0
	v_cvt_f32_i32_e32 v74, v74
	s_nop 0
	s_lshl_b64 s[0:1], s[42:43], 2
	s_add_u32 s0, s45, s0
	v_mul_f32_e32 v74, 0x38800000, v74
	v_cos_f32_e32 v78, v74
	v_sin_f32_e32 v79, v74
	s_addc_u32 s1, s24, s1
	s_and_b64 vcc, s[14:15], exec
	v_add_f32_e32 v76, v78, v78
	v_pk_mul_f32 v[74:75], v[78:79], v[78:79]
	v_mul_f32_e32 v76, v79, v76
	v_mov_b32_e32 v108, v79
	v_pk_add_f32 v[74:75], v[74:75], v[74:75] op_sel:[0,1] op_sel_hi:[0,1] neg_lo:[0,1] neg_hi:[0,1]
	v_pk_mul_f32 v[82:83], v[78:79], v[76:77] op_sel:[1,0] op_sel_hi:[0,0] neg_lo:[1,0]
	v_pk_mul_f32 v[106:107], v[68:69], v[108:109] op_sel:[1,0] op_sel_hi:[0,0] neg_lo:[1,0]
	v_pk_fma_f32 v[82:83], v[78:79], v[74:75], v[82:83]
	v_pk_fma_f32 v[68:69], v[68:69], v[78:79], v[106:107] op_sel_hi:[1,0,1]
	v_pk_mul_f32 v[78:79], v[76:77], s[46:47] op_sel_hi:[0,1]
	v_pk_fma_f32 v[106:107], v[74:75], s[40:41], v[78:79]
	v_pk_mul_f32 v[78:79], v[92:93], v[106:107] op_sel:[1,1] op_sel_hi:[0,1] neg_lo:[1,0]
	v_pk_fma_f32 v[78:79], v[92:93], v[106:107], v[78:79] op_sel_hi:[1,0,1]
	v_pk_mul_f32 v[92:93], v[76:77], v[82:83] op_sel:[0,1] op_sel_hi:[0,0] neg_lo:[0,1]
	v_pk_mul_f32 v[108:109], v[72:73], v[82:83] op_sel:[1,1] op_sel_hi:[0,1] neg_lo:[1,0]
	v_pk_fma_f32 v[92:93], v[74:75], v[82:83], v[92:93]
	v_pk_fma_f32 v[72:73], v[72:73], v[82:83], v[108:109] op_sel_hi:[1,0,1]
	v_pk_mul_f32 v[82:83], v[76:77], v[106:107] op_sel:[0,1] op_sel_hi:[0,0] neg_lo:[0,1]
	v_pk_fma_f32 v[106:107], v[74:75], v[106:107], v[82:83]
	v_pk_mul_f32 v[82:83], v[24:25], v[106:107] op_sel:[1,1] op_sel_hi:[0,1] neg_lo:[1,0]
	v_pk_fma_f32 v[82:83], v[24:25], v[106:107], v[82:83] op_sel_hi:[1,0,1]
	v_pk_mul_f32 v[24:25], v[76:77], v[92:93] op_sel:[0,1] op_sel_hi:[0,0] neg_lo:[0,1]
	v_pk_fma_f32 v[108:109], v[74:75], v[92:93], v[24:25]
	s_waitcnt lgkmcnt(7)
	v_pk_mul_f32 v[24:25], v[86:87], v[92:93] op_sel:[1,1] op_sel_hi:[0,1] neg_lo:[1,0]
	s_nop 0
	v_pk_fma_f32 v[24:25], v[86:87], v[92:93], v[24:25] op_sel_hi:[1,0,1]
	v_pk_mul_f32 v[86:87], v[76:77], v[106:107] op_sel:[0,1] op_sel_hi:[0,0] neg_lo:[0,1]
	v_pk_fma_f32 v[92:93], v[74:75], v[106:107], v[86:87]
	v_pk_mul_f32 v[86:87], v[20:21], v[92:93] op_sel:[1,1] op_sel_hi:[0,1] neg_lo:[1,0]
	v_pk_fma_f32 v[86:87], v[20:21], v[92:93], v[86:87] op_sel_hi:[1,0,1]
	v_pk_mul_f32 v[20:21], v[76:77], v[108:109] op_sel:[0,1] op_sel_hi:[0,0] neg_lo:[0,1]
	v_pk_fma_f32 v[106:107], v[74:75], v[108:109], v[20:21]
	s_waitcnt lgkmcnt(6)
	v_pk_mul_f32 v[20:21], v[102:103], v[108:109] op_sel:[1,1] op_sel_hi:[0,1] neg_lo:[1,0]
	s_nop 0
	v_pk_fma_f32 v[20:21], v[102:103], v[108:109], v[20:21] op_sel_hi:[1,0,1]
	v_pk_mul_f32 v[102:103], v[76:77], v[92:93] op_sel:[0,1] op_sel_hi:[0,0] neg_lo:[0,1]
	v_pk_fma_f32 v[102:103], v[74:75], v[92:93], v[102:103]
	v_pk_mul_f32 v[92:93], v[2:3], v[102:103] op_sel:[1,1] op_sel_hi:[0,1] neg_lo:[1,0]
	v_pk_fma_f32 v[92:93], v[2:3], v[102:103], v[92:93] op_sel_hi:[1,0,1]
	v_pk_mul_f32 v[2:3], v[76:77], v[106:107] op_sel:[0,1] op_sel_hi:[0,0] neg_lo:[0,1]
	v_pk_fma_f32 v[108:109], v[74:75], v[106:107], v[2:3]
	v_pk_mul_f32 v[2:3], v[96:97], v[106:107] op_sel:[1,1] op_sel_hi:[0,1] neg_lo:[1,0]
	v_pk_fma_f32 v[2:3], v[96:97], v[106:107], v[2:3] op_sel_hi:[1,0,1]
	v_pk_mul_f32 v[96:97], v[76:77], v[102:103] op_sel:[0,1] op_sel_hi:[0,0] neg_lo:[0,1]
	v_pk_fma_f32 v[102:103], v[74:75], v[102:103], v[96:97]
	v_pk_mul_f32 v[96:97], v[94:95], v[102:103] op_sel:[1,1] op_sel_hi:[0,1] neg_lo:[1,0]
	v_pk_fma_f32 v[96:97], v[94:95], v[102:103], v[96:97] op_sel_hi:[1,0,1]
	v_pk_mul_f32 v[94:95], v[76:77], v[108:109] op_sel:[0,1] op_sel_hi:[0,0] neg_lo:[0,1]
	v_pk_fma_f32 v[106:107], v[74:75], v[108:109], v[94:95]
	v_pk_mul_f32 v[94:95], v[100:101], v[108:109] op_sel:[1,1] op_sel_hi:[0,1] neg_lo:[1,0]
	v_pk_fma_f32 v[94:95], v[100:101], v[108:109], v[94:95] op_sel_hi:[1,0,1]
	v_pk_mul_f32 v[100:101], v[76:77], v[102:103] op_sel:[0,1] op_sel_hi:[0,0] neg_lo:[0,1]
	v_pk_fma_f32 v[100:101], v[74:75], v[102:103], v[100:101]
	s_nop 0
	v_pk_mul_f32 v[102:103], v[26:27], v[100:101] op_sel:[1,1] op_sel_hi:[0,1] neg_lo:[1,0]
	s_waitcnt lgkmcnt(3)
	v_pk_fma_f32 v[26:27], v[26:27], v[100:101], v[102:103] op_sel_hi:[1,0,1]
	v_pk_mul_f32 v[102:103], v[76:77], v[106:107] op_sel:[0,1] op_sel_hi:[0,0] neg_lo:[0,1]
	v_pk_mul_f32 v[108:109], v[98:99], v[106:107] op_sel:[1,1] op_sel_hi:[0,1] neg_lo:[1,0]
	v_pk_fma_f32 v[102:103], v[74:75], v[106:107], v[102:103]
	v_pk_fma_f32 v[98:99], v[98:99], v[106:107], v[108:109] op_sel_hi:[1,0,1]
	v_pk_mul_f32 v[106:107], v[76:77], v[100:101] op_sel:[0,1] op_sel_hi:[0,0] neg_lo:[0,1]
	v_pk_fma_f32 v[100:101], v[74:75], v[100:101], v[106:107]
	s_nop 0
	v_pk_mul_f32 v[106:107], v[22:23], v[100:101] op_sel:[1,1] op_sel_hi:[0,1] neg_lo:[1,0]
	s_waitcnt lgkmcnt(2)
	v_pk_fma_f32 v[22:23], v[22:23], v[100:101], v[106:107] op_sel_hi:[1,0,1]
	v_pk_mul_f32 v[106:107], v[76:77], v[102:103] op_sel:[0,1] op_sel_hi:[0,0] neg_lo:[0,1]
	v_pk_mul_f32 v[108:109], v[104:105], v[102:103] op_sel:[1,1] op_sel_hi:[0,1] neg_lo:[1,0]
	v_pk_fma_f32 v[106:107], v[74:75], v[102:103], v[106:107]
	v_pk_fma_f32 v[102:103], v[104:105], v[102:103], v[108:109] op_sel_hi:[1,0,1]
	v_pk_mul_f32 v[104:105], v[76:77], v[100:101] op_sel:[0,1] op_sel_hi:[0,0] neg_lo:[0,1]
	v_pk_fma_f32 v[100:101], v[74:75], v[100:101], v[104:105]
	v_pk_mul_f32 v[104:105], v[16:17], v[100:101] op_sel:[1,1] op_sel_hi:[0,1] neg_lo:[1,0]
	v_pk_fma_f32 v[16:17], v[16:17], v[100:101], v[104:105] op_sel_hi:[1,0,1]
	v_pk_mul_f32 v[104:105], v[76:77], v[106:107] op_sel:[0,1] op_sel_hi:[0,0] neg_lo:[0,1]
	v_pk_mul_f32 v[108:109], v[84:85], v[106:107] op_sel:[1,1] op_sel_hi:[0,1] neg_lo:[1,0]
	v_pk_fma_f32 v[104:105], v[74:75], v[106:107], v[104:105]
	v_pk_fma_f32 v[84:85], v[84:85], v[106:107], v[108:109] op_sel_hi:[1,0,1]
	v_pk_mul_f32 v[106:107], v[76:77], v[100:101] op_sel:[0,1] op_sel_hi:[0,0] neg_lo:[0,1]
	v_pk_fma_f32 v[100:101], v[74:75], v[100:101], v[106:107]
	v_pk_mul_f32 v[106:107], v[12:13], v[100:101] op_sel:[1,1] op_sel_hi:[0,1] neg_lo:[1,0]
	v_pk_fma_f32 v[12:13], v[12:13], v[100:101], v[106:107] op_sel_hi:[1,0,1]
	v_pk_mul_f32 v[106:107], v[76:77], v[104:105] op_sel:[0,1] op_sel_hi:[0,0] neg_lo:[0,1]
	v_pk_mul_f32 v[108:109], v[90:91], v[104:105] op_sel:[1,1] op_sel_hi:[0,1] neg_lo:[1,0]
	v_pk_fma_f32 v[106:107], v[74:75], v[104:105], v[106:107]
	v_pk_fma_f32 v[90:91], v[90:91], v[104:105], v[108:109] op_sel_hi:[1,0,1]
	v_pk_mul_f32 v[104:105], v[76:77], v[100:101] op_sel:[0,1] op_sel_hi:[0,0] neg_lo:[0,1]
	v_pk_fma_f32 v[100:101], v[74:75], v[100:101], v[104:105]
	v_pk_mul_f32 v[104:105], v[8:9], v[100:101] op_sel:[1,1] op_sel_hi:[0,1] neg_lo:[1,0]
	v_pk_fma_f32 v[8:9], v[8:9], v[100:101], v[104:105] op_sel_hi:[1,0,1]
	v_pk_mul_f32 v[104:105], v[76:77], v[106:107] op_sel:[0,1] op_sel_hi:[0,0] neg_lo:[0,1]
	v_pk_mul_f32 v[108:109], v[80:81], v[106:107] op_sel:[1,1] op_sel_hi:[0,1] neg_lo:[1,0]
	v_pk_fma_f32 v[104:105], v[74:75], v[106:107], v[104:105]
	v_pk_fma_f32 v[80:81], v[80:81], v[106:107], v[108:109] op_sel_hi:[1,0,1]
	v_pk_mul_f32 v[106:107], v[76:77], v[100:101] op_sel:[0,1] op_sel_hi:[0,0] neg_lo:[0,1]
	v_pk_fma_f32 v[100:101], v[74:75], v[100:101], v[106:107]
	v_pk_mul_f32 v[106:107], v[4:5], v[100:101] op_sel:[1,1] op_sel_hi:[0,1] neg_lo:[1,0]
	v_pk_fma_f32 v[4:5], v[4:5], v[100:101], v[106:107] op_sel_hi:[1,0,1]
	v_pk_mul_f32 v[106:107], v[76:77], v[104:105] op_sel:[0,1] op_sel_hi:[0,0] neg_lo:[0,1]
	v_pk_mul_f32 v[108:109], v[88:89], v[104:105] op_sel:[1,1] op_sel_hi:[0,1] neg_lo:[1,0]
	v_pk_fma_f32 v[106:107], v[74:75], v[104:105], v[106:107]
	v_pk_fma_f32 v[88:89], v[88:89], v[104:105], v[108:109] op_sel_hi:[1,0,1]
	v_pk_mul_f32 v[104:105], v[76:77], v[100:101] op_sel:[0,1] op_sel_hi:[0,0] neg_lo:[0,1]
	v_pk_fma_f32 v[100:101], v[74:75], v[100:101], v[104:105]
	v_pk_mul_f32 v[104:105], v[18:19], v[100:101] op_sel:[1,1] op_sel_hi:[0,1] neg_lo:[1,0]
	v_pk_fma_f32 v[18:19], v[18:19], v[100:101], v[104:105] op_sel_hi:[1,0,1]
	v_pk_mul_f32 v[104:105], v[76:77], v[106:107] op_sel:[0,1] op_sel_hi:[0,0] neg_lo:[0,1]
	v_pk_mul_f32 v[108:109], v[64:65], v[106:107] op_sel:[1,1] op_sel_hi:[0,1] neg_lo:[1,0]
	v_pk_fma_f32 v[104:105], v[74:75], v[106:107], v[104:105]
	v_pk_fma_f32 v[64:65], v[64:65], v[106:107], v[108:109] op_sel_hi:[1,0,1]
	v_pk_mul_f32 v[106:107], v[76:77], v[100:101] op_sel:[0,1] op_sel_hi:[0,0] neg_lo:[0,1]
	v_pk_fma_f32 v[100:101], v[74:75], v[100:101], v[106:107]
	v_pk_mul_f32 v[106:107], v[14:15], v[100:101] op_sel:[1,1] op_sel_hi:[0,1] neg_lo:[1,0]
	v_pk_fma_f32 v[14:15], v[14:15], v[100:101], v[106:107] op_sel_hi:[1,0,1]
	v_pk_mul_f32 v[106:107], v[76:77], v[104:105] op_sel:[0,1] op_sel_hi:[0,0] neg_lo:[0,1]
	v_pk_mul_f32 v[108:109], v[70:71], v[104:105] op_sel:[1,1] op_sel_hi:[0,1] neg_lo:[1,0]
	v_pk_fma_f32 v[106:107], v[74:75], v[104:105], v[106:107]
	v_pk_fma_f32 v[70:71], v[70:71], v[104:105], v[108:109] op_sel_hi:[1,0,1]
	v_pk_mul_f32 v[104:105], v[76:77], v[100:101] op_sel:[0,1] op_sel_hi:[0,0] neg_lo:[0,1]
	v_pk_fma_f32 v[100:101], v[74:75], v[100:101], v[104:105]
	s_nop 0
	v_pk_mul_f32 v[104:105], v[10:11], v[100:101] op_sel:[1,1] op_sel_hi:[0,1] neg_lo:[1,0]
	s_waitcnt lgkmcnt(1)
	v_pk_fma_f32 v[10:11], v[10:11], v[100:101], v[104:105] op_sel_hi:[1,0,1]
	v_pk_mul_f32 v[104:105], v[76:77], v[106:107] op_sel:[0,1] op_sel_hi:[0,0] neg_lo:[0,1]
	v_pk_mul_f32 v[108:109], v[62:63], v[106:107] op_sel:[1,1] op_sel_hi:[0,1] neg_lo:[1,0]
	v_pk_fma_f32 v[104:105], v[74:75], v[106:107], v[104:105]
	v_pk_fma_f32 v[62:63], v[62:63], v[106:107], v[108:109] op_sel_hi:[1,0,1]
	v_pk_mul_f32 v[76:77], v[76:77], v[100:101] op_sel:[0,1] op_sel_hi:[0,0] neg_lo:[0,1]
	v_pk_fma_f32 v[74:75], v[74:75], v[100:101], v[76:77]
	s_nop 0
	v_pk_mul_f32 v[76:77], v[6:7], v[74:75] op_sel:[1,1] op_sel_hi:[0,1] neg_lo:[1,0]
	s_nop 0
	v_pk_fma_f32 v[6:7], v[6:7], v[74:75], v[76:77] op_sel_hi:[1,0,1]
	s_waitcnt lgkmcnt(0)
	v_pk_mul_f32 v[74:75], v[66:67], v[104:105] op_sel:[1,1] op_sel_hi:[0,1] neg_lo:[1,0]
	v_pk_add_f32 v[76:77], v[82:83], v[8:9]
	v_pk_fma_f32 v[66:67], v[66:67], v[104:105], v[74:75] op_sel_hi:[1,0,1]
	v_pk_add_f32 v[74:75], v[0:1], v[16:17]
	v_pk_add_f32 v[0:1], v[0:1], v[16:17] neg_lo:[0,1] neg_hi:[0,1]
	v_pk_add_f32 v[16:17], v[92:93], v[18:19]
	v_pk_add_f32 v[18:19], v[92:93], v[18:19] neg_lo:[0,1] neg_hi:[0,1]
	v_pk_add_f32 v[8:9], v[82:83], v[8:9] neg_lo:[0,1] neg_hi:[0,1]
	v_pk_add_f32 v[82:83], v[26:27], v[10:11]
	v_pk_add_f32 v[10:11], v[26:27], v[10:11] neg_lo:[0,1] neg_hi:[0,1]
	v_pk_add_f32 v[92:93], v[86:87], v[4:5]
	v_pk_add_f32 v[4:5], v[86:87], v[4:5] neg_lo:[0,1] neg_hi:[0,1]
	v_pk_add_f32 v[86:87], v[22:23], v[6:7]
	v_pk_add_f32 v[6:7], v[22:23], v[6:7] neg_lo:[0,1] neg_hi:[0,1]
	v_pk_add_f32 v[22:23], v[68:69], v[84:85]
	v_pk_add_f32 v[68:69], v[68:69], v[84:85] neg_lo:[0,1] neg_hi:[0,1]
	v_pk_add_f32 v[84:85], v[2:3], v[64:65]
	v_pk_add_f32 v[2:3], v[2:3], v[64:65] neg_lo:[0,1] neg_hi:[0,1]
	v_pk_add_f32 v[64:65], v[24:25], v[80:81]
	v_pk_add_f32 v[24:25], v[24:25], v[80:81] neg_lo:[0,1] neg_hi:[0,1]
	v_pk_add_f32 v[80:81], v[98:99], v[62:63]
	v_pk_add_f32 v[62:63], v[98:99], v[62:63] neg_lo:[0,1] neg_hi:[0,1]
	v_pk_add_f32 v[98:99], v[74:75], v[16:17]
	v_pk_add_f32 v[16:17], v[74:75], v[16:17] neg_lo:[0,1] neg_hi:[0,1]
	v_xor_b32_e32 v74, 0x80000000, v19
	v_mov_b32_e32 v75, v18
	v_pk_add_f32 v[26:27], v[78:79], v[12:13]
	v_pk_add_f32 v[12:13], v[78:79], v[12:13] neg_lo:[0,1] neg_hi:[0,1]
	v_pk_add_f32 v[78:79], v[96:97], v[14:15]
	v_pk_add_f32 v[14:15], v[96:97], v[14:15] neg_lo:[0,1] neg_hi:[0,1]
	v_pk_add_f32 v[18:19], v[0:1], v[74:75]
	v_pk_add_f32 v[0:1], v[0:1], v[74:75] neg_lo:[0,1] neg_hi:[0,1]
	v_pk_add_f32 v[74:75], v[76:77], v[82:83]
	v_pk_add_f32 v[76:77], v[76:77], v[82:83] neg_lo:[0,1] neg_hi:[0,1]
	v_xor_b32_e32 v82, 0x80000000, v11
	v_mov_b32_e32 v83, v10
	v_pk_add_f32 v[10:11], v[8:9], v[82:83]
	v_pk_add_f32 v[8:9], v[8:9], v[82:83] neg_lo:[0,1] neg_hi:[0,1]
	v_pk_add_f32 v[82:83], v[26:27], v[78:79]
	v_pk_add_f32 v[26:27], v[26:27], v[78:79] neg_lo:[0,1] neg_hi:[0,1]
	v_xor_b32_e32 v78, 0x80000000, v15
	v_mov_b32_e32 v79, v14
	v_pk_add_f32 v[14:15], v[12:13], v[78:79]
	v_pk_add_f32 v[12:13], v[12:13], v[78:79] neg_lo:[0,1] neg_hi:[0,1]
	v_pk_add_f32 v[78:79], v[92:93], v[86:87]
	v_pk_add_f32 v[86:87], v[92:93], v[86:87] neg_lo:[0,1] neg_hi:[0,1]
	v_xor_b32_e32 v92, 0x80000000, v7
	v_mov_b32_e32 v93, v6
	v_pk_add_f32 v[6:7], v[4:5], v[92:93]
	v_pk_add_f32 v[4:5], v[4:5], v[92:93] neg_lo:[0,1] neg_hi:[0,1]
	v_pk_add_f32 v[92:93], v[22:23], v[84:85]
	v_pk_add_f32 v[22:23], v[22:23], v[84:85] neg_lo:[0,1] neg_hi:[0,1]
	v_xor_b32_e32 v84, 0x80000000, v3
	v_mov_b32_e32 v85, v2
	v_pk_add_f32 v[96:97], v[72:73], v[90:91]
	v_pk_add_f32 v[72:73], v[72:73], v[90:91] neg_lo:[0,1] neg_hi:[0,1]
	v_pk_add_f32 v[90:91], v[94:95], v[70:71]
	v_pk_add_f32 v[70:71], v[94:95], v[70:71] neg_lo:[0,1] neg_hi:[0,1]
	v_pk_add_f32 v[2:3], v[68:69], v[84:85]
	v_pk_add_f32 v[68:69], v[68:69], v[84:85] neg_lo:[0,1] neg_hi:[0,1]
	v_pk_add_f32 v[84:85], v[64:65], v[80:81]
	v_pk_add_f32 v[64:65], v[64:65], v[80:81] neg_lo:[0,1] neg_hi:[0,1]
	v_xor_b32_e32 v80, 0x80000000, v63
	v_mov_b32_e32 v81, v62
	v_pk_add_f32 v[94:95], v[20:21], v[88:89]
	v_pk_add_f32 v[20:21], v[20:21], v[88:89] neg_lo:[0,1] neg_hi:[0,1]
	v_pk_add_f32 v[88:89], v[102:103], v[66:67]
	v_pk_add_f32 v[66:67], v[102:103], v[66:67] neg_lo:[0,1] neg_hi:[0,1]
	v_pk_add_f32 v[62:63], v[24:25], v[80:81]
	v_pk_add_f32 v[24:25], v[24:25], v[80:81] neg_lo:[0,1] neg_hi:[0,1]
	v_pk_add_f32 v[80:81], v[96:97], v[90:91]
	v_pk_add_f32 v[90:91], v[96:97], v[90:91] neg_lo:[0,1] neg_hi:[0,1]
	v_xor_b32_e32 v96, 0x80000000, v71
	v_mov_b32_e32 v97, v70
	v_pk_add_f32 v[70:71], v[72:73], v[96:97]
	v_pk_add_f32 v[72:73], v[72:73], v[96:97] neg_lo:[0,1] neg_hi:[0,1]
	v_pk_add_f32 v[96:97], v[94:95], v[88:89]
	v_pk_add_f32 v[88:89], v[94:95], v[88:89] neg_lo:[0,1] neg_hi:[0,1]
	v_xor_b32_e32 v94, 0x80000000, v67
	v_mov_b32_e32 v95, v66
	v_pk_add_f32 v[66:67], v[20:21], v[94:95]
	v_pk_add_f32 v[20:21], v[20:21], v[94:95] neg_lo:[0,1] neg_hi:[0,1]
	v_pk_add_f32 v[94:95], v[98:99], v[74:75]
	v_pk_add_f32 v[74:75], v[98:99], v[74:75] neg_lo:[0,1] neg_hi:[0,1]
	v_pk_mul_f32 v[98:99], v[10:11], s[60:61] op_sel:[1,0] op_sel_hi:[0,0] neg_lo:[1,0]
	v_xor_b32_e32 v100, 0x80000000, v9
	v_pk_fma_f32 v[10:11], v[10:11], s[60:61], v[98:99] op_sel_hi:[1,0,1]
	v_mov_b32_e32 v101, v8
	v_pk_add_f32 v[98:99], v[18:19], v[10:11]
	v_pk_add_f32 v[10:11], v[18:19], v[10:11] neg_lo:[0,1] neg_hi:[0,1]
	v_xor_b32_e32 v18, 0x80000000, v77
	v_mov_b32_e32 v19, v76
	v_pk_add_f32 v[76:77], v[16:17], v[18:19]
	v_pk_add_f32 v[16:17], v[16:17], v[18:19] neg_lo:[0,1] neg_hi:[0,1]
	v_pk_mul_f32 v[18:19], v[8:9], s[60:61] op_sel_hi:[1,0]
	v_pk_fma_f32 v[8:9], v[100:101], s[60:61], v[18:19] op_sel_hi:[1,0,1] neg_lo:[0,0,1] neg_hi:[0,0,1]
	v_xor_b32_e32 v100, 0x80000000, v5
	v_pk_add_f32 v[18:19], v[0:1], v[8:9]
	v_pk_add_f32 v[0:1], v[0:1], v[8:9] neg_lo:[0,1] neg_hi:[0,1]
	v_pk_add_f32 v[8:9], v[82:83], v[78:79]
	v_pk_add_f32 v[78:79], v[82:83], v[78:79] neg_lo:[0,1] neg_hi:[0,1]
	v_pk_mul_f32 v[82:83], v[6:7], s[60:61] op_sel:[1,0] op_sel_hi:[0,0] neg_lo:[1,0]
	v_mov_b32_e32 v101, v4
	v_pk_fma_f32 v[6:7], v[6:7], s[60:61], v[82:83] op_sel_hi:[1,0,1]
	v_pk_add_f32 v[82:83], v[14:15], v[6:7]
	v_pk_add_f32 v[6:7], v[14:15], v[6:7] neg_lo:[0,1] neg_hi:[0,1]
	v_xor_b32_e32 v14, 0x80000000, v87
	v_mov_b32_e32 v15, v86
	v_pk_add_f32 v[86:87], v[26:27], v[14:15]
	v_pk_add_f32 v[14:15], v[26:27], v[14:15] neg_lo:[0,1] neg_hi:[0,1]
	v_pk_mul_f32 v[26:27], v[4:5], s[60:61] op_sel_hi:[1,0]
	v_pk_fma_f32 v[4:5], v[100:101], s[60:61], v[26:27] op_sel_hi:[1,0,1] neg_lo:[0,0,1] neg_hi:[0,0,1]
	v_xor_b32_e32 v100, 0x80000000, v25
	v_pk_add_f32 v[26:27], v[12:13], v[4:5]
	v_pk_add_f32 v[4:5], v[12:13], v[4:5] neg_lo:[0,1] neg_hi:[0,1]
	v_pk_add_f32 v[12:13], v[92:93], v[84:85]
	v_pk_add_f32 v[84:85], v[92:93], v[84:85] neg_lo:[0,1] neg_hi:[0,1]
	v_pk_mul_f32 v[92:93], v[62:63], s[60:61] op_sel:[1,0] op_sel_hi:[0,0] neg_lo:[1,0]
	v_mov_b32_e32 v101, v24
	v_pk_fma_f32 v[62:63], v[62:63], s[60:61], v[92:93] op_sel_hi:[1,0,1]
	v_pk_add_f32 v[92:93], v[2:3], v[62:63]
	v_pk_add_f32 v[2:3], v[2:3], v[62:63] neg_lo:[0,1] neg_hi:[0,1]
	v_xor_b32_e32 v62, 0x80000000, v65
	v_mov_b32_e32 v63, v64
	v_pk_add_f32 v[64:65], v[22:23], v[62:63]
	v_pk_add_f32 v[22:23], v[22:23], v[62:63] neg_lo:[0,1] neg_hi:[0,1]
	v_pk_mul_f32 v[62:63], v[24:25], s[60:61] op_sel_hi:[1,0]
	v_pk_fma_f32 v[24:25], v[100:101], s[60:61], v[62:63] op_sel_hi:[1,0,1] neg_lo:[0,0,1] neg_hi:[0,0,1]
	v_xor_b32_e32 v100, 0x80000000, v21
	v_pk_add_f32 v[62:63], v[68:69], v[24:25]
	v_pk_add_f32 v[24:25], v[68:69], v[24:25] neg_lo:[0,1] neg_hi:[0,1]
	v_pk_add_f32 v[68:69], v[80:81], v[96:97]
	v_pk_add_f32 v[80:81], v[80:81], v[96:97] neg_lo:[0,1] neg_hi:[0,1]
	v_pk_mul_f32 v[96:97], v[66:67], s[60:61] op_sel:[1,0] op_sel_hi:[0,0] neg_lo:[1,0]
	v_mov_b32_e32 v101, v20
	v_pk_fma_f32 v[66:67], v[66:67], s[60:61], v[96:97] op_sel_hi:[1,0,1]
	v_pk_add_f32 v[96:97], v[70:71], v[66:67]
	v_pk_add_f32 v[66:67], v[70:71], v[66:67] neg_lo:[0,1] neg_hi:[0,1]
	v_xor_b32_e32 v70, 0x80000000, v89
	v_mov_b32_e32 v71, v88
	v_pk_add_f32 v[88:89], v[90:91], v[70:71]
	v_pk_add_f32 v[70:71], v[90:91], v[70:71] neg_lo:[0,1] neg_hi:[0,1]
	v_pk_mul_f32 v[90:91], v[20:21], s[60:61] op_sel_hi:[1,0]
	v_pk_fma_f32 v[20:21], v[100:101], s[60:61], v[90:91] op_sel_hi:[1,0,1] neg_lo:[0,0,1] neg_hi:[0,0,1]
	v_pk_add_f32 v[90:91], v[72:73], v[20:21]
	v_pk_add_f32 v[20:21], v[72:73], v[20:21] neg_lo:[0,1] neg_hi:[0,1]
	v_pk_add_f32 v[72:73], v[94:95], v[8:9]
	v_pk_add_f32 v[8:9], v[94:95], v[8:9] neg_lo:[0,1] neg_hi:[0,1]
	v_pk_mul_f32 v[94:95], v[82:83], s[54:55] op_sel:[1,0] op_sel_hi:[0,0] neg_lo:[1,0]
	v_pk_fma_f32 v[82:83], v[82:83], s[52:53], v[94:95] op_sel_hi:[1,0,1]
	v_pk_add_f32 v[94:95], v[98:99], v[82:83]
	v_pk_add_f32 v[82:83], v[98:99], v[82:83] neg_lo:[0,1] neg_hi:[0,1]
	v_pk_mul_f32 v[98:99], v[86:87], s[60:61] op_sel:[1,0] op_sel_hi:[0,0] neg_lo:[1,0]
	v_pk_fma_f32 v[86:87], v[86:87], s[60:61], v[98:99] op_sel_hi:[1,0,1]
	v_pk_add_f32 v[98:99], v[76:77], v[86:87]
	v_pk_add_f32 v[86:87], v[76:77], v[86:87] neg_lo:[0,1] neg_hi:[0,1]
	v_pk_mul_f32 v[76:77], v[26:27], s[52:53] op_sel:[1,0] op_sel_hi:[0,0] neg_lo:[1,0]
	v_pk_fma_f32 v[26:27], v[26:27], s[54:55], v[76:77] op_sel_hi:[1,0,1]
	v_xor_b32_e32 v76, 0x80000000, v67
	v_pk_add_f32 v[100:101], v[18:19], v[26:27]
	v_pk_add_f32 v[26:27], v[18:19], v[26:27] neg_lo:[0,1] neg_hi:[0,1]
	v_pk_add_f32 v[102:103], v[74:75], v[78:79] op_sel:[0,1] op_sel_hi:[1,0] neg_lo:[0,1]
	v_pk_add_f32 v[104:105], v[74:75], v[78:79] op_sel:[0,1] op_sel_hi:[1,0] neg_hi:[0,1]
	v_pk_mul_f32 v[18:19], v[6:7], s[54:55] op_sel_hi:[1,0]
	v_xor_b32_e32 v74, 0x80000000, v7
	v_mov_b32_e32 v75, v6
	v_pk_fma_f32 v[6:7], v[74:75], s[52:53], v[18:19] op_sel_hi:[1,0,1] neg_lo:[0,0,1] neg_hi:[0,0,1]
	v_xor_b32_e32 v74, 0x80000000, v15
	v_pk_add_f32 v[18:19], v[10:11], v[6:7]
	v_pk_add_f32 v[6:7], v[10:11], v[6:7] neg_lo:[0,1] neg_hi:[0,1]
	v_pk_mul_f32 v[10:11], v[14:15], s[60:61] op_sel_hi:[1,0]
	v_mov_b32_e32 v75, v14
	v_pk_fma_f32 v[10:11], v[74:75], s[60:61], v[10:11] op_sel_hi:[1,0,1] neg_lo:[0,0,1] neg_hi:[0,0,1]
	v_xor_b32_e32 v74, 0x80000000, v5
	v_pk_add_f32 v[14:15], v[16:17], v[10:11]
	v_pk_add_f32 v[10:11], v[16:17], v[10:11] neg_lo:[0,1] neg_hi:[0,1]
	v_pk_mul_f32 v[16:17], v[4:5], s[52:53] op_sel_hi:[1,0]
	v_mov_b32_e32 v75, v4
	v_pk_fma_f32 v[4:5], v[74:75], s[54:55], v[16:17] op_sel_hi:[1,0,1] neg_lo:[0,0,1] neg_hi:[0,0,1]
	v_xor_b32_e32 v74, 0x80000000, v89
	v_pk_add_f32 v[16:17], v[0:1], v[4:5]
	v_pk_add_f32 v[106:107], v[0:1], v[4:5] neg_lo:[0,1] neg_hi:[0,1]
	v_pk_add_f32 v[0:1], v[12:13], v[68:69]
	v_pk_add_f32 v[4:5], v[12:13], v[68:69] neg_lo:[0,1] neg_hi:[0,1]
	v_mov_b32_e32 v75, v88
	v_pk_mul_f32 v[12:13], v[96:97], s[54:55] op_sel:[1,0] op_sel_hi:[0,0] neg_lo:[1,0]
	v_pk_mul_f32 v[74:75], v[74:75], s[60:61] op_sel_hi:[1,0]
	v_pk_fma_f32 v[12:13], v[96:97], s[52:53], v[12:13] op_sel_hi:[1,0,1]
	v_pk_fma_f32 v[74:75], v[88:89], s[60:61], v[74:75] op_sel_hi:[1,0,1]
	v_pk_add_f32 v[68:69], v[92:93], v[12:13]
	v_pk_add_f32 v[12:13], v[92:93], v[12:13] neg_lo:[0,1] neg_hi:[0,1]
	v_pk_add_f32 v[88:89], v[64:65], v[74:75]
	v_pk_add_f32 v[92:93], v[64:65], v[74:75] neg_lo:[0,1] neg_hi:[0,1]
	v_pk_mul_f32 v[64:65], v[90:91], s[52:53] op_sel:[1,0] op_sel_hi:[0,0] neg_lo:[1,0]
	v_pk_add_f32 v[78:79], v[72:73], v[0:1]
	v_pk_fma_f32 v[64:65], v[90:91], s[54:55], v[64:65] op_sel_hi:[1,0,1]
	v_pk_add_f32 v[74:75], v[62:63], v[64:65]
	v_pk_add_f32 v[90:91], v[62:63], v[64:65] neg_lo:[0,1] neg_hi:[0,1]
	v_pk_mul_f32 v[0:1], v[68:69], s[48:49] op_sel:[1,0] op_sel_hi:[0,0] neg_lo:[1,0]
	v_pk_add_f32 v[64:65], v[84:85], v[80:81] op_sel:[0,1] op_sel_hi:[1,0] neg_lo:[0,1]
	v_pk_add_f32 v[80:81], v[84:85], v[80:81] op_sel:[0,1] op_sel_hi:[1,0] neg_hi:[0,1]
	v_pk_mul_f32 v[62:63], v[66:67], s[54:55] op_sel_hi:[1,0]
	v_mov_b32_e32 v77, v66
	v_pk_fma_f32 v[0:1], v[68:69], s[44:45], v[0:1] op_sel_hi:[1,0,1]
	v_pk_fma_f32 v[62:63], v[76:77], s[52:53], v[62:63] op_sel_hi:[1,0,1] neg_lo:[0,0,1] neg_hi:[0,0,1]
	v_pk_add_f32 v[76:77], v[94:95], v[0:1]
	v_pk_mul_f32 v[0:1], v[88:89], s[54:55] op_sel:[1,0] op_sel_hi:[0,0] neg_lo:[1,0]
	v_pk_add_f32 v[84:85], v[2:3], v[62:63]
	v_pk_fma_f32 v[0:1], v[88:89], s[52:53], v[0:1] op_sel_hi:[1,0,1]
	v_pk_add_f32 v[2:3], v[2:3], v[62:63] neg_lo:[0,1] neg_hi:[0,1]
	v_pk_add_f32 v[72:73], v[98:99], v[0:1]
	v_pk_mul_f32 v[0:1], v[74:75], s[58:59] op_sel:[1,0] op_sel_hi:[0,0] neg_lo:[1,0]
	v_pk_mul_f32 v[62:63], v[70:71], s[60:61] op_sel_hi:[1,0]
	v_pk_fma_f32 v[0:1], v[74:75], s[56:57], v[0:1] op_sel_hi:[1,0,1]
	v_xor_b32_e32 v66, 0x80000000, v71
	v_pk_add_f32 v[74:75], v[100:101], v[0:1]
	v_pk_mul_f32 v[0:1], v[64:65], s[60:61] op_sel:[1,0] op_sel_hi:[0,0] neg_lo:[1,0]
	v_mov_b32_e32 v67, v70
	v_pk_fma_f32 v[0:1], v[64:65], s[60:61], v[0:1] op_sel_hi:[1,0,1]
	v_pk_fma_f32 v[62:63], v[66:67], s[60:61], v[62:63] op_sel_hi:[1,0,1] neg_lo:[0,0,1] neg_hi:[0,0,1]
	v_pk_add_f32 v[66:67], v[102:103], v[0:1]
	v_pk_mul_f32 v[0:1], v[84:85], s[56:57] op_sel:[1,0] op_sel_hi:[0,0] neg_lo:[1,0]
	v_pk_add_f32 v[70:71], v[22:23], v[62:63]
	v_pk_fma_f32 v[0:1], v[84:85], s[58:59], v[0:1] op_sel_hi:[1,0,1]
	v_pk_add_f32 v[96:97], v[22:23], v[62:63] neg_lo:[0,1] neg_hi:[0,1]
	v_pk_mul_f32 v[22:23], v[20:21], s[52:53] op_sel_hi:[1,0]
	v_pk_add_f32 v[68:69], v[18:19], v[0:1]
	v_pk_fma_f32 v[20:21], v[20:21], s[54:55], v[22:23] op_sel:[1,0,0] op_sel_hi:[0,0,1] neg_lo:[1,0,1] neg_hi:[0,0,1]
	v_pk_mul_f32 v[0:1], v[70:71], s[52:53] op_sel:[1,0] op_sel_hi:[0,0] neg_lo:[1,0]
	v_pk_add_f32 v[22:23], v[24:25], v[20:21]
	v_pk_fma_f32 v[0:1], v[70:71], s[54:55], v[0:1] op_sel_hi:[1,0,1]
	v_pk_add_f32 v[108:109], v[24:25], v[20:21] neg_lo:[0,1] neg_hi:[0,1]
	v_pk_add_f32 v[62:63], v[14:15], v[0:1]
	v_pk_mul_f32 v[0:1], v[22:23], s[44:45] op_sel:[1,0] op_sel_hi:[0,0] neg_lo:[1,0]
	v_pk_fma_f32 v[0:1], v[22:23], s[48:49], v[0:1] op_sel_hi:[1,0,1]
	v_pk_add_f32 v[64:65], v[16:17], v[0:1]
	v_pk_add_f32 v[22:23], v[8:9], v[4:5] op_sel:[0,1] op_sel_hi:[1,0] neg_lo:[0,1]
	v_pk_mul_f32 v[0:1], v[12:13], s[48:49] op_sel_hi:[1,0]
	v_xor_b32_e32 v4, 0x80000000, v13
	v_mov_b32_e32 v5, v12
	v_pk_fma_f32 v[0:1], v[4:5], s[44:45], v[0:1] op_sel_hi:[1,0,1] neg_lo:[0,0,1] neg_hi:[0,0,1]
	v_xor_b32_e32 v4, 0x80000000, v93
	v_pk_add_f32 v[24:25], v[82:83], v[0:1]
	v_pk_mul_f32 v[0:1], v[92:93], s[54:55] op_sel_hi:[1,0]
	v_mov_b32_e32 v5, v92
	v_pk_fma_f32 v[0:1], v[4:5], s[52:53], v[0:1] op_sel_hi:[1,0,1] neg_lo:[0,0,1] neg_hi:[0,0,1]
	v_xor_b32_e32 v4, 0x80000000, v91
	v_pk_add_f32 v[18:19], v[86:87], v[0:1]
	v_pk_mul_f32 v[0:1], v[90:91], s[58:59] op_sel_hi:[1,0]
	v_mov_b32_e32 v5, v90
	v_pk_fma_f32 v[0:1], v[4:5], s[56:57], v[0:1] op_sel_hi:[1,0,1] neg_lo:[0,0,1] neg_hi:[0,0,1]
	v_pk_add_f32 v[20:21], v[26:27], v[0:1]
	v_pk_mul_f32 v[0:1], v[80:81], s[60:61] op_sel_hi:[1,0]
	v_pk_fma_f32 v[0:1], v[80:81], s[60:61], v[0:1] op_sel:[1,0,0] op_sel_hi:[0,0,1] neg_lo:[1,0,1] neg_hi:[0,0,1]
	v_xor_b32_e32 v8, 0x80000000, v3
	v_pk_add_f32 v[4:5], v[104:105], v[0:1]
	v_pk_mul_f32 v[0:1], v[2:3], s[56:57] op_sel_hi:[1,0]
	v_mov_b32_e32 v9, v2
	v_pk_fma_f32 v[0:1], v[8:9], s[58:59], v[0:1] op_sel_hi:[1,0,1] neg_lo:[0,0,1] neg_hi:[0,0,1]
	v_pk_add_f32 v[6:7], v[6:7], v[0:1]
	v_pk_mul_f32 v[0:1], v[96:97], s[52:53] op_sel_hi:[1,0]
	v_pk_fma_f32 v[0:1], v[96:97], s[54:55], v[0:1] op_sel:[1,0,0] op_sel_hi:[0,0,1] neg_lo:[1,0,1] neg_hi:[0,0,1]
	v_pk_mul_f32 v[2:3], v[108:109], s[44:45] op_sel_hi:[1,0]
	v_pk_add_f32 v[0:1], v[10:11], v[0:1]
	v_xor_b32_e32 v8, 0x80000000, v109
	v_mov_b32_e32 v9, v108
	v_mov_b32_e32 v10, v146
	v_pk_fma_f32 v[2:3], v[8:9], s[48:49], v[2:3] op_sel_hi:[1,0,1] neg_lo:[0,0,1] neg_hi:[0,0,1]
	v_mov_b32_e32 v8, v221
	s_movk_i32 s0, 0x200
	s_cselect_b32 s4, s0, 0x400
	s_add_i32 s0, s4, s62
	s_ashr_i32 s1, s0, 31
	s_lshl_b32 s6, s4, 2
	s_add_u32 s4, s64, s6
	s_addc_u32 s5, s65, 0
	s_lshl_b64 s[0:1], s[0:1], 14
	v_min_i32_e32 v70, 0x1ffe, v10
	v_mov_b32_e32 v9, s6
	s_add_u32 s36, s26, s0
	v_ashrrev_i32_e32 v11, 31, v10
	v_ashrrev_i32_e32 v71, 31, v70
	v_mov_b32_e32 v16, v222
	v_mov_b32_e32 v14, v223
	v_mov_b32_e32 v17, v224
	v_mov_b32_e32 v12, v225
	s_addc_u32 s37, s27, s1
	v_max_i32_e32 v9, 1, v10
	v_lshlrev_b64 v[82:83], 1, v[10:11]
	v_lshlrev_b64 v[84:85], 1, v[70:71]
	v_lshl_add_u64 v[26:27], s[36:37], 0, v[82:83]
	v_lshlrev_b32_e32 v9, 1, v9
	v_lshl_add_u64 v[70:71], s[36:37], 0, v[84:85]
	v_mov_b32_e32 v13, v226
	s_add_u32 s72, s30, s0
	v_mov_b32_e32 v70, v227
	s_addc_u32 s73, s31, s1
	v_mov_b32_e32 v15, v228
	v_cmp_lt_i32_e64 s[0:1], 0, v10
	v_cmp_gt_i32_e64 s[4:5], s88, v10
	v_pk_add_f32 v[2:3], v[106:107], v[2:3]
	v_cndmask_b32_e64 v81, 0, 1.0, s[0:1]
	v_cndmask_b32_e64 v86, 0, 1.0, s[4:5]
	v_add_u32_e32 v92, 0x200, v10
	v_cmp_lt_i32_e64 s[20:21], s33, v10
	v_cmp_gt_i32_e64 s[18:19], s92, v10
	v_add_u32_e32 v90, 0x400, v10
	v_cmp_lt_i32_e64 s[16:17], s81, v10
	v_cmp_gt_i32_e64 s[0:1], s38, v10
	v_add_u32_e32 v88, 0x600, v10
	v_cmp_lt_i32_e64 s[12:13], s93, v10
	v_cmp_gt_i32_e64 s[10:11], s3, v10
	v_cmp_lt_i32_e64 s[8:9], s50, v10
	v_cmp_gt_i32_e64 s[6:7], s90, v10
	v_cmp_lt_i32_e64 s[4:5], s39, v10
	v_cmp_gt_i32_e64 s[22:23], s51, v10
	s_waitcnt vmcnt(2)
	v_lshlrev_b32_e32 v13, 16, v13
	s_waitcnt vmcnt(1)
	v_lshlrev_b32_e32 v70, 16, v70
	v_mul_f32_e32 v70, v86, v70
	s_waitcnt vmcnt(0)
	v_lshlrev_b32_e32 v15, 16, v15
	v_mul_f32_e32 v15, v81, v15
	v_mul_f32_e32 v15, v16, v15
	v_fmac_f32_e32 v15, v14, v13
	v_fmac_f32_e32 v15, v17, v70
	v_lshl_add_u64 v[70:71], s[72:73], 0, v[82:83]
	v_lshl_add_u64 v[82:83], s[72:73], 0, v[84:85]
	v_add_f32_e32 v80, v12, v15
	v_mov_b32_e32 v13, v229
	v_mov_b32_e32 v15, v230
	v_add_u32_e32 v84, 0x800, v10
	v_mov_b32_e32 v9, v231
	v_add_u32_e32 v82, 0xa00, v10
	s_waitcnt vmcnt(2)
	v_lshlrev_b32_e32 v13, 16, v13
	s_waitcnt vmcnt(1)
	v_lshlrev_b32_e32 v15, 16, v15
	v_mul_f32_e32 v15, v86, v15
	s_waitcnt vmcnt(0)
	v_lshlrev_b32_e32 v9, 16, v9
	v_mul_f32_e32 v9, v81, v9
	v_mul_f32_e32 v9, v16, v9
	v_fmac_f32_e32 v9, v14, v13
	v_fmac_f32_e32 v9, v17, v15
	v_add_f32_e32 v86, v12, v9
	s_cbranch_vccnz .LBB0_912
	s_mov_b32 s98, s29
	s_lshl_b64 s[0:1], s[66:67], 1
	s_add_u32 s4, s0, s30
	s_addc_u32 s5, s1, s31
	s_add_u32 s0, s0, s26
	s_addc_u32 s1, s1, s27
	s_add_u32 s18, s70, 0x800000
	s_addc_u32 s19, s71, 0
	s_cmpk_gt_i32 s98, 0xff
	s_cbranch_scc1 .Lhy_ep1_comb_L1
	v_lshlrev_b32_e32 v109, 1, v10
	v_add_u32_e32 v254, 0x1e00, v10
	v_add_u32_e32 v253, 0x1000, v109
	v_cmp_gt_i32_e32 vcc, 0x1fff, v254
	v_add_u32_e32 v251, 0x2000, v109
	v_add_u32_e32 v250, 0x3000, v109
	v_min_i32_e32 v254, 0x1ffe, v254
	v_cndmask_b32_e64 v255, 0, 1.0, vcc
	v_lshlrev_b32_e32 v254, 1, v254
	global_load_ushort v9, v109, s[0:1]
	global_load_ushort v11, v109, s[4:5]
	global_load_ushort v13, v109, s[36:37] offset:1022
	global_load_ushort v15, v109, s[36:37] offset:1024
	global_load_ushort v81, v109, s[36:37] offset:1026
	global_load_ushort v83, v109, s[72:73] offset:1022
	global_load_ushort v85, v109, s[72:73] offset:1024
	global_load_ushort v87, v109, s[72:73] offset:1026
	global_load_ushort v89, v109, s[0:1] offset:1024
	global_load_ushort v91, v109, s[4:5] offset:1024
	global_load_ushort v93, v109, s[36:37] offset:2046
	global_load_ushort v94, v109, s[36:37] offset:2048
	global_load_ushort v95, v109, s[36:37] offset:2050
	global_load_ushort v96, v109, s[72:73] offset:2046
	global_load_ushort v97, v109, s[72:73] offset:2048
	global_load_ushort v98, v109, s[72:73] offset:2050
	global_load_ushort v99, v109, s[0:1] offset:2048
	global_load_ushort v100, v109, s[4:5] offset:2048
	global_load_ushort v101, v109, s[36:37] offset:3070
	global_load_ushort v102, v109, s[36:37] offset:3072
	global_load_ushort v103, v109, s[36:37] offset:3074
	global_load_ushort v104, v109, s[72:73] offset:3070
	global_load_ushort v105, v109, s[72:73] offset:3072
	global_load_ushort v106, v109, s[72:73] offset:3074
	global_load_ushort v107, v109, s[0:1] offset:3072
	global_load_ushort v108, v109, s[4:5] offset:3072
	global_load_ushort v111, v253, s[36:37] offset:-2
	global_load_ushort v112, v253, s[36:37]
	global_load_ushort v113, v253, s[36:37] offset:2
	global_load_ushort v114, v253, s[72:73] offset:-2
	global_load_ushort v115, v253, s[72:73]
	global_load_ushort v116, v253, s[72:73] offset:2
	global_load_ushort v117, v253, s[0:1]
	global_load_ushort v118, v253, s[4:5]
	global_load_ushort v119, v253, s[36:37] offset:1022
	global_load_ushort v120, v253, s[36:37] offset:1024
	global_load_ushort v121, v253, s[36:37] offset:1026
	global_load_ushort v122, v253, s[72:73] offset:1022
	global_load_ushort v123, v253, s[72:73] offset:1024
	global_load_ushort v124, v253, s[72:73] offset:1026
	global_load_ushort v125, v253, s[0:1] offset:1024
	global_load_ushort v126, v253, s[4:5] offset:1024
	global_load_ushort v127, v253, s[36:37] offset:2046
	global_load_ushort v128, v253, s[36:37] offset:2048
	global_load_ushort v129, v253, s[36:37] offset:2050
	global_load_ushort v130, v253, s[72:73] offset:2046
	global_load_ushort v131, v253, s[72:73] offset:2048
	global_load_ushort v132, v253, s[72:73] offset:2050
	global_load_ushort v133, v253, s[0:1] offset:2048
	global_load_ushort v134, v253, s[4:5] offset:2048
	global_load_ushort v135, v253, s[36:37] offset:3070
	global_load_ushort v136, v253, s[36:37] offset:3072
	global_load_ushort v137, v253, s[36:37] offset:3074
	global_load_ushort v138, v253, s[72:73] offset:3070
	global_load_ushort v139, v253, s[72:73] offset:3072
	global_load_ushort v140, v253, s[72:73] offset:3074
	global_load_ushort v141, v253, s[0:1] offset:3072
	global_load_ushort v142, v253, s[4:5] offset:3072
	global_load_ushort v143, v251, s[36:37] offset:-2
	global_load_ushort v163, v251, s[36:37]
	global_load_ushort v164, v251, s[36:37] offset:2
	global_load_ushort v165, v251, s[72:73] offset:-2
	global_load_ushort v166, v251, s[72:73]
	global_load_ushort v167, v251, s[72:73] offset:2
	global_load_ushort v168, v251, s[0:1]
	global_load_ushort v169, v251, s[4:5]
	global_load_ushort v170, v251, s[36:37] offset:1022
	global_load_ushort v171, v251, s[36:37] offset:1024
	global_load_ushort v172, v251, s[36:37] offset:1026
	global_load_ushort v173, v251, s[72:73] offset:1022
	global_load_ushort v174, v251, s[72:73] offset:1024
	global_load_ushort v175, v251, s[72:73] offset:1026
	global_load_ushort v176, v251, s[0:1] offset:1024
	global_load_ushort v177, v251, s[4:5] offset:1024
	global_load_ushort v178, v251, s[36:37] offset:2046
	global_load_ushort v179, v251, s[36:37] offset:2048
	global_load_ushort v180, v251, s[36:37] offset:2050
	global_load_ushort v181, v251, s[72:73] offset:2046
	global_load_ushort v182, v251, s[72:73] offset:2048
	global_load_ushort v183, v251, s[72:73] offset:2050
	global_load_ushort v184, v251, s[0:1] offset:2048
	global_load_ushort v185, v251, s[4:5] offset:2048
	global_load_ushort v186, v251, s[36:37] offset:3070
	global_load_ushort v187, v251, s[36:37] offset:3072
	global_load_ushort v188, v251, s[36:37] offset:3074
	global_load_ushort v189, v251, s[72:73] offset:3070
	global_load_ushort v190, v251, s[72:73] offset:3072
	global_load_ushort v191, v251, s[72:73] offset:3074
	global_load_ushort v192, v251, s[0:1] offset:3072
	global_load_ushort v193, v251, s[4:5] offset:3072
	global_load_ushort v194, v250, s[36:37] offset:-2
	global_load_ushort v195, v250, s[36:37]
	global_load_ushort v196, v250, s[36:37] offset:2
	global_load_ushort v197, v250, s[72:73] offset:-2
	global_load_ushort v221, v250, s[72:73]
	global_load_ushort v222, v250, s[72:73] offset:2
	global_load_ushort v223, v250, s[0:1]
	global_load_ushort v224, v250, s[4:5]
	global_load_ushort v225, v250, s[36:37] offset:1022
	global_load_ushort v226, v250, s[36:37] offset:1024
	global_load_ushort v227, v250, s[36:37] offset:1026
	global_load_ushort v228, v250, s[72:73] offset:1022
	global_load_ushort v229, v250, s[72:73] offset:1024
	global_load_ushort v230, v250, s[72:73] offset:1026
	global_load_ushort v231, v250, s[0:1] offset:1024
	global_load_ushort v232, v250, s[4:5] offset:1024
	global_load_ushort v233, v250, s[36:37] offset:2046
	global_load_ushort v234, v250, s[36:37] offset:2048
	global_load_ushort v235, v250, s[36:37] offset:2050
	global_load_ushort v236, v250, s[72:73] offset:2046
	global_load_ushort v237, v250, s[72:73] offset:2048
	global_load_ushort v238, v250, s[72:73] offset:2050
	global_load_ushort v239, v250, s[0:1] offset:2048
	global_load_ushort v240, v250, s[4:5] offset:2048
	global_load_ushort v241, v250, s[36:37] offset:3070
	global_load_ushort v242, v250, s[36:37] offset:3072
	global_load_ushort v243, v254, s[36:37] offset:2
	global_load_ushort v244, v250, s[72:73] offset:3070
	global_load_ushort v245, v250, s[72:73] offset:3072
	global_load_ushort v246, v254, s[72:73] offset:2
	global_load_ushort v247, v250, s[0:1] offset:3072
	global_load_ushort v248, v250, s[4:5] offset:3072
	s_waitcnt vmcnt(63)
	v_fma_f32 v27, v32, v8, v78
	v_mul_f32_e32 v70, v80, v27
	v_lshlrev_b32_e32 v9, 16, v9
	v_mul_f32_e32 v84, 0xbfb8aa3b, v9
	v_exp_f32_e32 v84, v84
	s_nop 0
	v_add_f32_e32 v84, 1.0, v84
	v_div_scale_f32 v71, s[74:75], v84, v84, v9
	v_rcp_f32_e32 v82, v71
	s_nop 0
	v_fma_f32 v92, -v71, v82, 1.0
	v_fmac_f32_e32 v82, v92, v82
	v_div_scale_f32 v88, vcc, v9, v84, v9
	v_mul_f32_e32 v90, v88, v82
	v_fma_f32 v92, -v71, v90, v88
	v_fmac_f32_e32 v90, v92, v82
	v_fma_f32 v71, -v71, v90, v88
	v_div_fmas_f32 v71, v71, v82, v90
	v_div_fixup_f32 v9, v71, v84, v9
	v_mul_f32_e32 v70, v70, v9
	v_fma_f32 v27, v34, v8, v79
	v_mul_f32_e32 v110, v86, v27
	v_lshlrev_b32_e32 v11, 16, v11
	v_mul_f32_e32 v84, 0xbfb8aa3b, v11
	v_exp_f32_e32 v84, v84
	s_nop 0
	v_add_f32_e32 v84, 1.0, v84
	v_div_scale_f32 v71, s[74:75], v84, v84, v11
	v_rcp_f32_e32 v82, v71
	s_nop 0
	v_fma_f32 v92, -v71, v82, 1.0
	v_fmac_f32_e32 v82, v92, v82
	v_div_scale_f32 v88, vcc, v11, v84, v11
	v_mul_f32_e32 v90, v88, v82
	v_fma_f32 v92, -v71, v90, v88
	v_fmac_f32_e32 v90, v92, v82
	v_fma_f32 v71, -v71, v90, v88
	v_div_fmas_f32 v71, v71, v82, v90
	v_div_fixup_f32 v11, v71, v84, v11
	v_mul_f32_e32 v110, v110, v11
	v_cvt_pk_bf16_f32 v198, v70, v110
	v_lshlrev_b32_e32 v15, 16, v15
	v_lshlrev_b32_e32 v81, 16, v81
	v_lshlrev_b32_e32 v13, 16, v13
	v_mul_f32_e32 v13, v16, v13
	v_fmac_f32_e32 v13, v14, v15
	v_fmac_f32_e32 v13, v17, v81
	v_add_f32_e32 v13, v12, v13
	v_fma_f32 v27, v33, v8, v76
	v_mul_f32_e32 v70, v27, v13
	v_lshlrev_b32_e32 v89, 16, v89
	v_mul_f32_e32 v84, 0xbfb8aa3b, v89
	v_exp_f32_e32 v84, v84
	s_nop 0
	v_add_f32_e32 v84, 1.0, v84
	v_div_scale_f32 v71, s[74:75], v84, v84, v89
	v_rcp_f32_e32 v82, v71
	s_nop 0
	v_fma_f32 v92, -v71, v82, 1.0
	v_fmac_f32_e32 v82, v92, v82
	v_div_scale_f32 v88, vcc, v89, v84, v89
	v_mul_f32_e32 v90, v88, v82
	v_fma_f32 v92, -v71, v90, v88
	v_fmac_f32_e32 v90, v92, v82
	v_fma_f32 v71, -v71, v90, v88
	v_div_fmas_f32 v71, v71, v82, v90
	v_div_fixup_f32 v89, v71, v84, v89
	v_mul_f32_e32 v70, v70, v89
	v_lshlrev_b32_e32 v85, 16, v85
	v_lshlrev_b32_e32 v87, 16, v87
	v_lshlrev_b32_e32 v83, 16, v83
	v_mul_f32_e32 v83, v16, v83
	v_fmac_f32_e32 v83, v14, v85
	v_fmac_f32_e32 v83, v17, v87
	v_add_f32_e32 v83, v12, v83
	v_fma_f32 v27, v35, v8, v77
	v_mul_f32_e32 v110, v27, v83
	v_lshlrev_b32_e32 v91, 16, v91
	v_mul_f32_e32 v84, 0xbfb8aa3b, v91
	v_exp_f32_e32 v84, v84
	s_nop 0
	v_add_f32_e32 v84, 1.0, v84
	v_div_scale_f32 v71, s[74:75], v84, v84, v91
	v_rcp_f32_e32 v82, v71
	s_nop 0
	v_fma_f32 v92, -v71, v82, 1.0
	v_fmac_f32_e32 v82, v92, v82
	v_div_scale_f32 v88, vcc, v91, v84, v91
	v_mul_f32_e32 v90, v88, v82
	v_fma_f32 v92, -v71, v90, v88
	v_fmac_f32_e32 v90, v92, v82
	v_fma_f32 v71, -v71, v90, v88
	v_div_fmas_f32 v71, v71, v82, v90
	v_div_fixup_f32 v91, v71, v84, v91
	v_mul_f32_e32 v110, v110, v91
	v_cvt_pk_bf16_f32 v199, v70, v110
	v_lshlrev_b32_e32 v94, 16, v94
	v_lshlrev_b32_e32 v95, 16, v95
	v_lshlrev_b32_e32 v93, 16, v93
	v_mul_f32_e32 v93, v16, v93
	v_fmac_f32_e32 v93, v14, v94
	v_fmac_f32_e32 v93, v17, v95
	v_add_f32_e32 v93, v12, v93
	v_fma_f32 v27, v37, v8, v72
	v_mul_f32_e32 v70, v27, v93
	v_lshlrev_b32_e32 v99, 16, v99
	v_mul_f32_e32 v84, 0xbfb8aa3b, v99
	v_exp_f32_e32 v84, v84
	s_nop 0
	v_add_f32_e32 v84, 1.0, v84
	v_div_scale_f32 v71, s[74:75], v84, v84, v99
	v_rcp_f32_e32 v82, v71
	s_nop 0
	v_fma_f32 v92, -v71, v82, 1.0
	v_fmac_f32_e32 v82, v92, v82
	v_div_scale_f32 v88, vcc, v99, v84, v99
	v_mul_f32_e32 v90, v88, v82
	v_fma_f32 v92, -v71, v90, v88
	v_fmac_f32_e32 v90, v92, v82
	v_fma_f32 v71, -v71, v90, v88
	v_div_fmas_f32 v71, v71, v82, v90
	v_div_fixup_f32 v99, v71, v84, v99
	v_mul_f32_e32 v70, v70, v99
	v_lshlrev_b32_e32 v97, 16, v97
	v_lshlrev_b32_e32 v98, 16, v98
	v_lshlrev_b32_e32 v96, 16, v96
	v_mul_f32_e32 v96, v16, v96
	v_fmac_f32_e32 v96, v14, v97
	v_fmac_f32_e32 v96, v17, v98
	v_add_f32_e32 v96, v12, v96
	v_fma_f32 v27, v31, v8, v73
	v_mul_f32_e32 v110, v27, v96
	v_lshlrev_b32_e32 v100, 16, v100
	v_mul_f32_e32 v84, 0xbfb8aa3b, v100
	v_exp_f32_e32 v84, v84
	s_nop 0
	v_add_f32_e32 v84, 1.0, v84
	v_div_scale_f32 v71, s[74:75], v84, v84, v100
	v_rcp_f32_e32 v82, v71
	s_nop 0
	v_fma_f32 v92, -v71, v82, 1.0
	v_fmac_f32_e32 v82, v92, v82
	v_div_scale_f32 v88, vcc, v100, v84, v100
	v_mul_f32_e32 v90, v88, v82
	v_fma_f32 v92, -v71, v90, v88
	v_fmac_f32_e32 v90, v92, v82
	v_fma_f32 v71, -v71, v90, v88
	v_div_fmas_f32 v71, v71, v82, v90
	v_div_fixup_f32 v100, v71, v84, v100
	v_mul_f32_e32 v110, v110, v100
	v_cvt_pk_bf16_f32 v200, v70, v110
	v_lshlrev_b32_e32 v102, 16, v102
	v_lshlrev_b32_e32 v103, 16, v103
	v_lshlrev_b32_e32 v101, 16, v101
	v_mul_f32_e32 v101, v16, v101
	v_fmac_f32_e32 v101, v14, v102
	v_fmac_f32_e32 v101, v17, v103
	v_add_f32_e32 v101, v12, v101
	v_fma_f32 v27, v36, v8, v74
	v_mul_f32_e32 v70, v27, v101
	v_lshlrev_b32_e32 v107, 16, v107
	v_mul_f32_e32 v84, 0xbfb8aa3b, v107
	v_exp_f32_e32 v84, v84
	s_nop 0
	v_add_f32_e32 v84, 1.0, v84
	v_div_scale_f32 v71, s[74:75], v84, v84, v107
	v_rcp_f32_e32 v82, v71
	s_nop 0
	v_fma_f32 v92, -v71, v82, 1.0
	v_fmac_f32_e32 v82, v92, v82
	v_div_scale_f32 v88, vcc, v107, v84, v107
	v_mul_f32_e32 v90, v88, v82
	v_fma_f32 v92, -v71, v90, v88
	v_fmac_f32_e32 v90, v92, v82
	v_fma_f32 v71, -v71, v90, v88
	v_div_fmas_f32 v71, v71, v82, v90
	v_div_fixup_f32 v107, v71, v84, v107
	v_mul_f32_e32 v70, v70, v107
	v_lshlrev_b32_e32 v105, 16, v105
	v_lshlrev_b32_e32 v106, 16, v106
	v_lshlrev_b32_e32 v104, 16, v104
	v_mul_f32_e32 v104, v16, v104
	v_fmac_f32_e32 v104, v14, v105
	v_fmac_f32_e32 v104, v17, v106
	v_add_f32_e32 v104, v12, v104
	v_fma_f32 v27, v30, v8, v75
	v_mul_f32_e32 v110, v27, v104
	v_lshlrev_b32_e32 v108, 16, v108
	v_mul_f32_e32 v84, 0xbfb8aa3b, v108
	v_exp_f32_e32 v84, v84
	s_nop 0
	v_add_f32_e32 v84, 1.0, v84
	v_div_scale_f32 v71, s[74:75], v84, v84, v108
	v_rcp_f32_e32 v82, v71
	s_nop 0
	v_fma_f32 v92, -v71, v82, 1.0
	v_fmac_f32_e32 v82, v92, v82
	v_div_scale_f32 v88, vcc, v108, v84, v108
	v_mul_f32_e32 v90, v88, v82
	v_fma_f32 v92, -v71, v90, v88
	v_fmac_f32_e32 v90, v92, v82
	v_fma_f32 v71, -v71, v90, v88
	v_div_fmas_f32 v71, v71, v82, v90
	v_div_fixup_f32 v108, v71, v84, v108
	v_mul_f32_e32 v110, v110, v108
	v_cvt_pk_bf16_f32 v201, v70, v110
	s_waitcnt vmcnt(63)
	v_lshlrev_b32_e32 v112, 16, v112
	v_lshlrev_b32_e32 v113, 16, v113
	v_lshlrev_b32_e32 v111, 16, v111
	v_mul_f32_e32 v111, v16, v111
	v_fmac_f32_e32 v111, v14, v112
	v_fmac_f32_e32 v111, v17, v113
	v_add_f32_e32 v111, v12, v111
	v_fma_f32 v27, v39, v8, v66
	v_mul_f32_e32 v70, v27, v111
	v_lshlrev_b32_e32 v117, 16, v117
	v_mul_f32_e32 v84, 0xbfb8aa3b, v117
	v_exp_f32_e32 v84, v84
	s_nop 0
	v_add_f32_e32 v84, 1.0, v84
	v_div_scale_f32 v71, s[74:75], v84, v84, v117
	v_rcp_f32_e32 v82, v71
	s_nop 0
	v_fma_f32 v92, -v71, v82, 1.0
	v_fmac_f32_e32 v82, v92, v82
	v_div_scale_f32 v88, vcc, v117, v84, v117
	v_mul_f32_e32 v90, v88, v82
	v_fma_f32 v92, -v71, v90, v88
	v_fmac_f32_e32 v90, v92, v82
	v_fma_f32 v71, -v71, v90, v88
	v_div_fmas_f32 v71, v71, v82, v90
	v_div_fixup_f32 v117, v71, v84, v117
	v_mul_f32_e32 v70, v70, v117
	v_lshlrev_b32_e32 v115, 16, v115
	v_lshlrev_b32_e32 v116, 16, v116
	v_lshlrev_b32_e32 v114, 16, v114
	v_mul_f32_e32 v114, v16, v114
	v_fmac_f32_e32 v114, v14, v115
	v_fmac_f32_e32 v114, v17, v116
	v_add_f32_e32 v114, v12, v114
	v_fma_f32 v27, v41, v8, v67
	v_mul_f32_e32 v110, v27, v114
	v_lshlrev_b32_e32 v118, 16, v118
	v_mul_f32_e32 v84, 0xbfb8aa3b, v118
	v_exp_f32_e32 v84, v84
	s_nop 0
	v_add_f32_e32 v84, 1.0, v84
	v_div_scale_f32 v71, s[74:75], v84, v84, v118
	v_rcp_f32_e32 v82, v71
	s_nop 0
	v_fma_f32 v92, -v71, v82, 1.0
	v_fmac_f32_e32 v82, v92, v82
	v_div_scale_f32 v88, vcc, v118, v84, v118
	v_mul_f32_e32 v90, v88, v82
	v_fma_f32 v92, -v71, v90, v88
	v_fmac_f32_e32 v90, v92, v82
	v_fma_f32 v71, -v71, v90, v88
	v_div_fmas_f32 v71, v71, v82, v90
	v_div_fixup_f32 v118, v71, v84, v118
	v_mul_f32_e32 v110, v110, v118
	v_cvt_pk_bf16_f32 v202, v70, v110
	v_lshlrev_b32_e32 v120, 16, v120
	v_lshlrev_b32_e32 v121, 16, v121
	v_lshlrev_b32_e32 v119, 16, v119
	v_mul_f32_e32 v119, v16, v119
	v_fmac_f32_e32 v119, v14, v120
	v_fmac_f32_e32 v119, v17, v121
	v_add_f32_e32 v119, v12, v119
	v_fma_f32 v27, v38, v8, v68
	v_mul_f32_e32 v70, v27, v119
	v_lshlrev_b32_e32 v125, 16, v125
	v_mul_f32_e32 v84, 0xbfb8aa3b, v125
	v_exp_f32_e32 v84, v84
	s_nop 0
	v_add_f32_e32 v84, 1.0, v84
	v_div_scale_f32 v71, s[74:75], v84, v84, v125
	v_rcp_f32_e32 v82, v71
	s_nop 0
	v_fma_f32 v92, -v71, v82, 1.0
	v_fmac_f32_e32 v82, v92, v82
	v_div_scale_f32 v88, vcc, v125, v84, v125
	v_mul_f32_e32 v90, v88, v82
	v_fma_f32 v92, -v71, v90, v88
	v_fmac_f32_e32 v90, v92, v82
	v_fma_f32 v71, -v71, v90, v88
	v_div_fmas_f32 v71, v71, v82, v90
	v_div_fixup_f32 v125, v71, v84, v125
	v_mul_f32_e32 v70, v70, v125
	v_lshlrev_b32_e32 v123, 16, v123
	v_lshlrev_b32_e32 v124, 16, v124
	v_lshlrev_b32_e32 v122, 16, v122
	v_mul_f32_e32 v122, v16, v122
	v_fmac_f32_e32 v122, v14, v123
	v_fmac_f32_e32 v122, v17, v124
	v_add_f32_e32 v122, v12, v122
	v_fma_f32 v27, v40, v8, v69
	v_mul_f32_e32 v110, v27, v122
	v_lshlrev_b32_e32 v126, 16, v126
	v_mul_f32_e32 v84, 0xbfb8aa3b, v126
	v_exp_f32_e32 v84, v84
	s_nop 0
	v_add_f32_e32 v84, 1.0, v84
	v_div_scale_f32 v71, s[74:75], v84, v84, v126
	v_rcp_f32_e32 v82, v71
	s_nop 0
	v_fma_f32 v92, -v71, v82, 1.0
	v_fmac_f32_e32 v82, v92, v82
	v_div_scale_f32 v88, vcc, v126, v84, v126
	v_mul_f32_e32 v90, v88, v82
	v_fma_f32 v92, -v71, v90, v88
	v_fmac_f32_e32 v90, v92, v82
	v_fma_f32 v71, -v71, v90, v88
	v_div_fmas_f32 v71, v71, v82, v90
	v_div_fixup_f32 v126, v71, v84, v126
	v_mul_f32_e32 v110, v110, v126
	v_cvt_pk_bf16_f32 v203, v70, v110
	v_lshlrev_b32_e32 v128, 16, v128
	v_lshlrev_b32_e32 v129, 16, v129
	v_lshlrev_b32_e32 v127, 16, v127
	v_mul_f32_e32 v127, v16, v127
	v_fmac_f32_e32 v127, v14, v128
	v_fmac_f32_e32 v127, v17, v129
	v_add_f32_e32 v127, v12, v127
	v_fma_f32 v27, v43, v8, v62
	v_mul_f32_e32 v70, v27, v127
	v_lshlrev_b32_e32 v133, 16, v133
	v_mul_f32_e32 v84, 0xbfb8aa3b, v133
	v_exp_f32_e32 v84, v84
	s_nop 0
	v_add_f32_e32 v84, 1.0, v84
	v_div_scale_f32 v71, s[74:75], v84, v84, v133
	v_rcp_f32_e32 v82, v71
	s_nop 0
	v_fma_f32 v92, -v71, v82, 1.0
	v_fmac_f32_e32 v82, v92, v82
	v_div_scale_f32 v88, vcc, v133, v84, v133
	v_mul_f32_e32 v90, v88, v82
	v_fma_f32 v92, -v71, v90, v88
	v_fmac_f32_e32 v90, v92, v82
	v_fma_f32 v71, -v71, v90, v88
	v_div_fmas_f32 v71, v71, v82, v90
	v_div_fixup_f32 v133, v71, v84, v133
	v_mul_f32_e32 v70, v70, v133
	v_lshlrev_b32_e32 v131, 16, v131
	v_lshlrev_b32_e32 v132, 16, v132
	v_lshlrev_b32_e32 v130, 16, v130
	v_mul_f32_e32 v130, v16, v130
	v_fmac_f32_e32 v130, v14, v131
	v_fmac_f32_e32 v130, v17, v132
	v_add_f32_e32 v130, v12, v130
	v_fma_f32 v27, v45, v8, v63
	v_mul_f32_e32 v110, v27, v130
	v_lshlrev_b32_e32 v134, 16, v134
	v_mul_f32_e32 v84, 0xbfb8aa3b, v134
	v_exp_f32_e32 v84, v84
	s_nop 0
	v_add_f32_e32 v84, 1.0, v84
	v_div_scale_f32 v71, s[74:75], v84, v84, v134
	v_rcp_f32_e32 v82, v71
	s_nop 0
	v_fma_f32 v92, -v71, v82, 1.0
	v_fmac_f32_e32 v82, v92, v82
	v_div_scale_f32 v88, vcc, v134, v84, v134
	v_mul_f32_e32 v90, v88, v82
	v_fma_f32 v92, -v71, v90, v88
	v_fmac_f32_e32 v90, v92, v82
	v_fma_f32 v71, -v71, v90, v88
	v_div_fmas_f32 v71, v71, v82, v90
	v_div_fixup_f32 v134, v71, v84, v134
	v_mul_f32_e32 v110, v110, v134
	v_cvt_pk_bf16_f32 v204, v70, v110
	v_lshlrev_b32_e32 v136, 16, v136
	v_lshlrev_b32_e32 v137, 16, v137
	v_lshlrev_b32_e32 v135, 16, v135
	v_mul_f32_e32 v135, v16, v135
	v_fmac_f32_e32 v135, v14, v136
	v_fmac_f32_e32 v135, v17, v137
	v_add_f32_e32 v135, v12, v135
	v_fma_f32 v27, v42, v8, v64
	v_mul_f32_e32 v70, v27, v135
	v_lshlrev_b32_e32 v141, 16, v141
	v_mul_f32_e32 v84, 0xbfb8aa3b, v141
	v_exp_f32_e32 v84, v84
	s_nop 0
	v_add_f32_e32 v84, 1.0, v84
	v_div_scale_f32 v71, s[74:75], v84, v84, v141
	v_rcp_f32_e32 v82, v71
	s_nop 0
	v_fma_f32 v92, -v71, v82, 1.0
	v_fmac_f32_e32 v82, v92, v82
	v_div_scale_f32 v88, vcc, v141, v84, v141
	v_mul_f32_e32 v90, v88, v82
	v_fma_f32 v92, -v71, v90, v88
	v_fmac_f32_e32 v90, v92, v82
	v_fma_f32 v71, -v71, v90, v88
	v_div_fmas_f32 v71, v71, v82, v90
	v_div_fixup_f32 v141, v71, v84, v141
	v_mul_f32_e32 v70, v70, v141
	v_lshlrev_b32_e32 v139, 16, v139
	v_lshlrev_b32_e32 v140, 16, v140
	v_lshlrev_b32_e32 v138, 16, v138
	v_mul_f32_e32 v138, v16, v138
	v_fmac_f32_e32 v138, v14, v139
	v_fmac_f32_e32 v138, v17, v140
	v_add_f32_e32 v138, v12, v138
	v_fma_f32 v27, v44, v8, v65
	v_mul_f32_e32 v110, v27, v138
	v_lshlrev_b32_e32 v142, 16, v142
	v_mul_f32_e32 v84, 0xbfb8aa3b, v142
	v_exp_f32_e32 v84, v84
	s_nop 0
	v_add_f32_e32 v84, 1.0, v84
	v_div_scale_f32 v71, s[74:75], v84, v84, v142
	v_rcp_f32_e32 v82, v71
	s_nop 0
	v_fma_f32 v92, -v71, v82, 1.0
	v_fmac_f32_e32 v82, v92, v82
	v_div_scale_f32 v88, vcc, v142, v84, v142
	v_mul_f32_e32 v90, v88, v82
	v_fma_f32 v92, -v71, v90, v88
	v_fmac_f32_e32 v90, v92, v82
	v_fma_f32 v71, -v71, v90, v88
	v_div_fmas_f32 v71, v71, v82, v90
	v_div_fixup_f32 v142, v71, v84, v142
	v_mul_f32_e32 v110, v110, v142
	v_cvt_pk_bf16_f32 v205, v70, v110
	s_waitcnt vmcnt(32)
	v_lshlrev_b32_e32 v163, 16, v163
	v_lshlrev_b32_e32 v164, 16, v164
	v_lshlrev_b32_e32 v143, 16, v143
	v_mul_f32_e32 v143, v16, v143
	v_fmac_f32_e32 v143, v14, v163
	v_fmac_f32_e32 v143, v17, v164
	v_add_f32_e32 v143, v12, v143
	v_fma_f32 v27, v47, v8, v22
	v_mul_f32_e32 v70, v27, v143
	v_lshlrev_b32_e32 v168, 16, v168
	v_mul_f32_e32 v84, 0xbfb8aa3b, v168
	v_exp_f32_e32 v84, v84
	s_nop 0
	v_add_f32_e32 v84, 1.0, v84
	v_div_scale_f32 v71, s[74:75], v84, v84, v168
	v_rcp_f32_e32 v82, v71
	s_nop 0
	v_fma_f32 v92, -v71, v82, 1.0
	v_fmac_f32_e32 v82, v92, v82
	v_div_scale_f32 v88, vcc, v168, v84, v168
	v_mul_f32_e32 v90, v88, v82
	v_fma_f32 v92, -v71, v90, v88
	v_fmac_f32_e32 v90, v92, v82
	v_fma_f32 v71, -v71, v90, v88
	v_div_fmas_f32 v71, v71, v82, v90
	v_div_fixup_f32 v168, v71, v84, v168
	v_mul_f32_e32 v70, v70, v168
	v_lshlrev_b32_e32 v166, 16, v166
	v_lshlrev_b32_e32 v167, 16, v167
	v_lshlrev_b32_e32 v165, 16, v165
	v_mul_f32_e32 v165, v16, v165
	v_fmac_f32_e32 v165, v14, v166
	v_fmac_f32_e32 v165, v17, v167
	v_add_f32_e32 v165, v12, v165
	v_fma_f32 v27, v49, v8, v23
	v_mul_f32_e32 v110, v27, v165
	v_lshlrev_b32_e32 v169, 16, v169
	v_mul_f32_e32 v84, 0xbfb8aa3b, v169
	v_exp_f32_e32 v84, v84
	s_nop 0
	v_add_f32_e32 v84, 1.0, v84
	v_div_scale_f32 v71, s[74:75], v84, v84, v169
	v_rcp_f32_e32 v82, v71
	s_nop 0
	v_fma_f32 v92, -v71, v82, 1.0
	v_fmac_f32_e32 v82, v92, v82
	v_div_scale_f32 v88, vcc, v169, v84, v169
	v_mul_f32_e32 v90, v88, v82
	v_fma_f32 v92, -v71, v90, v88
	v_fmac_f32_e32 v90, v92, v82
	v_fma_f32 v71, -v71, v90, v88
	v_div_fmas_f32 v71, v71, v82, v90
	v_div_fixup_f32 v169, v71, v84, v169
	v_mul_f32_e32 v110, v110, v169
	v_cvt_pk_bf16_f32 v206, v70, v110
	v_lshlrev_b32_e32 v171, 16, v171
	v_lshlrev_b32_e32 v172, 16, v172
	v_lshlrev_b32_e32 v170, 16, v170
	v_mul_f32_e32 v170, v16, v170
	v_fmac_f32_e32 v170, v14, v171
	v_fmac_f32_e32 v170, v17, v172
	v_add_f32_e32 v170, v12, v170
	v_fma_f32 v27, v46, v8, v24
	v_mul_f32_e32 v70, v27, v170
	v_lshlrev_b32_e32 v176, 16, v176
	v_mul_f32_e32 v84, 0xbfb8aa3b, v176
	v_exp_f32_e32 v84, v84
	s_nop 0
	v_add_f32_e32 v84, 1.0, v84
	v_div_scale_f32 v71, s[74:75], v84, v84, v176
	v_rcp_f32_e32 v82, v71
	s_nop 0
	v_fma_f32 v92, -v71, v82, 1.0
	v_fmac_f32_e32 v82, v92, v82
	v_div_scale_f32 v88, vcc, v176, v84, v176
	v_mul_f32_e32 v90, v88, v82
	v_fma_f32 v92, -v71, v90, v88
	v_fmac_f32_e32 v90, v92, v82
	v_fma_f32 v71, -v71, v90, v88
	v_div_fmas_f32 v71, v71, v82, v90
	v_div_fixup_f32 v176, v71, v84, v176
	v_mul_f32_e32 v70, v70, v176
	v_lshlrev_b32_e32 v174, 16, v174
	v_lshlrev_b32_e32 v175, 16, v175
	v_lshlrev_b32_e32 v173, 16, v173
	v_mul_f32_e32 v173, v16, v173
	v_fmac_f32_e32 v173, v14, v174
	v_fmac_f32_e32 v173, v17, v175
	v_add_f32_e32 v173, v12, v173
	v_fma_f32 v27, v48, v8, v25
	v_mul_f32_e32 v110, v27, v173
	v_lshlrev_b32_e32 v177, 16, v177
	v_mul_f32_e32 v84, 0xbfb8aa3b, v177
	v_exp_f32_e32 v84, v84
	s_nop 0
	v_add_f32_e32 v84, 1.0, v84
	v_div_scale_f32 v71, s[74:75], v84, v84, v177
	v_rcp_f32_e32 v82, v71
	s_nop 0
	v_fma_f32 v92, -v71, v82, 1.0
	v_fmac_f32_e32 v82, v92, v82
	v_div_scale_f32 v88, vcc, v177, v84, v177
	v_mul_f32_e32 v90, v88, v82
	v_fma_f32 v92, -v71, v90, v88
	v_fmac_f32_e32 v90, v92, v82
	v_fma_f32 v71, -v71, v90, v88
	v_div_fmas_f32 v71, v71, v82, v90
	v_div_fixup_f32 v177, v71, v84, v177
	v_mul_f32_e32 v110, v110, v177
	v_cvt_pk_bf16_f32 v207, v70, v110
	v_lshlrev_b32_e32 v179, 16, v179
	v_lshlrev_b32_e32 v180, 16, v180
	v_lshlrev_b32_e32 v178, 16, v178
	v_mul_f32_e32 v178, v16, v178
	v_fmac_f32_e32 v178, v14, v179
	v_fmac_f32_e32 v178, v17, v180
	v_add_f32_e32 v178, v12, v178
	v_fma_f32 v27, v51, v8, v18
	v_mul_f32_e32 v70, v27, v178
	v_lshlrev_b32_e32 v184, 16, v184
	v_mul_f32_e32 v84, 0xbfb8aa3b, v184
	v_exp_f32_e32 v84, v84
	s_nop 0
	v_add_f32_e32 v84, 1.0, v84
	v_div_scale_f32 v71, s[74:75], v84, v84, v184
	v_rcp_f32_e32 v82, v71
	s_nop 0
	v_fma_f32 v92, -v71, v82, 1.0
	v_fmac_f32_e32 v82, v92, v82
	v_div_scale_f32 v88, vcc, v184, v84, v184
	v_mul_f32_e32 v90, v88, v82
	v_fma_f32 v92, -v71, v90, v88
	v_fmac_f32_e32 v90, v92, v82
	v_fma_f32 v71, -v71, v90, v88
	v_div_fmas_f32 v71, v71, v82, v90
	v_div_fixup_f32 v184, v71, v84, v184
	v_mul_f32_e32 v70, v70, v184
	v_lshlrev_b32_e32 v182, 16, v182
	v_lshlrev_b32_e32 v183, 16, v183
	v_lshlrev_b32_e32 v181, 16, v181
	v_mul_f32_e32 v181, v16, v181
	v_fmac_f32_e32 v181, v14, v182
	v_fmac_f32_e32 v181, v17, v183
	v_add_f32_e32 v181, v12, v181
	v_fma_f32 v27, v53, v8, v19
	v_mul_f32_e32 v110, v27, v181
	v_lshlrev_b32_e32 v185, 16, v185
	v_mul_f32_e32 v84, 0xbfb8aa3b, v185
	v_exp_f32_e32 v84, v84
	s_nop 0
	v_add_f32_e32 v84, 1.0, v84
	v_div_scale_f32 v71, s[74:75], v84, v84, v185
	v_rcp_f32_e32 v82, v71
	s_nop 0
	v_fma_f32 v92, -v71, v82, 1.0
	v_fmac_f32_e32 v82, v92, v82
	v_div_scale_f32 v88, vcc, v185, v84, v185
	v_mul_f32_e32 v90, v88, v82
	v_fma_f32 v92, -v71, v90, v88
	v_fmac_f32_e32 v90, v92, v82
	v_fma_f32 v71, -v71, v90, v88
	v_div_fmas_f32 v71, v71, v82, v90
	v_div_fixup_f32 v185, v71, v84, v185
	v_mul_f32_e32 v110, v110, v185
	v_cvt_pk_bf16_f32 v208, v70, v110
	v_lshlrev_b32_e32 v187, 16, v187
	v_lshlrev_b32_e32 v188, 16, v188
	v_lshlrev_b32_e32 v186, 16, v186
	v_mul_f32_e32 v186, v16, v186
	v_fmac_f32_e32 v186, v14, v187
	v_fmac_f32_e32 v186, v17, v188
	v_add_f32_e32 v186, v12, v186
	v_fma_f32 v27, v50, v8, v20
	v_mul_f32_e32 v70, v27, v186
	v_lshlrev_b32_e32 v192, 16, v192
	v_mul_f32_e32 v84, 0xbfb8aa3b, v192
	v_exp_f32_e32 v84, v84
	s_nop 0
	v_add_f32_e32 v84, 1.0, v84
	v_div_scale_f32 v71, s[74:75], v84, v84, v192
	v_rcp_f32_e32 v82, v71
	s_nop 0
	v_fma_f32 v92, -v71, v82, 1.0
	v_fmac_f32_e32 v82, v92, v82
	v_div_scale_f32 v88, vcc, v192, v84, v192
	v_mul_f32_e32 v90, v88, v82
	v_fma_f32 v92, -v71, v90, v88
	v_fmac_f32_e32 v90, v92, v82
	v_fma_f32 v71, -v71, v90, v88
	v_div_fmas_f32 v71, v71, v82, v90
	v_div_fixup_f32 v192, v71, v84, v192
	v_mul_f32_e32 v70, v70, v192
	v_lshlrev_b32_e32 v190, 16, v190
	v_lshlrev_b32_e32 v191, 16, v191
	v_lshlrev_b32_e32 v189, 16, v189
	v_mul_f32_e32 v189, v16, v189
	v_fmac_f32_e32 v189, v14, v190
	v_fmac_f32_e32 v189, v17, v191
	v_add_f32_e32 v189, v12, v189
	v_fma_f32 v27, v52, v8, v21
	v_mul_f32_e32 v110, v27, v189
	v_lshlrev_b32_e32 v193, 16, v193
	v_mul_f32_e32 v84, 0xbfb8aa3b, v193
	v_exp_f32_e32 v84, v84
	s_nop 0
	v_add_f32_e32 v84, 1.0, v84
	v_div_scale_f32 v71, s[74:75], v84, v84, v193
	v_rcp_f32_e32 v82, v71
	s_nop 0
	v_fma_f32 v92, -v71, v82, 1.0
	v_fmac_f32_e32 v82, v92, v82
	v_div_scale_f32 v88, vcc, v193, v84, v193
	v_mul_f32_e32 v90, v88, v82
	v_fma_f32 v92, -v71, v90, v88
	v_fmac_f32_e32 v90, v92, v82
	v_fma_f32 v71, -v71, v90, v88
	v_div_fmas_f32 v71, v71, v82, v90
	v_div_fixup_f32 v193, v71, v84, v193
	v_mul_f32_e32 v110, v110, v193
	v_cvt_pk_bf16_f32 v209, v70, v110
	s_waitcnt vmcnt(0)
	v_lshlrev_b32_e32 v195, 16, v195
	v_lshlrev_b32_e32 v196, 16, v196
	v_lshlrev_b32_e32 v194, 16, v194
	v_mul_f32_e32 v194, v16, v194
	v_fmac_f32_e32 v194, v14, v195
	v_fmac_f32_e32 v194, v17, v196
	v_add_f32_e32 v194, v12, v194
	v_fma_f32 v27, v55, v8, v4
	v_mul_f32_e32 v70, v27, v194
	v_lshlrev_b32_e32 v223, 16, v223
	v_mul_f32_e32 v84, 0xbfb8aa3b, v223
	v_exp_f32_e32 v84, v84
	s_nop 0
	v_add_f32_e32 v84, 1.0, v84
	v_div_scale_f32 v71, s[74:75], v84, v84, v223
	v_rcp_f32_e32 v82, v71
	s_nop 0
	v_fma_f32 v92, -v71, v82, 1.0
	v_fmac_f32_e32 v82, v92, v82
	v_div_scale_f32 v88, vcc, v223, v84, v223
	v_mul_f32_e32 v90, v88, v82
	v_fma_f32 v92, -v71, v90, v88
	v_fmac_f32_e32 v90, v92, v82
	v_fma_f32 v71, -v71, v90, v88
	v_div_fmas_f32 v71, v71, v82, v90
	v_div_fixup_f32 v223, v71, v84, v223
	v_mul_f32_e32 v70, v70, v223
	v_lshlrev_b32_e32 v221, 16, v221
	v_lshlrev_b32_e32 v222, 16, v222
	v_lshlrev_b32_e32 v197, 16, v197
	v_mul_f32_e32 v197, v16, v197
	v_fmac_f32_e32 v197, v14, v221
	v_fmac_f32_e32 v197, v17, v222
	v_add_f32_e32 v197, v12, v197
	v_fma_f32 v27, v57, v8, v5
	v_mul_f32_e32 v110, v27, v197
	v_lshlrev_b32_e32 v224, 16, v224
	v_mul_f32_e32 v84, 0xbfb8aa3b, v224
	v_exp_f32_e32 v84, v84
	s_nop 0
	v_add_f32_e32 v84, 1.0, v84
	v_div_scale_f32 v71, s[74:75], v84, v84, v224
	v_rcp_f32_e32 v82, v71
	s_nop 0
	v_fma_f32 v92, -v71, v82, 1.0
	v_fmac_f32_e32 v82, v92, v82
	v_div_scale_f32 v88, vcc, v224, v84, v224
	v_mul_f32_e32 v90, v88, v82
	v_fma_f32 v92, -v71, v90, v88
	v_fmac_f32_e32 v90, v92, v82
	v_fma_f32 v71, -v71, v90, v88
	v_div_fmas_f32 v71, v71, v82, v90
	v_div_fixup_f32 v224, v71, v84, v224
	v_mul_f32_e32 v110, v110, v224
	v_cvt_pk_bf16_f32 v210, v70, v110
	v_lshlrev_b32_e32 v226, 16, v226
	v_lshlrev_b32_e32 v227, 16, v227
	v_lshlrev_b32_e32 v225, 16, v225
	v_mul_f32_e32 v225, v16, v225
	v_fmac_f32_e32 v225, v14, v226
	v_fmac_f32_e32 v225, v17, v227
	v_add_f32_e32 v225, v12, v225
	v_fma_f32 v27, v54, v8, v6
	v_mul_f32_e32 v70, v27, v225
	v_lshlrev_b32_e32 v231, 16, v231
	v_mul_f32_e32 v84, 0xbfb8aa3b, v231
	v_exp_f32_e32 v84, v84
	s_nop 0
	v_add_f32_e32 v84, 1.0, v84
	v_div_scale_f32 v71, s[74:75], v84, v84, v231
	v_rcp_f32_e32 v82, v71
	s_nop 0
	v_fma_f32 v92, -v71, v82, 1.0
	v_fmac_f32_e32 v82, v92, v82
	v_div_scale_f32 v88, vcc, v231, v84, v231
	v_mul_f32_e32 v90, v88, v82
	v_fma_f32 v92, -v71, v90, v88
	v_fmac_f32_e32 v90, v92, v82
	v_fma_f32 v71, -v71, v90, v88
	v_div_fmas_f32 v71, v71, v82, v90
	v_div_fixup_f32 v231, v71, v84, v231
	v_mul_f32_e32 v70, v70, v231
	v_lshlrev_b32_e32 v229, 16, v229
	v_lshlrev_b32_e32 v230, 16, v230
	v_lshlrev_b32_e32 v228, 16, v228
	v_mul_f32_e32 v228, v16, v228
	v_fmac_f32_e32 v228, v14, v229
	v_fmac_f32_e32 v228, v17, v230
	v_add_f32_e32 v228, v12, v228
	v_fma_f32 v27, v56, v8, v7
	v_mul_f32_e32 v110, v27, v228
	v_lshlrev_b32_e32 v232, 16, v232
	v_mul_f32_e32 v84, 0xbfb8aa3b, v232
	v_exp_f32_e32 v84, v84
	s_nop 0
	v_add_f32_e32 v84, 1.0, v84
	v_div_scale_f32 v71, s[74:75], v84, v84, v232
	v_rcp_f32_e32 v82, v71
	s_nop 0
	v_fma_f32 v92, -v71, v82, 1.0
	v_fmac_f32_e32 v82, v92, v82
	v_div_scale_f32 v88, vcc, v232, v84, v232
	v_mul_f32_e32 v90, v88, v82
	v_fma_f32 v92, -v71, v90, v88
	v_fmac_f32_e32 v90, v92, v82
	v_fma_f32 v71, -v71, v90, v88
	v_div_fmas_f32 v71, v71, v82, v90
	v_div_fixup_f32 v232, v71, v84, v232
	v_mul_f32_e32 v110, v110, v232
	v_cvt_pk_bf16_f32 v211, v70, v110
	v_lshlrev_b32_e32 v234, 16, v234
	v_lshlrev_b32_e32 v235, 16, v235
	v_lshlrev_b32_e32 v233, 16, v233
	v_mul_f32_e32 v233, v16, v233
	v_fmac_f32_e32 v233, v14, v234
	v_fmac_f32_e32 v233, v17, v235
	v_add_f32_e32 v233, v12, v233
	v_fma_f32 v27, v59, v8, v0
	v_mul_f32_e32 v70, v27, v233
	v_lshlrev_b32_e32 v239, 16, v239
	v_mul_f32_e32 v84, 0xbfb8aa3b, v239
	v_exp_f32_e32 v84, v84
	s_nop 0
	v_add_f32_e32 v84, 1.0, v84
	v_div_scale_f32 v71, s[74:75], v84, v84, v239
	v_rcp_f32_e32 v82, v71
	s_nop 0
	v_fma_f32 v92, -v71, v82, 1.0
	v_fmac_f32_e32 v82, v92, v82
	v_div_scale_f32 v88, vcc, v239, v84, v239
	v_mul_f32_e32 v90, v88, v82
	v_fma_f32 v92, -v71, v90, v88
	v_fmac_f32_e32 v90, v92, v82
	v_fma_f32 v71, -v71, v90, v88
	v_div_fmas_f32 v71, v71, v82, v90
	v_div_fixup_f32 v239, v71, v84, v239
	v_mul_f32_e32 v70, v70, v239
	v_lshlrev_b32_e32 v237, 16, v237
	v_lshlrev_b32_e32 v238, 16, v238
	v_lshlrev_b32_e32 v236, 16, v236
	v_mul_f32_e32 v236, v16, v236
	v_fmac_f32_e32 v236, v14, v237
	v_fmac_f32_e32 v236, v17, v238
	v_add_f32_e32 v236, v12, v236
	v_fma_f32 v27, v61, v8, v1
	v_mul_f32_e32 v110, v27, v236
	v_lshlrev_b32_e32 v240, 16, v240
	v_mul_f32_e32 v84, 0xbfb8aa3b, v240
	v_exp_f32_e32 v84, v84
	s_nop 0
	v_add_f32_e32 v84, 1.0, v84
	v_div_scale_f32 v71, s[74:75], v84, v84, v240
	v_rcp_f32_e32 v82, v71
	s_nop 0
	v_fma_f32 v92, -v71, v82, 1.0
	v_fmac_f32_e32 v82, v92, v82
	v_div_scale_f32 v88, vcc, v240, v84, v240
	v_mul_f32_e32 v90, v88, v82
	v_fma_f32 v92, -v71, v90, v88
	v_fmac_f32_e32 v90, v92, v82
	v_fma_f32 v71, -v71, v90, v88
	v_div_fmas_f32 v71, v71, v82, v90
	v_div_fixup_f32 v240, v71, v84, v240
	v_mul_f32_e32 v110, v110, v240
	v_cvt_pk_bf16_f32 v212, v70, v110
	v_lshlrev_b32_e32 v242, 16, v242
	v_lshlrev_b32_e32 v243, 16, v243
	v_lshlrev_b32_e32 v241, 16, v241
	v_mul_f32_e32 v241, v16, v241
	v_mul_f32_e32 v243, v255, v243
	v_fmac_f32_e32 v241, v14, v242
	v_fmac_f32_e32 v241, v17, v243
	v_add_f32_e32 v241, v12, v241
	v_fma_f32 v27, v58, v8, v2
	v_mul_f32_e32 v70, v27, v241
	v_lshlrev_b32_e32 v247, 16, v247
	v_mul_f32_e32 v84, 0xbfb8aa3b, v247
	v_exp_f32_e32 v84, v84
	s_nop 0
	v_add_f32_e32 v84, 1.0, v84
	v_div_scale_f32 v71, s[74:75], v84, v84, v247
	v_rcp_f32_e32 v82, v71
	s_nop 0
	v_fma_f32 v92, -v71, v82, 1.0
	v_fmac_f32_e32 v82, v92, v82
	v_div_scale_f32 v88, vcc, v247, v84, v247
	v_mul_f32_e32 v90, v88, v82
	v_fma_f32 v92, -v71, v90, v88
	v_fmac_f32_e32 v90, v92, v82
	v_fma_f32 v71, -v71, v90, v88
	v_div_fmas_f32 v71, v71, v82, v90
	v_div_fixup_f32 v247, v71, v84, v247
	v_mul_f32_e32 v70, v70, v247
	v_lshlrev_b32_e32 v245, 16, v245
	v_lshlrev_b32_e32 v246, 16, v246
	v_lshlrev_b32_e32 v244, 16, v244
	v_mul_f32_e32 v244, v16, v244
	v_mul_f32_e32 v246, v255, v246
	v_fmac_f32_e32 v244, v14, v245
	v_fmac_f32_e32 v244, v17, v246
	v_add_f32_e32 v244, v12, v244
	v_fma_f32 v27, v60, v8, v3
	v_mul_f32_e32 v110, v27, v244
	v_lshlrev_b32_e32 v248, 16, v248
	v_mul_f32_e32 v84, 0xbfb8aa3b, v248
	v_exp_f32_e32 v84, v84
	s_nop 0
	v_add_f32_e32 v84, 1.0, v84
	v_div_scale_f32 v71, s[74:75], v84, v84, v248
	v_rcp_f32_e32 v82, v71
	s_nop 0
	v_fma_f32 v92, -v71, v82, 1.0
	v_fmac_f32_e32 v82, v92, v82
	v_div_scale_f32 v88, vcc, v248, v84, v248
	v_mul_f32_e32 v90, v88, v82
	v_fma_f32 v92, -v71, v90, v88
	v_fmac_f32_e32 v90, v92, v82
	v_fma_f32 v71, -v71, v90, v88
	v_div_fmas_f32 v71, v71, v82, v90
	v_div_fixup_f32 v248, v71, v84, v248
	v_mul_f32_e32 v110, v110, v248
	v_cvt_pk_bf16_f32 v213, v70, v110
	s_branch .Lhy_ep1_done_L1
